# stacked: K-loop first trip peeled with 0 addend (no accumulator clear) + the redundant s_setprio 0/1 pair between the two 16-MFMA runs of every compute segment removed (prio stays 1 over the 32 MFMAs)
# baseline (speedup 1.0000x reference)
;     __device__ __forceinline__ bool next(int i, Unit& u) const { if (i != 0) return false; const int c0 = (G >= 8) ? G - 5 : G - 2; int k = -1; if (c == c0) k = 0; else if (c == G - 1) k = 1; if (k < 0 || k >= n) return false; u.pm = k; u.pn = 0; return true; }
; #define PG8_STAGE(bufoff, gbase, voff) do { _Pragma("unroll") for (int _i = 0; _i < 2; ++_i) \
;         __builtin_amdgcn_global_load_lds((const unsigned*)((const char*)(gbase) + (voff)[_i]), (PG8_LAS unsigned*)(lds + (bufoff) + ldsw + _i * 8192), 16, 0, 0); } while (0)
; #define PG8_LDA(dst, b, h) do { _Pragma("unroll") for (int m = 0; m < 4; ++m) _Pragma("unroll") for (int k = 0; k < 2; ++k) dst[m][k] = *(const PG8_LAS bf16x8*)(lds + PG8_SA(b, h) + aoff + m * 2048 + k * 1024); } while (0)
; #define PG8_LDB(dst, b, h) do { _Pragma("unroll") for (int n = 0; n < 2; ++n) _Pragma("unroll") for (int k = 0; k < 2; ++k) dst[n][k] = *(const PG8_LAS bf16x8*)(lds + PG8_SB(b, h) + boff + n * 2048 + k * 1024); } while (0)
; #define PG8_WAIT_V(n) asm volatile("s_waitcnt vmcnt(" #n ")" ::: "memory")
; #define PG8_WAIT_L(n) asm volatile("s_waitcnt lgkmcnt(" #n ")" ::: "memory")
; template <class Epi, class Sched, bool ALIGN_EPI = false, bool SP2 = false>
; __device__ __forceinline__ void gemm_phase(PG8_LAS unsigned char* lds, const Gemm g, const Sched& S, const Epi& E) {
;     ...
;         const bool has_next = S.next(ui + 1, nxt);
;         const char* nA = has_next ? (const char*)g.A + (size_t)nxt.pm * tstep : cA; const char* nB = has_next ? (const char*)g.Bt + (size_t)nxt.pn * tstep : cB;
;         for (int t = 0; t < nt; t += 2) {
;             const bool last = (t == nt - 2);
;             const char* a1 = cA + (size_t)(t + 1) * kstep;
;             const char* a2 = last ? nA : cA + (size_t)(t + 2) * kstep; const char* b2 = last ? nB : cB + (size_t)(t + 2) * kstep;
;             const char* a3 = a2 + kstep; const char* b3 = b2 + kstep;
;             if (last && has_next) S.a_ready(nxt);
;             if constexpr (SP2) {
;             PG8_LDB(B0, 0, 0); PG8_LDB(B1, 0, 1); PG8_SCHED; PG8_LDA(At, 0, 0); PG8_STAGE(PG8_SA(1, 1), a1 + hstep, voffA);
;             PG8_WAIT_V(8); PG8_WAIT_L(0); PG8_BAR; PG8_MMA(0, 0, At, B0); PG8_MMA(0, 1, At, B1); PG8_BAR; PG8_SCHED;
;             PG8_LDA(At, 0, 1); PG8_STAGE(PG8_SB(0, 0), b2, voffB); PG8_STAGE(PG8_SB(0, 1), b2 + hstep, voffB); PG8_STAGE(PG8_SA(0, 0), a2, voffA);
.LBB0_337:
	s_ashr_i32 s29, s28, 31
	s_lshl_b64 s[42:43], s[28:29], 19
	s_add_u32 s42, s97, s42
	s_addc_u32 s43, s3, s43
	s_and_b64 s[46:47], s[30:31], exec
	s_cselect_b32 s5, s43, s7
	s_cselect_b32 s29, s42, s6
	s_ashr_i32 s27, s26, 31
	s_lshl_b64 s[46:47], s[26:27], 19
	s_add_u32 s46, s90, s46
	s_addc_u32 s47, s91, s47
	s_and_b64 s[58:59], s[30:31], exec
	s_cselect_b32 s27, s47, s57
	s_cselect_b32 s60, s46, s56
	s_add_u32 s6, s6, 0x40080
	s_addc_u32 s7, s7, 0
	s_add_u32 s61, s56, 0x100
	v_mov_b32_e32 v0, 0
	s_addc_u32 s82, s57, 0
	s_mov_b32 s83, -2
	ds_read_b128 v[146:149], v163
	ds_read_b128 v[168:171], v163 offset:1024
	ds_read_b128 v[172:175], v163 offset:2048
	ds_read_b128 v[176:179], v163 offset:3072
	ds_read_b128 v[180:183], v164
	ds_read_b128 v[184:187], v164 offset:1024
	ds_read_b128 v[188:191], v164 offset:2048
	ds_read_b128 v[192:195], v164 offset:3072
	s_add_u32 s56, s6, 0xfffc0080
	s_addc_u32 s57, s7, -1
	s_cmp_eq_u32 s83, 12
	s_cselect_b32 s59, s5, s57
	s_cselect_b32 s58, s29, s56
	s_cselect_b32 s57, s27, s82
	s_cselect_b32 s56, s60, s61
	v_lshl_add_u64 v[150:151], s[6:7], 0, v[140:141]
	s_add_i32 m0, s41, 0xc000
	ds_read_b128 v[196:199], v165
	ds_read_b128 v[200:203], v165 offset:1024
	ds_read_b128 v[208:211], v165 offset:2048
	ds_read_b128 v[212:215], v165 offset:3072
	ds_read_b128 v[216:219], v165 offset:4096
	ds_read_b128 v[220:223], v165 offset:5120
	ds_read_b128 v[224:227], v165 offset:6144
	ds_read_b128 v[228:231], v165 offset:7168
	global_load_lds_dwordx4 v[150:151], off
	v_lshl_add_u64 v[150:151], s[6:7], 0, v[142:143]
	s_add_i32 m0, s41, 0xe000
	s_nop 0
	global_load_lds_dwordx4 v[150:151], off
	s_waitcnt vmcnt(8)
	s_waitcnt lgkmcnt(0)
	s_barrier
	s_setprio 1
	s_waitcnt lgkmcnt(0)
	v_mfma_f32_16x16x32_bf16 v[124:127], v[146:149], v[196:199], 0
	v_mfma_f32_16x16x32_bf16 v[120:123], v[172:175], v[196:199], 0
	v_mfma_f32_16x16x32_bf16 v[108:111], v[146:149], v[208:211], 0
	v_mfma_f32_16x16x32_bf16 v[104:107], v[172:175], v[208:211], 0
	v_mfma_f32_16x16x32_bf16 v[92:95], v[146:149], v[216:219], 0
	v_mfma_f32_16x16x32_bf16 v[88:91], v[172:175], v[216:219], 0
	v_mfma_f32_16x16x32_bf16 v[76:79], v[146:149], v[224:227], 0
	v_mfma_f32_16x16x32_bf16 v[72:75], v[172:175], v[224:227], 0
	v_mfma_f32_16x16x32_bf16 v[124:127], v[168:171], v[200:203], v[124:127]
	v_mfma_f32_16x16x32_bf16 v[120:123], v[176:179], v[200:203], v[120:123]
	v_mfma_f32_16x16x32_bf16 v[108:111], v[168:171], v[212:215], v[108:111]
	v_mfma_f32_16x16x32_bf16 v[104:107], v[176:179], v[212:215], v[104:107]
	v_mfma_f32_16x16x32_bf16 v[92:95], v[168:171], v[220:223], v[92:95]
	v_mfma_f32_16x16x32_bf16 v[88:91], v[176:179], v[220:223], v[88:91]
	v_mfma_f32_16x16x32_bf16 v[76:79], v[168:171], v[228:231], v[76:79]
	v_mfma_f32_16x16x32_bf16 v[72:75], v[176:179], v[228:231], v[72:75]
	v_mfma_f32_16x16x32_bf16 v[116:119], v[180:183], v[196:199], 0
	v_mfma_f32_16x16x32_bf16 v[112:115], v[188:191], v[196:199], 0
	v_mfma_f32_16x16x32_bf16 v[100:103], v[180:183], v[208:211], 0
	v_mfma_f32_16x16x32_bf16 v[96:99], v[188:191], v[208:211], 0
	v_mfma_f32_16x16x32_bf16 v[84:87], v[180:183], v[216:219], 0
	v_mfma_f32_16x16x32_bf16 v[80:83], v[188:191], v[216:219], 0
	v_mfma_f32_16x16x32_bf16 v[68:71], v[180:183], v[224:227], 0
	v_mfma_f32_16x16x32_bf16 v[64:67], v[188:191], v[224:227], 0
	v_mfma_f32_16x16x32_bf16 v[116:119], v[184:187], v[200:203], v[116:119]
	v_mfma_f32_16x16x32_bf16 v[112:115], v[192:195], v[200:203], v[112:115]
	v_mfma_f32_16x16x32_bf16 v[100:103], v[184:187], v[212:215], v[100:103]
	v_mfma_f32_16x16x32_bf16 v[96:99], v[192:195], v[212:215], v[96:99]
	v_mfma_f32_16x16x32_bf16 v[84:87], v[184:187], v[220:223], v[84:87]
	v_mfma_f32_16x16x32_bf16 v[80:83], v[192:195], v[220:223], v[80:83]
	v_mfma_f32_16x16x32_bf16 v[68:71], v[184:187], v[228:231], v[68:71]
	v_mfma_f32_16x16x32_bf16 v[64:67], v[192:195], v[228:231], v[64:67]
	s_setprio 0
	s_barrier
	s_add_i32 s92, s79, s25
	v_lshl_add_u64 v[150:151], s[56:57], 0, v[130:131]
	s_mov_b32 m0, s92
	ds_read_b128 v[196:199], v165 offset:16384
	ds_read_b128 v[200:203], v165 offset:17408
	ds_read_b128 v[208:211], v165 offset:18432
	ds_read_b128 v[212:215], v165 offset:19456
	ds_read_b128 v[216:219], v165 offset:20480
	ds_read_b128 v[220:223], v165 offset:21504
	ds_read_b128 v[224:227], v165 offset:22528
	ds_read_b128 v[228:231], v165 offset:23552
	global_load_lds_dwordx4 v[150:151], off
	s_add_i32 m0, s92, 0x2000
	s_add_u32 s92, s56, 0x40000
	v_lshl_add_u64 v[204:205], s[56:57], 0, v[134:135]
	s_addc_u32 s93, s57, 0
	s_add_i32 s94, s80, s25
	global_load_lds_dwordx4 v[204:205], off
	v_lshl_add_u64 v[232:233], s[92:93], 0, v[130:131]
	s_mov_b32 m0, s94
	v_lshl_add_u64 v[234:235], s[58:59], 0, v[132:133]
	global_load_lds_dwordx4 v[232:233], off
	v_lshl_add_u64 v[232:233], s[92:93], 0, v[134:135]
	s_add_i32 m0, s94, 0x2000
	s_nop 0
	global_load_lds_dwordx4 v[232:233], off
	v_lshl_add_u64 v[232:233], s[58:59], 0, v[128:129]
	s_mov_b32 m0, s41
	s_nop 0
	global_load_lds_dwordx4 v[232:233], off
	s_mov_b32 m0, s68
	s_nop 0
	global_load_lds_dwordx4 v[234:235], off
	s_waitcnt vmcnt(8)
	s_waitcnt lgkmcnt(0)
	s_barrier
; #define PG8_STAGE(bufoff, gbase, voff) do { _Pragma("unroll") for (int _i = 0; _i < 2; ++_i) \
;         __builtin_amdgcn_global_load_lds((const unsigned*)((const char*)(gbase) + (voff)[_i]), (PG8_LAS unsigned*)(lds + (bufoff) + ldsw + _i * 8192), 16, 0, 0); } while (0)
; #define PG8_LDA(dst, b, h) do { _Pragma("unroll") for (int m = 0; m < 4; ++m) _Pragma("unroll") for (int k = 0; k < 2; ++k) dst[m][k] = *(const PG8_LAS bf16x8*)(lds + PG8_SA(b, h) + aoff + m * 2048 + k * 1024); } while (0)
; #define PG8_LDB(dst, b, h) do { _Pragma("unroll") for (int n = 0; n < 2; ++n) _Pragma("unroll") for (int k = 0; k < 2; ++k) dst[n][k] = *(const PG8_LAS bf16x8*)(lds + PG8_SB(b, h) + boff + n * 2048 + k * 1024); } while (0)
; #define PG8_MMA(ai, bj, At, Bt) do { __builtin_amdgcn_s_setprio(1); _Pragma("unroll") for (int m = 0; m < 4; ++m) _Pragma("unroll") for (int n = 0; n < 2; ++n) _Pragma("unroll") for (int k = 0; k < 2; ++k) \
;         acc[ai][bj][m][n] = __builtin_amdgcn_mfma_f32_16x16x32_bf16(Bt[n][k], At[m][k], acc[ai][bj][m][n], 0, 0, 0); __builtin_amdgcn_s_setprio(0); } while (0)
; #define PG8_WAIT_V(n) asm volatile("s_waitcnt vmcnt(" #n ")" ::: "memory")
; #define PG8_WAIT_L(n) asm volatile("s_waitcnt lgkmcnt(" #n ")" ::: "memory")
; #define PG8_BAR __builtin_amdgcn_s_barrier()
; #define PG8_SCHED __builtin_amdgcn_sched_barrier(0)
; template <class Epi, class Sched, bool ALIGN_EPI = false, bool SP2 = false>
; __device__ __forceinline__ void gemm_phase(PG8_LAS unsigned char* lds, const Gemm g, const Sched& S, const Epi& E) {
;     ...
;             PG8_WAIT_V(8); PG8_WAIT_L(0); PG8_BAR; PG8_MMA(1, 0, At, B0); PG8_MMA(1, 1, At, B1); PG8_BAR; PG8_SCHED;
;             PG8_LDB(B0, 1, 0); PG8_LDB(B1, 1, 1); PG8_SCHED; PG8_LDA(At, 1, 0); PG8_STAGE(PG8_SA(0, 1), a2 + hstep, voffA);
;             PG8_WAIT_V(8); PG8_WAIT_L(0); PG8_BAR; PG8_MMA(0, 0, At, B0); PG8_MMA(0, 1, At, B1); PG8_BAR; PG8_SCHED;
	s_setprio 1
	s_waitcnt lgkmcnt(0)
	v_mfma_f32_16x16x32_bf16 v[60:63], v[146:149], v[196:199], 0
	v_mfma_f32_16x16x32_bf16 v[56:59], v[172:175], v[196:199], 0
	v_mfma_f32_16x16x32_bf16 v[44:47], v[146:149], v[208:211], 0
	v_mfma_f32_16x16x32_bf16 v[40:43], v[172:175], v[208:211], 0
	v_mfma_f32_16x16x32_bf16 v[28:31], v[146:149], v[216:219], 0
	v_mfma_f32_16x16x32_bf16 v[24:27], v[172:175], v[216:219], 0
	v_mfma_f32_16x16x32_bf16 v[12:15], v[146:149], v[224:227], 0
	v_mfma_f32_16x16x32_bf16 v[8:11], v[172:175], v[224:227], 0
	v_mfma_f32_16x16x32_bf16 v[60:63], v[168:171], v[200:203], v[60:63]
	v_mfma_f32_16x16x32_bf16 v[56:59], v[176:179], v[200:203], v[56:59]
	v_mfma_f32_16x16x32_bf16 v[44:47], v[168:171], v[212:215], v[44:47]
	v_mfma_f32_16x16x32_bf16 v[40:43], v[176:179], v[212:215], v[40:43]
	v_mfma_f32_16x16x32_bf16 v[28:31], v[168:171], v[220:223], v[28:31]
	v_mfma_f32_16x16x32_bf16 v[24:27], v[176:179], v[220:223], v[24:27]
	v_mfma_f32_16x16x32_bf16 v[12:15], v[168:171], v[228:231], v[12:15]
	v_mfma_f32_16x16x32_bf16 v[8:11], v[176:179], v[228:231], v[8:11]
	v_mfma_f32_16x16x32_bf16 v[52:55], v[180:183], v[196:199], 0
	v_mfma_f32_16x16x32_bf16 v[48:51], v[188:191], v[196:199], 0
	v_mfma_f32_16x16x32_bf16 v[36:39], v[180:183], v[208:211], 0
	v_mfma_f32_16x16x32_bf16 v[32:35], v[188:191], v[208:211], 0
	v_mfma_f32_16x16x32_bf16 v[20:23], v[180:183], v[216:219], 0
	v_mfma_f32_16x16x32_bf16 v[16:19], v[188:191], v[216:219], 0
	v_mfma_f32_16x16x32_bf16 v[4:7], v[180:183], v[224:227], 0
	v_mfma_f32_16x16x32_bf16 v[0:3], v[188:191], v[224:227], 0
	v_mfma_f32_16x16x32_bf16 v[52:55], v[184:187], v[200:203], v[52:55]
	v_mfma_f32_16x16x32_bf16 v[48:51], v[192:195], v[200:203], v[48:51]
	v_mfma_f32_16x16x32_bf16 v[36:39], v[184:187], v[212:215], v[36:39]
	v_mfma_f32_16x16x32_bf16 v[32:35], v[192:195], v[212:215], v[32:35]
	v_mfma_f32_16x16x32_bf16 v[20:23], v[184:187], v[220:223], v[20:23]
	v_mfma_f32_16x16x32_bf16 v[16:19], v[192:195], v[220:223], v[16:19]
	v_mfma_f32_16x16x32_bf16 v[4:7], v[184:187], v[228:231], v[4:7]
	v_mfma_f32_16x16x32_bf16 v[0:3], v[192:195], v[228:231], v[0:3]
	s_setprio 0
	s_barrier
	s_add_i32 s92, 0, 0x18000
	v_add_u32_e32 v167, s92, v161
	s_add_i32 s93, 0, 0x1c000
	ds_read_b128 v[146:149], v167
	ds_read_b128 v[168:171], v167 offset:1024
	ds_read_b128 v[172:175], v167 offset:2048
	ds_read_b128 v[176:179], v167 offset:3072
	v_add_u32_e32 v167, s93, v161
	ds_read_b128 v[180:183], v167
	ds_read_b128 v[184:187], v167 offset:1024
	ds_read_b128 v[188:191], v167 offset:2048
	ds_read_b128 v[192:195], v167 offset:3072
	s_add_u32 s58, s58, 0x40000
	s_addc_u32 s59, s59, 0
	s_mov_b32 m0, s69
	v_lshl_add_u64 v[236:237], s[58:59], 0, v[128:129]
	ds_read_b128 v[196:199], v165 offset:32768
	ds_read_b128 v[200:203], v165 offset:33792
	ds_read_b128 v[208:211], v165 offset:34816
	ds_read_b128 v[212:215], v165 offset:35840
	ds_read_b128 v[216:219], v165 offset:36864
	ds_read_b128 v[220:223], v165 offset:37888
	ds_read_b128 v[224:227], v165 offset:38912
	ds_read_b128 v[228:231], v165 offset:39936
	global_load_lds_dwordx4 v[236:237], off
	v_lshl_add_u64 v[236:237], s[58:59], 0, v[132:133]
	s_mov_b32 m0, s71
	s_nop 0
	global_load_lds_dwordx4 v[236:237], off
	s_waitcnt vmcnt(8)
	s_waitcnt lgkmcnt(0)
	s_barrier
	s_setprio 1
	s_waitcnt lgkmcnt(0)
	v_mfma_f32_16x16x32_bf16 v[124:127], v[146:149], v[196:199], v[124:127]
	v_mfma_f32_16x16x32_bf16 v[120:123], v[172:175], v[196:199], v[120:123]
	v_mfma_f32_16x16x32_bf16 v[108:111], v[146:149], v[208:211], v[108:111]
	v_mfma_f32_16x16x32_bf16 v[104:107], v[172:175], v[208:211], v[104:107]
	v_mfma_f32_16x16x32_bf16 v[92:95], v[146:149], v[216:219], v[92:95]
	v_mfma_f32_16x16x32_bf16 v[88:91], v[172:175], v[216:219], v[88:91]
	v_mfma_f32_16x16x32_bf16 v[76:79], v[146:149], v[224:227], v[76:79]
	v_mfma_f32_16x16x32_bf16 v[72:75], v[172:175], v[224:227], v[72:75]
	v_mfma_f32_16x16x32_bf16 v[124:127], v[168:171], v[200:203], v[124:127]
	v_mfma_f32_16x16x32_bf16 v[120:123], v[176:179], v[200:203], v[120:123]
	v_mfma_f32_16x16x32_bf16 v[108:111], v[168:171], v[212:215], v[108:111]
	v_mfma_f32_16x16x32_bf16 v[104:107], v[176:179], v[212:215], v[104:107]
	v_mfma_f32_16x16x32_bf16 v[92:95], v[168:171], v[220:223], v[92:95]
	v_mfma_f32_16x16x32_bf16 v[88:91], v[176:179], v[220:223], v[88:91]
	v_mfma_f32_16x16x32_bf16 v[76:79], v[168:171], v[228:231], v[76:79]
	v_mfma_f32_16x16x32_bf16 v[72:75], v[176:179], v[228:231], v[72:75]
	v_mfma_f32_16x16x32_bf16 v[116:119], v[180:183], v[196:199], v[116:119]
	v_mfma_f32_16x16x32_bf16 v[112:115], v[188:191], v[196:199], v[112:115]
	v_mfma_f32_16x16x32_bf16 v[100:103], v[180:183], v[208:211], v[100:103]
	v_mfma_f32_16x16x32_bf16 v[96:99], v[188:191], v[208:211], v[96:99]
	v_mfma_f32_16x16x32_bf16 v[84:87], v[180:183], v[216:219], v[84:87]
	v_mfma_f32_16x16x32_bf16 v[80:83], v[188:191], v[216:219], v[80:83]
	v_mfma_f32_16x16x32_bf16 v[68:71], v[180:183], v[224:227], v[68:71]
	v_mfma_f32_16x16x32_bf16 v[64:67], v[188:191], v[224:227], v[64:67]
	v_mfma_f32_16x16x32_bf16 v[116:119], v[184:187], v[200:203], v[116:119]
	v_mfma_f32_16x16x32_bf16 v[112:115], v[192:195], v[200:203], v[112:115]
	v_mfma_f32_16x16x32_bf16 v[100:103], v[184:187], v[212:215], v[100:103]
	v_mfma_f32_16x16x32_bf16 v[96:99], v[192:195], v[212:215], v[96:99]
	v_mfma_f32_16x16x32_bf16 v[84:87], v[184:187], v[220:223], v[84:87]
	v_mfma_f32_16x16x32_bf16 v[80:83], v[192:195], v[220:223], v[80:83]
	v_mfma_f32_16x16x32_bf16 v[68:71], v[184:187], v[228:231], v[68:71]
	v_mfma_f32_16x16x32_bf16 v[64:67], v[192:195], v[228:231], v[64:67]
	s_setprio 0
	s_barrier
; #define PG8_STAGE(bufoff, gbase, voff) do { _Pragma("unroll") for (int _i = 0; _i < 2; ++_i) \
;         __builtin_amdgcn_global_load_lds((const unsigned*)((const char*)(gbase) + (voff)[_i]), (PG8_LAS unsigned*)(lds + (bufoff) + ldsw + _i * 8192), 16, 0, 0); } while (0)
; #define PG8_LDA(dst, b, h) do { _Pragma("unroll") for (int m = 0; m < 4; ++m) _Pragma("unroll") for (int k = 0; k < 2; ++k) dst[m][k] = *(const PG8_LAS bf16x8*)(lds + PG8_SA(b, h) + aoff + m * 2048 + k * 1024); } while (0)
; #define PG8_LDB(dst, b, h) do { _Pragma("unroll") for (int n = 0; n < 2; ++n) _Pragma("unroll") for (int k = 0; k < 2; ++k) dst[n][k] = *(const PG8_LAS bf16x8*)(lds + PG8_SB(b, h) + boff + n * 2048 + k * 1024); } while (0)
; #define PG8_MMA(ai, bj, At, Bt) do { __builtin_amdgcn_s_setprio(1); _Pragma("unroll") for (int m = 0; m < 4; ++m) _Pragma("unroll") for (int n = 0; n < 2; ++n) _Pragma("unroll") for (int k = 0; k < 2; ++k) \
;         acc[ai][bj][m][n] = __builtin_amdgcn_mfma_f32_16x16x32_bf16(Bt[n][k], At[m][k], acc[ai][bj][m][n], 0, 0, 0); __builtin_amdgcn_s_setprio(0); } while (0)
; #define PG8_WAIT_V(n) asm volatile("s_waitcnt vmcnt(" #n ")" ::: "memory")
; template <class Epi, class Sched, bool ALIGN_EPI = false, bool SP2 = false>
; __device__ __forceinline__ void gemm_phase(PG8_LAS unsigned char* lds, const Gemm g, const Sched& S, const Epi& E) {
;     ...
;             PG8_LDB(B0, 0, 0); PG8_LDB(B1, 0, 1); PG8_SCHED; PG8_LDA(At, 0, 0); PG8_STAGE(PG8_SA(1, 1), a1 + hstep, voffA);
;             PG8_WAIT_V(8); PG8_WAIT_L(0); PG8_BAR; PG8_MMA(0, 0, At, B0); PG8_MMA(0, 1, At, B1); PG8_BAR; PG8_SCHED;
;             PG8_LDA(At, 0, 1); PG8_STAGE(PG8_SB(0, 0), b2, voffB); PG8_STAGE(PG8_SB(0, 1), b2 + hstep, voffB); PG8_STAGE(PG8_SA(0, 0), a2, voffA);
;             PG8_WAIT_V(8); PG8_WAIT_L(0); PG8_BAR; PG8_MMA(1, 0, At, B0); PG8_MMA(1, 1, At, B1); PG8_BAR; PG8_SCHED;
;             PG8_LDB(B0, 1, 0); PG8_LDB(B1, 1, 1); PG8_SCHED; PG8_LDA(At, 1, 0); PG8_STAGE(PG8_SA(0, 1), a2 + hstep, voffA);
;             PG8_WAIT_V(8); PG8_WAIT_L(0); PG8_BAR; PG8_MMA(0, 0, At, B0); PG8_MMA(0, 1, At, B1); PG8_BAR; PG8_SCHED;
;             PG8_LDA(At, 1, 1); PG8_STAGE(PG8_SB(1, 0), b3, voffB); PG8_STAGE(PG8_SB(1, 1), b3 + hstep, voffB); PG8_STAGE(PG8_SA(1, 0), a3, voffA);
;             PG8_WAIT_V(8); PG8_WAIT_L(0); PG8_BAR; PG8_MMA(1, 0, At, B0); PG8_MMA(1, 1, At, B1); PG8_BAR; PG8_SCHED;
	s_add_i32 s58, s92, s25
	v_lshl_add_u64 v[150:151], v[150:151], 0, s[20:21]
	s_mov_b32 m0, s58
	ds_read_b128 v[196:199], v165 offset:49152
	ds_read_b128 v[200:203], v165 offset:50176
	ds_read_b128 v[208:211], v165 offset:51200
	ds_read_b128 v[212:215], v165 offset:52224
	ds_read_b128 v[216:219], v165 offset:53248
	ds_read_b128 v[220:223], v165 offset:54272
	ds_read_b128 v[224:227], v165 offset:55296
	ds_read_b128 v[228:231], v165 offset:56320
	global_load_lds_dwordx4 v[150:151], off
	s_add_i32 m0, s58, 0x2000
	s_add_u32 s56, s56, 0x40080
	v_lshl_add_u64 v[150:151], v[204:205], 0, s[20:21]
	s_addc_u32 s57, s57, 0
	s_add_i32 s58, s93, s25
	global_load_lds_dwordx4 v[150:151], off
	v_lshl_add_u64 v[150:151], s[56:57], 0, v[130:131]
	s_mov_b32 m0, s58
	s_nop 0
	global_load_lds_dwordx4 v[150:151], off
	v_lshl_add_u64 v[150:151], s[56:57], 0, v[134:135]
	s_add_i32 m0, s58, 0x2000
	s_nop 0
	global_load_lds_dwordx4 v[150:151], off
	v_lshl_add_u64 v[150:151], v[232:233], 0, s[20:21]
	s_mov_b32 m0, s73
	s_nop 0
	global_load_lds_dwordx4 v[150:151], off
	v_lshl_add_u64 v[150:151], v[234:235], 0, s[20:21]
	s_mov_b32 m0, s74
	s_nop 0
	global_load_lds_dwordx4 v[150:151], off
	s_waitcnt vmcnt(8)
	s_waitcnt lgkmcnt(0)
	s_barrier
	s_setprio 1
	s_waitcnt lgkmcnt(0)
	v_mfma_f32_16x16x32_bf16 v[60:63], v[146:149], v[196:199], v[60:63]
	v_mfma_f32_16x16x32_bf16 v[56:59], v[172:175], v[196:199], v[56:59]
	v_mfma_f32_16x16x32_bf16 v[44:47], v[146:149], v[208:211], v[44:47]
	v_mfma_f32_16x16x32_bf16 v[40:43], v[172:175], v[208:211], v[40:43]
	v_mfma_f32_16x16x32_bf16 v[28:31], v[146:149], v[216:219], v[28:31]
	v_mfma_f32_16x16x32_bf16 v[24:27], v[172:175], v[216:219], v[24:27]
	v_mfma_f32_16x16x32_bf16 v[12:15], v[146:149], v[224:227], v[12:15]
	v_mfma_f32_16x16x32_bf16 v[8:11], v[172:175], v[224:227], v[8:11]
	v_mfma_f32_16x16x32_bf16 v[60:63], v[168:171], v[200:203], v[60:63]
	v_mfma_f32_16x16x32_bf16 v[56:59], v[176:179], v[200:203], v[56:59]
	v_mfma_f32_16x16x32_bf16 v[44:47], v[168:171], v[212:215], v[44:47]
	v_mfma_f32_16x16x32_bf16 v[40:43], v[176:179], v[212:215], v[40:43]
	v_mfma_f32_16x16x32_bf16 v[28:31], v[168:171], v[220:223], v[28:31]
	v_mfma_f32_16x16x32_bf16 v[24:27], v[176:179], v[220:223], v[24:27]
	v_mfma_f32_16x16x32_bf16 v[12:15], v[168:171], v[228:231], v[12:15]
	v_mfma_f32_16x16x32_bf16 v[8:11], v[176:179], v[228:231], v[8:11]
	v_mfma_f32_16x16x32_bf16 v[52:55], v[180:183], v[196:199], v[52:55]
	v_mfma_f32_16x16x32_bf16 v[48:51], v[188:191], v[196:199], v[48:51]
	v_mfma_f32_16x16x32_bf16 v[36:39], v[180:183], v[208:211], v[36:39]
	v_mfma_f32_16x16x32_bf16 v[32:35], v[188:191], v[208:211], v[32:35]
	v_mfma_f32_16x16x32_bf16 v[20:23], v[180:183], v[216:219], v[20:23]
	v_mfma_f32_16x16x32_bf16 v[16:19], v[188:191], v[216:219], v[16:19]
	v_mfma_f32_16x16x32_bf16 v[4:7], v[180:183], v[224:227], v[4:7]
	v_mfma_f32_16x16x32_bf16 v[0:3], v[188:191], v[224:227], v[0:3]
	v_mfma_f32_16x16x32_bf16 v[52:55], v[184:187], v[200:203], v[52:55]
	v_mfma_f32_16x16x32_bf16 v[48:51], v[192:195], v[200:203], v[48:51]
	v_mfma_f32_16x16x32_bf16 v[36:39], v[184:187], v[212:215], v[36:39]
	v_mfma_f32_16x16x32_bf16 v[32:35], v[192:195], v[212:215], v[32:35]
	v_mfma_f32_16x16x32_bf16 v[20:23], v[184:187], v[220:223], v[20:23]
	v_mfma_f32_16x16x32_bf16 v[16:19], v[192:195], v[220:223], v[16:19]
	v_mfma_f32_16x16x32_bf16 v[4:7], v[184:187], v[228:231], v[4:7]
	v_mfma_f32_16x16x32_bf16 v[0:3], v[192:195], v[228:231], v[0:3]
	s_setprio 0
	s_barrier
	s_add_i32 s83, s83, 2
	s_add_u32 s6, s6, 0x100
	s_addc_u32 s7, s7, 0
	s_add_u32 s61, s61, 0x100
	s_addc_u32 s82, s82, 0
	s_cmp_gt_u32 s83, 13
	s_cbranch_scc0 .LBB0_338
	s_branch .Lpeel_exit_1
.LBB0_338:
	ds_read_b128 v[146:149], v163
	ds_read_b128 v[168:171], v163 offset:1024
	ds_read_b128 v[172:175], v163 offset:2048
	ds_read_b128 v[176:179], v163 offset:3072
	ds_read_b128 v[180:183], v164
	ds_read_b128 v[184:187], v164 offset:1024
	ds_read_b128 v[188:191], v164 offset:2048
	ds_read_b128 v[192:195], v164 offset:3072
	s_add_u32 s56, s6, 0xfffc0080
	s_addc_u32 s57, s7, -1
	s_cmp_eq_u32 s83, 12
	s_cselect_b32 s59, s5, s57
	s_cselect_b32 s58, s29, s56
	s_cselect_b32 s57, s27, s82
	s_cselect_b32 s56, s60, s61
	v_lshl_add_u64 v[150:151], s[6:7], 0, v[140:141]
	s_add_i32 m0, s41, 0xc000
	ds_read_b128 v[196:199], v165
	ds_read_b128 v[200:203], v165 offset:1024
	ds_read_b128 v[208:211], v165 offset:2048
	ds_read_b128 v[212:215], v165 offset:3072
	ds_read_b128 v[216:219], v165 offset:4096
	ds_read_b128 v[220:223], v165 offset:5120
	ds_read_b128 v[224:227], v165 offset:6144
	ds_read_b128 v[228:231], v165 offset:7168
	global_load_lds_dwordx4 v[150:151], off
	v_lshl_add_u64 v[150:151], s[6:7], 0, v[142:143]
	s_add_i32 m0, s41, 0xe000
	s_nop 0
	global_load_lds_dwordx4 v[150:151], off
	s_waitcnt vmcnt(8)
	s_waitcnt lgkmcnt(0)
	s_barrier
; #define PG8_STAGE(bufoff, gbase, voff) do { _Pragma("unroll") for (int _i = 0; _i < 2; ++_i) \
;         __builtin_amdgcn_global_load_lds((const unsigned*)((const char*)(gbase) + (voff)[_i]), (PG8_LAS unsigned*)(lds + (bufoff) + ldsw + _i * 8192), 16, 0, 0); } while (0)
; #define PG8_LDA(dst, b, h) do { _Pragma("unroll") for (int m = 0; m < 4; ++m) _Pragma("unroll") for (int k = 0; k < 2; ++k) dst[m][k] = *(const PG8_LAS bf16x8*)(lds + PG8_SA(b, h) + aoff + m * 2048 + k * 1024); } while (0)
; #define PG8_LDB(dst, b, h) do { _Pragma("unroll") for (int n = 0; n < 2; ++n) _Pragma("unroll") for (int k = 0; k < 2; ++k) dst[n][k] = *(const PG8_LAS bf16x8*)(lds + PG8_SB(b, h) + boff + n * 2048 + k * 1024); } while (0)
; #define PG8_MMA(ai, bj, At, Bt) do { __builtin_amdgcn_s_setprio(1); _Pragma("unroll") for (int m = 0; m < 4; ++m) _Pragma("unroll") for (int n = 0; n < 2; ++n) _Pragma("unroll") for (int k = 0; k < 2; ++k) \
;         acc[ai][bj][m][n] = __builtin_amdgcn_mfma_f32_16x16x32_bf16(Bt[n][k], At[m][k], acc[ai][bj][m][n], 0, 0, 0); __builtin_amdgcn_s_setprio(0); } while (0)
; #define PG8_WAIT_V(n) asm volatile("s_waitcnt vmcnt(" #n ")" ::: "memory")
; #define PG8_WAIT_L(n) asm volatile("s_waitcnt lgkmcnt(" #n ")" ::: "memory")
; #define PG8_BAR __builtin_amdgcn_s_barrier()
; #define PG8_SCHED __builtin_amdgcn_sched_barrier(0)
; template <class Epi, class Sched, bool ALIGN_EPI = false, bool SP2 = false>
; __device__ __forceinline__ void gemm_phase(PG8_LAS unsigned char* lds, const Gemm g, const Sched& S, const Epi& E) {
;     ...
;             PG8_LDB(B0, 0, 0); PG8_LDB(B1, 0, 1); PG8_SCHED; PG8_LDA(At, 0, 0); PG8_STAGE(PG8_SA(1, 1), a1 + hstep, voffA);
;             PG8_WAIT_V(8); PG8_WAIT_L(0); PG8_BAR; PG8_MMA(0, 0, At, B0); PG8_MMA(0, 1, At, B1); PG8_BAR; PG8_SCHED;
;             PG8_LDA(At, 0, 1); PG8_STAGE(PG8_SB(0, 0), b2, voffB); PG8_STAGE(PG8_SB(0, 1), b2 + hstep, voffB); PG8_STAGE(PG8_SA(0, 0), a2, voffA);
;             PG8_WAIT_V(8); PG8_WAIT_L(0); PG8_BAR; PG8_MMA(1, 0, At, B0); PG8_MMA(1, 1, At, B1); PG8_BAR; PG8_SCHED;
	s_setprio 1
	s_waitcnt lgkmcnt(0)
	v_mfma_f32_16x16x32_bf16 v[124:127], v[146:149], v[196:199], v[124:127]
	v_mfma_f32_16x16x32_bf16 v[120:123], v[172:175], v[196:199], v[120:123]
	v_mfma_f32_16x16x32_bf16 v[108:111], v[146:149], v[208:211], v[108:111]
	v_mfma_f32_16x16x32_bf16 v[104:107], v[172:175], v[208:211], v[104:107]
	v_mfma_f32_16x16x32_bf16 v[92:95], v[146:149], v[216:219], v[92:95]
	v_mfma_f32_16x16x32_bf16 v[88:91], v[172:175], v[216:219], v[88:91]
	v_mfma_f32_16x16x32_bf16 v[76:79], v[146:149], v[224:227], v[76:79]
	v_mfma_f32_16x16x32_bf16 v[72:75], v[172:175], v[224:227], v[72:75]
	v_mfma_f32_16x16x32_bf16 v[124:127], v[168:171], v[200:203], v[124:127]
	v_mfma_f32_16x16x32_bf16 v[120:123], v[176:179], v[200:203], v[120:123]
	v_mfma_f32_16x16x32_bf16 v[108:111], v[168:171], v[212:215], v[108:111]
	v_mfma_f32_16x16x32_bf16 v[104:107], v[176:179], v[212:215], v[104:107]
	v_mfma_f32_16x16x32_bf16 v[92:95], v[168:171], v[220:223], v[92:95]
	v_mfma_f32_16x16x32_bf16 v[88:91], v[176:179], v[220:223], v[88:91]
	v_mfma_f32_16x16x32_bf16 v[76:79], v[168:171], v[228:231], v[76:79]
	v_mfma_f32_16x16x32_bf16 v[72:75], v[176:179], v[228:231], v[72:75]
	v_mfma_f32_16x16x32_bf16 v[116:119], v[180:183], v[196:199], v[116:119]
	v_mfma_f32_16x16x32_bf16 v[112:115], v[188:191], v[196:199], v[112:115]
	v_mfma_f32_16x16x32_bf16 v[100:103], v[180:183], v[208:211], v[100:103]
	v_mfma_f32_16x16x32_bf16 v[96:99], v[188:191], v[208:211], v[96:99]
	v_mfma_f32_16x16x32_bf16 v[84:87], v[180:183], v[216:219], v[84:87]
	v_mfma_f32_16x16x32_bf16 v[80:83], v[188:191], v[216:219], v[80:83]
	v_mfma_f32_16x16x32_bf16 v[68:71], v[180:183], v[224:227], v[68:71]
	v_mfma_f32_16x16x32_bf16 v[64:67], v[188:191], v[224:227], v[64:67]
	v_mfma_f32_16x16x32_bf16 v[116:119], v[184:187], v[200:203], v[116:119]
	v_mfma_f32_16x16x32_bf16 v[112:115], v[192:195], v[200:203], v[112:115]
	v_mfma_f32_16x16x32_bf16 v[100:103], v[184:187], v[212:215], v[100:103]
	v_mfma_f32_16x16x32_bf16 v[96:99], v[192:195], v[212:215], v[96:99]
	v_mfma_f32_16x16x32_bf16 v[84:87], v[184:187], v[220:223], v[84:87]
	v_mfma_f32_16x16x32_bf16 v[80:83], v[192:195], v[220:223], v[80:83]
	v_mfma_f32_16x16x32_bf16 v[68:71], v[184:187], v[228:231], v[68:71]
	v_mfma_f32_16x16x32_bf16 v[64:67], v[192:195], v[228:231], v[64:67]
	s_setprio 0
	s_barrier
	s_add_i32 s92, s79, s25
	v_lshl_add_u64 v[150:151], s[56:57], 0, v[130:131]
	s_mov_b32 m0, s92
	ds_read_b128 v[196:199], v165 offset:16384
	ds_read_b128 v[200:203], v165 offset:17408
	ds_read_b128 v[208:211], v165 offset:18432
	ds_read_b128 v[212:215], v165 offset:19456
	ds_read_b128 v[216:219], v165 offset:20480
	ds_read_b128 v[220:223], v165 offset:21504
	ds_read_b128 v[224:227], v165 offset:22528
	ds_read_b128 v[228:231], v165 offset:23552
	global_load_lds_dwordx4 v[150:151], off
	s_add_i32 m0, s92, 0x2000
	s_add_u32 s92, s56, 0x40000
	v_lshl_add_u64 v[204:205], s[56:57], 0, v[134:135]
	s_addc_u32 s93, s57, 0
	s_add_i32 s94, s80, s25
	global_load_lds_dwordx4 v[204:205], off
	v_lshl_add_u64 v[232:233], s[92:93], 0, v[130:131]
	s_mov_b32 m0, s94
	v_lshl_add_u64 v[234:235], s[58:59], 0, v[132:133]
	global_load_lds_dwordx4 v[232:233], off
	v_lshl_add_u64 v[232:233], s[92:93], 0, v[134:135]
	s_add_i32 m0, s94, 0x2000
	s_nop 0
	global_load_lds_dwordx4 v[232:233], off
	v_lshl_add_u64 v[232:233], s[58:59], 0, v[128:129]
	s_mov_b32 m0, s41
	s_nop 0
	global_load_lds_dwordx4 v[232:233], off
	s_mov_b32 m0, s68
	s_nop 0
	global_load_lds_dwordx4 v[234:235], off
	s_waitcnt vmcnt(8)
	s_waitcnt lgkmcnt(0)
	s_barrier
	s_setprio 1
	s_waitcnt lgkmcnt(0)
	v_mfma_f32_16x16x32_bf16 v[60:63], v[146:149], v[196:199], v[60:63]
	v_mfma_f32_16x16x32_bf16 v[56:59], v[172:175], v[196:199], v[56:59]
	v_mfma_f32_16x16x32_bf16 v[44:47], v[146:149], v[208:211], v[44:47]
	v_mfma_f32_16x16x32_bf16 v[40:43], v[172:175], v[208:211], v[40:43]
	v_mfma_f32_16x16x32_bf16 v[28:31], v[146:149], v[216:219], v[28:31]
	v_mfma_f32_16x16x32_bf16 v[24:27], v[172:175], v[216:219], v[24:27]
	v_mfma_f32_16x16x32_bf16 v[12:15], v[146:149], v[224:227], v[12:15]
	v_mfma_f32_16x16x32_bf16 v[8:11], v[172:175], v[224:227], v[8:11]
	v_mfma_f32_16x16x32_bf16 v[60:63], v[168:171], v[200:203], v[60:63]
	v_mfma_f32_16x16x32_bf16 v[56:59], v[176:179], v[200:203], v[56:59]
	v_mfma_f32_16x16x32_bf16 v[44:47], v[168:171], v[212:215], v[44:47]
	v_mfma_f32_16x16x32_bf16 v[40:43], v[176:179], v[212:215], v[40:43]
	v_mfma_f32_16x16x32_bf16 v[28:31], v[168:171], v[220:223], v[28:31]
	v_mfma_f32_16x16x32_bf16 v[24:27], v[176:179], v[220:223], v[24:27]
	v_mfma_f32_16x16x32_bf16 v[12:15], v[168:171], v[228:231], v[12:15]
	v_mfma_f32_16x16x32_bf16 v[8:11], v[176:179], v[228:231], v[8:11]
	v_mfma_f32_16x16x32_bf16 v[52:55], v[180:183], v[196:199], v[52:55]
	v_mfma_f32_16x16x32_bf16 v[48:51], v[188:191], v[196:199], v[48:51]
	v_mfma_f32_16x16x32_bf16 v[36:39], v[180:183], v[208:211], v[36:39]
	v_mfma_f32_16x16x32_bf16 v[32:35], v[188:191], v[208:211], v[32:35]
	v_mfma_f32_16x16x32_bf16 v[20:23], v[180:183], v[216:219], v[20:23]
	v_mfma_f32_16x16x32_bf16 v[16:19], v[188:191], v[216:219], v[16:19]
	v_mfma_f32_16x16x32_bf16 v[4:7], v[180:183], v[224:227], v[4:7]
	v_mfma_f32_16x16x32_bf16 v[0:3], v[188:191], v[224:227], v[0:3]
	v_mfma_f32_16x16x32_bf16 v[52:55], v[184:187], v[200:203], v[52:55]
	v_mfma_f32_16x16x32_bf16 v[48:51], v[192:195], v[200:203], v[48:51]
	v_mfma_f32_16x16x32_bf16 v[36:39], v[184:187], v[212:215], v[36:39]
	v_mfma_f32_16x16x32_bf16 v[32:35], v[192:195], v[212:215], v[32:35]
	v_mfma_f32_16x16x32_bf16 v[20:23], v[184:187], v[220:223], v[20:23]
	v_mfma_f32_16x16x32_bf16 v[16:19], v[192:195], v[220:223], v[16:19]
	v_mfma_f32_16x16x32_bf16 v[4:7], v[184:187], v[228:231], v[4:7]
	v_mfma_f32_16x16x32_bf16 v[0:3], v[192:195], v[228:231], v[0:3]
	s_setprio 0
	s_barrier
; #define PG8_STAGE(bufoff, gbase, voff) do { _Pragma("unroll") for (int _i = 0; _i < 2; ++_i) \
;         __builtin_amdgcn_global_load_lds((const unsigned*)((const char*)(gbase) + (voff)[_i]), (PG8_LAS unsigned*)(lds + (bufoff) + ldsw + _i * 8192), 16, 0, 0); } while (0)
; #define PG8_LDA(dst, b, h) do { _Pragma("unroll") for (int m = 0; m < 4; ++m) _Pragma("unroll") for (int k = 0; k < 2; ++k) dst[m][k] = *(const PG8_LAS bf16x8*)(lds + PG8_SA(b, h) + aoff + m * 2048 + k * 1024); } while (0)
; #define PG8_LDB(dst, b, h) do { _Pragma("unroll") for (int n = 0; n < 2; ++n) _Pragma("unroll") for (int k = 0; k < 2; ++k) dst[n][k] = *(const PG8_LAS bf16x8*)(lds + PG8_SB(b, h) + boff + n * 2048 + k * 1024); } while (0)
; #define PG8_MMA(ai, bj, At, Bt) do { __builtin_amdgcn_s_setprio(1); _Pragma("unroll") for (int m = 0; m < 4; ++m) _Pragma("unroll") for (int n = 0; n < 2; ++n) _Pragma("unroll") for (int k = 0; k < 2; ++k) \
;         acc[ai][bj][m][n] = __builtin_amdgcn_mfma_f32_16x16x32_bf16(Bt[n][k], At[m][k], acc[ai][bj][m][n], 0, 0, 0); __builtin_amdgcn_s_setprio(0); } while (0)
; #define PG8_WAIT_V(n) asm volatile("s_waitcnt vmcnt(" #n ")" ::: "memory")
; #define PG8_WAIT_L(n) asm volatile("s_waitcnt lgkmcnt(" #n ")" ::: "memory")
; #define PG8_BAR __builtin_amdgcn_s_barrier()
; #define PG8_SCHED __builtin_amdgcn_sched_barrier(0)
; template <class Epi, class Sched, bool ALIGN_EPI = false, bool SP2 = false>
; __device__ __forceinline__ void gemm_phase(PG8_LAS unsigned char* lds, const Gemm g, const Sched& S, const Epi& E) {
;     ...
;             PG8_LDB(B0, 1, 0); PG8_LDB(B1, 1, 1); PG8_SCHED; PG8_LDA(At, 1, 0); PG8_STAGE(PG8_SA(0, 1), a2 + hstep, voffA);
;             PG8_WAIT_V(8); PG8_WAIT_L(0); PG8_BAR; PG8_MMA(0, 0, At, B0); PG8_MMA(0, 1, At, B1); PG8_BAR; PG8_SCHED;
	s_add_i32 s92, 0, 0x18000
	v_add_u32_e32 v167, s92, v161
	s_add_i32 s93, 0, 0x1c000
	ds_read_b128 v[146:149], v167
	ds_read_b128 v[168:171], v167 offset:1024
	ds_read_b128 v[172:175], v167 offset:2048
	ds_read_b128 v[176:179], v167 offset:3072
	v_add_u32_e32 v167, s93, v161
	ds_read_b128 v[180:183], v167
	ds_read_b128 v[184:187], v167 offset:1024
	ds_read_b128 v[188:191], v167 offset:2048
	ds_read_b128 v[192:195], v167 offset:3072
	s_add_u32 s58, s58, 0x40000
	s_addc_u32 s59, s59, 0
	s_mov_b32 m0, s69
	v_lshl_add_u64 v[236:237], s[58:59], 0, v[128:129]
	ds_read_b128 v[196:199], v165 offset:32768
	ds_read_b128 v[200:203], v165 offset:33792
	ds_read_b128 v[208:211], v165 offset:34816
	ds_read_b128 v[212:215], v165 offset:35840
	ds_read_b128 v[216:219], v165 offset:36864
	ds_read_b128 v[220:223], v165 offset:37888
	ds_read_b128 v[224:227], v165 offset:38912
	ds_read_b128 v[228:231], v165 offset:39936
	global_load_lds_dwordx4 v[236:237], off
	v_lshl_add_u64 v[236:237], s[58:59], 0, v[132:133]
	s_mov_b32 m0, s71
	s_nop 0
	global_load_lds_dwordx4 v[236:237], off
	s_waitcnt vmcnt(8)
	s_waitcnt lgkmcnt(0)
	s_barrier
	s_setprio 1
	s_waitcnt lgkmcnt(0)
	v_mfma_f32_16x16x32_bf16 v[124:127], v[146:149], v[196:199], v[124:127]
	v_mfma_f32_16x16x32_bf16 v[120:123], v[172:175], v[196:199], v[120:123]
	v_mfma_f32_16x16x32_bf16 v[108:111], v[146:149], v[208:211], v[108:111]
	v_mfma_f32_16x16x32_bf16 v[104:107], v[172:175], v[208:211], v[104:107]
	v_mfma_f32_16x16x32_bf16 v[92:95], v[146:149], v[216:219], v[92:95]
	v_mfma_f32_16x16x32_bf16 v[88:91], v[172:175], v[216:219], v[88:91]
	v_mfma_f32_16x16x32_bf16 v[76:79], v[146:149], v[224:227], v[76:79]
	v_mfma_f32_16x16x32_bf16 v[72:75], v[172:175], v[224:227], v[72:75]
	v_mfma_f32_16x16x32_bf16 v[124:127], v[168:171], v[200:203], v[124:127]
	v_mfma_f32_16x16x32_bf16 v[120:123], v[176:179], v[200:203], v[120:123]
	v_mfma_f32_16x16x32_bf16 v[108:111], v[168:171], v[212:215], v[108:111]
	v_mfma_f32_16x16x32_bf16 v[104:107], v[176:179], v[212:215], v[104:107]
	v_mfma_f32_16x16x32_bf16 v[92:95], v[168:171], v[220:223], v[92:95]
	v_mfma_f32_16x16x32_bf16 v[88:91], v[176:179], v[220:223], v[88:91]
	v_mfma_f32_16x16x32_bf16 v[76:79], v[168:171], v[228:231], v[76:79]
	v_mfma_f32_16x16x32_bf16 v[72:75], v[176:179], v[228:231], v[72:75]
	v_mfma_f32_16x16x32_bf16 v[116:119], v[180:183], v[196:199], v[116:119]
	v_mfma_f32_16x16x32_bf16 v[112:115], v[188:191], v[196:199], v[112:115]
	v_mfma_f32_16x16x32_bf16 v[100:103], v[180:183], v[208:211], v[100:103]
	v_mfma_f32_16x16x32_bf16 v[96:99], v[188:191], v[208:211], v[96:99]
	v_mfma_f32_16x16x32_bf16 v[84:87], v[180:183], v[216:219], v[84:87]
	v_mfma_f32_16x16x32_bf16 v[80:83], v[188:191], v[216:219], v[80:83]
	v_mfma_f32_16x16x32_bf16 v[68:71], v[180:183], v[224:227], v[68:71]
	v_mfma_f32_16x16x32_bf16 v[64:67], v[188:191], v[224:227], v[64:67]
	v_mfma_f32_16x16x32_bf16 v[116:119], v[184:187], v[200:203], v[116:119]
	v_mfma_f32_16x16x32_bf16 v[112:115], v[192:195], v[200:203], v[112:115]
	v_mfma_f32_16x16x32_bf16 v[100:103], v[184:187], v[212:215], v[100:103]
	v_mfma_f32_16x16x32_bf16 v[96:99], v[192:195], v[212:215], v[96:99]
	v_mfma_f32_16x16x32_bf16 v[84:87], v[184:187], v[220:223], v[84:87]
	v_mfma_f32_16x16x32_bf16 v[80:83], v[192:195], v[220:223], v[80:83]
	v_mfma_f32_16x16x32_bf16 v[68:71], v[184:187], v[228:231], v[68:71]
	v_mfma_f32_16x16x32_bf16 v[64:67], v[192:195], v[228:231], v[64:67]
	s_setprio 0
	s_barrier
; #define PG8_STAGE(bufoff, gbase, voff) do { _Pragma("unroll") for (int _i = 0; _i < 2; ++_i) \
;         __builtin_amdgcn_global_load_lds((const unsigned*)((const char*)(gbase) + (voff)[_i]), (PG8_LAS unsigned*)(lds + (bufoff) + ldsw + _i * 8192), 16, 0, 0); } while (0)
; #define PG8_LDA(dst, b, h) do { _Pragma("unroll") for (int m = 0; m < 4; ++m) _Pragma("unroll") for (int k = 0; k < 2; ++k) dst[m][k] = *(const PG8_LAS bf16x8*)(lds + PG8_SA(b, h) + aoff + m * 2048 + k * 1024); } while (0)
; #define PG8_MMA(ai, bj, At, Bt) do { __builtin_amdgcn_s_setprio(1); _Pragma("unroll") for (int m = 0; m < 4; ++m) _Pragma("unroll") for (int n = 0; n < 2; ++n) _Pragma("unroll") for (int k = 0; k < 2; ++k) \
;         acc[ai][bj][m][n] = __builtin_amdgcn_mfma_f32_16x16x32_bf16(Bt[n][k], At[m][k], acc[ai][bj][m][n], 0, 0, 0); __builtin_amdgcn_s_setprio(0); } while (0)
; #define PG8_WAIT_V(n) asm volatile("s_waitcnt vmcnt(" #n ")" ::: "memory")
; #define PG8_WAIT_L(n) asm volatile("s_waitcnt lgkmcnt(" #n ")" ::: "memory")
; #define PG8_BAR __builtin_amdgcn_s_barrier()
; #define PG8_SCHED __builtin_amdgcn_sched_barrier(0)
; template <class Epi, class Sched, bool ALIGN_EPI = false, bool SP2 = false>
; __device__ __forceinline__ void gemm_phase(PG8_LAS unsigned char* lds, const Gemm g, const Sched& S, const Epi& E) {
;     ...
;             PG8_LDA(At, 1, 1); PG8_STAGE(PG8_SB(1, 0), b3, voffB); PG8_STAGE(PG8_SB(1, 1), b3 + hstep, voffB); PG8_STAGE(PG8_SA(1, 0), a3, voffA);
;             PG8_WAIT_V(8); PG8_WAIT_L(0); PG8_BAR; PG8_MMA(1, 0, At, B0); PG8_MMA(1, 1, At, B1); PG8_BAR; PG8_SCHED;
	s_add_i32 s58, s92, s25
	v_lshl_add_u64 v[150:151], v[150:151], 0, s[20:21]
	s_mov_b32 m0, s58
	ds_read_b128 v[196:199], v165 offset:49152
	ds_read_b128 v[200:203], v165 offset:50176
	ds_read_b128 v[208:211], v165 offset:51200
	ds_read_b128 v[212:215], v165 offset:52224
	ds_read_b128 v[216:219], v165 offset:53248
	ds_read_b128 v[220:223], v165 offset:54272
	ds_read_b128 v[224:227], v165 offset:55296
	ds_read_b128 v[228:231], v165 offset:56320
	global_load_lds_dwordx4 v[150:151], off
	s_add_i32 m0, s58, 0x2000
	s_add_u32 s56, s56, 0x40080
	v_lshl_add_u64 v[150:151], v[204:205], 0, s[20:21]
	s_addc_u32 s57, s57, 0
	s_add_i32 s58, s93, s25
	global_load_lds_dwordx4 v[150:151], off
	v_lshl_add_u64 v[150:151], s[56:57], 0, v[130:131]
	s_mov_b32 m0, s58
	s_nop 0
	global_load_lds_dwordx4 v[150:151], off
	v_lshl_add_u64 v[150:151], s[56:57], 0, v[134:135]
	s_add_i32 m0, s58, 0x2000
	s_nop 0
	global_load_lds_dwordx4 v[150:151], off
	v_lshl_add_u64 v[150:151], v[232:233], 0, s[20:21]
	s_mov_b32 m0, s73
	s_nop 0
	global_load_lds_dwordx4 v[150:151], off
	v_lshl_add_u64 v[150:151], v[234:235], 0, s[20:21]
	s_mov_b32 m0, s74
	s_nop 0
	global_load_lds_dwordx4 v[150:151], off
	s_waitcnt vmcnt(8)
	s_waitcnt lgkmcnt(0)
	s_barrier
	s_setprio 1
	s_waitcnt lgkmcnt(0)
	v_mfma_f32_16x16x32_bf16 v[60:63], v[146:149], v[196:199], v[60:63]
	v_mfma_f32_16x16x32_bf16 v[56:59], v[172:175], v[196:199], v[56:59]
	v_mfma_f32_16x16x32_bf16 v[44:47], v[146:149], v[208:211], v[44:47]
	v_mfma_f32_16x16x32_bf16 v[40:43], v[172:175], v[208:211], v[40:43]
	v_mfma_f32_16x16x32_bf16 v[28:31], v[146:149], v[216:219], v[28:31]
	v_mfma_f32_16x16x32_bf16 v[24:27], v[172:175], v[216:219], v[24:27]
	v_mfma_f32_16x16x32_bf16 v[12:15], v[146:149], v[224:227], v[12:15]
	v_mfma_f32_16x16x32_bf16 v[8:11], v[172:175], v[224:227], v[8:11]
	v_mfma_f32_16x16x32_bf16 v[60:63], v[168:171], v[200:203], v[60:63]
	v_mfma_f32_16x16x32_bf16 v[56:59], v[176:179], v[200:203], v[56:59]
	v_mfma_f32_16x16x32_bf16 v[44:47], v[168:171], v[212:215], v[44:47]
	v_mfma_f32_16x16x32_bf16 v[40:43], v[176:179], v[212:215], v[40:43]
	v_mfma_f32_16x16x32_bf16 v[28:31], v[168:171], v[220:223], v[28:31]
	v_mfma_f32_16x16x32_bf16 v[24:27], v[176:179], v[220:223], v[24:27]
	v_mfma_f32_16x16x32_bf16 v[12:15], v[168:171], v[228:231], v[12:15]
	v_mfma_f32_16x16x32_bf16 v[8:11], v[176:179], v[228:231], v[8:11]
	v_mfma_f32_16x16x32_bf16 v[52:55], v[180:183], v[196:199], v[52:55]
	v_mfma_f32_16x16x32_bf16 v[48:51], v[188:191], v[196:199], v[48:51]
	v_mfma_f32_16x16x32_bf16 v[36:39], v[180:183], v[208:211], v[36:39]
	v_mfma_f32_16x16x32_bf16 v[32:35], v[188:191], v[208:211], v[32:35]
	v_mfma_f32_16x16x32_bf16 v[20:23], v[180:183], v[216:219], v[20:23]
	v_mfma_f32_16x16x32_bf16 v[16:19], v[188:191], v[216:219], v[16:19]
	v_mfma_f32_16x16x32_bf16 v[4:7], v[180:183], v[224:227], v[4:7]
	v_mfma_f32_16x16x32_bf16 v[0:3], v[188:191], v[224:227], v[0:3]
	v_mfma_f32_16x16x32_bf16 v[52:55], v[184:187], v[200:203], v[52:55]
	v_mfma_f32_16x16x32_bf16 v[48:51], v[192:195], v[200:203], v[48:51]
	v_mfma_f32_16x16x32_bf16 v[36:39], v[184:187], v[212:215], v[36:39]
	v_mfma_f32_16x16x32_bf16 v[32:35], v[192:195], v[212:215], v[32:35]
	v_mfma_f32_16x16x32_bf16 v[20:23], v[184:187], v[220:223], v[20:23]
	v_mfma_f32_16x16x32_bf16 v[16:19], v[192:195], v[220:223], v[16:19]
	v_mfma_f32_16x16x32_bf16 v[4:7], v[184:187], v[228:231], v[4:7]
	v_mfma_f32_16x16x32_bf16 v[0:3], v[192:195], v[228:231], v[0:3]
	s_setprio 0
	s_barrier
	s_add_i32 s83, s83, 2
	s_add_u32 s6, s6, 0x100
	s_addc_u32 s7, s7, 0
	s_add_u32 s61, s61, 0x100
	s_addc_u32 s82, s82, 0
	s_cmp_gt_u32 s83, 13
	s_cbranch_scc0 .LBB0_338

;     __device__ __forceinline__ bool next(int i, Unit& u) const { if (i != 0) return false; const int c0 = (G >= 8) ? G - 5 : G - 2; int k = -1; if (c == c0) k = 0; else if (c == G - 1) k = 1; if (k < 0 || k >= n) return false; u.pm = k; u.pn = 0; return true; }
; #define PG8_STAGE(bufoff, gbase, voff) do { _Pragma("unroll") for (int _i = 0; _i < 2; ++_i) \
;         __builtin_amdgcn_global_load_lds((const unsigned*)((const char*)(gbase) + (voff)[_i]), (PG8_LAS unsigned*)(lds + (bufoff) + ldsw + _i * 8192), 16, 0, 0); } while (0)
; #define PG8_WAIT_V(n) asm volatile("s_waitcnt vmcnt(" #n ")" ::: "memory")
; template <class Epi, class Sched, bool ALIGN_EPI = false, bool SP2 = false>
; __device__ __forceinline__ void gemm_phase(PG8_LAS unsigned char* lds, const Gemm g, const Sched& S, const Epi& E) {
;     ...
;         PG8_WAIT_V(2); PG8_BAR;
;         PG8_STAGE(PG8_SB(1, 0), cB + kstep, voffB); PG8_STAGE(PG8_SA(1, 0), cA + kstep, voffA); PG8_STAGE(PG8_SB(1, 1), cB + hstep + kstep, voffB);
;         PG8_WAIT_V(6); PG8_BAR;
;     } else {
;         PG8_STAGE(PG8_SB(0, 0), cB, voffB); PG8_STAGE(PG8_SA(0, 0), cA, voffA); PG8_STAGE(PG8_SB(0, 1), cB + hstep, voffB); PG8_STAGE(PG8_SA(0, 1), cA + hstep, voffA);
;         if (wr == 1) PG8_BAR;
;         PG8_WAIT_V(4); PG8_BAR;
;         PG8_STAGE(PG8_SB(1, 0), cB + kstep, voffB); PG8_STAGE(PG8_SA(1, 0), cA + kstep, voffA); PG8_STAGE(PG8_SB(1, 1), cB + hstep + kstep, voffB);
;         PG8_WAIT_V(6); PG8_BAR;
;     }
;     for (;;) {
;         const bool has_next = S.next(ui + 1, nxt);
;         const char* nA = has_next ? (const char*)g.A + (size_t)nxt.pm * tstep : cA; const char* nB = has_next ? (const char*)g.Bt + (size_t)nxt.pn * tstep : cB;
;         for (int t = 0; t < nt; t += 2) {
;             const bool last = (t == nt - 2);
;             const char* a1 = cA + (size_t)(t + 1) * kstep;
;             const char* a2 = last ? nA : cA + (size_t)(t + 2) * kstep; const char* b2 = last ? nB : cB + (size_t)(t + 2) * kstep;
;             const char* a3 = a2 + kstep; const char* b3 = b2 + kstep;
;             if (last && has_next) S.a_ready(nxt);
;             if constexpr (SP2) {
;             PG8_LDB(B0, 0, 0); PG8_LDB(B1, 0, 1); PG8_SCHED; PG8_LDA(At, 0, 0); PG8_STAGE(PG8_SA(1, 1), a1 + hstep, voffA);
;             PG8_WAIT_V(8); PG8_WAIT_L(0); PG8_BAR; PG8_MMA(0, 0, At, B0); PG8_MMA(0, 1, At, B1); PG8_BAR; PG8_SCHED;
.LBB0_396:
	s_lshl_b32 s14, s14, 5
	v_lshlrev_b32_e32 v4, 1, v152
	s_and_b32 s40, s14, 0x60
	v_lshl_or_b32 v140, s15, 6, v158
	v_lshl_or_b32 v5, v158, 6, v4
	s_lshl_b32 s15, s15, 13
	v_lshlrev_b32_e32 v6, 2, v158
	v_or_b32_e32 v4, v4, v157
	s_lshl_b32 s14, s40, 7
	v_and_b32_e32 v6, 32, v6
	v_bitop3_b32 v7, s14, v4, v159 bitop3:0xf6
	s_add_u32 s14, s50, 0x300080
	v_bitop3_b32 v6, v5, s15, v6 bitop3:0xde
	s_addc_u32 s15, s51, 0
	s_add_i32 m0, s5, 0x18000
	v_lshl_add_u64 v[4:5], s[14:15], 0, v[130:131]
	s_waitcnt vmcnt(2)
	s_barrier
	global_load_lds_dwordx4 v[4:5], off
	v_lshl_add_u64 v[4:5], s[14:15], 0, v[134:135]
	s_add_i32 m0, s5, 0x1a000
	s_mov_b64 s[14:15], 0x80
	s_add_i32 s41, s5, 0x8000
	s_add_i32 s42, s5, 0xa000
	global_load_lds_dwordx4 v[4:5], off
	v_lshl_add_u64 v[2:3], v[2:3], 0, s[14:15]
	s_mov_b32 m0, s41
	s_add_u32 s22, s50, 0x340080
	global_load_lds_dwordx4 v[2:3], off
	v_lshl_add_u64 v[0:1], v[0:1], 0, s[14:15]
	s_mov_b32 m0, s42
	s_addc_u32 s23, s51, 0
	global_load_lds_dwordx4 v[0:1], off
	s_add_i32 m0, s5, 0x1c000
	v_lshl_add_u64 v[0:1], s[22:23], 0, v[130:131]
	global_load_lds_dwordx4 v[0:1], off
	v_lshl_add_u64 v[0:1], s[22:23], 0, v[134:135]
	s_add_i32 m0, s5, 0x1e000
	v_lshlrev_b32_e32 v2, 11, v155
	global_load_lds_dwordx4 v[0:1], off
	v_lshlrev_b32_e32 v0, 8, v206
	v_and_b32_e32 v0, 0x38000, v0
	s_add_u32 s20, s50, s20
	v_or3_b32 v0, v153, v0, v2
	s_addc_u32 s21, s51, s21
	v_add_u32_e32 v0, v0, v154
	v_mov_b32_e32 v1, v131
	v_lshl_add_u64 v[0:1], s[20:21], 0, v[0:1]
	s_mov_b64 s[22:23], 0x7440080
	v_lshl_add_u64 v[136:137], v[0:1], 0, s[22:23]
	v_lshlrev_b32_e32 v0, 4, v156
	v_and_b32_e32 v0, 0x78000, v0
	v_or3_b32 v0, v153, v0, v2
	s_waitcnt vmcnt(6)
	v_add_u32_e32 v0, v0, v154
	v_mov_b32_e32 v1, v131
	s_add_i32 s56, 0, 0x10000
	s_add_i32 s58, 0, 0x14000
	s_add_i32 s60, 0, 0x18000
	s_add_i32 s68, 0, 0x1c000
	v_lshl_add_u64 v[0:1], s[20:21], 0, v[0:1]
	v_add_u32_e32 v141, s56, v7
	v_add_u32_e32 v142, s58, v7
	s_add_i32 s56, s56, s24
	s_add_i32 s58, s58, s24
	v_add_u32_e32 v144, s60, v7
	v_add_u32_e32 v145, s68, v7
	s_add_i32 s60, s60, s24
	s_add_i32 s68, s68, s24
	v_lshl_add_u64 v[138:139], v[0:1], 0, s[22:23]
	s_mov_b32 s43, -2
	s_mov_b64 s[22:23], 0
	v_add_u32_e32 v143, 0, v6
	s_add_i32 s46, s5, 0xc000
	s_add_i32 s47, s5, 0xe000
	s_add_i32 s57, s56, 0x2000
	s_add_i32 s59, s58, 0x2000
	s_add_i32 s61, s60, 0x2000
	s_add_i32 s69, s68, 0x2000
	s_barrier
	ds_read_b128 v[146:149], v141
	ds_read_b128 v[154:157], v141 offset:1024
	ds_read_b128 v[158:161], v141 offset:2048
	ds_read_b128 v[162:165], v141 offset:3072
	ds_read_b128 v[166:169], v142
	ds_read_b128 v[170:173], v142 offset:1024
	ds_read_b128 v[174:177], v142 offset:2048
	ds_read_b128 v[178:181], v142 offset:3072
	s_add_u32 s24, s20, s22
	s_addc_u32 s25, s21, s23
	s_add_u32 s24, s24, 0x7400100
	s_addc_u32 s25, s25, 0
	s_add_u32 s26, s50, s22
	s_addc_u32 s27, s51, s23
	s_add_u32 s71, s26, 0x300100
	s_addc_u32 s72, s27, 0
	s_cmpk_eq_i32 s22, 0x700
	s_cselect_b32 s27, s9, s25
	s_cselect_b32 s26, s8, s24
	s_cselect_b32 s25, s7, s72
	s_cselect_b32 s24, s6, s71
	s_mov_b32 m0, s46
	v_lshl_add_u64 v[150:151], v[136:137], 0, s[22:23]
	ds_read_b128 v[182:185], v143
	ds_read_b128 v[186:189], v143 offset:1024
	ds_read_b128 v[190:193], v143 offset:2048
	ds_read_b128 v[194:197], v143 offset:3072
	ds_read_b128 v[198:201], v143 offset:4096
	ds_read_b128 v[202:205], v143 offset:5120
	ds_read_b128 v[208:211], v143 offset:6144
	ds_read_b128 v[212:215], v143 offset:7168
	global_load_lds_dwordx4 v[150:151], off
	v_lshl_add_u64 v[150:151], v[138:139], 0, s[22:23]
	s_mov_b32 m0, s47
	s_nop 0
	global_load_lds_dwordx4 v[150:151], off
	s_waitcnt vmcnt(8)
	s_waitcnt lgkmcnt(0)
	s_barrier
	s_setprio 1
	s_waitcnt lgkmcnt(0)
	v_mfma_f32_16x16x32_bf16 v[124:127], v[146:149], v[182:185], 0
	v_mfma_f32_16x16x32_bf16 v[120:123], v[158:161], v[182:185], 0
	v_mfma_f32_16x16x32_bf16 v[116:119], v[146:149], v[190:193], 0
	v_mfma_f32_16x16x32_bf16 v[112:115], v[158:161], v[190:193], 0
	v_mfma_f32_16x16x32_bf16 v[100:103], v[146:149], v[198:201], 0
	v_mfma_f32_16x16x32_bf16 v[96:99], v[158:161], v[198:201], 0
	v_mfma_f32_16x16x32_bf16 v[84:87], v[146:149], v[208:211], 0
	v_mfma_f32_16x16x32_bf16 v[80:83], v[158:161], v[208:211], 0
	v_mfma_f32_16x16x32_bf16 v[124:127], v[154:157], v[186:189], v[124:127]
	v_mfma_f32_16x16x32_bf16 v[120:123], v[162:165], v[186:189], v[120:123]
	v_mfma_f32_16x16x32_bf16 v[116:119], v[154:157], v[194:197], v[116:119]
	v_mfma_f32_16x16x32_bf16 v[112:115], v[162:165], v[194:197], v[112:115]
	v_mfma_f32_16x16x32_bf16 v[100:103], v[154:157], v[202:205], v[100:103]
	v_mfma_f32_16x16x32_bf16 v[96:99], v[162:165], v[202:205], v[96:99]
	v_mfma_f32_16x16x32_bf16 v[84:87], v[154:157], v[212:215], v[84:87]
	v_mfma_f32_16x16x32_bf16 v[80:83], v[162:165], v[212:215], v[80:83]
	v_mfma_f32_16x16x32_bf16 v[108:111], v[166:169], v[182:185], 0
	v_mfma_f32_16x16x32_bf16 v[104:107], v[174:177], v[182:185], 0
	v_mfma_f32_16x16x32_bf16 v[92:95], v[166:169], v[190:193], 0
	v_mfma_f32_16x16x32_bf16 v[88:91], v[174:177], v[190:193], 0
	v_mfma_f32_16x16x32_bf16 v[76:79], v[166:169], v[198:201], 0
	v_mfma_f32_16x16x32_bf16 v[72:75], v[174:177], v[198:201], 0
	v_mfma_f32_16x16x32_bf16 v[68:71], v[166:169], v[208:211], 0
	v_mfma_f32_16x16x32_bf16 v[64:67], v[174:177], v[208:211], 0
	v_mfma_f32_16x16x32_bf16 v[108:111], v[170:173], v[186:189], v[108:111]
	v_mfma_f32_16x16x32_bf16 v[104:107], v[178:181], v[186:189], v[104:107]
	v_mfma_f32_16x16x32_bf16 v[92:95], v[170:173], v[194:197], v[92:95]
	v_mfma_f32_16x16x32_bf16 v[88:91], v[178:181], v[194:197], v[88:91]
	v_mfma_f32_16x16x32_bf16 v[76:79], v[170:173], v[202:205], v[76:79]
	v_mfma_f32_16x16x32_bf16 v[72:75], v[178:181], v[202:205], v[72:75]
	v_mfma_f32_16x16x32_bf16 v[68:71], v[170:173], v[212:215], v[68:71]
	v_mfma_f32_16x16x32_bf16 v[64:67], v[178:181], v[212:215], v[64:67]
	s_setprio 0
	s_barrier
; #define PG8_STAGE(bufoff, gbase, voff) do { _Pragma("unroll") for (int _i = 0; _i < 2; ++_i) \
;         __builtin_amdgcn_global_load_lds((const unsigned*)((const char*)(gbase) + (voff)[_i]), (PG8_LAS unsigned*)(lds + (bufoff) + ldsw + _i * 8192), 16, 0, 0); } while (0)
; #define PG8_LDA(dst, b, h) do { _Pragma("unroll") for (int m = 0; m < 4; ++m) _Pragma("unroll") for (int k = 0; k < 2; ++k) dst[m][k] = *(const PG8_LAS bf16x8*)(lds + PG8_SA(b, h) + aoff + m * 2048 + k * 1024); } while (0)
; #define PG8_LDB(dst, b, h) do { _Pragma("unroll") for (int n = 0; n < 2; ++n) _Pragma("unroll") for (int k = 0; k < 2; ++k) dst[n][k] = *(const PG8_LAS bf16x8*)(lds + PG8_SB(b, h) + boff + n * 2048 + k * 1024); } while (0)
; #define PG8_MMA(ai, bj, At, Bt) do { __builtin_amdgcn_s_setprio(1); _Pragma("unroll") for (int m = 0; m < 4; ++m) _Pragma("unroll") for (int n = 0; n < 2; ++n) _Pragma("unroll") for (int k = 0; k < 2; ++k) \
;         acc[ai][bj][m][n] = __builtin_amdgcn_mfma_f32_16x16x32_bf16(Bt[n][k], At[m][k], acc[ai][bj][m][n], 0, 0, 0); __builtin_amdgcn_s_setprio(0); } while (0)
; #define PG8_WAIT_V(n) asm volatile("s_waitcnt vmcnt(" #n ")" ::: "memory")
; #define PG8_WAIT_L(n) asm volatile("s_waitcnt lgkmcnt(" #n ")" ::: "memory")
; #define PG8_BAR __builtin_amdgcn_s_barrier()
; #define PG8_SCHED __builtin_amdgcn_sched_barrier(0)
; template <class Epi, class Sched, bool ALIGN_EPI = false, bool SP2 = false>
; __device__ __forceinline__ void gemm_phase(PG8_LAS unsigned char* lds, const Gemm g, const Sched& S, const Epi& E) {
;     ...
;             PG8_LDA(At, 0, 1); PG8_STAGE(PG8_SB(0, 0), b2, voffB); PG8_STAGE(PG8_SB(0, 1), b2 + hstep, voffB); PG8_STAGE(PG8_SA(0, 0), a2, voffA);
;             PG8_WAIT_V(8); PG8_WAIT_L(0); PG8_BAR; PG8_MMA(1, 0, At, B0); PG8_MMA(1, 1, At, B1); PG8_BAR; PG8_SCHED;
;             PG8_LDB(B0, 1, 0); PG8_LDB(B1, 1, 1); PG8_SCHED; PG8_LDA(At, 1, 0); PG8_STAGE(PG8_SA(0, 1), a2 + hstep, voffA);
;             PG8_WAIT_V(8); PG8_WAIT_L(0); PG8_BAR; PG8_MMA(0, 0, At, B0); PG8_MMA(0, 1, At, B1); PG8_BAR; PG8_SCHED;
	s_mov_b32 m0, s56
	v_lshl_add_u64 v[150:151], s[24:25], 0, v[130:131]
	s_add_u32 s72, s24, 0x40000
	ds_read_b128 v[182:185], v143 offset:16384
	ds_read_b128 v[186:189], v143 offset:17408
	ds_read_b128 v[190:193], v143 offset:18432
	ds_read_b128 v[194:197], v143 offset:19456
	ds_read_b128 v[198:201], v143 offset:20480
	ds_read_b128 v[202:205], v143 offset:21504
	ds_read_b128 v[208:211], v143 offset:22528
	ds_read_b128 v[212:215], v143 offset:23552
	global_load_lds_dwordx4 v[150:151], off
	v_lshl_add_u64 v[216:217], s[24:25], 0, v[134:135]
	s_mov_b32 m0, s57
	s_addc_u32 s73, s25, 0
	global_load_lds_dwordx4 v[216:217], off
	v_lshl_add_u64 v[218:219], s[72:73], 0, v[130:131]
	s_mov_b32 m0, s58
	v_lshl_add_u64 v[220:221], s[26:27], 0, v[132:133]
	global_load_lds_dwordx4 v[218:219], off
	v_lshl_add_u64 v[218:219], s[72:73], 0, v[134:135]
	s_mov_b32 m0, s59
	s_nop 0
	global_load_lds_dwordx4 v[218:219], off
	v_lshl_add_u64 v[218:219], s[26:27], 0, v[128:129]
	s_mov_b32 m0, s5
	s_nop 0
	global_load_lds_dwordx4 v[218:219], off
	s_mov_b32 m0, s29
	s_nop 0
	global_load_lds_dwordx4 v[220:221], off
	s_waitcnt vmcnt(8)
	s_waitcnt lgkmcnt(0)
	s_barrier
	s_setprio 1
	s_waitcnt lgkmcnt(0)
	v_mfma_f32_16x16x32_bf16 v[60:63], v[146:149], v[182:185], 0
	v_mfma_f32_16x16x32_bf16 v[56:59], v[158:161], v[182:185], 0
	v_mfma_f32_16x16x32_bf16 v[52:55], v[146:149], v[190:193], 0
	v_mfma_f32_16x16x32_bf16 v[48:51], v[158:161], v[190:193], 0
	v_mfma_f32_16x16x32_bf16 v[36:39], v[146:149], v[198:201], 0
	v_mfma_f32_16x16x32_bf16 v[32:35], v[158:161], v[198:201], 0
	v_mfma_f32_16x16x32_bf16 v[20:23], v[146:149], v[208:211], 0
	v_mfma_f32_16x16x32_bf16 v[16:19], v[158:161], v[208:211], 0
	v_mfma_f32_16x16x32_bf16 v[60:63], v[154:157], v[186:189], v[60:63]
	v_mfma_f32_16x16x32_bf16 v[56:59], v[162:165], v[186:189], v[56:59]
	v_mfma_f32_16x16x32_bf16 v[52:55], v[154:157], v[194:197], v[52:55]
	v_mfma_f32_16x16x32_bf16 v[48:51], v[162:165], v[194:197], v[48:51]
	v_mfma_f32_16x16x32_bf16 v[36:39], v[154:157], v[202:205], v[36:39]
	v_mfma_f32_16x16x32_bf16 v[32:35], v[162:165], v[202:205], v[32:35]
	v_mfma_f32_16x16x32_bf16 v[20:23], v[154:157], v[212:215], v[20:23]
	v_mfma_f32_16x16x32_bf16 v[16:19], v[162:165], v[212:215], v[16:19]
	v_mfma_f32_16x16x32_bf16 v[44:47], v[166:169], v[182:185], 0
	v_mfma_f32_16x16x32_bf16 v[40:43], v[174:177], v[182:185], 0
	v_mfma_f32_16x16x32_bf16 v[28:31], v[166:169], v[190:193], 0
	v_mfma_f32_16x16x32_bf16 v[24:27], v[174:177], v[190:193], 0
	v_mfma_f32_16x16x32_bf16 v[12:15], v[166:169], v[198:201], 0
	v_mfma_f32_16x16x32_bf16 v[8:11], v[174:177], v[198:201], 0
	v_mfma_f32_16x16x32_bf16 v[4:7], v[166:169], v[208:211], 0
	v_mfma_f32_16x16x32_bf16 v[0:3], v[174:177], v[208:211], 0
	v_mfma_f32_16x16x32_bf16 v[44:47], v[170:173], v[186:189], v[44:47]
	v_mfma_f32_16x16x32_bf16 v[40:43], v[178:181], v[186:189], v[40:43]
	v_mfma_f32_16x16x32_bf16 v[28:31], v[170:173], v[194:197], v[28:31]
	v_mfma_f32_16x16x32_bf16 v[24:27], v[178:181], v[194:197], v[24:27]
	v_mfma_f32_16x16x32_bf16 v[12:15], v[170:173], v[202:205], v[12:15]
	v_mfma_f32_16x16x32_bf16 v[8:11], v[178:181], v[202:205], v[8:11]
	v_mfma_f32_16x16x32_bf16 v[4:7], v[170:173], v[212:215], v[4:7]
	v_mfma_f32_16x16x32_bf16 v[0:3], v[178:181], v[212:215], v[0:3]
	s_setprio 0
	s_barrier
	ds_read_b128 v[146:149], v144
	ds_read_b128 v[154:157], v144 offset:1024
	ds_read_b128 v[158:161], v144 offset:2048
	ds_read_b128 v[162:165], v144 offset:3072
	ds_read_b128 v[166:169], v145
	ds_read_b128 v[170:173], v145 offset:1024
	ds_read_b128 v[174:177], v145 offset:2048
	ds_read_b128 v[178:181], v145 offset:3072
	s_add_u32 s26, s26, 0x40000
	s_addc_u32 s27, s27, 0
	s_mov_b32 m0, s30
	v_lshl_add_u64 v[222:223], s[26:27], 0, v[128:129]
	ds_read_b128 v[182:185], v143 offset:32768
	ds_read_b128 v[186:189], v143 offset:33792
	ds_read_b128 v[190:193], v143 offset:34816
	ds_read_b128 v[194:197], v143 offset:35840
	ds_read_b128 v[198:201], v143 offset:36864
	ds_read_b128 v[202:205], v143 offset:37888
	ds_read_b128 v[208:211], v143 offset:38912
	ds_read_b128 v[212:215], v143 offset:39936
	global_load_lds_dwordx4 v[222:223], off
	v_lshl_add_u64 v[222:223], s[26:27], 0, v[132:133]
	s_mov_b32 m0, s31
	s_nop 0
	global_load_lds_dwordx4 v[222:223], off
	s_waitcnt vmcnt(8)
	s_waitcnt lgkmcnt(0)
	s_barrier
	s_setprio 1
	s_waitcnt lgkmcnt(0)
	v_mfma_f32_16x16x32_bf16 v[124:127], v[146:149], v[182:185], v[124:127]
	v_mfma_f32_16x16x32_bf16 v[120:123], v[158:161], v[182:185], v[120:123]
	v_mfma_f32_16x16x32_bf16 v[116:119], v[146:149], v[190:193], v[116:119]
	v_mfma_f32_16x16x32_bf16 v[112:115], v[158:161], v[190:193], v[112:115]
	v_mfma_f32_16x16x32_bf16 v[100:103], v[146:149], v[198:201], v[100:103]
	v_mfma_f32_16x16x32_bf16 v[96:99], v[158:161], v[198:201], v[96:99]
	v_mfma_f32_16x16x32_bf16 v[84:87], v[146:149], v[208:211], v[84:87]
	v_mfma_f32_16x16x32_bf16 v[80:83], v[158:161], v[208:211], v[80:83]
	v_mfma_f32_16x16x32_bf16 v[124:127], v[154:157], v[186:189], v[124:127]
	v_mfma_f32_16x16x32_bf16 v[120:123], v[162:165], v[186:189], v[120:123]
	v_mfma_f32_16x16x32_bf16 v[116:119], v[154:157], v[194:197], v[116:119]
	v_mfma_f32_16x16x32_bf16 v[112:115], v[162:165], v[194:197], v[112:115]
	v_mfma_f32_16x16x32_bf16 v[100:103], v[154:157], v[202:205], v[100:103]
	v_mfma_f32_16x16x32_bf16 v[96:99], v[162:165], v[202:205], v[96:99]
	v_mfma_f32_16x16x32_bf16 v[84:87], v[154:157], v[212:215], v[84:87]
	v_mfma_f32_16x16x32_bf16 v[80:83], v[162:165], v[212:215], v[80:83]
	v_mfma_f32_16x16x32_bf16 v[108:111], v[166:169], v[182:185], v[108:111]
	v_mfma_f32_16x16x32_bf16 v[104:107], v[174:177], v[182:185], v[104:107]
	v_mfma_f32_16x16x32_bf16 v[92:95], v[166:169], v[190:193], v[92:95]
	v_mfma_f32_16x16x32_bf16 v[88:91], v[174:177], v[190:193], v[88:91]
	v_mfma_f32_16x16x32_bf16 v[76:79], v[166:169], v[198:201], v[76:79]
	v_mfma_f32_16x16x32_bf16 v[72:75], v[174:177], v[198:201], v[72:75]
	v_mfma_f32_16x16x32_bf16 v[68:71], v[166:169], v[208:211], v[68:71]
	v_mfma_f32_16x16x32_bf16 v[64:67], v[174:177], v[208:211], v[64:67]
	v_mfma_f32_16x16x32_bf16 v[108:111], v[170:173], v[186:189], v[108:111]
	v_mfma_f32_16x16x32_bf16 v[104:107], v[178:181], v[186:189], v[104:107]
	v_mfma_f32_16x16x32_bf16 v[92:95], v[170:173], v[194:197], v[92:95]
	v_mfma_f32_16x16x32_bf16 v[88:91], v[178:181], v[194:197], v[88:91]
	v_mfma_f32_16x16x32_bf16 v[76:79], v[170:173], v[202:205], v[76:79]
	v_mfma_f32_16x16x32_bf16 v[72:75], v[178:181], v[202:205], v[72:75]
	v_mfma_f32_16x16x32_bf16 v[68:71], v[170:173], v[212:215], v[68:71]
	v_mfma_f32_16x16x32_bf16 v[64:67], v[178:181], v[212:215], v[64:67]
	s_setprio 0
	s_barrier
; #define PG8_STAGE(bufoff, gbase, voff) do { _Pragma("unroll") for (int _i = 0; _i < 2; ++_i) \
;         __builtin_amdgcn_global_load_lds((const unsigned*)((const char*)(gbase) + (voff)[_i]), (PG8_LAS unsigned*)(lds + (bufoff) + ldsw + _i * 8192), 16, 0, 0); } while (0)
; #define PG8_LDA(dst, b, h) do { _Pragma("unroll") for (int m = 0; m < 4; ++m) _Pragma("unroll") for (int k = 0; k < 2; ++k) dst[m][k] = *(const PG8_LAS bf16x8*)(lds + PG8_SA(b, h) + aoff + m * 2048 + k * 1024); } while (0)
; #define PG8_LDB(dst, b, h) do { _Pragma("unroll") for (int n = 0; n < 2; ++n) _Pragma("unroll") for (int k = 0; k < 2; ++k) dst[n][k] = *(const PG8_LAS bf16x8*)(lds + PG8_SB(b, h) + boff + n * 2048 + k * 1024); } while (0)
; #define PG8_MMA(ai, bj, At, Bt) do { __builtin_amdgcn_s_setprio(1); _Pragma("unroll") for (int m = 0; m < 4; ++m) _Pragma("unroll") for (int n = 0; n < 2; ++n) _Pragma("unroll") for (int k = 0; k < 2; ++k) \
;         acc[ai][bj][m][n] = __builtin_amdgcn_mfma_f32_16x16x32_bf16(Bt[n][k], At[m][k], acc[ai][bj][m][n], 0, 0, 0); __builtin_amdgcn_s_setprio(0); } while (0)
; #define PG8_WAIT_V(n) asm volatile("s_waitcnt vmcnt(" #n ")" ::: "memory")
; template <class Epi, class Sched, bool ALIGN_EPI = false, bool SP2 = false>
; __device__ __forceinline__ void gemm_phase(PG8_LAS unsigned char* lds, const Gemm g, const Sched& S, const Epi& E) {
;     ...
;             PG8_LDB(B0, 0, 0); PG8_LDB(B1, 0, 1); PG8_SCHED; PG8_LDA(At, 0, 0); PG8_STAGE(PG8_SA(1, 1), a1 + hstep, voffA);
;             PG8_WAIT_V(8); PG8_WAIT_L(0); PG8_BAR; PG8_MMA(0, 0, At, B0); PG8_MMA(0, 1, At, B1); PG8_BAR; PG8_SCHED;
;             PG8_LDA(At, 0, 1); PG8_STAGE(PG8_SB(0, 0), b2, voffB); PG8_STAGE(PG8_SB(0, 1), b2 + hstep, voffB); PG8_STAGE(PG8_SA(0, 0), a2, voffA);
;             PG8_WAIT_V(8); PG8_WAIT_L(0); PG8_BAR; PG8_MMA(1, 0, At, B0); PG8_MMA(1, 1, At, B1); PG8_BAR; PG8_SCHED;
;             PG8_LDB(B0, 1, 0); PG8_LDB(B1, 1, 1); PG8_SCHED; PG8_LDA(At, 1, 0); PG8_STAGE(PG8_SA(0, 1), a2 + hstep, voffA);
;             PG8_WAIT_V(8); PG8_WAIT_L(0); PG8_BAR; PG8_MMA(0, 0, At, B0); PG8_MMA(0, 1, At, B1); PG8_BAR; PG8_SCHED;
;             PG8_LDA(At, 1, 1); PG8_STAGE(PG8_SB(1, 0), b3, voffB); PG8_STAGE(PG8_SB(1, 1), b3 + hstep, voffB); PG8_STAGE(PG8_SA(1, 0), a3, voffA);
;             PG8_WAIT_V(8); PG8_WAIT_L(0); PG8_BAR; PG8_MMA(1, 0, At, B0); PG8_MMA(1, 1, At, B1); PG8_BAR; PG8_SCHED;
	s_mov_b32 m0, s60
	v_lshl_add_u64 v[150:151], v[150:151], 0, s[14:15]
	s_add_u32 s24, s24, 0x40080
	ds_read_b128 v[182:185], v143 offset:49152
	ds_read_b128 v[186:189], v143 offset:50176
	ds_read_b128 v[190:193], v143 offset:51200
	ds_read_b128 v[194:197], v143 offset:52224
	ds_read_b128 v[198:201], v143 offset:53248
	ds_read_b128 v[202:205], v143 offset:54272
	ds_read_b128 v[208:211], v143 offset:55296
	ds_read_b128 v[212:215], v143 offset:56320
	global_load_lds_dwordx4 v[150:151], off
	v_lshl_add_u64 v[150:151], v[216:217], 0, s[14:15]
	s_mov_b32 m0, s61
	s_addc_u32 s25, s25, 0
	global_load_lds_dwordx4 v[150:151], off
	v_lshl_add_u64 v[150:151], s[24:25], 0, v[130:131]
	s_mov_b32 m0, s68
	s_nop 0
	global_load_lds_dwordx4 v[150:151], off
	v_lshl_add_u64 v[150:151], s[24:25], 0, v[134:135]
	s_mov_b32 m0, s69
	s_nop 0
	global_load_lds_dwordx4 v[150:151], off
	v_lshl_add_u64 v[150:151], v[218:219], 0, s[14:15]
	s_mov_b32 m0, s41
	s_nop 0
	global_load_lds_dwordx4 v[150:151], off
	v_lshl_add_u64 v[150:151], v[220:221], 0, s[14:15]
	s_mov_b32 m0, s42
	s_nop 0
	global_load_lds_dwordx4 v[150:151], off
	s_waitcnt vmcnt(8)
	s_waitcnt lgkmcnt(0)
	s_barrier
	s_setprio 1
	s_waitcnt lgkmcnt(0)
	v_mfma_f32_16x16x32_bf16 v[60:63], v[146:149], v[182:185], v[60:63]
	v_mfma_f32_16x16x32_bf16 v[56:59], v[158:161], v[182:185], v[56:59]
	v_mfma_f32_16x16x32_bf16 v[52:55], v[146:149], v[190:193], v[52:55]
	v_mfma_f32_16x16x32_bf16 v[48:51], v[158:161], v[190:193], v[48:51]
	v_mfma_f32_16x16x32_bf16 v[36:39], v[146:149], v[198:201], v[36:39]
	v_mfma_f32_16x16x32_bf16 v[32:35], v[158:161], v[198:201], v[32:35]
	v_mfma_f32_16x16x32_bf16 v[20:23], v[146:149], v[208:211], v[20:23]
	v_mfma_f32_16x16x32_bf16 v[16:19], v[158:161], v[208:211], v[16:19]
	v_mfma_f32_16x16x32_bf16 v[60:63], v[154:157], v[186:189], v[60:63]
	v_mfma_f32_16x16x32_bf16 v[56:59], v[162:165], v[186:189], v[56:59]
	v_mfma_f32_16x16x32_bf16 v[52:55], v[154:157], v[194:197], v[52:55]
	v_mfma_f32_16x16x32_bf16 v[48:51], v[162:165], v[194:197], v[48:51]
	v_mfma_f32_16x16x32_bf16 v[36:39], v[154:157], v[202:205], v[36:39]
	v_mfma_f32_16x16x32_bf16 v[32:35], v[162:165], v[202:205], v[32:35]
	v_mfma_f32_16x16x32_bf16 v[20:23], v[154:157], v[212:215], v[20:23]
	v_mfma_f32_16x16x32_bf16 v[16:19], v[162:165], v[212:215], v[16:19]
	v_mfma_f32_16x16x32_bf16 v[44:47], v[166:169], v[182:185], v[44:47]
	v_mfma_f32_16x16x32_bf16 v[40:43], v[174:177], v[182:185], v[40:43]
	v_mfma_f32_16x16x32_bf16 v[28:31], v[166:169], v[190:193], v[28:31]
	v_mfma_f32_16x16x32_bf16 v[24:27], v[174:177], v[190:193], v[24:27]
	v_mfma_f32_16x16x32_bf16 v[12:15], v[166:169], v[198:201], v[12:15]
	v_mfma_f32_16x16x32_bf16 v[8:11], v[174:177], v[198:201], v[8:11]
	v_mfma_f32_16x16x32_bf16 v[4:7], v[166:169], v[208:211], v[4:7]
	v_mfma_f32_16x16x32_bf16 v[0:3], v[174:177], v[208:211], v[0:3]
	v_mfma_f32_16x16x32_bf16 v[44:47], v[170:173], v[186:189], v[44:47]
	v_mfma_f32_16x16x32_bf16 v[40:43], v[178:181], v[186:189], v[40:43]
	v_mfma_f32_16x16x32_bf16 v[28:31], v[170:173], v[194:197], v[28:31]
	v_mfma_f32_16x16x32_bf16 v[24:27], v[178:181], v[194:197], v[24:27]
	v_mfma_f32_16x16x32_bf16 v[12:15], v[170:173], v[202:205], v[12:15]
	v_mfma_f32_16x16x32_bf16 v[8:11], v[178:181], v[202:205], v[8:11]
	v_mfma_f32_16x16x32_bf16 v[4:7], v[170:173], v[212:215], v[4:7]
	v_mfma_f32_16x16x32_bf16 v[0:3], v[178:181], v[212:215], v[0:3]
	s_setprio 0
	s_barrier
	s_add_i32 s43, s43, 2
	s_add_u32 s22, s22, 0x100
	s_addc_u32 s23, s23, 0
	s_cmp_gt_u32 s43, 13
	s_cbranch_scc0 .LBB0_397
	s_branch .Lpeel_exit_2
.LBB0_397:
	ds_read_b128 v[146:149], v141
	ds_read_b128 v[154:157], v141 offset:1024
	ds_read_b128 v[158:161], v141 offset:2048
	ds_read_b128 v[162:165], v141 offset:3072
	ds_read_b128 v[166:169], v142
	ds_read_b128 v[170:173], v142 offset:1024
	ds_read_b128 v[174:177], v142 offset:2048
	ds_read_b128 v[178:181], v142 offset:3072
	s_add_u32 s24, s20, s22
	s_addc_u32 s25, s21, s23
	s_add_u32 s24, s24, 0x7400100
	s_addc_u32 s25, s25, 0
	s_add_u32 s26, s50, s22
	s_addc_u32 s27, s51, s23
	s_add_u32 s71, s26, 0x300100
	s_addc_u32 s72, s27, 0
	s_cmpk_eq_i32 s22, 0x700
	s_cselect_b32 s27, s9, s25
	s_cselect_b32 s26, s8, s24
	s_cselect_b32 s25, s7, s72
	s_cselect_b32 s24, s6, s71
	s_mov_b32 m0, s46
	v_lshl_add_u64 v[150:151], v[136:137], 0, s[22:23]
	ds_read_b128 v[182:185], v143
	ds_read_b128 v[186:189], v143 offset:1024
	ds_read_b128 v[190:193], v143 offset:2048
	ds_read_b128 v[194:197], v143 offset:3072
	ds_read_b128 v[198:201], v143 offset:4096
	ds_read_b128 v[202:205], v143 offset:5120
	ds_read_b128 v[208:211], v143 offset:6144
	ds_read_b128 v[212:215], v143 offset:7168
	global_load_lds_dwordx4 v[150:151], off
	v_lshl_add_u64 v[150:151], v[138:139], 0, s[22:23]
	s_mov_b32 m0, s47
	s_nop 0
	global_load_lds_dwordx4 v[150:151], off
	s_waitcnt vmcnt(8)
	s_waitcnt lgkmcnt(0)
	s_barrier
; #define PG8_STAGE(bufoff, gbase, voff) do { _Pragma("unroll") for (int _i = 0; _i < 2; ++_i) \
;         __builtin_amdgcn_global_load_lds((const unsigned*)((const char*)(gbase) + (voff)[_i]), (PG8_LAS unsigned*)(lds + (bufoff) + ldsw + _i * 8192), 16, 0, 0); } while (0)
; #define PG8_LDA(dst, b, h) do { _Pragma("unroll") for (int m = 0; m < 4; ++m) _Pragma("unroll") for (int k = 0; k < 2; ++k) dst[m][k] = *(const PG8_LAS bf16x8*)(lds + PG8_SA(b, h) + aoff + m * 2048 + k * 1024); } while (0)
; #define PG8_LDB(dst, b, h) do { _Pragma("unroll") for (int n = 0; n < 2; ++n) _Pragma("unroll") for (int k = 0; k < 2; ++k) dst[n][k] = *(const PG8_LAS bf16x8*)(lds + PG8_SB(b, h) + boff + n * 2048 + k * 1024); } while (0)
; #define PG8_MMA(ai, bj, At, Bt) do { __builtin_amdgcn_s_setprio(1); _Pragma("unroll") for (int m = 0; m < 4; ++m) _Pragma("unroll") for (int n = 0; n < 2; ++n) _Pragma("unroll") for (int k = 0; k < 2; ++k) \
;         acc[ai][bj][m][n] = __builtin_amdgcn_mfma_f32_16x16x32_bf16(Bt[n][k], At[m][k], acc[ai][bj][m][n], 0, 0, 0); __builtin_amdgcn_s_setprio(0); } while (0)
; #define PG8_WAIT_V(n) asm volatile("s_waitcnt vmcnt(" #n ")" ::: "memory")
; #define PG8_WAIT_L(n) asm volatile("s_waitcnt lgkmcnt(" #n ")" ::: "memory")
; #define PG8_BAR __builtin_amdgcn_s_barrier()
; #define PG8_SCHED __builtin_amdgcn_sched_barrier(0)
; template <class Epi, class Sched, bool ALIGN_EPI = false, bool SP2 = false>
; __device__ __forceinline__ void gemm_phase(PG8_LAS unsigned char* lds, const Gemm g, const Sched& S, const Epi& E) {
;     ...
;             PG8_LDB(B0, 0, 0); PG8_LDB(B1, 0, 1); PG8_SCHED; PG8_LDA(At, 0, 0); PG8_STAGE(PG8_SA(1, 1), a1 + hstep, voffA);
;             PG8_WAIT_V(8); PG8_WAIT_L(0); PG8_BAR; PG8_MMA(0, 0, At, B0); PG8_MMA(0, 1, At, B1); PG8_BAR; PG8_SCHED;
;             PG8_LDA(At, 0, 1); PG8_STAGE(PG8_SB(0, 0), b2, voffB); PG8_STAGE(PG8_SB(0, 1), b2 + hstep, voffB); PG8_STAGE(PG8_SA(0, 0), a2, voffA);
;             PG8_WAIT_V(8); PG8_WAIT_L(0); PG8_BAR; PG8_MMA(1, 0, At, B0); PG8_MMA(1, 1, At, B1); PG8_BAR; PG8_SCHED;
	s_setprio 1
	s_waitcnt lgkmcnt(0)
	v_mfma_f32_16x16x32_bf16 v[124:127], v[146:149], v[182:185], v[124:127]
	v_mfma_f32_16x16x32_bf16 v[120:123], v[158:161], v[182:185], v[120:123]
	v_mfma_f32_16x16x32_bf16 v[116:119], v[146:149], v[190:193], v[116:119]
	v_mfma_f32_16x16x32_bf16 v[112:115], v[158:161], v[190:193], v[112:115]
	v_mfma_f32_16x16x32_bf16 v[100:103], v[146:149], v[198:201], v[100:103]
	v_mfma_f32_16x16x32_bf16 v[96:99], v[158:161], v[198:201], v[96:99]
	v_mfma_f32_16x16x32_bf16 v[84:87], v[146:149], v[208:211], v[84:87]
	v_mfma_f32_16x16x32_bf16 v[80:83], v[158:161], v[208:211], v[80:83]
	v_mfma_f32_16x16x32_bf16 v[124:127], v[154:157], v[186:189], v[124:127]
	v_mfma_f32_16x16x32_bf16 v[120:123], v[162:165], v[186:189], v[120:123]
	v_mfma_f32_16x16x32_bf16 v[116:119], v[154:157], v[194:197], v[116:119]
	v_mfma_f32_16x16x32_bf16 v[112:115], v[162:165], v[194:197], v[112:115]
	v_mfma_f32_16x16x32_bf16 v[100:103], v[154:157], v[202:205], v[100:103]
	v_mfma_f32_16x16x32_bf16 v[96:99], v[162:165], v[202:205], v[96:99]
	v_mfma_f32_16x16x32_bf16 v[84:87], v[154:157], v[212:215], v[84:87]
	v_mfma_f32_16x16x32_bf16 v[80:83], v[162:165], v[212:215], v[80:83]
	v_mfma_f32_16x16x32_bf16 v[108:111], v[166:169], v[182:185], v[108:111]
	v_mfma_f32_16x16x32_bf16 v[104:107], v[174:177], v[182:185], v[104:107]
	v_mfma_f32_16x16x32_bf16 v[92:95], v[166:169], v[190:193], v[92:95]
	v_mfma_f32_16x16x32_bf16 v[88:91], v[174:177], v[190:193], v[88:91]
	v_mfma_f32_16x16x32_bf16 v[76:79], v[166:169], v[198:201], v[76:79]
	v_mfma_f32_16x16x32_bf16 v[72:75], v[174:177], v[198:201], v[72:75]
	v_mfma_f32_16x16x32_bf16 v[68:71], v[166:169], v[208:211], v[68:71]
	v_mfma_f32_16x16x32_bf16 v[64:67], v[174:177], v[208:211], v[64:67]
	v_mfma_f32_16x16x32_bf16 v[108:111], v[170:173], v[186:189], v[108:111]
	v_mfma_f32_16x16x32_bf16 v[104:107], v[178:181], v[186:189], v[104:107]
	v_mfma_f32_16x16x32_bf16 v[92:95], v[170:173], v[194:197], v[92:95]
	v_mfma_f32_16x16x32_bf16 v[88:91], v[178:181], v[194:197], v[88:91]
	v_mfma_f32_16x16x32_bf16 v[76:79], v[170:173], v[202:205], v[76:79]
	v_mfma_f32_16x16x32_bf16 v[72:75], v[178:181], v[202:205], v[72:75]
	v_mfma_f32_16x16x32_bf16 v[68:71], v[170:173], v[212:215], v[68:71]
	v_mfma_f32_16x16x32_bf16 v[64:67], v[178:181], v[212:215], v[64:67]
	s_setprio 0
	s_barrier
	s_mov_b32 m0, s56
	v_lshl_add_u64 v[150:151], s[24:25], 0, v[130:131]
	s_add_u32 s72, s24, 0x40000
	ds_read_b128 v[182:185], v143 offset:16384
	ds_read_b128 v[186:189], v143 offset:17408
	ds_read_b128 v[190:193], v143 offset:18432
	ds_read_b128 v[194:197], v143 offset:19456
	ds_read_b128 v[198:201], v143 offset:20480
	ds_read_b128 v[202:205], v143 offset:21504
	ds_read_b128 v[208:211], v143 offset:22528
	ds_read_b128 v[212:215], v143 offset:23552
	global_load_lds_dwordx4 v[150:151], off
	v_lshl_add_u64 v[216:217], s[24:25], 0, v[134:135]
	s_mov_b32 m0, s57
	s_addc_u32 s73, s25, 0
	global_load_lds_dwordx4 v[216:217], off
	v_lshl_add_u64 v[218:219], s[72:73], 0, v[130:131]
	s_mov_b32 m0, s58
	v_lshl_add_u64 v[220:221], s[26:27], 0, v[132:133]
	global_load_lds_dwordx4 v[218:219], off
	v_lshl_add_u64 v[218:219], s[72:73], 0, v[134:135]
	s_mov_b32 m0, s59
	s_nop 0
	global_load_lds_dwordx4 v[218:219], off
	v_lshl_add_u64 v[218:219], s[26:27], 0, v[128:129]
	s_mov_b32 m0, s5
	s_nop 0
	global_load_lds_dwordx4 v[218:219], off
	s_mov_b32 m0, s29
	s_nop 0
	global_load_lds_dwordx4 v[220:221], off
	s_waitcnt vmcnt(8)
	s_waitcnt lgkmcnt(0)
	s_barrier
	s_setprio 1
	s_waitcnt lgkmcnt(0)
	v_mfma_f32_16x16x32_bf16 v[60:63], v[146:149], v[182:185], v[60:63]
	v_mfma_f32_16x16x32_bf16 v[56:59], v[158:161], v[182:185], v[56:59]
	v_mfma_f32_16x16x32_bf16 v[52:55], v[146:149], v[190:193], v[52:55]
	v_mfma_f32_16x16x32_bf16 v[48:51], v[158:161], v[190:193], v[48:51]
	v_mfma_f32_16x16x32_bf16 v[36:39], v[146:149], v[198:201], v[36:39]
	v_mfma_f32_16x16x32_bf16 v[32:35], v[158:161], v[198:201], v[32:35]
	v_mfma_f32_16x16x32_bf16 v[20:23], v[146:149], v[208:211], v[20:23]
	v_mfma_f32_16x16x32_bf16 v[16:19], v[158:161], v[208:211], v[16:19]
	v_mfma_f32_16x16x32_bf16 v[60:63], v[154:157], v[186:189], v[60:63]
	v_mfma_f32_16x16x32_bf16 v[56:59], v[162:165], v[186:189], v[56:59]
	v_mfma_f32_16x16x32_bf16 v[52:55], v[154:157], v[194:197], v[52:55]
	v_mfma_f32_16x16x32_bf16 v[48:51], v[162:165], v[194:197], v[48:51]
	v_mfma_f32_16x16x32_bf16 v[36:39], v[154:157], v[202:205], v[36:39]
	v_mfma_f32_16x16x32_bf16 v[32:35], v[162:165], v[202:205], v[32:35]
	v_mfma_f32_16x16x32_bf16 v[20:23], v[154:157], v[212:215], v[20:23]
	v_mfma_f32_16x16x32_bf16 v[16:19], v[162:165], v[212:215], v[16:19]
	v_mfma_f32_16x16x32_bf16 v[44:47], v[166:169], v[182:185], v[44:47]
	v_mfma_f32_16x16x32_bf16 v[40:43], v[174:177], v[182:185], v[40:43]
	v_mfma_f32_16x16x32_bf16 v[28:31], v[166:169], v[190:193], v[28:31]
	v_mfma_f32_16x16x32_bf16 v[24:27], v[174:177], v[190:193], v[24:27]
	v_mfma_f32_16x16x32_bf16 v[12:15], v[166:169], v[198:201], v[12:15]
	v_mfma_f32_16x16x32_bf16 v[8:11], v[174:177], v[198:201], v[8:11]
	v_mfma_f32_16x16x32_bf16 v[4:7], v[166:169], v[208:211], v[4:7]
	v_mfma_f32_16x16x32_bf16 v[0:3], v[174:177], v[208:211], v[0:3]
	v_mfma_f32_16x16x32_bf16 v[44:47], v[170:173], v[186:189], v[44:47]
	v_mfma_f32_16x16x32_bf16 v[40:43], v[178:181], v[186:189], v[40:43]
	v_mfma_f32_16x16x32_bf16 v[28:31], v[170:173], v[194:197], v[28:31]
	v_mfma_f32_16x16x32_bf16 v[24:27], v[178:181], v[194:197], v[24:27]
	v_mfma_f32_16x16x32_bf16 v[12:15], v[170:173], v[202:205], v[12:15]
	v_mfma_f32_16x16x32_bf16 v[8:11], v[178:181], v[202:205], v[8:11]
	v_mfma_f32_16x16x32_bf16 v[4:7], v[170:173], v[212:215], v[4:7]
	v_mfma_f32_16x16x32_bf16 v[0:3], v[178:181], v[212:215], v[0:3]
	s_setprio 0
	s_barrier
; #define PG8_STAGE(bufoff, gbase, voff) do { _Pragma("unroll") for (int _i = 0; _i < 2; ++_i) \
;         __builtin_amdgcn_global_load_lds((const unsigned*)((const char*)(gbase) + (voff)[_i]), (PG8_LAS unsigned*)(lds + (bufoff) + ldsw + _i * 8192), 16, 0, 0); } while (0)
; #define PG8_LDA(dst, b, h) do { _Pragma("unroll") for (int m = 0; m < 4; ++m) _Pragma("unroll") for (int k = 0; k < 2; ++k) dst[m][k] = *(const PG8_LAS bf16x8*)(lds + PG8_SA(b, h) + aoff + m * 2048 + k * 1024); } while (0)
; #define PG8_LDB(dst, b, h) do { _Pragma("unroll") for (int n = 0; n < 2; ++n) _Pragma("unroll") for (int k = 0; k < 2; ++k) dst[n][k] = *(const PG8_LAS bf16x8*)(lds + PG8_SB(b, h) + boff + n * 2048 + k * 1024); } while (0)
; #define PG8_MMA(ai, bj, At, Bt) do { __builtin_amdgcn_s_setprio(1); _Pragma("unroll") for (int m = 0; m < 4; ++m) _Pragma("unroll") for (int n = 0; n < 2; ++n) _Pragma("unroll") for (int k = 0; k < 2; ++k) \
;         acc[ai][bj][m][n] = __builtin_amdgcn_mfma_f32_16x16x32_bf16(Bt[n][k], At[m][k], acc[ai][bj][m][n], 0, 0, 0); __builtin_amdgcn_s_setprio(0); } while (0)
; #define PG8_WAIT_V(n) asm volatile("s_waitcnt vmcnt(" #n ")" ::: "memory")
; #define PG8_WAIT_L(n) asm volatile("s_waitcnt lgkmcnt(" #n ")" ::: "memory")
; #define PG8_BAR __builtin_amdgcn_s_barrier()
; #define PG8_SCHED __builtin_amdgcn_sched_barrier(0)
; template <class Epi, class Sched, bool ALIGN_EPI = false, bool SP2 = false>
; __device__ __forceinline__ void gemm_phase(PG8_LAS unsigned char* lds, const Gemm g, const Sched& S, const Epi& E) {
;     ...
;             PG8_LDB(B0, 1, 0); PG8_LDB(B1, 1, 1); PG8_SCHED; PG8_LDA(At, 1, 0); PG8_STAGE(PG8_SA(0, 1), a2 + hstep, voffA);
;             PG8_WAIT_V(8); PG8_WAIT_L(0); PG8_BAR; PG8_MMA(0, 0, At, B0); PG8_MMA(0, 1, At, B1); PG8_BAR; PG8_SCHED;
;             PG8_LDA(At, 1, 1); PG8_STAGE(PG8_SB(1, 0), b3, voffB); PG8_STAGE(PG8_SB(1, 1), b3 + hstep, voffB); PG8_STAGE(PG8_SA(1, 0), a3, voffA);
;             PG8_WAIT_V(8); PG8_WAIT_L(0); PG8_BAR; PG8_MMA(1, 0, At, B0); PG8_MMA(1, 1, At, B1); PG8_BAR; PG8_SCHED;
	ds_read_b128 v[146:149], v144
	ds_read_b128 v[154:157], v144 offset:1024
	ds_read_b128 v[158:161], v144 offset:2048
	ds_read_b128 v[162:165], v144 offset:3072
	ds_read_b128 v[166:169], v145
	ds_read_b128 v[170:173], v145 offset:1024
	ds_read_b128 v[174:177], v145 offset:2048
	ds_read_b128 v[178:181], v145 offset:3072
	s_add_u32 s26, s26, 0x40000
	s_addc_u32 s27, s27, 0
	s_mov_b32 m0, s30
	v_lshl_add_u64 v[222:223], s[26:27], 0, v[128:129]
	ds_read_b128 v[182:185], v143 offset:32768
	ds_read_b128 v[186:189], v143 offset:33792
	ds_read_b128 v[190:193], v143 offset:34816
	ds_read_b128 v[194:197], v143 offset:35840
	ds_read_b128 v[198:201], v143 offset:36864
	ds_read_b128 v[202:205], v143 offset:37888
	ds_read_b128 v[208:211], v143 offset:38912
	ds_read_b128 v[212:215], v143 offset:39936
	global_load_lds_dwordx4 v[222:223], off
	v_lshl_add_u64 v[222:223], s[26:27], 0, v[132:133]
	s_mov_b32 m0, s31
	s_nop 0
	global_load_lds_dwordx4 v[222:223], off
	s_waitcnt vmcnt(8)
	s_waitcnt lgkmcnt(0)
	s_barrier
	s_setprio 1
	s_waitcnt lgkmcnt(0)
	v_mfma_f32_16x16x32_bf16 v[124:127], v[146:149], v[182:185], v[124:127]
	v_mfma_f32_16x16x32_bf16 v[120:123], v[158:161], v[182:185], v[120:123]
	v_mfma_f32_16x16x32_bf16 v[116:119], v[146:149], v[190:193], v[116:119]
	v_mfma_f32_16x16x32_bf16 v[112:115], v[158:161], v[190:193], v[112:115]
	v_mfma_f32_16x16x32_bf16 v[100:103], v[146:149], v[198:201], v[100:103]
	v_mfma_f32_16x16x32_bf16 v[96:99], v[158:161], v[198:201], v[96:99]
	v_mfma_f32_16x16x32_bf16 v[84:87], v[146:149], v[208:211], v[84:87]
	v_mfma_f32_16x16x32_bf16 v[80:83], v[158:161], v[208:211], v[80:83]
	v_mfma_f32_16x16x32_bf16 v[124:127], v[154:157], v[186:189], v[124:127]
	v_mfma_f32_16x16x32_bf16 v[120:123], v[162:165], v[186:189], v[120:123]
	v_mfma_f32_16x16x32_bf16 v[116:119], v[154:157], v[194:197], v[116:119]
	v_mfma_f32_16x16x32_bf16 v[112:115], v[162:165], v[194:197], v[112:115]
	v_mfma_f32_16x16x32_bf16 v[100:103], v[154:157], v[202:205], v[100:103]
	v_mfma_f32_16x16x32_bf16 v[96:99], v[162:165], v[202:205], v[96:99]
	v_mfma_f32_16x16x32_bf16 v[84:87], v[154:157], v[212:215], v[84:87]
	v_mfma_f32_16x16x32_bf16 v[80:83], v[162:165], v[212:215], v[80:83]
	v_mfma_f32_16x16x32_bf16 v[108:111], v[166:169], v[182:185], v[108:111]
	v_mfma_f32_16x16x32_bf16 v[104:107], v[174:177], v[182:185], v[104:107]
	v_mfma_f32_16x16x32_bf16 v[92:95], v[166:169], v[190:193], v[92:95]
	v_mfma_f32_16x16x32_bf16 v[88:91], v[174:177], v[190:193], v[88:91]
	v_mfma_f32_16x16x32_bf16 v[76:79], v[166:169], v[198:201], v[76:79]
	v_mfma_f32_16x16x32_bf16 v[72:75], v[174:177], v[198:201], v[72:75]
	v_mfma_f32_16x16x32_bf16 v[68:71], v[166:169], v[208:211], v[68:71]
	v_mfma_f32_16x16x32_bf16 v[64:67], v[174:177], v[208:211], v[64:67]
	v_mfma_f32_16x16x32_bf16 v[108:111], v[170:173], v[186:189], v[108:111]
	v_mfma_f32_16x16x32_bf16 v[104:107], v[178:181], v[186:189], v[104:107]
	v_mfma_f32_16x16x32_bf16 v[92:95], v[170:173], v[194:197], v[92:95]
	v_mfma_f32_16x16x32_bf16 v[88:91], v[178:181], v[194:197], v[88:91]
	v_mfma_f32_16x16x32_bf16 v[76:79], v[170:173], v[202:205], v[76:79]
	v_mfma_f32_16x16x32_bf16 v[72:75], v[178:181], v[202:205], v[72:75]
	v_mfma_f32_16x16x32_bf16 v[68:71], v[170:173], v[212:215], v[68:71]
	v_mfma_f32_16x16x32_bf16 v[64:67], v[178:181], v[212:215], v[64:67]
	s_setprio 0
	s_barrier
	s_mov_b32 m0, s60
	v_lshl_add_u64 v[150:151], v[150:151], 0, s[14:15]
	s_add_u32 s24, s24, 0x40080
	ds_read_b128 v[182:185], v143 offset:49152
	ds_read_b128 v[186:189], v143 offset:50176
	ds_read_b128 v[190:193], v143 offset:51200
	ds_read_b128 v[194:197], v143 offset:52224
	ds_read_b128 v[198:201], v143 offset:53248
	ds_read_b128 v[202:205], v143 offset:54272
	ds_read_b128 v[208:211], v143 offset:55296
	ds_read_b128 v[212:215], v143 offset:56320
	global_load_lds_dwordx4 v[150:151], off
	v_lshl_add_u64 v[150:151], v[216:217], 0, s[14:15]
	s_mov_b32 m0, s61
	s_addc_u32 s25, s25, 0
	global_load_lds_dwordx4 v[150:151], off
	v_lshl_add_u64 v[150:151], s[24:25], 0, v[130:131]
	s_mov_b32 m0, s68
	s_nop 0
	global_load_lds_dwordx4 v[150:151], off
	v_lshl_add_u64 v[150:151], s[24:25], 0, v[134:135]
	s_mov_b32 m0, s69
	s_nop 0
	global_load_lds_dwordx4 v[150:151], off
	v_lshl_add_u64 v[150:151], v[218:219], 0, s[14:15]
	s_mov_b32 m0, s41
	s_nop 0
	global_load_lds_dwordx4 v[150:151], off
	v_lshl_add_u64 v[150:151], v[220:221], 0, s[14:15]
	s_mov_b32 m0, s42
	s_nop 0
	global_load_lds_dwordx4 v[150:151], off
	s_waitcnt vmcnt(8)
	s_waitcnt lgkmcnt(0)
	s_barrier
	s_setprio 1
	s_waitcnt lgkmcnt(0)
	v_mfma_f32_16x16x32_bf16 v[60:63], v[146:149], v[182:185], v[60:63]
	v_mfma_f32_16x16x32_bf16 v[56:59], v[158:161], v[182:185], v[56:59]
	v_mfma_f32_16x16x32_bf16 v[52:55], v[146:149], v[190:193], v[52:55]
	v_mfma_f32_16x16x32_bf16 v[48:51], v[158:161], v[190:193], v[48:51]
	v_mfma_f32_16x16x32_bf16 v[36:39], v[146:149], v[198:201], v[36:39]
	v_mfma_f32_16x16x32_bf16 v[32:35], v[158:161], v[198:201], v[32:35]
	v_mfma_f32_16x16x32_bf16 v[20:23], v[146:149], v[208:211], v[20:23]
	v_mfma_f32_16x16x32_bf16 v[16:19], v[158:161], v[208:211], v[16:19]
	v_mfma_f32_16x16x32_bf16 v[60:63], v[154:157], v[186:189], v[60:63]
	v_mfma_f32_16x16x32_bf16 v[56:59], v[162:165], v[186:189], v[56:59]
	v_mfma_f32_16x16x32_bf16 v[52:55], v[154:157], v[194:197], v[52:55]
	v_mfma_f32_16x16x32_bf16 v[48:51], v[162:165], v[194:197], v[48:51]
	v_mfma_f32_16x16x32_bf16 v[36:39], v[154:157], v[202:205], v[36:39]
	v_mfma_f32_16x16x32_bf16 v[32:35], v[162:165], v[202:205], v[32:35]
	v_mfma_f32_16x16x32_bf16 v[20:23], v[154:157], v[212:215], v[20:23]
	v_mfma_f32_16x16x32_bf16 v[16:19], v[162:165], v[212:215], v[16:19]
	v_mfma_f32_16x16x32_bf16 v[44:47], v[166:169], v[182:185], v[44:47]
	v_mfma_f32_16x16x32_bf16 v[40:43], v[174:177], v[182:185], v[40:43]
	v_mfma_f32_16x16x32_bf16 v[28:31], v[166:169], v[190:193], v[28:31]
	v_mfma_f32_16x16x32_bf16 v[24:27], v[174:177], v[190:193], v[24:27]
	v_mfma_f32_16x16x32_bf16 v[12:15], v[166:169], v[198:201], v[12:15]
	v_mfma_f32_16x16x32_bf16 v[8:11], v[174:177], v[198:201], v[8:11]
	v_mfma_f32_16x16x32_bf16 v[4:7], v[166:169], v[208:211], v[4:7]
	v_mfma_f32_16x16x32_bf16 v[0:3], v[174:177], v[208:211], v[0:3]
	v_mfma_f32_16x16x32_bf16 v[44:47], v[170:173], v[186:189], v[44:47]
	v_mfma_f32_16x16x32_bf16 v[40:43], v[178:181], v[186:189], v[40:43]
	v_mfma_f32_16x16x32_bf16 v[28:31], v[170:173], v[194:197], v[28:31]
	v_mfma_f32_16x16x32_bf16 v[24:27], v[178:181], v[194:197], v[24:27]
	v_mfma_f32_16x16x32_bf16 v[12:15], v[170:173], v[202:205], v[12:15]
	v_mfma_f32_16x16x32_bf16 v[8:11], v[178:181], v[202:205], v[8:11]
	v_mfma_f32_16x16x32_bf16 v[4:7], v[170:173], v[212:215], v[4:7]
	v_mfma_f32_16x16x32_bf16 v[0:3], v[178:181], v[212:215], v[0:3]
	s_setprio 0
	s_barrier
	s_add_i32 s43, s43, 2
	s_add_u32 s22, s22, 0x100
	s_addc_u32 s23, s23, 0
	s_cmp_gt_u32 s43, 13
	s_cbranch_scc0 .LBB0_397

;     __device__ __forceinline__ bool next(int i, Unit& u) const { if (i != 0) return false; const int c0 = (G >= 8) ? G - 5 : G - 2; int k = -1; if (c == c0) k = 0; else if (c == G - 1) k = 1; if (k < 0 || k >= n) return false; u.pm = k; u.pn = 0; return true; }
; #define PG8_STAGE(bufoff, gbase, voff) do { _Pragma("unroll") for (int _i = 0; _i < 2; ++_i) \
;         __builtin_amdgcn_global_load_lds((const unsigned*)((const char*)(gbase) + (voff)[_i]), (PG8_LAS unsigned*)(lds + (bufoff) + ldsw + _i * 8192), 16, 0, 0); } while (0)
; #define PG8_LDA(dst, b, h) do { _Pragma("unroll") for (int m = 0; m < 4; ++m) _Pragma("unroll") for (int k = 0; k < 2; ++k) dst[m][k] = *(const PG8_LAS bf16x8*)(lds + PG8_SA(b, h) + aoff + m * 2048 + k * 1024); } while (0)
; #define PG8_LDB(dst, b, h) do { _Pragma("unroll") for (int n = 0; n < 2; ++n) _Pragma("unroll") for (int k = 0; k < 2; ++k) dst[n][k] = *(const PG8_LAS bf16x8*)(lds + PG8_SB(b, h) + boff + n * 2048 + k * 1024); } while (0)
; template <class Epi, class Sched, bool ALIGN_EPI = false, bool SP2 = false>
; __device__ __forceinline__ void gemm_phase(PG8_LAS unsigned char* lds, const Gemm g, const Sched& S, const Epi& E) {
;     ...
;         const bool has_next = S.next(ui + 1, nxt);
;         const char* nA = has_next ? (const char*)g.A + (size_t)nxt.pm * tstep : cA; const char* nB = has_next ? (const char*)g.Bt + (size_t)nxt.pn * tstep : cB;
;         for (int t = 0; t < nt; t += 2) {
;             const bool last = (t == nt - 2);
;             const char* a1 = cA + (size_t)(t + 1) * kstep;
;             const char* a2 = last ? nA : cA + (size_t)(t + 2) * kstep; const char* b2 = last ? nB : cB + (size_t)(t + 2) * kstep;
;             const char* a3 = a2 + kstep; const char* b3 = b2 + kstep;
;             if (last && has_next) S.a_ready(nxt);
;             if constexpr (SP2) {
;             PG8_LDB(B0, 0, 0); PG8_LDB(B1, 0, 1); PG8_SCHED; PG8_LDA(At, 0, 0); PG8_STAGE(PG8_SA(1, 1), a1 + hstep, voffA);
;             PG8_WAIT_V(8); PG8_WAIT_L(0); PG8_BAR; PG8_MMA(0, 0, At, B0); PG8_MMA(0, 1, At, B1); PG8_BAR; PG8_SCHED;
;             PG8_LDA(At, 0, 1); PG8_STAGE(PG8_SB(0, 0), b2, voffB); PG8_STAGE(PG8_SB(0, 1), b2 + hstep, voffB); PG8_STAGE(PG8_SA(0, 0), a2, voffA);
;             PG8_WAIT_V(8); PG8_WAIT_L(0); PG8_BAR; PG8_MMA(1, 0, At, B0); PG8_MMA(1, 1, At, B1); PG8_BAR; PG8_SCHED;
.LBB0_658:
	s_ashr_i32 s39, s38, 31
	s_lshl_b64 s[42:43], s[38:39], 19
	s_add_u32 s42, s14, s42
	s_addc_u32 s43, s15, s43
	s_and_b64 s[46:47], s[40:41], exec
	s_cselect_b32 s39, s43, s57
	s_cselect_b32 s82, s42, s56
	s_ashr_i32 s31, s30, 31
	s_lshl_b64 s[46:47], s[30:31], 19
	s_add_u32 s46, s34, s46
	s_addc_u32 s47, s35, s47
	s_and_b64 s[60:61], s[40:41], exec
	s_cselect_b32 s31, s47, s59
	s_cselect_b32 s83, s46, s58
	s_add_u32 s56, s56, 0x40080
	s_addc_u32 s57, s57, 0
	s_add_u32 s90, s58, 0x100
	v_mov_b32_e32 v0, 0
	s_addc_u32 s91, s59, 0
	s_mov_b32 s92, -2
	ds_read_b128 v[148:151], v145
	ds_read_b128 v[152:155], v145 offset:1024
	ds_read_b128 v[156:159], v145 offset:2048
	ds_read_b128 v[160:163], v145 offset:3072
	ds_read_b128 v[164:167], v146
	ds_read_b128 v[168:171], v146 offset:1024
	ds_read_b128 v[172:175], v146 offset:2048
	ds_read_b128 v[176:179], v146 offset:3072
	s_add_u32 s58, s56, 0xfffc0080
	s_addc_u32 s59, s57, -1
	s_cmp_eq_u32 s92, 12
	s_cselect_b32 s61, s39, s59
	s_cselect_b32 s60, s82, s58
	s_cselect_b32 s59, s31, s91
	s_cselect_b32 s58, s83, s90
	v_lshl_add_u64 v[204:205], s[56:57], 0, v[136:137]
	s_add_i32 m0, s66, 0xc000
	ds_read_b128 v[180:183], v147
	ds_read_b128 v[184:187], v147 offset:1024
	ds_read_b128 v[188:191], v147 offset:2048
	ds_read_b128 v[192:195], v147 offset:3072
	ds_read_b128 v[196:199], v147 offset:4096
	ds_read_b128 v[200:203], v147 offset:5120
	ds_read_b128 v[208:211], v147 offset:6144
	ds_read_b128 v[212:215], v147 offset:7168
	global_load_lds_dwordx4 v[204:205], off
	v_lshl_add_u64 v[204:205], s[56:57], 0, v[138:139]
	s_add_i32 m0, s66, 0xe000
	s_nop 0
	global_load_lds_dwordx4 v[204:205], off
	s_waitcnt vmcnt(8)
	s_waitcnt lgkmcnt(0)
	s_barrier
	s_setprio 1
	s_waitcnt lgkmcnt(0)
	v_mfma_f32_16x16x32_bf16 v[124:127], v[148:151], v[180:183], 0
	v_mfma_f32_16x16x32_bf16 v[120:123], v[156:159], v[180:183], 0
	v_mfma_f32_16x16x32_bf16 v[116:119], v[148:151], v[188:191], 0
	v_mfma_f32_16x16x32_bf16 v[112:115], v[156:159], v[188:191], 0
	v_mfma_f32_16x16x32_bf16 v[100:103], v[148:151], v[196:199], 0
	v_mfma_f32_16x16x32_bf16 v[96:99], v[156:159], v[196:199], 0
	v_mfma_f32_16x16x32_bf16 v[84:87], v[148:151], v[208:211], 0
	v_mfma_f32_16x16x32_bf16 v[80:83], v[156:159], v[208:211], 0
	v_mfma_f32_16x16x32_bf16 v[124:127], v[152:155], v[184:187], v[124:127]
	v_mfma_f32_16x16x32_bf16 v[120:123], v[160:163], v[184:187], v[120:123]
	v_mfma_f32_16x16x32_bf16 v[116:119], v[152:155], v[192:195], v[116:119]
	v_mfma_f32_16x16x32_bf16 v[112:115], v[160:163], v[192:195], v[112:115]
	v_mfma_f32_16x16x32_bf16 v[100:103], v[152:155], v[200:203], v[100:103]
	v_mfma_f32_16x16x32_bf16 v[96:99], v[160:163], v[200:203], v[96:99]
	v_mfma_f32_16x16x32_bf16 v[84:87], v[152:155], v[212:215], v[84:87]
	v_mfma_f32_16x16x32_bf16 v[80:83], v[160:163], v[212:215], v[80:83]
	v_mfma_f32_16x16x32_bf16 v[108:111], v[164:167], v[180:183], 0
	v_mfma_f32_16x16x32_bf16 v[104:107], v[172:175], v[180:183], 0
	v_mfma_f32_16x16x32_bf16 v[92:95], v[164:167], v[188:191], 0
	v_mfma_f32_16x16x32_bf16 v[88:91], v[172:175], v[188:191], 0
	v_mfma_f32_16x16x32_bf16 v[76:79], v[164:167], v[196:199], 0
	v_mfma_f32_16x16x32_bf16 v[72:75], v[172:175], v[196:199], 0
	v_mfma_f32_16x16x32_bf16 v[68:71], v[164:167], v[208:211], 0
	v_mfma_f32_16x16x32_bf16 v[64:67], v[172:175], v[208:211], 0
	v_mfma_f32_16x16x32_bf16 v[108:111], v[168:171], v[184:187], v[108:111]
	v_mfma_f32_16x16x32_bf16 v[104:107], v[176:179], v[184:187], v[104:107]
	v_mfma_f32_16x16x32_bf16 v[92:95], v[168:171], v[192:195], v[92:95]
	v_mfma_f32_16x16x32_bf16 v[88:91], v[176:179], v[192:195], v[88:91]
	v_mfma_f32_16x16x32_bf16 v[76:79], v[168:171], v[200:203], v[76:79]
	v_mfma_f32_16x16x32_bf16 v[72:75], v[176:179], v[200:203], v[72:75]
	v_mfma_f32_16x16x32_bf16 v[68:71], v[168:171], v[212:215], v[68:71]
	v_mfma_f32_16x16x32_bf16 v[64:67], v[176:179], v[212:215], v[64:67]
	s_setprio 0
	s_barrier
	s_add_i32 s93, s76, s65
	v_lshl_add_u64 v[204:205], s[58:59], 0, v[130:131]
	s_mov_b32 m0, s93
	ds_read_b128 v[180:183], v147 offset:16384
	ds_read_b128 v[184:187], v147 offset:17408
	ds_read_b128 v[188:191], v147 offset:18432
	ds_read_b128 v[192:195], v147 offset:19456
	ds_read_b128 v[196:199], v147 offset:20480
	ds_read_b128 v[200:203], v147 offset:21504
	ds_read_b128 v[208:211], v147 offset:22528
	ds_read_b128 v[212:215], v147 offset:23552
	global_load_lds_dwordx4 v[204:205], off
	s_add_i32 m0, s93, 0x2000
	s_add_u32 s94, s58, 0x40000
	v_lshl_add_u64 v[216:217], s[58:59], 0, v[134:135]
	s_addc_u32 s95, s59, 0
	s_add_i32 s93, s77, s65
	global_load_lds_dwordx4 v[216:217], off
	v_lshl_add_u64 v[218:219], s[94:95], 0, v[130:131]
	s_mov_b32 m0, s93
	v_lshl_add_u64 v[220:221], s[60:61], 0, v[132:133]
	global_load_lds_dwordx4 v[218:219], off
	v_lshl_add_u64 v[218:219], s[94:95], 0, v[134:135]
	s_add_i32 m0, s93, 0x2000
	s_nop 0
	global_load_lds_dwordx4 v[218:219], off
	v_lshl_add_u64 v[218:219], s[60:61], 0, v[128:129]
	s_mov_b32 m0, s66
	s_nop 0
	global_load_lds_dwordx4 v[218:219], off
	s_mov_b32 m0, s67
	s_nop 0
	global_load_lds_dwordx4 v[220:221], off
	s_waitcnt vmcnt(8)
	s_waitcnt lgkmcnt(0)
	s_barrier
; #define PG8_STAGE(bufoff, gbase, voff) do { _Pragma("unroll") for (int _i = 0; _i < 2; ++_i) \
;         __builtin_amdgcn_global_load_lds((const unsigned*)((const char*)(gbase) + (voff)[_i]), (PG8_LAS unsigned*)(lds + (bufoff) + ldsw + _i * 8192), 16, 0, 0); } while (0)
; #define PG8_LDA(dst, b, h) do { _Pragma("unroll") for (int m = 0; m < 4; ++m) _Pragma("unroll") for (int k = 0; k < 2; ++k) dst[m][k] = *(const PG8_LAS bf16x8*)(lds + PG8_SA(b, h) + aoff + m * 2048 + k * 1024); } while (0)
; #define PG8_LDB(dst, b, h) do { _Pragma("unroll") for (int n = 0; n < 2; ++n) _Pragma("unroll") for (int k = 0; k < 2; ++k) dst[n][k] = *(const PG8_LAS bf16x8*)(lds + PG8_SB(b, h) + boff + n * 2048 + k * 1024); } while (0)
; #define PG8_MMA(ai, bj, At, Bt) do { __builtin_amdgcn_s_setprio(1); _Pragma("unroll") for (int m = 0; m < 4; ++m) _Pragma("unroll") for (int n = 0; n < 2; ++n) _Pragma("unroll") for (int k = 0; k < 2; ++k) \
;         acc[ai][bj][m][n] = __builtin_amdgcn_mfma_f32_16x16x32_bf16(Bt[n][k], At[m][k], acc[ai][bj][m][n], 0, 0, 0); __builtin_amdgcn_s_setprio(0); } while (0)
; #define PG8_WAIT_V(n) asm volatile("s_waitcnt vmcnt(" #n ")" ::: "memory")
; #define PG8_WAIT_L(n) asm volatile("s_waitcnt lgkmcnt(" #n ")" ::: "memory")
; #define PG8_BAR __builtin_amdgcn_s_barrier()
; #define PG8_SCHED __builtin_amdgcn_sched_barrier(0)
; template <class Epi, class Sched, bool ALIGN_EPI = false, bool SP2 = false>
; __device__ __forceinline__ void gemm_phase(PG8_LAS unsigned char* lds, const Gemm g, const Sched& S, const Epi& E) {
;     ...
;             PG8_LDA(At, 0, 1); PG8_STAGE(PG8_SB(0, 0), b2, voffB); PG8_STAGE(PG8_SB(0, 1), b2 + hstep, voffB); PG8_STAGE(PG8_SA(0, 0), a2, voffA);
;             PG8_WAIT_V(8); PG8_WAIT_L(0); PG8_BAR; PG8_MMA(1, 0, At, B0); PG8_MMA(1, 1, At, B1); PG8_BAR; PG8_SCHED;
;             PG8_LDB(B0, 1, 0); PG8_LDB(B1, 1, 1); PG8_SCHED; PG8_LDA(At, 1, 0); PG8_STAGE(PG8_SA(0, 1), a2 + hstep, voffA);
;             PG8_WAIT_V(8); PG8_WAIT_L(0); PG8_BAR; PG8_MMA(0, 0, At, B0); PG8_MMA(0, 1, At, B1); PG8_BAR; PG8_SCHED;
	s_setprio 1
	s_waitcnt lgkmcnt(0)
	v_mfma_f32_16x16x32_bf16 v[60:63], v[148:151], v[180:183], 0
	v_mfma_f32_16x16x32_bf16 v[56:59], v[156:159], v[180:183], 0
	v_mfma_f32_16x16x32_bf16 v[52:55], v[148:151], v[188:191], 0
	v_mfma_f32_16x16x32_bf16 v[48:51], v[156:159], v[188:191], 0
	v_mfma_f32_16x16x32_bf16 v[36:39], v[148:151], v[196:199], 0
	v_mfma_f32_16x16x32_bf16 v[32:35], v[156:159], v[196:199], 0
	v_mfma_f32_16x16x32_bf16 v[20:23], v[148:151], v[208:211], 0
	v_mfma_f32_16x16x32_bf16 v[16:19], v[156:159], v[208:211], 0
	v_mfma_f32_16x16x32_bf16 v[60:63], v[152:155], v[184:187], v[60:63]
	v_mfma_f32_16x16x32_bf16 v[56:59], v[160:163], v[184:187], v[56:59]
	v_mfma_f32_16x16x32_bf16 v[52:55], v[152:155], v[192:195], v[52:55]
	v_mfma_f32_16x16x32_bf16 v[48:51], v[160:163], v[192:195], v[48:51]
	v_mfma_f32_16x16x32_bf16 v[36:39], v[152:155], v[200:203], v[36:39]
	v_mfma_f32_16x16x32_bf16 v[32:35], v[160:163], v[200:203], v[32:35]
	v_mfma_f32_16x16x32_bf16 v[20:23], v[152:155], v[212:215], v[20:23]
	v_mfma_f32_16x16x32_bf16 v[16:19], v[160:163], v[212:215], v[16:19]
	v_mfma_f32_16x16x32_bf16 v[44:47], v[164:167], v[180:183], 0
	v_mfma_f32_16x16x32_bf16 v[40:43], v[172:175], v[180:183], 0
	v_mfma_f32_16x16x32_bf16 v[28:31], v[164:167], v[188:191], 0
	v_mfma_f32_16x16x32_bf16 v[24:27], v[172:175], v[188:191], 0
	v_mfma_f32_16x16x32_bf16 v[12:15], v[164:167], v[196:199], 0
	v_mfma_f32_16x16x32_bf16 v[8:11], v[172:175], v[196:199], 0
	v_mfma_f32_16x16x32_bf16 v[4:7], v[164:167], v[208:211], 0
	v_mfma_f32_16x16x32_bf16 v[0:3], v[172:175], v[208:211], 0
	v_mfma_f32_16x16x32_bf16 v[44:47], v[168:171], v[184:187], v[44:47]
	v_mfma_f32_16x16x32_bf16 v[40:43], v[176:179], v[184:187], v[40:43]
	v_mfma_f32_16x16x32_bf16 v[28:31], v[168:171], v[192:195], v[28:31]
	v_mfma_f32_16x16x32_bf16 v[24:27], v[176:179], v[192:195], v[24:27]
	v_mfma_f32_16x16x32_bf16 v[12:15], v[168:171], v[200:203], v[12:15]
	v_mfma_f32_16x16x32_bf16 v[8:11], v[176:179], v[200:203], v[8:11]
	v_mfma_f32_16x16x32_bf16 v[4:7], v[168:171], v[212:215], v[4:7]
	v_mfma_f32_16x16x32_bf16 v[0:3], v[176:179], v[212:215], v[0:3]
	s_setprio 0
	s_barrier
	s_add_i32 s93, 0, 0x18000
	s_add_i32 s94, 0, 0x1c000
	v_add_u32_e32 v160, s93, v143
	v_add_u32_e32 v176, s94, v143
	ds_read_b128 v[148:151], v160
	ds_read_b128 v[152:155], v160 offset:1024
	ds_read_b128 v[156:159], v160 offset:2048
	ds_read_b128 v[160:163], v160 offset:3072
	ds_read_b128 v[164:167], v176
	ds_read_b128 v[168:171], v176 offset:1024
	ds_read_b128 v[172:175], v176 offset:2048
	ds_read_b128 v[176:179], v176 offset:3072
	s_add_u32 s60, s60, 0x40000
	s_addc_u32 s61, s61, 0
	s_mov_b32 m0, s68
	v_lshl_add_u64 v[222:223], s[60:61], 0, v[128:129]
	ds_read_b128 v[180:183], v147 offset:32768
	ds_read_b128 v[184:187], v147 offset:33792
	ds_read_b128 v[188:191], v147 offset:34816
	ds_read_b128 v[192:195], v147 offset:35840
	ds_read_b128 v[196:199], v147 offset:36864
	ds_read_b128 v[200:203], v147 offset:37888
	ds_read_b128 v[208:211], v147 offset:38912
	ds_read_b128 v[212:215], v147 offset:39936
	global_load_lds_dwordx4 v[222:223], off
	v_lshl_add_u64 v[222:223], s[60:61], 0, v[132:133]
	s_mov_b32 m0, s69
	s_nop 0
	global_load_lds_dwordx4 v[222:223], off
	s_waitcnt vmcnt(8)
	s_waitcnt lgkmcnt(0)
	s_barrier
	s_setprio 1
	s_waitcnt lgkmcnt(0)
	v_mfma_f32_16x16x32_bf16 v[124:127], v[148:151], v[180:183], v[124:127]
	v_mfma_f32_16x16x32_bf16 v[120:123], v[156:159], v[180:183], v[120:123]
	v_mfma_f32_16x16x32_bf16 v[116:119], v[148:151], v[188:191], v[116:119]
	v_mfma_f32_16x16x32_bf16 v[112:115], v[156:159], v[188:191], v[112:115]
	v_mfma_f32_16x16x32_bf16 v[100:103], v[148:151], v[196:199], v[100:103]
	v_mfma_f32_16x16x32_bf16 v[96:99], v[156:159], v[196:199], v[96:99]
	v_mfma_f32_16x16x32_bf16 v[84:87], v[148:151], v[208:211], v[84:87]
	v_mfma_f32_16x16x32_bf16 v[80:83], v[156:159], v[208:211], v[80:83]
	v_mfma_f32_16x16x32_bf16 v[124:127], v[152:155], v[184:187], v[124:127]
	v_mfma_f32_16x16x32_bf16 v[120:123], v[160:163], v[184:187], v[120:123]
	v_mfma_f32_16x16x32_bf16 v[116:119], v[152:155], v[192:195], v[116:119]
	v_mfma_f32_16x16x32_bf16 v[112:115], v[160:163], v[192:195], v[112:115]
	v_mfma_f32_16x16x32_bf16 v[100:103], v[152:155], v[200:203], v[100:103]
	v_mfma_f32_16x16x32_bf16 v[96:99], v[160:163], v[200:203], v[96:99]
	v_mfma_f32_16x16x32_bf16 v[84:87], v[152:155], v[212:215], v[84:87]
	v_mfma_f32_16x16x32_bf16 v[80:83], v[160:163], v[212:215], v[80:83]
	v_mfma_f32_16x16x32_bf16 v[108:111], v[164:167], v[180:183], v[108:111]
	v_mfma_f32_16x16x32_bf16 v[104:107], v[172:175], v[180:183], v[104:107]
	v_mfma_f32_16x16x32_bf16 v[92:95], v[164:167], v[188:191], v[92:95]
	v_mfma_f32_16x16x32_bf16 v[88:91], v[172:175], v[188:191], v[88:91]
	v_mfma_f32_16x16x32_bf16 v[76:79], v[164:167], v[196:199], v[76:79]
	v_mfma_f32_16x16x32_bf16 v[72:75], v[172:175], v[196:199], v[72:75]
	v_mfma_f32_16x16x32_bf16 v[68:71], v[164:167], v[208:211], v[68:71]
	v_mfma_f32_16x16x32_bf16 v[64:67], v[172:175], v[208:211], v[64:67]
	v_mfma_f32_16x16x32_bf16 v[108:111], v[168:171], v[184:187], v[108:111]
	v_mfma_f32_16x16x32_bf16 v[104:107], v[176:179], v[184:187], v[104:107]
	v_mfma_f32_16x16x32_bf16 v[92:95], v[168:171], v[192:195], v[92:95]
	v_mfma_f32_16x16x32_bf16 v[88:91], v[176:179], v[192:195], v[88:91]
	v_mfma_f32_16x16x32_bf16 v[76:79], v[168:171], v[200:203], v[76:79]
	v_mfma_f32_16x16x32_bf16 v[72:75], v[176:179], v[200:203], v[72:75]
	v_mfma_f32_16x16x32_bf16 v[68:71], v[168:171], v[212:215], v[68:71]
	v_mfma_f32_16x16x32_bf16 v[64:67], v[176:179], v[212:215], v[64:67]
	s_setprio 0
	s_barrier
; #define PG8_STAGE(bufoff, gbase, voff) do { _Pragma("unroll") for (int _i = 0; _i < 2; ++_i) \
;         __builtin_amdgcn_global_load_lds((const unsigned*)((const char*)(gbase) + (voff)[_i]), (PG8_LAS unsigned*)(lds + (bufoff) + ldsw + _i * 8192), 16, 0, 0); } while (0)
; #define PG8_LDA(dst, b, h) do { _Pragma("unroll") for (int m = 0; m < 4; ++m) _Pragma("unroll") for (int k = 0; k < 2; ++k) dst[m][k] = *(const PG8_LAS bf16x8*)(lds + PG8_SA(b, h) + aoff + m * 2048 + k * 1024); } while (0)
; #define PG8_LDB(dst, b, h) do { _Pragma("unroll") for (int n = 0; n < 2; ++n) _Pragma("unroll") for (int k = 0; k < 2; ++k) dst[n][k] = *(const PG8_LAS bf16x8*)(lds + PG8_SB(b, h) + boff + n * 2048 + k * 1024); } while (0)
; #define PG8_MMA(ai, bj, At, Bt) do { __builtin_amdgcn_s_setprio(1); _Pragma("unroll") for (int m = 0; m < 4; ++m) _Pragma("unroll") for (int n = 0; n < 2; ++n) _Pragma("unroll") for (int k = 0; k < 2; ++k) \
;         acc[ai][bj][m][n] = __builtin_amdgcn_mfma_f32_16x16x32_bf16(Bt[n][k], At[m][k], acc[ai][bj][m][n], 0, 0, 0); __builtin_amdgcn_s_setprio(0); } while (0)
; #define PG8_WAIT_V(n) asm volatile("s_waitcnt vmcnt(" #n ")" ::: "memory")
; template <class Epi, class Sched, bool ALIGN_EPI = false, bool SP2 = false>
; __device__ __forceinline__ void gemm_phase(PG8_LAS unsigned char* lds, const Gemm g, const Sched& S, const Epi& E) {
;     ...
;             PG8_LDB(B0, 0, 0); PG8_LDB(B1, 0, 1); PG8_SCHED; PG8_LDA(At, 0, 0); PG8_STAGE(PG8_SA(1, 1), a1 + hstep, voffA);
;             PG8_WAIT_V(8); PG8_WAIT_L(0); PG8_BAR; PG8_MMA(0, 0, At, B0); PG8_MMA(0, 1, At, B1); PG8_BAR; PG8_SCHED;
;             PG8_LDA(At, 0, 1); PG8_STAGE(PG8_SB(0, 0), b2, voffB); PG8_STAGE(PG8_SB(0, 1), b2 + hstep, voffB); PG8_STAGE(PG8_SA(0, 0), a2, voffA);
;             PG8_WAIT_V(8); PG8_WAIT_L(0); PG8_BAR; PG8_MMA(1, 0, At, B0); PG8_MMA(1, 1, At, B1); PG8_BAR; PG8_SCHED;
;             PG8_LDB(B0, 1, 0); PG8_LDB(B1, 1, 1); PG8_SCHED; PG8_LDA(At, 1, 0); PG8_STAGE(PG8_SA(0, 1), a2 + hstep, voffA);
;             PG8_WAIT_V(8); PG8_WAIT_L(0); PG8_BAR; PG8_MMA(0, 0, At, B0); PG8_MMA(0, 1, At, B1); PG8_BAR; PG8_SCHED;
;             PG8_LDA(At, 1, 1); PG8_STAGE(PG8_SB(1, 0), b3, voffB); PG8_STAGE(PG8_SB(1, 1), b3 + hstep, voffB); PG8_STAGE(PG8_SA(1, 0), a3, voffA);
;             PG8_WAIT_V(8); PG8_WAIT_L(0); PG8_BAR; PG8_MMA(1, 0, At, B0); PG8_MMA(1, 1, At, B1); PG8_BAR; PG8_SCHED;
	s_add_i32 s60, s93, s65
	v_lshl_add_u64 v[204:205], v[204:205], 0, s[18:19]
	s_mov_b32 m0, s60
	ds_read_b128 v[180:183], v147 offset:49152
	ds_read_b128 v[184:187], v147 offset:50176
	ds_read_b128 v[188:191], v147 offset:51200
	ds_read_b128 v[192:195], v147 offset:52224
	ds_read_b128 v[196:199], v147 offset:53248
	ds_read_b128 v[200:203], v147 offset:54272
	ds_read_b128 v[208:211], v147 offset:55296
	ds_read_b128 v[212:215], v147 offset:56320
	global_load_lds_dwordx4 v[204:205], off
	s_add_i32 m0, s60, 0x2000
	s_add_u32 s58, s58, 0x40080
	v_lshl_add_u64 v[204:205], v[216:217], 0, s[18:19]
	s_addc_u32 s59, s59, 0
	s_add_i32 s60, s94, s65
	global_load_lds_dwordx4 v[204:205], off
	v_lshl_add_u64 v[204:205], s[58:59], 0, v[130:131]
	s_mov_b32 m0, s60
	s_nop 0
	global_load_lds_dwordx4 v[204:205], off
	v_lshl_add_u64 v[204:205], s[58:59], 0, v[134:135]
	s_add_i32 m0, s60, 0x2000
	s_nop 0
	global_load_lds_dwordx4 v[204:205], off
	v_lshl_add_u64 v[204:205], v[218:219], 0, s[18:19]
	s_mov_b32 m0, s73
	s_nop 0
	global_load_lds_dwordx4 v[204:205], off
	v_lshl_add_u64 v[204:205], v[220:221], 0, s[18:19]
	s_mov_b32 m0, s74
	s_nop 0
	global_load_lds_dwordx4 v[204:205], off
	s_waitcnt vmcnt(8)
	s_waitcnt lgkmcnt(0)
	s_barrier
	s_setprio 1
	s_waitcnt lgkmcnt(0)
	v_mfma_f32_16x16x32_bf16 v[60:63], v[148:151], v[180:183], v[60:63]
	v_mfma_f32_16x16x32_bf16 v[56:59], v[156:159], v[180:183], v[56:59]
	v_mfma_f32_16x16x32_bf16 v[52:55], v[148:151], v[188:191], v[52:55]
	v_mfma_f32_16x16x32_bf16 v[48:51], v[156:159], v[188:191], v[48:51]
	v_mfma_f32_16x16x32_bf16 v[36:39], v[148:151], v[196:199], v[36:39]
	v_mfma_f32_16x16x32_bf16 v[32:35], v[156:159], v[196:199], v[32:35]
	v_mfma_f32_16x16x32_bf16 v[20:23], v[148:151], v[208:211], v[20:23]
	v_mfma_f32_16x16x32_bf16 v[16:19], v[156:159], v[208:211], v[16:19]
	v_mfma_f32_16x16x32_bf16 v[60:63], v[152:155], v[184:187], v[60:63]
	v_mfma_f32_16x16x32_bf16 v[56:59], v[160:163], v[184:187], v[56:59]
	v_mfma_f32_16x16x32_bf16 v[52:55], v[152:155], v[192:195], v[52:55]
	v_mfma_f32_16x16x32_bf16 v[48:51], v[160:163], v[192:195], v[48:51]
	v_mfma_f32_16x16x32_bf16 v[36:39], v[152:155], v[200:203], v[36:39]
	v_mfma_f32_16x16x32_bf16 v[32:35], v[160:163], v[200:203], v[32:35]
	v_mfma_f32_16x16x32_bf16 v[20:23], v[152:155], v[212:215], v[20:23]
	v_mfma_f32_16x16x32_bf16 v[16:19], v[160:163], v[212:215], v[16:19]
	v_mfma_f32_16x16x32_bf16 v[44:47], v[164:167], v[180:183], v[44:47]
	v_mfma_f32_16x16x32_bf16 v[40:43], v[172:175], v[180:183], v[40:43]
	v_mfma_f32_16x16x32_bf16 v[28:31], v[164:167], v[188:191], v[28:31]
	v_mfma_f32_16x16x32_bf16 v[24:27], v[172:175], v[188:191], v[24:27]
	v_mfma_f32_16x16x32_bf16 v[12:15], v[164:167], v[196:199], v[12:15]
	v_mfma_f32_16x16x32_bf16 v[8:11], v[172:175], v[196:199], v[8:11]
	v_mfma_f32_16x16x32_bf16 v[4:7], v[164:167], v[208:211], v[4:7]
	v_mfma_f32_16x16x32_bf16 v[0:3], v[172:175], v[208:211], v[0:3]
	v_mfma_f32_16x16x32_bf16 v[44:47], v[168:171], v[184:187], v[44:47]
	v_mfma_f32_16x16x32_bf16 v[40:43], v[176:179], v[184:187], v[40:43]
	v_mfma_f32_16x16x32_bf16 v[28:31], v[168:171], v[192:195], v[28:31]
	v_mfma_f32_16x16x32_bf16 v[24:27], v[176:179], v[192:195], v[24:27]
	v_mfma_f32_16x16x32_bf16 v[12:15], v[168:171], v[200:203], v[12:15]
	v_mfma_f32_16x16x32_bf16 v[8:11], v[176:179], v[200:203], v[8:11]
	v_mfma_f32_16x16x32_bf16 v[4:7], v[168:171], v[212:215], v[4:7]
	v_mfma_f32_16x16x32_bf16 v[0:3], v[176:179], v[212:215], v[0:3]
	s_setprio 0
	s_barrier
	s_add_i32 s92, s92, 2
	s_add_u32 s56, s56, 0x100
	s_addc_u32 s57, s57, 0
	s_add_u32 s90, s90, 0x100
	s_addc_u32 s91, s91, 0
	s_cmp_gt_u32 s92, 13
	s_cbranch_scc0 .LBB0_659
	s_branch .Lpeel_exit_3
.LBB0_659:
	ds_read_b128 v[148:151], v145
	ds_read_b128 v[152:155], v145 offset:1024
	ds_read_b128 v[156:159], v145 offset:2048
	ds_read_b128 v[160:163], v145 offset:3072
	ds_read_b128 v[164:167], v146
	ds_read_b128 v[168:171], v146 offset:1024
	ds_read_b128 v[172:175], v146 offset:2048
	ds_read_b128 v[176:179], v146 offset:3072
	s_add_u32 s58, s56, 0xfffc0080
	s_addc_u32 s59, s57, -1
	s_cmp_eq_u32 s92, 12
	s_cselect_b32 s61, s39, s59
	s_cselect_b32 s60, s82, s58
	s_cselect_b32 s59, s31, s91
	s_cselect_b32 s58, s83, s90
	v_lshl_add_u64 v[204:205], s[56:57], 0, v[136:137]
	s_add_i32 m0, s66, 0xc000
	ds_read_b128 v[180:183], v147
	ds_read_b128 v[184:187], v147 offset:1024
	ds_read_b128 v[188:191], v147 offset:2048
	ds_read_b128 v[192:195], v147 offset:3072
	ds_read_b128 v[196:199], v147 offset:4096
	ds_read_b128 v[200:203], v147 offset:5120
	ds_read_b128 v[208:211], v147 offset:6144
	ds_read_b128 v[212:215], v147 offset:7168
	global_load_lds_dwordx4 v[204:205], off
	v_lshl_add_u64 v[204:205], s[56:57], 0, v[138:139]
	s_add_i32 m0, s66, 0xe000
	s_nop 0
	global_load_lds_dwordx4 v[204:205], off
	s_waitcnt vmcnt(8)
	s_waitcnt lgkmcnt(0)
	s_barrier
; #define PG8_STAGE(bufoff, gbase, voff) do { _Pragma("unroll") for (int _i = 0; _i < 2; ++_i) \
;         __builtin_amdgcn_global_load_lds((const unsigned*)((const char*)(gbase) + (voff)[_i]), (PG8_LAS unsigned*)(lds + (bufoff) + ldsw + _i * 8192), 16, 0, 0); } while (0)
; #define PG8_LDA(dst, b, h) do { _Pragma("unroll") for (int m = 0; m < 4; ++m) _Pragma("unroll") for (int k = 0; k < 2; ++k) dst[m][k] = *(const PG8_LAS bf16x8*)(lds + PG8_SA(b, h) + aoff + m * 2048 + k * 1024); } while (0)
; #define PG8_LDB(dst, b, h) do { _Pragma("unroll") for (int n = 0; n < 2; ++n) _Pragma("unroll") for (int k = 0; k < 2; ++k) dst[n][k] = *(const PG8_LAS bf16x8*)(lds + PG8_SB(b, h) + boff + n * 2048 + k * 1024); } while (0)
; #define PG8_MMA(ai, bj, At, Bt) do { __builtin_amdgcn_s_setprio(1); _Pragma("unroll") for (int m = 0; m < 4; ++m) _Pragma("unroll") for (int n = 0; n < 2; ++n) _Pragma("unroll") for (int k = 0; k < 2; ++k) \
;         acc[ai][bj][m][n] = __builtin_amdgcn_mfma_f32_16x16x32_bf16(Bt[n][k], At[m][k], acc[ai][bj][m][n], 0, 0, 0); __builtin_amdgcn_s_setprio(0); } while (0)
; #define PG8_WAIT_V(n) asm volatile("s_waitcnt vmcnt(" #n ")" ::: "memory")
; #define PG8_WAIT_L(n) asm volatile("s_waitcnt lgkmcnt(" #n ")" ::: "memory")
; #define PG8_BAR __builtin_amdgcn_s_barrier()
; #define PG8_SCHED __builtin_amdgcn_sched_barrier(0)
; template <class Epi, class Sched, bool ALIGN_EPI = false, bool SP2 = false>
; __device__ __forceinline__ void gemm_phase(PG8_LAS unsigned char* lds, const Gemm g, const Sched& S, const Epi& E) {
;     ...
;             PG8_LDB(B0, 0, 0); PG8_LDB(B1, 0, 1); PG8_SCHED; PG8_LDA(At, 0, 0); PG8_STAGE(PG8_SA(1, 1), a1 + hstep, voffA);
;             PG8_WAIT_V(8); PG8_WAIT_L(0); PG8_BAR; PG8_MMA(0, 0, At, B0); PG8_MMA(0, 1, At, B1); PG8_BAR; PG8_SCHED;
;             PG8_LDA(At, 0, 1); PG8_STAGE(PG8_SB(0, 0), b2, voffB); PG8_STAGE(PG8_SB(0, 1), b2 + hstep, voffB); PG8_STAGE(PG8_SA(0, 0), a2, voffA);
;             PG8_WAIT_V(8); PG8_WAIT_L(0); PG8_BAR; PG8_MMA(1, 0, At, B0); PG8_MMA(1, 1, At, B1); PG8_BAR; PG8_SCHED;
	s_setprio 1
	s_waitcnt lgkmcnt(0)
	v_mfma_f32_16x16x32_bf16 v[124:127], v[148:151], v[180:183], v[124:127]
	v_mfma_f32_16x16x32_bf16 v[120:123], v[156:159], v[180:183], v[120:123]
	v_mfma_f32_16x16x32_bf16 v[116:119], v[148:151], v[188:191], v[116:119]
	v_mfma_f32_16x16x32_bf16 v[112:115], v[156:159], v[188:191], v[112:115]
	v_mfma_f32_16x16x32_bf16 v[100:103], v[148:151], v[196:199], v[100:103]
	v_mfma_f32_16x16x32_bf16 v[96:99], v[156:159], v[196:199], v[96:99]
	v_mfma_f32_16x16x32_bf16 v[84:87], v[148:151], v[208:211], v[84:87]
	v_mfma_f32_16x16x32_bf16 v[80:83], v[156:159], v[208:211], v[80:83]
	v_mfma_f32_16x16x32_bf16 v[124:127], v[152:155], v[184:187], v[124:127]
	v_mfma_f32_16x16x32_bf16 v[120:123], v[160:163], v[184:187], v[120:123]
	v_mfma_f32_16x16x32_bf16 v[116:119], v[152:155], v[192:195], v[116:119]
	v_mfma_f32_16x16x32_bf16 v[112:115], v[160:163], v[192:195], v[112:115]
	v_mfma_f32_16x16x32_bf16 v[100:103], v[152:155], v[200:203], v[100:103]
	v_mfma_f32_16x16x32_bf16 v[96:99], v[160:163], v[200:203], v[96:99]
	v_mfma_f32_16x16x32_bf16 v[84:87], v[152:155], v[212:215], v[84:87]
	v_mfma_f32_16x16x32_bf16 v[80:83], v[160:163], v[212:215], v[80:83]
	v_mfma_f32_16x16x32_bf16 v[108:111], v[164:167], v[180:183], v[108:111]
	v_mfma_f32_16x16x32_bf16 v[104:107], v[172:175], v[180:183], v[104:107]
	v_mfma_f32_16x16x32_bf16 v[92:95], v[164:167], v[188:191], v[92:95]
	v_mfma_f32_16x16x32_bf16 v[88:91], v[172:175], v[188:191], v[88:91]
	v_mfma_f32_16x16x32_bf16 v[76:79], v[164:167], v[196:199], v[76:79]
	v_mfma_f32_16x16x32_bf16 v[72:75], v[172:175], v[196:199], v[72:75]
	v_mfma_f32_16x16x32_bf16 v[68:71], v[164:167], v[208:211], v[68:71]
	v_mfma_f32_16x16x32_bf16 v[64:67], v[172:175], v[208:211], v[64:67]
	v_mfma_f32_16x16x32_bf16 v[108:111], v[168:171], v[184:187], v[108:111]
	v_mfma_f32_16x16x32_bf16 v[104:107], v[176:179], v[184:187], v[104:107]
	v_mfma_f32_16x16x32_bf16 v[92:95], v[168:171], v[192:195], v[92:95]
	v_mfma_f32_16x16x32_bf16 v[88:91], v[176:179], v[192:195], v[88:91]
	v_mfma_f32_16x16x32_bf16 v[76:79], v[168:171], v[200:203], v[76:79]
	v_mfma_f32_16x16x32_bf16 v[72:75], v[176:179], v[200:203], v[72:75]
	v_mfma_f32_16x16x32_bf16 v[68:71], v[168:171], v[212:215], v[68:71]
	v_mfma_f32_16x16x32_bf16 v[64:67], v[176:179], v[212:215], v[64:67]
	s_setprio 0
	s_barrier
	s_add_i32 s93, s76, s65
	v_lshl_add_u64 v[204:205], s[58:59], 0, v[130:131]
	s_mov_b32 m0, s93
	ds_read_b128 v[180:183], v147 offset:16384
	ds_read_b128 v[184:187], v147 offset:17408
	ds_read_b128 v[188:191], v147 offset:18432
	ds_read_b128 v[192:195], v147 offset:19456
	ds_read_b128 v[196:199], v147 offset:20480
	ds_read_b128 v[200:203], v147 offset:21504
	ds_read_b128 v[208:211], v147 offset:22528
	ds_read_b128 v[212:215], v147 offset:23552
	global_load_lds_dwordx4 v[204:205], off
	s_add_i32 m0, s93, 0x2000
	s_add_u32 s94, s58, 0x40000
	v_lshl_add_u64 v[216:217], s[58:59], 0, v[134:135]
	s_addc_u32 s95, s59, 0
	s_add_i32 s93, s77, s65
	global_load_lds_dwordx4 v[216:217], off
	v_lshl_add_u64 v[218:219], s[94:95], 0, v[130:131]
	s_mov_b32 m0, s93
	v_lshl_add_u64 v[220:221], s[60:61], 0, v[132:133]
	global_load_lds_dwordx4 v[218:219], off
	v_lshl_add_u64 v[218:219], s[94:95], 0, v[134:135]
	s_add_i32 m0, s93, 0x2000
	s_nop 0
	global_load_lds_dwordx4 v[218:219], off
	v_lshl_add_u64 v[218:219], s[60:61], 0, v[128:129]
	s_mov_b32 m0, s66
	s_nop 0
	global_load_lds_dwordx4 v[218:219], off
	s_mov_b32 m0, s67
	s_nop 0
	global_load_lds_dwordx4 v[220:221], off
	s_waitcnt vmcnt(8)
	s_waitcnt lgkmcnt(0)
	s_barrier
	s_setprio 1
	s_waitcnt lgkmcnt(0)
	v_mfma_f32_16x16x32_bf16 v[60:63], v[148:151], v[180:183], v[60:63]
	v_mfma_f32_16x16x32_bf16 v[56:59], v[156:159], v[180:183], v[56:59]
	v_mfma_f32_16x16x32_bf16 v[52:55], v[148:151], v[188:191], v[52:55]
	v_mfma_f32_16x16x32_bf16 v[48:51], v[156:159], v[188:191], v[48:51]
	v_mfma_f32_16x16x32_bf16 v[36:39], v[148:151], v[196:199], v[36:39]
	v_mfma_f32_16x16x32_bf16 v[32:35], v[156:159], v[196:199], v[32:35]
	v_mfma_f32_16x16x32_bf16 v[20:23], v[148:151], v[208:211], v[20:23]
	v_mfma_f32_16x16x32_bf16 v[16:19], v[156:159], v[208:211], v[16:19]
	v_mfma_f32_16x16x32_bf16 v[60:63], v[152:155], v[184:187], v[60:63]
	v_mfma_f32_16x16x32_bf16 v[56:59], v[160:163], v[184:187], v[56:59]
	v_mfma_f32_16x16x32_bf16 v[52:55], v[152:155], v[192:195], v[52:55]
	v_mfma_f32_16x16x32_bf16 v[48:51], v[160:163], v[192:195], v[48:51]
	v_mfma_f32_16x16x32_bf16 v[36:39], v[152:155], v[200:203], v[36:39]
	v_mfma_f32_16x16x32_bf16 v[32:35], v[160:163], v[200:203], v[32:35]
	v_mfma_f32_16x16x32_bf16 v[20:23], v[152:155], v[212:215], v[20:23]
	v_mfma_f32_16x16x32_bf16 v[16:19], v[160:163], v[212:215], v[16:19]
	v_mfma_f32_16x16x32_bf16 v[44:47], v[164:167], v[180:183], v[44:47]
	v_mfma_f32_16x16x32_bf16 v[40:43], v[172:175], v[180:183], v[40:43]
	v_mfma_f32_16x16x32_bf16 v[28:31], v[164:167], v[188:191], v[28:31]
	v_mfma_f32_16x16x32_bf16 v[24:27], v[172:175], v[188:191], v[24:27]
	v_mfma_f32_16x16x32_bf16 v[12:15], v[164:167], v[196:199], v[12:15]
	v_mfma_f32_16x16x32_bf16 v[8:11], v[172:175], v[196:199], v[8:11]
	v_mfma_f32_16x16x32_bf16 v[4:7], v[164:167], v[208:211], v[4:7]
	v_mfma_f32_16x16x32_bf16 v[0:3], v[172:175], v[208:211], v[0:3]
	v_mfma_f32_16x16x32_bf16 v[44:47], v[168:171], v[184:187], v[44:47]
	v_mfma_f32_16x16x32_bf16 v[40:43], v[176:179], v[184:187], v[40:43]
	v_mfma_f32_16x16x32_bf16 v[28:31], v[168:171], v[192:195], v[28:31]
	v_mfma_f32_16x16x32_bf16 v[24:27], v[176:179], v[192:195], v[24:27]
	v_mfma_f32_16x16x32_bf16 v[12:15], v[168:171], v[200:203], v[12:15]
	v_mfma_f32_16x16x32_bf16 v[8:11], v[176:179], v[200:203], v[8:11]
	v_mfma_f32_16x16x32_bf16 v[4:7], v[168:171], v[212:215], v[4:7]
	v_mfma_f32_16x16x32_bf16 v[0:3], v[176:179], v[212:215], v[0:3]
	s_setprio 0
	s_barrier
; #define PG8_STAGE(bufoff, gbase, voff) do { _Pragma("unroll") for (int _i = 0; _i < 2; ++_i) \
;         __builtin_amdgcn_global_load_lds((const unsigned*)((const char*)(gbase) + (voff)[_i]), (PG8_LAS unsigned*)(lds + (bufoff) + ldsw + _i * 8192), 16, 0, 0); } while (0)
; #define PG8_LDA(dst, b, h) do { _Pragma("unroll") for (int m = 0; m < 4; ++m) _Pragma("unroll") for (int k = 0; k < 2; ++k) dst[m][k] = *(const PG8_LAS bf16x8*)(lds + PG8_SA(b, h) + aoff + m * 2048 + k * 1024); } while (0)
; #define PG8_LDB(dst, b, h) do { _Pragma("unroll") for (int n = 0; n < 2; ++n) _Pragma("unroll") for (int k = 0; k < 2; ++k) dst[n][k] = *(const PG8_LAS bf16x8*)(lds + PG8_SB(b, h) + boff + n * 2048 + k * 1024); } while (0)
; #define PG8_MMA(ai, bj, At, Bt) do { __builtin_amdgcn_s_setprio(1); _Pragma("unroll") for (int m = 0; m < 4; ++m) _Pragma("unroll") for (int n = 0; n < 2; ++n) _Pragma("unroll") for (int k = 0; k < 2; ++k) \
;         acc[ai][bj][m][n] = __builtin_amdgcn_mfma_f32_16x16x32_bf16(Bt[n][k], At[m][k], acc[ai][bj][m][n], 0, 0, 0); __builtin_amdgcn_s_setprio(0); } while (0)
; #define PG8_WAIT_V(n) asm volatile("s_waitcnt vmcnt(" #n ")" ::: "memory")
; #define PG8_WAIT_L(n) asm volatile("s_waitcnt lgkmcnt(" #n ")" ::: "memory")
; #define PG8_BAR __builtin_amdgcn_s_barrier()
; #define PG8_SCHED __builtin_amdgcn_sched_barrier(0)
; template <class Epi, class Sched, bool ALIGN_EPI = false, bool SP2 = false>
; __device__ __forceinline__ void gemm_phase(PG8_LAS unsigned char* lds, const Gemm g, const Sched& S, const Epi& E) {
;     ...
;             PG8_LDB(B0, 1, 0); PG8_LDB(B1, 1, 1); PG8_SCHED; PG8_LDA(At, 1, 0); PG8_STAGE(PG8_SA(0, 1), a2 + hstep, voffA);
;             PG8_WAIT_V(8); PG8_WAIT_L(0); PG8_BAR; PG8_MMA(0, 0, At, B0); PG8_MMA(0, 1, At, B1); PG8_BAR; PG8_SCHED;
	s_add_i32 s93, 0, 0x18000
	s_add_i32 s94, 0, 0x1c000
	v_add_u32_e32 v160, s93, v143
	v_add_u32_e32 v176, s94, v143
	ds_read_b128 v[148:151], v160
	ds_read_b128 v[152:155], v160 offset:1024
	ds_read_b128 v[156:159], v160 offset:2048
	ds_read_b128 v[160:163], v160 offset:3072
	ds_read_b128 v[164:167], v176
	ds_read_b128 v[168:171], v176 offset:1024
	ds_read_b128 v[172:175], v176 offset:2048
	ds_read_b128 v[176:179], v176 offset:3072
	s_add_u32 s60, s60, 0x40000
	s_addc_u32 s61, s61, 0
	s_mov_b32 m0, s68
	v_lshl_add_u64 v[222:223], s[60:61], 0, v[128:129]
	ds_read_b128 v[180:183], v147 offset:32768
	ds_read_b128 v[184:187], v147 offset:33792
	ds_read_b128 v[188:191], v147 offset:34816
	ds_read_b128 v[192:195], v147 offset:35840
	ds_read_b128 v[196:199], v147 offset:36864
	ds_read_b128 v[200:203], v147 offset:37888
	ds_read_b128 v[208:211], v147 offset:38912
	ds_read_b128 v[212:215], v147 offset:39936
	global_load_lds_dwordx4 v[222:223], off
	v_lshl_add_u64 v[222:223], s[60:61], 0, v[132:133]
	s_mov_b32 m0, s69
	s_nop 0
	global_load_lds_dwordx4 v[222:223], off
	s_waitcnt vmcnt(8)
	s_waitcnt lgkmcnt(0)
	s_barrier
	s_setprio 1
	s_waitcnt lgkmcnt(0)
	v_mfma_f32_16x16x32_bf16 v[124:127], v[148:151], v[180:183], v[124:127]
	v_mfma_f32_16x16x32_bf16 v[120:123], v[156:159], v[180:183], v[120:123]
	v_mfma_f32_16x16x32_bf16 v[116:119], v[148:151], v[188:191], v[116:119]
	v_mfma_f32_16x16x32_bf16 v[112:115], v[156:159], v[188:191], v[112:115]
	v_mfma_f32_16x16x32_bf16 v[100:103], v[148:151], v[196:199], v[100:103]
	v_mfma_f32_16x16x32_bf16 v[96:99], v[156:159], v[196:199], v[96:99]
	v_mfma_f32_16x16x32_bf16 v[84:87], v[148:151], v[208:211], v[84:87]
	v_mfma_f32_16x16x32_bf16 v[80:83], v[156:159], v[208:211], v[80:83]
	v_mfma_f32_16x16x32_bf16 v[124:127], v[152:155], v[184:187], v[124:127]
	v_mfma_f32_16x16x32_bf16 v[120:123], v[160:163], v[184:187], v[120:123]
	v_mfma_f32_16x16x32_bf16 v[116:119], v[152:155], v[192:195], v[116:119]
	v_mfma_f32_16x16x32_bf16 v[112:115], v[160:163], v[192:195], v[112:115]
	v_mfma_f32_16x16x32_bf16 v[100:103], v[152:155], v[200:203], v[100:103]
	v_mfma_f32_16x16x32_bf16 v[96:99], v[160:163], v[200:203], v[96:99]
	v_mfma_f32_16x16x32_bf16 v[84:87], v[152:155], v[212:215], v[84:87]
	v_mfma_f32_16x16x32_bf16 v[80:83], v[160:163], v[212:215], v[80:83]
	v_mfma_f32_16x16x32_bf16 v[108:111], v[164:167], v[180:183], v[108:111]
	v_mfma_f32_16x16x32_bf16 v[104:107], v[172:175], v[180:183], v[104:107]
	v_mfma_f32_16x16x32_bf16 v[92:95], v[164:167], v[188:191], v[92:95]
	v_mfma_f32_16x16x32_bf16 v[88:91], v[172:175], v[188:191], v[88:91]
	v_mfma_f32_16x16x32_bf16 v[76:79], v[164:167], v[196:199], v[76:79]
	v_mfma_f32_16x16x32_bf16 v[72:75], v[172:175], v[196:199], v[72:75]
	v_mfma_f32_16x16x32_bf16 v[68:71], v[164:167], v[208:211], v[68:71]
	v_mfma_f32_16x16x32_bf16 v[64:67], v[172:175], v[208:211], v[64:67]
	v_mfma_f32_16x16x32_bf16 v[108:111], v[168:171], v[184:187], v[108:111]
	v_mfma_f32_16x16x32_bf16 v[104:107], v[176:179], v[184:187], v[104:107]
	v_mfma_f32_16x16x32_bf16 v[92:95], v[168:171], v[192:195], v[92:95]
	v_mfma_f32_16x16x32_bf16 v[88:91], v[176:179], v[192:195], v[88:91]
	v_mfma_f32_16x16x32_bf16 v[76:79], v[168:171], v[200:203], v[76:79]
	v_mfma_f32_16x16x32_bf16 v[72:75], v[176:179], v[200:203], v[72:75]
	v_mfma_f32_16x16x32_bf16 v[68:71], v[168:171], v[212:215], v[68:71]
	v_mfma_f32_16x16x32_bf16 v[64:67], v[176:179], v[212:215], v[64:67]
	s_setprio 0
	s_barrier
; #define PG8_STAGE(bufoff, gbase, voff) do { _Pragma("unroll") for (int _i = 0; _i < 2; ++_i) \
;         __builtin_amdgcn_global_load_lds((const unsigned*)((const char*)(gbase) + (voff)[_i]), (PG8_LAS unsigned*)(lds + (bufoff) + ldsw + _i * 8192), 16, 0, 0); } while (0)
; #define PG8_LDA(dst, b, h) do { _Pragma("unroll") for (int m = 0; m < 4; ++m) _Pragma("unroll") for (int k = 0; k < 2; ++k) dst[m][k] = *(const PG8_LAS bf16x8*)(lds + PG8_SA(b, h) + aoff + m * 2048 + k * 1024); } while (0)
; #define PG8_MMA(ai, bj, At, Bt) do { __builtin_amdgcn_s_setprio(1); _Pragma("unroll") for (int m = 0; m < 4; ++m) _Pragma("unroll") for (int n = 0; n < 2; ++n) _Pragma("unroll") for (int k = 0; k < 2; ++k) \
;         acc[ai][bj][m][n] = __builtin_amdgcn_mfma_f32_16x16x32_bf16(Bt[n][k], At[m][k], acc[ai][bj][m][n], 0, 0, 0); __builtin_amdgcn_s_setprio(0); } while (0)
; #define PG8_WAIT_V(n) asm volatile("s_waitcnt vmcnt(" #n ")" ::: "memory")
; #define PG8_WAIT_L(n) asm volatile("s_waitcnt lgkmcnt(" #n ")" ::: "memory")
; #define PG8_BAR __builtin_amdgcn_s_barrier()
; #define PG8_SCHED __builtin_amdgcn_sched_barrier(0)
; template <class Epi, class Sched, bool ALIGN_EPI = false, bool SP2 = false>
; __device__ __forceinline__ void gemm_phase(PG8_LAS unsigned char* lds, const Gemm g, const Sched& S, const Epi& E) {
;     ...
;             PG8_LDA(At, 1, 1); PG8_STAGE(PG8_SB(1, 0), b3, voffB); PG8_STAGE(PG8_SB(1, 1), b3 + hstep, voffB); PG8_STAGE(PG8_SA(1, 0), a3, voffA);
;             PG8_WAIT_V(8); PG8_WAIT_L(0); PG8_BAR; PG8_MMA(1, 0, At, B0); PG8_MMA(1, 1, At, B1); PG8_BAR; PG8_SCHED;
	s_add_i32 s60, s93, s65
	v_lshl_add_u64 v[204:205], v[204:205], 0, s[18:19]
	s_mov_b32 m0, s60
	ds_read_b128 v[180:183], v147 offset:49152
	ds_read_b128 v[184:187], v147 offset:50176
	ds_read_b128 v[188:191], v147 offset:51200
	ds_read_b128 v[192:195], v147 offset:52224
	ds_read_b128 v[196:199], v147 offset:53248
	ds_read_b128 v[200:203], v147 offset:54272
	ds_read_b128 v[208:211], v147 offset:55296
	ds_read_b128 v[212:215], v147 offset:56320
	global_load_lds_dwordx4 v[204:205], off
	s_add_i32 m0, s60, 0x2000
	s_add_u32 s58, s58, 0x40080
	v_lshl_add_u64 v[204:205], v[216:217], 0, s[18:19]
	s_addc_u32 s59, s59, 0
	s_add_i32 s60, s94, s65
	global_load_lds_dwordx4 v[204:205], off
	v_lshl_add_u64 v[204:205], s[58:59], 0, v[130:131]
	s_mov_b32 m0, s60
	s_nop 0
	global_load_lds_dwordx4 v[204:205], off
	v_lshl_add_u64 v[204:205], s[58:59], 0, v[134:135]
	s_add_i32 m0, s60, 0x2000
	s_nop 0
	global_load_lds_dwordx4 v[204:205], off
	v_lshl_add_u64 v[204:205], v[218:219], 0, s[18:19]
	s_mov_b32 m0, s73
	s_nop 0
	global_load_lds_dwordx4 v[204:205], off
	v_lshl_add_u64 v[204:205], v[220:221], 0, s[18:19]
	s_mov_b32 m0, s74
	s_nop 0
	global_load_lds_dwordx4 v[204:205], off
	s_waitcnt vmcnt(8)
	s_waitcnt lgkmcnt(0)
	s_barrier
	s_setprio 1
	s_waitcnt lgkmcnt(0)
	v_mfma_f32_16x16x32_bf16 v[60:63], v[148:151], v[180:183], v[60:63]
	v_mfma_f32_16x16x32_bf16 v[56:59], v[156:159], v[180:183], v[56:59]
	v_mfma_f32_16x16x32_bf16 v[52:55], v[148:151], v[188:191], v[52:55]
	v_mfma_f32_16x16x32_bf16 v[48:51], v[156:159], v[188:191], v[48:51]
	v_mfma_f32_16x16x32_bf16 v[36:39], v[148:151], v[196:199], v[36:39]
	v_mfma_f32_16x16x32_bf16 v[32:35], v[156:159], v[196:199], v[32:35]
	v_mfma_f32_16x16x32_bf16 v[20:23], v[148:151], v[208:211], v[20:23]
	v_mfma_f32_16x16x32_bf16 v[16:19], v[156:159], v[208:211], v[16:19]
	v_mfma_f32_16x16x32_bf16 v[60:63], v[152:155], v[184:187], v[60:63]
	v_mfma_f32_16x16x32_bf16 v[56:59], v[160:163], v[184:187], v[56:59]
	v_mfma_f32_16x16x32_bf16 v[52:55], v[152:155], v[192:195], v[52:55]
	v_mfma_f32_16x16x32_bf16 v[48:51], v[160:163], v[192:195], v[48:51]
	v_mfma_f32_16x16x32_bf16 v[36:39], v[152:155], v[200:203], v[36:39]
	v_mfma_f32_16x16x32_bf16 v[32:35], v[160:163], v[200:203], v[32:35]
	v_mfma_f32_16x16x32_bf16 v[20:23], v[152:155], v[212:215], v[20:23]
	v_mfma_f32_16x16x32_bf16 v[16:19], v[160:163], v[212:215], v[16:19]
	v_mfma_f32_16x16x32_bf16 v[44:47], v[164:167], v[180:183], v[44:47]
	v_mfma_f32_16x16x32_bf16 v[40:43], v[172:175], v[180:183], v[40:43]
	v_mfma_f32_16x16x32_bf16 v[28:31], v[164:167], v[188:191], v[28:31]
	v_mfma_f32_16x16x32_bf16 v[24:27], v[172:175], v[188:191], v[24:27]
	v_mfma_f32_16x16x32_bf16 v[12:15], v[164:167], v[196:199], v[12:15]
	v_mfma_f32_16x16x32_bf16 v[8:11], v[172:175], v[196:199], v[8:11]
	v_mfma_f32_16x16x32_bf16 v[4:7], v[164:167], v[208:211], v[4:7]
	v_mfma_f32_16x16x32_bf16 v[0:3], v[172:175], v[208:211], v[0:3]
	v_mfma_f32_16x16x32_bf16 v[44:47], v[168:171], v[184:187], v[44:47]
	v_mfma_f32_16x16x32_bf16 v[40:43], v[176:179], v[184:187], v[40:43]
	v_mfma_f32_16x16x32_bf16 v[28:31], v[168:171], v[192:195], v[28:31]
	v_mfma_f32_16x16x32_bf16 v[24:27], v[176:179], v[192:195], v[24:27]
	v_mfma_f32_16x16x32_bf16 v[12:15], v[168:171], v[200:203], v[12:15]
	v_mfma_f32_16x16x32_bf16 v[8:11], v[176:179], v[200:203], v[8:11]
	v_mfma_f32_16x16x32_bf16 v[4:7], v[168:171], v[212:215], v[4:7]
	v_mfma_f32_16x16x32_bf16 v[0:3], v[176:179], v[212:215], v[0:3]
	s_setprio 0
	s_barrier
	s_add_i32 s92, s92, 2
	s_add_u32 s56, s56, 0x100
	s_addc_u32 s57, s57, 0
	s_add_u32 s90, s90, 0x100
	s_addc_u32 s91, s91, 0
	s_cmp_gt_u32 s92, 13
	s_cbranch_scc0 .LBB0_659

;     __device__ __forceinline__ bool next(int i, Unit& u) const { if (i != 0) return false; const int c0 = (G >= 8) ? G - 5 : G - 2; int k = -1; if (c == c0) k = 0; else if (c == G - 1) k = 1; if (k < 0 || k >= n) return false; u.pm = k; u.pn = 0; return true; }
; #define PG8_STAGE(bufoff, gbase, voff) do { _Pragma("unroll") for (int _i = 0; _i < 2; ++_i) \
;         __builtin_amdgcn_global_load_lds((const unsigned*)((const char*)(gbase) + (voff)[_i]), (PG8_LAS unsigned*)(lds + (bufoff) + ldsw + _i * 8192), 16, 0, 0); } while (0)
; #define PG8_LDA(dst, b, h) do { _Pragma("unroll") for (int m = 0; m < 4; ++m) _Pragma("unroll") for (int k = 0; k < 2; ++k) dst[m][k] = *(const PG8_LAS bf16x8*)(lds + PG8_SA(b, h) + aoff + m * 2048 + k * 1024); } while (0)
; #define PG8_LDB(dst, b, h) do { _Pragma("unroll") for (int n = 0; n < 2; ++n) _Pragma("unroll") for (int k = 0; k < 2; ++k) dst[n][k] = *(const PG8_LAS bf16x8*)(lds + PG8_SB(b, h) + boff + n * 2048 + k * 1024); } while (0)
; template <class Epi, class Sched, bool ALIGN_EPI = false, bool SP2 = false>
; __device__ __forceinline__ void gemm_phase(PG8_LAS unsigned char* lds, const Gemm g, const Sched& S, const Epi& E) {
;     ...
;         const bool has_next = S.next(ui + 1, nxt);
;         const char* nA = has_next ? (const char*)g.A + (size_t)nxt.pm * tstep : cA; const char* nB = has_next ? (const char*)g.Bt + (size_t)nxt.pn * tstep : cB;
;         for (int t = 0; t < nt; t += 2) {
;             const bool last = (t == nt - 2);
;             const char* a1 = cA + (size_t)(t + 1) * kstep;
;             const char* a2 = last ? nA : cA + (size_t)(t + 2) * kstep; const char* b2 = last ? nB : cB + (size_t)(t + 2) * kstep;
;             const char* a3 = a2 + kstep; const char* b3 = b2 + kstep;
;             if (last && has_next) S.a_ready(nxt);
;             if constexpr (SP2) {
;             PG8_LDB(B0, 0, 0); PG8_LDB(B1, 0, 1); PG8_SCHED; PG8_LDA(At, 0, 0); PG8_STAGE(PG8_SA(1, 1), a1 + hstep, voffA);
;             PG8_WAIT_V(8); PG8_WAIT_L(0); PG8_BAR; PG8_MMA(0, 0, At, B0); PG8_MMA(0, 1, At, B1); PG8_BAR; PG8_SCHED;
;             PG8_LDA(At, 0, 1); PG8_STAGE(PG8_SB(0, 0), b2, voffB); PG8_STAGE(PG8_SB(0, 1), b2 + hstep, voffB); PG8_STAGE(PG8_SA(0, 0), a2, voffA);
;             PG8_WAIT_V(8); PG8_WAIT_L(0); PG8_BAR; PG8_MMA(1, 0, At, B0); PG8_MMA(1, 1, At, B1); PG8_BAR; PG8_SCHED;
.LBB0_855:
	s_ashr_i32 s23, s22, 31
	s_lshl_b64 s[26:27], s[22:23], 19
	s_add_u32 s26, s97, s26
	s_addc_u32 s27, s3, s27
	s_and_b64 s[28:29], s[24:25], exec
	s_cselect_b32 s23, s27, s39
	s_cselect_b32 s74, s26, s38
	s_ashr_i32 s21, s20, 31
	s_lshl_b64 s[28:29], s[20:21], 19
	s_add_u32 s28, s46, s28
	s_addc_u32 s29, s47, s29
	s_and_b64 s[42:43], s[24:25], exec
	s_cselect_b32 s21, s29, s41
	s_cselect_b32 s75, s28, s40
	s_add_u32 s38, s38, 0x40080
	s_addc_u32 s39, s39, 0
	s_add_u32 s76, s40, 0x100
	v_mov_b32_e32 v0, 0
	s_addc_u32 s77, s41, 0
	s_mov_b32 s78, -2
	ds_read_b128 v[164:167], v160
	ds_read_b128 v[168:171], v160 offset:1024
	ds_read_b128 v[172:175], v160 offset:2048
	ds_read_b128 v[176:179], v160 offset:3072
	ds_read_b128 v[180:183], v161
	ds_read_b128 v[184:187], v161 offset:1024
	ds_read_b128 v[188:191], v161 offset:2048
	ds_read_b128 v[192:195], v161 offset:3072
	s_add_u32 s40, s38, 0xfffc0080
	s_addc_u32 s41, s39, -1
	s_cmp_eq_u32 s78, 12
	s_cselect_b32 s43, s23, s41
	s_cselect_b32 s42, s74, s40
	s_cselect_b32 s41, s21, s77
	s_cselect_b32 s40, s75, s76
	v_lshl_add_u64 v[142:143], s[38:39], 0, v[136:137]
	s_add_i32 m0, s31, 0xc000
	ds_read_b128 v[196:199], v162
	ds_read_b128 v[200:203], v162 offset:1024
	ds_read_b128 v[208:211], v162 offset:2048
	ds_read_b128 v[212:215], v162 offset:3072
	ds_read_b128 v[216:219], v162 offset:4096
	ds_read_b128 v[220:223], v162 offset:5120
	ds_read_b128 v[224:227], v162 offset:6144
	ds_read_b128 v[228:231], v162 offset:7168
	global_load_lds_dwordx4 v[142:143], off
	v_lshl_add_u64 v[142:143], s[38:39], 0, v[138:139]
	s_add_i32 m0, s31, 0xe000
	s_nop 0
	global_load_lds_dwordx4 v[142:143], off
	s_waitcnt vmcnt(8)
	s_waitcnt lgkmcnt(0)
	s_barrier
	s_setprio 1
	s_waitcnt lgkmcnt(0)
	v_mfma_f32_16x16x32_bf16 v[124:127], v[164:167], v[196:199], 0
	v_mfma_f32_16x16x32_bf16 v[120:123], v[172:175], v[196:199], 0
	v_mfma_f32_16x16x32_bf16 v[108:111], v[164:167], v[208:211], 0
	v_mfma_f32_16x16x32_bf16 v[104:107], v[172:175], v[208:211], 0
	v_mfma_f32_16x16x32_bf16 v[92:95], v[164:167], v[216:219], 0
	v_mfma_f32_16x16x32_bf16 v[88:91], v[172:175], v[216:219], 0
	v_mfma_f32_16x16x32_bf16 v[76:79], v[164:167], v[224:227], 0
	v_mfma_f32_16x16x32_bf16 v[72:75], v[172:175], v[224:227], 0
	v_mfma_f32_16x16x32_bf16 v[124:127], v[168:171], v[200:203], v[124:127]
	v_mfma_f32_16x16x32_bf16 v[120:123], v[176:179], v[200:203], v[120:123]
	v_mfma_f32_16x16x32_bf16 v[108:111], v[168:171], v[212:215], v[108:111]
	v_mfma_f32_16x16x32_bf16 v[104:107], v[176:179], v[212:215], v[104:107]
	v_mfma_f32_16x16x32_bf16 v[92:95], v[168:171], v[220:223], v[92:95]
	v_mfma_f32_16x16x32_bf16 v[88:91], v[176:179], v[220:223], v[88:91]
	v_mfma_f32_16x16x32_bf16 v[76:79], v[168:171], v[228:231], v[76:79]
	v_mfma_f32_16x16x32_bf16 v[72:75], v[176:179], v[228:231], v[72:75]
	v_mfma_f32_16x16x32_bf16 v[116:119], v[180:183], v[196:199], 0
	v_mfma_f32_16x16x32_bf16 v[112:115], v[188:191], v[196:199], 0
	v_mfma_f32_16x16x32_bf16 v[100:103], v[180:183], v[208:211], 0
	v_mfma_f32_16x16x32_bf16 v[96:99], v[188:191], v[208:211], 0
	v_mfma_f32_16x16x32_bf16 v[84:87], v[180:183], v[216:219], 0
	v_mfma_f32_16x16x32_bf16 v[80:83], v[188:191], v[216:219], 0
	v_mfma_f32_16x16x32_bf16 v[68:71], v[180:183], v[224:227], 0
	v_mfma_f32_16x16x32_bf16 v[64:67], v[188:191], v[224:227], 0
	v_mfma_f32_16x16x32_bf16 v[116:119], v[184:187], v[200:203], v[116:119]
	v_mfma_f32_16x16x32_bf16 v[112:115], v[192:195], v[200:203], v[112:115]
	v_mfma_f32_16x16x32_bf16 v[100:103], v[184:187], v[212:215], v[100:103]
	v_mfma_f32_16x16x32_bf16 v[96:99], v[192:195], v[212:215], v[96:99]
	v_mfma_f32_16x16x32_bf16 v[84:87], v[184:187], v[220:223], v[84:87]
	v_mfma_f32_16x16x32_bf16 v[80:83], v[192:195], v[220:223], v[80:83]
	v_mfma_f32_16x16x32_bf16 v[68:71], v[184:187], v[228:231], v[68:71]
	v_mfma_f32_16x16x32_bf16 v[64:67], v[192:195], v[228:231], v[64:67]
	s_setprio 0
	s_barrier
	s_add_i32 s79, s69, s56
	v_lshl_add_u64 v[142:143], s[40:41], 0, v[130:131]
	s_mov_b32 m0, s79
	ds_read_b128 v[196:199], v162 offset:16384
	ds_read_b128 v[200:203], v162 offset:17408
	ds_read_b128 v[208:211], v162 offset:18432
	ds_read_b128 v[212:215], v162 offset:19456
	ds_read_b128 v[216:219], v162 offset:20480
	ds_read_b128 v[220:223], v162 offset:21504
	ds_read_b128 v[224:227], v162 offset:22528
	ds_read_b128 v[228:231], v162 offset:23552
	global_load_lds_dwordx4 v[142:143], off
	s_add_i32 m0, s79, 0x2000
	s_add_u32 s80, s40, 0x40000
	v_lshl_add_u64 v[204:205], s[40:41], 0, v[134:135]
	s_addc_u32 s81, s41, 0
	s_add_i32 s79, s71, s56
	global_load_lds_dwordx4 v[204:205], off
	v_lshl_add_u64 v[232:233], s[80:81], 0, v[130:131]
	s_mov_b32 m0, s79
	v_lshl_add_u64 v[234:235], s[42:43], 0, v[132:133]
	global_load_lds_dwordx4 v[232:233], off
	v_lshl_add_u64 v[232:233], s[80:81], 0, v[134:135]
	s_add_i32 m0, s79, 0x2000
	s_nop 0
	global_load_lds_dwordx4 v[232:233], off
	v_lshl_add_u64 v[232:233], s[42:43], 0, v[128:129]
	s_mov_b32 m0, s31
	s_nop 0
	global_load_lds_dwordx4 v[232:233], off
	s_mov_b32 m0, s59
	s_nop 0
	global_load_lds_dwordx4 v[234:235], off
	s_waitcnt vmcnt(8)
	s_waitcnt lgkmcnt(0)
	s_barrier
; #define PG8_STAGE(bufoff, gbase, voff) do { _Pragma("unroll") for (int _i = 0; _i < 2; ++_i) \
;         __builtin_amdgcn_global_load_lds((const unsigned*)((const char*)(gbase) + (voff)[_i]), (PG8_LAS unsigned*)(lds + (bufoff) + ldsw + _i * 8192), 16, 0, 0); } while (0)
; #define PG8_LDA(dst, b, h) do { _Pragma("unroll") for (int m = 0; m < 4; ++m) _Pragma("unroll") for (int k = 0; k < 2; ++k) dst[m][k] = *(const PG8_LAS bf16x8*)(lds + PG8_SA(b, h) + aoff + m * 2048 + k * 1024); } while (0)
; #define PG8_LDB(dst, b, h) do { _Pragma("unroll") for (int n = 0; n < 2; ++n) _Pragma("unroll") for (int k = 0; k < 2; ++k) dst[n][k] = *(const PG8_LAS bf16x8*)(lds + PG8_SB(b, h) + boff + n * 2048 + k * 1024); } while (0)
; #define PG8_MMA(ai, bj, At, Bt) do { __builtin_amdgcn_s_setprio(1); _Pragma("unroll") for (int m = 0; m < 4; ++m) _Pragma("unroll") for (int n = 0; n < 2; ++n) _Pragma("unroll") for (int k = 0; k < 2; ++k) \
;         acc[ai][bj][m][n] = __builtin_amdgcn_mfma_f32_16x16x32_bf16(Bt[n][k], At[m][k], acc[ai][bj][m][n], 0, 0, 0); __builtin_amdgcn_s_setprio(0); } while (0)
; #define PG8_WAIT_V(n) asm volatile("s_waitcnt vmcnt(" #n ")" ::: "memory")
; #define PG8_WAIT_L(n) asm volatile("s_waitcnt lgkmcnt(" #n ")" ::: "memory")
; #define PG8_BAR __builtin_amdgcn_s_barrier()
; #define PG8_SCHED __builtin_amdgcn_sched_barrier(0)
; template <class Epi, class Sched, bool ALIGN_EPI = false, bool SP2 = false>
; __device__ __forceinline__ void gemm_phase(PG8_LAS unsigned char* lds, const Gemm g, const Sched& S, const Epi& E) {
;     ...
;             PG8_LDA(At, 0, 1); PG8_STAGE(PG8_SB(0, 0), b2, voffB); PG8_STAGE(PG8_SB(0, 1), b2 + hstep, voffB); PG8_STAGE(PG8_SA(0, 0), a2, voffA);
;             PG8_WAIT_V(8); PG8_WAIT_L(0); PG8_BAR; PG8_MMA(1, 0, At, B0); PG8_MMA(1, 1, At, B1); PG8_BAR; PG8_SCHED;
;             PG8_LDB(B0, 1, 0); PG8_LDB(B1, 1, 1); PG8_SCHED; PG8_LDA(At, 1, 0); PG8_STAGE(PG8_SA(0, 1), a2 + hstep, voffA);
;             PG8_WAIT_V(8); PG8_WAIT_L(0); PG8_BAR; PG8_MMA(0, 0, At, B0); PG8_MMA(0, 1, At, B1); PG8_BAR; PG8_SCHED;
	s_setprio 1
	s_waitcnt lgkmcnt(0)
	v_mfma_f32_16x16x32_bf16 v[60:63], v[164:167], v[196:199], 0
	v_mfma_f32_16x16x32_bf16 v[56:59], v[172:175], v[196:199], 0
	v_mfma_f32_16x16x32_bf16 v[44:47], v[164:167], v[208:211], 0
	v_mfma_f32_16x16x32_bf16 v[40:43], v[172:175], v[208:211], 0
	v_mfma_f32_16x16x32_bf16 v[28:31], v[164:167], v[216:219], 0
	v_mfma_f32_16x16x32_bf16 v[24:27], v[172:175], v[216:219], 0
	v_mfma_f32_16x16x32_bf16 v[12:15], v[164:167], v[224:227], 0
	v_mfma_f32_16x16x32_bf16 v[8:11], v[172:175], v[224:227], 0
	v_mfma_f32_16x16x32_bf16 v[60:63], v[168:171], v[200:203], v[60:63]
	v_mfma_f32_16x16x32_bf16 v[56:59], v[176:179], v[200:203], v[56:59]
	v_mfma_f32_16x16x32_bf16 v[44:47], v[168:171], v[212:215], v[44:47]
	v_mfma_f32_16x16x32_bf16 v[40:43], v[176:179], v[212:215], v[40:43]
	v_mfma_f32_16x16x32_bf16 v[28:31], v[168:171], v[220:223], v[28:31]
	v_mfma_f32_16x16x32_bf16 v[24:27], v[176:179], v[220:223], v[24:27]
	v_mfma_f32_16x16x32_bf16 v[12:15], v[168:171], v[228:231], v[12:15]
	v_mfma_f32_16x16x32_bf16 v[8:11], v[176:179], v[228:231], v[8:11]
	v_mfma_f32_16x16x32_bf16 v[52:55], v[180:183], v[196:199], 0
	v_mfma_f32_16x16x32_bf16 v[48:51], v[188:191], v[196:199], 0
	v_mfma_f32_16x16x32_bf16 v[36:39], v[180:183], v[208:211], 0
	v_mfma_f32_16x16x32_bf16 v[32:35], v[188:191], v[208:211], 0
	v_mfma_f32_16x16x32_bf16 v[20:23], v[180:183], v[216:219], 0
	v_mfma_f32_16x16x32_bf16 v[16:19], v[188:191], v[216:219], 0
	v_mfma_f32_16x16x32_bf16 v[4:7], v[180:183], v[224:227], 0
	v_mfma_f32_16x16x32_bf16 v[0:3], v[188:191], v[224:227], 0
	v_mfma_f32_16x16x32_bf16 v[52:55], v[184:187], v[200:203], v[52:55]
	v_mfma_f32_16x16x32_bf16 v[48:51], v[192:195], v[200:203], v[48:51]
	v_mfma_f32_16x16x32_bf16 v[36:39], v[184:187], v[212:215], v[36:39]
	v_mfma_f32_16x16x32_bf16 v[32:35], v[192:195], v[212:215], v[32:35]
	v_mfma_f32_16x16x32_bf16 v[20:23], v[184:187], v[220:223], v[20:23]
	v_mfma_f32_16x16x32_bf16 v[16:19], v[192:195], v[220:223], v[16:19]
	v_mfma_f32_16x16x32_bf16 v[4:7], v[184:187], v[228:231], v[4:7]
	v_mfma_f32_16x16x32_bf16 v[0:3], v[192:195], v[228:231], v[0:3]
	s_setprio 0
	s_barrier
	s_add_i32 s79, 0, 0x18000
	v_add_u32_e32 v163, s79, v158
	s_add_i32 s80, 0, 0x1c000
	ds_read_b128 v[164:167], v163
	ds_read_b128 v[168:171], v163 offset:1024
	ds_read_b128 v[172:175], v163 offset:2048
	ds_read_b128 v[176:179], v163 offset:3072
	v_add_u32_e32 v163, s80, v158
	ds_read_b128 v[180:183], v163
	ds_read_b128 v[184:187], v163 offset:1024
	ds_read_b128 v[188:191], v163 offset:2048
	ds_read_b128 v[192:195], v163 offset:3072
	s_add_u32 s42, s42, 0x40000
	s_addc_u32 s43, s43, 0
	s_mov_b32 m0, s60
	v_lshl_add_u64 v[236:237], s[42:43], 0, v[128:129]
	ds_read_b128 v[196:199], v162 offset:32768
	ds_read_b128 v[200:203], v162 offset:33792
	ds_read_b128 v[208:211], v162 offset:34816
	ds_read_b128 v[212:215], v162 offset:35840
	ds_read_b128 v[216:219], v162 offset:36864
	ds_read_b128 v[220:223], v162 offset:37888
	ds_read_b128 v[224:227], v162 offset:38912
	ds_read_b128 v[228:231], v162 offset:39936
	global_load_lds_dwordx4 v[236:237], off
	v_lshl_add_u64 v[236:237], s[42:43], 0, v[132:133]
	s_mov_b32 m0, s61
	s_nop 0
	global_load_lds_dwordx4 v[236:237], off
	s_waitcnt vmcnt(8)
	s_waitcnt lgkmcnt(0)
	s_barrier
	s_setprio 1
	s_waitcnt lgkmcnt(0)
	v_mfma_f32_16x16x32_bf16 v[124:127], v[164:167], v[196:199], v[124:127]
	v_mfma_f32_16x16x32_bf16 v[120:123], v[172:175], v[196:199], v[120:123]
	v_mfma_f32_16x16x32_bf16 v[108:111], v[164:167], v[208:211], v[108:111]
	v_mfma_f32_16x16x32_bf16 v[104:107], v[172:175], v[208:211], v[104:107]
	v_mfma_f32_16x16x32_bf16 v[92:95], v[164:167], v[216:219], v[92:95]
	v_mfma_f32_16x16x32_bf16 v[88:91], v[172:175], v[216:219], v[88:91]
	v_mfma_f32_16x16x32_bf16 v[76:79], v[164:167], v[224:227], v[76:79]
	v_mfma_f32_16x16x32_bf16 v[72:75], v[172:175], v[224:227], v[72:75]
	v_mfma_f32_16x16x32_bf16 v[124:127], v[168:171], v[200:203], v[124:127]
	v_mfma_f32_16x16x32_bf16 v[120:123], v[176:179], v[200:203], v[120:123]
	v_mfma_f32_16x16x32_bf16 v[108:111], v[168:171], v[212:215], v[108:111]
	v_mfma_f32_16x16x32_bf16 v[104:107], v[176:179], v[212:215], v[104:107]
	v_mfma_f32_16x16x32_bf16 v[92:95], v[168:171], v[220:223], v[92:95]
	v_mfma_f32_16x16x32_bf16 v[88:91], v[176:179], v[220:223], v[88:91]
	v_mfma_f32_16x16x32_bf16 v[76:79], v[168:171], v[228:231], v[76:79]
	v_mfma_f32_16x16x32_bf16 v[72:75], v[176:179], v[228:231], v[72:75]
	v_mfma_f32_16x16x32_bf16 v[116:119], v[180:183], v[196:199], v[116:119]
	v_mfma_f32_16x16x32_bf16 v[112:115], v[188:191], v[196:199], v[112:115]
	v_mfma_f32_16x16x32_bf16 v[100:103], v[180:183], v[208:211], v[100:103]
	v_mfma_f32_16x16x32_bf16 v[96:99], v[188:191], v[208:211], v[96:99]
	v_mfma_f32_16x16x32_bf16 v[84:87], v[180:183], v[216:219], v[84:87]
	v_mfma_f32_16x16x32_bf16 v[80:83], v[188:191], v[216:219], v[80:83]
	v_mfma_f32_16x16x32_bf16 v[68:71], v[180:183], v[224:227], v[68:71]
	v_mfma_f32_16x16x32_bf16 v[64:67], v[188:191], v[224:227], v[64:67]
	v_mfma_f32_16x16x32_bf16 v[116:119], v[184:187], v[200:203], v[116:119]
	v_mfma_f32_16x16x32_bf16 v[112:115], v[192:195], v[200:203], v[112:115]
	v_mfma_f32_16x16x32_bf16 v[100:103], v[184:187], v[212:215], v[100:103]
	v_mfma_f32_16x16x32_bf16 v[96:99], v[192:195], v[212:215], v[96:99]
	v_mfma_f32_16x16x32_bf16 v[84:87], v[184:187], v[220:223], v[84:87]
	v_mfma_f32_16x16x32_bf16 v[80:83], v[192:195], v[220:223], v[80:83]
	v_mfma_f32_16x16x32_bf16 v[68:71], v[184:187], v[228:231], v[68:71]
	v_mfma_f32_16x16x32_bf16 v[64:67], v[192:195], v[228:231], v[64:67]
	s_setprio 0
	s_barrier
; #define PG8_STAGE(bufoff, gbase, voff) do { _Pragma("unroll") for (int _i = 0; _i < 2; ++_i) \
;         __builtin_amdgcn_global_load_lds((const unsigned*)((const char*)(gbase) + (voff)[_i]), (PG8_LAS unsigned*)(lds + (bufoff) + ldsw + _i * 8192), 16, 0, 0); } while (0)
; #define PG8_LDA(dst, b, h) do { _Pragma("unroll") for (int m = 0; m < 4; ++m) _Pragma("unroll") for (int k = 0; k < 2; ++k) dst[m][k] = *(const PG8_LAS bf16x8*)(lds + PG8_SA(b, h) + aoff + m * 2048 + k * 1024); } while (0)
; #define PG8_LDB(dst, b, h) do { _Pragma("unroll") for (int n = 0; n < 2; ++n) _Pragma("unroll") for (int k = 0; k < 2; ++k) dst[n][k] = *(const PG8_LAS bf16x8*)(lds + PG8_SB(b, h) + boff + n * 2048 + k * 1024); } while (0)
; #define PG8_MMA(ai, bj, At, Bt) do { __builtin_amdgcn_s_setprio(1); _Pragma("unroll") for (int m = 0; m < 4; ++m) _Pragma("unroll") for (int n = 0; n < 2; ++n) _Pragma("unroll") for (int k = 0; k < 2; ++k) \
;         acc[ai][bj][m][n] = __builtin_amdgcn_mfma_f32_16x16x32_bf16(Bt[n][k], At[m][k], acc[ai][bj][m][n], 0, 0, 0); __builtin_amdgcn_s_setprio(0); } while (0)
; #define PG8_WAIT_V(n) asm volatile("s_waitcnt vmcnt(" #n ")" ::: "memory")
; template <class Epi, class Sched, bool ALIGN_EPI = false, bool SP2 = false>
; __device__ __forceinline__ void gemm_phase(PG8_LAS unsigned char* lds, const Gemm g, const Sched& S, const Epi& E) {
;     ...
;             PG8_LDB(B0, 0, 0); PG8_LDB(B1, 0, 1); PG8_SCHED; PG8_LDA(At, 0, 0); PG8_STAGE(PG8_SA(1, 1), a1 + hstep, voffA);
;             PG8_WAIT_V(8); PG8_WAIT_L(0); PG8_BAR; PG8_MMA(0, 0, At, B0); PG8_MMA(0, 1, At, B1); PG8_BAR; PG8_SCHED;
;             PG8_LDA(At, 0, 1); PG8_STAGE(PG8_SB(0, 0), b2, voffB); PG8_STAGE(PG8_SB(0, 1), b2 + hstep, voffB); PG8_STAGE(PG8_SA(0, 0), a2, voffA);
;             PG8_WAIT_V(8); PG8_WAIT_L(0); PG8_BAR; PG8_MMA(1, 0, At, B0); PG8_MMA(1, 1, At, B1); PG8_BAR; PG8_SCHED;
;             PG8_LDB(B0, 1, 0); PG8_LDB(B1, 1, 1); PG8_SCHED; PG8_LDA(At, 1, 0); PG8_STAGE(PG8_SA(0, 1), a2 + hstep, voffA);
;             PG8_WAIT_V(8); PG8_WAIT_L(0); PG8_BAR; PG8_MMA(0, 0, At, B0); PG8_MMA(0, 1, At, B1); PG8_BAR; PG8_SCHED;
;             PG8_LDA(At, 1, 1); PG8_STAGE(PG8_SB(1, 0), b3, voffB); PG8_STAGE(PG8_SB(1, 1), b3 + hstep, voffB); PG8_STAGE(PG8_SA(1, 0), a3, voffA);
;             PG8_WAIT_V(8); PG8_WAIT_L(0); PG8_BAR; PG8_MMA(1, 0, At, B0); PG8_MMA(1, 1, At, B1); PG8_BAR; PG8_SCHED;
	s_add_i32 s42, s79, s56
	v_lshl_add_u64 v[142:143], v[142:143], 0, s[8:9]
	s_mov_b32 m0, s42
	ds_read_b128 v[196:199], v162 offset:49152
	ds_read_b128 v[200:203], v162 offset:50176
	ds_read_b128 v[208:211], v162 offset:51200
	ds_read_b128 v[212:215], v162 offset:52224
	ds_read_b128 v[216:219], v162 offset:53248
	ds_read_b128 v[220:223], v162 offset:54272
	ds_read_b128 v[224:227], v162 offset:55296
	ds_read_b128 v[228:231], v162 offset:56320
	global_load_lds_dwordx4 v[142:143], off
	s_add_i32 m0, s42, 0x2000
	s_add_u32 s40, s40, 0x40080
	v_lshl_add_u64 v[142:143], v[204:205], 0, s[8:9]
	s_addc_u32 s41, s41, 0
	s_add_i32 s42, s80, s56
	global_load_lds_dwordx4 v[142:143], off
	v_lshl_add_u64 v[142:143], s[40:41], 0, v[130:131]
	s_mov_b32 m0, s42
	s_nop 0
	global_load_lds_dwordx4 v[142:143], off
	v_lshl_add_u64 v[142:143], s[40:41], 0, v[134:135]
	s_add_i32 m0, s42, 0x2000
	s_nop 0
	global_load_lds_dwordx4 v[142:143], off
	v_lshl_add_u64 v[142:143], v[232:233], 0, s[8:9]
	s_mov_b32 m0, s66
	s_nop 0
	global_load_lds_dwordx4 v[142:143], off
	v_lshl_add_u64 v[142:143], v[234:235], 0, s[8:9]
	s_mov_b32 m0, s67
	s_nop 0
	global_load_lds_dwordx4 v[142:143], off
	s_waitcnt vmcnt(8)
	s_waitcnt lgkmcnt(0)
	s_barrier
	s_setprio 1
	s_waitcnt lgkmcnt(0)
	v_mfma_f32_16x16x32_bf16 v[60:63], v[164:167], v[196:199], v[60:63]
	v_mfma_f32_16x16x32_bf16 v[56:59], v[172:175], v[196:199], v[56:59]
	v_mfma_f32_16x16x32_bf16 v[44:47], v[164:167], v[208:211], v[44:47]
	v_mfma_f32_16x16x32_bf16 v[40:43], v[172:175], v[208:211], v[40:43]
	v_mfma_f32_16x16x32_bf16 v[28:31], v[164:167], v[216:219], v[28:31]
	v_mfma_f32_16x16x32_bf16 v[24:27], v[172:175], v[216:219], v[24:27]
	v_mfma_f32_16x16x32_bf16 v[12:15], v[164:167], v[224:227], v[12:15]
	v_mfma_f32_16x16x32_bf16 v[8:11], v[172:175], v[224:227], v[8:11]
	v_mfma_f32_16x16x32_bf16 v[60:63], v[168:171], v[200:203], v[60:63]
	v_mfma_f32_16x16x32_bf16 v[56:59], v[176:179], v[200:203], v[56:59]
	v_mfma_f32_16x16x32_bf16 v[44:47], v[168:171], v[212:215], v[44:47]
	v_mfma_f32_16x16x32_bf16 v[40:43], v[176:179], v[212:215], v[40:43]
	v_mfma_f32_16x16x32_bf16 v[28:31], v[168:171], v[220:223], v[28:31]
	v_mfma_f32_16x16x32_bf16 v[24:27], v[176:179], v[220:223], v[24:27]
	v_mfma_f32_16x16x32_bf16 v[12:15], v[168:171], v[228:231], v[12:15]
	v_mfma_f32_16x16x32_bf16 v[8:11], v[176:179], v[228:231], v[8:11]
	v_mfma_f32_16x16x32_bf16 v[52:55], v[180:183], v[196:199], v[52:55]
	v_mfma_f32_16x16x32_bf16 v[48:51], v[188:191], v[196:199], v[48:51]
	v_mfma_f32_16x16x32_bf16 v[36:39], v[180:183], v[208:211], v[36:39]
	v_mfma_f32_16x16x32_bf16 v[32:35], v[188:191], v[208:211], v[32:35]
	v_mfma_f32_16x16x32_bf16 v[20:23], v[180:183], v[216:219], v[20:23]
	v_mfma_f32_16x16x32_bf16 v[16:19], v[188:191], v[216:219], v[16:19]
	v_mfma_f32_16x16x32_bf16 v[4:7], v[180:183], v[224:227], v[4:7]
	v_mfma_f32_16x16x32_bf16 v[0:3], v[188:191], v[224:227], v[0:3]
	v_mfma_f32_16x16x32_bf16 v[52:55], v[184:187], v[200:203], v[52:55]
	v_mfma_f32_16x16x32_bf16 v[48:51], v[192:195], v[200:203], v[48:51]
	v_mfma_f32_16x16x32_bf16 v[36:39], v[184:187], v[212:215], v[36:39]
	v_mfma_f32_16x16x32_bf16 v[32:35], v[192:195], v[212:215], v[32:35]
	v_mfma_f32_16x16x32_bf16 v[20:23], v[184:187], v[220:223], v[20:23]
	v_mfma_f32_16x16x32_bf16 v[16:19], v[192:195], v[220:223], v[16:19]
	v_mfma_f32_16x16x32_bf16 v[4:7], v[184:187], v[228:231], v[4:7]
	v_mfma_f32_16x16x32_bf16 v[0:3], v[192:195], v[228:231], v[0:3]
	s_setprio 0
	s_barrier
	s_add_i32 s78, s78, 2
	s_add_u32 s38, s38, 0x100
	s_addc_u32 s39, s39, 0
	s_add_u32 s76, s76, 0x100
	s_addc_u32 s77, s77, 0
	s_cmp_gt_u32 s78, 13
	s_cbranch_scc0 .LBB0_856
	s_branch .Lpeel_exit_4
.LBB0_856:
	ds_read_b128 v[164:167], v160
	ds_read_b128 v[168:171], v160 offset:1024
	ds_read_b128 v[172:175], v160 offset:2048
	ds_read_b128 v[176:179], v160 offset:3072
	ds_read_b128 v[180:183], v161
	ds_read_b128 v[184:187], v161 offset:1024
	ds_read_b128 v[188:191], v161 offset:2048
	ds_read_b128 v[192:195], v161 offset:3072
	s_add_u32 s40, s38, 0xfffc0080
	s_addc_u32 s41, s39, -1
	s_cmp_eq_u32 s78, 12
	s_cselect_b32 s43, s23, s41
	s_cselect_b32 s42, s74, s40
	s_cselect_b32 s41, s21, s77
	s_cselect_b32 s40, s75, s76
	v_lshl_add_u64 v[142:143], s[38:39], 0, v[136:137]
	s_add_i32 m0, s31, 0xc000
	ds_read_b128 v[196:199], v162
	ds_read_b128 v[200:203], v162 offset:1024
	ds_read_b128 v[208:211], v162 offset:2048
	ds_read_b128 v[212:215], v162 offset:3072
	ds_read_b128 v[216:219], v162 offset:4096
	ds_read_b128 v[220:223], v162 offset:5120
	ds_read_b128 v[224:227], v162 offset:6144
	ds_read_b128 v[228:231], v162 offset:7168
	global_load_lds_dwordx4 v[142:143], off
	v_lshl_add_u64 v[142:143], s[38:39], 0, v[138:139]
	s_add_i32 m0, s31, 0xe000
	s_nop 0
	global_load_lds_dwordx4 v[142:143], off
	s_waitcnt vmcnt(8)
	s_waitcnt lgkmcnt(0)
	s_barrier
; #define PG8_STAGE(bufoff, gbase, voff) do { _Pragma("unroll") for (int _i = 0; _i < 2; ++_i) \
;         __builtin_amdgcn_global_load_lds((const unsigned*)((const char*)(gbase) + (voff)[_i]), (PG8_LAS unsigned*)(lds + (bufoff) + ldsw + _i * 8192), 16, 0, 0); } while (0)
; #define PG8_LDA(dst, b, h) do { _Pragma("unroll") for (int m = 0; m < 4; ++m) _Pragma("unroll") for (int k = 0; k < 2; ++k) dst[m][k] = *(const PG8_LAS bf16x8*)(lds + PG8_SA(b, h) + aoff + m * 2048 + k * 1024); } while (0)
; #define PG8_LDB(dst, b, h) do { _Pragma("unroll") for (int n = 0; n < 2; ++n) _Pragma("unroll") for (int k = 0; k < 2; ++k) dst[n][k] = *(const PG8_LAS bf16x8*)(lds + PG8_SB(b, h) + boff + n * 2048 + k * 1024); } while (0)
; #define PG8_MMA(ai, bj, At, Bt) do { __builtin_amdgcn_s_setprio(1); _Pragma("unroll") for (int m = 0; m < 4; ++m) _Pragma("unroll") for (int n = 0; n < 2; ++n) _Pragma("unroll") for (int k = 0; k < 2; ++k) \
;         acc[ai][bj][m][n] = __builtin_amdgcn_mfma_f32_16x16x32_bf16(Bt[n][k], At[m][k], acc[ai][bj][m][n], 0, 0, 0); __builtin_amdgcn_s_setprio(0); } while (0)
; #define PG8_WAIT_V(n) asm volatile("s_waitcnt vmcnt(" #n ")" ::: "memory")
; #define PG8_WAIT_L(n) asm volatile("s_waitcnt lgkmcnt(" #n ")" ::: "memory")
; #define PG8_BAR __builtin_amdgcn_s_barrier()
; #define PG8_SCHED __builtin_amdgcn_sched_barrier(0)
; template <class Epi, class Sched, bool ALIGN_EPI = false, bool SP2 = false>
; __device__ __forceinline__ void gemm_phase(PG8_LAS unsigned char* lds, const Gemm g, const Sched& S, const Epi& E) {
;     ...
;             PG8_LDB(B0, 0, 0); PG8_LDB(B1, 0, 1); PG8_SCHED; PG8_LDA(At, 0, 0); PG8_STAGE(PG8_SA(1, 1), a1 + hstep, voffA);
;             PG8_WAIT_V(8); PG8_WAIT_L(0); PG8_BAR; PG8_MMA(0, 0, At, B0); PG8_MMA(0, 1, At, B1); PG8_BAR; PG8_SCHED;
;             PG8_LDA(At, 0, 1); PG8_STAGE(PG8_SB(0, 0), b2, voffB); PG8_STAGE(PG8_SB(0, 1), b2 + hstep, voffB); PG8_STAGE(PG8_SA(0, 0), a2, voffA);
;             PG8_WAIT_V(8); PG8_WAIT_L(0); PG8_BAR; PG8_MMA(1, 0, At, B0); PG8_MMA(1, 1, At, B1); PG8_BAR; PG8_SCHED;
	s_setprio 1
	s_waitcnt lgkmcnt(0)
	v_mfma_f32_16x16x32_bf16 v[124:127], v[164:167], v[196:199], v[124:127]
	v_mfma_f32_16x16x32_bf16 v[120:123], v[172:175], v[196:199], v[120:123]
	v_mfma_f32_16x16x32_bf16 v[108:111], v[164:167], v[208:211], v[108:111]
	v_mfma_f32_16x16x32_bf16 v[104:107], v[172:175], v[208:211], v[104:107]
	v_mfma_f32_16x16x32_bf16 v[92:95], v[164:167], v[216:219], v[92:95]
	v_mfma_f32_16x16x32_bf16 v[88:91], v[172:175], v[216:219], v[88:91]
	v_mfma_f32_16x16x32_bf16 v[76:79], v[164:167], v[224:227], v[76:79]
	v_mfma_f32_16x16x32_bf16 v[72:75], v[172:175], v[224:227], v[72:75]
	v_mfma_f32_16x16x32_bf16 v[124:127], v[168:171], v[200:203], v[124:127]
	v_mfma_f32_16x16x32_bf16 v[120:123], v[176:179], v[200:203], v[120:123]
	v_mfma_f32_16x16x32_bf16 v[108:111], v[168:171], v[212:215], v[108:111]
	v_mfma_f32_16x16x32_bf16 v[104:107], v[176:179], v[212:215], v[104:107]
	v_mfma_f32_16x16x32_bf16 v[92:95], v[168:171], v[220:223], v[92:95]
	v_mfma_f32_16x16x32_bf16 v[88:91], v[176:179], v[220:223], v[88:91]
	v_mfma_f32_16x16x32_bf16 v[76:79], v[168:171], v[228:231], v[76:79]
	v_mfma_f32_16x16x32_bf16 v[72:75], v[176:179], v[228:231], v[72:75]
	v_mfma_f32_16x16x32_bf16 v[116:119], v[180:183], v[196:199], v[116:119]
	v_mfma_f32_16x16x32_bf16 v[112:115], v[188:191], v[196:199], v[112:115]
	v_mfma_f32_16x16x32_bf16 v[100:103], v[180:183], v[208:211], v[100:103]
	v_mfma_f32_16x16x32_bf16 v[96:99], v[188:191], v[208:211], v[96:99]
	v_mfma_f32_16x16x32_bf16 v[84:87], v[180:183], v[216:219], v[84:87]
	v_mfma_f32_16x16x32_bf16 v[80:83], v[188:191], v[216:219], v[80:83]
	v_mfma_f32_16x16x32_bf16 v[68:71], v[180:183], v[224:227], v[68:71]
	v_mfma_f32_16x16x32_bf16 v[64:67], v[188:191], v[224:227], v[64:67]
	v_mfma_f32_16x16x32_bf16 v[116:119], v[184:187], v[200:203], v[116:119]
	v_mfma_f32_16x16x32_bf16 v[112:115], v[192:195], v[200:203], v[112:115]
	v_mfma_f32_16x16x32_bf16 v[100:103], v[184:187], v[212:215], v[100:103]
	v_mfma_f32_16x16x32_bf16 v[96:99], v[192:195], v[212:215], v[96:99]
	v_mfma_f32_16x16x32_bf16 v[84:87], v[184:187], v[220:223], v[84:87]
	v_mfma_f32_16x16x32_bf16 v[80:83], v[192:195], v[220:223], v[80:83]
	v_mfma_f32_16x16x32_bf16 v[68:71], v[184:187], v[228:231], v[68:71]
	v_mfma_f32_16x16x32_bf16 v[64:67], v[192:195], v[228:231], v[64:67]
	s_setprio 0
	s_barrier
	s_add_i32 s79, s69, s56
	v_lshl_add_u64 v[142:143], s[40:41], 0, v[130:131]
	s_mov_b32 m0, s79
	ds_read_b128 v[196:199], v162 offset:16384
	ds_read_b128 v[200:203], v162 offset:17408
	ds_read_b128 v[208:211], v162 offset:18432
	ds_read_b128 v[212:215], v162 offset:19456
	ds_read_b128 v[216:219], v162 offset:20480
	ds_read_b128 v[220:223], v162 offset:21504
	ds_read_b128 v[224:227], v162 offset:22528
	ds_read_b128 v[228:231], v162 offset:23552
	global_load_lds_dwordx4 v[142:143], off
	s_add_i32 m0, s79, 0x2000
	s_add_u32 s80, s40, 0x40000
	v_lshl_add_u64 v[204:205], s[40:41], 0, v[134:135]
	s_addc_u32 s81, s41, 0
	s_add_i32 s79, s71, s56
	global_load_lds_dwordx4 v[204:205], off
	v_lshl_add_u64 v[232:233], s[80:81], 0, v[130:131]
	s_mov_b32 m0, s79
	v_lshl_add_u64 v[234:235], s[42:43], 0, v[132:133]
	global_load_lds_dwordx4 v[232:233], off
	v_lshl_add_u64 v[232:233], s[80:81], 0, v[134:135]
	s_add_i32 m0, s79, 0x2000
	s_nop 0
	global_load_lds_dwordx4 v[232:233], off
	v_lshl_add_u64 v[232:233], s[42:43], 0, v[128:129]
	s_mov_b32 m0, s31
	s_nop 0
	global_load_lds_dwordx4 v[232:233], off
	s_mov_b32 m0, s59
	s_nop 0
	global_load_lds_dwordx4 v[234:235], off
	s_waitcnt vmcnt(8)
	s_waitcnt lgkmcnt(0)
	s_barrier
	s_setprio 1
	s_waitcnt lgkmcnt(0)
	v_mfma_f32_16x16x32_bf16 v[60:63], v[164:167], v[196:199], v[60:63]
	v_mfma_f32_16x16x32_bf16 v[56:59], v[172:175], v[196:199], v[56:59]
	v_mfma_f32_16x16x32_bf16 v[44:47], v[164:167], v[208:211], v[44:47]
	v_mfma_f32_16x16x32_bf16 v[40:43], v[172:175], v[208:211], v[40:43]
	v_mfma_f32_16x16x32_bf16 v[28:31], v[164:167], v[216:219], v[28:31]
	v_mfma_f32_16x16x32_bf16 v[24:27], v[172:175], v[216:219], v[24:27]
	v_mfma_f32_16x16x32_bf16 v[12:15], v[164:167], v[224:227], v[12:15]
	v_mfma_f32_16x16x32_bf16 v[8:11], v[172:175], v[224:227], v[8:11]
	v_mfma_f32_16x16x32_bf16 v[60:63], v[168:171], v[200:203], v[60:63]
	v_mfma_f32_16x16x32_bf16 v[56:59], v[176:179], v[200:203], v[56:59]
	v_mfma_f32_16x16x32_bf16 v[44:47], v[168:171], v[212:215], v[44:47]
	v_mfma_f32_16x16x32_bf16 v[40:43], v[176:179], v[212:215], v[40:43]
	v_mfma_f32_16x16x32_bf16 v[28:31], v[168:171], v[220:223], v[28:31]
	v_mfma_f32_16x16x32_bf16 v[24:27], v[176:179], v[220:223], v[24:27]
	v_mfma_f32_16x16x32_bf16 v[12:15], v[168:171], v[228:231], v[12:15]
	v_mfma_f32_16x16x32_bf16 v[8:11], v[176:179], v[228:231], v[8:11]
	v_mfma_f32_16x16x32_bf16 v[52:55], v[180:183], v[196:199], v[52:55]
	v_mfma_f32_16x16x32_bf16 v[48:51], v[188:191], v[196:199], v[48:51]
	v_mfma_f32_16x16x32_bf16 v[36:39], v[180:183], v[208:211], v[36:39]
	v_mfma_f32_16x16x32_bf16 v[32:35], v[188:191], v[208:211], v[32:35]
	v_mfma_f32_16x16x32_bf16 v[20:23], v[180:183], v[216:219], v[20:23]
	v_mfma_f32_16x16x32_bf16 v[16:19], v[188:191], v[216:219], v[16:19]
	v_mfma_f32_16x16x32_bf16 v[4:7], v[180:183], v[224:227], v[4:7]
	v_mfma_f32_16x16x32_bf16 v[0:3], v[188:191], v[224:227], v[0:3]
	v_mfma_f32_16x16x32_bf16 v[52:55], v[184:187], v[200:203], v[52:55]
	v_mfma_f32_16x16x32_bf16 v[48:51], v[192:195], v[200:203], v[48:51]
	v_mfma_f32_16x16x32_bf16 v[36:39], v[184:187], v[212:215], v[36:39]
	v_mfma_f32_16x16x32_bf16 v[32:35], v[192:195], v[212:215], v[32:35]
	v_mfma_f32_16x16x32_bf16 v[20:23], v[184:187], v[220:223], v[20:23]
	v_mfma_f32_16x16x32_bf16 v[16:19], v[192:195], v[220:223], v[16:19]
	v_mfma_f32_16x16x32_bf16 v[4:7], v[184:187], v[228:231], v[4:7]
	v_mfma_f32_16x16x32_bf16 v[0:3], v[192:195], v[228:231], v[0:3]
	s_setprio 0
	s_barrier
; #define PG8_STAGE(bufoff, gbase, voff) do { _Pragma("unroll") for (int _i = 0; _i < 2; ++_i) \
;         __builtin_amdgcn_global_load_lds((const unsigned*)((const char*)(gbase) + (voff)[_i]), (PG8_LAS unsigned*)(lds + (bufoff) + ldsw + _i * 8192), 16, 0, 0); } while (0)
; #define PG8_LDA(dst, b, h) do { _Pragma("unroll") for (int m = 0; m < 4; ++m) _Pragma("unroll") for (int k = 0; k < 2; ++k) dst[m][k] = *(const PG8_LAS bf16x8*)(lds + PG8_SA(b, h) + aoff + m * 2048 + k * 1024); } while (0)
; #define PG8_LDB(dst, b, h) do { _Pragma("unroll") for (int n = 0; n < 2; ++n) _Pragma("unroll") for (int k = 0; k < 2; ++k) dst[n][k] = *(const PG8_LAS bf16x8*)(lds + PG8_SB(b, h) + boff + n * 2048 + k * 1024); } while (0)
; #define PG8_MMA(ai, bj, At, Bt) do { __builtin_amdgcn_s_setprio(1); _Pragma("unroll") for (int m = 0; m < 4; ++m) _Pragma("unroll") for (int n = 0; n < 2; ++n) _Pragma("unroll") for (int k = 0; k < 2; ++k) \
;         acc[ai][bj][m][n] = __builtin_amdgcn_mfma_f32_16x16x32_bf16(Bt[n][k], At[m][k], acc[ai][bj][m][n], 0, 0, 0); __builtin_amdgcn_s_setprio(0); } while (0)
; #define PG8_WAIT_V(n) asm volatile("s_waitcnt vmcnt(" #n ")" ::: "memory")
; #define PG8_WAIT_L(n) asm volatile("s_waitcnt lgkmcnt(" #n ")" ::: "memory")
; #define PG8_BAR __builtin_amdgcn_s_barrier()
; #define PG8_SCHED __builtin_amdgcn_sched_barrier(0)
; template <class Epi, class Sched, bool ALIGN_EPI = false, bool SP2 = false>
; __device__ __forceinline__ void gemm_phase(PG8_LAS unsigned char* lds, const Gemm g, const Sched& S, const Epi& E) {
;     ...
;             PG8_LDB(B0, 1, 0); PG8_LDB(B1, 1, 1); PG8_SCHED; PG8_LDA(At, 1, 0); PG8_STAGE(PG8_SA(0, 1), a2 + hstep, voffA);
;             PG8_WAIT_V(8); PG8_WAIT_L(0); PG8_BAR; PG8_MMA(0, 0, At, B0); PG8_MMA(0, 1, At, B1); PG8_BAR; PG8_SCHED;
	s_add_i32 s79, 0, 0x18000
	v_add_u32_e32 v163, s79, v158
	s_add_i32 s80, 0, 0x1c000
	ds_read_b128 v[164:167], v163
	ds_read_b128 v[168:171], v163 offset:1024
	ds_read_b128 v[172:175], v163 offset:2048
	ds_read_b128 v[176:179], v163 offset:3072
	v_add_u32_e32 v163, s80, v158
	ds_read_b128 v[180:183], v163
	ds_read_b128 v[184:187], v163 offset:1024
	ds_read_b128 v[188:191], v163 offset:2048
	ds_read_b128 v[192:195], v163 offset:3072
	s_add_u32 s42, s42, 0x40000
	s_addc_u32 s43, s43, 0
	s_mov_b32 m0, s60
	v_lshl_add_u64 v[236:237], s[42:43], 0, v[128:129]
	ds_read_b128 v[196:199], v162 offset:32768
	ds_read_b128 v[200:203], v162 offset:33792
	ds_read_b128 v[208:211], v162 offset:34816
	ds_read_b128 v[212:215], v162 offset:35840
	ds_read_b128 v[216:219], v162 offset:36864
	ds_read_b128 v[220:223], v162 offset:37888
	ds_read_b128 v[224:227], v162 offset:38912
	ds_read_b128 v[228:231], v162 offset:39936
	global_load_lds_dwordx4 v[236:237], off
	v_lshl_add_u64 v[236:237], s[42:43], 0, v[132:133]
	s_mov_b32 m0, s61
	s_nop 0
	global_load_lds_dwordx4 v[236:237], off
	s_waitcnt vmcnt(8)
	s_waitcnt lgkmcnt(0)
	s_barrier
	s_setprio 1
	s_waitcnt lgkmcnt(0)
	v_mfma_f32_16x16x32_bf16 v[124:127], v[164:167], v[196:199], v[124:127]
	v_mfma_f32_16x16x32_bf16 v[120:123], v[172:175], v[196:199], v[120:123]
	v_mfma_f32_16x16x32_bf16 v[108:111], v[164:167], v[208:211], v[108:111]
	v_mfma_f32_16x16x32_bf16 v[104:107], v[172:175], v[208:211], v[104:107]
	v_mfma_f32_16x16x32_bf16 v[92:95], v[164:167], v[216:219], v[92:95]
	v_mfma_f32_16x16x32_bf16 v[88:91], v[172:175], v[216:219], v[88:91]
	v_mfma_f32_16x16x32_bf16 v[76:79], v[164:167], v[224:227], v[76:79]
	v_mfma_f32_16x16x32_bf16 v[72:75], v[172:175], v[224:227], v[72:75]
	v_mfma_f32_16x16x32_bf16 v[124:127], v[168:171], v[200:203], v[124:127]
	v_mfma_f32_16x16x32_bf16 v[120:123], v[176:179], v[200:203], v[120:123]
	v_mfma_f32_16x16x32_bf16 v[108:111], v[168:171], v[212:215], v[108:111]
	v_mfma_f32_16x16x32_bf16 v[104:107], v[176:179], v[212:215], v[104:107]
	v_mfma_f32_16x16x32_bf16 v[92:95], v[168:171], v[220:223], v[92:95]
	v_mfma_f32_16x16x32_bf16 v[88:91], v[176:179], v[220:223], v[88:91]
	v_mfma_f32_16x16x32_bf16 v[76:79], v[168:171], v[228:231], v[76:79]
	v_mfma_f32_16x16x32_bf16 v[72:75], v[176:179], v[228:231], v[72:75]
	v_mfma_f32_16x16x32_bf16 v[116:119], v[180:183], v[196:199], v[116:119]
	v_mfma_f32_16x16x32_bf16 v[112:115], v[188:191], v[196:199], v[112:115]
	v_mfma_f32_16x16x32_bf16 v[100:103], v[180:183], v[208:211], v[100:103]
	v_mfma_f32_16x16x32_bf16 v[96:99], v[188:191], v[208:211], v[96:99]
	v_mfma_f32_16x16x32_bf16 v[84:87], v[180:183], v[216:219], v[84:87]
	v_mfma_f32_16x16x32_bf16 v[80:83], v[188:191], v[216:219], v[80:83]
	v_mfma_f32_16x16x32_bf16 v[68:71], v[180:183], v[224:227], v[68:71]
	v_mfma_f32_16x16x32_bf16 v[64:67], v[188:191], v[224:227], v[64:67]
	v_mfma_f32_16x16x32_bf16 v[116:119], v[184:187], v[200:203], v[116:119]
	v_mfma_f32_16x16x32_bf16 v[112:115], v[192:195], v[200:203], v[112:115]
	v_mfma_f32_16x16x32_bf16 v[100:103], v[184:187], v[212:215], v[100:103]
	v_mfma_f32_16x16x32_bf16 v[96:99], v[192:195], v[212:215], v[96:99]
	v_mfma_f32_16x16x32_bf16 v[84:87], v[184:187], v[220:223], v[84:87]
	v_mfma_f32_16x16x32_bf16 v[80:83], v[192:195], v[220:223], v[80:83]
	v_mfma_f32_16x16x32_bf16 v[68:71], v[184:187], v[228:231], v[68:71]
	v_mfma_f32_16x16x32_bf16 v[64:67], v[192:195], v[228:231], v[64:67]
	s_setprio 0
	s_barrier
; #define PG8_STAGE(bufoff, gbase, voff) do { _Pragma("unroll") for (int _i = 0; _i < 2; ++_i) \
;         __builtin_amdgcn_global_load_lds((const unsigned*)((const char*)(gbase) + (voff)[_i]), (PG8_LAS unsigned*)(lds + (bufoff) + ldsw + _i * 8192), 16, 0, 0); } while (0)
; #define PG8_LDA(dst, b, h) do { _Pragma("unroll") for (int m = 0; m < 4; ++m) _Pragma("unroll") for (int k = 0; k < 2; ++k) dst[m][k] = *(const PG8_LAS bf16x8*)(lds + PG8_SA(b, h) + aoff + m * 2048 + k * 1024); } while (0)
; #define PG8_MMA(ai, bj, At, Bt) do { __builtin_amdgcn_s_setprio(1); _Pragma("unroll") for (int m = 0; m < 4; ++m) _Pragma("unroll") for (int n = 0; n < 2; ++n) _Pragma("unroll") for (int k = 0; k < 2; ++k) \
;         acc[ai][bj][m][n] = __builtin_amdgcn_mfma_f32_16x16x32_bf16(Bt[n][k], At[m][k], acc[ai][bj][m][n], 0, 0, 0); __builtin_amdgcn_s_setprio(0); } while (0)
; #define PG8_WAIT_V(n) asm volatile("s_waitcnt vmcnt(" #n ")" ::: "memory")
; #define PG8_WAIT_L(n) asm volatile("s_waitcnt lgkmcnt(" #n ")" ::: "memory")
; #define PG8_BAR __builtin_amdgcn_s_barrier()
; #define PG8_SCHED __builtin_amdgcn_sched_barrier(0)
; template <class Epi, class Sched, bool ALIGN_EPI = false, bool SP2 = false>
; __device__ __forceinline__ void gemm_phase(PG8_LAS unsigned char* lds, const Gemm g, const Sched& S, const Epi& E) {
;     ...
;             PG8_LDA(At, 1, 1); PG8_STAGE(PG8_SB(1, 0), b3, voffB); PG8_STAGE(PG8_SB(1, 1), b3 + hstep, voffB); PG8_STAGE(PG8_SA(1, 0), a3, voffA);
;             PG8_WAIT_V(8); PG8_WAIT_L(0); PG8_BAR; PG8_MMA(1, 0, At, B0); PG8_MMA(1, 1, At, B1); PG8_BAR; PG8_SCHED;
	s_add_i32 s42, s79, s56
	v_lshl_add_u64 v[142:143], v[142:143], 0, s[8:9]
	s_mov_b32 m0, s42
	ds_read_b128 v[196:199], v162 offset:49152
	ds_read_b128 v[200:203], v162 offset:50176
	ds_read_b128 v[208:211], v162 offset:51200
	ds_read_b128 v[212:215], v162 offset:52224
	ds_read_b128 v[216:219], v162 offset:53248
	ds_read_b128 v[220:223], v162 offset:54272
	ds_read_b128 v[224:227], v162 offset:55296
	ds_read_b128 v[228:231], v162 offset:56320
	global_load_lds_dwordx4 v[142:143], off
	s_add_i32 m0, s42, 0x2000
	s_add_u32 s40, s40, 0x40080
	v_lshl_add_u64 v[142:143], v[204:205], 0, s[8:9]
	s_addc_u32 s41, s41, 0
	s_add_i32 s42, s80, s56
	global_load_lds_dwordx4 v[142:143], off
	v_lshl_add_u64 v[142:143], s[40:41], 0, v[130:131]
	s_mov_b32 m0, s42
	s_nop 0
	global_load_lds_dwordx4 v[142:143], off
	v_lshl_add_u64 v[142:143], s[40:41], 0, v[134:135]
	s_add_i32 m0, s42, 0x2000
	s_nop 0
	global_load_lds_dwordx4 v[142:143], off
	v_lshl_add_u64 v[142:143], v[232:233], 0, s[8:9]
	s_mov_b32 m0, s66
	s_nop 0
	global_load_lds_dwordx4 v[142:143], off
	v_lshl_add_u64 v[142:143], v[234:235], 0, s[8:9]
	s_mov_b32 m0, s67
	s_nop 0
	global_load_lds_dwordx4 v[142:143], off
	s_waitcnt vmcnt(8)
	s_waitcnt lgkmcnt(0)
	s_barrier
	s_setprio 1
	s_waitcnt lgkmcnt(0)
	v_mfma_f32_16x16x32_bf16 v[60:63], v[164:167], v[196:199], v[60:63]
	v_mfma_f32_16x16x32_bf16 v[56:59], v[172:175], v[196:199], v[56:59]
	v_mfma_f32_16x16x32_bf16 v[44:47], v[164:167], v[208:211], v[44:47]
	v_mfma_f32_16x16x32_bf16 v[40:43], v[172:175], v[208:211], v[40:43]
	v_mfma_f32_16x16x32_bf16 v[28:31], v[164:167], v[216:219], v[28:31]
	v_mfma_f32_16x16x32_bf16 v[24:27], v[172:175], v[216:219], v[24:27]
	v_mfma_f32_16x16x32_bf16 v[12:15], v[164:167], v[224:227], v[12:15]
	v_mfma_f32_16x16x32_bf16 v[8:11], v[172:175], v[224:227], v[8:11]
	v_mfma_f32_16x16x32_bf16 v[60:63], v[168:171], v[200:203], v[60:63]
	v_mfma_f32_16x16x32_bf16 v[56:59], v[176:179], v[200:203], v[56:59]
	v_mfma_f32_16x16x32_bf16 v[44:47], v[168:171], v[212:215], v[44:47]
	v_mfma_f32_16x16x32_bf16 v[40:43], v[176:179], v[212:215], v[40:43]
	v_mfma_f32_16x16x32_bf16 v[28:31], v[168:171], v[220:223], v[28:31]
	v_mfma_f32_16x16x32_bf16 v[24:27], v[176:179], v[220:223], v[24:27]
	v_mfma_f32_16x16x32_bf16 v[12:15], v[168:171], v[228:231], v[12:15]
	v_mfma_f32_16x16x32_bf16 v[8:11], v[176:179], v[228:231], v[8:11]
	v_mfma_f32_16x16x32_bf16 v[52:55], v[180:183], v[196:199], v[52:55]
	v_mfma_f32_16x16x32_bf16 v[48:51], v[188:191], v[196:199], v[48:51]
	v_mfma_f32_16x16x32_bf16 v[36:39], v[180:183], v[208:211], v[36:39]
	v_mfma_f32_16x16x32_bf16 v[32:35], v[188:191], v[208:211], v[32:35]
	v_mfma_f32_16x16x32_bf16 v[20:23], v[180:183], v[216:219], v[20:23]
	v_mfma_f32_16x16x32_bf16 v[16:19], v[188:191], v[216:219], v[16:19]
	v_mfma_f32_16x16x32_bf16 v[4:7], v[180:183], v[224:227], v[4:7]
	v_mfma_f32_16x16x32_bf16 v[0:3], v[188:191], v[224:227], v[0:3]
	v_mfma_f32_16x16x32_bf16 v[52:55], v[184:187], v[200:203], v[52:55]
	v_mfma_f32_16x16x32_bf16 v[48:51], v[192:195], v[200:203], v[48:51]
	v_mfma_f32_16x16x32_bf16 v[36:39], v[184:187], v[212:215], v[36:39]
	v_mfma_f32_16x16x32_bf16 v[32:35], v[192:195], v[212:215], v[32:35]
	v_mfma_f32_16x16x32_bf16 v[20:23], v[184:187], v[220:223], v[20:23]
	v_mfma_f32_16x16x32_bf16 v[16:19], v[192:195], v[220:223], v[16:19]
	v_mfma_f32_16x16x32_bf16 v[4:7], v[184:187], v[228:231], v[4:7]
	v_mfma_f32_16x16x32_bf16 v[0:3], v[192:195], v[228:231], v[0:3]
	s_setprio 0
	s_barrier
	s_add_i32 s78, s78, 2
	s_add_u32 s38, s38, 0x100
	s_addc_u32 s39, s39, 0
	s_add_u32 s76, s76, 0x100
	s_addc_u32 s77, s77, 0
	s_cmp_gt_u32 s78, 13
	s_cbranch_scc0 .LBB0_856

;     __device__ __forceinline__ bool next(int i, Unit& u) const { if (i != 0) return false; const int c0 = (G >= 8) ? G - 5 : G - 2; int k = -1; if (c == c0) k = 0; else if (c == G - 1) k = 1; if (k < 0 || k >= n) return false; u.pm = k; u.pn = 0; return true; }
; #define PG8_STAGE(bufoff, gbase, voff) do { _Pragma("unroll") for (int _i = 0; _i < 2; ++_i) \
;         __builtin_amdgcn_global_load_lds((const unsigned*)((const char*)(gbase) + (voff)[_i]), (PG8_LAS unsigned*)(lds + (bufoff) + ldsw + _i * 8192), 16, 0, 0); } while (0)
; #define PG8_LDA(dst, b, h) do { _Pragma("unroll") for (int m = 0; m < 4; ++m) _Pragma("unroll") for (int k = 0; k < 2; ++k) dst[m][k] = *(const PG8_LAS bf16x8*)(lds + PG8_SA(b, h) + aoff + m * 2048 + k * 1024); } while (0)
; #define PG8_LDB(dst, b, h) do { _Pragma("unroll") for (int n = 0; n < 2; ++n) _Pragma("unroll") for (int k = 0; k < 2; ++k) dst[n][k] = *(const PG8_LAS bf16x8*)(lds + PG8_SB(b, h) + boff + n * 2048 + k * 1024); } while (0)
; template <class Epi, class Sched, bool ALIGN_EPI = false, bool SP2 = false>
; __device__ __forceinline__ void gemm_phase(PG8_LAS unsigned char* lds, const Gemm g, const Sched& S, const Epi& E) {
;     ...
;         const bool has_next = S.next(ui + 1, nxt);
;         const char* nA = has_next ? (const char*)g.A + (size_t)nxt.pm * tstep : cA; const char* nB = has_next ? (const char*)g.Bt + (size_t)nxt.pn * tstep : cB;
;         for (int t = 0; t < nt; t += 2) {
;             const bool last = (t == nt - 2);
;             const char* a1 = cA + (size_t)(t + 1) * kstep;
;             const char* a2 = last ? nA : cA + (size_t)(t + 2) * kstep; const char* b2 = last ? nB : cB + (size_t)(t + 2) * kstep;
;             const char* a3 = a2 + kstep; const char* b3 = b2 + kstep;
;             if (last && has_next) S.a_ready(nxt);
;             if constexpr (SP2) {
;             PG8_LDB(B0, 0, 0); PG8_LDB(B1, 0, 1); PG8_SCHED; PG8_LDA(At, 0, 0); PG8_STAGE(PG8_SA(1, 1), a1 + hstep, voffA);
;             PG8_WAIT_V(8); PG8_WAIT_L(0); PG8_BAR; PG8_MMA(0, 0, At, B0); PG8_MMA(0, 1, At, B1); PG8_BAR; PG8_SCHED;
;             PG8_LDA(At, 0, 1); PG8_STAGE(PG8_SB(0, 0), b2, voffB); PG8_STAGE(PG8_SB(0, 1), b2 + hstep, voffB); PG8_STAGE(PG8_SA(0, 0), a2, voffA);
;             PG8_WAIT_V(8); PG8_WAIT_L(0); PG8_BAR; PG8_MMA(1, 0, At, B0); PG8_MMA(1, 1, At, B1); PG8_BAR; PG8_SCHED;
.LBB0_876:
	s_ashr_i32 s21, s20, 31
	s_lshl_b64 s[26:27], s[20:21], 19
	s_add_u32 s26, s97, s26
	s_addc_u32 s27, s3, s27
	s_and_b64 s[28:29], s[24:25], exec
	s_cselect_b32 s21, s27, s39
	s_cselect_b32 s72, s26, s38
	s_ashr_i32 s23, s22, 31
	s_lshl_b64 s[28:29], s[22:23], 19
	s_add_u32 s28, s46, s28
	s_addc_u32 s29, s47, s29
	s_and_b64 s[42:43], s[24:25], exec
	s_cselect_b32 s23, s29, s41
	s_cselect_b32 s73, s28, s40
	s_add_u32 s38, s38, 0x40080
	s_addc_u32 s39, s39, 0
	s_add_u32 s74, s40, 0x100
	v_mov_b32_e32 v0, 0
	s_addc_u32 s75, s41, 0
	s_mov_b32 s76, -2
	ds_read_b128 v[164:167], v160
	ds_read_b128 v[168:171], v160 offset:1024
	ds_read_b128 v[172:175], v160 offset:2048
	ds_read_b128 v[176:179], v160 offset:3072
	ds_read_b128 v[180:183], v161
	ds_read_b128 v[184:187], v161 offset:1024
	ds_read_b128 v[188:191], v161 offset:2048
	ds_read_b128 v[192:195], v161 offset:3072
	s_add_u32 s40, s38, 0xfffc0080
	s_addc_u32 s41, s39, -1
	s_cmp_eq_u32 s76, 12
	s_cselect_b32 s43, s21, s41
	s_cselect_b32 s42, s72, s40
	s_cselect_b32 s41, s23, s75
	s_cselect_b32 s40, s73, s74
	v_lshl_add_u64 v[142:143], s[38:39], 0, v[136:137]
	s_add_i32 m0, s31, 0xc000
	ds_read_b128 v[196:199], v162
	ds_read_b128 v[200:203], v162 offset:1024
	ds_read_b128 v[208:211], v162 offset:2048
	ds_read_b128 v[212:215], v162 offset:3072
	ds_read_b128 v[216:219], v162 offset:4096
	ds_read_b128 v[220:223], v162 offset:5120
	ds_read_b128 v[224:227], v162 offset:6144
	ds_read_b128 v[228:231], v162 offset:7168
	global_load_lds_dwordx4 v[142:143], off
	v_lshl_add_u64 v[142:143], s[38:39], 0, v[138:139]
	s_add_i32 m0, s31, 0xe000
	s_nop 0
	global_load_lds_dwordx4 v[142:143], off
	s_waitcnt vmcnt(8)
	s_waitcnt lgkmcnt(0)
	s_barrier
	s_setprio 1
	s_waitcnt lgkmcnt(0)
	v_mfma_f32_16x16x32_bf16 v[124:127], v[164:167], v[196:199], 0
	v_mfma_f32_16x16x32_bf16 v[120:123], v[172:175], v[196:199], 0
	v_mfma_f32_16x16x32_bf16 v[108:111], v[164:167], v[208:211], 0
	v_mfma_f32_16x16x32_bf16 v[104:107], v[172:175], v[208:211], 0
	v_mfma_f32_16x16x32_bf16 v[92:95], v[164:167], v[216:219], 0
	v_mfma_f32_16x16x32_bf16 v[88:91], v[172:175], v[216:219], 0
	v_mfma_f32_16x16x32_bf16 v[76:79], v[164:167], v[224:227], 0
	v_mfma_f32_16x16x32_bf16 v[72:75], v[172:175], v[224:227], 0
	v_mfma_f32_16x16x32_bf16 v[124:127], v[168:171], v[200:203], v[124:127]
	v_mfma_f32_16x16x32_bf16 v[120:123], v[176:179], v[200:203], v[120:123]
	v_mfma_f32_16x16x32_bf16 v[108:111], v[168:171], v[212:215], v[108:111]
	v_mfma_f32_16x16x32_bf16 v[104:107], v[176:179], v[212:215], v[104:107]
	v_mfma_f32_16x16x32_bf16 v[92:95], v[168:171], v[220:223], v[92:95]
	v_mfma_f32_16x16x32_bf16 v[88:91], v[176:179], v[220:223], v[88:91]
	v_mfma_f32_16x16x32_bf16 v[76:79], v[168:171], v[228:231], v[76:79]
	v_mfma_f32_16x16x32_bf16 v[72:75], v[176:179], v[228:231], v[72:75]
	v_mfma_f32_16x16x32_bf16 v[116:119], v[180:183], v[196:199], 0
	v_mfma_f32_16x16x32_bf16 v[112:115], v[188:191], v[196:199], 0
	v_mfma_f32_16x16x32_bf16 v[100:103], v[180:183], v[208:211], 0
	v_mfma_f32_16x16x32_bf16 v[96:99], v[188:191], v[208:211], 0
	v_mfma_f32_16x16x32_bf16 v[84:87], v[180:183], v[216:219], 0
	v_mfma_f32_16x16x32_bf16 v[80:83], v[188:191], v[216:219], 0
	v_mfma_f32_16x16x32_bf16 v[68:71], v[180:183], v[224:227], 0
	v_mfma_f32_16x16x32_bf16 v[64:67], v[188:191], v[224:227], 0
	v_mfma_f32_16x16x32_bf16 v[116:119], v[184:187], v[200:203], v[116:119]
	v_mfma_f32_16x16x32_bf16 v[112:115], v[192:195], v[200:203], v[112:115]
	v_mfma_f32_16x16x32_bf16 v[100:103], v[184:187], v[212:215], v[100:103]
	v_mfma_f32_16x16x32_bf16 v[96:99], v[192:195], v[212:215], v[96:99]
	v_mfma_f32_16x16x32_bf16 v[84:87], v[184:187], v[220:223], v[84:87]
	v_mfma_f32_16x16x32_bf16 v[80:83], v[192:195], v[220:223], v[80:83]
	v_mfma_f32_16x16x32_bf16 v[68:71], v[184:187], v[228:231], v[68:71]
	v_mfma_f32_16x16x32_bf16 v[64:67], v[192:195], v[228:231], v[64:67]
	s_setprio 0
	s_barrier
	s_add_i32 s77, s67, s57
	v_lshl_add_u64 v[142:143], s[40:41], 0, v[130:131]
	s_mov_b32 m0, s77
	ds_read_b128 v[196:199], v162 offset:16384
	ds_read_b128 v[200:203], v162 offset:17408
	ds_read_b128 v[208:211], v162 offset:18432
	ds_read_b128 v[212:215], v162 offset:19456
	ds_read_b128 v[216:219], v162 offset:20480
	ds_read_b128 v[220:223], v162 offset:21504
	ds_read_b128 v[224:227], v162 offset:22528
	ds_read_b128 v[228:231], v162 offset:23552
	global_load_lds_dwordx4 v[142:143], off
	s_add_i32 m0, s77, 0x2000
	s_add_u32 s78, s40, 0x40000
	v_lshl_add_u64 v[204:205], s[40:41], 0, v[134:135]
	s_addc_u32 s79, s41, 0
	s_add_i32 s77, s68, s57
	global_load_lds_dwordx4 v[204:205], off
	v_lshl_add_u64 v[232:233], s[78:79], 0, v[130:131]
	s_mov_b32 m0, s77
	v_lshl_add_u64 v[234:235], s[42:43], 0, v[132:133]
	global_load_lds_dwordx4 v[232:233], off
	v_lshl_add_u64 v[232:233], s[78:79], 0, v[134:135]
	s_add_i32 m0, s77, 0x2000
	s_nop 0
	global_load_lds_dwordx4 v[232:233], off
	v_lshl_add_u64 v[232:233], s[42:43], 0, v[128:129]
	s_mov_b32 m0, s31
	s_nop 0
	global_load_lds_dwordx4 v[232:233], off
	s_mov_b32 m0, s59
	s_nop 0
	global_load_lds_dwordx4 v[234:235], off
	s_waitcnt vmcnt(8)
	s_waitcnt lgkmcnt(0)
	s_barrier
; #define PG8_STAGE(bufoff, gbase, voff) do { _Pragma("unroll") for (int _i = 0; _i < 2; ++_i) \
;         __builtin_amdgcn_global_load_lds((const unsigned*)((const char*)(gbase) + (voff)[_i]), (PG8_LAS unsigned*)(lds + (bufoff) + ldsw + _i * 8192), 16, 0, 0); } while (0)
; #define PG8_LDA(dst, b, h) do { _Pragma("unroll") for (int m = 0; m < 4; ++m) _Pragma("unroll") for (int k = 0; k < 2; ++k) dst[m][k] = *(const PG8_LAS bf16x8*)(lds + PG8_SA(b, h) + aoff + m * 2048 + k * 1024); } while (0)
; #define PG8_LDB(dst, b, h) do { _Pragma("unroll") for (int n = 0; n < 2; ++n) _Pragma("unroll") for (int k = 0; k < 2; ++k) dst[n][k] = *(const PG8_LAS bf16x8*)(lds + PG8_SB(b, h) + boff + n * 2048 + k * 1024); } while (0)
; #define PG8_MMA(ai, bj, At, Bt) do { __builtin_amdgcn_s_setprio(1); _Pragma("unroll") for (int m = 0; m < 4; ++m) _Pragma("unroll") for (int n = 0; n < 2; ++n) _Pragma("unroll") for (int k = 0; k < 2; ++k) \
;         acc[ai][bj][m][n] = __builtin_amdgcn_mfma_f32_16x16x32_bf16(Bt[n][k], At[m][k], acc[ai][bj][m][n], 0, 0, 0); __builtin_amdgcn_s_setprio(0); } while (0)
; #define PG8_WAIT_V(n) asm volatile("s_waitcnt vmcnt(" #n ")" ::: "memory")
; #define PG8_WAIT_L(n) asm volatile("s_waitcnt lgkmcnt(" #n ")" ::: "memory")
; #define PG8_BAR __builtin_amdgcn_s_barrier()
; #define PG8_SCHED __builtin_amdgcn_sched_barrier(0)
; template <class Epi, class Sched, bool ALIGN_EPI = false, bool SP2 = false>
; __device__ __forceinline__ void gemm_phase(PG8_LAS unsigned char* lds, const Gemm g, const Sched& S, const Epi& E) {
;     ...
;             PG8_LDA(At, 0, 1); PG8_STAGE(PG8_SB(0, 0), b2, voffB); PG8_STAGE(PG8_SB(0, 1), b2 + hstep, voffB); PG8_STAGE(PG8_SA(0, 0), a2, voffA);
;             PG8_WAIT_V(8); PG8_WAIT_L(0); PG8_BAR; PG8_MMA(1, 0, At, B0); PG8_MMA(1, 1, At, B1); PG8_BAR; PG8_SCHED;
;             PG8_LDB(B0, 1, 0); PG8_LDB(B1, 1, 1); PG8_SCHED; PG8_LDA(At, 1, 0); PG8_STAGE(PG8_SA(0, 1), a2 + hstep, voffA);
;             PG8_WAIT_V(8); PG8_WAIT_L(0); PG8_BAR; PG8_MMA(0, 0, At, B0); PG8_MMA(0, 1, At, B1); PG8_BAR; PG8_SCHED;
	s_setprio 1
	s_waitcnt lgkmcnt(0)
	v_mfma_f32_16x16x32_bf16 v[60:63], v[164:167], v[196:199], 0
	v_mfma_f32_16x16x32_bf16 v[56:59], v[172:175], v[196:199], 0
	v_mfma_f32_16x16x32_bf16 v[44:47], v[164:167], v[208:211], 0
	v_mfma_f32_16x16x32_bf16 v[40:43], v[172:175], v[208:211], 0
	v_mfma_f32_16x16x32_bf16 v[28:31], v[164:167], v[216:219], 0
	v_mfma_f32_16x16x32_bf16 v[24:27], v[172:175], v[216:219], 0
	v_mfma_f32_16x16x32_bf16 v[12:15], v[164:167], v[224:227], 0
	v_mfma_f32_16x16x32_bf16 v[8:11], v[172:175], v[224:227], 0
	v_mfma_f32_16x16x32_bf16 v[60:63], v[168:171], v[200:203], v[60:63]
	v_mfma_f32_16x16x32_bf16 v[56:59], v[176:179], v[200:203], v[56:59]
	v_mfma_f32_16x16x32_bf16 v[44:47], v[168:171], v[212:215], v[44:47]
	v_mfma_f32_16x16x32_bf16 v[40:43], v[176:179], v[212:215], v[40:43]
	v_mfma_f32_16x16x32_bf16 v[28:31], v[168:171], v[220:223], v[28:31]
	v_mfma_f32_16x16x32_bf16 v[24:27], v[176:179], v[220:223], v[24:27]
	v_mfma_f32_16x16x32_bf16 v[12:15], v[168:171], v[228:231], v[12:15]
	v_mfma_f32_16x16x32_bf16 v[8:11], v[176:179], v[228:231], v[8:11]
	v_mfma_f32_16x16x32_bf16 v[52:55], v[180:183], v[196:199], 0
	v_mfma_f32_16x16x32_bf16 v[48:51], v[188:191], v[196:199], 0
	v_mfma_f32_16x16x32_bf16 v[36:39], v[180:183], v[208:211], 0
	v_mfma_f32_16x16x32_bf16 v[32:35], v[188:191], v[208:211], 0
	v_mfma_f32_16x16x32_bf16 v[20:23], v[180:183], v[216:219], 0
	v_mfma_f32_16x16x32_bf16 v[16:19], v[188:191], v[216:219], 0
	v_mfma_f32_16x16x32_bf16 v[4:7], v[180:183], v[224:227], 0
	v_mfma_f32_16x16x32_bf16 v[0:3], v[188:191], v[224:227], 0
	v_mfma_f32_16x16x32_bf16 v[52:55], v[184:187], v[200:203], v[52:55]
	v_mfma_f32_16x16x32_bf16 v[48:51], v[192:195], v[200:203], v[48:51]
	v_mfma_f32_16x16x32_bf16 v[36:39], v[184:187], v[212:215], v[36:39]
	v_mfma_f32_16x16x32_bf16 v[32:35], v[192:195], v[212:215], v[32:35]
	v_mfma_f32_16x16x32_bf16 v[20:23], v[184:187], v[220:223], v[20:23]
	v_mfma_f32_16x16x32_bf16 v[16:19], v[192:195], v[220:223], v[16:19]
	v_mfma_f32_16x16x32_bf16 v[4:7], v[184:187], v[228:231], v[4:7]
	v_mfma_f32_16x16x32_bf16 v[0:3], v[192:195], v[228:231], v[0:3]
	s_setprio 0
	s_barrier
	s_add_i32 s77, 0, 0x18000
	v_add_u32_e32 v163, s77, v158
	s_add_i32 s78, 0, 0x1c000
	ds_read_b128 v[164:167], v163
	ds_read_b128 v[168:171], v163 offset:1024
	ds_read_b128 v[172:175], v163 offset:2048
	ds_read_b128 v[176:179], v163 offset:3072
	v_add_u32_e32 v163, s78, v158
	ds_read_b128 v[180:183], v163
	ds_read_b128 v[184:187], v163 offset:1024
	ds_read_b128 v[188:191], v163 offset:2048
	ds_read_b128 v[192:195], v163 offset:3072
	s_add_u32 s42, s42, 0x40000
	s_addc_u32 s43, s43, 0
	s_mov_b32 m0, s60
	v_lshl_add_u64 v[236:237], s[42:43], 0, v[128:129]
	ds_read_b128 v[196:199], v162 offset:32768
	ds_read_b128 v[200:203], v162 offset:33792
	ds_read_b128 v[208:211], v162 offset:34816
	ds_read_b128 v[212:215], v162 offset:35840
	ds_read_b128 v[216:219], v162 offset:36864
	ds_read_b128 v[220:223], v162 offset:37888
	ds_read_b128 v[224:227], v162 offset:38912
	ds_read_b128 v[228:231], v162 offset:39936
	global_load_lds_dwordx4 v[236:237], off
	v_lshl_add_u64 v[236:237], s[42:43], 0, v[132:133]
	s_mov_b32 m0, s61
	s_nop 0
	global_load_lds_dwordx4 v[236:237], off
	s_waitcnt vmcnt(8)
	s_waitcnt lgkmcnt(0)
	s_barrier
	s_setprio 1
	s_waitcnt lgkmcnt(0)
	v_mfma_f32_16x16x32_bf16 v[124:127], v[164:167], v[196:199], v[124:127]
	v_mfma_f32_16x16x32_bf16 v[120:123], v[172:175], v[196:199], v[120:123]
	v_mfma_f32_16x16x32_bf16 v[108:111], v[164:167], v[208:211], v[108:111]
	v_mfma_f32_16x16x32_bf16 v[104:107], v[172:175], v[208:211], v[104:107]
	v_mfma_f32_16x16x32_bf16 v[92:95], v[164:167], v[216:219], v[92:95]
	v_mfma_f32_16x16x32_bf16 v[88:91], v[172:175], v[216:219], v[88:91]
	v_mfma_f32_16x16x32_bf16 v[76:79], v[164:167], v[224:227], v[76:79]
	v_mfma_f32_16x16x32_bf16 v[72:75], v[172:175], v[224:227], v[72:75]
	v_mfma_f32_16x16x32_bf16 v[124:127], v[168:171], v[200:203], v[124:127]
	v_mfma_f32_16x16x32_bf16 v[120:123], v[176:179], v[200:203], v[120:123]
	v_mfma_f32_16x16x32_bf16 v[108:111], v[168:171], v[212:215], v[108:111]
	v_mfma_f32_16x16x32_bf16 v[104:107], v[176:179], v[212:215], v[104:107]
	v_mfma_f32_16x16x32_bf16 v[92:95], v[168:171], v[220:223], v[92:95]
	v_mfma_f32_16x16x32_bf16 v[88:91], v[176:179], v[220:223], v[88:91]
	v_mfma_f32_16x16x32_bf16 v[76:79], v[168:171], v[228:231], v[76:79]
	v_mfma_f32_16x16x32_bf16 v[72:75], v[176:179], v[228:231], v[72:75]
	v_mfma_f32_16x16x32_bf16 v[116:119], v[180:183], v[196:199], v[116:119]
	v_mfma_f32_16x16x32_bf16 v[112:115], v[188:191], v[196:199], v[112:115]
	v_mfma_f32_16x16x32_bf16 v[100:103], v[180:183], v[208:211], v[100:103]
	v_mfma_f32_16x16x32_bf16 v[96:99], v[188:191], v[208:211], v[96:99]
	v_mfma_f32_16x16x32_bf16 v[84:87], v[180:183], v[216:219], v[84:87]
	v_mfma_f32_16x16x32_bf16 v[80:83], v[188:191], v[216:219], v[80:83]
	v_mfma_f32_16x16x32_bf16 v[68:71], v[180:183], v[224:227], v[68:71]
	v_mfma_f32_16x16x32_bf16 v[64:67], v[188:191], v[224:227], v[64:67]
	v_mfma_f32_16x16x32_bf16 v[116:119], v[184:187], v[200:203], v[116:119]
	v_mfma_f32_16x16x32_bf16 v[112:115], v[192:195], v[200:203], v[112:115]
	v_mfma_f32_16x16x32_bf16 v[100:103], v[184:187], v[212:215], v[100:103]
	v_mfma_f32_16x16x32_bf16 v[96:99], v[192:195], v[212:215], v[96:99]
	v_mfma_f32_16x16x32_bf16 v[84:87], v[184:187], v[220:223], v[84:87]
	v_mfma_f32_16x16x32_bf16 v[80:83], v[192:195], v[220:223], v[80:83]
	v_mfma_f32_16x16x32_bf16 v[68:71], v[184:187], v[228:231], v[68:71]
	v_mfma_f32_16x16x32_bf16 v[64:67], v[192:195], v[228:231], v[64:67]
	s_setprio 0
	s_barrier
; #define PG8_STAGE(bufoff, gbase, voff) do { _Pragma("unroll") for (int _i = 0; _i < 2; ++_i) \
;         __builtin_amdgcn_global_load_lds((const unsigned*)((const char*)(gbase) + (voff)[_i]), (PG8_LAS unsigned*)(lds + (bufoff) + ldsw + _i * 8192), 16, 0, 0); } while (0)
; #define PG8_LDA(dst, b, h) do { _Pragma("unroll") for (int m = 0; m < 4; ++m) _Pragma("unroll") for (int k = 0; k < 2; ++k) dst[m][k] = *(const PG8_LAS bf16x8*)(lds + PG8_SA(b, h) + aoff + m * 2048 + k * 1024); } while (0)
; #define PG8_LDB(dst, b, h) do { _Pragma("unroll") for (int n = 0; n < 2; ++n) _Pragma("unroll") for (int k = 0; k < 2; ++k) dst[n][k] = *(const PG8_LAS bf16x8*)(lds + PG8_SB(b, h) + boff + n * 2048 + k * 1024); } while (0)
; #define PG8_MMA(ai, bj, At, Bt) do { __builtin_amdgcn_s_setprio(1); _Pragma("unroll") for (int m = 0; m < 4; ++m) _Pragma("unroll") for (int n = 0; n < 2; ++n) _Pragma("unroll") for (int k = 0; k < 2; ++k) \
;         acc[ai][bj][m][n] = __builtin_amdgcn_mfma_f32_16x16x32_bf16(Bt[n][k], At[m][k], acc[ai][bj][m][n], 0, 0, 0); __builtin_amdgcn_s_setprio(0); } while (0)
; #define PG8_WAIT_V(n) asm volatile("s_waitcnt vmcnt(" #n ")" ::: "memory")
; template <class Epi, class Sched, bool ALIGN_EPI = false, bool SP2 = false>
; __device__ __forceinline__ void gemm_phase(PG8_LAS unsigned char* lds, const Gemm g, const Sched& S, const Epi& E) {
;     ...
;             PG8_LDB(B0, 0, 0); PG8_LDB(B1, 0, 1); PG8_SCHED; PG8_LDA(At, 0, 0); PG8_STAGE(PG8_SA(1, 1), a1 + hstep, voffA);
;             PG8_WAIT_V(8); PG8_WAIT_L(0); PG8_BAR; PG8_MMA(0, 0, At, B0); PG8_MMA(0, 1, At, B1); PG8_BAR; PG8_SCHED;
;             PG8_LDA(At, 0, 1); PG8_STAGE(PG8_SB(0, 0), b2, voffB); PG8_STAGE(PG8_SB(0, 1), b2 + hstep, voffB); PG8_STAGE(PG8_SA(0, 0), a2, voffA);
;             PG8_WAIT_V(8); PG8_WAIT_L(0); PG8_BAR; PG8_MMA(1, 0, At, B0); PG8_MMA(1, 1, At, B1); PG8_BAR; PG8_SCHED;
;             PG8_LDB(B0, 1, 0); PG8_LDB(B1, 1, 1); PG8_SCHED; PG8_LDA(At, 1, 0); PG8_STAGE(PG8_SA(0, 1), a2 + hstep, voffA);
;             PG8_WAIT_V(8); PG8_WAIT_L(0); PG8_BAR; PG8_MMA(0, 0, At, B0); PG8_MMA(0, 1, At, B1); PG8_BAR; PG8_SCHED;
;             PG8_LDA(At, 1, 1); PG8_STAGE(PG8_SB(1, 0), b3, voffB); PG8_STAGE(PG8_SB(1, 1), b3 + hstep, voffB); PG8_STAGE(PG8_SA(1, 0), a3, voffA);
;             PG8_WAIT_V(8); PG8_WAIT_L(0); PG8_BAR; PG8_MMA(1, 0, At, B0); PG8_MMA(1, 1, At, B1); PG8_BAR; PG8_SCHED;
	s_add_i32 s42, s77, s57
	v_lshl_add_u64 v[142:143], v[142:143], 0, s[8:9]
	s_mov_b32 m0, s42
	ds_read_b128 v[196:199], v162 offset:49152
	ds_read_b128 v[200:203], v162 offset:50176
	ds_read_b128 v[208:211], v162 offset:51200
	ds_read_b128 v[212:215], v162 offset:52224
	ds_read_b128 v[216:219], v162 offset:53248
	ds_read_b128 v[220:223], v162 offset:54272
	ds_read_b128 v[224:227], v162 offset:55296
	ds_read_b128 v[228:231], v162 offset:56320
	global_load_lds_dwordx4 v[142:143], off
	s_add_i32 m0, s42, 0x2000
	s_add_u32 s40, s40, 0x40080
	v_lshl_add_u64 v[142:143], v[204:205], 0, s[8:9]
	s_addc_u32 s41, s41, 0
	s_add_i32 s42, s78, s57
	global_load_lds_dwordx4 v[142:143], off
	v_lshl_add_u64 v[142:143], s[40:41], 0, v[130:131]
	s_mov_b32 m0, s42
	s_nop 0
	global_load_lds_dwordx4 v[142:143], off
	v_lshl_add_u64 v[142:143], s[40:41], 0, v[134:135]
	s_add_i32 m0, s42, 0x2000
	s_nop 0
	global_load_lds_dwordx4 v[142:143], off
	v_lshl_add_u64 v[142:143], v[232:233], 0, s[8:9]
	s_mov_b32 m0, s65
	s_nop 0
	global_load_lds_dwordx4 v[142:143], off
	v_lshl_add_u64 v[142:143], v[234:235], 0, s[8:9]
	s_mov_b32 m0, s66
	s_nop 0
	global_load_lds_dwordx4 v[142:143], off
	s_waitcnt vmcnt(8)
	s_waitcnt lgkmcnt(0)
	s_barrier
	s_setprio 1
	s_waitcnt lgkmcnt(0)
	v_mfma_f32_16x16x32_bf16 v[60:63], v[164:167], v[196:199], v[60:63]
	v_mfma_f32_16x16x32_bf16 v[56:59], v[172:175], v[196:199], v[56:59]
	v_mfma_f32_16x16x32_bf16 v[44:47], v[164:167], v[208:211], v[44:47]
	v_mfma_f32_16x16x32_bf16 v[40:43], v[172:175], v[208:211], v[40:43]
	v_mfma_f32_16x16x32_bf16 v[28:31], v[164:167], v[216:219], v[28:31]
	v_mfma_f32_16x16x32_bf16 v[24:27], v[172:175], v[216:219], v[24:27]
	v_mfma_f32_16x16x32_bf16 v[12:15], v[164:167], v[224:227], v[12:15]
	v_mfma_f32_16x16x32_bf16 v[8:11], v[172:175], v[224:227], v[8:11]
	v_mfma_f32_16x16x32_bf16 v[60:63], v[168:171], v[200:203], v[60:63]
	v_mfma_f32_16x16x32_bf16 v[56:59], v[176:179], v[200:203], v[56:59]
	v_mfma_f32_16x16x32_bf16 v[44:47], v[168:171], v[212:215], v[44:47]
	v_mfma_f32_16x16x32_bf16 v[40:43], v[176:179], v[212:215], v[40:43]
	v_mfma_f32_16x16x32_bf16 v[28:31], v[168:171], v[220:223], v[28:31]
	v_mfma_f32_16x16x32_bf16 v[24:27], v[176:179], v[220:223], v[24:27]
	v_mfma_f32_16x16x32_bf16 v[12:15], v[168:171], v[228:231], v[12:15]
	v_mfma_f32_16x16x32_bf16 v[8:11], v[176:179], v[228:231], v[8:11]
	v_mfma_f32_16x16x32_bf16 v[52:55], v[180:183], v[196:199], v[52:55]
	v_mfma_f32_16x16x32_bf16 v[48:51], v[188:191], v[196:199], v[48:51]
	v_mfma_f32_16x16x32_bf16 v[36:39], v[180:183], v[208:211], v[36:39]
	v_mfma_f32_16x16x32_bf16 v[32:35], v[188:191], v[208:211], v[32:35]
	v_mfma_f32_16x16x32_bf16 v[20:23], v[180:183], v[216:219], v[20:23]
	v_mfma_f32_16x16x32_bf16 v[16:19], v[188:191], v[216:219], v[16:19]
	v_mfma_f32_16x16x32_bf16 v[4:7], v[180:183], v[224:227], v[4:7]
	v_mfma_f32_16x16x32_bf16 v[0:3], v[188:191], v[224:227], v[0:3]
	v_mfma_f32_16x16x32_bf16 v[52:55], v[184:187], v[200:203], v[52:55]
	v_mfma_f32_16x16x32_bf16 v[48:51], v[192:195], v[200:203], v[48:51]
	v_mfma_f32_16x16x32_bf16 v[36:39], v[184:187], v[212:215], v[36:39]
	v_mfma_f32_16x16x32_bf16 v[32:35], v[192:195], v[212:215], v[32:35]
	v_mfma_f32_16x16x32_bf16 v[20:23], v[184:187], v[220:223], v[20:23]
	v_mfma_f32_16x16x32_bf16 v[16:19], v[192:195], v[220:223], v[16:19]
	v_mfma_f32_16x16x32_bf16 v[4:7], v[184:187], v[228:231], v[4:7]
	v_mfma_f32_16x16x32_bf16 v[0:3], v[192:195], v[228:231], v[0:3]
	s_setprio 0
	s_barrier
	s_add_i32 s76, s76, 2
	s_add_u32 s38, s38, 0x100
	s_addc_u32 s39, s39, 0
	s_add_u32 s74, s74, 0x100
	s_addc_u32 s75, s75, 0
	s_cmp_gt_u32 s76, 13
	s_cbranch_scc0 .LBB0_877
	s_branch .Lpeel_exit_5
.LBB0_877:
	ds_read_b128 v[164:167], v160
	ds_read_b128 v[168:171], v160 offset:1024
	ds_read_b128 v[172:175], v160 offset:2048
	ds_read_b128 v[176:179], v160 offset:3072
	ds_read_b128 v[180:183], v161
	ds_read_b128 v[184:187], v161 offset:1024
	ds_read_b128 v[188:191], v161 offset:2048
	ds_read_b128 v[192:195], v161 offset:3072
	s_add_u32 s40, s38, 0xfffc0080
	s_addc_u32 s41, s39, -1
	s_cmp_eq_u32 s76, 12
	s_cselect_b32 s43, s21, s41
	s_cselect_b32 s42, s72, s40
	s_cselect_b32 s41, s23, s75
	s_cselect_b32 s40, s73, s74
	v_lshl_add_u64 v[142:143], s[38:39], 0, v[136:137]
	s_add_i32 m0, s31, 0xc000
	ds_read_b128 v[196:199], v162
	ds_read_b128 v[200:203], v162 offset:1024
	ds_read_b128 v[208:211], v162 offset:2048
	ds_read_b128 v[212:215], v162 offset:3072
	ds_read_b128 v[216:219], v162 offset:4096
	ds_read_b128 v[220:223], v162 offset:5120
	ds_read_b128 v[224:227], v162 offset:6144
	ds_read_b128 v[228:231], v162 offset:7168
	global_load_lds_dwordx4 v[142:143], off
	v_lshl_add_u64 v[142:143], s[38:39], 0, v[138:139]
	s_add_i32 m0, s31, 0xe000
	s_nop 0
	global_load_lds_dwordx4 v[142:143], off
	s_waitcnt vmcnt(8)
	s_waitcnt lgkmcnt(0)
	s_barrier
; #define PG8_STAGE(bufoff, gbase, voff) do { _Pragma("unroll") for (int _i = 0; _i < 2; ++_i) \
;         __builtin_amdgcn_global_load_lds((const unsigned*)((const char*)(gbase) + (voff)[_i]), (PG8_LAS unsigned*)(lds + (bufoff) + ldsw + _i * 8192), 16, 0, 0); } while (0)
; #define PG8_LDA(dst, b, h) do { _Pragma("unroll") for (int m = 0; m < 4; ++m) _Pragma("unroll") for (int k = 0; k < 2; ++k) dst[m][k] = *(const PG8_LAS bf16x8*)(lds + PG8_SA(b, h) + aoff + m * 2048 + k * 1024); } while (0)
; #define PG8_MMA(ai, bj, At, Bt) do { __builtin_amdgcn_s_setprio(1); _Pragma("unroll") for (int m = 0; m < 4; ++m) _Pragma("unroll") for (int n = 0; n < 2; ++n) _Pragma("unroll") for (int k = 0; k < 2; ++k) \
;         acc[ai][bj][m][n] = __builtin_amdgcn_mfma_f32_16x16x32_bf16(Bt[n][k], At[m][k], acc[ai][bj][m][n], 0, 0, 0); __builtin_amdgcn_s_setprio(0); } while (0)
; #define PG8_WAIT_V(n) asm volatile("s_waitcnt vmcnt(" #n ")" ::: "memory")
; #define PG8_WAIT_L(n) asm volatile("s_waitcnt lgkmcnt(" #n ")" ::: "memory")
; #define PG8_BAR __builtin_amdgcn_s_barrier()
; #define PG8_SCHED __builtin_amdgcn_sched_barrier(0)
; template <class Epi, class Sched, bool ALIGN_EPI = false, bool SP2 = false>
; __device__ __forceinline__ void gemm_phase(PG8_LAS unsigned char* lds, const Gemm g, const Sched& S, const Epi& E) {
;     ...
;             PG8_WAIT_V(8); PG8_WAIT_L(0); PG8_BAR; PG8_MMA(0, 0, At, B0); PG8_MMA(0, 1, At, B1); PG8_BAR; PG8_SCHED;
;             PG8_LDA(At, 0, 1); PG8_STAGE(PG8_SB(0, 0), b2, voffB); PG8_STAGE(PG8_SB(0, 1), b2 + hstep, voffB); PG8_STAGE(PG8_SA(0, 0), a2, voffA);
;             PG8_WAIT_V(8); PG8_WAIT_L(0); PG8_BAR; PG8_MMA(1, 0, At, B0); PG8_MMA(1, 1, At, B1); PG8_BAR; PG8_SCHED;
	s_setprio 1
	s_waitcnt lgkmcnt(0)
	v_mfma_f32_16x16x32_bf16 v[124:127], v[164:167], v[196:199], v[124:127]
	v_mfma_f32_16x16x32_bf16 v[120:123], v[172:175], v[196:199], v[120:123]
	v_mfma_f32_16x16x32_bf16 v[108:111], v[164:167], v[208:211], v[108:111]
	v_mfma_f32_16x16x32_bf16 v[104:107], v[172:175], v[208:211], v[104:107]
	v_mfma_f32_16x16x32_bf16 v[92:95], v[164:167], v[216:219], v[92:95]
	v_mfma_f32_16x16x32_bf16 v[88:91], v[172:175], v[216:219], v[88:91]
	v_mfma_f32_16x16x32_bf16 v[76:79], v[164:167], v[224:227], v[76:79]
	v_mfma_f32_16x16x32_bf16 v[72:75], v[172:175], v[224:227], v[72:75]
	v_mfma_f32_16x16x32_bf16 v[124:127], v[168:171], v[200:203], v[124:127]
	v_mfma_f32_16x16x32_bf16 v[120:123], v[176:179], v[200:203], v[120:123]
	v_mfma_f32_16x16x32_bf16 v[108:111], v[168:171], v[212:215], v[108:111]
	v_mfma_f32_16x16x32_bf16 v[104:107], v[176:179], v[212:215], v[104:107]
	v_mfma_f32_16x16x32_bf16 v[92:95], v[168:171], v[220:223], v[92:95]
	v_mfma_f32_16x16x32_bf16 v[88:91], v[176:179], v[220:223], v[88:91]
	v_mfma_f32_16x16x32_bf16 v[76:79], v[168:171], v[228:231], v[76:79]
	v_mfma_f32_16x16x32_bf16 v[72:75], v[176:179], v[228:231], v[72:75]
	v_mfma_f32_16x16x32_bf16 v[116:119], v[180:183], v[196:199], v[116:119]
	v_mfma_f32_16x16x32_bf16 v[112:115], v[188:191], v[196:199], v[112:115]
	v_mfma_f32_16x16x32_bf16 v[100:103], v[180:183], v[208:211], v[100:103]
	v_mfma_f32_16x16x32_bf16 v[96:99], v[188:191], v[208:211], v[96:99]
	v_mfma_f32_16x16x32_bf16 v[84:87], v[180:183], v[216:219], v[84:87]
	v_mfma_f32_16x16x32_bf16 v[80:83], v[188:191], v[216:219], v[80:83]
	v_mfma_f32_16x16x32_bf16 v[68:71], v[180:183], v[224:227], v[68:71]
	v_mfma_f32_16x16x32_bf16 v[64:67], v[188:191], v[224:227], v[64:67]
	v_mfma_f32_16x16x32_bf16 v[116:119], v[184:187], v[200:203], v[116:119]
	v_mfma_f32_16x16x32_bf16 v[112:115], v[192:195], v[200:203], v[112:115]
	v_mfma_f32_16x16x32_bf16 v[100:103], v[184:187], v[212:215], v[100:103]
	v_mfma_f32_16x16x32_bf16 v[96:99], v[192:195], v[212:215], v[96:99]
	v_mfma_f32_16x16x32_bf16 v[84:87], v[184:187], v[220:223], v[84:87]
	v_mfma_f32_16x16x32_bf16 v[80:83], v[192:195], v[220:223], v[80:83]
	v_mfma_f32_16x16x32_bf16 v[68:71], v[184:187], v[228:231], v[68:71]
	v_mfma_f32_16x16x32_bf16 v[64:67], v[192:195], v[228:231], v[64:67]
	s_setprio 0
	s_barrier
	s_add_i32 s77, s67, s57
	v_lshl_add_u64 v[142:143], s[40:41], 0, v[130:131]
	s_mov_b32 m0, s77
	ds_read_b128 v[196:199], v162 offset:16384
	ds_read_b128 v[200:203], v162 offset:17408
	ds_read_b128 v[208:211], v162 offset:18432
	ds_read_b128 v[212:215], v162 offset:19456
	ds_read_b128 v[216:219], v162 offset:20480
	ds_read_b128 v[220:223], v162 offset:21504
	ds_read_b128 v[224:227], v162 offset:22528
	ds_read_b128 v[228:231], v162 offset:23552
	global_load_lds_dwordx4 v[142:143], off
	s_add_i32 m0, s77, 0x2000
	s_add_u32 s78, s40, 0x40000
	v_lshl_add_u64 v[204:205], s[40:41], 0, v[134:135]
	s_addc_u32 s79, s41, 0
	s_add_i32 s77, s68, s57
	global_load_lds_dwordx4 v[204:205], off
	v_lshl_add_u64 v[232:233], s[78:79], 0, v[130:131]
	s_mov_b32 m0, s77
	v_lshl_add_u64 v[234:235], s[42:43], 0, v[132:133]
	global_load_lds_dwordx4 v[232:233], off
	v_lshl_add_u64 v[232:233], s[78:79], 0, v[134:135]
	s_add_i32 m0, s77, 0x2000
	s_nop 0
	global_load_lds_dwordx4 v[232:233], off
	v_lshl_add_u64 v[232:233], s[42:43], 0, v[128:129]
	s_mov_b32 m0, s31
	s_nop 0
	global_load_lds_dwordx4 v[232:233], off
	s_mov_b32 m0, s59
	s_nop 0
	global_load_lds_dwordx4 v[234:235], off
	s_waitcnt vmcnt(8)
	s_waitcnt lgkmcnt(0)
	s_barrier
	s_setprio 1
	s_waitcnt lgkmcnt(0)
	v_mfma_f32_16x16x32_bf16 v[60:63], v[164:167], v[196:199], v[60:63]
	v_mfma_f32_16x16x32_bf16 v[56:59], v[172:175], v[196:199], v[56:59]
	v_mfma_f32_16x16x32_bf16 v[44:47], v[164:167], v[208:211], v[44:47]
	v_mfma_f32_16x16x32_bf16 v[40:43], v[172:175], v[208:211], v[40:43]
	v_mfma_f32_16x16x32_bf16 v[28:31], v[164:167], v[216:219], v[28:31]
	v_mfma_f32_16x16x32_bf16 v[24:27], v[172:175], v[216:219], v[24:27]
	v_mfma_f32_16x16x32_bf16 v[12:15], v[164:167], v[224:227], v[12:15]
	v_mfma_f32_16x16x32_bf16 v[8:11], v[172:175], v[224:227], v[8:11]
	v_mfma_f32_16x16x32_bf16 v[60:63], v[168:171], v[200:203], v[60:63]
	v_mfma_f32_16x16x32_bf16 v[56:59], v[176:179], v[200:203], v[56:59]
	v_mfma_f32_16x16x32_bf16 v[44:47], v[168:171], v[212:215], v[44:47]
	v_mfma_f32_16x16x32_bf16 v[40:43], v[176:179], v[212:215], v[40:43]
	v_mfma_f32_16x16x32_bf16 v[28:31], v[168:171], v[220:223], v[28:31]
	v_mfma_f32_16x16x32_bf16 v[24:27], v[176:179], v[220:223], v[24:27]
	v_mfma_f32_16x16x32_bf16 v[12:15], v[168:171], v[228:231], v[12:15]
	v_mfma_f32_16x16x32_bf16 v[8:11], v[176:179], v[228:231], v[8:11]
	v_mfma_f32_16x16x32_bf16 v[52:55], v[180:183], v[196:199], v[52:55]
	v_mfma_f32_16x16x32_bf16 v[48:51], v[188:191], v[196:199], v[48:51]
	v_mfma_f32_16x16x32_bf16 v[36:39], v[180:183], v[208:211], v[36:39]
	v_mfma_f32_16x16x32_bf16 v[32:35], v[188:191], v[208:211], v[32:35]
	v_mfma_f32_16x16x32_bf16 v[20:23], v[180:183], v[216:219], v[20:23]
	v_mfma_f32_16x16x32_bf16 v[16:19], v[188:191], v[216:219], v[16:19]
	v_mfma_f32_16x16x32_bf16 v[4:7], v[180:183], v[224:227], v[4:7]
	v_mfma_f32_16x16x32_bf16 v[0:3], v[188:191], v[224:227], v[0:3]
	v_mfma_f32_16x16x32_bf16 v[52:55], v[184:187], v[200:203], v[52:55]
	v_mfma_f32_16x16x32_bf16 v[48:51], v[192:195], v[200:203], v[48:51]
	v_mfma_f32_16x16x32_bf16 v[36:39], v[184:187], v[212:215], v[36:39]
	v_mfma_f32_16x16x32_bf16 v[32:35], v[192:195], v[212:215], v[32:35]
	v_mfma_f32_16x16x32_bf16 v[20:23], v[184:187], v[220:223], v[20:23]
	v_mfma_f32_16x16x32_bf16 v[16:19], v[192:195], v[220:223], v[16:19]
	v_mfma_f32_16x16x32_bf16 v[4:7], v[184:187], v[228:231], v[4:7]
	v_mfma_f32_16x16x32_bf16 v[0:3], v[192:195], v[228:231], v[0:3]
	s_setprio 0
	s_barrier
; #define PG8_STAGE(bufoff, gbase, voff) do { _Pragma("unroll") for (int _i = 0; _i < 2; ++_i) \
;         __builtin_amdgcn_global_load_lds((const unsigned*)((const char*)(gbase) + (voff)[_i]), (PG8_LAS unsigned*)(lds + (bufoff) + ldsw + _i * 8192), 16, 0, 0); } while (0)
; #define PG8_LDA(dst, b, h) do { _Pragma("unroll") for (int m = 0; m < 4; ++m) _Pragma("unroll") for (int k = 0; k < 2; ++k) dst[m][k] = *(const PG8_LAS bf16x8*)(lds + PG8_SA(b, h) + aoff + m * 2048 + k * 1024); } while (0)
; #define PG8_LDB(dst, b, h) do { _Pragma("unroll") for (int n = 0; n < 2; ++n) _Pragma("unroll") for (int k = 0; k < 2; ++k) dst[n][k] = *(const PG8_LAS bf16x8*)(lds + PG8_SB(b, h) + boff + n * 2048 + k * 1024); } while (0)
; #define PG8_MMA(ai, bj, At, Bt) do { __builtin_amdgcn_s_setprio(1); _Pragma("unroll") for (int m = 0; m < 4; ++m) _Pragma("unroll") for (int n = 0; n < 2; ++n) _Pragma("unroll") for (int k = 0; k < 2; ++k) \
;         acc[ai][bj][m][n] = __builtin_amdgcn_mfma_f32_16x16x32_bf16(Bt[n][k], At[m][k], acc[ai][bj][m][n], 0, 0, 0); __builtin_amdgcn_s_setprio(0); } while (0)
; #define PG8_WAIT_V(n) asm volatile("s_waitcnt vmcnt(" #n ")" ::: "memory")
; #define PG8_WAIT_L(n) asm volatile("s_waitcnt lgkmcnt(" #n ")" ::: "memory")
; #define PG8_BAR __builtin_amdgcn_s_barrier()
; #define PG8_SCHED __builtin_amdgcn_sched_barrier(0)
; template <class Epi, class Sched, bool ALIGN_EPI = false, bool SP2 = false>
; __device__ __forceinline__ void gemm_phase(PG8_LAS unsigned char* lds, const Gemm g, const Sched& S, const Epi& E) {
;     ...
;             PG8_LDB(B0, 1, 0); PG8_LDB(B1, 1, 1); PG8_SCHED; PG8_LDA(At, 1, 0); PG8_STAGE(PG8_SA(0, 1), a2 + hstep, voffA);
;             PG8_WAIT_V(8); PG8_WAIT_L(0); PG8_BAR; PG8_MMA(0, 0, At, B0); PG8_MMA(0, 1, At, B1); PG8_BAR; PG8_SCHED;
	s_add_i32 s77, 0, 0x18000
	v_add_u32_e32 v163, s77, v158
	s_add_i32 s78, 0, 0x1c000
	ds_read_b128 v[164:167], v163
	ds_read_b128 v[168:171], v163 offset:1024
	ds_read_b128 v[172:175], v163 offset:2048
	ds_read_b128 v[176:179], v163 offset:3072
	v_add_u32_e32 v163, s78, v158
	ds_read_b128 v[180:183], v163
	ds_read_b128 v[184:187], v163 offset:1024
	ds_read_b128 v[188:191], v163 offset:2048
	ds_read_b128 v[192:195], v163 offset:3072
	s_add_u32 s42, s42, 0x40000
	s_addc_u32 s43, s43, 0
	s_mov_b32 m0, s60
	v_lshl_add_u64 v[236:237], s[42:43], 0, v[128:129]
	ds_read_b128 v[196:199], v162 offset:32768
	ds_read_b128 v[200:203], v162 offset:33792
	ds_read_b128 v[208:211], v162 offset:34816
	ds_read_b128 v[212:215], v162 offset:35840
	ds_read_b128 v[216:219], v162 offset:36864
	ds_read_b128 v[220:223], v162 offset:37888
	ds_read_b128 v[224:227], v162 offset:38912
	ds_read_b128 v[228:231], v162 offset:39936
	global_load_lds_dwordx4 v[236:237], off
	v_lshl_add_u64 v[236:237], s[42:43], 0, v[132:133]
	s_mov_b32 m0, s61
	s_nop 0
	global_load_lds_dwordx4 v[236:237], off
	s_waitcnt vmcnt(8)
	s_waitcnt lgkmcnt(0)
	s_barrier
	s_setprio 1
	s_waitcnt lgkmcnt(0)
	v_mfma_f32_16x16x32_bf16 v[124:127], v[164:167], v[196:199], v[124:127]
	v_mfma_f32_16x16x32_bf16 v[120:123], v[172:175], v[196:199], v[120:123]
	v_mfma_f32_16x16x32_bf16 v[108:111], v[164:167], v[208:211], v[108:111]
	v_mfma_f32_16x16x32_bf16 v[104:107], v[172:175], v[208:211], v[104:107]
	v_mfma_f32_16x16x32_bf16 v[92:95], v[164:167], v[216:219], v[92:95]
	v_mfma_f32_16x16x32_bf16 v[88:91], v[172:175], v[216:219], v[88:91]
	v_mfma_f32_16x16x32_bf16 v[76:79], v[164:167], v[224:227], v[76:79]
	v_mfma_f32_16x16x32_bf16 v[72:75], v[172:175], v[224:227], v[72:75]
	v_mfma_f32_16x16x32_bf16 v[124:127], v[168:171], v[200:203], v[124:127]
	v_mfma_f32_16x16x32_bf16 v[120:123], v[176:179], v[200:203], v[120:123]
	v_mfma_f32_16x16x32_bf16 v[108:111], v[168:171], v[212:215], v[108:111]
	v_mfma_f32_16x16x32_bf16 v[104:107], v[176:179], v[212:215], v[104:107]
	v_mfma_f32_16x16x32_bf16 v[92:95], v[168:171], v[220:223], v[92:95]
	v_mfma_f32_16x16x32_bf16 v[88:91], v[176:179], v[220:223], v[88:91]
	v_mfma_f32_16x16x32_bf16 v[76:79], v[168:171], v[228:231], v[76:79]
	v_mfma_f32_16x16x32_bf16 v[72:75], v[176:179], v[228:231], v[72:75]
	v_mfma_f32_16x16x32_bf16 v[116:119], v[180:183], v[196:199], v[116:119]
	v_mfma_f32_16x16x32_bf16 v[112:115], v[188:191], v[196:199], v[112:115]
	v_mfma_f32_16x16x32_bf16 v[100:103], v[180:183], v[208:211], v[100:103]
	v_mfma_f32_16x16x32_bf16 v[96:99], v[188:191], v[208:211], v[96:99]
	v_mfma_f32_16x16x32_bf16 v[84:87], v[180:183], v[216:219], v[84:87]
	v_mfma_f32_16x16x32_bf16 v[80:83], v[188:191], v[216:219], v[80:83]
	v_mfma_f32_16x16x32_bf16 v[68:71], v[180:183], v[224:227], v[68:71]
	v_mfma_f32_16x16x32_bf16 v[64:67], v[188:191], v[224:227], v[64:67]
	v_mfma_f32_16x16x32_bf16 v[116:119], v[184:187], v[200:203], v[116:119]
	v_mfma_f32_16x16x32_bf16 v[112:115], v[192:195], v[200:203], v[112:115]
	v_mfma_f32_16x16x32_bf16 v[100:103], v[184:187], v[212:215], v[100:103]
	v_mfma_f32_16x16x32_bf16 v[96:99], v[192:195], v[212:215], v[96:99]
	v_mfma_f32_16x16x32_bf16 v[84:87], v[184:187], v[220:223], v[84:87]
	v_mfma_f32_16x16x32_bf16 v[80:83], v[192:195], v[220:223], v[80:83]
	v_mfma_f32_16x16x32_bf16 v[68:71], v[184:187], v[228:231], v[68:71]
	v_mfma_f32_16x16x32_bf16 v[64:67], v[192:195], v[228:231], v[64:67]
	s_setprio 0
	s_barrier
; #define PG8_STAGE(bufoff, gbase, voff) do { _Pragma("unroll") for (int _i = 0; _i < 2; ++_i) \
;         __builtin_amdgcn_global_load_lds((const unsigned*)((const char*)(gbase) + (voff)[_i]), (PG8_LAS unsigned*)(lds + (bufoff) + ldsw + _i * 8192), 16, 0, 0); } while (0)
; #define PG8_LDA(dst, b, h) do { _Pragma("unroll") for (int m = 0; m < 4; ++m) _Pragma("unroll") for (int k = 0; k < 2; ++k) dst[m][k] = *(const PG8_LAS bf16x8*)(lds + PG8_SA(b, h) + aoff + m * 2048 + k * 1024); } while (0)
; #define PG8_MMA(ai, bj, At, Bt) do { __builtin_amdgcn_s_setprio(1); _Pragma("unroll") for (int m = 0; m < 4; ++m) _Pragma("unroll") for (int n = 0; n < 2; ++n) _Pragma("unroll") for (int k = 0; k < 2; ++k) \
;         acc[ai][bj][m][n] = __builtin_amdgcn_mfma_f32_16x16x32_bf16(Bt[n][k], At[m][k], acc[ai][bj][m][n], 0, 0, 0); __builtin_amdgcn_s_setprio(0); } while (0)
; #define PG8_WAIT_V(n) asm volatile("s_waitcnt vmcnt(" #n ")" ::: "memory")
; #define PG8_WAIT_L(n) asm volatile("s_waitcnt lgkmcnt(" #n ")" ::: "memory")
; #define PG8_BAR __builtin_amdgcn_s_barrier()
; #define PG8_SCHED __builtin_amdgcn_sched_barrier(0)
; template <class Epi, class Sched, bool ALIGN_EPI = false, bool SP2 = false>
; __device__ __forceinline__ void gemm_phase(PG8_LAS unsigned char* lds, const Gemm g, const Sched& S, const Epi& E) {
;     ...
;         for (int t = 0; t < nt; t += 2) {
;             const bool last = (t == nt - 2);
;             const char* a1 = cA + (size_t)(t + 1) * kstep;
;             const char* a2 = last ? nA : cA + (size_t)(t + 2) * kstep; const char* b2 = last ? nB : cB + (size_t)(t + 2) * kstep;
;             const char* a3 = a2 + kstep; const char* b3 = b2 + kstep;
;     ...
;             PG8_LDA(At, 1, 1); PG8_STAGE(PG8_SB(1, 0), b3, voffB); PG8_STAGE(PG8_SB(1, 1), b3 + hstep, voffB); PG8_STAGE(PG8_SA(1, 0), a3, voffA);
;             PG8_WAIT_V(8); PG8_WAIT_L(0); PG8_BAR; PG8_MMA(1, 0, At, B0); PG8_MMA(1, 1, At, B1); PG8_BAR; PG8_SCHED;
	s_add_i32 s42, s77, s57
	v_lshl_add_u64 v[142:143], v[142:143], 0, s[8:9]
	s_mov_b32 m0, s42
	ds_read_b128 v[196:199], v162 offset:49152
	ds_read_b128 v[200:203], v162 offset:50176
	ds_read_b128 v[208:211], v162 offset:51200
	ds_read_b128 v[212:215], v162 offset:52224
	ds_read_b128 v[216:219], v162 offset:53248
	ds_read_b128 v[220:223], v162 offset:54272
	ds_read_b128 v[224:227], v162 offset:55296
	ds_read_b128 v[228:231], v162 offset:56320
	global_load_lds_dwordx4 v[142:143], off
	s_add_i32 m0, s42, 0x2000
	s_add_u32 s40, s40, 0x40080
	v_lshl_add_u64 v[142:143], v[204:205], 0, s[8:9]
	s_addc_u32 s41, s41, 0
	s_add_i32 s42, s78, s57
	global_load_lds_dwordx4 v[142:143], off
	v_lshl_add_u64 v[142:143], s[40:41], 0, v[130:131]
	s_mov_b32 m0, s42
	s_nop 0
	global_load_lds_dwordx4 v[142:143], off
	v_lshl_add_u64 v[142:143], s[40:41], 0, v[134:135]
	s_add_i32 m0, s42, 0x2000
	s_nop 0
	global_load_lds_dwordx4 v[142:143], off
	v_lshl_add_u64 v[142:143], v[232:233], 0, s[8:9]
	s_mov_b32 m0, s65
	s_nop 0
	global_load_lds_dwordx4 v[142:143], off
	v_lshl_add_u64 v[142:143], v[234:235], 0, s[8:9]
	s_mov_b32 m0, s66
	s_nop 0
	global_load_lds_dwordx4 v[142:143], off
	s_waitcnt vmcnt(8)
	s_waitcnt lgkmcnt(0)
	s_barrier
	s_setprio 1
	s_waitcnt lgkmcnt(0)
	v_mfma_f32_16x16x32_bf16 v[60:63], v[164:167], v[196:199], v[60:63]
	v_mfma_f32_16x16x32_bf16 v[56:59], v[172:175], v[196:199], v[56:59]
	v_mfma_f32_16x16x32_bf16 v[44:47], v[164:167], v[208:211], v[44:47]
	v_mfma_f32_16x16x32_bf16 v[40:43], v[172:175], v[208:211], v[40:43]
	v_mfma_f32_16x16x32_bf16 v[28:31], v[164:167], v[216:219], v[28:31]
	v_mfma_f32_16x16x32_bf16 v[24:27], v[172:175], v[216:219], v[24:27]
	v_mfma_f32_16x16x32_bf16 v[12:15], v[164:167], v[224:227], v[12:15]
	v_mfma_f32_16x16x32_bf16 v[8:11], v[172:175], v[224:227], v[8:11]
	v_mfma_f32_16x16x32_bf16 v[60:63], v[168:171], v[200:203], v[60:63]
	v_mfma_f32_16x16x32_bf16 v[56:59], v[176:179], v[200:203], v[56:59]
	v_mfma_f32_16x16x32_bf16 v[44:47], v[168:171], v[212:215], v[44:47]
	v_mfma_f32_16x16x32_bf16 v[40:43], v[176:179], v[212:215], v[40:43]
	v_mfma_f32_16x16x32_bf16 v[28:31], v[168:171], v[220:223], v[28:31]
	v_mfma_f32_16x16x32_bf16 v[24:27], v[176:179], v[220:223], v[24:27]
	v_mfma_f32_16x16x32_bf16 v[12:15], v[168:171], v[228:231], v[12:15]
	v_mfma_f32_16x16x32_bf16 v[8:11], v[176:179], v[228:231], v[8:11]
	v_mfma_f32_16x16x32_bf16 v[52:55], v[180:183], v[196:199], v[52:55]
	v_mfma_f32_16x16x32_bf16 v[48:51], v[188:191], v[196:199], v[48:51]
	v_mfma_f32_16x16x32_bf16 v[36:39], v[180:183], v[208:211], v[36:39]
	v_mfma_f32_16x16x32_bf16 v[32:35], v[188:191], v[208:211], v[32:35]
	v_mfma_f32_16x16x32_bf16 v[20:23], v[180:183], v[216:219], v[20:23]
	v_mfma_f32_16x16x32_bf16 v[16:19], v[188:191], v[216:219], v[16:19]
	v_mfma_f32_16x16x32_bf16 v[4:7], v[180:183], v[224:227], v[4:7]
	v_mfma_f32_16x16x32_bf16 v[0:3], v[188:191], v[224:227], v[0:3]
	v_mfma_f32_16x16x32_bf16 v[52:55], v[184:187], v[200:203], v[52:55]
	v_mfma_f32_16x16x32_bf16 v[48:51], v[192:195], v[200:203], v[48:51]
	v_mfma_f32_16x16x32_bf16 v[36:39], v[184:187], v[212:215], v[36:39]
	v_mfma_f32_16x16x32_bf16 v[32:35], v[192:195], v[212:215], v[32:35]
	v_mfma_f32_16x16x32_bf16 v[20:23], v[184:187], v[220:223], v[20:23]
	v_mfma_f32_16x16x32_bf16 v[16:19], v[192:195], v[220:223], v[16:19]
	v_mfma_f32_16x16x32_bf16 v[4:7], v[184:187], v[228:231], v[4:7]
	v_mfma_f32_16x16x32_bf16 v[0:3], v[192:195], v[228:231], v[0:3]
	s_setprio 0
	s_barrier
	s_add_i32 s76, s76, 2
	s_add_u32 s38, s38, 0x100
	s_addc_u32 s39, s39, 0
	s_add_u32 s74, s74, 0x100
	s_addc_u32 s75, s75, 0
	s_cmp_gt_u32 s76, 13
	s_cbranch_scc0 .LBB0_877

;     __device__ __forceinline__ bool next(int i, Unit& u) const { if (i != 0) return false; const int c0 = (G >= 8) ? G - 5 : G - 2; int k = -1; if (c == c0) k = 0; else if (c == G - 1) k = 1; if (k < 0 || k >= n) return false; u.pm = k; u.pn = 0; return true; }
; #define PG8_STAGE(bufoff, gbase, voff) do { _Pragma("unroll") for (int _i = 0; _i < 2; ++_i) \
;         __builtin_amdgcn_global_load_lds((const unsigned*)((const char*)(gbase) + (voff)[_i]), (PG8_LAS unsigned*)(lds + (bufoff) + ldsw + _i * 8192), 16, 0, 0); } while (0)
; #define PG8_WAIT_V(n) asm volatile("s_waitcnt vmcnt(" #n ")" ::: "memory")
; template <class Epi, class Sched, bool ALIGN_EPI = false, bool SP2 = false>
; __device__ __forceinline__ void gemm_phase(PG8_LAS unsigned char* lds, const Gemm g, const Sched& S, const Epi& E) {
;     ...
;         PG8_WAIT_V(2); PG8_BAR;
;         PG8_STAGE(PG8_SB(1, 0), cB + kstep, voffB); PG8_STAGE(PG8_SA(1, 0), cA + kstep, voffA); PG8_STAGE(PG8_SB(1, 1), cB + hstep + kstep, voffB);
;         PG8_WAIT_V(6); PG8_BAR;
;     } else {
;         PG8_STAGE(PG8_SB(0, 0), cB, voffB); PG8_STAGE(PG8_SA(0, 0), cA, voffA); PG8_STAGE(PG8_SB(0, 1), cB + hstep, voffB); PG8_STAGE(PG8_SA(0, 1), cA + hstep, voffA);
;         if (wr == 1) PG8_BAR;
;         PG8_WAIT_V(4); PG8_BAR;
;         PG8_STAGE(PG8_SB(1, 0), cB + kstep, voffB); PG8_STAGE(PG8_SA(1, 0), cA + kstep, voffA); PG8_STAGE(PG8_SB(1, 1), cB + hstep + kstep, voffB);
;         PG8_WAIT_V(6); PG8_BAR;
;     }
;     for (;;) {
;         const bool has_next = S.next(ui + 1, nxt);
;         const char* nA = has_next ? (const char*)g.A + (size_t)nxt.pm * tstep : cA; const char* nB = has_next ? (const char*)g.Bt + (size_t)nxt.pn * tstep : cB;
;         for (int t = 0; t < nt; t += 2) {
;             const bool last = (t == nt - 2);
;             const char* a1 = cA + (size_t)(t + 1) * kstep;
;             const char* a2 = last ? nA : cA + (size_t)(t + 2) * kstep; const char* b2 = last ? nB : cB + (size_t)(t + 2) * kstep;
;             const char* a3 = a2 + kstep; const char* b3 = b2 + kstep;
;             if (last && has_next) S.a_ready(nxt);
;             if constexpr (SP2) {
;             PG8_LDB(B0, 0, 0); PG8_LDB(B1, 0, 1); PG8_SCHED; PG8_LDA(At, 0, 0); PG8_STAGE(PG8_SA(1, 1), a1 + hstep, voffA);
;             PG8_WAIT_V(8); PG8_WAIT_L(0); PG8_BAR; PG8_MMA(0, 0, At, B0); PG8_MMA(0, 1, At, B1); PG8_BAR; PG8_SCHED;
.LBB0_965:
	v_lshlrev_b32_e32 v11, 2, v153
	v_lshl_or_b32 v129, s19, 6, v153
	v_lshl_or_b32 v10, v153, 6, v154
	s_lshl_b32 s19, s19, 13
	v_and_b32_e32 v11, 32, v11
	s_lshl_b32 s18, s18, 5
	v_bitop3_b32 v10, v10, s19, v11 bitop3:0xde
	s_and_b32 s39, s18, 0x60
	s_mov_b64 s[18:19], 0x80
	s_add_i32 m0, s29, 0x18000
	v_lshl_add_u64 v[6:7], v[6:7], 0, s[18:19]
	s_waitcnt vmcnt(2)
	s_barrier
	global_load_lds_dwordx4 v[6:7], off
	v_lshl_add_u64 v[4:5], v[4:5], 0, s[18:19]
	s_add_i32 m0, s29, 0x1a000
	s_add_i32 s40, s29, 0x8000
	s_add_i32 s41, s29, 0xa000
	global_load_lds_dwordx4 v[4:5], off
	v_lshl_add_u64 v[2:3], v[2:3], 0, s[18:19]
	s_mov_b32 m0, s40
	s_add_u32 s24, s6, 0xb0080
	global_load_lds_dwordx4 v[2:3], off
	v_lshl_add_u64 v[0:1], v[0:1], 0, s[18:19]
	s_mov_b32 m0, s41
	s_addc_u32 s25, s7, 0
	global_load_lds_dwordx4 v[0:1], off
	s_add_i32 m0, s29, 0x1c000
	v_lshl_add_u64 v[0:1], s[24:25], 0, v[138:139]
	global_load_lds_dwordx4 v[0:1], off
	v_lshl_add_u64 v[0:1], s[24:25], 0, v[142:143]
	s_add_i32 m0, s29, 0x1e000
	s_add_u32 s24, s50, s21
	global_load_lds_dwordx4 v[0:1], off
	v_add_u16_e32 v0, v148, v149
	v_lshrrev_b16_e32 v2, 1, v0
	v_lshl_or_b32 v11, s39, 7, v155
	s_waitcnt vmcnt(6)
	v_add_lshl_u32 v0, v9, v2, 1
	v_mov_b32_e32 v1, v139
	s_addc_u32 s25, s51, s20
	s_add_i32 s58, 0, 0x10000
	s_add_i32 s60, 0, 0x14000
	s_add_i32 s64, 0, 0x18000
	s_add_i32 s66, 0, 0x1c000
	v_lshl_add_u64 v[144:145], s[24:25], 0, v[0:1]
	v_add_lshl_u32 v0, v8, v2, 1
	v_add_u32_e32 v131, s58, v11
	v_add_u32_e32 v133, s60, v11
	s_add_i32 s58, s58, s22
	s_add_i32 s60, s60, s22
	v_add_u32_e32 v156, s64, v11
	v_add_u32_e32 v157, s66, v11
	s_add_i32 s64, s64, s22
	s_add_i32 s66, s66, s22
	v_lshl_add_u64 v[146:147], s[24:25], 0, v[0:1]
	s_mov_b32 s42, -2
	s_mov_b64 s[20:21], 0x78b0080
	v_add_u32_e32 v135, 0, v10
	s_add_i32 s43, s29, 0xc000
	s_add_i32 s57, s29, 0xe000
	s_add_i32 s59, s58, 0x2000
	s_add_i32 s61, s60, 0x2000
	s_add_i32 s65, s64, 0x2000
	s_add_i32 s67, s66, 0x2000
	s_barrier
	ds_read_b128 v[158:161], v131
	ds_read_b128 v[162:165], v131 offset:1024
	ds_read_b128 v[166:169], v131 offset:2048
	ds_read_b128 v[170:173], v131 offset:3072
	ds_read_b128 v[174:177], v133
	ds_read_b128 v[178:181], v133 offset:1024
	ds_read_b128 v[182:185], v133 offset:2048
	ds_read_b128 v[186:189], v133 offset:3072
	s_add_u32 s22, s20, 0xf8750080
	s_addc_u32 s23, s21, -1
	s_cmp_lg_u32 s42, 40
	s_cselect_b32 s22, s22, 0
	s_cselect_b32 s23, s23, 0
	s_add_u32 s24, s8, s22
	s_addc_u32 s25, s9, s23
	s_add_u32 s22, s6, s22
	s_addc_u32 s23, s7, s23
	s_mov_b32 m0, s43
	v_lshl_add_u64 v[224:225], v[144:145], 0, s[20:21]
	ds_read_b128 v[190:193], v135
	ds_read_b128 v[194:197], v135 offset:1024
	ds_read_b128 v[198:201], v135 offset:2048
	ds_read_b128 v[202:205], v135 offset:3072
	ds_read_b128 v[208:211], v135 offset:4096
	ds_read_b128 v[212:215], v135 offset:5120
	ds_read_b128 v[216:219], v135 offset:6144
	ds_read_b128 v[220:223], v135 offset:7168
	global_load_lds_dwordx4 v[224:225], off
	v_lshl_add_u64 v[224:225], v[146:147], 0, s[20:21]
	s_mov_b32 m0, s57
	s_nop 0
	global_load_lds_dwordx4 v[224:225], off
	s_waitcnt vmcnt(8)
	s_waitcnt lgkmcnt(0)
	s_barrier
	s_setprio 1
	s_waitcnt lgkmcnt(0)
	v_mfma_f32_16x16x32_bf16 v[124:127], v[158:161], v[190:193], 0
	v_mfma_f32_16x16x32_bf16 v[120:123], v[166:169], v[190:193], 0
	v_mfma_f32_16x16x32_bf16 v[116:119], v[158:161], v[198:201], 0
	v_mfma_f32_16x16x32_bf16 v[112:115], v[166:169], v[198:201], 0
	v_mfma_f32_16x16x32_bf16 v[100:103], v[158:161], v[208:211], 0
	v_mfma_f32_16x16x32_bf16 v[96:99], v[166:169], v[208:211], 0
	v_mfma_f32_16x16x32_bf16 v[84:87], v[158:161], v[216:219], 0
	v_mfma_f32_16x16x32_bf16 v[80:83], v[166:169], v[216:219], 0
	v_mfma_f32_16x16x32_bf16 v[124:127], v[162:165], v[194:197], v[124:127]
	v_mfma_f32_16x16x32_bf16 v[120:123], v[170:173], v[194:197], v[120:123]
	v_mfma_f32_16x16x32_bf16 v[116:119], v[162:165], v[202:205], v[116:119]
	v_mfma_f32_16x16x32_bf16 v[112:115], v[170:173], v[202:205], v[112:115]
	v_mfma_f32_16x16x32_bf16 v[100:103], v[162:165], v[212:215], v[100:103]
	v_mfma_f32_16x16x32_bf16 v[96:99], v[170:173], v[212:215], v[96:99]
	v_mfma_f32_16x16x32_bf16 v[84:87], v[162:165], v[220:223], v[84:87]
	v_mfma_f32_16x16x32_bf16 v[80:83], v[170:173], v[220:223], v[80:83]
	v_mfma_f32_16x16x32_bf16 v[108:111], v[174:177], v[190:193], 0
	v_mfma_f32_16x16x32_bf16 v[104:107], v[182:185], v[190:193], 0
	v_mfma_f32_16x16x32_bf16 v[92:95], v[174:177], v[198:201], 0
	v_mfma_f32_16x16x32_bf16 v[88:91], v[182:185], v[198:201], 0
	v_mfma_f32_16x16x32_bf16 v[76:79], v[174:177], v[208:211], 0
	v_mfma_f32_16x16x32_bf16 v[72:75], v[182:185], v[208:211], 0
	v_mfma_f32_16x16x32_bf16 v[68:71], v[174:177], v[216:219], 0
	v_mfma_f32_16x16x32_bf16 v[64:67], v[182:185], v[216:219], 0
	v_mfma_f32_16x16x32_bf16 v[108:111], v[178:181], v[194:197], v[108:111]
	v_mfma_f32_16x16x32_bf16 v[104:107], v[186:189], v[194:197], v[104:107]
	v_mfma_f32_16x16x32_bf16 v[92:95], v[178:181], v[202:205], v[92:95]
	v_mfma_f32_16x16x32_bf16 v[88:91], v[186:189], v[202:205], v[88:91]
	v_mfma_f32_16x16x32_bf16 v[76:79], v[178:181], v[212:215], v[76:79]
	v_mfma_f32_16x16x32_bf16 v[72:75], v[186:189], v[212:215], v[72:75]
	v_mfma_f32_16x16x32_bf16 v[68:71], v[178:181], v[220:223], v[68:71]
	v_mfma_f32_16x16x32_bf16 v[64:67], v[186:189], v[220:223], v[64:67]
	s_setprio 0
	s_barrier
; #define PG8_STAGE(bufoff, gbase, voff) do { _Pragma("unroll") for (int _i = 0; _i < 2; ++_i) \
;         __builtin_amdgcn_global_load_lds((const unsigned*)((const char*)(gbase) + (voff)[_i]), (PG8_LAS unsigned*)(lds + (bufoff) + ldsw + _i * 8192), 16, 0, 0); } while (0)
; #define PG8_LDA(dst, b, h) do { _Pragma("unroll") for (int m = 0; m < 4; ++m) _Pragma("unroll") for (int k = 0; k < 2; ++k) dst[m][k] = *(const PG8_LAS bf16x8*)(lds + PG8_SA(b, h) + aoff + m * 2048 + k * 1024); } while (0)
; #define PG8_LDB(dst, b, h) do { _Pragma("unroll") for (int n = 0; n < 2; ++n) _Pragma("unroll") for (int k = 0; k < 2; ++k) dst[n][k] = *(const PG8_LAS bf16x8*)(lds + PG8_SB(b, h) + boff + n * 2048 + k * 1024); } while (0)
; #define PG8_MMA(ai, bj, At, Bt) do { __builtin_amdgcn_s_setprio(1); _Pragma("unroll") for (int m = 0; m < 4; ++m) _Pragma("unroll") for (int n = 0; n < 2; ++n) _Pragma("unroll") for (int k = 0; k < 2; ++k) \
;         acc[ai][bj][m][n] = __builtin_amdgcn_mfma_f32_16x16x32_bf16(Bt[n][k], At[m][k], acc[ai][bj][m][n], 0, 0, 0); __builtin_amdgcn_s_setprio(0); } while (0)
; #define PG8_WAIT_V(n) asm volatile("s_waitcnt vmcnt(" #n ")" ::: "memory")
; #define PG8_WAIT_L(n) asm volatile("s_waitcnt lgkmcnt(" #n ")" ::: "memory")
; #define PG8_BAR __builtin_amdgcn_s_barrier()
; #define PG8_SCHED __builtin_amdgcn_sched_barrier(0)
; template <class Epi, class Sched, bool ALIGN_EPI = false, bool SP2 = false>
; __device__ __forceinline__ void gemm_phase(PG8_LAS unsigned char* lds, const Gemm g, const Sched& S, const Epi& E) {
;     ...
;             PG8_LDA(At, 0, 1); PG8_STAGE(PG8_SB(0, 0), b2, voffB); PG8_STAGE(PG8_SB(0, 1), b2 + hstep, voffB); PG8_STAGE(PG8_SA(0, 0), a2, voffA);
;             PG8_WAIT_V(8); PG8_WAIT_L(0); PG8_BAR; PG8_MMA(1, 0, At, B0); PG8_MMA(1, 1, At, B1); PG8_BAR; PG8_SCHED;
;             PG8_LDB(B0, 1, 0); PG8_LDB(B1, 1, 1); PG8_SCHED; PG8_LDA(At, 1, 0); PG8_STAGE(PG8_SA(0, 1), a2 + hstep, voffA);
;             PG8_WAIT_V(8); PG8_WAIT_L(0); PG8_BAR; PG8_MMA(0, 0, At, B0); PG8_MMA(0, 1, At, B1); PG8_BAR; PG8_SCHED;
	s_mov_b32 m0, s58
	v_lshl_add_u64 v[224:225], s[22:23], 0, v[138:139]
	s_add_u32 s68, s22, 0xb0000
	ds_read_b128 v[190:193], v135 offset:16384
	ds_read_b128 v[194:197], v135 offset:17408
	ds_read_b128 v[198:201], v135 offset:18432
	ds_read_b128 v[202:205], v135 offset:19456
	ds_read_b128 v[208:211], v135 offset:20480
	ds_read_b128 v[212:215], v135 offset:21504
	ds_read_b128 v[216:219], v135 offset:22528
	ds_read_b128 v[220:223], v135 offset:23552
	global_load_lds_dwordx4 v[224:225], off
	v_lshl_add_u64 v[226:227], s[22:23], 0, v[142:143]
	s_mov_b32 m0, s59
	s_addc_u32 s69, s23, 0
	global_load_lds_dwordx4 v[226:227], off
	v_lshl_add_u64 v[228:229], s[68:69], 0, v[138:139]
	s_mov_b32 m0, s60
	v_lshl_add_u64 v[230:231], s[24:25], 0, v[140:141]
	global_load_lds_dwordx4 v[228:229], off
	v_lshl_add_u64 v[228:229], s[68:69], 0, v[142:143]
	s_mov_b32 m0, s61
	s_nop 0
	global_load_lds_dwordx4 v[228:229], off
	v_lshl_add_u64 v[228:229], s[24:25], 0, v[136:137]
	s_mov_b32 m0, s29
	s_nop 0
	global_load_lds_dwordx4 v[228:229], off
	s_mov_b32 m0, s30
	s_nop 0
	global_load_lds_dwordx4 v[230:231], off
	s_waitcnt vmcnt(8)
	s_waitcnt lgkmcnt(0)
	s_barrier
	s_setprio 1
	s_waitcnt lgkmcnt(0)
	v_mfma_f32_16x16x32_bf16 v[60:63], v[158:161], v[190:193], 0
	v_mfma_f32_16x16x32_bf16 v[56:59], v[166:169], v[190:193], 0
	v_mfma_f32_16x16x32_bf16 v[52:55], v[158:161], v[198:201], 0
	v_mfma_f32_16x16x32_bf16 v[48:51], v[166:169], v[198:201], 0
	v_mfma_f32_16x16x32_bf16 v[36:39], v[158:161], v[208:211], 0
	v_mfma_f32_16x16x32_bf16 v[32:35], v[166:169], v[208:211], 0
	v_mfma_f32_16x16x32_bf16 v[20:23], v[158:161], v[216:219], 0
	v_mfma_f32_16x16x32_bf16 v[16:19], v[166:169], v[216:219], 0
	v_mfma_f32_16x16x32_bf16 v[60:63], v[162:165], v[194:197], v[60:63]
	v_mfma_f32_16x16x32_bf16 v[56:59], v[170:173], v[194:197], v[56:59]
	v_mfma_f32_16x16x32_bf16 v[52:55], v[162:165], v[202:205], v[52:55]
	v_mfma_f32_16x16x32_bf16 v[48:51], v[170:173], v[202:205], v[48:51]
	v_mfma_f32_16x16x32_bf16 v[36:39], v[162:165], v[212:215], v[36:39]
	v_mfma_f32_16x16x32_bf16 v[32:35], v[170:173], v[212:215], v[32:35]
	v_mfma_f32_16x16x32_bf16 v[20:23], v[162:165], v[220:223], v[20:23]
	v_mfma_f32_16x16x32_bf16 v[16:19], v[170:173], v[220:223], v[16:19]
	v_mfma_f32_16x16x32_bf16 v[44:47], v[174:177], v[190:193], 0
	v_mfma_f32_16x16x32_bf16 v[40:43], v[182:185], v[190:193], 0
	v_mfma_f32_16x16x32_bf16 v[28:31], v[174:177], v[198:201], 0
	v_mfma_f32_16x16x32_bf16 v[24:27], v[182:185], v[198:201], 0
	v_mfma_f32_16x16x32_bf16 v[12:15], v[174:177], v[208:211], 0
	v_mfma_f32_16x16x32_bf16 v[8:11], v[182:185], v[208:211], 0
	v_mfma_f32_16x16x32_bf16 v[4:7], v[174:177], v[216:219], 0
	v_mfma_f32_16x16x32_bf16 v[0:3], v[182:185], v[216:219], 0
	v_mfma_f32_16x16x32_bf16 v[44:47], v[178:181], v[194:197], v[44:47]
	v_mfma_f32_16x16x32_bf16 v[40:43], v[186:189], v[194:197], v[40:43]
	v_mfma_f32_16x16x32_bf16 v[28:31], v[178:181], v[202:205], v[28:31]
	v_mfma_f32_16x16x32_bf16 v[24:27], v[186:189], v[202:205], v[24:27]
	v_mfma_f32_16x16x32_bf16 v[12:15], v[178:181], v[212:215], v[12:15]
	v_mfma_f32_16x16x32_bf16 v[8:11], v[186:189], v[212:215], v[8:11]
	v_mfma_f32_16x16x32_bf16 v[4:7], v[178:181], v[220:223], v[4:7]
	v_mfma_f32_16x16x32_bf16 v[0:3], v[186:189], v[220:223], v[0:3]
	s_setprio 0
	s_barrier
	ds_read_b128 v[158:161], v156
	ds_read_b128 v[162:165], v156 offset:1024
	ds_read_b128 v[166:169], v156 offset:2048
	ds_read_b128 v[170:173], v156 offset:3072
	ds_read_b128 v[174:177], v157
	ds_read_b128 v[178:181], v157 offset:1024
	ds_read_b128 v[182:185], v157 offset:2048
	ds_read_b128 v[186:189], v157 offset:3072
	s_add_u32 s24, s24, 0xb0000
	s_addc_u32 s25, s25, 0
	s_mov_b32 m0, s31
	v_lshl_add_u64 v[232:233], s[24:25], 0, v[136:137]
	ds_read_b128 v[190:193], v135 offset:32768
	ds_read_b128 v[194:197], v135 offset:33792
	ds_read_b128 v[198:201], v135 offset:34816
	ds_read_b128 v[202:205], v135 offset:35840
	ds_read_b128 v[208:211], v135 offset:36864
	ds_read_b128 v[212:215], v135 offset:37888
	ds_read_b128 v[216:219], v135 offset:38912
	ds_read_b128 v[220:223], v135 offset:39936
	global_load_lds_dwordx4 v[232:233], off
	v_lshl_add_u64 v[232:233], s[24:25], 0, v[140:141]
	s_mov_b32 m0, s38
	s_nop 0
	global_load_lds_dwordx4 v[232:233], off
	s_waitcnt vmcnt(8)
	s_waitcnt lgkmcnt(0)
	s_barrier
	s_setprio 1
	s_waitcnt lgkmcnt(0)
	v_mfma_f32_16x16x32_bf16 v[124:127], v[158:161], v[190:193], v[124:127]
	v_mfma_f32_16x16x32_bf16 v[120:123], v[166:169], v[190:193], v[120:123]
	v_mfma_f32_16x16x32_bf16 v[116:119], v[158:161], v[198:201], v[116:119]
	v_mfma_f32_16x16x32_bf16 v[112:115], v[166:169], v[198:201], v[112:115]
	v_mfma_f32_16x16x32_bf16 v[100:103], v[158:161], v[208:211], v[100:103]
	v_mfma_f32_16x16x32_bf16 v[96:99], v[166:169], v[208:211], v[96:99]
	v_mfma_f32_16x16x32_bf16 v[84:87], v[158:161], v[216:219], v[84:87]
	v_mfma_f32_16x16x32_bf16 v[80:83], v[166:169], v[216:219], v[80:83]
	v_mfma_f32_16x16x32_bf16 v[124:127], v[162:165], v[194:197], v[124:127]
	v_mfma_f32_16x16x32_bf16 v[120:123], v[170:173], v[194:197], v[120:123]
	v_mfma_f32_16x16x32_bf16 v[116:119], v[162:165], v[202:205], v[116:119]
	v_mfma_f32_16x16x32_bf16 v[112:115], v[170:173], v[202:205], v[112:115]
	v_mfma_f32_16x16x32_bf16 v[100:103], v[162:165], v[212:215], v[100:103]
	v_mfma_f32_16x16x32_bf16 v[96:99], v[170:173], v[212:215], v[96:99]
	v_mfma_f32_16x16x32_bf16 v[84:87], v[162:165], v[220:223], v[84:87]
	v_mfma_f32_16x16x32_bf16 v[80:83], v[170:173], v[220:223], v[80:83]
	v_mfma_f32_16x16x32_bf16 v[108:111], v[174:177], v[190:193], v[108:111]
	v_mfma_f32_16x16x32_bf16 v[104:107], v[182:185], v[190:193], v[104:107]
	v_mfma_f32_16x16x32_bf16 v[92:95], v[174:177], v[198:201], v[92:95]
	v_mfma_f32_16x16x32_bf16 v[88:91], v[182:185], v[198:201], v[88:91]
	v_mfma_f32_16x16x32_bf16 v[76:79], v[174:177], v[208:211], v[76:79]
	v_mfma_f32_16x16x32_bf16 v[72:75], v[182:185], v[208:211], v[72:75]
	v_mfma_f32_16x16x32_bf16 v[68:71], v[174:177], v[216:219], v[68:71]
	v_mfma_f32_16x16x32_bf16 v[64:67], v[182:185], v[216:219], v[64:67]
	v_mfma_f32_16x16x32_bf16 v[108:111], v[178:181], v[194:197], v[108:111]
	v_mfma_f32_16x16x32_bf16 v[104:107], v[186:189], v[194:197], v[104:107]
	v_mfma_f32_16x16x32_bf16 v[92:95], v[178:181], v[202:205], v[92:95]
	v_mfma_f32_16x16x32_bf16 v[88:91], v[186:189], v[202:205], v[88:91]
	v_mfma_f32_16x16x32_bf16 v[76:79], v[178:181], v[212:215], v[76:79]
	v_mfma_f32_16x16x32_bf16 v[72:75], v[186:189], v[212:215], v[72:75]
	v_mfma_f32_16x16x32_bf16 v[68:71], v[178:181], v[220:223], v[68:71]
	v_mfma_f32_16x16x32_bf16 v[64:67], v[186:189], v[220:223], v[64:67]
	s_setprio 0
	s_barrier
; #define PG8_STAGE(bufoff, gbase, voff) do { _Pragma("unroll") for (int _i = 0; _i < 2; ++_i) \
;         __builtin_amdgcn_global_load_lds((const unsigned*)((const char*)(gbase) + (voff)[_i]), (PG8_LAS unsigned*)(lds + (bufoff) + ldsw + _i * 8192), 16, 0, 0); } while (0)
; #define PG8_LDA(dst, b, h) do { _Pragma("unroll") for (int m = 0; m < 4; ++m) _Pragma("unroll") for (int k = 0; k < 2; ++k) dst[m][k] = *(const PG8_LAS bf16x8*)(lds + PG8_SA(b, h) + aoff + m * 2048 + k * 1024); } while (0)
; #define PG8_LDB(dst, b, h) do { _Pragma("unroll") for (int n = 0; n < 2; ++n) _Pragma("unroll") for (int k = 0; k < 2; ++k) dst[n][k] = *(const PG8_LAS bf16x8*)(lds + PG8_SB(b, h) + boff + n * 2048 + k * 1024); } while (0)
; #define PG8_MMA(ai, bj, At, Bt) do { __builtin_amdgcn_s_setprio(1); _Pragma("unroll") for (int m = 0; m < 4; ++m) _Pragma("unroll") for (int n = 0; n < 2; ++n) _Pragma("unroll") for (int k = 0; k < 2; ++k) \
;         acc[ai][bj][m][n] = __builtin_amdgcn_mfma_f32_16x16x32_bf16(Bt[n][k], At[m][k], acc[ai][bj][m][n], 0, 0, 0); __builtin_amdgcn_s_setprio(0); } while (0)
; #define PG8_WAIT_V(n) asm volatile("s_waitcnt vmcnt(" #n ")" ::: "memory")
; #define PG8_WAIT_L(n) asm volatile("s_waitcnt lgkmcnt(" #n ")" ::: "memory")
; #define PG8_BAR __builtin_amdgcn_s_barrier()
; #define PG8_SCHED __builtin_amdgcn_sched_barrier(0)
; template <class Epi, class Sched, bool ALIGN_EPI = false, bool SP2 = false>
; __device__ __forceinline__ void gemm_phase(PG8_LAS unsigned char* lds, const Gemm g, const Sched& S, const Epi& E) {
;     ...
;             PG8_LDB(B0, 0, 0); PG8_LDB(B1, 0, 1); PG8_SCHED; PG8_LDA(At, 0, 0); PG8_STAGE(PG8_SA(1, 1), a1 + hstep, voffA);
;             PG8_WAIT_V(8); PG8_WAIT_L(0); PG8_BAR; PG8_MMA(0, 0, At, B0); PG8_MMA(0, 1, At, B1); PG8_BAR; PG8_SCHED;
;     ...
;             PG8_LDA(At, 1, 1); PG8_STAGE(PG8_SB(1, 0), b3, voffB); PG8_STAGE(PG8_SB(1, 1), b3 + hstep, voffB); PG8_STAGE(PG8_SA(1, 0), a3, voffA);
;             PG8_WAIT_V(8); PG8_WAIT_L(0); PG8_BAR; PG8_MMA(1, 0, At, B0); PG8_MMA(1, 1, At, B1); PG8_BAR; PG8_SCHED;
	s_mov_b32 m0, s64
	v_lshl_add_u64 v[224:225], v[224:225], 0, s[18:19]
	s_add_u32 s22, s22, 0xb0080
	ds_read_b128 v[190:193], v135 offset:49152
	ds_read_b128 v[194:197], v135 offset:50176
	ds_read_b128 v[198:201], v135 offset:51200
	ds_read_b128 v[202:205], v135 offset:52224
	ds_read_b128 v[208:211], v135 offset:53248
	ds_read_b128 v[212:215], v135 offset:54272
	ds_read_b128 v[216:219], v135 offset:55296
	ds_read_b128 v[220:223], v135 offset:56320
	global_load_lds_dwordx4 v[224:225], off
	v_lshl_add_u64 v[224:225], v[226:227], 0, s[18:19]
	s_mov_b32 m0, s65
	s_addc_u32 s23, s23, 0
	global_load_lds_dwordx4 v[224:225], off
	v_lshl_add_u64 v[224:225], s[22:23], 0, v[138:139]
	s_mov_b32 m0, s66
	s_nop 0
	global_load_lds_dwordx4 v[224:225], off
	v_lshl_add_u64 v[224:225], s[22:23], 0, v[142:143]
	s_mov_b32 m0, s67
	s_nop 0
	global_load_lds_dwordx4 v[224:225], off
	v_lshl_add_u64 v[224:225], v[228:229], 0, s[18:19]
	s_mov_b32 m0, s40
	s_nop 0
	global_load_lds_dwordx4 v[224:225], off
	v_lshl_add_u64 v[224:225], v[230:231], 0, s[18:19]
	s_mov_b32 m0, s41
	s_nop 0
	global_load_lds_dwordx4 v[224:225], off
	s_waitcnt vmcnt(8)
	s_waitcnt lgkmcnt(0)
	s_barrier
	s_setprio 1
	s_waitcnt lgkmcnt(0)
	v_mfma_f32_16x16x32_bf16 v[60:63], v[158:161], v[190:193], v[60:63]
	v_mfma_f32_16x16x32_bf16 v[56:59], v[166:169], v[190:193], v[56:59]
	v_mfma_f32_16x16x32_bf16 v[52:55], v[158:161], v[198:201], v[52:55]
	v_mfma_f32_16x16x32_bf16 v[48:51], v[166:169], v[198:201], v[48:51]
	v_mfma_f32_16x16x32_bf16 v[36:39], v[158:161], v[208:211], v[36:39]
	v_mfma_f32_16x16x32_bf16 v[32:35], v[166:169], v[208:211], v[32:35]
	v_mfma_f32_16x16x32_bf16 v[20:23], v[158:161], v[216:219], v[20:23]
	v_mfma_f32_16x16x32_bf16 v[16:19], v[166:169], v[216:219], v[16:19]
	v_mfma_f32_16x16x32_bf16 v[60:63], v[162:165], v[194:197], v[60:63]
	v_mfma_f32_16x16x32_bf16 v[56:59], v[170:173], v[194:197], v[56:59]
	v_mfma_f32_16x16x32_bf16 v[52:55], v[162:165], v[202:205], v[52:55]
	v_mfma_f32_16x16x32_bf16 v[48:51], v[170:173], v[202:205], v[48:51]
	v_mfma_f32_16x16x32_bf16 v[36:39], v[162:165], v[212:215], v[36:39]
	v_mfma_f32_16x16x32_bf16 v[32:35], v[170:173], v[212:215], v[32:35]
	v_mfma_f32_16x16x32_bf16 v[20:23], v[162:165], v[220:223], v[20:23]
	v_mfma_f32_16x16x32_bf16 v[16:19], v[170:173], v[220:223], v[16:19]
	v_mfma_f32_16x16x32_bf16 v[44:47], v[174:177], v[190:193], v[44:47]
	v_mfma_f32_16x16x32_bf16 v[40:43], v[182:185], v[190:193], v[40:43]
	v_mfma_f32_16x16x32_bf16 v[28:31], v[174:177], v[198:201], v[28:31]
	v_mfma_f32_16x16x32_bf16 v[24:27], v[182:185], v[198:201], v[24:27]
	v_mfma_f32_16x16x32_bf16 v[12:15], v[174:177], v[208:211], v[12:15]
	v_mfma_f32_16x16x32_bf16 v[8:11], v[182:185], v[208:211], v[8:11]
	v_mfma_f32_16x16x32_bf16 v[4:7], v[174:177], v[216:219], v[4:7]
	v_mfma_f32_16x16x32_bf16 v[0:3], v[182:185], v[216:219], v[0:3]
	v_mfma_f32_16x16x32_bf16 v[44:47], v[178:181], v[194:197], v[44:47]
	v_mfma_f32_16x16x32_bf16 v[40:43], v[186:189], v[194:197], v[40:43]
	v_mfma_f32_16x16x32_bf16 v[28:31], v[178:181], v[202:205], v[28:31]
	v_mfma_f32_16x16x32_bf16 v[24:27], v[186:189], v[202:205], v[24:27]
	v_mfma_f32_16x16x32_bf16 v[12:15], v[178:181], v[212:215], v[12:15]
	v_mfma_f32_16x16x32_bf16 v[8:11], v[186:189], v[212:215], v[8:11]
	v_mfma_f32_16x16x32_bf16 v[4:7], v[178:181], v[220:223], v[4:7]
	v_mfma_f32_16x16x32_bf16 v[0:3], v[186:189], v[220:223], v[0:3]
	s_setprio 0
	s_barrier
	s_add_i32 s42, s42, 2
	s_add_u32 s20, s20, 0x100
	s_addc_u32 s21, s21, 0
	s_cmp_gt_u32 s42, 41
	s_cbranch_scc0 .LBB0_966
	s_branch .Lpeel_exit_6
.LBB0_966:
	ds_read_b128 v[158:161], v131
	ds_read_b128 v[162:165], v131 offset:1024
	ds_read_b128 v[166:169], v131 offset:2048
	ds_read_b128 v[170:173], v131 offset:3072
	ds_read_b128 v[174:177], v133
	ds_read_b128 v[178:181], v133 offset:1024
	ds_read_b128 v[182:185], v133 offset:2048
	ds_read_b128 v[186:189], v133 offset:3072
	s_add_u32 s22, s20, 0xf8750080
	s_addc_u32 s23, s21, -1
	s_cmp_lg_u32 s42, 40
	s_cselect_b32 s22, s22, 0
	s_cselect_b32 s23, s23, 0
	s_add_u32 s24, s8, s22
	s_addc_u32 s25, s9, s23
	s_add_u32 s22, s6, s22
	s_addc_u32 s23, s7, s23
	s_mov_b32 m0, s43
	v_lshl_add_u64 v[224:225], v[144:145], 0, s[20:21]
	ds_read_b128 v[190:193], v135
	ds_read_b128 v[194:197], v135 offset:1024
	ds_read_b128 v[198:201], v135 offset:2048
	ds_read_b128 v[202:205], v135 offset:3072
	ds_read_b128 v[208:211], v135 offset:4096
	ds_read_b128 v[212:215], v135 offset:5120
	ds_read_b128 v[216:219], v135 offset:6144
	ds_read_b128 v[220:223], v135 offset:7168
	global_load_lds_dwordx4 v[224:225], off
	v_lshl_add_u64 v[224:225], v[146:147], 0, s[20:21]
	s_mov_b32 m0, s57
	s_nop 0
	global_load_lds_dwordx4 v[224:225], off
	s_waitcnt vmcnt(8)
	s_waitcnt lgkmcnt(0)
	s_barrier
; #define PG8_STAGE(bufoff, gbase, voff) do { _Pragma("unroll") for (int _i = 0; _i < 2; ++_i) \
;         __builtin_amdgcn_global_load_lds((const unsigned*)((const char*)(gbase) + (voff)[_i]), (PG8_LAS unsigned*)(lds + (bufoff) + ldsw + _i * 8192), 16, 0, 0); } while (0)
; #define PG8_LDA(dst, b, h) do { _Pragma("unroll") for (int m = 0; m < 4; ++m) _Pragma("unroll") for (int k = 0; k < 2; ++k) dst[m][k] = *(const PG8_LAS bf16x8*)(lds + PG8_SA(b, h) + aoff + m * 2048 + k * 1024); } while (0)
; #define PG8_MMA(ai, bj, At, Bt) do { __builtin_amdgcn_s_setprio(1); _Pragma("unroll") for (int m = 0; m < 4; ++m) _Pragma("unroll") for (int n = 0; n < 2; ++n) _Pragma("unroll") for (int k = 0; k < 2; ++k) \
;         acc[ai][bj][m][n] = __builtin_amdgcn_mfma_f32_16x16x32_bf16(Bt[n][k], At[m][k], acc[ai][bj][m][n], 0, 0, 0); __builtin_amdgcn_s_setprio(0); } while (0)
; #define PG8_WAIT_V(n) asm volatile("s_waitcnt vmcnt(" #n ")" ::: "memory")
; #define PG8_WAIT_L(n) asm volatile("s_waitcnt lgkmcnt(" #n ")" ::: "memory")
; #define PG8_BAR __builtin_amdgcn_s_barrier()
; #define PG8_SCHED __builtin_amdgcn_sched_barrier(0)
; template <class Epi, class Sched, bool ALIGN_EPI = false, bool SP2 = false>
; __device__ __forceinline__ void gemm_phase(PG8_LAS unsigned char* lds, const Gemm g, const Sched& S, const Epi& E) {
;     ...
;             PG8_WAIT_V(8); PG8_WAIT_L(0); PG8_BAR; PG8_MMA(0, 0, At, B0); PG8_MMA(0, 1, At, B1); PG8_BAR; PG8_SCHED;
;             PG8_LDA(At, 0, 1); PG8_STAGE(PG8_SB(0, 0), b2, voffB); PG8_STAGE(PG8_SB(0, 1), b2 + hstep, voffB); PG8_STAGE(PG8_SA(0, 0), a2, voffA);
;             PG8_WAIT_V(8); PG8_WAIT_L(0); PG8_BAR; PG8_MMA(1, 0, At, B0); PG8_MMA(1, 1, At, B1); PG8_BAR; PG8_SCHED;
	s_setprio 1
	s_waitcnt lgkmcnt(0)
	v_mfma_f32_16x16x32_bf16 v[124:127], v[158:161], v[190:193], v[124:127]
	v_mfma_f32_16x16x32_bf16 v[120:123], v[166:169], v[190:193], v[120:123]
	v_mfma_f32_16x16x32_bf16 v[116:119], v[158:161], v[198:201], v[116:119]
	v_mfma_f32_16x16x32_bf16 v[112:115], v[166:169], v[198:201], v[112:115]
	v_mfma_f32_16x16x32_bf16 v[100:103], v[158:161], v[208:211], v[100:103]
	v_mfma_f32_16x16x32_bf16 v[96:99], v[166:169], v[208:211], v[96:99]
	v_mfma_f32_16x16x32_bf16 v[84:87], v[158:161], v[216:219], v[84:87]
	v_mfma_f32_16x16x32_bf16 v[80:83], v[166:169], v[216:219], v[80:83]
	v_mfma_f32_16x16x32_bf16 v[124:127], v[162:165], v[194:197], v[124:127]
	v_mfma_f32_16x16x32_bf16 v[120:123], v[170:173], v[194:197], v[120:123]
	v_mfma_f32_16x16x32_bf16 v[116:119], v[162:165], v[202:205], v[116:119]
	v_mfma_f32_16x16x32_bf16 v[112:115], v[170:173], v[202:205], v[112:115]
	v_mfma_f32_16x16x32_bf16 v[100:103], v[162:165], v[212:215], v[100:103]
	v_mfma_f32_16x16x32_bf16 v[96:99], v[170:173], v[212:215], v[96:99]
	v_mfma_f32_16x16x32_bf16 v[84:87], v[162:165], v[220:223], v[84:87]
	v_mfma_f32_16x16x32_bf16 v[80:83], v[170:173], v[220:223], v[80:83]
	v_mfma_f32_16x16x32_bf16 v[108:111], v[174:177], v[190:193], v[108:111]
	v_mfma_f32_16x16x32_bf16 v[104:107], v[182:185], v[190:193], v[104:107]
	v_mfma_f32_16x16x32_bf16 v[92:95], v[174:177], v[198:201], v[92:95]
	v_mfma_f32_16x16x32_bf16 v[88:91], v[182:185], v[198:201], v[88:91]
	v_mfma_f32_16x16x32_bf16 v[76:79], v[174:177], v[208:211], v[76:79]
	v_mfma_f32_16x16x32_bf16 v[72:75], v[182:185], v[208:211], v[72:75]
	v_mfma_f32_16x16x32_bf16 v[68:71], v[174:177], v[216:219], v[68:71]
	v_mfma_f32_16x16x32_bf16 v[64:67], v[182:185], v[216:219], v[64:67]
	v_mfma_f32_16x16x32_bf16 v[108:111], v[178:181], v[194:197], v[108:111]
	v_mfma_f32_16x16x32_bf16 v[104:107], v[186:189], v[194:197], v[104:107]
	v_mfma_f32_16x16x32_bf16 v[92:95], v[178:181], v[202:205], v[92:95]
	v_mfma_f32_16x16x32_bf16 v[88:91], v[186:189], v[202:205], v[88:91]
	v_mfma_f32_16x16x32_bf16 v[76:79], v[178:181], v[212:215], v[76:79]
	v_mfma_f32_16x16x32_bf16 v[72:75], v[186:189], v[212:215], v[72:75]
	v_mfma_f32_16x16x32_bf16 v[68:71], v[178:181], v[220:223], v[68:71]
	v_mfma_f32_16x16x32_bf16 v[64:67], v[186:189], v[220:223], v[64:67]
	s_setprio 0
	s_barrier
	s_mov_b32 m0, s58
	v_lshl_add_u64 v[224:225], s[22:23], 0, v[138:139]
	s_add_u32 s68, s22, 0xb0000
	ds_read_b128 v[190:193], v135 offset:16384
	ds_read_b128 v[194:197], v135 offset:17408
	ds_read_b128 v[198:201], v135 offset:18432
	ds_read_b128 v[202:205], v135 offset:19456
	ds_read_b128 v[208:211], v135 offset:20480
	ds_read_b128 v[212:215], v135 offset:21504
	ds_read_b128 v[216:219], v135 offset:22528
	ds_read_b128 v[220:223], v135 offset:23552
	global_load_lds_dwordx4 v[224:225], off
	v_lshl_add_u64 v[226:227], s[22:23], 0, v[142:143]
	s_mov_b32 m0, s59
	s_addc_u32 s69, s23, 0
	global_load_lds_dwordx4 v[226:227], off
	v_lshl_add_u64 v[228:229], s[68:69], 0, v[138:139]
	s_mov_b32 m0, s60
	v_lshl_add_u64 v[230:231], s[24:25], 0, v[140:141]
	global_load_lds_dwordx4 v[228:229], off
	v_lshl_add_u64 v[228:229], s[68:69], 0, v[142:143]
	s_mov_b32 m0, s61
	s_nop 0
	global_load_lds_dwordx4 v[228:229], off
	v_lshl_add_u64 v[228:229], s[24:25], 0, v[136:137]
	s_mov_b32 m0, s29
	s_nop 0
	global_load_lds_dwordx4 v[228:229], off
	s_mov_b32 m0, s30
	s_nop 0
	global_load_lds_dwordx4 v[230:231], off
	s_waitcnt vmcnt(8)
	s_waitcnt lgkmcnt(0)
	s_barrier
	s_setprio 1
	s_waitcnt lgkmcnt(0)
	v_mfma_f32_16x16x32_bf16 v[60:63], v[158:161], v[190:193], v[60:63]
	v_mfma_f32_16x16x32_bf16 v[56:59], v[166:169], v[190:193], v[56:59]
	v_mfma_f32_16x16x32_bf16 v[52:55], v[158:161], v[198:201], v[52:55]
	v_mfma_f32_16x16x32_bf16 v[48:51], v[166:169], v[198:201], v[48:51]
	v_mfma_f32_16x16x32_bf16 v[36:39], v[158:161], v[208:211], v[36:39]
	v_mfma_f32_16x16x32_bf16 v[32:35], v[166:169], v[208:211], v[32:35]
	v_mfma_f32_16x16x32_bf16 v[20:23], v[158:161], v[216:219], v[20:23]
	v_mfma_f32_16x16x32_bf16 v[16:19], v[166:169], v[216:219], v[16:19]
	v_mfma_f32_16x16x32_bf16 v[60:63], v[162:165], v[194:197], v[60:63]
	v_mfma_f32_16x16x32_bf16 v[56:59], v[170:173], v[194:197], v[56:59]
	v_mfma_f32_16x16x32_bf16 v[52:55], v[162:165], v[202:205], v[52:55]
	v_mfma_f32_16x16x32_bf16 v[48:51], v[170:173], v[202:205], v[48:51]
	v_mfma_f32_16x16x32_bf16 v[36:39], v[162:165], v[212:215], v[36:39]
	v_mfma_f32_16x16x32_bf16 v[32:35], v[170:173], v[212:215], v[32:35]
	v_mfma_f32_16x16x32_bf16 v[20:23], v[162:165], v[220:223], v[20:23]
	v_mfma_f32_16x16x32_bf16 v[16:19], v[170:173], v[220:223], v[16:19]
	v_mfma_f32_16x16x32_bf16 v[44:47], v[174:177], v[190:193], v[44:47]
	v_mfma_f32_16x16x32_bf16 v[40:43], v[182:185], v[190:193], v[40:43]
	v_mfma_f32_16x16x32_bf16 v[28:31], v[174:177], v[198:201], v[28:31]
	v_mfma_f32_16x16x32_bf16 v[24:27], v[182:185], v[198:201], v[24:27]
	v_mfma_f32_16x16x32_bf16 v[12:15], v[174:177], v[208:211], v[12:15]
	v_mfma_f32_16x16x32_bf16 v[8:11], v[182:185], v[208:211], v[8:11]
	v_mfma_f32_16x16x32_bf16 v[4:7], v[174:177], v[216:219], v[4:7]
	v_mfma_f32_16x16x32_bf16 v[0:3], v[182:185], v[216:219], v[0:3]
	v_mfma_f32_16x16x32_bf16 v[44:47], v[178:181], v[194:197], v[44:47]
	v_mfma_f32_16x16x32_bf16 v[40:43], v[186:189], v[194:197], v[40:43]
	v_mfma_f32_16x16x32_bf16 v[28:31], v[178:181], v[202:205], v[28:31]
	v_mfma_f32_16x16x32_bf16 v[24:27], v[186:189], v[202:205], v[24:27]
	v_mfma_f32_16x16x32_bf16 v[12:15], v[178:181], v[212:215], v[12:15]
	v_mfma_f32_16x16x32_bf16 v[8:11], v[186:189], v[212:215], v[8:11]
	v_mfma_f32_16x16x32_bf16 v[4:7], v[178:181], v[220:223], v[4:7]
	v_mfma_f32_16x16x32_bf16 v[0:3], v[186:189], v[220:223], v[0:3]
	s_setprio 0
	s_barrier
; #define PG8_STAGE(bufoff, gbase, voff) do { _Pragma("unroll") for (int _i = 0; _i < 2; ++_i) \
;         __builtin_amdgcn_global_load_lds((const unsigned*)((const char*)(gbase) + (voff)[_i]), (PG8_LAS unsigned*)(lds + (bufoff) + ldsw + _i * 8192), 16, 0, 0); } while (0)
; #define PG8_LDA(dst, b, h) do { _Pragma("unroll") for (int m = 0; m < 4; ++m) _Pragma("unroll") for (int k = 0; k < 2; ++k) dst[m][k] = *(const PG8_LAS bf16x8*)(lds + PG8_SA(b, h) + aoff + m * 2048 + k * 1024); } while (0)
; #define PG8_LDB(dst, b, h) do { _Pragma("unroll") for (int n = 0; n < 2; ++n) _Pragma("unroll") for (int k = 0; k < 2; ++k) dst[n][k] = *(const PG8_LAS bf16x8*)(lds + PG8_SB(b, h) + boff + n * 2048 + k * 1024); } while (0)
; #define PG8_MMA(ai, bj, At, Bt) do { __builtin_amdgcn_s_setprio(1); _Pragma("unroll") for (int m = 0; m < 4; ++m) _Pragma("unroll") for (int n = 0; n < 2; ++n) _Pragma("unroll") for (int k = 0; k < 2; ++k) \
;         acc[ai][bj][m][n] = __builtin_amdgcn_mfma_f32_16x16x32_bf16(Bt[n][k], At[m][k], acc[ai][bj][m][n], 0, 0, 0); __builtin_amdgcn_s_setprio(0); } while (0)
; #define PG8_WAIT_V(n) asm volatile("s_waitcnt vmcnt(" #n ")" ::: "memory")
; #define PG8_WAIT_L(n) asm volatile("s_waitcnt lgkmcnt(" #n ")" ::: "memory")
; #define PG8_BAR __builtin_amdgcn_s_barrier()
; #define PG8_SCHED __builtin_amdgcn_sched_barrier(0)
; template <class Epi, class Sched, bool ALIGN_EPI = false, bool SP2 = false>
; __device__ __forceinline__ void gemm_phase(PG8_LAS unsigned char* lds, const Gemm g, const Sched& S, const Epi& E) {
;     ...
;             PG8_LDB(B0, 1, 0); PG8_LDB(B1, 1, 1); PG8_SCHED; PG8_LDA(At, 1, 0); PG8_STAGE(PG8_SA(0, 1), a2 + hstep, voffA);
;             PG8_WAIT_V(8); PG8_WAIT_L(0); PG8_BAR; PG8_MMA(0, 0, At, B0); PG8_MMA(0, 1, At, B1); PG8_BAR; PG8_SCHED;
;             PG8_LDA(At, 1, 1); PG8_STAGE(PG8_SB(1, 0), b3, voffB); PG8_STAGE(PG8_SB(1, 1), b3 + hstep, voffB); PG8_STAGE(PG8_SA(1, 0), a3, voffA);
;             PG8_WAIT_V(8); PG8_WAIT_L(0); PG8_BAR; PG8_MMA(1, 0, At, B0); PG8_MMA(1, 1, At, B1); PG8_BAR; PG8_SCHED;
	ds_read_b128 v[158:161], v156
	ds_read_b128 v[162:165], v156 offset:1024
	ds_read_b128 v[166:169], v156 offset:2048
	ds_read_b128 v[170:173], v156 offset:3072
	ds_read_b128 v[174:177], v157
	ds_read_b128 v[178:181], v157 offset:1024
	ds_read_b128 v[182:185], v157 offset:2048
	ds_read_b128 v[186:189], v157 offset:3072
	s_add_u32 s24, s24, 0xb0000
	s_addc_u32 s25, s25, 0
	s_mov_b32 m0, s31
	v_lshl_add_u64 v[232:233], s[24:25], 0, v[136:137]
	ds_read_b128 v[190:193], v135 offset:32768
	ds_read_b128 v[194:197], v135 offset:33792
	ds_read_b128 v[198:201], v135 offset:34816
	ds_read_b128 v[202:205], v135 offset:35840
	ds_read_b128 v[208:211], v135 offset:36864
	ds_read_b128 v[212:215], v135 offset:37888
	ds_read_b128 v[216:219], v135 offset:38912
	ds_read_b128 v[220:223], v135 offset:39936
	global_load_lds_dwordx4 v[232:233], off
	v_lshl_add_u64 v[232:233], s[24:25], 0, v[140:141]
	s_mov_b32 m0, s38
	s_nop 0
	global_load_lds_dwordx4 v[232:233], off
	s_waitcnt vmcnt(8)
	s_waitcnt lgkmcnt(0)
	s_barrier
	s_setprio 1
	s_waitcnt lgkmcnt(0)
	v_mfma_f32_16x16x32_bf16 v[124:127], v[158:161], v[190:193], v[124:127]
	v_mfma_f32_16x16x32_bf16 v[120:123], v[166:169], v[190:193], v[120:123]
	v_mfma_f32_16x16x32_bf16 v[116:119], v[158:161], v[198:201], v[116:119]
	v_mfma_f32_16x16x32_bf16 v[112:115], v[166:169], v[198:201], v[112:115]
	v_mfma_f32_16x16x32_bf16 v[100:103], v[158:161], v[208:211], v[100:103]
	v_mfma_f32_16x16x32_bf16 v[96:99], v[166:169], v[208:211], v[96:99]
	v_mfma_f32_16x16x32_bf16 v[84:87], v[158:161], v[216:219], v[84:87]
	v_mfma_f32_16x16x32_bf16 v[80:83], v[166:169], v[216:219], v[80:83]
	v_mfma_f32_16x16x32_bf16 v[124:127], v[162:165], v[194:197], v[124:127]
	v_mfma_f32_16x16x32_bf16 v[120:123], v[170:173], v[194:197], v[120:123]
	v_mfma_f32_16x16x32_bf16 v[116:119], v[162:165], v[202:205], v[116:119]
	v_mfma_f32_16x16x32_bf16 v[112:115], v[170:173], v[202:205], v[112:115]
	v_mfma_f32_16x16x32_bf16 v[100:103], v[162:165], v[212:215], v[100:103]
	v_mfma_f32_16x16x32_bf16 v[96:99], v[170:173], v[212:215], v[96:99]
	v_mfma_f32_16x16x32_bf16 v[84:87], v[162:165], v[220:223], v[84:87]
	v_mfma_f32_16x16x32_bf16 v[80:83], v[170:173], v[220:223], v[80:83]
	v_mfma_f32_16x16x32_bf16 v[108:111], v[174:177], v[190:193], v[108:111]
	v_mfma_f32_16x16x32_bf16 v[104:107], v[182:185], v[190:193], v[104:107]
	v_mfma_f32_16x16x32_bf16 v[92:95], v[174:177], v[198:201], v[92:95]
	v_mfma_f32_16x16x32_bf16 v[88:91], v[182:185], v[198:201], v[88:91]
	v_mfma_f32_16x16x32_bf16 v[76:79], v[174:177], v[208:211], v[76:79]
	v_mfma_f32_16x16x32_bf16 v[72:75], v[182:185], v[208:211], v[72:75]
	v_mfma_f32_16x16x32_bf16 v[68:71], v[174:177], v[216:219], v[68:71]
	v_mfma_f32_16x16x32_bf16 v[64:67], v[182:185], v[216:219], v[64:67]
	v_mfma_f32_16x16x32_bf16 v[108:111], v[178:181], v[194:197], v[108:111]
	v_mfma_f32_16x16x32_bf16 v[104:107], v[186:189], v[194:197], v[104:107]
	v_mfma_f32_16x16x32_bf16 v[92:95], v[178:181], v[202:205], v[92:95]
	v_mfma_f32_16x16x32_bf16 v[88:91], v[186:189], v[202:205], v[88:91]
	v_mfma_f32_16x16x32_bf16 v[76:79], v[178:181], v[212:215], v[76:79]
	v_mfma_f32_16x16x32_bf16 v[72:75], v[186:189], v[212:215], v[72:75]
	v_mfma_f32_16x16x32_bf16 v[68:71], v[178:181], v[220:223], v[68:71]
	v_mfma_f32_16x16x32_bf16 v[64:67], v[186:189], v[220:223], v[64:67]
	s_setprio 0
	s_barrier
	s_mov_b32 m0, s64
	v_lshl_add_u64 v[224:225], v[224:225], 0, s[18:19]
	s_add_u32 s22, s22, 0xb0080
	ds_read_b128 v[190:193], v135 offset:49152
	ds_read_b128 v[194:197], v135 offset:50176
	ds_read_b128 v[198:201], v135 offset:51200
	ds_read_b128 v[202:205], v135 offset:52224
	ds_read_b128 v[208:211], v135 offset:53248
	ds_read_b128 v[212:215], v135 offset:54272
	ds_read_b128 v[216:219], v135 offset:55296
	ds_read_b128 v[220:223], v135 offset:56320
	global_load_lds_dwordx4 v[224:225], off
	v_lshl_add_u64 v[224:225], v[226:227], 0, s[18:19]
	s_mov_b32 m0, s65
	s_addc_u32 s23, s23, 0
	global_load_lds_dwordx4 v[224:225], off
	v_lshl_add_u64 v[224:225], s[22:23], 0, v[138:139]
	s_mov_b32 m0, s66
	s_nop 0
	global_load_lds_dwordx4 v[224:225], off
	v_lshl_add_u64 v[224:225], s[22:23], 0, v[142:143]
	s_mov_b32 m0, s67
	s_nop 0
	global_load_lds_dwordx4 v[224:225], off
	v_lshl_add_u64 v[224:225], v[228:229], 0, s[18:19]
	s_mov_b32 m0, s40
	s_nop 0
	global_load_lds_dwordx4 v[224:225], off
	v_lshl_add_u64 v[224:225], v[230:231], 0, s[18:19]
	s_mov_b32 m0, s41
	s_nop 0
	global_load_lds_dwordx4 v[224:225], off
	s_waitcnt vmcnt(8)
	s_waitcnt lgkmcnt(0)
	s_barrier
	s_setprio 1
	s_waitcnt lgkmcnt(0)
	v_mfma_f32_16x16x32_bf16 v[60:63], v[158:161], v[190:193], v[60:63]
	v_mfma_f32_16x16x32_bf16 v[56:59], v[166:169], v[190:193], v[56:59]
	v_mfma_f32_16x16x32_bf16 v[52:55], v[158:161], v[198:201], v[52:55]
	v_mfma_f32_16x16x32_bf16 v[48:51], v[166:169], v[198:201], v[48:51]
	v_mfma_f32_16x16x32_bf16 v[36:39], v[158:161], v[208:211], v[36:39]
	v_mfma_f32_16x16x32_bf16 v[32:35], v[166:169], v[208:211], v[32:35]
	v_mfma_f32_16x16x32_bf16 v[20:23], v[158:161], v[216:219], v[20:23]
	v_mfma_f32_16x16x32_bf16 v[16:19], v[166:169], v[216:219], v[16:19]
	v_mfma_f32_16x16x32_bf16 v[60:63], v[162:165], v[194:197], v[60:63]
	v_mfma_f32_16x16x32_bf16 v[56:59], v[170:173], v[194:197], v[56:59]
	v_mfma_f32_16x16x32_bf16 v[52:55], v[162:165], v[202:205], v[52:55]
	v_mfma_f32_16x16x32_bf16 v[48:51], v[170:173], v[202:205], v[48:51]
	v_mfma_f32_16x16x32_bf16 v[36:39], v[162:165], v[212:215], v[36:39]
	v_mfma_f32_16x16x32_bf16 v[32:35], v[170:173], v[212:215], v[32:35]
	v_mfma_f32_16x16x32_bf16 v[20:23], v[162:165], v[220:223], v[20:23]
	v_mfma_f32_16x16x32_bf16 v[16:19], v[170:173], v[220:223], v[16:19]
	v_mfma_f32_16x16x32_bf16 v[44:47], v[174:177], v[190:193], v[44:47]
	v_mfma_f32_16x16x32_bf16 v[40:43], v[182:185], v[190:193], v[40:43]
	v_mfma_f32_16x16x32_bf16 v[28:31], v[174:177], v[198:201], v[28:31]
	v_mfma_f32_16x16x32_bf16 v[24:27], v[182:185], v[198:201], v[24:27]
	v_mfma_f32_16x16x32_bf16 v[12:15], v[174:177], v[208:211], v[12:15]
	v_mfma_f32_16x16x32_bf16 v[8:11], v[182:185], v[208:211], v[8:11]
	v_mfma_f32_16x16x32_bf16 v[4:7], v[174:177], v[216:219], v[4:7]
	v_mfma_f32_16x16x32_bf16 v[0:3], v[182:185], v[216:219], v[0:3]
	v_mfma_f32_16x16x32_bf16 v[44:47], v[178:181], v[194:197], v[44:47]
	v_mfma_f32_16x16x32_bf16 v[40:43], v[186:189], v[194:197], v[40:43]
	v_mfma_f32_16x16x32_bf16 v[28:31], v[178:181], v[202:205], v[28:31]
	v_mfma_f32_16x16x32_bf16 v[24:27], v[186:189], v[202:205], v[24:27]
	v_mfma_f32_16x16x32_bf16 v[12:15], v[178:181], v[212:215], v[12:15]
	v_mfma_f32_16x16x32_bf16 v[8:11], v[186:189], v[212:215], v[8:11]
	v_mfma_f32_16x16x32_bf16 v[4:7], v[178:181], v[220:223], v[4:7]
	v_mfma_f32_16x16x32_bf16 v[0:3], v[186:189], v[220:223], v[0:3]
	s_setprio 0
	s_barrier
	s_add_i32 s42, s42, 2
	s_add_u32 s20, s20, 0x100
	s_addc_u32 s21, s21, 0
	s_cmp_gt_u32 s42, 41
	s_cbranch_scc0 .LBB0_966

;     __device__ __forceinline__ bool next(int i, Unit& u) const { if (i != 0) return false; const int c0 = (G >= 8) ? G - 5 : G - 2; int k = -1; if (c == c0) k = 0; else if (c == G - 1) k = 1; if (k < 0 || k >= n) return false; u.pm = k; u.pn = 0; return true; }
; #define PG8_STAGE(bufoff, gbase, voff) do { _Pragma("unroll") for (int _i = 0; _i < 2; ++_i) \
;         __builtin_amdgcn_global_load_lds((const unsigned*)((const char*)(gbase) + (voff)[_i]), (PG8_LAS unsigned*)(lds + (bufoff) + ldsw + _i * 8192), 16, 0, 0); } while (0)
; #define PG8_LDA(dst, b, h) do { _Pragma("unroll") for (int m = 0; m < 4; ++m) _Pragma("unroll") for (int k = 0; k < 2; ++k) dst[m][k] = *(const PG8_LAS bf16x8*)(lds + PG8_SA(b, h) + aoff + m * 2048 + k * 1024); } while (0)
; #define PG8_LDB(dst, b, h) do { _Pragma("unroll") for (int n = 0; n < 2; ++n) _Pragma("unroll") for (int k = 0; k < 2; ++k) dst[n][k] = *(const PG8_LAS bf16x8*)(lds + PG8_SB(b, h) + boff + n * 2048 + k * 1024); } while (0)
; #define PG8_WAIT_V(n) asm volatile("s_waitcnt vmcnt(" #n ")" ::: "memory")
; #define PG8_WAIT_L(n) asm volatile("s_waitcnt lgkmcnt(" #n ")" ::: "memory")
; #define PG8_BAR __builtin_amdgcn_s_barrier()
; #define PG8_SCHED __builtin_amdgcn_sched_barrier(0)
; template <class Epi, class Sched, bool ALIGN_EPI = false, bool SP2 = false>
; __device__ __forceinline__ void gemm_phase(PG8_LAS unsigned char* lds, const Gemm g, const Sched& S, const Epi& E) {
;     ...
;         const bool has_next = S.next(ui + 1, nxt);
;         const char* nA = has_next ? (const char*)g.A + (size_t)nxt.pm * tstep : cA; const char* nB = has_next ? (const char*)g.Bt + (size_t)nxt.pn * tstep : cB;
;         for (int t = 0; t < nt; t += 2) {
;             const bool last = (t == nt - 2);
;             const char* a1 = cA + (size_t)(t + 1) * kstep;
;             const char* a2 = last ? nA : cA + (size_t)(t + 2) * kstep; const char* b2 = last ? nB : cB + (size_t)(t + 2) * kstep;
;             const char* a3 = a2 + kstep; const char* b3 = b2 + kstep;
;             if (last && has_next) S.a_ready(nxt);
;             if constexpr (SP2) {
;             PG8_LDB(B0, 0, 0); PG8_LDB(B1, 0, 1); PG8_SCHED; PG8_LDA(At, 0, 0); PG8_STAGE(PG8_SA(1, 1), a1 + hstep, voffA);
;             PG8_WAIT_V(8); PG8_WAIT_L(0); PG8_BAR; PG8_MMA(0, 0, At, B0); PG8_MMA(0, 1, At, B1); PG8_BAR; PG8_SCHED;
.LBB0_1051:
	s_ashr_i32 s21, s20, 31
	s_lshl_b64 s[26:27], s[20:21], 19
	s_add_u32 s26, s97, s26
	s_addc_u32 s27, s3, s27
	s_and_b64 s[28:29], s[24:25], exec
	s_cselect_b32 s21, s27, s39
	s_cselect_b32 s72, s26, s38
	s_ashr_i32 s23, s22, 31
	s_lshl_b64 s[28:29], s[22:23], 19
	s_add_u32 s28, s46, s28
	s_addc_u32 s29, s47, s29
	s_and_b64 s[42:43], s[24:25], exec
	s_cselect_b32 s23, s29, s41
	s_cselect_b32 s73, s28, s40
	s_add_u32 s38, s38, 0x40080
	s_addc_u32 s39, s39, 0
	s_add_u32 s74, s40, 0x100
	v_mov_b32_e32 v0, 0
	s_addc_u32 s75, s41, 0
	s_mov_b32 s76, -2
	ds_read_b128 v[150:153], v147
	ds_read_b128 v[154:157], v147 offset:1024
	ds_read_b128 v[158:161], v147 offset:2048
	ds_read_b128 v[162:165], v147 offset:3072
	ds_read_b128 v[166:169], v148
	ds_read_b128 v[170:173], v148 offset:1024
	ds_read_b128 v[174:177], v148 offset:2048
	ds_read_b128 v[178:181], v148 offset:3072
	s_add_u32 s40, s38, 0xfffc0080
	s_addc_u32 s41, s39, -1
	s_cmp_eq_u32 s76, 12
	s_cselect_b32 s43, s21, s41
	s_cselect_b32 s42, s72, s40
	s_cselect_b32 s41, s23, s75
	s_cselect_b32 s40, s73, s74
	v_lshl_add_u64 v[142:143], s[38:39], 0, v[136:137]
	s_add_i32 m0, s31, 0xc000
	ds_read_b128 v[182:185], v149
	ds_read_b128 v[186:189], v149 offset:1024
	ds_read_b128 v[190:193], v149 offset:2048
	ds_read_b128 v[194:197], v149 offset:3072
	ds_read_b128 v[198:201], v149 offset:4096
	ds_read_b128 v[202:205], v149 offset:5120
	ds_read_b128 v[208:211], v149 offset:6144
	ds_read_b128 v[212:215], v149 offset:7168
	global_load_lds_dwordx4 v[142:143], off
	v_lshl_add_u64 v[142:143], s[38:39], 0, v[138:139]
	s_add_i32 m0, s31, 0xe000
	s_nop 0
	global_load_lds_dwordx4 v[142:143], off
	s_waitcnt vmcnt(8)
	s_waitcnt lgkmcnt(0)
	s_barrier
	s_setprio 1
	s_waitcnt lgkmcnt(0)
	v_mfma_f32_16x16x32_bf16 v[124:127], v[150:153], v[182:185], 0
	v_mfma_f32_16x16x32_bf16 v[120:123], v[158:161], v[182:185], 0
	v_mfma_f32_16x16x32_bf16 v[108:111], v[150:153], v[190:193], 0
	v_mfma_f32_16x16x32_bf16 v[104:107], v[158:161], v[190:193], 0
	v_mfma_f32_16x16x32_bf16 v[92:95], v[150:153], v[198:201], 0
	v_mfma_f32_16x16x32_bf16 v[88:91], v[158:161], v[198:201], 0
	v_mfma_f32_16x16x32_bf16 v[76:79], v[150:153], v[208:211], 0
	v_mfma_f32_16x16x32_bf16 v[72:75], v[158:161], v[208:211], 0
	v_mfma_f32_16x16x32_bf16 v[124:127], v[154:157], v[186:189], v[124:127]
	v_mfma_f32_16x16x32_bf16 v[120:123], v[162:165], v[186:189], v[120:123]
	v_mfma_f32_16x16x32_bf16 v[108:111], v[154:157], v[194:197], v[108:111]
	v_mfma_f32_16x16x32_bf16 v[104:107], v[162:165], v[194:197], v[104:107]
	v_mfma_f32_16x16x32_bf16 v[92:95], v[154:157], v[202:205], v[92:95]
	v_mfma_f32_16x16x32_bf16 v[88:91], v[162:165], v[202:205], v[88:91]
	v_mfma_f32_16x16x32_bf16 v[76:79], v[154:157], v[212:215], v[76:79]
	v_mfma_f32_16x16x32_bf16 v[72:75], v[162:165], v[212:215], v[72:75]
	v_mfma_f32_16x16x32_bf16 v[116:119], v[166:169], v[182:185], 0
	v_mfma_f32_16x16x32_bf16 v[112:115], v[174:177], v[182:185], 0
	v_mfma_f32_16x16x32_bf16 v[100:103], v[166:169], v[190:193], 0
	v_mfma_f32_16x16x32_bf16 v[96:99], v[174:177], v[190:193], 0
	v_mfma_f32_16x16x32_bf16 v[84:87], v[166:169], v[198:201], 0
	v_mfma_f32_16x16x32_bf16 v[80:83], v[174:177], v[198:201], 0
	v_mfma_f32_16x16x32_bf16 v[68:71], v[166:169], v[208:211], 0
	v_mfma_f32_16x16x32_bf16 v[64:67], v[174:177], v[208:211], 0
	v_mfma_f32_16x16x32_bf16 v[116:119], v[170:173], v[186:189], v[116:119]
	v_mfma_f32_16x16x32_bf16 v[112:115], v[178:181], v[186:189], v[112:115]
	v_mfma_f32_16x16x32_bf16 v[100:103], v[170:173], v[194:197], v[100:103]
	v_mfma_f32_16x16x32_bf16 v[96:99], v[178:181], v[194:197], v[96:99]
	v_mfma_f32_16x16x32_bf16 v[84:87], v[170:173], v[202:205], v[84:87]
	v_mfma_f32_16x16x32_bf16 v[80:83], v[178:181], v[202:205], v[80:83]
	v_mfma_f32_16x16x32_bf16 v[68:71], v[170:173], v[212:215], v[68:71]
	v_mfma_f32_16x16x32_bf16 v[64:67], v[178:181], v[212:215], v[64:67]
	s_setprio 0
	s_barrier
	s_add_i32 s77, s67, s57
	v_lshl_add_u64 v[142:143], s[40:41], 0, v[130:131]
	s_mov_b32 m0, s77
	ds_read_b128 v[182:185], v149 offset:16384
	ds_read_b128 v[186:189], v149 offset:17408
	ds_read_b128 v[190:193], v149 offset:18432
	ds_read_b128 v[194:197], v149 offset:19456
	ds_read_b128 v[198:201], v149 offset:20480
	ds_read_b128 v[202:205], v149 offset:21504
	ds_read_b128 v[208:211], v149 offset:22528
	ds_read_b128 v[212:215], v149 offset:23552
	global_load_lds_dwordx4 v[142:143], off
	s_add_i32 m0, s77, 0x2000
	s_add_u32 s78, s40, 0x40000
	v_lshl_add_u64 v[216:217], s[40:41], 0, v[134:135]
	s_addc_u32 s79, s41, 0
	s_add_i32 s77, s68, s57
	global_load_lds_dwordx4 v[216:217], off
	v_lshl_add_u64 v[218:219], s[78:79], 0, v[130:131]
	s_mov_b32 m0, s77
	v_lshl_add_u64 v[220:221], s[42:43], 0, v[132:133]
	global_load_lds_dwordx4 v[218:219], off
	v_lshl_add_u64 v[218:219], s[78:79], 0, v[134:135]
	s_add_i32 m0, s77, 0x2000
	s_nop 0
	global_load_lds_dwordx4 v[218:219], off
	v_lshl_add_u64 v[218:219], s[42:43], 0, v[128:129]
	s_mov_b32 m0, s31
	s_nop 0
	global_load_lds_dwordx4 v[218:219], off
	s_mov_b32 m0, s59
	s_nop 0
	global_load_lds_dwordx4 v[220:221], off
	s_waitcnt vmcnt(8)
	s_waitcnt lgkmcnt(0)
	s_barrier
; #define PG8_STAGE(bufoff, gbase, voff) do { _Pragma("unroll") for (int _i = 0; _i < 2; ++_i) \
;         __builtin_amdgcn_global_load_lds((const unsigned*)((const char*)(gbase) + (voff)[_i]), (PG8_LAS unsigned*)(lds + (bufoff) + ldsw + _i * 8192), 16, 0, 0); } while (0)
; #define PG8_LDA(dst, b, h) do { _Pragma("unroll") for (int m = 0; m < 4; ++m) _Pragma("unroll") for (int k = 0; k < 2; ++k) dst[m][k] = *(const PG8_LAS bf16x8*)(lds + PG8_SA(b, h) + aoff + m * 2048 + k * 1024); } while (0)
; #define PG8_LDB(dst, b, h) do { _Pragma("unroll") for (int n = 0; n < 2; ++n) _Pragma("unroll") for (int k = 0; k < 2; ++k) dst[n][k] = *(const PG8_LAS bf16x8*)(lds + PG8_SB(b, h) + boff + n * 2048 + k * 1024); } while (0)
; #define PG8_MMA(ai, bj, At, Bt) do { __builtin_amdgcn_s_setprio(1); _Pragma("unroll") for (int m = 0; m < 4; ++m) _Pragma("unroll") for (int n = 0; n < 2; ++n) _Pragma("unroll") for (int k = 0; k < 2; ++k) \
;         acc[ai][bj][m][n] = __builtin_amdgcn_mfma_f32_16x16x32_bf16(Bt[n][k], At[m][k], acc[ai][bj][m][n], 0, 0, 0); __builtin_amdgcn_s_setprio(0); } while (0)
; #define PG8_WAIT_V(n) asm volatile("s_waitcnt vmcnt(" #n ")" ::: "memory")
; #define PG8_WAIT_L(n) asm volatile("s_waitcnt lgkmcnt(" #n ")" ::: "memory")
; #define PG8_BAR __builtin_amdgcn_s_barrier()
; #define PG8_SCHED __builtin_amdgcn_sched_barrier(0)
; template <class Epi, class Sched, bool ALIGN_EPI = false, bool SP2 = false>
; __device__ __forceinline__ void gemm_phase(PG8_LAS unsigned char* lds, const Gemm g, const Sched& S, const Epi& E) {
;     ...
;             PG8_LDA(At, 0, 1); PG8_STAGE(PG8_SB(0, 0), b2, voffB); PG8_STAGE(PG8_SB(0, 1), b2 + hstep, voffB); PG8_STAGE(PG8_SA(0, 0), a2, voffA);
;             PG8_WAIT_V(8); PG8_WAIT_L(0); PG8_BAR; PG8_MMA(1, 0, At, B0); PG8_MMA(1, 1, At, B1); PG8_BAR; PG8_SCHED;
;             PG8_LDB(B0, 1, 0); PG8_LDB(B1, 1, 1); PG8_SCHED; PG8_LDA(At, 1, 0); PG8_STAGE(PG8_SA(0, 1), a2 + hstep, voffA);
;             PG8_WAIT_V(8); PG8_WAIT_L(0); PG8_BAR; PG8_MMA(0, 0, At, B0); PG8_MMA(0, 1, At, B1); PG8_BAR; PG8_SCHED;
	s_setprio 1
	s_waitcnt lgkmcnt(0)
	v_mfma_f32_16x16x32_bf16 v[60:63], v[150:153], v[182:185], 0
	v_mfma_f32_16x16x32_bf16 v[56:59], v[158:161], v[182:185], 0
	v_mfma_f32_16x16x32_bf16 v[44:47], v[150:153], v[190:193], 0
	v_mfma_f32_16x16x32_bf16 v[40:43], v[158:161], v[190:193], 0
	v_mfma_f32_16x16x32_bf16 v[28:31], v[150:153], v[198:201], 0
	v_mfma_f32_16x16x32_bf16 v[24:27], v[158:161], v[198:201], 0
	v_mfma_f32_16x16x32_bf16 v[12:15], v[150:153], v[208:211], 0
	v_mfma_f32_16x16x32_bf16 v[8:11], v[158:161], v[208:211], 0
	v_mfma_f32_16x16x32_bf16 v[60:63], v[154:157], v[186:189], v[60:63]
	v_mfma_f32_16x16x32_bf16 v[56:59], v[162:165], v[186:189], v[56:59]
	v_mfma_f32_16x16x32_bf16 v[44:47], v[154:157], v[194:197], v[44:47]
	v_mfma_f32_16x16x32_bf16 v[40:43], v[162:165], v[194:197], v[40:43]
	v_mfma_f32_16x16x32_bf16 v[28:31], v[154:157], v[202:205], v[28:31]
	v_mfma_f32_16x16x32_bf16 v[24:27], v[162:165], v[202:205], v[24:27]
	v_mfma_f32_16x16x32_bf16 v[12:15], v[154:157], v[212:215], v[12:15]
	v_mfma_f32_16x16x32_bf16 v[8:11], v[162:165], v[212:215], v[8:11]
	v_mfma_f32_16x16x32_bf16 v[52:55], v[166:169], v[182:185], 0
	v_mfma_f32_16x16x32_bf16 v[48:51], v[174:177], v[182:185], 0
	v_mfma_f32_16x16x32_bf16 v[36:39], v[166:169], v[190:193], 0
	v_mfma_f32_16x16x32_bf16 v[32:35], v[174:177], v[190:193], 0
	v_mfma_f32_16x16x32_bf16 v[20:23], v[166:169], v[198:201], 0
	v_mfma_f32_16x16x32_bf16 v[16:19], v[174:177], v[198:201], 0
	v_mfma_f32_16x16x32_bf16 v[4:7], v[166:169], v[208:211], 0
	v_mfma_f32_16x16x32_bf16 v[0:3], v[174:177], v[208:211], 0
	v_mfma_f32_16x16x32_bf16 v[52:55], v[170:173], v[186:189], v[52:55]
	v_mfma_f32_16x16x32_bf16 v[48:51], v[178:181], v[186:189], v[48:51]
	v_mfma_f32_16x16x32_bf16 v[36:39], v[170:173], v[194:197], v[36:39]
	v_mfma_f32_16x16x32_bf16 v[32:35], v[178:181], v[194:197], v[32:35]
	v_mfma_f32_16x16x32_bf16 v[20:23], v[170:173], v[202:205], v[20:23]
	v_mfma_f32_16x16x32_bf16 v[16:19], v[178:181], v[202:205], v[16:19]
	v_mfma_f32_16x16x32_bf16 v[4:7], v[170:173], v[212:215], v[4:7]
	v_mfma_f32_16x16x32_bf16 v[0:3], v[178:181], v[212:215], v[0:3]
	s_setprio 0
	s_barrier
	s_add_i32 s77, 0, 0x18000
	s_add_i32 s78, 0, 0x1c000
	v_add_u32_e32 v162, s77, v145
	v_add_u32_e32 v178, s78, v145
	ds_read_b128 v[150:153], v162
	ds_read_b128 v[154:157], v162 offset:1024
	ds_read_b128 v[158:161], v162 offset:2048
	ds_read_b128 v[162:165], v162 offset:3072
	ds_read_b128 v[166:169], v178
	ds_read_b128 v[170:173], v178 offset:1024
	ds_read_b128 v[174:177], v178 offset:2048
	ds_read_b128 v[178:181], v178 offset:3072
	s_add_u32 s42, s42, 0x40000
	s_addc_u32 s43, s43, 0
	s_mov_b32 m0, s60
	v_lshl_add_u64 v[222:223], s[42:43], 0, v[128:129]
	ds_read_b128 v[182:185], v149 offset:32768
	ds_read_b128 v[186:189], v149 offset:33792
	ds_read_b128 v[190:193], v149 offset:34816
	ds_read_b128 v[194:197], v149 offset:35840
	ds_read_b128 v[198:201], v149 offset:36864
	ds_read_b128 v[202:205], v149 offset:37888
	ds_read_b128 v[208:211], v149 offset:38912
	ds_read_b128 v[212:215], v149 offset:39936
	global_load_lds_dwordx4 v[222:223], off
	v_lshl_add_u64 v[222:223], s[42:43], 0, v[132:133]
	s_mov_b32 m0, s61
	s_nop 0
	global_load_lds_dwordx4 v[222:223], off
	s_waitcnt vmcnt(8)
	s_waitcnt lgkmcnt(0)
	s_barrier
	s_setprio 1
	s_waitcnt lgkmcnt(0)
	v_mfma_f32_16x16x32_bf16 v[124:127], v[150:153], v[182:185], v[124:127]
	v_mfma_f32_16x16x32_bf16 v[120:123], v[158:161], v[182:185], v[120:123]
	v_mfma_f32_16x16x32_bf16 v[108:111], v[150:153], v[190:193], v[108:111]
	v_mfma_f32_16x16x32_bf16 v[104:107], v[158:161], v[190:193], v[104:107]
	v_mfma_f32_16x16x32_bf16 v[92:95], v[150:153], v[198:201], v[92:95]
	v_mfma_f32_16x16x32_bf16 v[88:91], v[158:161], v[198:201], v[88:91]
	v_mfma_f32_16x16x32_bf16 v[76:79], v[150:153], v[208:211], v[76:79]
	v_mfma_f32_16x16x32_bf16 v[72:75], v[158:161], v[208:211], v[72:75]
	v_mfma_f32_16x16x32_bf16 v[124:127], v[154:157], v[186:189], v[124:127]
	v_mfma_f32_16x16x32_bf16 v[120:123], v[162:165], v[186:189], v[120:123]
	v_mfma_f32_16x16x32_bf16 v[108:111], v[154:157], v[194:197], v[108:111]
	v_mfma_f32_16x16x32_bf16 v[104:107], v[162:165], v[194:197], v[104:107]
	v_mfma_f32_16x16x32_bf16 v[92:95], v[154:157], v[202:205], v[92:95]
	v_mfma_f32_16x16x32_bf16 v[88:91], v[162:165], v[202:205], v[88:91]
	v_mfma_f32_16x16x32_bf16 v[76:79], v[154:157], v[212:215], v[76:79]
	v_mfma_f32_16x16x32_bf16 v[72:75], v[162:165], v[212:215], v[72:75]
	v_mfma_f32_16x16x32_bf16 v[116:119], v[166:169], v[182:185], v[116:119]
	v_mfma_f32_16x16x32_bf16 v[112:115], v[174:177], v[182:185], v[112:115]
	v_mfma_f32_16x16x32_bf16 v[100:103], v[166:169], v[190:193], v[100:103]
	v_mfma_f32_16x16x32_bf16 v[96:99], v[174:177], v[190:193], v[96:99]
	v_mfma_f32_16x16x32_bf16 v[84:87], v[166:169], v[198:201], v[84:87]
	v_mfma_f32_16x16x32_bf16 v[80:83], v[174:177], v[198:201], v[80:83]
	v_mfma_f32_16x16x32_bf16 v[68:71], v[166:169], v[208:211], v[68:71]
	v_mfma_f32_16x16x32_bf16 v[64:67], v[174:177], v[208:211], v[64:67]
	v_mfma_f32_16x16x32_bf16 v[116:119], v[170:173], v[186:189], v[116:119]
	v_mfma_f32_16x16x32_bf16 v[112:115], v[178:181], v[186:189], v[112:115]
	v_mfma_f32_16x16x32_bf16 v[100:103], v[170:173], v[194:197], v[100:103]
	v_mfma_f32_16x16x32_bf16 v[96:99], v[178:181], v[194:197], v[96:99]
	v_mfma_f32_16x16x32_bf16 v[84:87], v[170:173], v[202:205], v[84:87]
	v_mfma_f32_16x16x32_bf16 v[80:83], v[178:181], v[202:205], v[80:83]
	v_mfma_f32_16x16x32_bf16 v[68:71], v[170:173], v[212:215], v[68:71]
	v_mfma_f32_16x16x32_bf16 v[64:67], v[178:181], v[212:215], v[64:67]
	s_setprio 0
	s_barrier
; #define PG8_STAGE(bufoff, gbase, voff) do { _Pragma("unroll") for (int _i = 0; _i < 2; ++_i) \
;         __builtin_amdgcn_global_load_lds((const unsigned*)((const char*)(gbase) + (voff)[_i]), (PG8_LAS unsigned*)(lds + (bufoff) + ldsw + _i * 8192), 16, 0, 0); } while (0)
; #define PG8_LDA(dst, b, h) do { _Pragma("unroll") for (int m = 0; m < 4; ++m) _Pragma("unroll") for (int k = 0; k < 2; ++k) dst[m][k] = *(const PG8_LAS bf16x8*)(lds + PG8_SA(b, h) + aoff + m * 2048 + k * 1024); } while (0)
; #define PG8_LDB(dst, b, h) do { _Pragma("unroll") for (int n = 0; n < 2; ++n) _Pragma("unroll") for (int k = 0; k < 2; ++k) dst[n][k] = *(const PG8_LAS bf16x8*)(lds + PG8_SB(b, h) + boff + n * 2048 + k * 1024); } while (0)
; #define PG8_MMA(ai, bj, At, Bt) do { __builtin_amdgcn_s_setprio(1); _Pragma("unroll") for (int m = 0; m < 4; ++m) _Pragma("unroll") for (int n = 0; n < 2; ++n) _Pragma("unroll") for (int k = 0; k < 2; ++k) \
;         acc[ai][bj][m][n] = __builtin_amdgcn_mfma_f32_16x16x32_bf16(Bt[n][k], At[m][k], acc[ai][bj][m][n], 0, 0, 0); __builtin_amdgcn_s_setprio(0); } while (0)
; #define PG8_WAIT_V(n) asm volatile("s_waitcnt vmcnt(" #n ")" ::: "memory")
; #define PG8_WAIT_L(n) asm volatile("s_waitcnt lgkmcnt(" #n ")" ::: "memory")
; #define PG8_BAR __builtin_amdgcn_s_barrier()
; #define PG8_SCHED __builtin_amdgcn_sched_barrier(0)
; template <class Epi, class Sched, bool ALIGN_EPI = false, bool SP2 = false>
; __device__ __forceinline__ void gemm_phase(PG8_LAS unsigned char* lds, const Gemm g, const Sched& S, const Epi& E) {
;     ...
;             PG8_LDB(B0, 0, 0); PG8_LDB(B1, 0, 1); PG8_SCHED; PG8_LDA(At, 0, 0); PG8_STAGE(PG8_SA(1, 1), a1 + hstep, voffA);
;             PG8_WAIT_V(8); PG8_WAIT_L(0); PG8_BAR; PG8_MMA(0, 0, At, B0); PG8_MMA(0, 1, At, B1); PG8_BAR; PG8_SCHED;
;     ...
;             PG8_LDA(At, 1, 1); PG8_STAGE(PG8_SB(1, 0), b3, voffB); PG8_STAGE(PG8_SB(1, 1), b3 + hstep, voffB); PG8_STAGE(PG8_SA(1, 0), a3, voffA);
;             PG8_WAIT_V(8); PG8_WAIT_L(0); PG8_BAR; PG8_MMA(1, 0, At, B0); PG8_MMA(1, 1, At, B1); PG8_BAR; PG8_SCHED;
	s_add_i32 s42, s77, s57
	v_lshl_add_u64 v[142:143], v[142:143], 0, s[8:9]
	s_mov_b32 m0, s42
	ds_read_b128 v[182:185], v149 offset:49152
	ds_read_b128 v[186:189], v149 offset:50176
	ds_read_b128 v[190:193], v149 offset:51200
	ds_read_b128 v[194:197], v149 offset:52224
	ds_read_b128 v[198:201], v149 offset:53248
	ds_read_b128 v[202:205], v149 offset:54272
	ds_read_b128 v[208:211], v149 offset:55296
	ds_read_b128 v[212:215], v149 offset:56320
	global_load_lds_dwordx4 v[142:143], off
	s_add_i32 m0, s42, 0x2000
	s_add_u32 s40, s40, 0x40080
	v_lshl_add_u64 v[142:143], v[216:217], 0, s[8:9]
	s_addc_u32 s41, s41, 0
	s_add_i32 s42, s78, s57
	global_load_lds_dwordx4 v[142:143], off
	v_lshl_add_u64 v[142:143], s[40:41], 0, v[130:131]
	s_mov_b32 m0, s42
	s_nop 0
	global_load_lds_dwordx4 v[142:143], off
	v_lshl_add_u64 v[142:143], s[40:41], 0, v[134:135]
	s_add_i32 m0, s42, 0x2000
	s_nop 0
	global_load_lds_dwordx4 v[142:143], off
	v_lshl_add_u64 v[142:143], v[218:219], 0, s[8:9]
	s_mov_b32 m0, s65
	s_nop 0
	global_load_lds_dwordx4 v[142:143], off
	v_lshl_add_u64 v[142:143], v[220:221], 0, s[8:9]
	s_mov_b32 m0, s66
	s_nop 0
	global_load_lds_dwordx4 v[142:143], off
	s_waitcnt vmcnt(8)
	s_waitcnt lgkmcnt(0)
	s_barrier
	s_setprio 1
	s_waitcnt lgkmcnt(0)
	v_mfma_f32_16x16x32_bf16 v[60:63], v[150:153], v[182:185], v[60:63]
	v_mfma_f32_16x16x32_bf16 v[56:59], v[158:161], v[182:185], v[56:59]
	v_mfma_f32_16x16x32_bf16 v[44:47], v[150:153], v[190:193], v[44:47]
	v_mfma_f32_16x16x32_bf16 v[40:43], v[158:161], v[190:193], v[40:43]
	v_mfma_f32_16x16x32_bf16 v[28:31], v[150:153], v[198:201], v[28:31]
	v_mfma_f32_16x16x32_bf16 v[24:27], v[158:161], v[198:201], v[24:27]
	v_mfma_f32_16x16x32_bf16 v[12:15], v[150:153], v[208:211], v[12:15]
	v_mfma_f32_16x16x32_bf16 v[8:11], v[158:161], v[208:211], v[8:11]
	v_mfma_f32_16x16x32_bf16 v[60:63], v[154:157], v[186:189], v[60:63]
	v_mfma_f32_16x16x32_bf16 v[56:59], v[162:165], v[186:189], v[56:59]
	v_mfma_f32_16x16x32_bf16 v[44:47], v[154:157], v[194:197], v[44:47]
	v_mfma_f32_16x16x32_bf16 v[40:43], v[162:165], v[194:197], v[40:43]
	v_mfma_f32_16x16x32_bf16 v[28:31], v[154:157], v[202:205], v[28:31]
	v_mfma_f32_16x16x32_bf16 v[24:27], v[162:165], v[202:205], v[24:27]
	v_mfma_f32_16x16x32_bf16 v[12:15], v[154:157], v[212:215], v[12:15]
	v_mfma_f32_16x16x32_bf16 v[8:11], v[162:165], v[212:215], v[8:11]
	v_mfma_f32_16x16x32_bf16 v[52:55], v[166:169], v[182:185], v[52:55]
	v_mfma_f32_16x16x32_bf16 v[48:51], v[174:177], v[182:185], v[48:51]
	v_mfma_f32_16x16x32_bf16 v[36:39], v[166:169], v[190:193], v[36:39]
	v_mfma_f32_16x16x32_bf16 v[32:35], v[174:177], v[190:193], v[32:35]
	v_mfma_f32_16x16x32_bf16 v[20:23], v[166:169], v[198:201], v[20:23]
	v_mfma_f32_16x16x32_bf16 v[16:19], v[174:177], v[198:201], v[16:19]
	v_mfma_f32_16x16x32_bf16 v[4:7], v[166:169], v[208:211], v[4:7]
	v_mfma_f32_16x16x32_bf16 v[0:3], v[174:177], v[208:211], v[0:3]
	v_mfma_f32_16x16x32_bf16 v[52:55], v[170:173], v[186:189], v[52:55]
	v_mfma_f32_16x16x32_bf16 v[48:51], v[178:181], v[186:189], v[48:51]
	v_mfma_f32_16x16x32_bf16 v[36:39], v[170:173], v[194:197], v[36:39]
	v_mfma_f32_16x16x32_bf16 v[32:35], v[178:181], v[194:197], v[32:35]
	v_mfma_f32_16x16x32_bf16 v[20:23], v[170:173], v[202:205], v[20:23]
	v_mfma_f32_16x16x32_bf16 v[16:19], v[178:181], v[202:205], v[16:19]
	v_mfma_f32_16x16x32_bf16 v[4:7], v[170:173], v[212:215], v[4:7]
	v_mfma_f32_16x16x32_bf16 v[0:3], v[178:181], v[212:215], v[0:3]
	s_setprio 0
	s_barrier
	s_add_i32 s76, s76, 2
	s_add_u32 s38, s38, 0x100
	s_addc_u32 s39, s39, 0
	s_add_u32 s74, s74, 0x100
	s_addc_u32 s75, s75, 0
	s_cmp_gt_u32 s76, 13
	s_cbranch_scc0 .LBB0_1052
	s_branch .Lpeel_exit_7
.LBB0_1052:
	ds_read_b128 v[150:153], v147
	ds_read_b128 v[154:157], v147 offset:1024
	ds_read_b128 v[158:161], v147 offset:2048
	ds_read_b128 v[162:165], v147 offset:3072
	ds_read_b128 v[166:169], v148
	ds_read_b128 v[170:173], v148 offset:1024
	ds_read_b128 v[174:177], v148 offset:2048
	ds_read_b128 v[178:181], v148 offset:3072
	s_add_u32 s40, s38, 0xfffc0080
	s_addc_u32 s41, s39, -1
	s_cmp_eq_u32 s76, 12
	s_cselect_b32 s43, s21, s41
	s_cselect_b32 s42, s72, s40
	s_cselect_b32 s41, s23, s75
	s_cselect_b32 s40, s73, s74
	v_lshl_add_u64 v[142:143], s[38:39], 0, v[136:137]
	s_add_i32 m0, s31, 0xc000
	ds_read_b128 v[182:185], v149
	ds_read_b128 v[186:189], v149 offset:1024
	ds_read_b128 v[190:193], v149 offset:2048
	ds_read_b128 v[194:197], v149 offset:3072
	ds_read_b128 v[198:201], v149 offset:4096
	ds_read_b128 v[202:205], v149 offset:5120
	ds_read_b128 v[208:211], v149 offset:6144
	ds_read_b128 v[212:215], v149 offset:7168
	global_load_lds_dwordx4 v[142:143], off
	v_lshl_add_u64 v[142:143], s[38:39], 0, v[138:139]
	s_add_i32 m0, s31, 0xe000
	s_nop 0
	global_load_lds_dwordx4 v[142:143], off
	s_waitcnt vmcnt(8)
	s_waitcnt lgkmcnt(0)
	s_barrier
; #define PG8_STAGE(bufoff, gbase, voff) do { _Pragma("unroll") for (int _i = 0; _i < 2; ++_i) \
;         __builtin_amdgcn_global_load_lds((const unsigned*)((const char*)(gbase) + (voff)[_i]), (PG8_LAS unsigned*)(lds + (bufoff) + ldsw + _i * 8192), 16, 0, 0); } while (0)
; #define PG8_LDA(dst, b, h) do { _Pragma("unroll") for (int m = 0; m < 4; ++m) _Pragma("unroll") for (int k = 0; k < 2; ++k) dst[m][k] = *(const PG8_LAS bf16x8*)(lds + PG8_SA(b, h) + aoff + m * 2048 + k * 1024); } while (0)
; #define PG8_MMA(ai, bj, At, Bt) do { __builtin_amdgcn_s_setprio(1); _Pragma("unroll") for (int m = 0; m < 4; ++m) _Pragma("unroll") for (int n = 0; n < 2; ++n) _Pragma("unroll") for (int k = 0; k < 2; ++k) \
;         acc[ai][bj][m][n] = __builtin_amdgcn_mfma_f32_16x16x32_bf16(Bt[n][k], At[m][k], acc[ai][bj][m][n], 0, 0, 0); __builtin_amdgcn_s_setprio(0); } while (0)
; #define PG8_WAIT_V(n) asm volatile("s_waitcnt vmcnt(" #n ")" ::: "memory")
; #define PG8_WAIT_L(n) asm volatile("s_waitcnt lgkmcnt(" #n ")" ::: "memory")
; #define PG8_BAR __builtin_amdgcn_s_barrier()
; #define PG8_SCHED __builtin_amdgcn_sched_barrier(0)
; template <class Epi, class Sched, bool ALIGN_EPI = false, bool SP2 = false>
; __device__ __forceinline__ void gemm_phase(PG8_LAS unsigned char* lds, const Gemm g, const Sched& S, const Epi& E) {
;     ...
;             PG8_WAIT_V(8); PG8_WAIT_L(0); PG8_BAR; PG8_MMA(0, 0, At, B0); PG8_MMA(0, 1, At, B1); PG8_BAR; PG8_SCHED;
;             PG8_LDA(At, 0, 1); PG8_STAGE(PG8_SB(0, 0), b2, voffB); PG8_STAGE(PG8_SB(0, 1), b2 + hstep, voffB); PG8_STAGE(PG8_SA(0, 0), a2, voffA);
;             PG8_WAIT_V(8); PG8_WAIT_L(0); PG8_BAR; PG8_MMA(1, 0, At, B0); PG8_MMA(1, 1, At, B1); PG8_BAR; PG8_SCHED;
	s_setprio 1
	s_waitcnt lgkmcnt(0)
	v_mfma_f32_16x16x32_bf16 v[124:127], v[150:153], v[182:185], v[124:127]
	v_mfma_f32_16x16x32_bf16 v[120:123], v[158:161], v[182:185], v[120:123]
	v_mfma_f32_16x16x32_bf16 v[108:111], v[150:153], v[190:193], v[108:111]
	v_mfma_f32_16x16x32_bf16 v[104:107], v[158:161], v[190:193], v[104:107]
	v_mfma_f32_16x16x32_bf16 v[92:95], v[150:153], v[198:201], v[92:95]
	v_mfma_f32_16x16x32_bf16 v[88:91], v[158:161], v[198:201], v[88:91]
	v_mfma_f32_16x16x32_bf16 v[76:79], v[150:153], v[208:211], v[76:79]
	v_mfma_f32_16x16x32_bf16 v[72:75], v[158:161], v[208:211], v[72:75]
	v_mfma_f32_16x16x32_bf16 v[124:127], v[154:157], v[186:189], v[124:127]
	v_mfma_f32_16x16x32_bf16 v[120:123], v[162:165], v[186:189], v[120:123]
	v_mfma_f32_16x16x32_bf16 v[108:111], v[154:157], v[194:197], v[108:111]
	v_mfma_f32_16x16x32_bf16 v[104:107], v[162:165], v[194:197], v[104:107]
	v_mfma_f32_16x16x32_bf16 v[92:95], v[154:157], v[202:205], v[92:95]
	v_mfma_f32_16x16x32_bf16 v[88:91], v[162:165], v[202:205], v[88:91]
	v_mfma_f32_16x16x32_bf16 v[76:79], v[154:157], v[212:215], v[76:79]
	v_mfma_f32_16x16x32_bf16 v[72:75], v[162:165], v[212:215], v[72:75]
	v_mfma_f32_16x16x32_bf16 v[116:119], v[166:169], v[182:185], v[116:119]
	v_mfma_f32_16x16x32_bf16 v[112:115], v[174:177], v[182:185], v[112:115]
	v_mfma_f32_16x16x32_bf16 v[100:103], v[166:169], v[190:193], v[100:103]
	v_mfma_f32_16x16x32_bf16 v[96:99], v[174:177], v[190:193], v[96:99]
	v_mfma_f32_16x16x32_bf16 v[84:87], v[166:169], v[198:201], v[84:87]
	v_mfma_f32_16x16x32_bf16 v[80:83], v[174:177], v[198:201], v[80:83]
	v_mfma_f32_16x16x32_bf16 v[68:71], v[166:169], v[208:211], v[68:71]
	v_mfma_f32_16x16x32_bf16 v[64:67], v[174:177], v[208:211], v[64:67]
	v_mfma_f32_16x16x32_bf16 v[116:119], v[170:173], v[186:189], v[116:119]
	v_mfma_f32_16x16x32_bf16 v[112:115], v[178:181], v[186:189], v[112:115]
	v_mfma_f32_16x16x32_bf16 v[100:103], v[170:173], v[194:197], v[100:103]
	v_mfma_f32_16x16x32_bf16 v[96:99], v[178:181], v[194:197], v[96:99]
	v_mfma_f32_16x16x32_bf16 v[84:87], v[170:173], v[202:205], v[84:87]
	v_mfma_f32_16x16x32_bf16 v[80:83], v[178:181], v[202:205], v[80:83]
	v_mfma_f32_16x16x32_bf16 v[68:71], v[170:173], v[212:215], v[68:71]
	v_mfma_f32_16x16x32_bf16 v[64:67], v[178:181], v[212:215], v[64:67]
	s_setprio 0
	s_barrier
	s_add_i32 s77, s67, s57
	v_lshl_add_u64 v[142:143], s[40:41], 0, v[130:131]
	s_mov_b32 m0, s77
	ds_read_b128 v[182:185], v149 offset:16384
	ds_read_b128 v[186:189], v149 offset:17408
	ds_read_b128 v[190:193], v149 offset:18432
	ds_read_b128 v[194:197], v149 offset:19456
	ds_read_b128 v[198:201], v149 offset:20480
	ds_read_b128 v[202:205], v149 offset:21504
	ds_read_b128 v[208:211], v149 offset:22528
	ds_read_b128 v[212:215], v149 offset:23552
	global_load_lds_dwordx4 v[142:143], off
	s_add_i32 m0, s77, 0x2000
	s_add_u32 s78, s40, 0x40000
	v_lshl_add_u64 v[216:217], s[40:41], 0, v[134:135]
	s_addc_u32 s79, s41, 0
	s_add_i32 s77, s68, s57
	global_load_lds_dwordx4 v[216:217], off
	v_lshl_add_u64 v[218:219], s[78:79], 0, v[130:131]
	s_mov_b32 m0, s77
	v_lshl_add_u64 v[220:221], s[42:43], 0, v[132:133]
	global_load_lds_dwordx4 v[218:219], off
	v_lshl_add_u64 v[218:219], s[78:79], 0, v[134:135]
	s_add_i32 m0, s77, 0x2000
	s_nop 0
	global_load_lds_dwordx4 v[218:219], off
	v_lshl_add_u64 v[218:219], s[42:43], 0, v[128:129]
	s_mov_b32 m0, s31
	s_nop 0
	global_load_lds_dwordx4 v[218:219], off
	s_mov_b32 m0, s59
	s_nop 0
	global_load_lds_dwordx4 v[220:221], off
	s_waitcnt vmcnt(8)
	s_waitcnt lgkmcnt(0)
	s_barrier
	s_setprio 1
	s_waitcnt lgkmcnt(0)
	v_mfma_f32_16x16x32_bf16 v[60:63], v[150:153], v[182:185], v[60:63]
	v_mfma_f32_16x16x32_bf16 v[56:59], v[158:161], v[182:185], v[56:59]
	v_mfma_f32_16x16x32_bf16 v[44:47], v[150:153], v[190:193], v[44:47]
	v_mfma_f32_16x16x32_bf16 v[40:43], v[158:161], v[190:193], v[40:43]
	v_mfma_f32_16x16x32_bf16 v[28:31], v[150:153], v[198:201], v[28:31]
	v_mfma_f32_16x16x32_bf16 v[24:27], v[158:161], v[198:201], v[24:27]
	v_mfma_f32_16x16x32_bf16 v[12:15], v[150:153], v[208:211], v[12:15]
	v_mfma_f32_16x16x32_bf16 v[8:11], v[158:161], v[208:211], v[8:11]
	v_mfma_f32_16x16x32_bf16 v[60:63], v[154:157], v[186:189], v[60:63]
	v_mfma_f32_16x16x32_bf16 v[56:59], v[162:165], v[186:189], v[56:59]
	v_mfma_f32_16x16x32_bf16 v[44:47], v[154:157], v[194:197], v[44:47]
	v_mfma_f32_16x16x32_bf16 v[40:43], v[162:165], v[194:197], v[40:43]
	v_mfma_f32_16x16x32_bf16 v[28:31], v[154:157], v[202:205], v[28:31]
	v_mfma_f32_16x16x32_bf16 v[24:27], v[162:165], v[202:205], v[24:27]
	v_mfma_f32_16x16x32_bf16 v[12:15], v[154:157], v[212:215], v[12:15]
	v_mfma_f32_16x16x32_bf16 v[8:11], v[162:165], v[212:215], v[8:11]
	v_mfma_f32_16x16x32_bf16 v[52:55], v[166:169], v[182:185], v[52:55]
	v_mfma_f32_16x16x32_bf16 v[48:51], v[174:177], v[182:185], v[48:51]
	v_mfma_f32_16x16x32_bf16 v[36:39], v[166:169], v[190:193], v[36:39]
	v_mfma_f32_16x16x32_bf16 v[32:35], v[174:177], v[190:193], v[32:35]
	v_mfma_f32_16x16x32_bf16 v[20:23], v[166:169], v[198:201], v[20:23]
	v_mfma_f32_16x16x32_bf16 v[16:19], v[174:177], v[198:201], v[16:19]
	v_mfma_f32_16x16x32_bf16 v[4:7], v[166:169], v[208:211], v[4:7]
	v_mfma_f32_16x16x32_bf16 v[0:3], v[174:177], v[208:211], v[0:3]
	v_mfma_f32_16x16x32_bf16 v[52:55], v[170:173], v[186:189], v[52:55]
	v_mfma_f32_16x16x32_bf16 v[48:51], v[178:181], v[186:189], v[48:51]
	v_mfma_f32_16x16x32_bf16 v[36:39], v[170:173], v[194:197], v[36:39]
	v_mfma_f32_16x16x32_bf16 v[32:35], v[178:181], v[194:197], v[32:35]
	v_mfma_f32_16x16x32_bf16 v[20:23], v[170:173], v[202:205], v[20:23]
	v_mfma_f32_16x16x32_bf16 v[16:19], v[178:181], v[202:205], v[16:19]
	v_mfma_f32_16x16x32_bf16 v[4:7], v[170:173], v[212:215], v[4:7]
	v_mfma_f32_16x16x32_bf16 v[0:3], v[178:181], v[212:215], v[0:3]
	s_setprio 0
	s_barrier
; #define PG8_STAGE(bufoff, gbase, voff) do { _Pragma("unroll") for (int _i = 0; _i < 2; ++_i) \
;         __builtin_amdgcn_global_load_lds((const unsigned*)((const char*)(gbase) + (voff)[_i]), (PG8_LAS unsigned*)(lds + (bufoff) + ldsw + _i * 8192), 16, 0, 0); } while (0)
; #define PG8_LDA(dst, b, h) do { _Pragma("unroll") for (int m = 0; m < 4; ++m) _Pragma("unroll") for (int k = 0; k < 2; ++k) dst[m][k] = *(const PG8_LAS bf16x8*)(lds + PG8_SA(b, h) + aoff + m * 2048 + k * 1024); } while (0)
; #define PG8_LDB(dst, b, h) do { _Pragma("unroll") for (int n = 0; n < 2; ++n) _Pragma("unroll") for (int k = 0; k < 2; ++k) dst[n][k] = *(const PG8_LAS bf16x8*)(lds + PG8_SB(b, h) + boff + n * 2048 + k * 1024); } while (0)
; #define PG8_MMA(ai, bj, At, Bt) do { __builtin_amdgcn_s_setprio(1); _Pragma("unroll") for (int m = 0; m < 4; ++m) _Pragma("unroll") for (int n = 0; n < 2; ++n) _Pragma("unroll") for (int k = 0; k < 2; ++k) \
;         acc[ai][bj][m][n] = __builtin_amdgcn_mfma_f32_16x16x32_bf16(Bt[n][k], At[m][k], acc[ai][bj][m][n], 0, 0, 0); __builtin_amdgcn_s_setprio(0); } while (0)
; #define PG8_WAIT_V(n) asm volatile("s_waitcnt vmcnt(" #n ")" ::: "memory")
; #define PG8_WAIT_L(n) asm volatile("s_waitcnt lgkmcnt(" #n ")" ::: "memory")
; #define PG8_BAR __builtin_amdgcn_s_barrier()
; #define PG8_SCHED __builtin_amdgcn_sched_barrier(0)
; template <class Epi, class Sched, bool ALIGN_EPI = false, bool SP2 = false>
; __device__ __forceinline__ void gemm_phase(PG8_LAS unsigned char* lds, const Gemm g, const Sched& S, const Epi& E) {
;     ...
;             PG8_LDB(B0, 1, 0); PG8_LDB(B1, 1, 1); PG8_SCHED; PG8_LDA(At, 1, 0); PG8_STAGE(PG8_SA(0, 1), a2 + hstep, voffA);
;             PG8_WAIT_V(8); PG8_WAIT_L(0); PG8_BAR; PG8_MMA(0, 0, At, B0); PG8_MMA(0, 1, At, B1); PG8_BAR; PG8_SCHED;
	s_add_i32 s77, 0, 0x18000
	s_add_i32 s78, 0, 0x1c000
	v_add_u32_e32 v162, s77, v145
	v_add_u32_e32 v178, s78, v145
	ds_read_b128 v[150:153], v162
	ds_read_b128 v[154:157], v162 offset:1024
	ds_read_b128 v[158:161], v162 offset:2048
	ds_read_b128 v[162:165], v162 offset:3072
	ds_read_b128 v[166:169], v178
	ds_read_b128 v[170:173], v178 offset:1024
	ds_read_b128 v[174:177], v178 offset:2048
	ds_read_b128 v[178:181], v178 offset:3072
	s_add_u32 s42, s42, 0x40000
	s_addc_u32 s43, s43, 0
	s_mov_b32 m0, s60
	v_lshl_add_u64 v[222:223], s[42:43], 0, v[128:129]
	ds_read_b128 v[182:185], v149 offset:32768
	ds_read_b128 v[186:189], v149 offset:33792
	ds_read_b128 v[190:193], v149 offset:34816
	ds_read_b128 v[194:197], v149 offset:35840
	ds_read_b128 v[198:201], v149 offset:36864
	ds_read_b128 v[202:205], v149 offset:37888
	ds_read_b128 v[208:211], v149 offset:38912
	ds_read_b128 v[212:215], v149 offset:39936
	global_load_lds_dwordx4 v[222:223], off
	v_lshl_add_u64 v[222:223], s[42:43], 0, v[132:133]
	s_mov_b32 m0, s61
	s_nop 0
	global_load_lds_dwordx4 v[222:223], off
	s_waitcnt vmcnt(8)
	s_waitcnt lgkmcnt(0)
	s_barrier
	s_setprio 1
	s_waitcnt lgkmcnt(0)
	v_mfma_f32_16x16x32_bf16 v[124:127], v[150:153], v[182:185], v[124:127]
	v_mfma_f32_16x16x32_bf16 v[120:123], v[158:161], v[182:185], v[120:123]
	v_mfma_f32_16x16x32_bf16 v[108:111], v[150:153], v[190:193], v[108:111]
	v_mfma_f32_16x16x32_bf16 v[104:107], v[158:161], v[190:193], v[104:107]
	v_mfma_f32_16x16x32_bf16 v[92:95], v[150:153], v[198:201], v[92:95]
	v_mfma_f32_16x16x32_bf16 v[88:91], v[158:161], v[198:201], v[88:91]
	v_mfma_f32_16x16x32_bf16 v[76:79], v[150:153], v[208:211], v[76:79]
	v_mfma_f32_16x16x32_bf16 v[72:75], v[158:161], v[208:211], v[72:75]
	v_mfma_f32_16x16x32_bf16 v[124:127], v[154:157], v[186:189], v[124:127]
	v_mfma_f32_16x16x32_bf16 v[120:123], v[162:165], v[186:189], v[120:123]
	v_mfma_f32_16x16x32_bf16 v[108:111], v[154:157], v[194:197], v[108:111]
	v_mfma_f32_16x16x32_bf16 v[104:107], v[162:165], v[194:197], v[104:107]
	v_mfma_f32_16x16x32_bf16 v[92:95], v[154:157], v[202:205], v[92:95]
	v_mfma_f32_16x16x32_bf16 v[88:91], v[162:165], v[202:205], v[88:91]
	v_mfma_f32_16x16x32_bf16 v[76:79], v[154:157], v[212:215], v[76:79]
	v_mfma_f32_16x16x32_bf16 v[72:75], v[162:165], v[212:215], v[72:75]
	v_mfma_f32_16x16x32_bf16 v[116:119], v[166:169], v[182:185], v[116:119]
	v_mfma_f32_16x16x32_bf16 v[112:115], v[174:177], v[182:185], v[112:115]
	v_mfma_f32_16x16x32_bf16 v[100:103], v[166:169], v[190:193], v[100:103]
	v_mfma_f32_16x16x32_bf16 v[96:99], v[174:177], v[190:193], v[96:99]
	v_mfma_f32_16x16x32_bf16 v[84:87], v[166:169], v[198:201], v[84:87]
	v_mfma_f32_16x16x32_bf16 v[80:83], v[174:177], v[198:201], v[80:83]
	v_mfma_f32_16x16x32_bf16 v[68:71], v[166:169], v[208:211], v[68:71]
	v_mfma_f32_16x16x32_bf16 v[64:67], v[174:177], v[208:211], v[64:67]
	v_mfma_f32_16x16x32_bf16 v[116:119], v[170:173], v[186:189], v[116:119]
	v_mfma_f32_16x16x32_bf16 v[112:115], v[178:181], v[186:189], v[112:115]
	v_mfma_f32_16x16x32_bf16 v[100:103], v[170:173], v[194:197], v[100:103]
	v_mfma_f32_16x16x32_bf16 v[96:99], v[178:181], v[194:197], v[96:99]
	v_mfma_f32_16x16x32_bf16 v[84:87], v[170:173], v[202:205], v[84:87]
	v_mfma_f32_16x16x32_bf16 v[80:83], v[178:181], v[202:205], v[80:83]
	v_mfma_f32_16x16x32_bf16 v[68:71], v[170:173], v[212:215], v[68:71]
	v_mfma_f32_16x16x32_bf16 v[64:67], v[178:181], v[212:215], v[64:67]
	s_setprio 0
	s_barrier
; #define PG8_STAGE(bufoff, gbase, voff) do { _Pragma("unroll") for (int _i = 0; _i < 2; ++_i) \
;         __builtin_amdgcn_global_load_lds((const unsigned*)((const char*)(gbase) + (voff)[_i]), (PG8_LAS unsigned*)(lds + (bufoff) + ldsw + _i * 8192), 16, 0, 0); } while (0)
; #define PG8_LDA(dst, b, h) do { _Pragma("unroll") for (int m = 0; m < 4; ++m) _Pragma("unroll") for (int k = 0; k < 2; ++k) dst[m][k] = *(const PG8_LAS bf16x8*)(lds + PG8_SA(b, h) + aoff + m * 2048 + k * 1024); } while (0)
; #define PG8_MMA(ai, bj, At, Bt) do { __builtin_amdgcn_s_setprio(1); _Pragma("unroll") for (int m = 0; m < 4; ++m) _Pragma("unroll") for (int n = 0; n < 2; ++n) _Pragma("unroll") for (int k = 0; k < 2; ++k) \
;         acc[ai][bj][m][n] = __builtin_amdgcn_mfma_f32_16x16x32_bf16(Bt[n][k], At[m][k], acc[ai][bj][m][n], 0, 0, 0); __builtin_amdgcn_s_setprio(0); } while (0)
; #define PG8_WAIT_V(n) asm volatile("s_waitcnt vmcnt(" #n ")" ::: "memory")
; #define PG8_WAIT_L(n) asm volatile("s_waitcnt lgkmcnt(" #n ")" ::: "memory")
; #define PG8_BAR __builtin_amdgcn_s_barrier()
; #define PG8_SCHED __builtin_amdgcn_sched_barrier(0)
; template <class Epi, class Sched, bool ALIGN_EPI = false, bool SP2 = false>
; __device__ __forceinline__ void gemm_phase(PG8_LAS unsigned char* lds, const Gemm g, const Sched& S, const Epi& E) {
;     ...
;         for (int t = 0; t < nt; t += 2) {
;             const bool last = (t == nt - 2);
;             const char* a1 = cA + (size_t)(t + 1) * kstep;
;             const char* a2 = last ? nA : cA + (size_t)(t + 2) * kstep; const char* b2 = last ? nB : cB + (size_t)(t + 2) * kstep;
;             const char* a3 = a2 + kstep; const char* b3 = b2 + kstep;
;     ...
;             PG8_LDA(At, 1, 1); PG8_STAGE(PG8_SB(1, 0), b3, voffB); PG8_STAGE(PG8_SB(1, 1), b3 + hstep, voffB); PG8_STAGE(PG8_SA(1, 0), a3, voffA);
;             PG8_WAIT_V(8); PG8_WAIT_L(0); PG8_BAR; PG8_MMA(1, 0, At, B0); PG8_MMA(1, 1, At, B1); PG8_BAR; PG8_SCHED;
	s_add_i32 s42, s77, s57
	v_lshl_add_u64 v[142:143], v[142:143], 0, s[8:9]
	s_mov_b32 m0, s42
	ds_read_b128 v[182:185], v149 offset:49152
	ds_read_b128 v[186:189], v149 offset:50176
	ds_read_b128 v[190:193], v149 offset:51200
	ds_read_b128 v[194:197], v149 offset:52224
	ds_read_b128 v[198:201], v149 offset:53248
	ds_read_b128 v[202:205], v149 offset:54272
	ds_read_b128 v[208:211], v149 offset:55296
	ds_read_b128 v[212:215], v149 offset:56320
	global_load_lds_dwordx4 v[142:143], off
	s_add_i32 m0, s42, 0x2000
	s_add_u32 s40, s40, 0x40080
	v_lshl_add_u64 v[142:143], v[216:217], 0, s[8:9]
	s_addc_u32 s41, s41, 0
	s_add_i32 s42, s78, s57
	global_load_lds_dwordx4 v[142:143], off
	v_lshl_add_u64 v[142:143], s[40:41], 0, v[130:131]
	s_mov_b32 m0, s42
	s_nop 0
	global_load_lds_dwordx4 v[142:143], off
	v_lshl_add_u64 v[142:143], s[40:41], 0, v[134:135]
	s_add_i32 m0, s42, 0x2000
	s_nop 0
	global_load_lds_dwordx4 v[142:143], off
	v_lshl_add_u64 v[142:143], v[218:219], 0, s[8:9]
	s_mov_b32 m0, s65
	s_nop 0
	global_load_lds_dwordx4 v[142:143], off
	v_lshl_add_u64 v[142:143], v[220:221], 0, s[8:9]
	s_mov_b32 m0, s66
	s_nop 0
	global_load_lds_dwordx4 v[142:143], off
	s_waitcnt vmcnt(8)
	s_waitcnt lgkmcnt(0)
	s_barrier
	s_setprio 1
	s_waitcnt lgkmcnt(0)
	v_mfma_f32_16x16x32_bf16 v[60:63], v[150:153], v[182:185], v[60:63]
	v_mfma_f32_16x16x32_bf16 v[56:59], v[158:161], v[182:185], v[56:59]
	v_mfma_f32_16x16x32_bf16 v[44:47], v[150:153], v[190:193], v[44:47]
	v_mfma_f32_16x16x32_bf16 v[40:43], v[158:161], v[190:193], v[40:43]
	v_mfma_f32_16x16x32_bf16 v[28:31], v[150:153], v[198:201], v[28:31]
	v_mfma_f32_16x16x32_bf16 v[24:27], v[158:161], v[198:201], v[24:27]
	v_mfma_f32_16x16x32_bf16 v[12:15], v[150:153], v[208:211], v[12:15]
	v_mfma_f32_16x16x32_bf16 v[8:11], v[158:161], v[208:211], v[8:11]
	v_mfma_f32_16x16x32_bf16 v[60:63], v[154:157], v[186:189], v[60:63]
	v_mfma_f32_16x16x32_bf16 v[56:59], v[162:165], v[186:189], v[56:59]
	v_mfma_f32_16x16x32_bf16 v[44:47], v[154:157], v[194:197], v[44:47]
	v_mfma_f32_16x16x32_bf16 v[40:43], v[162:165], v[194:197], v[40:43]
	v_mfma_f32_16x16x32_bf16 v[28:31], v[154:157], v[202:205], v[28:31]
	v_mfma_f32_16x16x32_bf16 v[24:27], v[162:165], v[202:205], v[24:27]
	v_mfma_f32_16x16x32_bf16 v[12:15], v[154:157], v[212:215], v[12:15]
	v_mfma_f32_16x16x32_bf16 v[8:11], v[162:165], v[212:215], v[8:11]
	v_mfma_f32_16x16x32_bf16 v[52:55], v[166:169], v[182:185], v[52:55]
	v_mfma_f32_16x16x32_bf16 v[48:51], v[174:177], v[182:185], v[48:51]
	v_mfma_f32_16x16x32_bf16 v[36:39], v[166:169], v[190:193], v[36:39]
	v_mfma_f32_16x16x32_bf16 v[32:35], v[174:177], v[190:193], v[32:35]
	v_mfma_f32_16x16x32_bf16 v[20:23], v[166:169], v[198:201], v[20:23]
	v_mfma_f32_16x16x32_bf16 v[16:19], v[174:177], v[198:201], v[16:19]
	v_mfma_f32_16x16x32_bf16 v[4:7], v[166:169], v[208:211], v[4:7]
	v_mfma_f32_16x16x32_bf16 v[0:3], v[174:177], v[208:211], v[0:3]
	v_mfma_f32_16x16x32_bf16 v[52:55], v[170:173], v[186:189], v[52:55]
	v_mfma_f32_16x16x32_bf16 v[48:51], v[178:181], v[186:189], v[48:51]
	v_mfma_f32_16x16x32_bf16 v[36:39], v[170:173], v[194:197], v[36:39]
	v_mfma_f32_16x16x32_bf16 v[32:35], v[178:181], v[194:197], v[32:35]
	v_mfma_f32_16x16x32_bf16 v[20:23], v[170:173], v[202:205], v[20:23]
	v_mfma_f32_16x16x32_bf16 v[16:19], v[178:181], v[202:205], v[16:19]
	v_mfma_f32_16x16x32_bf16 v[4:7], v[170:173], v[212:215], v[4:7]
	v_mfma_f32_16x16x32_bf16 v[0:3], v[178:181], v[212:215], v[0:3]
	s_setprio 0
	s_barrier
	s_add_i32 s76, s76, 2
	s_add_u32 s38, s38, 0x100
	s_addc_u32 s39, s39, 0
	s_add_u32 s74, s74, 0x100
	s_addc_u32 s75, s75, 0
	s_cmp_gt_u32 s76, 13
	s_cbranch_scc0 .LBB0_1052

;     __device__ __forceinline__ bool next(int i, Unit& u) const { if (i != 0) return false; const int c0 = (G >= 8) ? G - 5 : G - 2; int k = -1; if (c == c0) k = 0; else if (c == G - 1) k = 1; if (k < 0 || k >= n) return false; u.pm = k; u.pn = 0; return true; }
; #define PG8_STAGE(bufoff, gbase, voff) do { _Pragma("unroll") for (int _i = 0; _i < 2; ++_i) \
;         __builtin_amdgcn_global_load_lds((const unsigned*)((const char*)(gbase) + (voff)[_i]), (PG8_LAS unsigned*)(lds + (bufoff) + ldsw + _i * 8192), 16, 0, 0); } while (0)
; #define PG8_LDA(dst, b, h) do { _Pragma("unroll") for (int m = 0; m < 4; ++m) _Pragma("unroll") for (int k = 0; k < 2; ++k) dst[m][k] = *(const PG8_LAS bf16x8*)(lds + PG8_SA(b, h) + aoff + m * 2048 + k * 1024); } while (0)
; #define PG8_LDB(dst, b, h) do { _Pragma("unroll") for (int n = 0; n < 2; ++n) _Pragma("unroll") for (int k = 0; k < 2; ++k) dst[n][k] = *(const PG8_LAS bf16x8*)(lds + PG8_SB(b, h) + boff + n * 2048 + k * 1024); } while (0)
; #define PG8_WAIT_V(n) asm volatile("s_waitcnt vmcnt(" #n ")" ::: "memory")
; #define PG8_WAIT_L(n) asm volatile("s_waitcnt lgkmcnt(" #n ")" ::: "memory")
; #define PG8_BAR __builtin_amdgcn_s_barrier()
; #define PG8_SCHED __builtin_amdgcn_sched_barrier(0)
; template <class Epi, class Sched, bool ALIGN_EPI = false, bool SP2 = false>
; __device__ __forceinline__ void gemm_phase(PG8_LAS unsigned char* lds, const Gemm g, const Sched& S, const Epi& E) {
;     ...
;         const bool has_next = S.next(ui + 1, nxt);
;         const char* nA = has_next ? (const char*)g.A + (size_t)nxt.pm * tstep : cA; const char* nB = has_next ? (const char*)g.Bt + (size_t)nxt.pn * tstep : cB;
;         for (int t = 0; t < nt; t += 2) {
;             const bool last = (t == nt - 2);
;             const char* a1 = cA + (size_t)(t + 1) * kstep;
;             const char* a2 = last ? nA : cA + (size_t)(t + 2) * kstep; const char* b2 = last ? nB : cB + (size_t)(t + 2) * kstep;
;             const char* a3 = a2 + kstep; const char* b3 = b2 + kstep;
;             if (last && has_next) S.a_ready(nxt);
;             if constexpr (SP2) {
;             PG8_LDB(B0, 0, 0); PG8_LDB(B1, 0, 1); PG8_SCHED; PG8_LDA(At, 0, 0); PG8_STAGE(PG8_SA(1, 1), a1 + hstep, voffA);
;             PG8_WAIT_V(8); PG8_WAIT_L(0); PG8_BAR; PG8_MMA(0, 0, At, B0); PG8_MMA(0, 1, At, B1); PG8_BAR; PG8_SCHED;
.LBB0_1162:
	s_add_u32 s46, s46, 0xb0080
	s_addc_u32 s47, s47, 0
	s_add_u32 s91, s56, 0x100
	v_mov_b32_e32 v0, 0
	s_addc_u32 s92, s57, 0
	s_mov_b32 s93, -2
	ds_read_b128 v[148:151], v145
	ds_read_b128 v[152:155], v145 offset:1024
	ds_read_b128 v[156:159], v145 offset:2048
	ds_read_b128 v[160:163], v145 offset:3072
	ds_read_b128 v[164:167], v146
	ds_read_b128 v[168:171], v146 offset:1024
	ds_read_b128 v[172:175], v146 offset:2048
	ds_read_b128 v[176:179], v146 offset:3072
	s_add_u32 s56, s46, 0xfff50080
	s_addc_u32 s57, s47, -1
	s_cmp_eq_u32 s93, 40
	s_cselect_b32 s59, s41, s57
	s_cselect_b32 s58, s40, s56
	s_cselect_b32 s57, s43, s92
	s_cselect_b32 s56, s42, s91
	v_lshl_add_u64 v[204:205], s[46:47], 0, v[136:137]
	s_add_i32 m0, s69, 0xc000
	ds_read_b128 v[180:183], v147
	ds_read_b128 v[184:187], v147 offset:1024
	ds_read_b128 v[188:191], v147 offset:2048
	ds_read_b128 v[192:195], v147 offset:3072
	ds_read_b128 v[196:199], v147 offset:4096
	ds_read_b128 v[200:203], v147 offset:5120
	ds_read_b128 v[208:211], v147 offset:6144
	ds_read_b128 v[212:215], v147 offset:7168
	global_load_lds_dwordx4 v[204:205], off
	v_lshl_add_u64 v[204:205], s[46:47], 0, v[138:139]
	s_add_i32 m0, s69, 0xe000
	s_nop 0
	global_load_lds_dwordx4 v[204:205], off
	s_waitcnt vmcnt(8)
	s_waitcnt lgkmcnt(0)
	s_barrier
	s_setprio 1
	s_waitcnt lgkmcnt(0)
	v_mfma_f32_16x16x32_bf16 v[124:127], v[148:151], v[180:183], 0
	v_mfma_f32_16x16x32_bf16 v[120:123], v[156:159], v[180:183], 0
	v_mfma_f32_16x16x32_bf16 v[116:119], v[148:151], v[188:191], 0
	v_mfma_f32_16x16x32_bf16 v[112:115], v[156:159], v[188:191], 0
	v_mfma_f32_16x16x32_bf16 v[100:103], v[148:151], v[196:199], 0
	v_mfma_f32_16x16x32_bf16 v[96:99], v[156:159], v[196:199], 0
	v_mfma_f32_16x16x32_bf16 v[84:87], v[148:151], v[208:211], 0
	v_mfma_f32_16x16x32_bf16 v[80:83], v[156:159], v[208:211], 0
	v_mfma_f32_16x16x32_bf16 v[124:127], v[152:155], v[184:187], v[124:127]
	v_mfma_f32_16x16x32_bf16 v[120:123], v[160:163], v[184:187], v[120:123]
	v_mfma_f32_16x16x32_bf16 v[116:119], v[152:155], v[192:195], v[116:119]
	v_mfma_f32_16x16x32_bf16 v[112:115], v[160:163], v[192:195], v[112:115]
	v_mfma_f32_16x16x32_bf16 v[100:103], v[152:155], v[200:203], v[100:103]
	v_mfma_f32_16x16x32_bf16 v[96:99], v[160:163], v[200:203], v[96:99]
	v_mfma_f32_16x16x32_bf16 v[84:87], v[152:155], v[212:215], v[84:87]
	v_mfma_f32_16x16x32_bf16 v[80:83], v[160:163], v[212:215], v[80:83]
	v_mfma_f32_16x16x32_bf16 v[108:111], v[164:167], v[180:183], 0
	v_mfma_f32_16x16x32_bf16 v[104:107], v[172:175], v[180:183], 0
	v_mfma_f32_16x16x32_bf16 v[92:95], v[164:167], v[188:191], 0
	v_mfma_f32_16x16x32_bf16 v[88:91], v[172:175], v[188:191], 0
	v_mfma_f32_16x16x32_bf16 v[76:79], v[164:167], v[196:199], 0
	v_mfma_f32_16x16x32_bf16 v[72:75], v[172:175], v[196:199], 0
	v_mfma_f32_16x16x32_bf16 v[68:71], v[164:167], v[208:211], 0
	v_mfma_f32_16x16x32_bf16 v[64:67], v[172:175], v[208:211], 0
	v_mfma_f32_16x16x32_bf16 v[108:111], v[168:171], v[184:187], v[108:111]
	v_mfma_f32_16x16x32_bf16 v[104:107], v[176:179], v[184:187], v[104:107]
	v_mfma_f32_16x16x32_bf16 v[92:95], v[168:171], v[192:195], v[92:95]
	v_mfma_f32_16x16x32_bf16 v[88:91], v[176:179], v[192:195], v[88:91]
	v_mfma_f32_16x16x32_bf16 v[76:79], v[168:171], v[200:203], v[76:79]
	v_mfma_f32_16x16x32_bf16 v[72:75], v[176:179], v[200:203], v[72:75]
	v_mfma_f32_16x16x32_bf16 v[68:71], v[168:171], v[212:215], v[68:71]
	v_mfma_f32_16x16x32_bf16 v[64:67], v[176:179], v[212:215], v[64:67]
	s_setprio 0
	s_barrier
	s_add_i32 s94, s77, s66
	v_lshl_add_u64 v[204:205], s[56:57], 0, v[130:131]
	s_mov_b32 m0, s94
	ds_read_b128 v[180:183], v147 offset:16384
	ds_read_b128 v[184:187], v147 offset:17408
	ds_read_b128 v[188:191], v147 offset:18432
	ds_read_b128 v[192:195], v147 offset:19456
	ds_read_b128 v[196:199], v147 offset:20480
	ds_read_b128 v[200:203], v147 offset:21504
	ds_read_b128 v[208:211], v147 offset:22528
	ds_read_b128 v[212:215], v147 offset:23552
	global_load_lds_dwordx4 v[204:205], off
	s_add_i32 m0, s94, 0x2000
	s_add_u32 s94, s56, 0xb0000
	v_lshl_add_u64 v[216:217], s[56:57], 0, v[134:135]
	s_addc_u32 s95, s57, 0
	s_add_i32 s96, s78, s66
	global_load_lds_dwordx4 v[216:217], off
	v_lshl_add_u64 v[218:219], s[94:95], 0, v[130:131]
	s_mov_b32 m0, s96
	v_lshl_add_u64 v[220:221], s[58:59], 0, v[132:133]
	global_load_lds_dwordx4 v[218:219], off
	v_lshl_add_u64 v[218:219], s[94:95], 0, v[134:135]
	s_add_i32 m0, s96, 0x2000
	s_nop 0
	global_load_lds_dwordx4 v[218:219], off
	v_lshl_add_u64 v[218:219], s[58:59], 0, v[128:129]
	s_mov_b32 m0, s69
	s_nop 0
	global_load_lds_dwordx4 v[218:219], off
	s_mov_b32 m0, s71
	s_nop 0
	global_load_lds_dwordx4 v[220:221], off
	s_waitcnt vmcnt(8)
	s_waitcnt lgkmcnt(0)
	s_barrier
; #define PG8_STAGE(bufoff, gbase, voff) do { _Pragma("unroll") for (int _i = 0; _i < 2; ++_i) \
;         __builtin_amdgcn_global_load_lds((const unsigned*)((const char*)(gbase) + (voff)[_i]), (PG8_LAS unsigned*)(lds + (bufoff) + ldsw + _i * 8192), 16, 0, 0); } while (0)
; #define PG8_LDA(dst, b, h) do { _Pragma("unroll") for (int m = 0; m < 4; ++m) _Pragma("unroll") for (int k = 0; k < 2; ++k) dst[m][k] = *(const PG8_LAS bf16x8*)(lds + PG8_SA(b, h) + aoff + m * 2048 + k * 1024); } while (0)
; #define PG8_LDB(dst, b, h) do { _Pragma("unroll") for (int n = 0; n < 2; ++n) _Pragma("unroll") for (int k = 0; k < 2; ++k) dst[n][k] = *(const PG8_LAS bf16x8*)(lds + PG8_SB(b, h) + boff + n * 2048 + k * 1024); } while (0)
; #define PG8_MMA(ai, bj, At, Bt) do { __builtin_amdgcn_s_setprio(1); _Pragma("unroll") for (int m = 0; m < 4; ++m) _Pragma("unroll") for (int n = 0; n < 2; ++n) _Pragma("unroll") for (int k = 0; k < 2; ++k) \
;         acc[ai][bj][m][n] = __builtin_amdgcn_mfma_f32_16x16x32_bf16(Bt[n][k], At[m][k], acc[ai][bj][m][n], 0, 0, 0); __builtin_amdgcn_s_setprio(0); } while (0)
; #define PG8_WAIT_V(n) asm volatile("s_waitcnt vmcnt(" #n ")" ::: "memory")
; #define PG8_WAIT_L(n) asm volatile("s_waitcnt lgkmcnt(" #n ")" ::: "memory")
; #define PG8_BAR __builtin_amdgcn_s_barrier()
; #define PG8_SCHED __builtin_amdgcn_sched_barrier(0)
; template <class Epi, class Sched, bool ALIGN_EPI = false, bool SP2 = false>
; __device__ __forceinline__ void gemm_phase(PG8_LAS unsigned char* lds, const Gemm g, const Sched& S, const Epi& E) {
;     ...
;             PG8_LDA(At, 0, 1); PG8_STAGE(PG8_SB(0, 0), b2, voffB); PG8_STAGE(PG8_SB(0, 1), b2 + hstep, voffB); PG8_STAGE(PG8_SA(0, 0), a2, voffA);
;             PG8_WAIT_V(8); PG8_WAIT_L(0); PG8_BAR; PG8_MMA(1, 0, At, B0); PG8_MMA(1, 1, At, B1); PG8_BAR; PG8_SCHED;
;             PG8_LDB(B0, 1, 0); PG8_LDB(B1, 1, 1); PG8_SCHED; PG8_LDA(At, 1, 0); PG8_STAGE(PG8_SA(0, 1), a2 + hstep, voffA);
;             PG8_WAIT_V(8); PG8_WAIT_L(0); PG8_BAR; PG8_MMA(0, 0, At, B0); PG8_MMA(0, 1, At, B1); PG8_BAR; PG8_SCHED;
	s_setprio 1
	s_waitcnt lgkmcnt(0)
	v_mfma_f32_16x16x32_bf16 v[60:63], v[148:151], v[180:183], 0
	v_mfma_f32_16x16x32_bf16 v[56:59], v[156:159], v[180:183], 0
	v_mfma_f32_16x16x32_bf16 v[52:55], v[148:151], v[188:191], 0
	v_mfma_f32_16x16x32_bf16 v[48:51], v[156:159], v[188:191], 0
	v_mfma_f32_16x16x32_bf16 v[36:39], v[148:151], v[196:199], 0
	v_mfma_f32_16x16x32_bf16 v[32:35], v[156:159], v[196:199], 0
	v_mfma_f32_16x16x32_bf16 v[20:23], v[148:151], v[208:211], 0
	v_mfma_f32_16x16x32_bf16 v[16:19], v[156:159], v[208:211], 0
	v_mfma_f32_16x16x32_bf16 v[60:63], v[152:155], v[184:187], v[60:63]
	v_mfma_f32_16x16x32_bf16 v[56:59], v[160:163], v[184:187], v[56:59]
	v_mfma_f32_16x16x32_bf16 v[52:55], v[152:155], v[192:195], v[52:55]
	v_mfma_f32_16x16x32_bf16 v[48:51], v[160:163], v[192:195], v[48:51]
	v_mfma_f32_16x16x32_bf16 v[36:39], v[152:155], v[200:203], v[36:39]
	v_mfma_f32_16x16x32_bf16 v[32:35], v[160:163], v[200:203], v[32:35]
	v_mfma_f32_16x16x32_bf16 v[20:23], v[152:155], v[212:215], v[20:23]
	v_mfma_f32_16x16x32_bf16 v[16:19], v[160:163], v[212:215], v[16:19]
	v_mfma_f32_16x16x32_bf16 v[44:47], v[164:167], v[180:183], 0
	v_mfma_f32_16x16x32_bf16 v[40:43], v[172:175], v[180:183], 0
	v_mfma_f32_16x16x32_bf16 v[28:31], v[164:167], v[188:191], 0
	v_mfma_f32_16x16x32_bf16 v[24:27], v[172:175], v[188:191], 0
	v_mfma_f32_16x16x32_bf16 v[12:15], v[164:167], v[196:199], 0
	v_mfma_f32_16x16x32_bf16 v[8:11], v[172:175], v[196:199], 0
	v_mfma_f32_16x16x32_bf16 v[4:7], v[164:167], v[208:211], 0
	v_mfma_f32_16x16x32_bf16 v[0:3], v[172:175], v[208:211], 0
	v_mfma_f32_16x16x32_bf16 v[44:47], v[168:171], v[184:187], v[44:47]
	v_mfma_f32_16x16x32_bf16 v[40:43], v[176:179], v[184:187], v[40:43]
	v_mfma_f32_16x16x32_bf16 v[28:31], v[168:171], v[192:195], v[28:31]
	v_mfma_f32_16x16x32_bf16 v[24:27], v[176:179], v[192:195], v[24:27]
	v_mfma_f32_16x16x32_bf16 v[12:15], v[168:171], v[200:203], v[12:15]
	v_mfma_f32_16x16x32_bf16 v[8:11], v[176:179], v[200:203], v[8:11]
	v_mfma_f32_16x16x32_bf16 v[4:7], v[168:171], v[212:215], v[4:7]
	v_mfma_f32_16x16x32_bf16 v[0:3], v[176:179], v[212:215], v[0:3]
	s_setprio 0
	s_barrier
	s_add_i32 s94, 0, 0x18000
	s_add_i32 s95, 0, 0x1c000
	v_add_u32_e32 v160, s94, v143
	v_add_u32_e32 v176, s95, v143
	ds_read_b128 v[148:151], v160
	ds_read_b128 v[152:155], v160 offset:1024
	ds_read_b128 v[156:159], v160 offset:2048
	ds_read_b128 v[160:163], v160 offset:3072
	ds_read_b128 v[164:167], v176
	ds_read_b128 v[168:171], v176 offset:1024
	ds_read_b128 v[172:175], v176 offset:2048
	ds_read_b128 v[176:179], v176 offset:3072
	s_add_u32 s58, s58, 0xb0000
	s_addc_u32 s59, s59, 0
	s_mov_b32 m0, s72
	v_lshl_add_u64 v[222:223], s[58:59], 0, v[128:129]
	ds_read_b128 v[180:183], v147 offset:32768
	ds_read_b128 v[184:187], v147 offset:33792
	ds_read_b128 v[188:191], v147 offset:34816
	ds_read_b128 v[192:195], v147 offset:35840
	ds_read_b128 v[196:199], v147 offset:36864
	ds_read_b128 v[200:203], v147 offset:37888
	ds_read_b128 v[208:211], v147 offset:38912
	ds_read_b128 v[212:215], v147 offset:39936
	global_load_lds_dwordx4 v[222:223], off
	v_lshl_add_u64 v[222:223], s[58:59], 0, v[132:133]
	s_mov_b32 m0, s73
	s_nop 0
	global_load_lds_dwordx4 v[222:223], off
	s_waitcnt vmcnt(8)
	s_waitcnt lgkmcnt(0)
	s_barrier
	s_setprio 1
	s_waitcnt lgkmcnt(0)
	v_mfma_f32_16x16x32_bf16 v[124:127], v[148:151], v[180:183], v[124:127]
	v_mfma_f32_16x16x32_bf16 v[120:123], v[156:159], v[180:183], v[120:123]
	v_mfma_f32_16x16x32_bf16 v[116:119], v[148:151], v[188:191], v[116:119]
	v_mfma_f32_16x16x32_bf16 v[112:115], v[156:159], v[188:191], v[112:115]
	v_mfma_f32_16x16x32_bf16 v[100:103], v[148:151], v[196:199], v[100:103]
	v_mfma_f32_16x16x32_bf16 v[96:99], v[156:159], v[196:199], v[96:99]
	v_mfma_f32_16x16x32_bf16 v[84:87], v[148:151], v[208:211], v[84:87]
	v_mfma_f32_16x16x32_bf16 v[80:83], v[156:159], v[208:211], v[80:83]
	v_mfma_f32_16x16x32_bf16 v[124:127], v[152:155], v[184:187], v[124:127]
	v_mfma_f32_16x16x32_bf16 v[120:123], v[160:163], v[184:187], v[120:123]
	v_mfma_f32_16x16x32_bf16 v[116:119], v[152:155], v[192:195], v[116:119]
	v_mfma_f32_16x16x32_bf16 v[112:115], v[160:163], v[192:195], v[112:115]
	v_mfma_f32_16x16x32_bf16 v[100:103], v[152:155], v[200:203], v[100:103]
	v_mfma_f32_16x16x32_bf16 v[96:99], v[160:163], v[200:203], v[96:99]
	v_mfma_f32_16x16x32_bf16 v[84:87], v[152:155], v[212:215], v[84:87]
	v_mfma_f32_16x16x32_bf16 v[80:83], v[160:163], v[212:215], v[80:83]
	v_mfma_f32_16x16x32_bf16 v[108:111], v[164:167], v[180:183], v[108:111]
	v_mfma_f32_16x16x32_bf16 v[104:107], v[172:175], v[180:183], v[104:107]
	v_mfma_f32_16x16x32_bf16 v[92:95], v[164:167], v[188:191], v[92:95]
	v_mfma_f32_16x16x32_bf16 v[88:91], v[172:175], v[188:191], v[88:91]
	v_mfma_f32_16x16x32_bf16 v[76:79], v[164:167], v[196:199], v[76:79]
	v_mfma_f32_16x16x32_bf16 v[72:75], v[172:175], v[196:199], v[72:75]
	v_mfma_f32_16x16x32_bf16 v[68:71], v[164:167], v[208:211], v[68:71]
	v_mfma_f32_16x16x32_bf16 v[64:67], v[172:175], v[208:211], v[64:67]
	v_mfma_f32_16x16x32_bf16 v[108:111], v[168:171], v[184:187], v[108:111]
	v_mfma_f32_16x16x32_bf16 v[104:107], v[176:179], v[184:187], v[104:107]
	v_mfma_f32_16x16x32_bf16 v[92:95], v[168:171], v[192:195], v[92:95]
	v_mfma_f32_16x16x32_bf16 v[88:91], v[176:179], v[192:195], v[88:91]
	v_mfma_f32_16x16x32_bf16 v[76:79], v[168:171], v[200:203], v[76:79]
	v_mfma_f32_16x16x32_bf16 v[72:75], v[176:179], v[200:203], v[72:75]
	v_mfma_f32_16x16x32_bf16 v[68:71], v[168:171], v[212:215], v[68:71]
	v_mfma_f32_16x16x32_bf16 v[64:67], v[176:179], v[212:215], v[64:67]
	s_setprio 0
	s_barrier
; #define PG8_STAGE(bufoff, gbase, voff) do { _Pragma("unroll") for (int _i = 0; _i < 2; ++_i) \
;         __builtin_amdgcn_global_load_lds((const unsigned*)((const char*)(gbase) + (voff)[_i]), (PG8_LAS unsigned*)(lds + (bufoff) + ldsw + _i * 8192), 16, 0, 0); } while (0)
; #define PG8_LDA(dst, b, h) do { _Pragma("unroll") for (int m = 0; m < 4; ++m) _Pragma("unroll") for (int k = 0; k < 2; ++k) dst[m][k] = *(const PG8_LAS bf16x8*)(lds + PG8_SA(b, h) + aoff + m * 2048 + k * 1024); } while (0)
; #define PG8_LDB(dst, b, h) do { _Pragma("unroll") for (int n = 0; n < 2; ++n) _Pragma("unroll") for (int k = 0; k < 2; ++k) dst[n][k] = *(const PG8_LAS bf16x8*)(lds + PG8_SB(b, h) + boff + n * 2048 + k * 1024); } while (0)
; #define PG8_MMA(ai, bj, At, Bt) do { __builtin_amdgcn_s_setprio(1); _Pragma("unroll") for (int m = 0; m < 4; ++m) _Pragma("unroll") for (int n = 0; n < 2; ++n) _Pragma("unroll") for (int k = 0; k < 2; ++k) \
;         acc[ai][bj][m][n] = __builtin_amdgcn_mfma_f32_16x16x32_bf16(Bt[n][k], At[m][k], acc[ai][bj][m][n], 0, 0, 0); __builtin_amdgcn_s_setprio(0); } while (0)
; #define PG8_WAIT_V(n) asm volatile("s_waitcnt vmcnt(" #n ")" ::: "memory")
; #define PG8_WAIT_L(n) asm volatile("s_waitcnt lgkmcnt(" #n ")" ::: "memory")
; #define PG8_BAR __builtin_amdgcn_s_barrier()
; #define PG8_SCHED __builtin_amdgcn_sched_barrier(0)
; template <class Epi, class Sched, bool ALIGN_EPI = false, bool SP2 = false>
; __device__ __forceinline__ void gemm_phase(PG8_LAS unsigned char* lds, const Gemm g, const Sched& S, const Epi& E) {
;     ...
;             PG8_LDB(B0, 0, 0); PG8_LDB(B1, 0, 1); PG8_SCHED; PG8_LDA(At, 0, 0); PG8_STAGE(PG8_SA(1, 1), a1 + hstep, voffA);
;             PG8_WAIT_V(8); PG8_WAIT_L(0); PG8_BAR; PG8_MMA(0, 0, At, B0); PG8_MMA(0, 1, At, B1); PG8_BAR; PG8_SCHED;
;     ...
;             PG8_LDA(At, 1, 1); PG8_STAGE(PG8_SB(1, 0), b3, voffB); PG8_STAGE(PG8_SB(1, 1), b3 + hstep, voffB); PG8_STAGE(PG8_SA(1, 0), a3, voffA);
;             PG8_WAIT_V(8); PG8_WAIT_L(0); PG8_BAR; PG8_MMA(1, 0, At, B0); PG8_MMA(1, 1, At, B1); PG8_BAR; PG8_SCHED;
	s_add_i32 s58, s94, s66
	v_lshl_add_u64 v[204:205], v[204:205], 0, s[20:21]
	s_mov_b32 m0, s58
	ds_read_b128 v[180:183], v147 offset:49152
	ds_read_b128 v[184:187], v147 offset:50176
	ds_read_b128 v[188:191], v147 offset:51200
	ds_read_b128 v[192:195], v147 offset:52224
	ds_read_b128 v[196:199], v147 offset:53248
	ds_read_b128 v[200:203], v147 offset:54272
	ds_read_b128 v[208:211], v147 offset:55296
	ds_read_b128 v[212:215], v147 offset:56320
	global_load_lds_dwordx4 v[204:205], off
	s_add_i32 m0, s58, 0x2000
	s_add_u32 s56, s56, 0xb0080
	v_lshl_add_u64 v[204:205], v[216:217], 0, s[20:21]
	s_addc_u32 s57, s57, 0
	s_add_i32 s58, s95, s66
	global_load_lds_dwordx4 v[204:205], off
	v_lshl_add_u64 v[204:205], s[56:57], 0, v[130:131]
	s_mov_b32 m0, s58
	s_nop 0
	global_load_lds_dwordx4 v[204:205], off
	v_lshl_add_u64 v[204:205], s[56:57], 0, v[134:135]
	s_add_i32 m0, s58, 0x2000
	s_nop 0
	global_load_lds_dwordx4 v[204:205], off
	v_lshl_add_u64 v[204:205], v[218:219], 0, s[20:21]
	s_mov_b32 m0, s75
	s_nop 0
	global_load_lds_dwordx4 v[204:205], off
	v_lshl_add_u64 v[204:205], v[220:221], 0, s[20:21]
	s_mov_b32 m0, s76
	s_nop 0
	global_load_lds_dwordx4 v[204:205], off
	s_waitcnt vmcnt(8)
	s_waitcnt lgkmcnt(0)
	s_barrier
	s_setprio 1
	s_waitcnt lgkmcnt(0)
	v_mfma_f32_16x16x32_bf16 v[60:63], v[148:151], v[180:183], v[60:63]
	v_mfma_f32_16x16x32_bf16 v[56:59], v[156:159], v[180:183], v[56:59]
	v_mfma_f32_16x16x32_bf16 v[52:55], v[148:151], v[188:191], v[52:55]
	v_mfma_f32_16x16x32_bf16 v[48:51], v[156:159], v[188:191], v[48:51]
	v_mfma_f32_16x16x32_bf16 v[36:39], v[148:151], v[196:199], v[36:39]
	v_mfma_f32_16x16x32_bf16 v[32:35], v[156:159], v[196:199], v[32:35]
	v_mfma_f32_16x16x32_bf16 v[20:23], v[148:151], v[208:211], v[20:23]
	v_mfma_f32_16x16x32_bf16 v[16:19], v[156:159], v[208:211], v[16:19]
	v_mfma_f32_16x16x32_bf16 v[60:63], v[152:155], v[184:187], v[60:63]
	v_mfma_f32_16x16x32_bf16 v[56:59], v[160:163], v[184:187], v[56:59]
	v_mfma_f32_16x16x32_bf16 v[52:55], v[152:155], v[192:195], v[52:55]
	v_mfma_f32_16x16x32_bf16 v[48:51], v[160:163], v[192:195], v[48:51]
	v_mfma_f32_16x16x32_bf16 v[36:39], v[152:155], v[200:203], v[36:39]
	v_mfma_f32_16x16x32_bf16 v[32:35], v[160:163], v[200:203], v[32:35]
	v_mfma_f32_16x16x32_bf16 v[20:23], v[152:155], v[212:215], v[20:23]
	v_mfma_f32_16x16x32_bf16 v[16:19], v[160:163], v[212:215], v[16:19]
	v_mfma_f32_16x16x32_bf16 v[44:47], v[164:167], v[180:183], v[44:47]
	v_mfma_f32_16x16x32_bf16 v[40:43], v[172:175], v[180:183], v[40:43]
	v_mfma_f32_16x16x32_bf16 v[28:31], v[164:167], v[188:191], v[28:31]
	v_mfma_f32_16x16x32_bf16 v[24:27], v[172:175], v[188:191], v[24:27]
	v_mfma_f32_16x16x32_bf16 v[12:15], v[164:167], v[196:199], v[12:15]
	v_mfma_f32_16x16x32_bf16 v[8:11], v[172:175], v[196:199], v[8:11]
	v_mfma_f32_16x16x32_bf16 v[4:7], v[164:167], v[208:211], v[4:7]
	v_mfma_f32_16x16x32_bf16 v[0:3], v[172:175], v[208:211], v[0:3]
	v_mfma_f32_16x16x32_bf16 v[44:47], v[168:171], v[184:187], v[44:47]
	v_mfma_f32_16x16x32_bf16 v[40:43], v[176:179], v[184:187], v[40:43]
	v_mfma_f32_16x16x32_bf16 v[28:31], v[168:171], v[192:195], v[28:31]
	v_mfma_f32_16x16x32_bf16 v[24:27], v[176:179], v[192:195], v[24:27]
	v_mfma_f32_16x16x32_bf16 v[12:15], v[168:171], v[200:203], v[12:15]
	v_mfma_f32_16x16x32_bf16 v[8:11], v[176:179], v[200:203], v[8:11]
	v_mfma_f32_16x16x32_bf16 v[4:7], v[168:171], v[212:215], v[4:7]
	v_mfma_f32_16x16x32_bf16 v[0:3], v[176:179], v[212:215], v[0:3]
	s_setprio 0
	s_barrier
	s_add_i32 s93, s93, 2
	s_add_u32 s46, s46, 0x100
	s_addc_u32 s47, s47, 0
	s_add_u32 s91, s91, 0x100
	s_addc_u32 s92, s92, 0
	s_cmp_gt_u32 s93, 41
	s_cbranch_scc0 .LBB0_1163
	s_branch .Lpeel_exit_8
.LBB0_1163:
	ds_read_b128 v[148:151], v145
	ds_read_b128 v[152:155], v145 offset:1024
	ds_read_b128 v[156:159], v145 offset:2048
	ds_read_b128 v[160:163], v145 offset:3072
	ds_read_b128 v[164:167], v146
	ds_read_b128 v[168:171], v146 offset:1024
	ds_read_b128 v[172:175], v146 offset:2048
	ds_read_b128 v[176:179], v146 offset:3072
	s_add_u32 s56, s46, 0xfff50080
	s_addc_u32 s57, s47, -1
	s_cmp_eq_u32 s93, 40
	s_cselect_b32 s59, s41, s57
	s_cselect_b32 s58, s40, s56
	s_cselect_b32 s57, s43, s92
	s_cselect_b32 s56, s42, s91
	v_lshl_add_u64 v[204:205], s[46:47], 0, v[136:137]
	s_add_i32 m0, s69, 0xc000
	ds_read_b128 v[180:183], v147
	ds_read_b128 v[184:187], v147 offset:1024
	ds_read_b128 v[188:191], v147 offset:2048
	ds_read_b128 v[192:195], v147 offset:3072
	ds_read_b128 v[196:199], v147 offset:4096
	ds_read_b128 v[200:203], v147 offset:5120
	ds_read_b128 v[208:211], v147 offset:6144
	ds_read_b128 v[212:215], v147 offset:7168
	global_load_lds_dwordx4 v[204:205], off
	v_lshl_add_u64 v[204:205], s[46:47], 0, v[138:139]
	s_add_i32 m0, s69, 0xe000
	s_nop 0
	global_load_lds_dwordx4 v[204:205], off
	s_waitcnt vmcnt(8)
	s_waitcnt lgkmcnt(0)
	s_barrier
; #define PG8_STAGE(bufoff, gbase, voff) do { _Pragma("unroll") for (int _i = 0; _i < 2; ++_i) \
;         __builtin_amdgcn_global_load_lds((const unsigned*)((const char*)(gbase) + (voff)[_i]), (PG8_LAS unsigned*)(lds + (bufoff) + ldsw + _i * 8192), 16, 0, 0); } while (0)
; #define PG8_LDA(dst, b, h) do { _Pragma("unroll") for (int m = 0; m < 4; ++m) _Pragma("unroll") for (int k = 0; k < 2; ++k) dst[m][k] = *(const PG8_LAS bf16x8*)(lds + PG8_SA(b, h) + aoff + m * 2048 + k * 1024); } while (0)
; #define PG8_MMA(ai, bj, At, Bt) do { __builtin_amdgcn_s_setprio(1); _Pragma("unroll") for (int m = 0; m < 4; ++m) _Pragma("unroll") for (int n = 0; n < 2; ++n) _Pragma("unroll") for (int k = 0; k < 2; ++k) \
;         acc[ai][bj][m][n] = __builtin_amdgcn_mfma_f32_16x16x32_bf16(Bt[n][k], At[m][k], acc[ai][bj][m][n], 0, 0, 0); __builtin_amdgcn_s_setprio(0); } while (0)
; #define PG8_WAIT_V(n) asm volatile("s_waitcnt vmcnt(" #n ")" ::: "memory")
; #define PG8_WAIT_L(n) asm volatile("s_waitcnt lgkmcnt(" #n ")" ::: "memory")
; #define PG8_BAR __builtin_amdgcn_s_barrier()
; #define PG8_SCHED __builtin_amdgcn_sched_barrier(0)
; template <class Epi, class Sched, bool ALIGN_EPI = false, bool SP2 = false>
; __device__ __forceinline__ void gemm_phase(PG8_LAS unsigned char* lds, const Gemm g, const Sched& S, const Epi& E) {
;     ...
;             PG8_WAIT_V(8); PG8_WAIT_L(0); PG8_BAR; PG8_MMA(0, 0, At, B0); PG8_MMA(0, 1, At, B1); PG8_BAR; PG8_SCHED;
;             PG8_LDA(At, 0, 1); PG8_STAGE(PG8_SB(0, 0), b2, voffB); PG8_STAGE(PG8_SB(0, 1), b2 + hstep, voffB); PG8_STAGE(PG8_SA(0, 0), a2, voffA);
;             PG8_WAIT_V(8); PG8_WAIT_L(0); PG8_BAR; PG8_MMA(1, 0, At, B0); PG8_MMA(1, 1, At, B1); PG8_BAR; PG8_SCHED;
	s_setprio 1
	s_waitcnt lgkmcnt(0)
	v_mfma_f32_16x16x32_bf16 v[124:127], v[148:151], v[180:183], v[124:127]
	v_mfma_f32_16x16x32_bf16 v[120:123], v[156:159], v[180:183], v[120:123]
	v_mfma_f32_16x16x32_bf16 v[116:119], v[148:151], v[188:191], v[116:119]
	v_mfma_f32_16x16x32_bf16 v[112:115], v[156:159], v[188:191], v[112:115]
	v_mfma_f32_16x16x32_bf16 v[100:103], v[148:151], v[196:199], v[100:103]
	v_mfma_f32_16x16x32_bf16 v[96:99], v[156:159], v[196:199], v[96:99]
	v_mfma_f32_16x16x32_bf16 v[84:87], v[148:151], v[208:211], v[84:87]
	v_mfma_f32_16x16x32_bf16 v[80:83], v[156:159], v[208:211], v[80:83]
	v_mfma_f32_16x16x32_bf16 v[124:127], v[152:155], v[184:187], v[124:127]
	v_mfma_f32_16x16x32_bf16 v[120:123], v[160:163], v[184:187], v[120:123]
	v_mfma_f32_16x16x32_bf16 v[116:119], v[152:155], v[192:195], v[116:119]
	v_mfma_f32_16x16x32_bf16 v[112:115], v[160:163], v[192:195], v[112:115]
	v_mfma_f32_16x16x32_bf16 v[100:103], v[152:155], v[200:203], v[100:103]
	v_mfma_f32_16x16x32_bf16 v[96:99], v[160:163], v[200:203], v[96:99]
	v_mfma_f32_16x16x32_bf16 v[84:87], v[152:155], v[212:215], v[84:87]
	v_mfma_f32_16x16x32_bf16 v[80:83], v[160:163], v[212:215], v[80:83]
	v_mfma_f32_16x16x32_bf16 v[108:111], v[164:167], v[180:183], v[108:111]
	v_mfma_f32_16x16x32_bf16 v[104:107], v[172:175], v[180:183], v[104:107]
	v_mfma_f32_16x16x32_bf16 v[92:95], v[164:167], v[188:191], v[92:95]
	v_mfma_f32_16x16x32_bf16 v[88:91], v[172:175], v[188:191], v[88:91]
	v_mfma_f32_16x16x32_bf16 v[76:79], v[164:167], v[196:199], v[76:79]
	v_mfma_f32_16x16x32_bf16 v[72:75], v[172:175], v[196:199], v[72:75]
	v_mfma_f32_16x16x32_bf16 v[68:71], v[164:167], v[208:211], v[68:71]
	v_mfma_f32_16x16x32_bf16 v[64:67], v[172:175], v[208:211], v[64:67]
	v_mfma_f32_16x16x32_bf16 v[108:111], v[168:171], v[184:187], v[108:111]
	v_mfma_f32_16x16x32_bf16 v[104:107], v[176:179], v[184:187], v[104:107]
	v_mfma_f32_16x16x32_bf16 v[92:95], v[168:171], v[192:195], v[92:95]
	v_mfma_f32_16x16x32_bf16 v[88:91], v[176:179], v[192:195], v[88:91]
	v_mfma_f32_16x16x32_bf16 v[76:79], v[168:171], v[200:203], v[76:79]
	v_mfma_f32_16x16x32_bf16 v[72:75], v[176:179], v[200:203], v[72:75]
	v_mfma_f32_16x16x32_bf16 v[68:71], v[168:171], v[212:215], v[68:71]
	v_mfma_f32_16x16x32_bf16 v[64:67], v[176:179], v[212:215], v[64:67]
	s_setprio 0
	s_barrier
	s_add_i32 s94, s77, s66
	v_lshl_add_u64 v[204:205], s[56:57], 0, v[130:131]
	s_mov_b32 m0, s94
	ds_read_b128 v[180:183], v147 offset:16384
	ds_read_b128 v[184:187], v147 offset:17408
	ds_read_b128 v[188:191], v147 offset:18432
	ds_read_b128 v[192:195], v147 offset:19456
	ds_read_b128 v[196:199], v147 offset:20480
	ds_read_b128 v[200:203], v147 offset:21504
	ds_read_b128 v[208:211], v147 offset:22528
	ds_read_b128 v[212:215], v147 offset:23552
	global_load_lds_dwordx4 v[204:205], off
	s_add_i32 m0, s94, 0x2000
	s_add_u32 s94, s56, 0xb0000
	v_lshl_add_u64 v[216:217], s[56:57], 0, v[134:135]
	s_addc_u32 s95, s57, 0
	s_add_i32 s96, s78, s66
	global_load_lds_dwordx4 v[216:217], off
	v_lshl_add_u64 v[218:219], s[94:95], 0, v[130:131]
	s_mov_b32 m0, s96
	v_lshl_add_u64 v[220:221], s[58:59], 0, v[132:133]
	global_load_lds_dwordx4 v[218:219], off
	v_lshl_add_u64 v[218:219], s[94:95], 0, v[134:135]
	s_add_i32 m0, s96, 0x2000
	s_nop 0
	global_load_lds_dwordx4 v[218:219], off
	v_lshl_add_u64 v[218:219], s[58:59], 0, v[128:129]
	s_mov_b32 m0, s69
	s_nop 0
	global_load_lds_dwordx4 v[218:219], off
	s_mov_b32 m0, s71
	s_nop 0
	global_load_lds_dwordx4 v[220:221], off
	s_waitcnt vmcnt(8)
	s_waitcnt lgkmcnt(0)
	s_barrier
	s_setprio 1
	s_waitcnt lgkmcnt(0)
	v_mfma_f32_16x16x32_bf16 v[60:63], v[148:151], v[180:183], v[60:63]
	v_mfma_f32_16x16x32_bf16 v[56:59], v[156:159], v[180:183], v[56:59]
	v_mfma_f32_16x16x32_bf16 v[52:55], v[148:151], v[188:191], v[52:55]
	v_mfma_f32_16x16x32_bf16 v[48:51], v[156:159], v[188:191], v[48:51]
	v_mfma_f32_16x16x32_bf16 v[36:39], v[148:151], v[196:199], v[36:39]
	v_mfma_f32_16x16x32_bf16 v[32:35], v[156:159], v[196:199], v[32:35]
	v_mfma_f32_16x16x32_bf16 v[20:23], v[148:151], v[208:211], v[20:23]
	v_mfma_f32_16x16x32_bf16 v[16:19], v[156:159], v[208:211], v[16:19]
	v_mfma_f32_16x16x32_bf16 v[60:63], v[152:155], v[184:187], v[60:63]
	v_mfma_f32_16x16x32_bf16 v[56:59], v[160:163], v[184:187], v[56:59]
	v_mfma_f32_16x16x32_bf16 v[52:55], v[152:155], v[192:195], v[52:55]
	v_mfma_f32_16x16x32_bf16 v[48:51], v[160:163], v[192:195], v[48:51]
	v_mfma_f32_16x16x32_bf16 v[36:39], v[152:155], v[200:203], v[36:39]
	v_mfma_f32_16x16x32_bf16 v[32:35], v[160:163], v[200:203], v[32:35]
	v_mfma_f32_16x16x32_bf16 v[20:23], v[152:155], v[212:215], v[20:23]
	v_mfma_f32_16x16x32_bf16 v[16:19], v[160:163], v[212:215], v[16:19]
	v_mfma_f32_16x16x32_bf16 v[44:47], v[164:167], v[180:183], v[44:47]
	v_mfma_f32_16x16x32_bf16 v[40:43], v[172:175], v[180:183], v[40:43]
	v_mfma_f32_16x16x32_bf16 v[28:31], v[164:167], v[188:191], v[28:31]
	v_mfma_f32_16x16x32_bf16 v[24:27], v[172:175], v[188:191], v[24:27]
	v_mfma_f32_16x16x32_bf16 v[12:15], v[164:167], v[196:199], v[12:15]
	v_mfma_f32_16x16x32_bf16 v[8:11], v[172:175], v[196:199], v[8:11]
	v_mfma_f32_16x16x32_bf16 v[4:7], v[164:167], v[208:211], v[4:7]
	v_mfma_f32_16x16x32_bf16 v[0:3], v[172:175], v[208:211], v[0:3]
	v_mfma_f32_16x16x32_bf16 v[44:47], v[168:171], v[184:187], v[44:47]
	v_mfma_f32_16x16x32_bf16 v[40:43], v[176:179], v[184:187], v[40:43]
	v_mfma_f32_16x16x32_bf16 v[28:31], v[168:171], v[192:195], v[28:31]
	v_mfma_f32_16x16x32_bf16 v[24:27], v[176:179], v[192:195], v[24:27]
	v_mfma_f32_16x16x32_bf16 v[12:15], v[168:171], v[200:203], v[12:15]
	v_mfma_f32_16x16x32_bf16 v[8:11], v[176:179], v[200:203], v[8:11]
	v_mfma_f32_16x16x32_bf16 v[4:7], v[168:171], v[212:215], v[4:7]
	v_mfma_f32_16x16x32_bf16 v[0:3], v[176:179], v[212:215], v[0:3]
	s_setprio 0
	s_barrier
; #define PG8_STAGE(bufoff, gbase, voff) do { _Pragma("unroll") for (int _i = 0; _i < 2; ++_i) \
;         __builtin_amdgcn_global_load_lds((const unsigned*)((const char*)(gbase) + (voff)[_i]), (PG8_LAS unsigned*)(lds + (bufoff) + ldsw + _i * 8192), 16, 0, 0); } while (0)
; #define PG8_LDA(dst, b, h) do { _Pragma("unroll") for (int m = 0; m < 4; ++m) _Pragma("unroll") for (int k = 0; k < 2; ++k) dst[m][k] = *(const PG8_LAS bf16x8*)(lds + PG8_SA(b, h) + aoff + m * 2048 + k * 1024); } while (0)
; #define PG8_LDB(dst, b, h) do { _Pragma("unroll") for (int n = 0; n < 2; ++n) _Pragma("unroll") for (int k = 0; k < 2; ++k) dst[n][k] = *(const PG8_LAS bf16x8*)(lds + PG8_SB(b, h) + boff + n * 2048 + k * 1024); } while (0)
; #define PG8_MMA(ai, bj, At, Bt) do { __builtin_amdgcn_s_setprio(1); _Pragma("unroll") for (int m = 0; m < 4; ++m) _Pragma("unroll") for (int n = 0; n < 2; ++n) _Pragma("unroll") for (int k = 0; k < 2; ++k) \
;         acc[ai][bj][m][n] = __builtin_amdgcn_mfma_f32_16x16x32_bf16(Bt[n][k], At[m][k], acc[ai][bj][m][n], 0, 0, 0); __builtin_amdgcn_s_setprio(0); } while (0)
; #define PG8_WAIT_V(n) asm volatile("s_waitcnt vmcnt(" #n ")" ::: "memory")
; #define PG8_WAIT_L(n) asm volatile("s_waitcnt lgkmcnt(" #n ")" ::: "memory")
; #define PG8_BAR __builtin_amdgcn_s_barrier()
; #define PG8_SCHED __builtin_amdgcn_sched_barrier(0)
; template <class Epi, class Sched, bool ALIGN_EPI = false, bool SP2 = false>
; __device__ __forceinline__ void gemm_phase(PG8_LAS unsigned char* lds, const Gemm g, const Sched& S, const Epi& E) {
;     ...
;             PG8_LDB(B0, 1, 0); PG8_LDB(B1, 1, 1); PG8_SCHED; PG8_LDA(At, 1, 0); PG8_STAGE(PG8_SA(0, 1), a2 + hstep, voffA);
;             PG8_WAIT_V(8); PG8_WAIT_L(0); PG8_BAR; PG8_MMA(0, 0, At, B0); PG8_MMA(0, 1, At, B1); PG8_BAR; PG8_SCHED;
	s_add_i32 s94, 0, 0x18000
	s_add_i32 s95, 0, 0x1c000
	v_add_u32_e32 v160, s94, v143
	v_add_u32_e32 v176, s95, v143
	ds_read_b128 v[148:151], v160
	ds_read_b128 v[152:155], v160 offset:1024
	ds_read_b128 v[156:159], v160 offset:2048
	ds_read_b128 v[160:163], v160 offset:3072
	ds_read_b128 v[164:167], v176
	ds_read_b128 v[168:171], v176 offset:1024
	ds_read_b128 v[172:175], v176 offset:2048
	ds_read_b128 v[176:179], v176 offset:3072
	s_add_u32 s58, s58, 0xb0000
	s_addc_u32 s59, s59, 0
	s_mov_b32 m0, s72
	v_lshl_add_u64 v[222:223], s[58:59], 0, v[128:129]
	ds_read_b128 v[180:183], v147 offset:32768
	ds_read_b128 v[184:187], v147 offset:33792
	ds_read_b128 v[188:191], v147 offset:34816
	ds_read_b128 v[192:195], v147 offset:35840
	ds_read_b128 v[196:199], v147 offset:36864
	ds_read_b128 v[200:203], v147 offset:37888
	ds_read_b128 v[208:211], v147 offset:38912
	ds_read_b128 v[212:215], v147 offset:39936
	global_load_lds_dwordx4 v[222:223], off
	v_lshl_add_u64 v[222:223], s[58:59], 0, v[132:133]
	s_mov_b32 m0, s73
	s_nop 0
	global_load_lds_dwordx4 v[222:223], off
	s_waitcnt vmcnt(8)
	s_waitcnt lgkmcnt(0)
	s_barrier
	s_setprio 1
	s_waitcnt lgkmcnt(0)
	v_mfma_f32_16x16x32_bf16 v[124:127], v[148:151], v[180:183], v[124:127]
	v_mfma_f32_16x16x32_bf16 v[120:123], v[156:159], v[180:183], v[120:123]
	v_mfma_f32_16x16x32_bf16 v[116:119], v[148:151], v[188:191], v[116:119]
	v_mfma_f32_16x16x32_bf16 v[112:115], v[156:159], v[188:191], v[112:115]
	v_mfma_f32_16x16x32_bf16 v[100:103], v[148:151], v[196:199], v[100:103]
	v_mfma_f32_16x16x32_bf16 v[96:99], v[156:159], v[196:199], v[96:99]
	v_mfma_f32_16x16x32_bf16 v[84:87], v[148:151], v[208:211], v[84:87]
	v_mfma_f32_16x16x32_bf16 v[80:83], v[156:159], v[208:211], v[80:83]
	v_mfma_f32_16x16x32_bf16 v[124:127], v[152:155], v[184:187], v[124:127]
	v_mfma_f32_16x16x32_bf16 v[120:123], v[160:163], v[184:187], v[120:123]
	v_mfma_f32_16x16x32_bf16 v[116:119], v[152:155], v[192:195], v[116:119]
	v_mfma_f32_16x16x32_bf16 v[112:115], v[160:163], v[192:195], v[112:115]
	v_mfma_f32_16x16x32_bf16 v[100:103], v[152:155], v[200:203], v[100:103]
	v_mfma_f32_16x16x32_bf16 v[96:99], v[160:163], v[200:203], v[96:99]
	v_mfma_f32_16x16x32_bf16 v[84:87], v[152:155], v[212:215], v[84:87]
	v_mfma_f32_16x16x32_bf16 v[80:83], v[160:163], v[212:215], v[80:83]
	v_mfma_f32_16x16x32_bf16 v[108:111], v[164:167], v[180:183], v[108:111]
	v_mfma_f32_16x16x32_bf16 v[104:107], v[172:175], v[180:183], v[104:107]
	v_mfma_f32_16x16x32_bf16 v[92:95], v[164:167], v[188:191], v[92:95]
	v_mfma_f32_16x16x32_bf16 v[88:91], v[172:175], v[188:191], v[88:91]
	v_mfma_f32_16x16x32_bf16 v[76:79], v[164:167], v[196:199], v[76:79]
	v_mfma_f32_16x16x32_bf16 v[72:75], v[172:175], v[196:199], v[72:75]
	v_mfma_f32_16x16x32_bf16 v[68:71], v[164:167], v[208:211], v[68:71]
	v_mfma_f32_16x16x32_bf16 v[64:67], v[172:175], v[208:211], v[64:67]
	v_mfma_f32_16x16x32_bf16 v[108:111], v[168:171], v[184:187], v[108:111]
	v_mfma_f32_16x16x32_bf16 v[104:107], v[176:179], v[184:187], v[104:107]
	v_mfma_f32_16x16x32_bf16 v[92:95], v[168:171], v[192:195], v[92:95]
	v_mfma_f32_16x16x32_bf16 v[88:91], v[176:179], v[192:195], v[88:91]
	v_mfma_f32_16x16x32_bf16 v[76:79], v[168:171], v[200:203], v[76:79]
	v_mfma_f32_16x16x32_bf16 v[72:75], v[176:179], v[200:203], v[72:75]
	v_mfma_f32_16x16x32_bf16 v[68:71], v[168:171], v[212:215], v[68:71]
	v_mfma_f32_16x16x32_bf16 v[64:67], v[176:179], v[212:215], v[64:67]
	s_setprio 0
	s_barrier
; #define PG8_STAGE(bufoff, gbase, voff) do { _Pragma("unroll") for (int _i = 0; _i < 2; ++_i) \
;         __builtin_amdgcn_global_load_lds((const unsigned*)((const char*)(gbase) + (voff)[_i]), (PG8_LAS unsigned*)(lds + (bufoff) + ldsw + _i * 8192), 16, 0, 0); } while (0)
; #define PG8_LDA(dst, b, h) do { _Pragma("unroll") for (int m = 0; m < 4; ++m) _Pragma("unroll") for (int k = 0; k < 2; ++k) dst[m][k] = *(const PG8_LAS bf16x8*)(lds + PG8_SA(b, h) + aoff + m * 2048 + k * 1024); } while (0)
; #define PG8_MMA(ai, bj, At, Bt) do { __builtin_amdgcn_s_setprio(1); _Pragma("unroll") for (int m = 0; m < 4; ++m) _Pragma("unroll") for (int n = 0; n < 2; ++n) _Pragma("unroll") for (int k = 0; k < 2; ++k) \
;         acc[ai][bj][m][n] = __builtin_amdgcn_mfma_f32_16x16x32_bf16(Bt[n][k], At[m][k], acc[ai][bj][m][n], 0, 0, 0); __builtin_amdgcn_s_setprio(0); } while (0)
; #define PG8_WAIT_V(n) asm volatile("s_waitcnt vmcnt(" #n ")" ::: "memory")
; #define PG8_WAIT_L(n) asm volatile("s_waitcnt lgkmcnt(" #n ")" ::: "memory")
; #define PG8_BAR __builtin_amdgcn_s_barrier()
; #define PG8_SCHED __builtin_amdgcn_sched_barrier(0)
; template <class Epi, class Sched, bool ALIGN_EPI = false, bool SP2 = false>
; __device__ __forceinline__ void gemm_phase(PG8_LAS unsigned char* lds, const Gemm g, const Sched& S, const Epi& E) {
;     ...
;         for (int t = 0; t < nt; t += 2) {
;             const bool last = (t == nt - 2);
;             const char* a1 = cA + (size_t)(t + 1) * kstep;
;             const char* a2 = last ? nA : cA + (size_t)(t + 2) * kstep; const char* b2 = last ? nB : cB + (size_t)(t + 2) * kstep;
;             const char* a3 = a2 + kstep; const char* b3 = b2 + kstep;
;     ...
;             PG8_LDA(At, 1, 1); PG8_STAGE(PG8_SB(1, 0), b3, voffB); PG8_STAGE(PG8_SB(1, 1), b3 + hstep, voffB); PG8_STAGE(PG8_SA(1, 0), a3, voffA);
;             PG8_WAIT_V(8); PG8_WAIT_L(0); PG8_BAR; PG8_MMA(1, 0, At, B0); PG8_MMA(1, 1, At, B1); PG8_BAR; PG8_SCHED;
	s_add_i32 s58, s94, s66
	v_lshl_add_u64 v[204:205], v[204:205], 0, s[20:21]
	s_mov_b32 m0, s58
	ds_read_b128 v[180:183], v147 offset:49152
	ds_read_b128 v[184:187], v147 offset:50176
	ds_read_b128 v[188:191], v147 offset:51200
	ds_read_b128 v[192:195], v147 offset:52224
	ds_read_b128 v[196:199], v147 offset:53248
	ds_read_b128 v[200:203], v147 offset:54272
	ds_read_b128 v[208:211], v147 offset:55296
	ds_read_b128 v[212:215], v147 offset:56320
	global_load_lds_dwordx4 v[204:205], off
	s_add_i32 m0, s58, 0x2000
	s_add_u32 s56, s56, 0xb0080
	v_lshl_add_u64 v[204:205], v[216:217], 0, s[20:21]
	s_addc_u32 s57, s57, 0
	s_add_i32 s58, s95, s66
	global_load_lds_dwordx4 v[204:205], off
	v_lshl_add_u64 v[204:205], s[56:57], 0, v[130:131]
	s_mov_b32 m0, s58
	s_nop 0
	global_load_lds_dwordx4 v[204:205], off
	v_lshl_add_u64 v[204:205], s[56:57], 0, v[134:135]
	s_add_i32 m0, s58, 0x2000
	s_nop 0
	global_load_lds_dwordx4 v[204:205], off
	v_lshl_add_u64 v[204:205], v[218:219], 0, s[20:21]
	s_mov_b32 m0, s75
	s_nop 0
	global_load_lds_dwordx4 v[204:205], off
	v_lshl_add_u64 v[204:205], v[220:221], 0, s[20:21]
	s_mov_b32 m0, s76
	s_nop 0
	global_load_lds_dwordx4 v[204:205], off
	s_waitcnt vmcnt(8)
	s_waitcnt lgkmcnt(0)
	s_barrier
	s_setprio 1
	s_waitcnt lgkmcnt(0)
	v_mfma_f32_16x16x32_bf16 v[60:63], v[148:151], v[180:183], v[60:63]
	v_mfma_f32_16x16x32_bf16 v[56:59], v[156:159], v[180:183], v[56:59]
	v_mfma_f32_16x16x32_bf16 v[52:55], v[148:151], v[188:191], v[52:55]
	v_mfma_f32_16x16x32_bf16 v[48:51], v[156:159], v[188:191], v[48:51]
	v_mfma_f32_16x16x32_bf16 v[36:39], v[148:151], v[196:199], v[36:39]
	v_mfma_f32_16x16x32_bf16 v[32:35], v[156:159], v[196:199], v[32:35]
	v_mfma_f32_16x16x32_bf16 v[20:23], v[148:151], v[208:211], v[20:23]
	v_mfma_f32_16x16x32_bf16 v[16:19], v[156:159], v[208:211], v[16:19]
	v_mfma_f32_16x16x32_bf16 v[60:63], v[152:155], v[184:187], v[60:63]
	v_mfma_f32_16x16x32_bf16 v[56:59], v[160:163], v[184:187], v[56:59]
	v_mfma_f32_16x16x32_bf16 v[52:55], v[152:155], v[192:195], v[52:55]
	v_mfma_f32_16x16x32_bf16 v[48:51], v[160:163], v[192:195], v[48:51]
	v_mfma_f32_16x16x32_bf16 v[36:39], v[152:155], v[200:203], v[36:39]
	v_mfma_f32_16x16x32_bf16 v[32:35], v[160:163], v[200:203], v[32:35]
	v_mfma_f32_16x16x32_bf16 v[20:23], v[152:155], v[212:215], v[20:23]
	v_mfma_f32_16x16x32_bf16 v[16:19], v[160:163], v[212:215], v[16:19]
	v_mfma_f32_16x16x32_bf16 v[44:47], v[164:167], v[180:183], v[44:47]
	v_mfma_f32_16x16x32_bf16 v[40:43], v[172:175], v[180:183], v[40:43]
	v_mfma_f32_16x16x32_bf16 v[28:31], v[164:167], v[188:191], v[28:31]
	v_mfma_f32_16x16x32_bf16 v[24:27], v[172:175], v[188:191], v[24:27]
	v_mfma_f32_16x16x32_bf16 v[12:15], v[164:167], v[196:199], v[12:15]
	v_mfma_f32_16x16x32_bf16 v[8:11], v[172:175], v[196:199], v[8:11]
	v_mfma_f32_16x16x32_bf16 v[4:7], v[164:167], v[208:211], v[4:7]
	v_mfma_f32_16x16x32_bf16 v[0:3], v[172:175], v[208:211], v[0:3]
	v_mfma_f32_16x16x32_bf16 v[44:47], v[168:171], v[184:187], v[44:47]
	v_mfma_f32_16x16x32_bf16 v[40:43], v[176:179], v[184:187], v[40:43]
	v_mfma_f32_16x16x32_bf16 v[28:31], v[168:171], v[192:195], v[28:31]
	v_mfma_f32_16x16x32_bf16 v[24:27], v[176:179], v[192:195], v[24:27]
	v_mfma_f32_16x16x32_bf16 v[12:15], v[168:171], v[200:203], v[12:15]
	v_mfma_f32_16x16x32_bf16 v[8:11], v[176:179], v[200:203], v[8:11]
	v_mfma_f32_16x16x32_bf16 v[4:7], v[168:171], v[212:215], v[4:7]
	v_mfma_f32_16x16x32_bf16 v[0:3], v[176:179], v[212:215], v[0:3]
	s_setprio 0
	s_barrier
	s_add_i32 s93, s93, 2
	s_add_u32 s46, s46, 0x100
	s_addc_u32 s47, s47, 0
	s_add_u32 s91, s91, 0x100
	s_addc_u32 s92, s92, 0
	s_cmp_gt_u32 s93, 41
	s_cbranch_scc0 .LBB0_1163

;     __device__ __forceinline__ bool next(int i, Unit& u) const { if (i != 0) return false; const int c0 = (G >= 8) ? G - 5 : G - 2; int k = -1; if (c == c0) k = 0; else if (c == G - 1) k = 1; if (k < 0 || k >= n) return false; u.pm = k; u.pn = 0; return true; }
; #define PG8_STAGE(bufoff, gbase, voff) do { _Pragma("unroll") for (int _i = 0; _i < 2; ++_i) \
;         __builtin_amdgcn_global_load_lds((const unsigned*)((const char*)(gbase) + (voff)[_i]), (PG8_LAS unsigned*)(lds + (bufoff) + ldsw + _i * 8192), 16, 0, 0); } while (0)
; #define PG8_LDA(dst, b, h) do { _Pragma("unroll") for (int m = 0; m < 4; ++m) _Pragma("unroll") for (int k = 0; k < 2; ++k) dst[m][k] = *(const PG8_LAS bf16x8*)(lds + PG8_SA(b, h) + aoff + m * 2048 + k * 1024); } while (0)
; #define PG8_LDB(dst, b, h) do { _Pragma("unroll") for (int n = 0; n < 2; ++n) _Pragma("unroll") for (int k = 0; k < 2; ++k) dst[n][k] = *(const PG8_LAS bf16x8*)(lds + PG8_SB(b, h) + boff + n * 2048 + k * 1024); } while (0)
; #define PG8_WAIT_V(n) asm volatile("s_waitcnt vmcnt(" #n ")" ::: "memory")
; #define PG8_WAIT_L(n) asm volatile("s_waitcnt lgkmcnt(" #n ")" ::: "memory")
; #define PG8_BAR __builtin_amdgcn_s_barrier()
; #define PG8_SCHED __builtin_amdgcn_sched_barrier(0)
; template <class Epi, class Sched, bool ALIGN_EPI = false, bool SP2 = false>
; __device__ __forceinline__ void gemm_phase(PG8_LAS unsigned char* lds, const Gemm g, const Sched& S, const Epi& E) {
;     ...
;         const bool has_next = S.next(ui + 1, nxt);
;         const char* nA = has_next ? (const char*)g.A + (size_t)nxt.pm * tstep : cA; const char* nB = has_next ? (const char*)g.Bt + (size_t)nxt.pn * tstep : cB;
;         for (int t = 0; t < nt; t += 2) {
;             const bool last = (t == nt - 2);
;             const char* a1 = cA + (size_t)(t + 1) * kstep;
;             const char* a2 = last ? nA : cA + (size_t)(t + 2) * kstep; const char* b2 = last ? nB : cB + (size_t)(t + 2) * kstep;
;             const char* a3 = a2 + kstep; const char* b3 = b2 + kstep;
;             if (last && has_next) S.a_ready(nxt);
;             if constexpr (SP2) {
;             PG8_LDB(B0, 0, 0); PG8_LDB(B1, 0, 1); PG8_SCHED; PG8_LDA(At, 0, 0); PG8_STAGE(PG8_SA(1, 1), a1 + hstep, voffA);
;             PG8_WAIT_V(8); PG8_WAIT_L(0); PG8_BAR; PG8_MMA(0, 0, At, B0); PG8_MMA(0, 1, At, B1); PG8_BAR; PG8_SCHED;
.LBB0_1348:
	s_ashr_i32 s25, s24, 31
	s_lshl_b64 s[28:29], s[24:25], 19
	s_add_u32 s28, s97, s28
	s_addc_u32 s29, s3, s29
	s_and_b64 s[30:31], s[26:27], exec
	s_cselect_b32 s25, s29, s39
	s_cselect_b32 s73, s28, s38
	s_ashr_i32 s23, s22, 31
	s_lshl_b64 s[30:31], s[22:23], 19
	s_add_u32 s30, s36, s30
	s_addc_u32 s31, s37, s31
	s_and_b64 s[42:43], s[26:27], exec
	s_cselect_b32 s23, s31, s41
	s_cselect_b32 s74, s30, s40
	s_add_u32 s38, s38, 0x40080
	s_addc_u32 s39, s39, 0
	s_add_u32 s75, s40, 0x100
	v_mov_b32_e32 v0, 0
	s_addc_u32 s76, s41, 0
	s_mov_b32 s77, -2
	ds_read_b128 v[148:151], v145
	ds_read_b128 v[152:155], v145 offset:1024
	ds_read_b128 v[156:159], v145 offset:2048
	ds_read_b128 v[160:163], v145 offset:3072
	ds_read_b128 v[164:167], v146
	ds_read_b128 v[168:171], v146 offset:1024
	ds_read_b128 v[172:175], v146 offset:2048
	ds_read_b128 v[176:179], v146 offset:3072
	s_add_u32 s40, s38, 0xfffc0080
	s_addc_u32 s41, s39, -1
	s_cmp_eq_u32 s77, 12
	s_cselect_b32 s43, s25, s41
	s_cselect_b32 s42, s73, s40
	s_cselect_b32 s41, s23, s76
	s_cselect_b32 s40, s74, s75
	v_lshl_add_u64 v[204:205], s[38:39], 0, v[136:137]
	s_add_i32 m0, s56, 0xc000
	ds_read_b128 v[180:183], v147
	ds_read_b128 v[184:187], v147 offset:1024
	ds_read_b128 v[188:191], v147 offset:2048
	ds_read_b128 v[192:195], v147 offset:3072
	ds_read_b128 v[196:199], v147 offset:4096
	ds_read_b128 v[200:203], v147 offset:5120
	ds_read_b128 v[208:211], v147 offset:6144
	ds_read_b128 v[212:215], v147 offset:7168
	global_load_lds_dwordx4 v[204:205], off
	v_lshl_add_u64 v[204:205], s[38:39], 0, v[138:139]
	s_add_i32 m0, s56, 0xe000
	s_nop 0
	global_load_lds_dwordx4 v[204:205], off
	s_waitcnt vmcnt(8)
	s_waitcnt lgkmcnt(0)
	s_barrier
	s_setprio 1
	s_waitcnt lgkmcnt(0)
	v_mfma_f32_16x16x32_bf16 v[124:127], v[148:151], v[180:183], 0
	v_mfma_f32_16x16x32_bf16 v[120:123], v[156:159], v[180:183], 0
	v_mfma_f32_16x16x32_bf16 v[112:115], v[148:151], v[188:191], 0
	v_mfma_f32_16x16x32_bf16 v[104:107], v[156:159], v[188:191], 0
	v_mfma_f32_16x16x32_bf16 v[96:99], v[148:151], v[196:199], 0
	v_mfma_f32_16x16x32_bf16 v[88:91], v[156:159], v[196:199], 0
	v_mfma_f32_16x16x32_bf16 v[80:83], v[148:151], v[208:211], 0
	v_mfma_f32_16x16x32_bf16 v[72:75], v[156:159], v[208:211], 0
	v_mfma_f32_16x16x32_bf16 v[124:127], v[152:155], v[184:187], v[124:127]
	v_mfma_f32_16x16x32_bf16 v[120:123], v[160:163], v[184:187], v[120:123]
	v_mfma_f32_16x16x32_bf16 v[112:115], v[152:155], v[192:195], v[112:115]
	v_mfma_f32_16x16x32_bf16 v[104:107], v[160:163], v[192:195], v[104:107]
	v_mfma_f32_16x16x32_bf16 v[96:99], v[152:155], v[200:203], v[96:99]
	v_mfma_f32_16x16x32_bf16 v[88:91], v[160:163], v[200:203], v[88:91]
	v_mfma_f32_16x16x32_bf16 v[80:83], v[152:155], v[212:215], v[80:83]
	v_mfma_f32_16x16x32_bf16 v[72:75], v[160:163], v[212:215], v[72:75]
	v_mfma_f32_16x16x32_bf16 v[116:119], v[164:167], v[180:183], 0
	v_mfma_f32_16x16x32_bf16 v[108:111], v[172:175], v[180:183], 0
	v_mfma_f32_16x16x32_bf16 v[100:103], v[164:167], v[188:191], 0
	v_mfma_f32_16x16x32_bf16 v[92:95], v[172:175], v[188:191], 0
	v_mfma_f32_16x16x32_bf16 v[84:87], v[164:167], v[196:199], 0
	v_mfma_f32_16x16x32_bf16 v[76:79], v[172:175], v[196:199], 0
	v_mfma_f32_16x16x32_bf16 v[68:71], v[164:167], v[208:211], 0
	v_mfma_f32_16x16x32_bf16 v[64:67], v[172:175], v[208:211], 0
	v_mfma_f32_16x16x32_bf16 v[116:119], v[168:171], v[184:187], v[116:119]
	v_mfma_f32_16x16x32_bf16 v[108:111], v[176:179], v[184:187], v[108:111]
	v_mfma_f32_16x16x32_bf16 v[100:103], v[168:171], v[192:195], v[100:103]
	v_mfma_f32_16x16x32_bf16 v[92:95], v[176:179], v[192:195], v[92:95]
	v_mfma_f32_16x16x32_bf16 v[84:87], v[168:171], v[200:203], v[84:87]
	v_mfma_f32_16x16x32_bf16 v[76:79], v[176:179], v[200:203], v[76:79]
	v_mfma_f32_16x16x32_bf16 v[68:71], v[168:171], v[212:215], v[68:71]
	v_mfma_f32_16x16x32_bf16 v[64:67], v[176:179], v[212:215], v[64:67]
	s_setprio 0
	s_barrier
	s_add_i32 s78, s67, s47
	v_lshl_add_u64 v[204:205], s[40:41], 0, v[130:131]
	s_mov_b32 m0, s78
	ds_read_b128 v[180:183], v147 offset:16384
	ds_read_b128 v[184:187], v147 offset:17408
	ds_read_b128 v[188:191], v147 offset:18432
	ds_read_b128 v[192:195], v147 offset:19456
	ds_read_b128 v[196:199], v147 offset:20480
	ds_read_b128 v[200:203], v147 offset:21504
	ds_read_b128 v[208:211], v147 offset:22528
	ds_read_b128 v[212:215], v147 offset:23552
	global_load_lds_dwordx4 v[204:205], off
	s_add_i32 m0, s78, 0x2000
	s_add_u32 s78, s40, 0x40000
	v_lshl_add_u64 v[216:217], s[40:41], 0, v[134:135]
	s_addc_u32 s79, s41, 0
	s_add_i32 s80, s68, s47
	global_load_lds_dwordx4 v[216:217], off
	v_lshl_add_u64 v[218:219], s[78:79], 0, v[130:131]
	s_mov_b32 m0, s80
	v_lshl_add_u64 v[220:221], s[42:43], 0, v[132:133]
	global_load_lds_dwordx4 v[218:219], off
	v_lshl_add_u64 v[218:219], s[78:79], 0, v[134:135]
	s_add_i32 m0, s80, 0x2000
	s_nop 0
	global_load_lds_dwordx4 v[218:219], off
	v_lshl_add_u64 v[218:219], s[42:43], 0, v[128:129]
	s_mov_b32 m0, s56
	s_nop 0
	global_load_lds_dwordx4 v[218:219], off
	s_mov_b32 m0, s57
	s_nop 0
	global_load_lds_dwordx4 v[220:221], off
	s_waitcnt vmcnt(8)
	s_waitcnt lgkmcnt(0)
	s_barrier
; #define PG8_STAGE(bufoff, gbase, voff) do { _Pragma("unroll") for (int _i = 0; _i < 2; ++_i) \
;         __builtin_amdgcn_global_load_lds((const unsigned*)((const char*)(gbase) + (voff)[_i]), (PG8_LAS unsigned*)(lds + (bufoff) + ldsw + _i * 8192), 16, 0, 0); } while (0)
; #define PG8_LDA(dst, b, h) do { _Pragma("unroll") for (int m = 0; m < 4; ++m) _Pragma("unroll") for (int k = 0; k < 2; ++k) dst[m][k] = *(const PG8_LAS bf16x8*)(lds + PG8_SA(b, h) + aoff + m * 2048 + k * 1024); } while (0)
; #define PG8_LDB(dst, b, h) do { _Pragma("unroll") for (int n = 0; n < 2; ++n) _Pragma("unroll") for (int k = 0; k < 2; ++k) dst[n][k] = *(const PG8_LAS bf16x8*)(lds + PG8_SB(b, h) + boff + n * 2048 + k * 1024); } while (0)
; #define PG8_MMA(ai, bj, At, Bt) do { __builtin_amdgcn_s_setprio(1); _Pragma("unroll") for (int m = 0; m < 4; ++m) _Pragma("unroll") for (int n = 0; n < 2; ++n) _Pragma("unroll") for (int k = 0; k < 2; ++k) \
;         acc[ai][bj][m][n] = __builtin_amdgcn_mfma_f32_16x16x32_bf16(Bt[n][k], At[m][k], acc[ai][bj][m][n], 0, 0, 0); __builtin_amdgcn_s_setprio(0); } while (0)
; #define PG8_WAIT_V(n) asm volatile("s_waitcnt vmcnt(" #n ")" ::: "memory")
; #define PG8_WAIT_L(n) asm volatile("s_waitcnt lgkmcnt(" #n ")" ::: "memory")
; #define PG8_BAR __builtin_amdgcn_s_barrier()
; #define PG8_SCHED __builtin_amdgcn_sched_barrier(0)
; template <class Epi, class Sched, bool ALIGN_EPI = false, bool SP2 = false>
; __device__ __forceinline__ void gemm_phase(PG8_LAS unsigned char* lds, const Gemm g, const Sched& S, const Epi& E) {
;     ...
;             PG8_LDA(At, 0, 1); PG8_STAGE(PG8_SB(0, 0), b2, voffB); PG8_STAGE(PG8_SB(0, 1), b2 + hstep, voffB); PG8_STAGE(PG8_SA(0, 0), a2, voffA);
;             PG8_WAIT_V(8); PG8_WAIT_L(0); PG8_BAR; PG8_MMA(1, 0, At, B0); PG8_MMA(1, 1, At, B1); PG8_BAR; PG8_SCHED;
;             PG8_LDB(B0, 1, 0); PG8_LDB(B1, 1, 1); PG8_SCHED; PG8_LDA(At, 1, 0); PG8_STAGE(PG8_SA(0, 1), a2 + hstep, voffA);
;             PG8_WAIT_V(8); PG8_WAIT_L(0); PG8_BAR; PG8_MMA(0, 0, At, B0); PG8_MMA(0, 1, At, B1); PG8_BAR; PG8_SCHED;
	s_setprio 1
	s_waitcnt lgkmcnt(0)
	v_mfma_f32_16x16x32_bf16 v[60:63], v[148:151], v[180:183], 0
	v_mfma_f32_16x16x32_bf16 v[56:59], v[156:159], v[180:183], 0
	v_mfma_f32_16x16x32_bf16 v[48:51], v[148:151], v[188:191], 0
	v_mfma_f32_16x16x32_bf16 v[40:43], v[156:159], v[188:191], 0
	v_mfma_f32_16x16x32_bf16 v[32:35], v[148:151], v[196:199], 0
	v_mfma_f32_16x16x32_bf16 v[24:27], v[156:159], v[196:199], 0
	v_mfma_f32_16x16x32_bf16 v[16:19], v[148:151], v[208:211], 0
	v_mfma_f32_16x16x32_bf16 v[8:11], v[156:159], v[208:211], 0
	v_mfma_f32_16x16x32_bf16 v[60:63], v[152:155], v[184:187], v[60:63]
	v_mfma_f32_16x16x32_bf16 v[56:59], v[160:163], v[184:187], v[56:59]
	v_mfma_f32_16x16x32_bf16 v[48:51], v[152:155], v[192:195], v[48:51]
	v_mfma_f32_16x16x32_bf16 v[40:43], v[160:163], v[192:195], v[40:43]
	v_mfma_f32_16x16x32_bf16 v[32:35], v[152:155], v[200:203], v[32:35]
	v_mfma_f32_16x16x32_bf16 v[24:27], v[160:163], v[200:203], v[24:27]
	v_mfma_f32_16x16x32_bf16 v[16:19], v[152:155], v[212:215], v[16:19]
	v_mfma_f32_16x16x32_bf16 v[8:11], v[160:163], v[212:215], v[8:11]
	v_mfma_f32_16x16x32_bf16 v[52:55], v[164:167], v[180:183], 0
	v_mfma_f32_16x16x32_bf16 v[44:47], v[172:175], v[180:183], 0
	v_mfma_f32_16x16x32_bf16 v[36:39], v[164:167], v[188:191], 0
	v_mfma_f32_16x16x32_bf16 v[28:31], v[172:175], v[188:191], 0
	v_mfma_f32_16x16x32_bf16 v[20:23], v[164:167], v[196:199], 0
	v_mfma_f32_16x16x32_bf16 v[12:15], v[172:175], v[196:199], 0
	v_mfma_f32_16x16x32_bf16 v[4:7], v[164:167], v[208:211], 0
	v_mfma_f32_16x16x32_bf16 v[0:3], v[172:175], v[208:211], 0
	v_mfma_f32_16x16x32_bf16 v[52:55], v[168:171], v[184:187], v[52:55]
	v_mfma_f32_16x16x32_bf16 v[44:47], v[176:179], v[184:187], v[44:47]
	v_mfma_f32_16x16x32_bf16 v[36:39], v[168:171], v[192:195], v[36:39]
	v_mfma_f32_16x16x32_bf16 v[28:31], v[176:179], v[192:195], v[28:31]
	v_mfma_f32_16x16x32_bf16 v[20:23], v[168:171], v[200:203], v[20:23]
	v_mfma_f32_16x16x32_bf16 v[12:15], v[176:179], v[200:203], v[12:15]
	v_mfma_f32_16x16x32_bf16 v[4:7], v[168:171], v[212:215], v[4:7]
	v_mfma_f32_16x16x32_bf16 v[0:3], v[176:179], v[212:215], v[0:3]
	s_setprio 0
	s_barrier
	s_add_i32 s78, 0, 0x18000
	s_add_i32 s79, 0, 0x1c000
	v_add_u32_e32 v160, s78, v143
	v_add_u32_e32 v176, s79, v143
	ds_read_b128 v[148:151], v160
	ds_read_b128 v[152:155], v160 offset:1024
	ds_read_b128 v[156:159], v160 offset:2048
	ds_read_b128 v[160:163], v160 offset:3072
	ds_read_b128 v[164:167], v176
	ds_read_b128 v[168:171], v176 offset:1024
	ds_read_b128 v[172:175], v176 offset:2048
	ds_read_b128 v[176:179], v176 offset:3072
	s_add_u32 s42, s42, 0x40000
	s_addc_u32 s43, s43, 0
	s_mov_b32 m0, s58
	v_lshl_add_u64 v[222:223], s[42:43], 0, v[128:129]
	ds_read_b128 v[180:183], v147 offset:32768
	ds_read_b128 v[184:187], v147 offset:33792
	ds_read_b128 v[188:191], v147 offset:34816
	ds_read_b128 v[192:195], v147 offset:35840
	ds_read_b128 v[196:199], v147 offset:36864
	ds_read_b128 v[200:203], v147 offset:37888
	ds_read_b128 v[208:211], v147 offset:38912
	ds_read_b128 v[212:215], v147 offset:39936
	global_load_lds_dwordx4 v[222:223], off
	v_lshl_add_u64 v[222:223], s[42:43], 0, v[132:133]
	s_mov_b32 m0, s59
	s_nop 0
	global_load_lds_dwordx4 v[222:223], off
	s_waitcnt vmcnt(8)
	s_waitcnt lgkmcnt(0)
	s_barrier
	s_setprio 1
	s_waitcnt lgkmcnt(0)
	v_mfma_f32_16x16x32_bf16 v[124:127], v[148:151], v[180:183], v[124:127]
	v_mfma_f32_16x16x32_bf16 v[120:123], v[156:159], v[180:183], v[120:123]
	v_mfma_f32_16x16x32_bf16 v[112:115], v[148:151], v[188:191], v[112:115]
	v_mfma_f32_16x16x32_bf16 v[104:107], v[156:159], v[188:191], v[104:107]
	v_mfma_f32_16x16x32_bf16 v[96:99], v[148:151], v[196:199], v[96:99]
	v_mfma_f32_16x16x32_bf16 v[88:91], v[156:159], v[196:199], v[88:91]
	v_mfma_f32_16x16x32_bf16 v[80:83], v[148:151], v[208:211], v[80:83]
	v_mfma_f32_16x16x32_bf16 v[72:75], v[156:159], v[208:211], v[72:75]
	v_mfma_f32_16x16x32_bf16 v[124:127], v[152:155], v[184:187], v[124:127]
	v_mfma_f32_16x16x32_bf16 v[120:123], v[160:163], v[184:187], v[120:123]
	v_mfma_f32_16x16x32_bf16 v[112:115], v[152:155], v[192:195], v[112:115]
	v_mfma_f32_16x16x32_bf16 v[104:107], v[160:163], v[192:195], v[104:107]
	v_mfma_f32_16x16x32_bf16 v[96:99], v[152:155], v[200:203], v[96:99]
	v_mfma_f32_16x16x32_bf16 v[88:91], v[160:163], v[200:203], v[88:91]
	v_mfma_f32_16x16x32_bf16 v[80:83], v[152:155], v[212:215], v[80:83]
	v_mfma_f32_16x16x32_bf16 v[72:75], v[160:163], v[212:215], v[72:75]
	v_mfma_f32_16x16x32_bf16 v[116:119], v[164:167], v[180:183], v[116:119]
	v_mfma_f32_16x16x32_bf16 v[108:111], v[172:175], v[180:183], v[108:111]
	v_mfma_f32_16x16x32_bf16 v[100:103], v[164:167], v[188:191], v[100:103]
	v_mfma_f32_16x16x32_bf16 v[92:95], v[172:175], v[188:191], v[92:95]
	v_mfma_f32_16x16x32_bf16 v[84:87], v[164:167], v[196:199], v[84:87]
	v_mfma_f32_16x16x32_bf16 v[76:79], v[172:175], v[196:199], v[76:79]
	v_mfma_f32_16x16x32_bf16 v[68:71], v[164:167], v[208:211], v[68:71]
	v_mfma_f32_16x16x32_bf16 v[64:67], v[172:175], v[208:211], v[64:67]
	v_mfma_f32_16x16x32_bf16 v[116:119], v[168:171], v[184:187], v[116:119]
	v_mfma_f32_16x16x32_bf16 v[108:111], v[176:179], v[184:187], v[108:111]
	v_mfma_f32_16x16x32_bf16 v[100:103], v[168:171], v[192:195], v[100:103]
	v_mfma_f32_16x16x32_bf16 v[92:95], v[176:179], v[192:195], v[92:95]
	v_mfma_f32_16x16x32_bf16 v[84:87], v[168:171], v[200:203], v[84:87]
	v_mfma_f32_16x16x32_bf16 v[76:79], v[176:179], v[200:203], v[76:79]
	v_mfma_f32_16x16x32_bf16 v[68:71], v[168:171], v[212:215], v[68:71]
	v_mfma_f32_16x16x32_bf16 v[64:67], v[176:179], v[212:215], v[64:67]
	s_setprio 0
	s_barrier
; #define PG8_STAGE(bufoff, gbase, voff) do { _Pragma("unroll") for (int _i = 0; _i < 2; ++_i) \
;         __builtin_amdgcn_global_load_lds((const unsigned*)((const char*)(gbase) + (voff)[_i]), (PG8_LAS unsigned*)(lds + (bufoff) + ldsw + _i * 8192), 16, 0, 0); } while (0)
; #define PG8_LDA(dst, b, h) do { _Pragma("unroll") for (int m = 0; m < 4; ++m) _Pragma("unroll") for (int k = 0; k < 2; ++k) dst[m][k] = *(const PG8_LAS bf16x8*)(lds + PG8_SA(b, h) + aoff + m * 2048 + k * 1024); } while (0)
; #define PG8_LDB(dst, b, h) do { _Pragma("unroll") for (int n = 0; n < 2; ++n) _Pragma("unroll") for (int k = 0; k < 2; ++k) dst[n][k] = *(const PG8_LAS bf16x8*)(lds + PG8_SB(b, h) + boff + n * 2048 + k * 1024); } while (0)
; #define PG8_MMA(ai, bj, At, Bt) do { __builtin_amdgcn_s_setprio(1); _Pragma("unroll") for (int m = 0; m < 4; ++m) _Pragma("unroll") for (int n = 0; n < 2; ++n) _Pragma("unroll") for (int k = 0; k < 2; ++k) \
;         acc[ai][bj][m][n] = __builtin_amdgcn_mfma_f32_16x16x32_bf16(Bt[n][k], At[m][k], acc[ai][bj][m][n], 0, 0, 0); __builtin_amdgcn_s_setprio(0); } while (0)
; #define PG8_WAIT_V(n) asm volatile("s_waitcnt vmcnt(" #n ")" ::: "memory")
; #define PG8_WAIT_L(n) asm volatile("s_waitcnt lgkmcnt(" #n ")" ::: "memory")
; #define PG8_BAR __builtin_amdgcn_s_barrier()
; #define PG8_SCHED __builtin_amdgcn_sched_barrier(0)
; template <class Epi, class Sched, bool ALIGN_EPI = false, bool SP2 = false>
; __device__ __forceinline__ void gemm_phase(PG8_LAS unsigned char* lds, const Gemm g, const Sched& S, const Epi& E) {
;     ...
;             PG8_LDB(B0, 0, 0); PG8_LDB(B1, 0, 1); PG8_SCHED; PG8_LDA(At, 0, 0); PG8_STAGE(PG8_SA(1, 1), a1 + hstep, voffA);
;             PG8_WAIT_V(8); PG8_WAIT_L(0); PG8_BAR; PG8_MMA(0, 0, At, B0); PG8_MMA(0, 1, At, B1); PG8_BAR; PG8_SCHED;
;     ...
;             PG8_LDA(At, 1, 1); PG8_STAGE(PG8_SB(1, 0), b3, voffB); PG8_STAGE(PG8_SB(1, 1), b3 + hstep, voffB); PG8_STAGE(PG8_SA(1, 0), a3, voffA);
;             PG8_WAIT_V(8); PG8_WAIT_L(0); PG8_BAR; PG8_MMA(1, 0, At, B0); PG8_MMA(1, 1, At, B1); PG8_BAR; PG8_SCHED;
	s_add_i32 s42, s78, s47
	v_lshl_add_u64 v[204:205], v[204:205], 0, s[8:9]
	s_mov_b32 m0, s42
	ds_read_b128 v[180:183], v147 offset:49152
	ds_read_b128 v[184:187], v147 offset:50176
	ds_read_b128 v[188:191], v147 offset:51200
	ds_read_b128 v[192:195], v147 offset:52224
	ds_read_b128 v[196:199], v147 offset:53248
	ds_read_b128 v[200:203], v147 offset:54272
	ds_read_b128 v[208:211], v147 offset:55296
	ds_read_b128 v[212:215], v147 offset:56320
	global_load_lds_dwordx4 v[204:205], off
	s_add_i32 m0, s42, 0x2000
	s_add_u32 s40, s40, 0x40080
	v_lshl_add_u64 v[204:205], v[216:217], 0, s[8:9]
	s_addc_u32 s41, s41, 0
	s_add_i32 s42, s79, s47
	global_load_lds_dwordx4 v[204:205], off
	v_lshl_add_u64 v[204:205], s[40:41], 0, v[130:131]
	s_mov_b32 m0, s42
	s_nop 0
	global_load_lds_dwordx4 v[204:205], off
	v_lshl_add_u64 v[204:205], s[40:41], 0, v[134:135]
	s_add_i32 m0, s42, 0x2000
	s_nop 0
	global_load_lds_dwordx4 v[204:205], off
	v_lshl_add_u64 v[204:205], v[218:219], 0, s[8:9]
	s_mov_b32 m0, s64
	s_nop 0
	global_load_lds_dwordx4 v[204:205], off
	v_lshl_add_u64 v[204:205], v[220:221], 0, s[8:9]
	s_mov_b32 m0, s65
	s_nop 0
	global_load_lds_dwordx4 v[204:205], off
	s_waitcnt vmcnt(8)
	s_waitcnt lgkmcnt(0)
	s_barrier
	s_setprio 1
	s_waitcnt lgkmcnt(0)
	v_mfma_f32_16x16x32_bf16 v[60:63], v[148:151], v[180:183], v[60:63]
	v_mfma_f32_16x16x32_bf16 v[56:59], v[156:159], v[180:183], v[56:59]
	v_mfma_f32_16x16x32_bf16 v[48:51], v[148:151], v[188:191], v[48:51]
	v_mfma_f32_16x16x32_bf16 v[40:43], v[156:159], v[188:191], v[40:43]
	v_mfma_f32_16x16x32_bf16 v[32:35], v[148:151], v[196:199], v[32:35]
	v_mfma_f32_16x16x32_bf16 v[24:27], v[156:159], v[196:199], v[24:27]
	v_mfma_f32_16x16x32_bf16 v[16:19], v[148:151], v[208:211], v[16:19]
	v_mfma_f32_16x16x32_bf16 v[8:11], v[156:159], v[208:211], v[8:11]
	v_mfma_f32_16x16x32_bf16 v[60:63], v[152:155], v[184:187], v[60:63]
	v_mfma_f32_16x16x32_bf16 v[56:59], v[160:163], v[184:187], v[56:59]
	v_mfma_f32_16x16x32_bf16 v[48:51], v[152:155], v[192:195], v[48:51]
	v_mfma_f32_16x16x32_bf16 v[40:43], v[160:163], v[192:195], v[40:43]
	v_mfma_f32_16x16x32_bf16 v[32:35], v[152:155], v[200:203], v[32:35]
	v_mfma_f32_16x16x32_bf16 v[24:27], v[160:163], v[200:203], v[24:27]
	v_mfma_f32_16x16x32_bf16 v[16:19], v[152:155], v[212:215], v[16:19]
	v_mfma_f32_16x16x32_bf16 v[8:11], v[160:163], v[212:215], v[8:11]
	v_mfma_f32_16x16x32_bf16 v[52:55], v[164:167], v[180:183], v[52:55]
	v_mfma_f32_16x16x32_bf16 v[44:47], v[172:175], v[180:183], v[44:47]
	v_mfma_f32_16x16x32_bf16 v[36:39], v[164:167], v[188:191], v[36:39]
	v_mfma_f32_16x16x32_bf16 v[28:31], v[172:175], v[188:191], v[28:31]
	v_mfma_f32_16x16x32_bf16 v[20:23], v[164:167], v[196:199], v[20:23]
	v_mfma_f32_16x16x32_bf16 v[12:15], v[172:175], v[196:199], v[12:15]
	v_mfma_f32_16x16x32_bf16 v[4:7], v[164:167], v[208:211], v[4:7]
	v_mfma_f32_16x16x32_bf16 v[0:3], v[172:175], v[208:211], v[0:3]
	v_mfma_f32_16x16x32_bf16 v[52:55], v[168:171], v[184:187], v[52:55]
	v_mfma_f32_16x16x32_bf16 v[44:47], v[176:179], v[184:187], v[44:47]
	v_mfma_f32_16x16x32_bf16 v[36:39], v[168:171], v[192:195], v[36:39]
	v_mfma_f32_16x16x32_bf16 v[28:31], v[176:179], v[192:195], v[28:31]
	v_mfma_f32_16x16x32_bf16 v[20:23], v[168:171], v[200:203], v[20:23]
	v_mfma_f32_16x16x32_bf16 v[12:15], v[176:179], v[200:203], v[12:15]
	v_mfma_f32_16x16x32_bf16 v[4:7], v[168:171], v[212:215], v[4:7]
	v_mfma_f32_16x16x32_bf16 v[0:3], v[176:179], v[212:215], v[0:3]
	s_setprio 0
	s_barrier
	s_add_i32 s77, s77, 2
	s_add_u32 s38, s38, 0x100
	s_addc_u32 s39, s39, 0
	s_add_u32 s75, s75, 0x100
	s_addc_u32 s76, s76, 0
	s_cmp_gt_u32 s77, 13
	s_cbranch_scc0 .LBB0_1349
	s_branch .Lpeel_exit_9
.LBB0_1349:
	ds_read_b128 v[148:151], v145
	ds_read_b128 v[152:155], v145 offset:1024
	ds_read_b128 v[156:159], v145 offset:2048
	ds_read_b128 v[160:163], v145 offset:3072
	ds_read_b128 v[164:167], v146
	ds_read_b128 v[168:171], v146 offset:1024
	ds_read_b128 v[172:175], v146 offset:2048
	ds_read_b128 v[176:179], v146 offset:3072
	s_add_u32 s40, s38, 0xfffc0080
	s_addc_u32 s41, s39, -1
	s_cmp_eq_u32 s77, 12
	s_cselect_b32 s43, s25, s41
	s_cselect_b32 s42, s73, s40
	s_cselect_b32 s41, s23, s76
	s_cselect_b32 s40, s74, s75
	v_lshl_add_u64 v[204:205], s[38:39], 0, v[136:137]
	s_add_i32 m0, s56, 0xc000
	ds_read_b128 v[180:183], v147
	ds_read_b128 v[184:187], v147 offset:1024
	ds_read_b128 v[188:191], v147 offset:2048
	ds_read_b128 v[192:195], v147 offset:3072
	ds_read_b128 v[196:199], v147 offset:4096
	ds_read_b128 v[200:203], v147 offset:5120
	ds_read_b128 v[208:211], v147 offset:6144
	ds_read_b128 v[212:215], v147 offset:7168
	global_load_lds_dwordx4 v[204:205], off
	v_lshl_add_u64 v[204:205], s[38:39], 0, v[138:139]
	s_add_i32 m0, s56, 0xe000
	s_nop 0
	global_load_lds_dwordx4 v[204:205], off
	s_waitcnt vmcnt(8)
	s_waitcnt lgkmcnt(0)
	s_barrier
; #define PG8_STAGE(bufoff, gbase, voff) do { _Pragma("unroll") for (int _i = 0; _i < 2; ++_i) \
;         __builtin_amdgcn_global_load_lds((const unsigned*)((const char*)(gbase) + (voff)[_i]), (PG8_LAS unsigned*)(lds + (bufoff) + ldsw + _i * 8192), 16, 0, 0); } while (0)
; #define PG8_LDA(dst, b, h) do { _Pragma("unroll") for (int m = 0; m < 4; ++m) _Pragma("unroll") for (int k = 0; k < 2; ++k) dst[m][k] = *(const PG8_LAS bf16x8*)(lds + PG8_SA(b, h) + aoff + m * 2048 + k * 1024); } while (0)
; #define PG8_LDB(dst, b, h) do { _Pragma("unroll") for (int n = 0; n < 2; ++n) _Pragma("unroll") for (int k = 0; k < 2; ++k) dst[n][k] = *(const PG8_LAS bf16x8*)(lds + PG8_SB(b, h) + boff + n * 2048 + k * 1024); } while (0)
; #define PG8_MMA(ai, bj, At, Bt) do { __builtin_amdgcn_s_setprio(1); _Pragma("unroll") for (int m = 0; m < 4; ++m) _Pragma("unroll") for (int n = 0; n < 2; ++n) _Pragma("unroll") for (int k = 0; k < 2; ++k) \
;         acc[ai][bj][m][n] = __builtin_amdgcn_mfma_f32_16x16x32_bf16(Bt[n][k], At[m][k], acc[ai][bj][m][n], 0, 0, 0); __builtin_amdgcn_s_setprio(0); } while (0)
; #define PG8_WAIT_V(n) asm volatile("s_waitcnt vmcnt(" #n ")" ::: "memory")
; #define PG8_WAIT_L(n) asm volatile("s_waitcnt lgkmcnt(" #n ")" ::: "memory")
; #define PG8_BAR __builtin_amdgcn_s_barrier()
; #define PG8_SCHED __builtin_amdgcn_sched_barrier(0)
; template <class Epi, class Sched, bool ALIGN_EPI = false, bool SP2 = false>
; __device__ __forceinline__ void gemm_phase(PG8_LAS unsigned char* lds, const Gemm g, const Sched& S, const Epi& E) {
;     ...
;             PG8_WAIT_V(8); PG8_WAIT_L(0); PG8_BAR; PG8_MMA(0, 0, At, B0); PG8_MMA(0, 1, At, B1); PG8_BAR; PG8_SCHED;
;             PG8_LDA(At, 0, 1); PG8_STAGE(PG8_SB(0, 0), b2, voffB); PG8_STAGE(PG8_SB(0, 1), b2 + hstep, voffB); PG8_STAGE(PG8_SA(0, 0), a2, voffA);
;             PG8_WAIT_V(8); PG8_WAIT_L(0); PG8_BAR; PG8_MMA(1, 0, At, B0); PG8_MMA(1, 1, At, B1); PG8_BAR; PG8_SCHED;
;             PG8_LDB(B0, 1, 0); PG8_LDB(B1, 1, 1); PG8_SCHED; PG8_LDA(At, 1, 0); PG8_STAGE(PG8_SA(0, 1), a2 + hstep, voffA);
;             PG8_WAIT_V(8); PG8_WAIT_L(0); PG8_BAR; PG8_MMA(0, 0, At, B0); PG8_MMA(0, 1, At, B1); PG8_BAR; PG8_SCHED;
	s_setprio 1
	s_waitcnt lgkmcnt(0)
	v_mfma_f32_16x16x32_bf16 v[124:127], v[148:151], v[180:183], v[124:127]
	v_mfma_f32_16x16x32_bf16 v[120:123], v[156:159], v[180:183], v[120:123]
	v_mfma_f32_16x16x32_bf16 v[112:115], v[148:151], v[188:191], v[112:115]
	v_mfma_f32_16x16x32_bf16 v[104:107], v[156:159], v[188:191], v[104:107]
	v_mfma_f32_16x16x32_bf16 v[96:99], v[148:151], v[196:199], v[96:99]
	v_mfma_f32_16x16x32_bf16 v[88:91], v[156:159], v[196:199], v[88:91]
	v_mfma_f32_16x16x32_bf16 v[80:83], v[148:151], v[208:211], v[80:83]
	v_mfma_f32_16x16x32_bf16 v[72:75], v[156:159], v[208:211], v[72:75]
	v_mfma_f32_16x16x32_bf16 v[124:127], v[152:155], v[184:187], v[124:127]
	v_mfma_f32_16x16x32_bf16 v[120:123], v[160:163], v[184:187], v[120:123]
	v_mfma_f32_16x16x32_bf16 v[112:115], v[152:155], v[192:195], v[112:115]
	v_mfma_f32_16x16x32_bf16 v[104:107], v[160:163], v[192:195], v[104:107]
	v_mfma_f32_16x16x32_bf16 v[96:99], v[152:155], v[200:203], v[96:99]
	v_mfma_f32_16x16x32_bf16 v[88:91], v[160:163], v[200:203], v[88:91]
	v_mfma_f32_16x16x32_bf16 v[80:83], v[152:155], v[212:215], v[80:83]
	v_mfma_f32_16x16x32_bf16 v[72:75], v[160:163], v[212:215], v[72:75]
	v_mfma_f32_16x16x32_bf16 v[116:119], v[164:167], v[180:183], v[116:119]
	v_mfma_f32_16x16x32_bf16 v[108:111], v[172:175], v[180:183], v[108:111]
	v_mfma_f32_16x16x32_bf16 v[100:103], v[164:167], v[188:191], v[100:103]
	v_mfma_f32_16x16x32_bf16 v[92:95], v[172:175], v[188:191], v[92:95]
	v_mfma_f32_16x16x32_bf16 v[84:87], v[164:167], v[196:199], v[84:87]
	v_mfma_f32_16x16x32_bf16 v[76:79], v[172:175], v[196:199], v[76:79]
	v_mfma_f32_16x16x32_bf16 v[68:71], v[164:167], v[208:211], v[68:71]
	v_mfma_f32_16x16x32_bf16 v[64:67], v[172:175], v[208:211], v[64:67]
	v_mfma_f32_16x16x32_bf16 v[116:119], v[168:171], v[184:187], v[116:119]
	v_mfma_f32_16x16x32_bf16 v[108:111], v[176:179], v[184:187], v[108:111]
	v_mfma_f32_16x16x32_bf16 v[100:103], v[168:171], v[192:195], v[100:103]
	v_mfma_f32_16x16x32_bf16 v[92:95], v[176:179], v[192:195], v[92:95]
	v_mfma_f32_16x16x32_bf16 v[84:87], v[168:171], v[200:203], v[84:87]
	v_mfma_f32_16x16x32_bf16 v[76:79], v[176:179], v[200:203], v[76:79]
	v_mfma_f32_16x16x32_bf16 v[68:71], v[168:171], v[212:215], v[68:71]
	v_mfma_f32_16x16x32_bf16 v[64:67], v[176:179], v[212:215], v[64:67]
	s_setprio 0
	s_barrier
	s_add_i32 s78, s67, s47
	v_lshl_add_u64 v[204:205], s[40:41], 0, v[130:131]
	s_mov_b32 m0, s78
	ds_read_b128 v[180:183], v147 offset:16384
	ds_read_b128 v[184:187], v147 offset:17408
	ds_read_b128 v[188:191], v147 offset:18432
	ds_read_b128 v[192:195], v147 offset:19456
	ds_read_b128 v[196:199], v147 offset:20480
	ds_read_b128 v[200:203], v147 offset:21504
	ds_read_b128 v[208:211], v147 offset:22528
	ds_read_b128 v[212:215], v147 offset:23552
	global_load_lds_dwordx4 v[204:205], off
	s_add_i32 m0, s78, 0x2000
	s_add_u32 s78, s40, 0x40000
	v_lshl_add_u64 v[216:217], s[40:41], 0, v[134:135]
	s_addc_u32 s79, s41, 0
	s_add_i32 s80, s68, s47
	global_load_lds_dwordx4 v[216:217], off
	v_lshl_add_u64 v[218:219], s[78:79], 0, v[130:131]
	s_mov_b32 m0, s80
	v_lshl_add_u64 v[220:221], s[42:43], 0, v[132:133]
	global_load_lds_dwordx4 v[218:219], off
	v_lshl_add_u64 v[218:219], s[78:79], 0, v[134:135]
	s_add_i32 m0, s80, 0x2000
	s_nop 0
	global_load_lds_dwordx4 v[218:219], off
	v_lshl_add_u64 v[218:219], s[42:43], 0, v[128:129]
	s_mov_b32 m0, s56
	s_nop 0
	global_load_lds_dwordx4 v[218:219], off
	s_mov_b32 m0, s57
	s_nop 0
	global_load_lds_dwordx4 v[220:221], off
	s_waitcnt vmcnt(8)
	s_waitcnt lgkmcnt(0)
	s_barrier
	s_setprio 1
	s_waitcnt lgkmcnt(0)
	v_mfma_f32_16x16x32_bf16 v[60:63], v[148:151], v[180:183], v[60:63]
	v_mfma_f32_16x16x32_bf16 v[56:59], v[156:159], v[180:183], v[56:59]
	v_mfma_f32_16x16x32_bf16 v[48:51], v[148:151], v[188:191], v[48:51]
	v_mfma_f32_16x16x32_bf16 v[40:43], v[156:159], v[188:191], v[40:43]
	v_mfma_f32_16x16x32_bf16 v[32:35], v[148:151], v[196:199], v[32:35]
	v_mfma_f32_16x16x32_bf16 v[24:27], v[156:159], v[196:199], v[24:27]
	v_mfma_f32_16x16x32_bf16 v[16:19], v[148:151], v[208:211], v[16:19]
	v_mfma_f32_16x16x32_bf16 v[8:11], v[156:159], v[208:211], v[8:11]
	v_mfma_f32_16x16x32_bf16 v[60:63], v[152:155], v[184:187], v[60:63]
	v_mfma_f32_16x16x32_bf16 v[56:59], v[160:163], v[184:187], v[56:59]
	v_mfma_f32_16x16x32_bf16 v[48:51], v[152:155], v[192:195], v[48:51]
	v_mfma_f32_16x16x32_bf16 v[40:43], v[160:163], v[192:195], v[40:43]
	v_mfma_f32_16x16x32_bf16 v[32:35], v[152:155], v[200:203], v[32:35]
	v_mfma_f32_16x16x32_bf16 v[24:27], v[160:163], v[200:203], v[24:27]
	v_mfma_f32_16x16x32_bf16 v[16:19], v[152:155], v[212:215], v[16:19]
	v_mfma_f32_16x16x32_bf16 v[8:11], v[160:163], v[212:215], v[8:11]
	v_mfma_f32_16x16x32_bf16 v[52:55], v[164:167], v[180:183], v[52:55]
	v_mfma_f32_16x16x32_bf16 v[44:47], v[172:175], v[180:183], v[44:47]
	v_mfma_f32_16x16x32_bf16 v[36:39], v[164:167], v[188:191], v[36:39]
	v_mfma_f32_16x16x32_bf16 v[28:31], v[172:175], v[188:191], v[28:31]
	v_mfma_f32_16x16x32_bf16 v[20:23], v[164:167], v[196:199], v[20:23]
	v_mfma_f32_16x16x32_bf16 v[12:15], v[172:175], v[196:199], v[12:15]
	v_mfma_f32_16x16x32_bf16 v[4:7], v[164:167], v[208:211], v[4:7]
	v_mfma_f32_16x16x32_bf16 v[0:3], v[172:175], v[208:211], v[0:3]
	v_mfma_f32_16x16x32_bf16 v[52:55], v[168:171], v[184:187], v[52:55]
	v_mfma_f32_16x16x32_bf16 v[44:47], v[176:179], v[184:187], v[44:47]
	v_mfma_f32_16x16x32_bf16 v[36:39], v[168:171], v[192:195], v[36:39]
	v_mfma_f32_16x16x32_bf16 v[28:31], v[176:179], v[192:195], v[28:31]
	v_mfma_f32_16x16x32_bf16 v[20:23], v[168:171], v[200:203], v[20:23]
	v_mfma_f32_16x16x32_bf16 v[12:15], v[176:179], v[200:203], v[12:15]
	v_mfma_f32_16x16x32_bf16 v[4:7], v[168:171], v[212:215], v[4:7]
	v_mfma_f32_16x16x32_bf16 v[0:3], v[176:179], v[212:215], v[0:3]
	s_setprio 0
	s_barrier
; #define PG8_STAGE(bufoff, gbase, voff) do { _Pragma("unroll") for (int _i = 0; _i < 2; ++_i) \
;         __builtin_amdgcn_global_load_lds((const unsigned*)((const char*)(gbase) + (voff)[_i]), (PG8_LAS unsigned*)(lds + (bufoff) + ldsw + _i * 8192), 16, 0, 0); } while (0)
; #define PG8_LDA(dst, b, h) do { _Pragma("unroll") for (int m = 0; m < 4; ++m) _Pragma("unroll") for (int k = 0; k < 2; ++k) dst[m][k] = *(const PG8_LAS bf16x8*)(lds + PG8_SA(b, h) + aoff + m * 2048 + k * 1024); } while (0)
; #define PG8_LDB(dst, b, h) do { _Pragma("unroll") for (int n = 0; n < 2; ++n) _Pragma("unroll") for (int k = 0; k < 2; ++k) dst[n][k] = *(const PG8_LAS bf16x8*)(lds + PG8_SB(b, h) + boff + n * 2048 + k * 1024); } while (0)
; #define PG8_MMA(ai, bj, At, Bt) do { __builtin_amdgcn_s_setprio(1); _Pragma("unroll") for (int m = 0; m < 4; ++m) _Pragma("unroll") for (int n = 0; n < 2; ++n) _Pragma("unroll") for (int k = 0; k < 2; ++k) \
;         acc[ai][bj][m][n] = __builtin_amdgcn_mfma_f32_16x16x32_bf16(Bt[n][k], At[m][k], acc[ai][bj][m][n], 0, 0, 0); __builtin_amdgcn_s_setprio(0); } while (0)
; #define PG8_WAIT_V(n) asm volatile("s_waitcnt vmcnt(" #n ")" ::: "memory")
; #define PG8_WAIT_L(n) asm volatile("s_waitcnt lgkmcnt(" #n ")" ::: "memory")
; #define PG8_BAR __builtin_amdgcn_s_barrier()
; #define PG8_SCHED __builtin_amdgcn_sched_barrier(0)
; template <class Epi, class Sched, bool ALIGN_EPI = false, bool SP2 = false>
; __device__ __forceinline__ void gemm_phase(PG8_LAS unsigned char* lds, const Gemm g, const Sched& S, const Epi& E) {
;     ...
;             PG8_LDB(B0, 1, 0); PG8_LDB(B1, 1, 1); PG8_SCHED; PG8_LDA(At, 1, 0); PG8_STAGE(PG8_SA(0, 1), a2 + hstep, voffA);
;             PG8_WAIT_V(8); PG8_WAIT_L(0); PG8_BAR; PG8_MMA(0, 0, At, B0); PG8_MMA(0, 1, At, B1); PG8_BAR; PG8_SCHED;
	s_add_i32 s78, 0, 0x18000
	s_add_i32 s79, 0, 0x1c000
	v_add_u32_e32 v160, s78, v143
	v_add_u32_e32 v176, s79, v143
	ds_read_b128 v[148:151], v160
	ds_read_b128 v[152:155], v160 offset:1024
	ds_read_b128 v[156:159], v160 offset:2048
	ds_read_b128 v[160:163], v160 offset:3072
	ds_read_b128 v[164:167], v176
	ds_read_b128 v[168:171], v176 offset:1024
	ds_read_b128 v[172:175], v176 offset:2048
	ds_read_b128 v[176:179], v176 offset:3072
	s_add_u32 s42, s42, 0x40000
	s_addc_u32 s43, s43, 0
	s_mov_b32 m0, s58
	v_lshl_add_u64 v[222:223], s[42:43], 0, v[128:129]
	ds_read_b128 v[180:183], v147 offset:32768
	ds_read_b128 v[184:187], v147 offset:33792
	ds_read_b128 v[188:191], v147 offset:34816
	ds_read_b128 v[192:195], v147 offset:35840
	ds_read_b128 v[196:199], v147 offset:36864
	ds_read_b128 v[200:203], v147 offset:37888
	ds_read_b128 v[208:211], v147 offset:38912
	ds_read_b128 v[212:215], v147 offset:39936
	global_load_lds_dwordx4 v[222:223], off
	v_lshl_add_u64 v[222:223], s[42:43], 0, v[132:133]
	s_mov_b32 m0, s59
	s_nop 0
	global_load_lds_dwordx4 v[222:223], off
	s_waitcnt vmcnt(8)
	s_waitcnt lgkmcnt(0)
	s_barrier
	s_setprio 1
	s_waitcnt lgkmcnt(0)
	v_mfma_f32_16x16x32_bf16 v[124:127], v[148:151], v[180:183], v[124:127]
	v_mfma_f32_16x16x32_bf16 v[120:123], v[156:159], v[180:183], v[120:123]
	v_mfma_f32_16x16x32_bf16 v[112:115], v[148:151], v[188:191], v[112:115]
	v_mfma_f32_16x16x32_bf16 v[104:107], v[156:159], v[188:191], v[104:107]
	v_mfma_f32_16x16x32_bf16 v[96:99], v[148:151], v[196:199], v[96:99]
	v_mfma_f32_16x16x32_bf16 v[88:91], v[156:159], v[196:199], v[88:91]
	v_mfma_f32_16x16x32_bf16 v[80:83], v[148:151], v[208:211], v[80:83]
	v_mfma_f32_16x16x32_bf16 v[72:75], v[156:159], v[208:211], v[72:75]
	v_mfma_f32_16x16x32_bf16 v[124:127], v[152:155], v[184:187], v[124:127]
	v_mfma_f32_16x16x32_bf16 v[120:123], v[160:163], v[184:187], v[120:123]
	v_mfma_f32_16x16x32_bf16 v[112:115], v[152:155], v[192:195], v[112:115]
	v_mfma_f32_16x16x32_bf16 v[104:107], v[160:163], v[192:195], v[104:107]
	v_mfma_f32_16x16x32_bf16 v[96:99], v[152:155], v[200:203], v[96:99]
	v_mfma_f32_16x16x32_bf16 v[88:91], v[160:163], v[200:203], v[88:91]
	v_mfma_f32_16x16x32_bf16 v[80:83], v[152:155], v[212:215], v[80:83]
	v_mfma_f32_16x16x32_bf16 v[72:75], v[160:163], v[212:215], v[72:75]
	v_mfma_f32_16x16x32_bf16 v[116:119], v[164:167], v[180:183], v[116:119]
	v_mfma_f32_16x16x32_bf16 v[108:111], v[172:175], v[180:183], v[108:111]
	v_mfma_f32_16x16x32_bf16 v[100:103], v[164:167], v[188:191], v[100:103]
	v_mfma_f32_16x16x32_bf16 v[92:95], v[172:175], v[188:191], v[92:95]
	v_mfma_f32_16x16x32_bf16 v[84:87], v[164:167], v[196:199], v[84:87]
	v_mfma_f32_16x16x32_bf16 v[76:79], v[172:175], v[196:199], v[76:79]
	v_mfma_f32_16x16x32_bf16 v[68:71], v[164:167], v[208:211], v[68:71]
	v_mfma_f32_16x16x32_bf16 v[64:67], v[172:175], v[208:211], v[64:67]
	v_mfma_f32_16x16x32_bf16 v[116:119], v[168:171], v[184:187], v[116:119]
	v_mfma_f32_16x16x32_bf16 v[108:111], v[176:179], v[184:187], v[108:111]
	v_mfma_f32_16x16x32_bf16 v[100:103], v[168:171], v[192:195], v[100:103]
	v_mfma_f32_16x16x32_bf16 v[92:95], v[176:179], v[192:195], v[92:95]
	v_mfma_f32_16x16x32_bf16 v[84:87], v[168:171], v[200:203], v[84:87]
	v_mfma_f32_16x16x32_bf16 v[76:79], v[176:179], v[200:203], v[76:79]
	v_mfma_f32_16x16x32_bf16 v[68:71], v[168:171], v[212:215], v[68:71]
	v_mfma_f32_16x16x32_bf16 v[64:67], v[176:179], v[212:215], v[64:67]
	s_setprio 0
	s_barrier
; #define PG8_STAGE(bufoff, gbase, voff) do { _Pragma("unroll") for (int _i = 0; _i < 2; ++_i) \
;         __builtin_amdgcn_global_load_lds((const unsigned*)((const char*)(gbase) + (voff)[_i]), (PG8_LAS unsigned*)(lds + (bufoff) + ldsw + _i * 8192), 16, 0, 0); } while (0)
; #define PG8_LDA(dst, b, h) do { _Pragma("unroll") for (int m = 0; m < 4; ++m) _Pragma("unroll") for (int k = 0; k < 2; ++k) dst[m][k] = *(const PG8_LAS bf16x8*)(lds + PG8_SA(b, h) + aoff + m * 2048 + k * 1024); } while (0)
; #define PG8_MMA(ai, bj, At, Bt) do { __builtin_amdgcn_s_setprio(1); _Pragma("unroll") for (int m = 0; m < 4; ++m) _Pragma("unroll") for (int n = 0; n < 2; ++n) _Pragma("unroll") for (int k = 0; k < 2; ++k) \
;         acc[ai][bj][m][n] = __builtin_amdgcn_mfma_f32_16x16x32_bf16(Bt[n][k], At[m][k], acc[ai][bj][m][n], 0, 0, 0); __builtin_amdgcn_s_setprio(0); } while (0)
; #define PG8_WAIT_V(n) asm volatile("s_waitcnt vmcnt(" #n ")" ::: "memory")
; #define PG8_WAIT_L(n) asm volatile("s_waitcnt lgkmcnt(" #n ")" ::: "memory")
; #define PG8_BAR __builtin_amdgcn_s_barrier()
; #define PG8_SCHED __builtin_amdgcn_sched_barrier(0)
; template <class Epi, class Sched, bool ALIGN_EPI = false, bool SP2 = false>
; __device__ __forceinline__ void gemm_phase(PG8_LAS unsigned char* lds, const Gemm g, const Sched& S, const Epi& E) {
;     ...
;         for (int t = 0; t < nt; t += 2) {
;             const bool last = (t == nt - 2);
;             const char* a1 = cA + (size_t)(t + 1) * kstep;
;             const char* a2 = last ? nA : cA + (size_t)(t + 2) * kstep; const char* b2 = last ? nB : cB + (size_t)(t + 2) * kstep;
;             const char* a3 = a2 + kstep; const char* b3 = b2 + kstep;
;     ...
;             PG8_LDA(At, 1, 1); PG8_STAGE(PG8_SB(1, 0), b3, voffB); PG8_STAGE(PG8_SB(1, 1), b3 + hstep, voffB); PG8_STAGE(PG8_SA(1, 0), a3, voffA);
;             PG8_WAIT_V(8); PG8_WAIT_L(0); PG8_BAR; PG8_MMA(1, 0, At, B0); PG8_MMA(1, 1, At, B1); PG8_BAR; PG8_SCHED;
	s_add_i32 s42, s78, s47
	v_lshl_add_u64 v[204:205], v[204:205], 0, s[8:9]
	s_mov_b32 m0, s42
	ds_read_b128 v[180:183], v147 offset:49152
	ds_read_b128 v[184:187], v147 offset:50176
	ds_read_b128 v[188:191], v147 offset:51200
	ds_read_b128 v[192:195], v147 offset:52224
	ds_read_b128 v[196:199], v147 offset:53248
	ds_read_b128 v[200:203], v147 offset:54272
	ds_read_b128 v[208:211], v147 offset:55296
	ds_read_b128 v[212:215], v147 offset:56320
	global_load_lds_dwordx4 v[204:205], off
	s_add_i32 m0, s42, 0x2000
	s_add_u32 s40, s40, 0x40080
	v_lshl_add_u64 v[204:205], v[216:217], 0, s[8:9]
	s_addc_u32 s41, s41, 0
	s_add_i32 s42, s79, s47
	global_load_lds_dwordx4 v[204:205], off
	v_lshl_add_u64 v[204:205], s[40:41], 0, v[130:131]
	s_mov_b32 m0, s42
	s_nop 0
	global_load_lds_dwordx4 v[204:205], off
	v_lshl_add_u64 v[204:205], s[40:41], 0, v[134:135]
	s_add_i32 m0, s42, 0x2000
	s_nop 0
	global_load_lds_dwordx4 v[204:205], off
	v_lshl_add_u64 v[204:205], v[218:219], 0, s[8:9]
	s_mov_b32 m0, s64
	s_nop 0
	global_load_lds_dwordx4 v[204:205], off
	v_lshl_add_u64 v[204:205], v[220:221], 0, s[8:9]
	s_mov_b32 m0, s65
	s_nop 0
	global_load_lds_dwordx4 v[204:205], off
	s_waitcnt vmcnt(8)
	s_waitcnt lgkmcnt(0)
	s_barrier
	s_setprio 1
	s_waitcnt lgkmcnt(0)
	v_mfma_f32_16x16x32_bf16 v[60:63], v[148:151], v[180:183], v[60:63]
	v_mfma_f32_16x16x32_bf16 v[56:59], v[156:159], v[180:183], v[56:59]
	v_mfma_f32_16x16x32_bf16 v[48:51], v[148:151], v[188:191], v[48:51]
	v_mfma_f32_16x16x32_bf16 v[40:43], v[156:159], v[188:191], v[40:43]
	v_mfma_f32_16x16x32_bf16 v[32:35], v[148:151], v[196:199], v[32:35]
	v_mfma_f32_16x16x32_bf16 v[24:27], v[156:159], v[196:199], v[24:27]
	v_mfma_f32_16x16x32_bf16 v[16:19], v[148:151], v[208:211], v[16:19]
	v_mfma_f32_16x16x32_bf16 v[8:11], v[156:159], v[208:211], v[8:11]
	v_mfma_f32_16x16x32_bf16 v[60:63], v[152:155], v[184:187], v[60:63]
	v_mfma_f32_16x16x32_bf16 v[56:59], v[160:163], v[184:187], v[56:59]
	v_mfma_f32_16x16x32_bf16 v[48:51], v[152:155], v[192:195], v[48:51]
	v_mfma_f32_16x16x32_bf16 v[40:43], v[160:163], v[192:195], v[40:43]
	v_mfma_f32_16x16x32_bf16 v[32:35], v[152:155], v[200:203], v[32:35]
	v_mfma_f32_16x16x32_bf16 v[24:27], v[160:163], v[200:203], v[24:27]
	v_mfma_f32_16x16x32_bf16 v[16:19], v[152:155], v[212:215], v[16:19]
	v_mfma_f32_16x16x32_bf16 v[8:11], v[160:163], v[212:215], v[8:11]
	v_mfma_f32_16x16x32_bf16 v[52:55], v[164:167], v[180:183], v[52:55]
	v_mfma_f32_16x16x32_bf16 v[44:47], v[172:175], v[180:183], v[44:47]
	v_mfma_f32_16x16x32_bf16 v[36:39], v[164:167], v[188:191], v[36:39]
	v_mfma_f32_16x16x32_bf16 v[28:31], v[172:175], v[188:191], v[28:31]
	v_mfma_f32_16x16x32_bf16 v[20:23], v[164:167], v[196:199], v[20:23]
	v_mfma_f32_16x16x32_bf16 v[12:15], v[172:175], v[196:199], v[12:15]
	v_mfma_f32_16x16x32_bf16 v[4:7], v[164:167], v[208:211], v[4:7]
	v_mfma_f32_16x16x32_bf16 v[0:3], v[172:175], v[208:211], v[0:3]
	v_mfma_f32_16x16x32_bf16 v[52:55], v[168:171], v[184:187], v[52:55]
	v_mfma_f32_16x16x32_bf16 v[44:47], v[176:179], v[184:187], v[44:47]
	v_mfma_f32_16x16x32_bf16 v[36:39], v[168:171], v[192:195], v[36:39]
	v_mfma_f32_16x16x32_bf16 v[28:31], v[176:179], v[192:195], v[28:31]
	v_mfma_f32_16x16x32_bf16 v[20:23], v[168:171], v[200:203], v[20:23]
	v_mfma_f32_16x16x32_bf16 v[12:15], v[176:179], v[200:203], v[12:15]
	v_mfma_f32_16x16x32_bf16 v[4:7], v[168:171], v[212:215], v[4:7]
	v_mfma_f32_16x16x32_bf16 v[0:3], v[176:179], v[212:215], v[0:3]
	s_setprio 0
	s_barrier
	s_add_i32 s77, s77, 2
	s_add_u32 s38, s38, 0x100
	s_addc_u32 s39, s39, 0
	s_add_u32 s75, s75, 0x100
	s_addc_u32 s76, s76, 0
	s_cmp_gt_u32 s77, 13
	s_cbranch_scc0 .LBB0_1349

;     __device__ __forceinline__ bool next(int i, Unit& u) const { if (i != 0) return false; const int c0 = (G >= 8) ? G - 5 : G - 2; int k = -1; if (c == c0) k = 0; else if (c == G - 1) k = 1; if (k < 0 || k >= n) return false; u.pm = k; u.pn = 0; return true; }
; #define PG8_STAGE(bufoff, gbase, voff) do { _Pragma("unroll") for (int _i = 0; _i < 2; ++_i) \
;         __builtin_amdgcn_global_load_lds((const unsigned*)((const char*)(gbase) + (voff)[_i]), (PG8_LAS unsigned*)(lds + (bufoff) + ldsw + _i * 8192), 16, 0, 0); } while (0)
; #define PG8_LDA(dst, b, h) do { _Pragma("unroll") for (int m = 0; m < 4; ++m) _Pragma("unroll") for (int k = 0; k < 2; ++k) dst[m][k] = *(const PG8_LAS bf16x8*)(lds + PG8_SA(b, h) + aoff + m * 2048 + k * 1024); } while (0)
; #define PG8_LDB(dst, b, h) do { _Pragma("unroll") for (int n = 0; n < 2; ++n) _Pragma("unroll") for (int k = 0; k < 2; ++k) dst[n][k] = *(const PG8_LAS bf16x8*)(lds + PG8_SB(b, h) + boff + n * 2048 + k * 1024); } while (0)
; template <class Epi, class Sched, bool ALIGN_EPI = false, bool SP2 = false>
; __device__ __forceinline__ void gemm_phase(PG8_LAS unsigned char* lds, const Gemm g, const Sched& S, const Epi& E) {
;     ...
;         const bool has_next = S.next(ui + 1, nxt);
;         const char* nA = has_next ? (const char*)g.A + (size_t)nxt.pm * tstep : cA; const char* nB = has_next ? (const char*)g.Bt + (size_t)nxt.pn * tstep : cB;
;         for (int t = 0; t < nt; t += 2) {
;             const bool last = (t == nt - 2);
;             const char* a1 = cA + (size_t)(t + 1) * kstep;
;             const char* a2 = last ? nA : cA + (size_t)(t + 2) * kstep; const char* b2 = last ? nB : cB + (size_t)(t + 2) * kstep;
;             const char* a3 = a2 + kstep; const char* b3 = b2 + kstep;
;             if (last && has_next) S.a_ready(nxt);
;             if constexpr (SP2) {
;             PG8_LDB(B0, 0, 0); PG8_LDB(B1, 0, 1); PG8_SCHED; PG8_LDA(At, 0, 0); PG8_STAGE(PG8_SA(1, 1), a1 + hstep, voffA);
;             PG8_WAIT_V(8); PG8_WAIT_L(0); PG8_BAR; PG8_MMA(0, 0, At, B0); PG8_MMA(0, 1, At, B1); PG8_BAR; PG8_SCHED;
;             PG8_LDA(At, 0, 1); PG8_STAGE(PG8_SB(0, 0), b2, voffB); PG8_STAGE(PG8_SB(0, 1), b2 + hstep, voffB); PG8_STAGE(PG8_SA(0, 0), a2, voffA);
;             PG8_WAIT_V(8); PG8_WAIT_L(0); PG8_BAR; PG8_MMA(1, 0, At, B0); PG8_MMA(1, 1, At, B1); PG8_BAR; PG8_SCHED;
.LBB0_1471:
	s_ashr_i32 s41, s40, 31
	s_lshl_b64 s[46:47], s[40:41], 19
	s_add_u32 s46, s97, s46
	s_addc_u32 s47, s3, s47
	s_and_b64 s[56:57], s[42:43], exec
	s_cselect_b32 s5, s47, s9
	s_cselect_b32 s7, s46, s8
	s_ashr_i32 s39, s38, 31
	s_lshl_b64 s[56:57], s[38:39], 19
	s_add_u32 s56, s64, s56
	s_addc_u32 s57, s65, s57
	s_and_b64 s[60:61], s[42:43], exec
	s_cselect_b32 s39, s57, s59
	s_cselect_b32 s41, s56, s58
	s_add_u32 s8, s8, 0x40080
	s_addc_u32 s9, s9, 0
	s_add_u32 s81, s58, 0x100
	v_mov_b32_e32 v0, 0
	s_addc_u32 s82, s59, 0
	s_mov_b32 s83, -2
	ds_read_b128 v[108:111], v210
	ds_read_b128 v[112:115], v210 offset:1024
	ds_read_b128 v[116:119], v210 offset:2048
	ds_read_b128 v[124:127], v210 offset:3072
	ds_read_b128 v[128:131], v211
	ds_read_b128 v[136:139], v211 offset:1024
	ds_read_b128 v[152:155], v211 offset:2048
	ds_read_b128 v[156:159], v211 offset:3072
	s_add_u32 s58, s8, 0xfffc0080
	s_addc_u32 s59, s9, -1
	s_cmp_eq_u32 s83, 12
	s_cselect_b32 s61, s5, s59
	s_cselect_b32 s60, s7, s58
	s_cselect_b32 s59, s39, s82
	s_cselect_b32 s58, s41, s81
	v_lshl_add_u64 v[176:177], s[8:9], 0, v[186:187]
	s_add_i32 m0, s67, 0xc000
	ds_read_b128 v[160:163], v212
	ds_read_b128 v[164:167], v212 offset:1024
	ds_read_b128 v[168:171], v212 offset:2048
	ds_read_b128 v[172:175], v212 offset:3072
	ds_read_b128 v[192:195], v212 offset:4096
	ds_read_b128 v[196:199], v212 offset:5120
	ds_read_b128 v[200:203], v212 offset:6144
	ds_read_b128 v[214:217], v212 offset:7168
	global_load_lds_dwordx4 v[176:177], off
	v_lshl_add_u64 v[176:177], s[8:9], 0, v[188:189]
	s_add_i32 m0, s67, 0xe000
	s_nop 0
	global_load_lds_dwordx4 v[176:177], off
	s_waitcnt vmcnt(8)
	s_waitcnt lgkmcnt(0)
	s_barrier
	s_setprio 1
	s_waitcnt lgkmcnt(0)
	v_mfma_f32_16x16x32_bf16 v[148:151], v[108:111], v[160:163], 0
	v_mfma_f32_16x16x32_bf16 v[144:147], v[116:119], v[160:163], 0
	v_mfma_f32_16x16x32_bf16 v[140:143], v[108:111], v[168:171], 0
	v_mfma_f32_16x16x32_bf16 v[132:135], v[116:119], v[168:171], 0
	v_mfma_f32_16x16x32_bf16 v[120:123], v[108:111], v[192:195], 0
	v_mfma_f32_16x16x32_bf16 v[104:107], v[116:119], v[192:195], 0
	v_mfma_f32_16x16x32_bf16 v[100:103], v[108:111], v[200:203], 0
	v_mfma_f32_16x16x32_bf16 v[96:99], v[116:119], v[200:203], 0
	v_mfma_f32_16x16x32_bf16 v[148:151], v[112:115], v[164:167], v[148:151]
	v_mfma_f32_16x16x32_bf16 v[144:147], v[124:127], v[164:167], v[144:147]
	v_mfma_f32_16x16x32_bf16 v[140:143], v[112:115], v[172:175], v[140:143]
	v_mfma_f32_16x16x32_bf16 v[132:135], v[124:127], v[172:175], v[132:135]
	v_mfma_f32_16x16x32_bf16 v[120:123], v[112:115], v[196:199], v[120:123]
	v_mfma_f32_16x16x32_bf16 v[104:107], v[124:127], v[196:199], v[104:107]
	v_mfma_f32_16x16x32_bf16 v[100:103], v[112:115], v[214:217], v[100:103]
	v_mfma_f32_16x16x32_bf16 v[96:99], v[124:127], v[214:217], v[96:99]
	v_mfma_f32_16x16x32_bf16 v[60:63], v[128:131], v[160:163], 0
	v_mfma_f32_16x16x32_bf16 v[56:59], v[152:155], v[160:163], 0
	v_mfma_f32_16x16x32_bf16 v[52:55], v[128:131], v[168:171], 0
	v_mfma_f32_16x16x32_bf16 v[48:51], v[152:155], v[168:171], 0
	v_mfma_f32_16x16x32_bf16 v[44:47], v[128:131], v[192:195], 0
	v_mfma_f32_16x16x32_bf16 v[40:43], v[152:155], v[192:195], 0
	v_mfma_f32_16x16x32_bf16 v[36:39], v[128:131], v[200:203], 0
	v_mfma_f32_16x16x32_bf16 v[32:35], v[152:155], v[200:203], 0
	v_mfma_f32_16x16x32_bf16 v[60:63], v[136:139], v[164:167], v[60:63]
	v_mfma_f32_16x16x32_bf16 v[56:59], v[156:159], v[164:167], v[56:59]
	v_mfma_f32_16x16x32_bf16 v[52:55], v[136:139], v[172:175], v[52:55]
	v_mfma_f32_16x16x32_bf16 v[48:51], v[156:159], v[172:175], v[48:51]
	v_mfma_f32_16x16x32_bf16 v[44:47], v[136:139], v[196:199], v[44:47]
	v_mfma_f32_16x16x32_bf16 v[40:43], v[156:159], v[196:199], v[40:43]
	v_mfma_f32_16x16x32_bf16 v[36:39], v[136:139], v[214:217], v[36:39]
	v_mfma_f32_16x16x32_bf16 v[32:35], v[156:159], v[214:217], v[32:35]
	s_setprio 0
	s_barrier
	s_add_i32 s88, s78, s66
	v_lshl_add_u64 v[176:177], s[58:59], 0, v[180:181]
	s_mov_b32 m0, s88
	ds_read_b128 v[160:163], v212 offset:16384
	ds_read_b128 v[164:167], v212 offset:17408
	ds_read_b128 v[168:171], v212 offset:18432
	ds_read_b128 v[172:175], v212 offset:19456
	ds_read_b128 v[192:195], v212 offset:20480
	ds_read_b128 v[196:199], v212 offset:21504
	ds_read_b128 v[200:203], v212 offset:22528
	ds_read_b128 v[214:217], v212 offset:23552
	global_load_lds_dwordx4 v[176:177], off
	s_add_i32 m0, s88, 0x2000
	s_add_u32 s88, s58, 0x40000
	v_lshl_add_u64 v[204:205], s[58:59], 0, v[184:185]
	s_addc_u32 s89, s59, 0
	s_add_i32 s90, s79, s66
	global_load_lds_dwordx4 v[204:205], off
	v_lshl_add_u64 v[218:219], s[88:89], 0, v[180:181]
	s_mov_b32 m0, s90
	v_lshl_add_u64 v[220:221], s[60:61], 0, v[182:183]
	global_load_lds_dwordx4 v[218:219], off
	v_lshl_add_u64 v[218:219], s[88:89], 0, v[184:185]
	s_add_i32 m0, s90, 0x2000
	s_nop 0
	global_load_lds_dwordx4 v[218:219], off
	v_lshl_add_u64 v[218:219], s[60:61], 0, v[178:179]
	s_mov_b32 m0, s67
	s_nop 0
	global_load_lds_dwordx4 v[218:219], off
	s_mov_b32 m0, s68
	s_nop 0
	global_load_lds_dwordx4 v[220:221], off
	s_waitcnt vmcnt(8)
	s_waitcnt lgkmcnt(0)
	s_barrier
; #define PG8_STAGE(bufoff, gbase, voff) do { _Pragma("unroll") for (int _i = 0; _i < 2; ++_i) \
;         __builtin_amdgcn_global_load_lds((const unsigned*)((const char*)(gbase) + (voff)[_i]), (PG8_LAS unsigned*)(lds + (bufoff) + ldsw + _i * 8192), 16, 0, 0); } while (0)
; #define PG8_LDA(dst, b, h) do { _Pragma("unroll") for (int m = 0; m < 4; ++m) _Pragma("unroll") for (int k = 0; k < 2; ++k) dst[m][k] = *(const PG8_LAS bf16x8*)(lds + PG8_SA(b, h) + aoff + m * 2048 + k * 1024); } while (0)
; #define PG8_LDB(dst, b, h) do { _Pragma("unroll") for (int n = 0; n < 2; ++n) _Pragma("unroll") for (int k = 0; k < 2; ++k) dst[n][k] = *(const PG8_LAS bf16x8*)(lds + PG8_SB(b, h) + boff + n * 2048 + k * 1024); } while (0)
; #define PG8_MMA(ai, bj, At, Bt) do { __builtin_amdgcn_s_setprio(1); _Pragma("unroll") for (int m = 0; m < 4; ++m) _Pragma("unroll") for (int n = 0; n < 2; ++n) _Pragma("unroll") for (int k = 0; k < 2; ++k) \
;         acc[ai][bj][m][n] = __builtin_amdgcn_mfma_f32_16x16x32_bf16(Bt[n][k], At[m][k], acc[ai][bj][m][n], 0, 0, 0); __builtin_amdgcn_s_setprio(0); } while (0)
; #define PG8_WAIT_V(n) asm volatile("s_waitcnt vmcnt(" #n ")" ::: "memory")
; #define PG8_WAIT_L(n) asm volatile("s_waitcnt lgkmcnt(" #n ")" ::: "memory")
; #define PG8_BAR __builtin_amdgcn_s_barrier()
; #define PG8_SCHED __builtin_amdgcn_sched_barrier(0)
; template <class Epi, class Sched, bool ALIGN_EPI = false, bool SP2 = false>
; __device__ __forceinline__ void gemm_phase(PG8_LAS unsigned char* lds, const Gemm g, const Sched& S, const Epi& E) {
;     ...
;             PG8_WAIT_V(8); PG8_WAIT_L(0); PG8_BAR; PG8_MMA(1, 0, At, B0); PG8_MMA(1, 1, At, B1); PG8_BAR; PG8_SCHED;
;             PG8_LDB(B0, 1, 0); PG8_LDB(B1, 1, 1); PG8_SCHED; PG8_LDA(At, 1, 0); PG8_STAGE(PG8_SA(0, 1), a2 + hstep, voffA);
;             PG8_WAIT_V(8); PG8_WAIT_L(0); PG8_BAR; PG8_MMA(0, 0, At, B0); PG8_MMA(0, 1, At, B1); PG8_BAR; PG8_SCHED;
	s_setprio 1
	s_waitcnt lgkmcnt(0)
	v_mfma_f32_16x16x32_bf16 v[92:95], v[108:111], v[160:163], 0
	v_mfma_f32_16x16x32_bf16 v[88:91], v[116:119], v[160:163], 0
	v_mfma_f32_16x16x32_bf16 v[84:87], v[108:111], v[168:171], 0
	v_mfma_f32_16x16x32_bf16 v[80:83], v[116:119], v[168:171], 0
	v_mfma_f32_16x16x32_bf16 v[76:79], v[108:111], v[192:195], 0
	v_mfma_f32_16x16x32_bf16 v[72:75], v[116:119], v[192:195], 0
	v_mfma_f32_16x16x32_bf16 v[68:71], v[108:111], v[200:203], 0
	v_mfma_f32_16x16x32_bf16 v[64:67], v[116:119], v[200:203], 0
	v_mfma_f32_16x16x32_bf16 v[92:95], v[112:115], v[164:167], v[92:95]
	v_mfma_f32_16x16x32_bf16 v[88:91], v[124:127], v[164:167], v[88:91]
	v_mfma_f32_16x16x32_bf16 v[84:87], v[112:115], v[172:175], v[84:87]
	v_mfma_f32_16x16x32_bf16 v[80:83], v[124:127], v[172:175], v[80:83]
	v_mfma_f32_16x16x32_bf16 v[76:79], v[112:115], v[196:199], v[76:79]
	v_mfma_f32_16x16x32_bf16 v[72:75], v[124:127], v[196:199], v[72:75]
	v_mfma_f32_16x16x32_bf16 v[68:71], v[112:115], v[214:217], v[68:71]
	v_mfma_f32_16x16x32_bf16 v[64:67], v[124:127], v[214:217], v[64:67]
	v_mfma_f32_16x16x32_bf16 v[28:31], v[128:131], v[160:163], 0
	v_mfma_f32_16x16x32_bf16 v[24:27], v[152:155], v[160:163], 0
	v_mfma_f32_16x16x32_bf16 v[20:23], v[128:131], v[168:171], 0
	v_mfma_f32_16x16x32_bf16 v[16:19], v[152:155], v[168:171], 0
	v_mfma_f32_16x16x32_bf16 v[12:15], v[128:131], v[192:195], 0
	v_mfma_f32_16x16x32_bf16 v[8:11], v[152:155], v[192:195], 0
	v_mfma_f32_16x16x32_bf16 v[4:7], v[128:131], v[200:203], 0
	v_mfma_f32_16x16x32_bf16 v[0:3], v[152:155], v[200:203], 0
	v_mfma_f32_16x16x32_bf16 v[28:31], v[136:139], v[164:167], v[28:31]
	v_mfma_f32_16x16x32_bf16 v[24:27], v[156:159], v[164:167], v[24:27]
	v_mfma_f32_16x16x32_bf16 v[20:23], v[136:139], v[172:175], v[20:23]
	v_mfma_f32_16x16x32_bf16 v[16:19], v[156:159], v[172:175], v[16:19]
	v_mfma_f32_16x16x32_bf16 v[12:15], v[136:139], v[196:199], v[12:15]
	v_mfma_f32_16x16x32_bf16 v[8:11], v[156:159], v[196:199], v[8:11]
	v_mfma_f32_16x16x32_bf16 v[4:7], v[136:139], v[214:217], v[4:7]
	v_mfma_f32_16x16x32_bf16 v[0:3], v[156:159], v[214:217], v[0:3]
	s_setprio 0
	s_barrier
	s_add_i32 s88, 0, 0x18000
	s_add_i32 s89, 0, 0x1c000
	v_add_u32_e32 v124, s88, v208
	v_add_u32_e32 v156, s89, v208
	ds_read_b128 v[108:111], v124
	ds_read_b128 v[112:115], v124 offset:1024
	ds_read_b128 v[116:119], v124 offset:2048
	ds_read_b128 v[124:127], v124 offset:3072
	ds_read_b128 v[128:131], v156
	ds_read_b128 v[136:139], v156 offset:1024
	ds_read_b128 v[152:155], v156 offset:2048
	ds_read_b128 v[156:159], v156 offset:3072
	s_add_u32 s60, s60, 0x40000
	s_addc_u32 s61, s61, 0
	s_mov_b32 m0, s69
	v_lshl_add_u64 v[222:223], s[60:61], 0, v[178:179]
	ds_read_b128 v[160:163], v212 offset:32768
	ds_read_b128 v[164:167], v212 offset:33792
	ds_read_b128 v[168:171], v212 offset:34816
	ds_read_b128 v[172:175], v212 offset:35840
	ds_read_b128 v[192:195], v212 offset:36864
	ds_read_b128 v[196:199], v212 offset:37888
	ds_read_b128 v[200:203], v212 offset:38912
	ds_read_b128 v[214:217], v212 offset:39936
	global_load_lds_dwordx4 v[222:223], off
	v_lshl_add_u64 v[222:223], s[60:61], 0, v[182:183]
	s_mov_b32 m0, s71
	s_nop 0
	global_load_lds_dwordx4 v[222:223], off
	s_waitcnt vmcnt(8)
	s_waitcnt lgkmcnt(0)
	s_barrier
	s_setprio 1
	s_waitcnt lgkmcnt(0)
	v_mfma_f32_16x16x32_bf16 v[148:151], v[108:111], v[160:163], v[148:151]
	v_mfma_f32_16x16x32_bf16 v[144:147], v[116:119], v[160:163], v[144:147]
	v_mfma_f32_16x16x32_bf16 v[140:143], v[108:111], v[168:171], v[140:143]
	v_mfma_f32_16x16x32_bf16 v[132:135], v[116:119], v[168:171], v[132:135]
	v_mfma_f32_16x16x32_bf16 v[120:123], v[108:111], v[192:195], v[120:123]
	v_mfma_f32_16x16x32_bf16 v[104:107], v[116:119], v[192:195], v[104:107]
	v_mfma_f32_16x16x32_bf16 v[100:103], v[108:111], v[200:203], v[100:103]
	v_mfma_f32_16x16x32_bf16 v[96:99], v[116:119], v[200:203], v[96:99]
	v_mfma_f32_16x16x32_bf16 v[148:151], v[112:115], v[164:167], v[148:151]
	v_mfma_f32_16x16x32_bf16 v[144:147], v[124:127], v[164:167], v[144:147]
	v_mfma_f32_16x16x32_bf16 v[140:143], v[112:115], v[172:175], v[140:143]
	v_mfma_f32_16x16x32_bf16 v[132:135], v[124:127], v[172:175], v[132:135]
	v_mfma_f32_16x16x32_bf16 v[120:123], v[112:115], v[196:199], v[120:123]
	v_mfma_f32_16x16x32_bf16 v[104:107], v[124:127], v[196:199], v[104:107]
	v_mfma_f32_16x16x32_bf16 v[100:103], v[112:115], v[214:217], v[100:103]
	v_mfma_f32_16x16x32_bf16 v[96:99], v[124:127], v[214:217], v[96:99]
	v_mfma_f32_16x16x32_bf16 v[60:63], v[128:131], v[160:163], v[60:63]
	v_mfma_f32_16x16x32_bf16 v[56:59], v[152:155], v[160:163], v[56:59]
	v_mfma_f32_16x16x32_bf16 v[52:55], v[128:131], v[168:171], v[52:55]
	v_mfma_f32_16x16x32_bf16 v[48:51], v[152:155], v[168:171], v[48:51]
	v_mfma_f32_16x16x32_bf16 v[44:47], v[128:131], v[192:195], v[44:47]
	v_mfma_f32_16x16x32_bf16 v[40:43], v[152:155], v[192:195], v[40:43]
	v_mfma_f32_16x16x32_bf16 v[36:39], v[128:131], v[200:203], v[36:39]
	v_mfma_f32_16x16x32_bf16 v[32:35], v[152:155], v[200:203], v[32:35]
	v_mfma_f32_16x16x32_bf16 v[60:63], v[136:139], v[164:167], v[60:63]
	v_mfma_f32_16x16x32_bf16 v[56:59], v[156:159], v[164:167], v[56:59]
	v_mfma_f32_16x16x32_bf16 v[52:55], v[136:139], v[172:175], v[52:55]
	v_mfma_f32_16x16x32_bf16 v[48:51], v[156:159], v[172:175], v[48:51]
	v_mfma_f32_16x16x32_bf16 v[44:47], v[136:139], v[196:199], v[44:47]
	v_mfma_f32_16x16x32_bf16 v[40:43], v[156:159], v[196:199], v[40:43]
	v_mfma_f32_16x16x32_bf16 v[36:39], v[136:139], v[214:217], v[36:39]
	v_mfma_f32_16x16x32_bf16 v[32:35], v[156:159], v[214:217], v[32:35]
	s_setprio 0
	s_barrier
; #define PG8_STAGE(bufoff, gbase, voff) do { _Pragma("unroll") for (int _i = 0; _i < 2; ++_i) \
;         __builtin_amdgcn_global_load_lds((const unsigned*)((const char*)(gbase) + (voff)[_i]), (PG8_LAS unsigned*)(lds + (bufoff) + ldsw + _i * 8192), 16, 0, 0); } while (0)
; #define PG8_LDA(dst, b, h) do { _Pragma("unroll") for (int m = 0; m < 4; ++m) _Pragma("unroll") for (int k = 0; k < 2; ++k) dst[m][k] = *(const PG8_LAS bf16x8*)(lds + PG8_SA(b, h) + aoff + m * 2048 + k * 1024); } while (0)
; #define PG8_LDB(dst, b, h) do { _Pragma("unroll") for (int n = 0; n < 2; ++n) _Pragma("unroll") for (int k = 0; k < 2; ++k) dst[n][k] = *(const PG8_LAS bf16x8*)(lds + PG8_SB(b, h) + boff + n * 2048 + k * 1024); } while (0)
; #define PG8_MMA(ai, bj, At, Bt) do { __builtin_amdgcn_s_setprio(1); _Pragma("unroll") for (int m = 0; m < 4; ++m) _Pragma("unroll") for (int n = 0; n < 2; ++n) _Pragma("unroll") for (int k = 0; k < 2; ++k) \
;         acc[ai][bj][m][n] = __builtin_amdgcn_mfma_f32_16x16x32_bf16(Bt[n][k], At[m][k], acc[ai][bj][m][n], 0, 0, 0); __builtin_amdgcn_s_setprio(0); } while (0)
; #define PG8_WAIT_V(n) asm volatile("s_waitcnt vmcnt(" #n ")" ::: "memory")
; #define PG8_WAIT_L(n) asm volatile("s_waitcnt lgkmcnt(" #n ")" ::: "memory")
; #define PG8_BAR __builtin_amdgcn_s_barrier()
; #define PG8_SCHED __builtin_amdgcn_sched_barrier(0)
; template <class Epi, class Sched, bool ALIGN_EPI = false, bool SP2 = false>
; __device__ __forceinline__ void gemm_phase(PG8_LAS unsigned char* lds, const Gemm g, const Sched& S, const Epi& E) {
;     ...
;             PG8_LDB(B0, 0, 0); PG8_LDB(B1, 0, 1); PG8_SCHED; PG8_LDA(At, 0, 0); PG8_STAGE(PG8_SA(1, 1), a1 + hstep, voffA);
;     ...
;             PG8_LDA(At, 1, 1); PG8_STAGE(PG8_SB(1, 0), b3, voffB); PG8_STAGE(PG8_SB(1, 1), b3 + hstep, voffB); PG8_STAGE(PG8_SA(1, 0), a3, voffA);
;             PG8_WAIT_V(8); PG8_WAIT_L(0); PG8_BAR; PG8_MMA(1, 0, At, B0); PG8_MMA(1, 1, At, B1); PG8_BAR; PG8_SCHED;
	s_add_i32 s60, s88, s66
	v_lshl_add_u64 v[176:177], v[176:177], 0, s[22:23]
	s_mov_b32 m0, s60
	ds_read_b128 v[160:163], v212 offset:49152
	ds_read_b128 v[164:167], v212 offset:50176
	ds_read_b128 v[168:171], v212 offset:51200
	ds_read_b128 v[172:175], v212 offset:52224
	ds_read_b128 v[192:195], v212 offset:53248
	ds_read_b128 v[196:199], v212 offset:54272
	ds_read_b128 v[200:203], v212 offset:55296
	ds_read_b128 v[214:217], v212 offset:56320
	global_load_lds_dwordx4 v[176:177], off
	s_add_i32 m0, s60, 0x2000
	s_add_u32 s58, s58, 0x40080
	v_lshl_add_u64 v[176:177], v[204:205], 0, s[22:23]
	s_addc_u32 s59, s59, 0
	s_add_i32 s60, s89, s66
	global_load_lds_dwordx4 v[176:177], off
	v_lshl_add_u64 v[176:177], s[58:59], 0, v[180:181]
	s_mov_b32 m0, s60
	s_nop 0
	global_load_lds_dwordx4 v[176:177], off
	v_lshl_add_u64 v[176:177], s[58:59], 0, v[184:185]
	s_add_i32 m0, s60, 0x2000
	s_nop 0
	global_load_lds_dwordx4 v[176:177], off
	v_lshl_add_u64 v[176:177], v[218:219], 0, s[22:23]
	s_mov_b32 m0, s73
	s_nop 0
	global_load_lds_dwordx4 v[176:177], off
	v_lshl_add_u64 v[176:177], v[220:221], 0, s[22:23]
	s_mov_b32 m0, s74
	s_nop 0
	global_load_lds_dwordx4 v[176:177], off
	s_waitcnt vmcnt(8)
	s_waitcnt lgkmcnt(0)
	s_barrier
	s_setprio 1
	s_waitcnt lgkmcnt(0)
	v_mfma_f32_16x16x32_bf16 v[92:95], v[108:111], v[160:163], v[92:95]
	v_mfma_f32_16x16x32_bf16 v[88:91], v[116:119], v[160:163], v[88:91]
	v_mfma_f32_16x16x32_bf16 v[84:87], v[108:111], v[168:171], v[84:87]
	v_mfma_f32_16x16x32_bf16 v[80:83], v[116:119], v[168:171], v[80:83]
	v_mfma_f32_16x16x32_bf16 v[76:79], v[108:111], v[192:195], v[76:79]
	v_mfma_f32_16x16x32_bf16 v[72:75], v[116:119], v[192:195], v[72:75]
	v_mfma_f32_16x16x32_bf16 v[68:71], v[108:111], v[200:203], v[68:71]
	v_mfma_f32_16x16x32_bf16 v[64:67], v[116:119], v[200:203], v[64:67]
	v_mfma_f32_16x16x32_bf16 v[92:95], v[112:115], v[164:167], v[92:95]
	v_mfma_f32_16x16x32_bf16 v[88:91], v[124:127], v[164:167], v[88:91]
	v_mfma_f32_16x16x32_bf16 v[84:87], v[112:115], v[172:175], v[84:87]
	v_mfma_f32_16x16x32_bf16 v[80:83], v[124:127], v[172:175], v[80:83]
	v_mfma_f32_16x16x32_bf16 v[76:79], v[112:115], v[196:199], v[76:79]
	v_mfma_f32_16x16x32_bf16 v[72:75], v[124:127], v[196:199], v[72:75]
	v_mfma_f32_16x16x32_bf16 v[68:71], v[112:115], v[214:217], v[68:71]
	v_mfma_f32_16x16x32_bf16 v[64:67], v[124:127], v[214:217], v[64:67]
	v_mfma_f32_16x16x32_bf16 v[28:31], v[128:131], v[160:163], v[28:31]
	v_mfma_f32_16x16x32_bf16 v[24:27], v[152:155], v[160:163], v[24:27]
	v_mfma_f32_16x16x32_bf16 v[20:23], v[128:131], v[168:171], v[20:23]
	v_mfma_f32_16x16x32_bf16 v[16:19], v[152:155], v[168:171], v[16:19]
	v_mfma_f32_16x16x32_bf16 v[12:15], v[128:131], v[192:195], v[12:15]
	v_mfma_f32_16x16x32_bf16 v[8:11], v[152:155], v[192:195], v[8:11]
	v_mfma_f32_16x16x32_bf16 v[4:7], v[128:131], v[200:203], v[4:7]
	v_mfma_f32_16x16x32_bf16 v[0:3], v[152:155], v[200:203], v[0:3]
	v_mfma_f32_16x16x32_bf16 v[28:31], v[136:139], v[164:167], v[28:31]
	v_mfma_f32_16x16x32_bf16 v[24:27], v[156:159], v[164:167], v[24:27]
	v_mfma_f32_16x16x32_bf16 v[20:23], v[136:139], v[172:175], v[20:23]
	v_mfma_f32_16x16x32_bf16 v[16:19], v[156:159], v[172:175], v[16:19]
	v_mfma_f32_16x16x32_bf16 v[12:15], v[136:139], v[196:199], v[12:15]
	v_mfma_f32_16x16x32_bf16 v[8:11], v[156:159], v[196:199], v[8:11]
	v_mfma_f32_16x16x32_bf16 v[4:7], v[136:139], v[214:217], v[4:7]
	v_mfma_f32_16x16x32_bf16 v[0:3], v[156:159], v[214:217], v[0:3]
	s_setprio 0
	s_barrier
	s_add_i32 s83, s83, 2
	s_add_u32 s8, s8, 0x100
	s_addc_u32 s9, s9, 0
	s_add_u32 s81, s81, 0x100
	s_addc_u32 s82, s82, 0
	s_cmp_gt_u32 s83, 13
	s_cbranch_scc0 .LBB0_1472
	s_branch .Lpeel_exit_10
.LBB0_1472:
	ds_read_b128 v[108:111], v210
	ds_read_b128 v[112:115], v210 offset:1024
	ds_read_b128 v[116:119], v210 offset:2048
	ds_read_b128 v[124:127], v210 offset:3072
	ds_read_b128 v[128:131], v211
	ds_read_b128 v[136:139], v211 offset:1024
	ds_read_b128 v[152:155], v211 offset:2048
	ds_read_b128 v[156:159], v211 offset:3072
	s_add_u32 s58, s8, 0xfffc0080
	s_addc_u32 s59, s9, -1
	s_cmp_eq_u32 s83, 12
	s_cselect_b32 s61, s5, s59
	s_cselect_b32 s60, s7, s58
	s_cselect_b32 s59, s39, s82
	s_cselect_b32 s58, s41, s81
	v_lshl_add_u64 v[176:177], s[8:9], 0, v[186:187]
	s_add_i32 m0, s67, 0xc000
	ds_read_b128 v[160:163], v212
	ds_read_b128 v[164:167], v212 offset:1024
	ds_read_b128 v[168:171], v212 offset:2048
	ds_read_b128 v[172:175], v212 offset:3072
	ds_read_b128 v[192:195], v212 offset:4096
	ds_read_b128 v[196:199], v212 offset:5120
	ds_read_b128 v[200:203], v212 offset:6144
	ds_read_b128 v[214:217], v212 offset:7168
	global_load_lds_dwordx4 v[176:177], off
	v_lshl_add_u64 v[176:177], s[8:9], 0, v[188:189]
	s_add_i32 m0, s67, 0xe000
	s_nop 0
	global_load_lds_dwordx4 v[176:177], off
	s_waitcnt vmcnt(8)
	s_waitcnt lgkmcnt(0)
	s_barrier
; #define PG8_STAGE(bufoff, gbase, voff) do { _Pragma("unroll") for (int _i = 0; _i < 2; ++_i) \
;         __builtin_amdgcn_global_load_lds((const unsigned*)((const char*)(gbase) + (voff)[_i]), (PG8_LAS unsigned*)(lds + (bufoff) + ldsw + _i * 8192), 16, 0, 0); } while (0)
; #define PG8_LDA(dst, b, h) do { _Pragma("unroll") for (int m = 0; m < 4; ++m) _Pragma("unroll") for (int k = 0; k < 2; ++k) dst[m][k] = *(const PG8_LAS bf16x8*)(lds + PG8_SA(b, h) + aoff + m * 2048 + k * 1024); } while (0)
; #define PG8_MMA(ai, bj, At, Bt) do { __builtin_amdgcn_s_setprio(1); _Pragma("unroll") for (int m = 0; m < 4; ++m) _Pragma("unroll") for (int n = 0; n < 2; ++n) _Pragma("unroll") for (int k = 0; k < 2; ++k) \
;         acc[ai][bj][m][n] = __builtin_amdgcn_mfma_f32_16x16x32_bf16(Bt[n][k], At[m][k], acc[ai][bj][m][n], 0, 0, 0); __builtin_amdgcn_s_setprio(0); } while (0)
; #define PG8_WAIT_V(n) asm volatile("s_waitcnt vmcnt(" #n ")" ::: "memory")
; #define PG8_WAIT_L(n) asm volatile("s_waitcnt lgkmcnt(" #n ")" ::: "memory")
; #define PG8_BAR __builtin_amdgcn_s_barrier()
; #define PG8_SCHED __builtin_amdgcn_sched_barrier(0)
; template <class Epi, class Sched, bool ALIGN_EPI = false, bool SP2 = false>
; __device__ __forceinline__ void gemm_phase(PG8_LAS unsigned char* lds, const Gemm g, const Sched& S, const Epi& E) {
;     ...
;             PG8_WAIT_V(8); PG8_WAIT_L(0); PG8_BAR; PG8_MMA(0, 0, At, B0); PG8_MMA(0, 1, At, B1); PG8_BAR; PG8_SCHED;
;             PG8_LDA(At, 0, 1); PG8_STAGE(PG8_SB(0, 0), b2, voffB); PG8_STAGE(PG8_SB(0, 1), b2 + hstep, voffB); PG8_STAGE(PG8_SA(0, 0), a2, voffA);
;             PG8_WAIT_V(8); PG8_WAIT_L(0); PG8_BAR; PG8_MMA(1, 0, At, B0); PG8_MMA(1, 1, At, B1); PG8_BAR; PG8_SCHED;
	s_setprio 1
	s_waitcnt lgkmcnt(0)
	v_mfma_f32_16x16x32_bf16 v[148:151], v[108:111], v[160:163], v[148:151]
	v_mfma_f32_16x16x32_bf16 v[144:147], v[116:119], v[160:163], v[144:147]
	v_mfma_f32_16x16x32_bf16 v[140:143], v[108:111], v[168:171], v[140:143]
	v_mfma_f32_16x16x32_bf16 v[132:135], v[116:119], v[168:171], v[132:135]
	v_mfma_f32_16x16x32_bf16 v[120:123], v[108:111], v[192:195], v[120:123]
	v_mfma_f32_16x16x32_bf16 v[104:107], v[116:119], v[192:195], v[104:107]
	v_mfma_f32_16x16x32_bf16 v[100:103], v[108:111], v[200:203], v[100:103]
	v_mfma_f32_16x16x32_bf16 v[96:99], v[116:119], v[200:203], v[96:99]
	v_mfma_f32_16x16x32_bf16 v[148:151], v[112:115], v[164:167], v[148:151]
	v_mfma_f32_16x16x32_bf16 v[144:147], v[124:127], v[164:167], v[144:147]
	v_mfma_f32_16x16x32_bf16 v[140:143], v[112:115], v[172:175], v[140:143]
	v_mfma_f32_16x16x32_bf16 v[132:135], v[124:127], v[172:175], v[132:135]
	v_mfma_f32_16x16x32_bf16 v[120:123], v[112:115], v[196:199], v[120:123]
	v_mfma_f32_16x16x32_bf16 v[104:107], v[124:127], v[196:199], v[104:107]
	v_mfma_f32_16x16x32_bf16 v[100:103], v[112:115], v[214:217], v[100:103]
	v_mfma_f32_16x16x32_bf16 v[96:99], v[124:127], v[214:217], v[96:99]
	v_mfma_f32_16x16x32_bf16 v[60:63], v[128:131], v[160:163], v[60:63]
	v_mfma_f32_16x16x32_bf16 v[56:59], v[152:155], v[160:163], v[56:59]
	v_mfma_f32_16x16x32_bf16 v[52:55], v[128:131], v[168:171], v[52:55]
	v_mfma_f32_16x16x32_bf16 v[48:51], v[152:155], v[168:171], v[48:51]
	v_mfma_f32_16x16x32_bf16 v[44:47], v[128:131], v[192:195], v[44:47]
	v_mfma_f32_16x16x32_bf16 v[40:43], v[152:155], v[192:195], v[40:43]
	v_mfma_f32_16x16x32_bf16 v[36:39], v[128:131], v[200:203], v[36:39]
	v_mfma_f32_16x16x32_bf16 v[32:35], v[152:155], v[200:203], v[32:35]
	v_mfma_f32_16x16x32_bf16 v[60:63], v[136:139], v[164:167], v[60:63]
	v_mfma_f32_16x16x32_bf16 v[56:59], v[156:159], v[164:167], v[56:59]
	v_mfma_f32_16x16x32_bf16 v[52:55], v[136:139], v[172:175], v[52:55]
	v_mfma_f32_16x16x32_bf16 v[48:51], v[156:159], v[172:175], v[48:51]
	v_mfma_f32_16x16x32_bf16 v[44:47], v[136:139], v[196:199], v[44:47]
	v_mfma_f32_16x16x32_bf16 v[40:43], v[156:159], v[196:199], v[40:43]
	v_mfma_f32_16x16x32_bf16 v[36:39], v[136:139], v[214:217], v[36:39]
	v_mfma_f32_16x16x32_bf16 v[32:35], v[156:159], v[214:217], v[32:35]
	s_setprio 0
	s_barrier
	s_add_i32 s88, s78, s66
	v_lshl_add_u64 v[176:177], s[58:59], 0, v[180:181]
	s_mov_b32 m0, s88
	ds_read_b128 v[160:163], v212 offset:16384
	ds_read_b128 v[164:167], v212 offset:17408
	ds_read_b128 v[168:171], v212 offset:18432
	ds_read_b128 v[172:175], v212 offset:19456
	ds_read_b128 v[192:195], v212 offset:20480
	ds_read_b128 v[196:199], v212 offset:21504
	ds_read_b128 v[200:203], v212 offset:22528
	ds_read_b128 v[214:217], v212 offset:23552
	global_load_lds_dwordx4 v[176:177], off
	s_add_i32 m0, s88, 0x2000
	s_add_u32 s88, s58, 0x40000
	v_lshl_add_u64 v[204:205], s[58:59], 0, v[184:185]
	s_addc_u32 s89, s59, 0
	s_add_i32 s90, s79, s66
	global_load_lds_dwordx4 v[204:205], off
	v_lshl_add_u64 v[218:219], s[88:89], 0, v[180:181]
	s_mov_b32 m0, s90
	v_lshl_add_u64 v[220:221], s[60:61], 0, v[182:183]
	global_load_lds_dwordx4 v[218:219], off
	v_lshl_add_u64 v[218:219], s[88:89], 0, v[184:185]
	s_add_i32 m0, s90, 0x2000
	s_nop 0
	global_load_lds_dwordx4 v[218:219], off
	v_lshl_add_u64 v[218:219], s[60:61], 0, v[178:179]
	s_mov_b32 m0, s67
	s_nop 0
	global_load_lds_dwordx4 v[218:219], off
	s_mov_b32 m0, s68
	s_nop 0
	global_load_lds_dwordx4 v[220:221], off
	s_waitcnt vmcnt(8)
	s_waitcnt lgkmcnt(0)
	s_barrier
	s_setprio 1
	s_waitcnt lgkmcnt(0)
	v_mfma_f32_16x16x32_bf16 v[92:95], v[108:111], v[160:163], v[92:95]
	v_mfma_f32_16x16x32_bf16 v[88:91], v[116:119], v[160:163], v[88:91]
	v_mfma_f32_16x16x32_bf16 v[84:87], v[108:111], v[168:171], v[84:87]
	v_mfma_f32_16x16x32_bf16 v[80:83], v[116:119], v[168:171], v[80:83]
	v_mfma_f32_16x16x32_bf16 v[76:79], v[108:111], v[192:195], v[76:79]
	v_mfma_f32_16x16x32_bf16 v[72:75], v[116:119], v[192:195], v[72:75]
	v_mfma_f32_16x16x32_bf16 v[68:71], v[108:111], v[200:203], v[68:71]
	v_mfma_f32_16x16x32_bf16 v[64:67], v[116:119], v[200:203], v[64:67]
	v_mfma_f32_16x16x32_bf16 v[92:95], v[112:115], v[164:167], v[92:95]
	v_mfma_f32_16x16x32_bf16 v[88:91], v[124:127], v[164:167], v[88:91]
	v_mfma_f32_16x16x32_bf16 v[84:87], v[112:115], v[172:175], v[84:87]
	v_mfma_f32_16x16x32_bf16 v[80:83], v[124:127], v[172:175], v[80:83]
	v_mfma_f32_16x16x32_bf16 v[76:79], v[112:115], v[196:199], v[76:79]
	v_mfma_f32_16x16x32_bf16 v[72:75], v[124:127], v[196:199], v[72:75]
	v_mfma_f32_16x16x32_bf16 v[68:71], v[112:115], v[214:217], v[68:71]
	v_mfma_f32_16x16x32_bf16 v[64:67], v[124:127], v[214:217], v[64:67]
	v_mfma_f32_16x16x32_bf16 v[28:31], v[128:131], v[160:163], v[28:31]
	v_mfma_f32_16x16x32_bf16 v[24:27], v[152:155], v[160:163], v[24:27]
	v_mfma_f32_16x16x32_bf16 v[20:23], v[128:131], v[168:171], v[20:23]
	v_mfma_f32_16x16x32_bf16 v[16:19], v[152:155], v[168:171], v[16:19]
	v_mfma_f32_16x16x32_bf16 v[12:15], v[128:131], v[192:195], v[12:15]
	v_mfma_f32_16x16x32_bf16 v[8:11], v[152:155], v[192:195], v[8:11]
	v_mfma_f32_16x16x32_bf16 v[4:7], v[128:131], v[200:203], v[4:7]
	v_mfma_f32_16x16x32_bf16 v[0:3], v[152:155], v[200:203], v[0:3]
	v_mfma_f32_16x16x32_bf16 v[28:31], v[136:139], v[164:167], v[28:31]
	v_mfma_f32_16x16x32_bf16 v[24:27], v[156:159], v[164:167], v[24:27]
	v_mfma_f32_16x16x32_bf16 v[20:23], v[136:139], v[172:175], v[20:23]
	v_mfma_f32_16x16x32_bf16 v[16:19], v[156:159], v[172:175], v[16:19]
	v_mfma_f32_16x16x32_bf16 v[12:15], v[136:139], v[196:199], v[12:15]
	v_mfma_f32_16x16x32_bf16 v[8:11], v[156:159], v[196:199], v[8:11]
	v_mfma_f32_16x16x32_bf16 v[4:7], v[136:139], v[214:217], v[4:7]
	v_mfma_f32_16x16x32_bf16 v[0:3], v[156:159], v[214:217], v[0:3]
	s_setprio 0
	s_barrier
; #define PG8_STAGE(bufoff, gbase, voff) do { _Pragma("unroll") for (int _i = 0; _i < 2; ++_i) \
;         __builtin_amdgcn_global_load_lds((const unsigned*)((const char*)(gbase) + (voff)[_i]), (PG8_LAS unsigned*)(lds + (bufoff) + ldsw + _i * 8192), 16, 0, 0); } while (0)
; #define PG8_LDA(dst, b, h) do { _Pragma("unroll") for (int m = 0; m < 4; ++m) _Pragma("unroll") for (int k = 0; k < 2; ++k) dst[m][k] = *(const PG8_LAS bf16x8*)(lds + PG8_SA(b, h) + aoff + m * 2048 + k * 1024); } while (0)
; #define PG8_LDB(dst, b, h) do { _Pragma("unroll") for (int n = 0; n < 2; ++n) _Pragma("unroll") for (int k = 0; k < 2; ++k) dst[n][k] = *(const PG8_LAS bf16x8*)(lds + PG8_SB(b, h) + boff + n * 2048 + k * 1024); } while (0)
; #define PG8_MMA(ai, bj, At, Bt) do { __builtin_amdgcn_s_setprio(1); _Pragma("unroll") for (int m = 0; m < 4; ++m) _Pragma("unroll") for (int n = 0; n < 2; ++n) _Pragma("unroll") for (int k = 0; k < 2; ++k) \
;         acc[ai][bj][m][n] = __builtin_amdgcn_mfma_f32_16x16x32_bf16(Bt[n][k], At[m][k], acc[ai][bj][m][n], 0, 0, 0); __builtin_amdgcn_s_setprio(0); } while (0)
; #define PG8_WAIT_V(n) asm volatile("s_waitcnt vmcnt(" #n ")" ::: "memory")
; #define PG8_WAIT_L(n) asm volatile("s_waitcnt lgkmcnt(" #n ")" ::: "memory")
; #define PG8_BAR __builtin_amdgcn_s_barrier()
; #define PG8_SCHED __builtin_amdgcn_sched_barrier(0)
; template <class Epi, class Sched, bool ALIGN_EPI = false, bool SP2 = false>
; __device__ __forceinline__ void gemm_phase(PG8_LAS unsigned char* lds, const Gemm g, const Sched& S, const Epi& E) {
;     ...
;             PG8_LDB(B0, 1, 0); PG8_LDB(B1, 1, 1); PG8_SCHED; PG8_LDA(At, 1, 0); PG8_STAGE(PG8_SA(0, 1), a2 + hstep, voffA);
;             PG8_WAIT_V(8); PG8_WAIT_L(0); PG8_BAR; PG8_MMA(0, 0, At, B0); PG8_MMA(0, 1, At, B1); PG8_BAR; PG8_SCHED;
	s_add_i32 s88, 0, 0x18000
	s_add_i32 s89, 0, 0x1c000
	v_add_u32_e32 v124, s88, v208
	v_add_u32_e32 v156, s89, v208
	ds_read_b128 v[108:111], v124
	ds_read_b128 v[112:115], v124 offset:1024
	ds_read_b128 v[116:119], v124 offset:2048
	ds_read_b128 v[124:127], v124 offset:3072
	ds_read_b128 v[128:131], v156
	ds_read_b128 v[136:139], v156 offset:1024
	ds_read_b128 v[152:155], v156 offset:2048
	ds_read_b128 v[156:159], v156 offset:3072
	s_add_u32 s60, s60, 0x40000
	s_addc_u32 s61, s61, 0
	s_mov_b32 m0, s69
	v_lshl_add_u64 v[222:223], s[60:61], 0, v[178:179]
	ds_read_b128 v[160:163], v212 offset:32768
	ds_read_b128 v[164:167], v212 offset:33792
	ds_read_b128 v[168:171], v212 offset:34816
	ds_read_b128 v[172:175], v212 offset:35840
	ds_read_b128 v[192:195], v212 offset:36864
	ds_read_b128 v[196:199], v212 offset:37888
	ds_read_b128 v[200:203], v212 offset:38912
	ds_read_b128 v[214:217], v212 offset:39936
	global_load_lds_dwordx4 v[222:223], off
	v_lshl_add_u64 v[222:223], s[60:61], 0, v[182:183]
	s_mov_b32 m0, s71
	s_nop 0
	global_load_lds_dwordx4 v[222:223], off
	s_waitcnt vmcnt(8)
	s_waitcnt lgkmcnt(0)
	s_barrier
	s_setprio 1
	s_waitcnt lgkmcnt(0)
	v_mfma_f32_16x16x32_bf16 v[148:151], v[108:111], v[160:163], v[148:151]
	v_mfma_f32_16x16x32_bf16 v[144:147], v[116:119], v[160:163], v[144:147]
	v_mfma_f32_16x16x32_bf16 v[140:143], v[108:111], v[168:171], v[140:143]
	v_mfma_f32_16x16x32_bf16 v[132:135], v[116:119], v[168:171], v[132:135]
	v_mfma_f32_16x16x32_bf16 v[120:123], v[108:111], v[192:195], v[120:123]
	v_mfma_f32_16x16x32_bf16 v[104:107], v[116:119], v[192:195], v[104:107]
	v_mfma_f32_16x16x32_bf16 v[100:103], v[108:111], v[200:203], v[100:103]
	v_mfma_f32_16x16x32_bf16 v[96:99], v[116:119], v[200:203], v[96:99]
	v_mfma_f32_16x16x32_bf16 v[148:151], v[112:115], v[164:167], v[148:151]
	v_mfma_f32_16x16x32_bf16 v[144:147], v[124:127], v[164:167], v[144:147]
	v_mfma_f32_16x16x32_bf16 v[140:143], v[112:115], v[172:175], v[140:143]
	v_mfma_f32_16x16x32_bf16 v[132:135], v[124:127], v[172:175], v[132:135]
	v_mfma_f32_16x16x32_bf16 v[120:123], v[112:115], v[196:199], v[120:123]
	v_mfma_f32_16x16x32_bf16 v[104:107], v[124:127], v[196:199], v[104:107]
	v_mfma_f32_16x16x32_bf16 v[100:103], v[112:115], v[214:217], v[100:103]
	v_mfma_f32_16x16x32_bf16 v[96:99], v[124:127], v[214:217], v[96:99]
	v_mfma_f32_16x16x32_bf16 v[60:63], v[128:131], v[160:163], v[60:63]
	v_mfma_f32_16x16x32_bf16 v[56:59], v[152:155], v[160:163], v[56:59]
	v_mfma_f32_16x16x32_bf16 v[52:55], v[128:131], v[168:171], v[52:55]
	v_mfma_f32_16x16x32_bf16 v[48:51], v[152:155], v[168:171], v[48:51]
	v_mfma_f32_16x16x32_bf16 v[44:47], v[128:131], v[192:195], v[44:47]
	v_mfma_f32_16x16x32_bf16 v[40:43], v[152:155], v[192:195], v[40:43]
	v_mfma_f32_16x16x32_bf16 v[36:39], v[128:131], v[200:203], v[36:39]
	v_mfma_f32_16x16x32_bf16 v[32:35], v[152:155], v[200:203], v[32:35]
	v_mfma_f32_16x16x32_bf16 v[60:63], v[136:139], v[164:167], v[60:63]
	v_mfma_f32_16x16x32_bf16 v[56:59], v[156:159], v[164:167], v[56:59]
	v_mfma_f32_16x16x32_bf16 v[52:55], v[136:139], v[172:175], v[52:55]
	v_mfma_f32_16x16x32_bf16 v[48:51], v[156:159], v[172:175], v[48:51]
	v_mfma_f32_16x16x32_bf16 v[44:47], v[136:139], v[196:199], v[44:47]
	v_mfma_f32_16x16x32_bf16 v[40:43], v[156:159], v[196:199], v[40:43]
	v_mfma_f32_16x16x32_bf16 v[36:39], v[136:139], v[214:217], v[36:39]
	v_mfma_f32_16x16x32_bf16 v[32:35], v[156:159], v[214:217], v[32:35]
	s_setprio 0
	s_barrier
; #define PG8_STAGE(bufoff, gbase, voff) do { _Pragma("unroll") for (int _i = 0; _i < 2; ++_i) \
;         __builtin_amdgcn_global_load_lds((const unsigned*)((const char*)(gbase) + (voff)[_i]), (PG8_LAS unsigned*)(lds + (bufoff) + ldsw + _i * 8192), 16, 0, 0); } while (0)
; #define PG8_LDA(dst, b, h) do { _Pragma("unroll") for (int m = 0; m < 4; ++m) _Pragma("unroll") for (int k = 0; k < 2; ++k) dst[m][k] = *(const PG8_LAS bf16x8*)(lds + PG8_SA(b, h) + aoff + m * 2048 + k * 1024); } while (0)
; #define PG8_MMA(ai, bj, At, Bt) do { __builtin_amdgcn_s_setprio(1); _Pragma("unroll") for (int m = 0; m < 4; ++m) _Pragma("unroll") for (int n = 0; n < 2; ++n) _Pragma("unroll") for (int k = 0; k < 2; ++k) \
;         acc[ai][bj][m][n] = __builtin_amdgcn_mfma_f32_16x16x32_bf16(Bt[n][k], At[m][k], acc[ai][bj][m][n], 0, 0, 0); __builtin_amdgcn_s_setprio(0); } while (0)
; #define PG8_WAIT_V(n) asm volatile("s_waitcnt vmcnt(" #n ")" ::: "memory")
; #define PG8_WAIT_L(n) asm volatile("s_waitcnt lgkmcnt(" #n ")" ::: "memory")
; #define PG8_BAR __builtin_amdgcn_s_barrier()
; #define PG8_SCHED __builtin_amdgcn_sched_barrier(0)
; template <class Epi, class Sched, bool ALIGN_EPI = false, bool SP2 = false>
; __device__ __forceinline__ void gemm_phase(PG8_LAS unsigned char* lds, const Gemm g, const Sched& S, const Epi& E) {
;     ...
;         for (int t = 0; t < nt; t += 2) {
;     ...
;             PG8_LDA(At, 1, 1); PG8_STAGE(PG8_SB(1, 0), b3, voffB); PG8_STAGE(PG8_SB(1, 1), b3 + hstep, voffB); PG8_STAGE(PG8_SA(1, 0), a3, voffA);
;             PG8_WAIT_V(8); PG8_WAIT_L(0); PG8_BAR; PG8_MMA(1, 0, At, B0); PG8_MMA(1, 1, At, B1); PG8_BAR; PG8_SCHED;
	s_add_i32 s60, s88, s66
	v_lshl_add_u64 v[176:177], v[176:177], 0, s[22:23]
	s_mov_b32 m0, s60
	ds_read_b128 v[160:163], v212 offset:49152
	ds_read_b128 v[164:167], v212 offset:50176
	ds_read_b128 v[168:171], v212 offset:51200
	ds_read_b128 v[172:175], v212 offset:52224
	ds_read_b128 v[192:195], v212 offset:53248
	ds_read_b128 v[196:199], v212 offset:54272
	ds_read_b128 v[200:203], v212 offset:55296
	ds_read_b128 v[214:217], v212 offset:56320
	global_load_lds_dwordx4 v[176:177], off
	s_add_i32 m0, s60, 0x2000
	s_add_u32 s58, s58, 0x40080
	v_lshl_add_u64 v[176:177], v[204:205], 0, s[22:23]
	s_addc_u32 s59, s59, 0
	s_add_i32 s60, s89, s66
	global_load_lds_dwordx4 v[176:177], off
	v_lshl_add_u64 v[176:177], s[58:59], 0, v[180:181]
	s_mov_b32 m0, s60
	s_nop 0
	global_load_lds_dwordx4 v[176:177], off
	v_lshl_add_u64 v[176:177], s[58:59], 0, v[184:185]
	s_add_i32 m0, s60, 0x2000
	s_nop 0
	global_load_lds_dwordx4 v[176:177], off
	v_lshl_add_u64 v[176:177], v[218:219], 0, s[22:23]
	s_mov_b32 m0, s73
	s_nop 0
	global_load_lds_dwordx4 v[176:177], off
	v_lshl_add_u64 v[176:177], v[220:221], 0, s[22:23]
	s_mov_b32 m0, s74
	s_nop 0
	global_load_lds_dwordx4 v[176:177], off
	s_waitcnt vmcnt(8)
	s_waitcnt lgkmcnt(0)
	s_barrier
	s_setprio 1
	s_waitcnt lgkmcnt(0)
	v_mfma_f32_16x16x32_bf16 v[92:95], v[108:111], v[160:163], v[92:95]
	v_mfma_f32_16x16x32_bf16 v[88:91], v[116:119], v[160:163], v[88:91]
	v_mfma_f32_16x16x32_bf16 v[84:87], v[108:111], v[168:171], v[84:87]
	v_mfma_f32_16x16x32_bf16 v[80:83], v[116:119], v[168:171], v[80:83]
	v_mfma_f32_16x16x32_bf16 v[76:79], v[108:111], v[192:195], v[76:79]
	v_mfma_f32_16x16x32_bf16 v[72:75], v[116:119], v[192:195], v[72:75]
	v_mfma_f32_16x16x32_bf16 v[68:71], v[108:111], v[200:203], v[68:71]
	v_mfma_f32_16x16x32_bf16 v[64:67], v[116:119], v[200:203], v[64:67]
	v_mfma_f32_16x16x32_bf16 v[92:95], v[112:115], v[164:167], v[92:95]
	v_mfma_f32_16x16x32_bf16 v[88:91], v[124:127], v[164:167], v[88:91]
	v_mfma_f32_16x16x32_bf16 v[84:87], v[112:115], v[172:175], v[84:87]
	v_mfma_f32_16x16x32_bf16 v[80:83], v[124:127], v[172:175], v[80:83]
	v_mfma_f32_16x16x32_bf16 v[76:79], v[112:115], v[196:199], v[76:79]
	v_mfma_f32_16x16x32_bf16 v[72:75], v[124:127], v[196:199], v[72:75]
	v_mfma_f32_16x16x32_bf16 v[68:71], v[112:115], v[214:217], v[68:71]
	v_mfma_f32_16x16x32_bf16 v[64:67], v[124:127], v[214:217], v[64:67]
	v_mfma_f32_16x16x32_bf16 v[28:31], v[128:131], v[160:163], v[28:31]
	v_mfma_f32_16x16x32_bf16 v[24:27], v[152:155], v[160:163], v[24:27]
	v_mfma_f32_16x16x32_bf16 v[20:23], v[128:131], v[168:171], v[20:23]
	v_mfma_f32_16x16x32_bf16 v[16:19], v[152:155], v[168:171], v[16:19]
	v_mfma_f32_16x16x32_bf16 v[12:15], v[128:131], v[192:195], v[12:15]
	v_mfma_f32_16x16x32_bf16 v[8:11], v[152:155], v[192:195], v[8:11]
	v_mfma_f32_16x16x32_bf16 v[4:7], v[128:131], v[200:203], v[4:7]
	v_mfma_f32_16x16x32_bf16 v[0:3], v[152:155], v[200:203], v[0:3]
	v_mfma_f32_16x16x32_bf16 v[28:31], v[136:139], v[164:167], v[28:31]
	v_mfma_f32_16x16x32_bf16 v[24:27], v[156:159], v[164:167], v[24:27]
	v_mfma_f32_16x16x32_bf16 v[20:23], v[136:139], v[172:175], v[20:23]
	v_mfma_f32_16x16x32_bf16 v[16:19], v[156:159], v[172:175], v[16:19]
	v_mfma_f32_16x16x32_bf16 v[12:15], v[136:139], v[196:199], v[12:15]
	v_mfma_f32_16x16x32_bf16 v[8:11], v[156:159], v[196:199], v[8:11]
	v_mfma_f32_16x16x32_bf16 v[4:7], v[136:139], v[214:217], v[4:7]
	v_mfma_f32_16x16x32_bf16 v[0:3], v[156:159], v[214:217], v[0:3]
	s_setprio 0
	s_barrier
	s_add_i32 s83, s83, 2
	s_add_u32 s8, s8, 0x100
	s_addc_u32 s9, s9, 0
	s_add_u32 s81, s81, 0x100
	s_addc_u32 s82, s82, 0
	s_cmp_gt_u32 s83, 13
	s_cbranch_scc0 .LBB0_1472

;     __device__ __forceinline__ bool next(int i, Unit& u) const { if (i != 0) return false; const int c0 = (G >= 8) ? G - 5 : G - 2; int k = -1; if (c == c0) k = 0; else if (c == G - 1) k = 1; if (k < 0 || k >= n) return false; u.pm = k; u.pn = 0; return true; }
; #define PG8_STAGE(bufoff, gbase, voff) do { _Pragma("unroll") for (int _i = 0; _i < 2; ++_i) \
;         __builtin_amdgcn_global_load_lds((const unsigned*)((const char*)(gbase) + (voff)[_i]), (PG8_LAS unsigned*)(lds + (bufoff) + ldsw + _i * 8192), 16, 0, 0); } while (0)
; #define PG8_LDA(dst, b, h) do { _Pragma("unroll") for (int m = 0; m < 4; ++m) _Pragma("unroll") for (int k = 0; k < 2; ++k) dst[m][k] = *(const PG8_LAS bf16x8*)(lds + PG8_SA(b, h) + aoff + m * 2048 + k * 1024); } while (0)
; #define PG8_LDB(dst, b, h) do { _Pragma("unroll") for (int n = 0; n < 2; ++n) _Pragma("unroll") for (int k = 0; k < 2; ++k) dst[n][k] = *(const PG8_LAS bf16x8*)(lds + PG8_SB(b, h) + boff + n * 2048 + k * 1024); } while (0)
; template <class Epi, class Sched, bool ALIGN_EPI = false, bool SP2 = false>
; __device__ __forceinline__ void gemm_phase(PG8_LAS unsigned char* lds, const Gemm g, const Sched& S, const Epi& E) {
;     ...
;         const bool has_next = S.next(ui + 1, nxt);
;         const char* nA = has_next ? (const char*)g.A + (size_t)nxt.pm * tstep : cA; const char* nB = has_next ? (const char*)g.Bt + (size_t)nxt.pn * tstep : cB;
;         for (int t = 0; t < nt; t += 2) {
;             const bool last = (t == nt - 2);
;             const char* a1 = cA + (size_t)(t + 1) * kstep;
;             const char* a2 = last ? nA : cA + (size_t)(t + 2) * kstep; const char* b2 = last ? nB : cB + (size_t)(t + 2) * kstep;
;             const char* a3 = a2 + kstep; const char* b3 = b2 + kstep;
;             if (last && has_next) S.a_ready(nxt);
;             if constexpr (SP2) {
;             PG8_LDB(B0, 0, 0); PG8_LDB(B1, 0, 1); PG8_SCHED; PG8_LDA(At, 0, 0); PG8_STAGE(PG8_SA(1, 1), a1 + hstep, voffA);
;             PG8_WAIT_V(8); PG8_WAIT_L(0); PG8_BAR; PG8_MMA(0, 0, At, B0); PG8_MMA(0, 1, At, B1); PG8_BAR; PG8_SCHED;
;             PG8_LDA(At, 0, 1); PG8_STAGE(PG8_SB(0, 0), b2, voffB); PG8_STAGE(PG8_SB(0, 1), b2 + hstep, voffB); PG8_STAGE(PG8_SA(0, 0), a2, voffA);
;             PG8_WAIT_V(8); PG8_WAIT_L(0); PG8_BAR; PG8_MMA(1, 0, At, B0); PG8_MMA(1, 1, At, B1); PG8_BAR; PG8_SCHED;
.LBB0_1608:
	s_ashr_i32 s37, s36, 31
	s_lshl_b64 s[40:41], s[36:37], 19
	s_add_u32 s40, s14, s40
	s_addc_u32 s41, s15, s41
	s_and_b64 s[42:43], s[38:39], exec
	s_cselect_b32 s37, s41, s45
	s_cselect_b32 s77, s40, s44
	s_ashr_i32 s31, s30, 31
	s_lshl_b64 s[42:43], s[30:31], 19
	s_add_u32 s42, s34, s42
	s_addc_u32 s43, s35, s43
	s_and_b64 s[56:57], s[38:39], exec
	s_cselect_b32 s31, s43, s47
	s_cselect_b32 s78, s42, s46
	s_add_u32 s44, s44, 0x40080
	s_addc_u32 s45, s45, 0
	s_add_u32 s79, s46, 0x100
	v_mov_b32_e32 v0, 0
	s_addc_u32 s80, s47, 0
	s_mov_b32 s81, -2
	ds_read_b128 v[148:151], v145
	ds_read_b128 v[152:155], v145 offset:1024
	ds_read_b128 v[156:159], v145 offset:2048
	ds_read_b128 v[160:163], v145 offset:3072
	ds_read_b128 v[164:167], v146
	ds_read_b128 v[168:171], v146 offset:1024
	ds_read_b128 v[172:175], v146 offset:2048
	ds_read_b128 v[176:179], v146 offset:3072
	s_add_u32 s46, s44, 0xfffc0080
	s_addc_u32 s47, s45, -1
	s_cmp_eq_u32 s81, 12
	s_cselect_b32 s57, s37, s47
	s_cselect_b32 s56, s77, s46
	s_cselect_b32 s47, s31, s80
	s_cselect_b32 s46, s78, s79
	v_lshl_add_u64 v[204:205], s[44:45], 0, v[136:137]
	s_add_i32 m0, s60, 0xc000
	ds_read_b128 v[180:183], v147
	ds_read_b128 v[184:187], v147 offset:1024
	ds_read_b128 v[188:191], v147 offset:2048
	ds_read_b128 v[192:195], v147 offset:3072
	ds_read_b128 v[196:199], v147 offset:4096
	ds_read_b128 v[200:203], v147 offset:5120
	ds_read_b128 v[208:211], v147 offset:6144
	ds_read_b128 v[212:215], v147 offset:7168
	global_load_lds_dwordx4 v[204:205], off
	v_lshl_add_u64 v[204:205], s[44:45], 0, v[138:139]
	s_add_i32 m0, s60, 0xe000
	s_nop 0
	global_load_lds_dwordx4 v[204:205], off
	s_waitcnt vmcnt(8)
	s_waitcnt lgkmcnt(0)
	s_barrier
	s_setprio 1
	s_waitcnt lgkmcnt(0)
	v_mfma_f32_16x16x32_bf16 v[124:127], v[148:151], v[180:183], 0
	v_mfma_f32_16x16x32_bf16 v[120:123], v[156:159], v[180:183], 0
	v_mfma_f32_16x16x32_bf16 v[116:119], v[148:151], v[188:191], 0
	v_mfma_f32_16x16x32_bf16 v[112:115], v[156:159], v[188:191], 0
	v_mfma_f32_16x16x32_bf16 v[100:103], v[148:151], v[196:199], 0
	v_mfma_f32_16x16x32_bf16 v[96:99], v[156:159], v[196:199], 0
	v_mfma_f32_16x16x32_bf16 v[84:87], v[148:151], v[208:211], 0
	v_mfma_f32_16x16x32_bf16 v[80:83], v[156:159], v[208:211], 0
	v_mfma_f32_16x16x32_bf16 v[124:127], v[152:155], v[184:187], v[124:127]
	v_mfma_f32_16x16x32_bf16 v[120:123], v[160:163], v[184:187], v[120:123]
	v_mfma_f32_16x16x32_bf16 v[116:119], v[152:155], v[192:195], v[116:119]
	v_mfma_f32_16x16x32_bf16 v[112:115], v[160:163], v[192:195], v[112:115]
	v_mfma_f32_16x16x32_bf16 v[100:103], v[152:155], v[200:203], v[100:103]
	v_mfma_f32_16x16x32_bf16 v[96:99], v[160:163], v[200:203], v[96:99]
	v_mfma_f32_16x16x32_bf16 v[84:87], v[152:155], v[212:215], v[84:87]
	v_mfma_f32_16x16x32_bf16 v[80:83], v[160:163], v[212:215], v[80:83]
	v_mfma_f32_16x16x32_bf16 v[108:111], v[164:167], v[180:183], 0
	v_mfma_f32_16x16x32_bf16 v[104:107], v[172:175], v[180:183], 0
	v_mfma_f32_16x16x32_bf16 v[92:95], v[164:167], v[188:191], 0
	v_mfma_f32_16x16x32_bf16 v[88:91], v[172:175], v[188:191], 0
	v_mfma_f32_16x16x32_bf16 v[76:79], v[164:167], v[196:199], 0
	v_mfma_f32_16x16x32_bf16 v[72:75], v[172:175], v[196:199], 0
	v_mfma_f32_16x16x32_bf16 v[68:71], v[164:167], v[208:211], 0
	v_mfma_f32_16x16x32_bf16 v[64:67], v[172:175], v[208:211], 0
	v_mfma_f32_16x16x32_bf16 v[108:111], v[168:171], v[184:187], v[108:111]
	v_mfma_f32_16x16x32_bf16 v[104:107], v[176:179], v[184:187], v[104:107]
	v_mfma_f32_16x16x32_bf16 v[92:95], v[168:171], v[192:195], v[92:95]
	v_mfma_f32_16x16x32_bf16 v[88:91], v[176:179], v[192:195], v[88:91]
	v_mfma_f32_16x16x32_bf16 v[76:79], v[168:171], v[200:203], v[76:79]
	v_mfma_f32_16x16x32_bf16 v[72:75], v[176:179], v[200:203], v[72:75]
	v_mfma_f32_16x16x32_bf16 v[68:71], v[168:171], v[212:215], v[68:71]
	v_mfma_f32_16x16x32_bf16 v[64:67], v[176:179], v[212:215], v[64:67]
	s_setprio 0
	s_barrier
	s_add_i32 s82, s71, s59
	v_lshl_add_u64 v[204:205], s[46:47], 0, v[130:131]
	s_mov_b32 m0, s82
	ds_read_b128 v[180:183], v147 offset:16384
	ds_read_b128 v[184:187], v147 offset:17408
	ds_read_b128 v[188:191], v147 offset:18432
	ds_read_b128 v[192:195], v147 offset:19456
	ds_read_b128 v[196:199], v147 offset:20480
	ds_read_b128 v[200:203], v147 offset:21504
	ds_read_b128 v[208:211], v147 offset:22528
	ds_read_b128 v[212:215], v147 offset:23552
	global_load_lds_dwordx4 v[204:205], off
	s_add_i32 m0, s82, 0x2000
	s_add_u32 s82, s46, 0x40000
	v_lshl_add_u64 v[216:217], s[46:47], 0, v[134:135]
	s_addc_u32 s83, s47, 0
	s_add_i32 s88, s72, s59
	global_load_lds_dwordx4 v[216:217], off
	v_lshl_add_u64 v[218:219], s[82:83], 0, v[130:131]
	s_mov_b32 m0, s88
	v_lshl_add_u64 v[220:221], s[56:57], 0, v[132:133]
	global_load_lds_dwordx4 v[218:219], off
	v_lshl_add_u64 v[218:219], s[82:83], 0, v[134:135]
	s_add_i32 m0, s88, 0x2000
	s_nop 0
	global_load_lds_dwordx4 v[218:219], off
	v_lshl_add_u64 v[218:219], s[56:57], 0, v[128:129]
	s_mov_b32 m0, s60
	s_nop 0
	global_load_lds_dwordx4 v[218:219], off
	s_mov_b32 m0, s61
	s_nop 0
	global_load_lds_dwordx4 v[220:221], off
	s_waitcnt vmcnt(8)
	s_waitcnt lgkmcnt(0)
	s_barrier
; #define PG8_STAGE(bufoff, gbase, voff) do { _Pragma("unroll") for (int _i = 0; _i < 2; ++_i) \
;         __builtin_amdgcn_global_load_lds((const unsigned*)((const char*)(gbase) + (voff)[_i]), (PG8_LAS unsigned*)(lds + (bufoff) + ldsw + _i * 8192), 16, 0, 0); } while (0)
; #define PG8_LDA(dst, b, h) do { _Pragma("unroll") for (int m = 0; m < 4; ++m) _Pragma("unroll") for (int k = 0; k < 2; ++k) dst[m][k] = *(const PG8_LAS bf16x8*)(lds + PG8_SA(b, h) + aoff + m * 2048 + k * 1024); } while (0)
; #define PG8_LDB(dst, b, h) do { _Pragma("unroll") for (int n = 0; n < 2; ++n) _Pragma("unroll") for (int k = 0; k < 2; ++k) dst[n][k] = *(const PG8_LAS bf16x8*)(lds + PG8_SB(b, h) + boff + n * 2048 + k * 1024); } while (0)
; #define PG8_MMA(ai, bj, At, Bt) do { __builtin_amdgcn_s_setprio(1); _Pragma("unroll") for (int m = 0; m < 4; ++m) _Pragma("unroll") for (int n = 0; n < 2; ++n) _Pragma("unroll") for (int k = 0; k < 2; ++k) \
;         acc[ai][bj][m][n] = __builtin_amdgcn_mfma_f32_16x16x32_bf16(Bt[n][k], At[m][k], acc[ai][bj][m][n], 0, 0, 0); __builtin_amdgcn_s_setprio(0); } while (0)
; #define PG8_WAIT_V(n) asm volatile("s_waitcnt vmcnt(" #n ")" ::: "memory")
; #define PG8_WAIT_L(n) asm volatile("s_waitcnt lgkmcnt(" #n ")" ::: "memory")
; #define PG8_BAR __builtin_amdgcn_s_barrier()
; #define PG8_SCHED __builtin_amdgcn_sched_barrier(0)
; template <class Epi, class Sched, bool ALIGN_EPI = false, bool SP2 = false>
; __device__ __forceinline__ void gemm_phase(PG8_LAS unsigned char* lds, const Gemm g, const Sched& S, const Epi& E) {
;     ...
;             PG8_WAIT_V(8); PG8_WAIT_L(0); PG8_BAR; PG8_MMA(1, 0, At, B0); PG8_MMA(1, 1, At, B1); PG8_BAR; PG8_SCHED;
;             PG8_LDB(B0, 1, 0); PG8_LDB(B1, 1, 1); PG8_SCHED; PG8_LDA(At, 1, 0); PG8_STAGE(PG8_SA(0, 1), a2 + hstep, voffA);
;             PG8_WAIT_V(8); PG8_WAIT_L(0); PG8_BAR; PG8_MMA(0, 0, At, B0); PG8_MMA(0, 1, At, B1); PG8_BAR; PG8_SCHED;
	s_setprio 1
	s_waitcnt lgkmcnt(0)
	v_mfma_f32_16x16x32_bf16 v[60:63], v[148:151], v[180:183], 0
	v_mfma_f32_16x16x32_bf16 v[56:59], v[156:159], v[180:183], 0
	v_mfma_f32_16x16x32_bf16 v[52:55], v[148:151], v[188:191], 0
	v_mfma_f32_16x16x32_bf16 v[48:51], v[156:159], v[188:191], 0
	v_mfma_f32_16x16x32_bf16 v[36:39], v[148:151], v[196:199], 0
	v_mfma_f32_16x16x32_bf16 v[32:35], v[156:159], v[196:199], 0
	v_mfma_f32_16x16x32_bf16 v[20:23], v[148:151], v[208:211], 0
	v_mfma_f32_16x16x32_bf16 v[16:19], v[156:159], v[208:211], 0
	v_mfma_f32_16x16x32_bf16 v[60:63], v[152:155], v[184:187], v[60:63]
	v_mfma_f32_16x16x32_bf16 v[56:59], v[160:163], v[184:187], v[56:59]
	v_mfma_f32_16x16x32_bf16 v[52:55], v[152:155], v[192:195], v[52:55]
	v_mfma_f32_16x16x32_bf16 v[48:51], v[160:163], v[192:195], v[48:51]
	v_mfma_f32_16x16x32_bf16 v[36:39], v[152:155], v[200:203], v[36:39]
	v_mfma_f32_16x16x32_bf16 v[32:35], v[160:163], v[200:203], v[32:35]
	v_mfma_f32_16x16x32_bf16 v[20:23], v[152:155], v[212:215], v[20:23]
	v_mfma_f32_16x16x32_bf16 v[16:19], v[160:163], v[212:215], v[16:19]
	v_mfma_f32_16x16x32_bf16 v[44:47], v[164:167], v[180:183], 0
	v_mfma_f32_16x16x32_bf16 v[40:43], v[172:175], v[180:183], 0
	v_mfma_f32_16x16x32_bf16 v[28:31], v[164:167], v[188:191], 0
	v_mfma_f32_16x16x32_bf16 v[24:27], v[172:175], v[188:191], 0
	v_mfma_f32_16x16x32_bf16 v[12:15], v[164:167], v[196:199], 0
	v_mfma_f32_16x16x32_bf16 v[8:11], v[172:175], v[196:199], 0
	v_mfma_f32_16x16x32_bf16 v[4:7], v[164:167], v[208:211], 0
	v_mfma_f32_16x16x32_bf16 v[0:3], v[172:175], v[208:211], 0
	v_mfma_f32_16x16x32_bf16 v[44:47], v[168:171], v[184:187], v[44:47]
	v_mfma_f32_16x16x32_bf16 v[40:43], v[176:179], v[184:187], v[40:43]
	v_mfma_f32_16x16x32_bf16 v[28:31], v[168:171], v[192:195], v[28:31]
	v_mfma_f32_16x16x32_bf16 v[24:27], v[176:179], v[192:195], v[24:27]
	v_mfma_f32_16x16x32_bf16 v[12:15], v[168:171], v[200:203], v[12:15]
	v_mfma_f32_16x16x32_bf16 v[8:11], v[176:179], v[200:203], v[8:11]
	v_mfma_f32_16x16x32_bf16 v[4:7], v[168:171], v[212:215], v[4:7]
	v_mfma_f32_16x16x32_bf16 v[0:3], v[176:179], v[212:215], v[0:3]
	s_setprio 0
	s_barrier
	s_add_i32 s82, 0, 0x18000
	s_add_i32 s83, 0, 0x1c000
	v_add_u32_e32 v160, s82, v143
	v_add_u32_e32 v176, s83, v143
	ds_read_b128 v[148:151], v160
	ds_read_b128 v[152:155], v160 offset:1024
	ds_read_b128 v[156:159], v160 offset:2048
	ds_read_b128 v[160:163], v160 offset:3072
	ds_read_b128 v[164:167], v176
	ds_read_b128 v[168:171], v176 offset:1024
	ds_read_b128 v[172:175], v176 offset:2048
	ds_read_b128 v[176:179], v176 offset:3072
	s_add_u32 s56, s56, 0x40000
	s_addc_u32 s57, s57, 0
	s_mov_b32 m0, s64
	v_lshl_add_u64 v[222:223], s[56:57], 0, v[128:129]
	ds_read_b128 v[180:183], v147 offset:32768
	ds_read_b128 v[184:187], v147 offset:33792
	ds_read_b128 v[188:191], v147 offset:34816
	ds_read_b128 v[192:195], v147 offset:35840
	ds_read_b128 v[196:199], v147 offset:36864
	ds_read_b128 v[200:203], v147 offset:37888
	ds_read_b128 v[208:211], v147 offset:38912
	ds_read_b128 v[212:215], v147 offset:39936
	global_load_lds_dwordx4 v[222:223], off
	v_lshl_add_u64 v[222:223], s[56:57], 0, v[132:133]
	s_mov_b32 m0, s65
	s_nop 0
	global_load_lds_dwordx4 v[222:223], off
	s_waitcnt vmcnt(8)
	s_waitcnt lgkmcnt(0)
	s_barrier
	s_setprio 1
	s_waitcnt lgkmcnt(0)
	v_mfma_f32_16x16x32_bf16 v[124:127], v[148:151], v[180:183], v[124:127]
	v_mfma_f32_16x16x32_bf16 v[120:123], v[156:159], v[180:183], v[120:123]
	v_mfma_f32_16x16x32_bf16 v[116:119], v[148:151], v[188:191], v[116:119]
	v_mfma_f32_16x16x32_bf16 v[112:115], v[156:159], v[188:191], v[112:115]
	v_mfma_f32_16x16x32_bf16 v[100:103], v[148:151], v[196:199], v[100:103]
	v_mfma_f32_16x16x32_bf16 v[96:99], v[156:159], v[196:199], v[96:99]
	v_mfma_f32_16x16x32_bf16 v[84:87], v[148:151], v[208:211], v[84:87]
	v_mfma_f32_16x16x32_bf16 v[80:83], v[156:159], v[208:211], v[80:83]
	v_mfma_f32_16x16x32_bf16 v[124:127], v[152:155], v[184:187], v[124:127]
	v_mfma_f32_16x16x32_bf16 v[120:123], v[160:163], v[184:187], v[120:123]
	v_mfma_f32_16x16x32_bf16 v[116:119], v[152:155], v[192:195], v[116:119]
	v_mfma_f32_16x16x32_bf16 v[112:115], v[160:163], v[192:195], v[112:115]
	v_mfma_f32_16x16x32_bf16 v[100:103], v[152:155], v[200:203], v[100:103]
	v_mfma_f32_16x16x32_bf16 v[96:99], v[160:163], v[200:203], v[96:99]
	v_mfma_f32_16x16x32_bf16 v[84:87], v[152:155], v[212:215], v[84:87]
	v_mfma_f32_16x16x32_bf16 v[80:83], v[160:163], v[212:215], v[80:83]
	v_mfma_f32_16x16x32_bf16 v[108:111], v[164:167], v[180:183], v[108:111]
	v_mfma_f32_16x16x32_bf16 v[104:107], v[172:175], v[180:183], v[104:107]
	v_mfma_f32_16x16x32_bf16 v[92:95], v[164:167], v[188:191], v[92:95]
	v_mfma_f32_16x16x32_bf16 v[88:91], v[172:175], v[188:191], v[88:91]
	v_mfma_f32_16x16x32_bf16 v[76:79], v[164:167], v[196:199], v[76:79]
	v_mfma_f32_16x16x32_bf16 v[72:75], v[172:175], v[196:199], v[72:75]
	v_mfma_f32_16x16x32_bf16 v[68:71], v[164:167], v[208:211], v[68:71]
	v_mfma_f32_16x16x32_bf16 v[64:67], v[172:175], v[208:211], v[64:67]
	v_mfma_f32_16x16x32_bf16 v[108:111], v[168:171], v[184:187], v[108:111]
	v_mfma_f32_16x16x32_bf16 v[104:107], v[176:179], v[184:187], v[104:107]
	v_mfma_f32_16x16x32_bf16 v[92:95], v[168:171], v[192:195], v[92:95]
	v_mfma_f32_16x16x32_bf16 v[88:91], v[176:179], v[192:195], v[88:91]
	v_mfma_f32_16x16x32_bf16 v[76:79], v[168:171], v[200:203], v[76:79]
	v_mfma_f32_16x16x32_bf16 v[72:75], v[176:179], v[200:203], v[72:75]
	v_mfma_f32_16x16x32_bf16 v[68:71], v[168:171], v[212:215], v[68:71]
	v_mfma_f32_16x16x32_bf16 v[64:67], v[176:179], v[212:215], v[64:67]
	s_setprio 0
	s_barrier
; #define PG8_STAGE(bufoff, gbase, voff) do { _Pragma("unroll") for (int _i = 0; _i < 2; ++_i) \
;         __builtin_amdgcn_global_load_lds((const unsigned*)((const char*)(gbase) + (voff)[_i]), (PG8_LAS unsigned*)(lds + (bufoff) + ldsw + _i * 8192), 16, 0, 0); } while (0)
; #define PG8_LDA(dst, b, h) do { _Pragma("unroll") for (int m = 0; m < 4; ++m) _Pragma("unroll") for (int k = 0; k < 2; ++k) dst[m][k] = *(const PG8_LAS bf16x8*)(lds + PG8_SA(b, h) + aoff + m * 2048 + k * 1024); } while (0)
; #define PG8_LDB(dst, b, h) do { _Pragma("unroll") for (int n = 0; n < 2; ++n) _Pragma("unroll") for (int k = 0; k < 2; ++k) dst[n][k] = *(const PG8_LAS bf16x8*)(lds + PG8_SB(b, h) + boff + n * 2048 + k * 1024); } while (0)
; #define PG8_MMA(ai, bj, At, Bt) do { __builtin_amdgcn_s_setprio(1); _Pragma("unroll") for (int m = 0; m < 4; ++m) _Pragma("unroll") for (int n = 0; n < 2; ++n) _Pragma("unroll") for (int k = 0; k < 2; ++k) \
;         acc[ai][bj][m][n] = __builtin_amdgcn_mfma_f32_16x16x32_bf16(Bt[n][k], At[m][k], acc[ai][bj][m][n], 0, 0, 0); __builtin_amdgcn_s_setprio(0); } while (0)
; #define PG8_WAIT_V(n) asm volatile("s_waitcnt vmcnt(" #n ")" ::: "memory")
; #define PG8_WAIT_L(n) asm volatile("s_waitcnt lgkmcnt(" #n ")" ::: "memory")
; #define PG8_BAR __builtin_amdgcn_s_barrier()
; #define PG8_SCHED __builtin_amdgcn_sched_barrier(0)
; template <class Epi, class Sched, bool ALIGN_EPI = false, bool SP2 = false>
; __device__ __forceinline__ void gemm_phase(PG8_LAS unsigned char* lds, const Gemm g, const Sched& S, const Epi& E) {
;     ...
;             PG8_LDB(B0, 0, 0); PG8_LDB(B1, 0, 1); PG8_SCHED; PG8_LDA(At, 0, 0); PG8_STAGE(PG8_SA(1, 1), a1 + hstep, voffA);
;     ...
;             PG8_LDA(At, 1, 1); PG8_STAGE(PG8_SB(1, 0), b3, voffB); PG8_STAGE(PG8_SB(1, 1), b3 + hstep, voffB); PG8_STAGE(PG8_SA(1, 0), a3, voffA);
;             PG8_WAIT_V(8); PG8_WAIT_L(0); PG8_BAR; PG8_MMA(1, 0, At, B0); PG8_MMA(1, 1, At, B1); PG8_BAR; PG8_SCHED;
	s_add_i32 s56, s82, s59
	v_lshl_add_u64 v[204:205], v[204:205], 0, s[18:19]
	s_mov_b32 m0, s56
	ds_read_b128 v[180:183], v147 offset:49152
	ds_read_b128 v[184:187], v147 offset:50176
	ds_read_b128 v[188:191], v147 offset:51200
	ds_read_b128 v[192:195], v147 offset:52224
	ds_read_b128 v[196:199], v147 offset:53248
	ds_read_b128 v[200:203], v147 offset:54272
	ds_read_b128 v[208:211], v147 offset:55296
	ds_read_b128 v[212:215], v147 offset:56320
	global_load_lds_dwordx4 v[204:205], off
	s_add_i32 m0, s56, 0x2000
	s_add_u32 s46, s46, 0x40080
	v_lshl_add_u64 v[204:205], v[216:217], 0, s[18:19]
	s_addc_u32 s47, s47, 0
	s_add_i32 s56, s83, s59
	global_load_lds_dwordx4 v[204:205], off
	v_lshl_add_u64 v[204:205], s[46:47], 0, v[130:131]
	s_mov_b32 m0, s56
	s_nop 0
	global_load_lds_dwordx4 v[204:205], off
	v_lshl_add_u64 v[204:205], s[46:47], 0, v[134:135]
	s_add_i32 m0, s56, 0x2000
	s_nop 0
	global_load_lds_dwordx4 v[204:205], off
	v_lshl_add_u64 v[204:205], v[218:219], 0, s[18:19]
	s_mov_b32 m0, s68
	s_nop 0
	global_load_lds_dwordx4 v[204:205], off
	v_lshl_add_u64 v[204:205], v[220:221], 0, s[18:19]
	s_mov_b32 m0, s69
	s_nop 0
	global_load_lds_dwordx4 v[204:205], off
	s_waitcnt vmcnt(8)
	s_waitcnt lgkmcnt(0)
	s_barrier
	s_setprio 1
	s_waitcnt lgkmcnt(0)
	v_mfma_f32_16x16x32_bf16 v[60:63], v[148:151], v[180:183], v[60:63]
	v_mfma_f32_16x16x32_bf16 v[56:59], v[156:159], v[180:183], v[56:59]
	v_mfma_f32_16x16x32_bf16 v[52:55], v[148:151], v[188:191], v[52:55]
	v_mfma_f32_16x16x32_bf16 v[48:51], v[156:159], v[188:191], v[48:51]
	v_mfma_f32_16x16x32_bf16 v[36:39], v[148:151], v[196:199], v[36:39]
	v_mfma_f32_16x16x32_bf16 v[32:35], v[156:159], v[196:199], v[32:35]
	v_mfma_f32_16x16x32_bf16 v[20:23], v[148:151], v[208:211], v[20:23]
	v_mfma_f32_16x16x32_bf16 v[16:19], v[156:159], v[208:211], v[16:19]
	v_mfma_f32_16x16x32_bf16 v[60:63], v[152:155], v[184:187], v[60:63]
	v_mfma_f32_16x16x32_bf16 v[56:59], v[160:163], v[184:187], v[56:59]
	v_mfma_f32_16x16x32_bf16 v[52:55], v[152:155], v[192:195], v[52:55]
	v_mfma_f32_16x16x32_bf16 v[48:51], v[160:163], v[192:195], v[48:51]
	v_mfma_f32_16x16x32_bf16 v[36:39], v[152:155], v[200:203], v[36:39]
	v_mfma_f32_16x16x32_bf16 v[32:35], v[160:163], v[200:203], v[32:35]
	v_mfma_f32_16x16x32_bf16 v[20:23], v[152:155], v[212:215], v[20:23]
	v_mfma_f32_16x16x32_bf16 v[16:19], v[160:163], v[212:215], v[16:19]
	v_mfma_f32_16x16x32_bf16 v[44:47], v[164:167], v[180:183], v[44:47]
	v_mfma_f32_16x16x32_bf16 v[40:43], v[172:175], v[180:183], v[40:43]
	v_mfma_f32_16x16x32_bf16 v[28:31], v[164:167], v[188:191], v[28:31]
	v_mfma_f32_16x16x32_bf16 v[24:27], v[172:175], v[188:191], v[24:27]
	v_mfma_f32_16x16x32_bf16 v[12:15], v[164:167], v[196:199], v[12:15]
	v_mfma_f32_16x16x32_bf16 v[8:11], v[172:175], v[196:199], v[8:11]
	v_mfma_f32_16x16x32_bf16 v[4:7], v[164:167], v[208:211], v[4:7]
	v_mfma_f32_16x16x32_bf16 v[0:3], v[172:175], v[208:211], v[0:3]
	v_mfma_f32_16x16x32_bf16 v[44:47], v[168:171], v[184:187], v[44:47]
	v_mfma_f32_16x16x32_bf16 v[40:43], v[176:179], v[184:187], v[40:43]
	v_mfma_f32_16x16x32_bf16 v[28:31], v[168:171], v[192:195], v[28:31]
	v_mfma_f32_16x16x32_bf16 v[24:27], v[176:179], v[192:195], v[24:27]
	v_mfma_f32_16x16x32_bf16 v[12:15], v[168:171], v[200:203], v[12:15]
	v_mfma_f32_16x16x32_bf16 v[8:11], v[176:179], v[200:203], v[8:11]
	v_mfma_f32_16x16x32_bf16 v[4:7], v[168:171], v[212:215], v[4:7]
	v_mfma_f32_16x16x32_bf16 v[0:3], v[176:179], v[212:215], v[0:3]
	s_setprio 0
	s_barrier
	s_add_i32 s81, s81, 2
	s_add_u32 s44, s44, 0x100
	s_addc_u32 s45, s45, 0
	s_add_u32 s79, s79, 0x100
	s_addc_u32 s80, s80, 0
	s_cmp_gt_u32 s81, 13
	s_cbranch_scc0 .LBB0_1609
	s_branch .Lpeel_exit_11
.LBB0_1609:
	ds_read_b128 v[148:151], v145
	ds_read_b128 v[152:155], v145 offset:1024
	ds_read_b128 v[156:159], v145 offset:2048
	ds_read_b128 v[160:163], v145 offset:3072
	ds_read_b128 v[164:167], v146
	ds_read_b128 v[168:171], v146 offset:1024
	ds_read_b128 v[172:175], v146 offset:2048
	ds_read_b128 v[176:179], v146 offset:3072
	s_add_u32 s46, s44, 0xfffc0080
	s_addc_u32 s47, s45, -1
	s_cmp_eq_u32 s81, 12
	s_cselect_b32 s57, s37, s47
	s_cselect_b32 s56, s77, s46
	s_cselect_b32 s47, s31, s80
	s_cselect_b32 s46, s78, s79
	v_lshl_add_u64 v[204:205], s[44:45], 0, v[136:137]
	s_add_i32 m0, s60, 0xc000
	ds_read_b128 v[180:183], v147
	ds_read_b128 v[184:187], v147 offset:1024
	ds_read_b128 v[188:191], v147 offset:2048
	ds_read_b128 v[192:195], v147 offset:3072
	ds_read_b128 v[196:199], v147 offset:4096
	ds_read_b128 v[200:203], v147 offset:5120
	ds_read_b128 v[208:211], v147 offset:6144
	ds_read_b128 v[212:215], v147 offset:7168
	global_load_lds_dwordx4 v[204:205], off
	v_lshl_add_u64 v[204:205], s[44:45], 0, v[138:139]
	s_add_i32 m0, s60, 0xe000
	s_nop 0
	global_load_lds_dwordx4 v[204:205], off
	s_waitcnt vmcnt(8)
	s_waitcnt lgkmcnt(0)
	s_barrier
; #define PG8_STAGE(bufoff, gbase, voff) do { _Pragma("unroll") for (int _i = 0; _i < 2; ++_i) \
;         __builtin_amdgcn_global_load_lds((const unsigned*)((const char*)(gbase) + (voff)[_i]), (PG8_LAS unsigned*)(lds + (bufoff) + ldsw + _i * 8192), 16, 0, 0); } while (0)
; #define PG8_LDA(dst, b, h) do { _Pragma("unroll") for (int m = 0; m < 4; ++m) _Pragma("unroll") for (int k = 0; k < 2; ++k) dst[m][k] = *(const PG8_LAS bf16x8*)(lds + PG8_SA(b, h) + aoff + m * 2048 + k * 1024); } while (0)
; #define PG8_MMA(ai, bj, At, Bt) do { __builtin_amdgcn_s_setprio(1); _Pragma("unroll") for (int m = 0; m < 4; ++m) _Pragma("unroll") for (int n = 0; n < 2; ++n) _Pragma("unroll") for (int k = 0; k < 2; ++k) \
;         acc[ai][bj][m][n] = __builtin_amdgcn_mfma_f32_16x16x32_bf16(Bt[n][k], At[m][k], acc[ai][bj][m][n], 0, 0, 0); __builtin_amdgcn_s_setprio(0); } while (0)
; #define PG8_WAIT_V(n) asm volatile("s_waitcnt vmcnt(" #n ")" ::: "memory")
; #define PG8_WAIT_L(n) asm volatile("s_waitcnt lgkmcnt(" #n ")" ::: "memory")
; #define PG8_BAR __builtin_amdgcn_s_barrier()
; #define PG8_SCHED __builtin_amdgcn_sched_barrier(0)
; template <class Epi, class Sched, bool ALIGN_EPI = false, bool SP2 = false>
; __device__ __forceinline__ void gemm_phase(PG8_LAS unsigned char* lds, const Gemm g, const Sched& S, const Epi& E) {
;     ...
;             PG8_WAIT_V(8); PG8_WAIT_L(0); PG8_BAR; PG8_MMA(0, 0, At, B0); PG8_MMA(0, 1, At, B1); PG8_BAR; PG8_SCHED;
;             PG8_LDA(At, 0, 1); PG8_STAGE(PG8_SB(0, 0), b2, voffB); PG8_STAGE(PG8_SB(0, 1), b2 + hstep, voffB); PG8_STAGE(PG8_SA(0, 0), a2, voffA);
;             PG8_WAIT_V(8); PG8_WAIT_L(0); PG8_BAR; PG8_MMA(1, 0, At, B0); PG8_MMA(1, 1, At, B1); PG8_BAR; PG8_SCHED;
	s_setprio 1
	s_waitcnt lgkmcnt(0)
	v_mfma_f32_16x16x32_bf16 v[124:127], v[148:151], v[180:183], v[124:127]
	v_mfma_f32_16x16x32_bf16 v[120:123], v[156:159], v[180:183], v[120:123]
	v_mfma_f32_16x16x32_bf16 v[116:119], v[148:151], v[188:191], v[116:119]
	v_mfma_f32_16x16x32_bf16 v[112:115], v[156:159], v[188:191], v[112:115]
	v_mfma_f32_16x16x32_bf16 v[100:103], v[148:151], v[196:199], v[100:103]
	v_mfma_f32_16x16x32_bf16 v[96:99], v[156:159], v[196:199], v[96:99]
	v_mfma_f32_16x16x32_bf16 v[84:87], v[148:151], v[208:211], v[84:87]
	v_mfma_f32_16x16x32_bf16 v[80:83], v[156:159], v[208:211], v[80:83]
	v_mfma_f32_16x16x32_bf16 v[124:127], v[152:155], v[184:187], v[124:127]
	v_mfma_f32_16x16x32_bf16 v[120:123], v[160:163], v[184:187], v[120:123]
	v_mfma_f32_16x16x32_bf16 v[116:119], v[152:155], v[192:195], v[116:119]
	v_mfma_f32_16x16x32_bf16 v[112:115], v[160:163], v[192:195], v[112:115]
	v_mfma_f32_16x16x32_bf16 v[100:103], v[152:155], v[200:203], v[100:103]
	v_mfma_f32_16x16x32_bf16 v[96:99], v[160:163], v[200:203], v[96:99]
	v_mfma_f32_16x16x32_bf16 v[84:87], v[152:155], v[212:215], v[84:87]
	v_mfma_f32_16x16x32_bf16 v[80:83], v[160:163], v[212:215], v[80:83]
	v_mfma_f32_16x16x32_bf16 v[108:111], v[164:167], v[180:183], v[108:111]
	v_mfma_f32_16x16x32_bf16 v[104:107], v[172:175], v[180:183], v[104:107]
	v_mfma_f32_16x16x32_bf16 v[92:95], v[164:167], v[188:191], v[92:95]
	v_mfma_f32_16x16x32_bf16 v[88:91], v[172:175], v[188:191], v[88:91]
	v_mfma_f32_16x16x32_bf16 v[76:79], v[164:167], v[196:199], v[76:79]
	v_mfma_f32_16x16x32_bf16 v[72:75], v[172:175], v[196:199], v[72:75]
	v_mfma_f32_16x16x32_bf16 v[68:71], v[164:167], v[208:211], v[68:71]
	v_mfma_f32_16x16x32_bf16 v[64:67], v[172:175], v[208:211], v[64:67]
	v_mfma_f32_16x16x32_bf16 v[108:111], v[168:171], v[184:187], v[108:111]
	v_mfma_f32_16x16x32_bf16 v[104:107], v[176:179], v[184:187], v[104:107]
	v_mfma_f32_16x16x32_bf16 v[92:95], v[168:171], v[192:195], v[92:95]
	v_mfma_f32_16x16x32_bf16 v[88:91], v[176:179], v[192:195], v[88:91]
	v_mfma_f32_16x16x32_bf16 v[76:79], v[168:171], v[200:203], v[76:79]
	v_mfma_f32_16x16x32_bf16 v[72:75], v[176:179], v[200:203], v[72:75]
	v_mfma_f32_16x16x32_bf16 v[68:71], v[168:171], v[212:215], v[68:71]
	v_mfma_f32_16x16x32_bf16 v[64:67], v[176:179], v[212:215], v[64:67]
	s_setprio 0
	s_barrier
	s_add_i32 s82, s71, s59
	v_lshl_add_u64 v[204:205], s[46:47], 0, v[130:131]
	s_mov_b32 m0, s82
	ds_read_b128 v[180:183], v147 offset:16384
	ds_read_b128 v[184:187], v147 offset:17408
	ds_read_b128 v[188:191], v147 offset:18432
	ds_read_b128 v[192:195], v147 offset:19456
	ds_read_b128 v[196:199], v147 offset:20480
	ds_read_b128 v[200:203], v147 offset:21504
	ds_read_b128 v[208:211], v147 offset:22528
	ds_read_b128 v[212:215], v147 offset:23552
	global_load_lds_dwordx4 v[204:205], off
	s_add_i32 m0, s82, 0x2000
	s_add_u32 s82, s46, 0x40000
	v_lshl_add_u64 v[216:217], s[46:47], 0, v[134:135]
	s_addc_u32 s83, s47, 0
	s_add_i32 s88, s72, s59
	global_load_lds_dwordx4 v[216:217], off
	v_lshl_add_u64 v[218:219], s[82:83], 0, v[130:131]
	s_mov_b32 m0, s88
	v_lshl_add_u64 v[220:221], s[56:57], 0, v[132:133]
	global_load_lds_dwordx4 v[218:219], off
	v_lshl_add_u64 v[218:219], s[82:83], 0, v[134:135]
	s_add_i32 m0, s88, 0x2000
	s_nop 0
	global_load_lds_dwordx4 v[218:219], off
	v_lshl_add_u64 v[218:219], s[56:57], 0, v[128:129]
	s_mov_b32 m0, s60
	s_nop 0
	global_load_lds_dwordx4 v[218:219], off
	s_mov_b32 m0, s61
	s_nop 0
	global_load_lds_dwordx4 v[220:221], off
	s_waitcnt vmcnt(8)
	s_waitcnt lgkmcnt(0)
	s_barrier
	s_setprio 1
	s_waitcnt lgkmcnt(0)
	v_mfma_f32_16x16x32_bf16 v[60:63], v[148:151], v[180:183], v[60:63]
	v_mfma_f32_16x16x32_bf16 v[56:59], v[156:159], v[180:183], v[56:59]
	v_mfma_f32_16x16x32_bf16 v[52:55], v[148:151], v[188:191], v[52:55]
	v_mfma_f32_16x16x32_bf16 v[48:51], v[156:159], v[188:191], v[48:51]
	v_mfma_f32_16x16x32_bf16 v[36:39], v[148:151], v[196:199], v[36:39]
	v_mfma_f32_16x16x32_bf16 v[32:35], v[156:159], v[196:199], v[32:35]
	v_mfma_f32_16x16x32_bf16 v[20:23], v[148:151], v[208:211], v[20:23]
	v_mfma_f32_16x16x32_bf16 v[16:19], v[156:159], v[208:211], v[16:19]
	v_mfma_f32_16x16x32_bf16 v[60:63], v[152:155], v[184:187], v[60:63]
	v_mfma_f32_16x16x32_bf16 v[56:59], v[160:163], v[184:187], v[56:59]
	v_mfma_f32_16x16x32_bf16 v[52:55], v[152:155], v[192:195], v[52:55]
	v_mfma_f32_16x16x32_bf16 v[48:51], v[160:163], v[192:195], v[48:51]
	v_mfma_f32_16x16x32_bf16 v[36:39], v[152:155], v[200:203], v[36:39]
	v_mfma_f32_16x16x32_bf16 v[32:35], v[160:163], v[200:203], v[32:35]
	v_mfma_f32_16x16x32_bf16 v[20:23], v[152:155], v[212:215], v[20:23]
	v_mfma_f32_16x16x32_bf16 v[16:19], v[160:163], v[212:215], v[16:19]
	v_mfma_f32_16x16x32_bf16 v[44:47], v[164:167], v[180:183], v[44:47]
	v_mfma_f32_16x16x32_bf16 v[40:43], v[172:175], v[180:183], v[40:43]
	v_mfma_f32_16x16x32_bf16 v[28:31], v[164:167], v[188:191], v[28:31]
	v_mfma_f32_16x16x32_bf16 v[24:27], v[172:175], v[188:191], v[24:27]
	v_mfma_f32_16x16x32_bf16 v[12:15], v[164:167], v[196:199], v[12:15]
	v_mfma_f32_16x16x32_bf16 v[8:11], v[172:175], v[196:199], v[8:11]
	v_mfma_f32_16x16x32_bf16 v[4:7], v[164:167], v[208:211], v[4:7]
	v_mfma_f32_16x16x32_bf16 v[0:3], v[172:175], v[208:211], v[0:3]
	v_mfma_f32_16x16x32_bf16 v[44:47], v[168:171], v[184:187], v[44:47]
	v_mfma_f32_16x16x32_bf16 v[40:43], v[176:179], v[184:187], v[40:43]
	v_mfma_f32_16x16x32_bf16 v[28:31], v[168:171], v[192:195], v[28:31]
	v_mfma_f32_16x16x32_bf16 v[24:27], v[176:179], v[192:195], v[24:27]
	v_mfma_f32_16x16x32_bf16 v[12:15], v[168:171], v[200:203], v[12:15]
	v_mfma_f32_16x16x32_bf16 v[8:11], v[176:179], v[200:203], v[8:11]
	v_mfma_f32_16x16x32_bf16 v[4:7], v[168:171], v[212:215], v[4:7]
	v_mfma_f32_16x16x32_bf16 v[0:3], v[176:179], v[212:215], v[0:3]
	s_setprio 0
	s_barrier
; #define PG8_STAGE(bufoff, gbase, voff) do { _Pragma("unroll") for (int _i = 0; _i < 2; ++_i) \
;         __builtin_amdgcn_global_load_lds((const unsigned*)((const char*)(gbase) + (voff)[_i]), (PG8_LAS unsigned*)(lds + (bufoff) + ldsw + _i * 8192), 16, 0, 0); } while (0)
; #define PG8_LDA(dst, b, h) do { _Pragma("unroll") for (int m = 0; m < 4; ++m) _Pragma("unroll") for (int k = 0; k < 2; ++k) dst[m][k] = *(const PG8_LAS bf16x8*)(lds + PG8_SA(b, h) + aoff + m * 2048 + k * 1024); } while (0)
; #define PG8_LDB(dst, b, h) do { _Pragma("unroll") for (int n = 0; n < 2; ++n) _Pragma("unroll") for (int k = 0; k < 2; ++k) dst[n][k] = *(const PG8_LAS bf16x8*)(lds + PG8_SB(b, h) + boff + n * 2048 + k * 1024); } while (0)
; #define PG8_MMA(ai, bj, At, Bt) do { __builtin_amdgcn_s_setprio(1); _Pragma("unroll") for (int m = 0; m < 4; ++m) _Pragma("unroll") for (int n = 0; n < 2; ++n) _Pragma("unroll") for (int k = 0; k < 2; ++k) \
;         acc[ai][bj][m][n] = __builtin_amdgcn_mfma_f32_16x16x32_bf16(Bt[n][k], At[m][k], acc[ai][bj][m][n], 0, 0, 0); __builtin_amdgcn_s_setprio(0); } while (0)
; #define PG8_WAIT_V(n) asm volatile("s_waitcnt vmcnt(" #n ")" ::: "memory")
; #define PG8_WAIT_L(n) asm volatile("s_waitcnt lgkmcnt(" #n ")" ::: "memory")
; #define PG8_BAR __builtin_amdgcn_s_barrier()
; #define PG8_SCHED __builtin_amdgcn_sched_barrier(0)
; template <class Epi, class Sched, bool ALIGN_EPI = false, bool SP2 = false>
; __device__ __forceinline__ void gemm_phase(PG8_LAS unsigned char* lds, const Gemm g, const Sched& S, const Epi& E) {
;     ...
;             PG8_LDB(B0, 1, 0); PG8_LDB(B1, 1, 1); PG8_SCHED; PG8_LDA(At, 1, 0); PG8_STAGE(PG8_SA(0, 1), a2 + hstep, voffA);
;             PG8_WAIT_V(8); PG8_WAIT_L(0); PG8_BAR; PG8_MMA(0, 0, At, B0); PG8_MMA(0, 1, At, B1); PG8_BAR; PG8_SCHED;
	s_add_i32 s82, 0, 0x18000
	s_add_i32 s83, 0, 0x1c000
	v_add_u32_e32 v160, s82, v143
	v_add_u32_e32 v176, s83, v143
	ds_read_b128 v[148:151], v160
	ds_read_b128 v[152:155], v160 offset:1024
	ds_read_b128 v[156:159], v160 offset:2048
	ds_read_b128 v[160:163], v160 offset:3072
	ds_read_b128 v[164:167], v176
	ds_read_b128 v[168:171], v176 offset:1024
	ds_read_b128 v[172:175], v176 offset:2048
	ds_read_b128 v[176:179], v176 offset:3072
	s_add_u32 s56, s56, 0x40000
	s_addc_u32 s57, s57, 0
	s_mov_b32 m0, s64
	v_lshl_add_u64 v[222:223], s[56:57], 0, v[128:129]
	ds_read_b128 v[180:183], v147 offset:32768
	ds_read_b128 v[184:187], v147 offset:33792
	ds_read_b128 v[188:191], v147 offset:34816
	ds_read_b128 v[192:195], v147 offset:35840
	ds_read_b128 v[196:199], v147 offset:36864
	ds_read_b128 v[200:203], v147 offset:37888
	ds_read_b128 v[208:211], v147 offset:38912
	ds_read_b128 v[212:215], v147 offset:39936
	global_load_lds_dwordx4 v[222:223], off
	v_lshl_add_u64 v[222:223], s[56:57], 0, v[132:133]
	s_mov_b32 m0, s65
	s_nop 0
	global_load_lds_dwordx4 v[222:223], off
	s_waitcnt vmcnt(8)
	s_waitcnt lgkmcnt(0)
	s_barrier
	s_setprio 1
	s_waitcnt lgkmcnt(0)
	v_mfma_f32_16x16x32_bf16 v[124:127], v[148:151], v[180:183], v[124:127]
	v_mfma_f32_16x16x32_bf16 v[120:123], v[156:159], v[180:183], v[120:123]
	v_mfma_f32_16x16x32_bf16 v[116:119], v[148:151], v[188:191], v[116:119]
	v_mfma_f32_16x16x32_bf16 v[112:115], v[156:159], v[188:191], v[112:115]
	v_mfma_f32_16x16x32_bf16 v[100:103], v[148:151], v[196:199], v[100:103]
	v_mfma_f32_16x16x32_bf16 v[96:99], v[156:159], v[196:199], v[96:99]
	v_mfma_f32_16x16x32_bf16 v[84:87], v[148:151], v[208:211], v[84:87]
	v_mfma_f32_16x16x32_bf16 v[80:83], v[156:159], v[208:211], v[80:83]
	v_mfma_f32_16x16x32_bf16 v[124:127], v[152:155], v[184:187], v[124:127]
	v_mfma_f32_16x16x32_bf16 v[120:123], v[160:163], v[184:187], v[120:123]
	v_mfma_f32_16x16x32_bf16 v[116:119], v[152:155], v[192:195], v[116:119]
	v_mfma_f32_16x16x32_bf16 v[112:115], v[160:163], v[192:195], v[112:115]
	v_mfma_f32_16x16x32_bf16 v[100:103], v[152:155], v[200:203], v[100:103]
	v_mfma_f32_16x16x32_bf16 v[96:99], v[160:163], v[200:203], v[96:99]
	v_mfma_f32_16x16x32_bf16 v[84:87], v[152:155], v[212:215], v[84:87]
	v_mfma_f32_16x16x32_bf16 v[80:83], v[160:163], v[212:215], v[80:83]
	v_mfma_f32_16x16x32_bf16 v[108:111], v[164:167], v[180:183], v[108:111]
	v_mfma_f32_16x16x32_bf16 v[104:107], v[172:175], v[180:183], v[104:107]
	v_mfma_f32_16x16x32_bf16 v[92:95], v[164:167], v[188:191], v[92:95]
	v_mfma_f32_16x16x32_bf16 v[88:91], v[172:175], v[188:191], v[88:91]
	v_mfma_f32_16x16x32_bf16 v[76:79], v[164:167], v[196:199], v[76:79]
	v_mfma_f32_16x16x32_bf16 v[72:75], v[172:175], v[196:199], v[72:75]
	v_mfma_f32_16x16x32_bf16 v[68:71], v[164:167], v[208:211], v[68:71]
	v_mfma_f32_16x16x32_bf16 v[64:67], v[172:175], v[208:211], v[64:67]
	v_mfma_f32_16x16x32_bf16 v[108:111], v[168:171], v[184:187], v[108:111]
	v_mfma_f32_16x16x32_bf16 v[104:107], v[176:179], v[184:187], v[104:107]
	v_mfma_f32_16x16x32_bf16 v[92:95], v[168:171], v[192:195], v[92:95]
	v_mfma_f32_16x16x32_bf16 v[88:91], v[176:179], v[192:195], v[88:91]
	v_mfma_f32_16x16x32_bf16 v[76:79], v[168:171], v[200:203], v[76:79]
	v_mfma_f32_16x16x32_bf16 v[72:75], v[176:179], v[200:203], v[72:75]
	v_mfma_f32_16x16x32_bf16 v[68:71], v[168:171], v[212:215], v[68:71]
	v_mfma_f32_16x16x32_bf16 v[64:67], v[176:179], v[212:215], v[64:67]
	s_setprio 0
	s_barrier
; #define PG8_STAGE(bufoff, gbase, voff) do { _Pragma("unroll") for (int _i = 0; _i < 2; ++_i) \
;         __builtin_amdgcn_global_load_lds((const unsigned*)((const char*)(gbase) + (voff)[_i]), (PG8_LAS unsigned*)(lds + (bufoff) + ldsw + _i * 8192), 16, 0, 0); } while (0)
; #define PG8_LDA(dst, b, h) do { _Pragma("unroll") for (int m = 0; m < 4; ++m) _Pragma("unroll") for (int k = 0; k < 2; ++k) dst[m][k] = *(const PG8_LAS bf16x8*)(lds + PG8_SA(b, h) + aoff + m * 2048 + k * 1024); } while (0)
; #define PG8_MMA(ai, bj, At, Bt) do { __builtin_amdgcn_s_setprio(1); _Pragma("unroll") for (int m = 0; m < 4; ++m) _Pragma("unroll") for (int n = 0; n < 2; ++n) _Pragma("unroll") for (int k = 0; k < 2; ++k) \
;         acc[ai][bj][m][n] = __builtin_amdgcn_mfma_f32_16x16x32_bf16(Bt[n][k], At[m][k], acc[ai][bj][m][n], 0, 0, 0); __builtin_amdgcn_s_setprio(0); } while (0)
; #define PG8_WAIT_V(n) asm volatile("s_waitcnt vmcnt(" #n ")" ::: "memory")
; #define PG8_WAIT_L(n) asm volatile("s_waitcnt lgkmcnt(" #n ")" ::: "memory")
; #define PG8_BAR __builtin_amdgcn_s_barrier()
; #define PG8_SCHED __builtin_amdgcn_sched_barrier(0)
; template <class Epi, class Sched, bool ALIGN_EPI = false, bool SP2 = false>
; __device__ __forceinline__ void gemm_phase(PG8_LAS unsigned char* lds, const Gemm g, const Sched& S, const Epi& E) {
;     ...
;         for (int t = 0; t < nt; t += 2) {
;     ...
;             PG8_LDA(At, 1, 1); PG8_STAGE(PG8_SB(1, 0), b3, voffB); PG8_STAGE(PG8_SB(1, 1), b3 + hstep, voffB); PG8_STAGE(PG8_SA(1, 0), a3, voffA);
;             PG8_WAIT_V(8); PG8_WAIT_L(0); PG8_BAR; PG8_MMA(1, 0, At, B0); PG8_MMA(1, 1, At, B1); PG8_BAR; PG8_SCHED;
	s_add_i32 s56, s82, s59
	v_lshl_add_u64 v[204:205], v[204:205], 0, s[18:19]
	s_mov_b32 m0, s56
	ds_read_b128 v[180:183], v147 offset:49152
	ds_read_b128 v[184:187], v147 offset:50176
	ds_read_b128 v[188:191], v147 offset:51200
	ds_read_b128 v[192:195], v147 offset:52224
	ds_read_b128 v[196:199], v147 offset:53248
	ds_read_b128 v[200:203], v147 offset:54272
	ds_read_b128 v[208:211], v147 offset:55296
	ds_read_b128 v[212:215], v147 offset:56320
	global_load_lds_dwordx4 v[204:205], off
	s_add_i32 m0, s56, 0x2000
	s_add_u32 s46, s46, 0x40080
	v_lshl_add_u64 v[204:205], v[216:217], 0, s[18:19]
	s_addc_u32 s47, s47, 0
	s_add_i32 s56, s83, s59
	global_load_lds_dwordx4 v[204:205], off
	v_lshl_add_u64 v[204:205], s[46:47], 0, v[130:131]
	s_mov_b32 m0, s56
	s_nop 0
	global_load_lds_dwordx4 v[204:205], off
	v_lshl_add_u64 v[204:205], s[46:47], 0, v[134:135]
	s_add_i32 m0, s56, 0x2000
	s_nop 0
	global_load_lds_dwordx4 v[204:205], off
	v_lshl_add_u64 v[204:205], v[218:219], 0, s[18:19]
	s_mov_b32 m0, s68
	s_nop 0
	global_load_lds_dwordx4 v[204:205], off
	v_lshl_add_u64 v[204:205], v[220:221], 0, s[18:19]
	s_mov_b32 m0, s69
	s_nop 0
	global_load_lds_dwordx4 v[204:205], off
	s_waitcnt vmcnt(8)
	s_waitcnt lgkmcnt(0)
	s_barrier
	s_setprio 1
	s_waitcnt lgkmcnt(0)
	v_mfma_f32_16x16x32_bf16 v[60:63], v[148:151], v[180:183], v[60:63]
	v_mfma_f32_16x16x32_bf16 v[56:59], v[156:159], v[180:183], v[56:59]
	v_mfma_f32_16x16x32_bf16 v[52:55], v[148:151], v[188:191], v[52:55]
	v_mfma_f32_16x16x32_bf16 v[48:51], v[156:159], v[188:191], v[48:51]
	v_mfma_f32_16x16x32_bf16 v[36:39], v[148:151], v[196:199], v[36:39]
	v_mfma_f32_16x16x32_bf16 v[32:35], v[156:159], v[196:199], v[32:35]
	v_mfma_f32_16x16x32_bf16 v[20:23], v[148:151], v[208:211], v[20:23]
	v_mfma_f32_16x16x32_bf16 v[16:19], v[156:159], v[208:211], v[16:19]
	v_mfma_f32_16x16x32_bf16 v[60:63], v[152:155], v[184:187], v[60:63]
	v_mfma_f32_16x16x32_bf16 v[56:59], v[160:163], v[184:187], v[56:59]
	v_mfma_f32_16x16x32_bf16 v[52:55], v[152:155], v[192:195], v[52:55]
	v_mfma_f32_16x16x32_bf16 v[48:51], v[160:163], v[192:195], v[48:51]
	v_mfma_f32_16x16x32_bf16 v[36:39], v[152:155], v[200:203], v[36:39]
	v_mfma_f32_16x16x32_bf16 v[32:35], v[160:163], v[200:203], v[32:35]
	v_mfma_f32_16x16x32_bf16 v[20:23], v[152:155], v[212:215], v[20:23]
	v_mfma_f32_16x16x32_bf16 v[16:19], v[160:163], v[212:215], v[16:19]
	v_mfma_f32_16x16x32_bf16 v[44:47], v[164:167], v[180:183], v[44:47]
	v_mfma_f32_16x16x32_bf16 v[40:43], v[172:175], v[180:183], v[40:43]
	v_mfma_f32_16x16x32_bf16 v[28:31], v[164:167], v[188:191], v[28:31]
	v_mfma_f32_16x16x32_bf16 v[24:27], v[172:175], v[188:191], v[24:27]
	v_mfma_f32_16x16x32_bf16 v[12:15], v[164:167], v[196:199], v[12:15]
	v_mfma_f32_16x16x32_bf16 v[8:11], v[172:175], v[196:199], v[8:11]
	v_mfma_f32_16x16x32_bf16 v[4:7], v[164:167], v[208:211], v[4:7]
	v_mfma_f32_16x16x32_bf16 v[0:3], v[172:175], v[208:211], v[0:3]
	v_mfma_f32_16x16x32_bf16 v[44:47], v[168:171], v[184:187], v[44:47]
	v_mfma_f32_16x16x32_bf16 v[40:43], v[176:179], v[184:187], v[40:43]
	v_mfma_f32_16x16x32_bf16 v[28:31], v[168:171], v[192:195], v[28:31]
	v_mfma_f32_16x16x32_bf16 v[24:27], v[176:179], v[192:195], v[24:27]
	v_mfma_f32_16x16x32_bf16 v[12:15], v[168:171], v[200:203], v[12:15]
	v_mfma_f32_16x16x32_bf16 v[8:11], v[176:179], v[200:203], v[8:11]
	v_mfma_f32_16x16x32_bf16 v[4:7], v[168:171], v[212:215], v[4:7]
	v_mfma_f32_16x16x32_bf16 v[0:3], v[176:179], v[212:215], v[0:3]
	s_setprio 0
	s_barrier
	s_add_i32 s81, s81, 2
	s_add_u32 s44, s44, 0x100
	s_addc_u32 s45, s45, 0
	s_add_u32 s79, s79, 0x100
	s_addc_u32 s80, s80, 0
	s_cmp_gt_u32 s81, 13
	s_cbranch_scc0 .LBB0_1609

;     __device__ __forceinline__ bool next(int i, Unit& u) const { if (i != 0) return false; const int c0 = (G >= 8) ? G - 5 : G - 2; int k = -1; if (c == c0) k = 0; else if (c == G - 1) k = 1; if (k < 0 || k >= n) return false; u.pm = k; u.pn = 0; return true; }
; #define PG8_STAGE(bufoff, gbase, voff) do { _Pragma("unroll") for (int _i = 0; _i < 2; ++_i) \
;         __builtin_amdgcn_global_load_lds((const unsigned*)((const char*)(gbase) + (voff)[_i]), (PG8_LAS unsigned*)(lds + (bufoff) + ldsw + _i * 8192), 16, 0, 0); } while (0)
; #define PG8_LDA(dst, b, h) do { _Pragma("unroll") for (int m = 0; m < 4; ++m) _Pragma("unroll") for (int k = 0; k < 2; ++k) dst[m][k] = *(const PG8_LAS bf16x8*)(lds + PG8_SA(b, h) + aoff + m * 2048 + k * 1024); } while (0)
; #define PG8_LDB(dst, b, h) do { _Pragma("unroll") for (int n = 0; n < 2; ++n) _Pragma("unroll") for (int k = 0; k < 2; ++k) dst[n][k] = *(const PG8_LAS bf16x8*)(lds + PG8_SB(b, h) + boff + n * 2048 + k * 1024); } while (0)
; template <class Epi, class Sched, bool ALIGN_EPI = false, bool SP2 = false>
; __device__ __forceinline__ void gemm_phase(PG8_LAS unsigned char* lds, const Gemm g, const Sched& S, const Epi& E) {
;     ...
;         const bool has_next = S.next(ui + 1, nxt);
;         const char* nA = has_next ? (const char*)g.A + (size_t)nxt.pm * tstep : cA; const char* nB = has_next ? (const char*)g.Bt + (size_t)nxt.pn * tstep : cB;
;         for (int t = 0; t < nt; t += 2) {
;             const bool last = (t == nt - 2);
;             const char* a1 = cA + (size_t)(t + 1) * kstep;
;             const char* a2 = last ? nA : cA + (size_t)(t + 2) * kstep; const char* b2 = last ? nB : cB + (size_t)(t + 2) * kstep;
;             const char* a3 = a2 + kstep; const char* b3 = b2 + kstep;
;             if (last && has_next) S.a_ready(nxt);
;             if constexpr (SP2) {
;             PG8_LDB(B0, 0, 0); PG8_LDB(B1, 0, 1); PG8_SCHED; PG8_LDA(At, 0, 0); PG8_STAGE(PG8_SA(1, 1), a1 + hstep, voffA);
;             PG8_WAIT_V(8); PG8_WAIT_L(0); PG8_BAR; PG8_MMA(0, 0, At, B0); PG8_MMA(0, 1, At, B1); PG8_BAR; PG8_SCHED;
;             PG8_LDA(At, 0, 1); PG8_STAGE(PG8_SB(0, 0), b2, voffB); PG8_STAGE(PG8_SB(0, 1), b2 + hstep, voffB); PG8_STAGE(PG8_SA(0, 0), a2, voffA);
;             PG8_WAIT_V(8); PG8_WAIT_L(0); PG8_BAR; PG8_MMA(1, 0, At, B0); PG8_MMA(1, 1, At, B1); PG8_BAR; PG8_SCHED;
.LBB0_1787:
	s_ashr_i32 s21, s20, 31
	s_lshl_b64 s[24:25], s[20:21], 19
	s_add_u32 s24, s97, s24
	s_addc_u32 s25, s3, s25
	s_and_b64 s[26:27], s[22:23], exec
	s_cselect_b32 s21, s25, s31
	s_cselect_b32 s61, s24, s30
	s_ashr_i32 s19, s18, 31
	s_lshl_b64 s[26:27], s[18:19], 19
	s_add_u32 s26, s38, s26
	s_addc_u32 s27, s39, s27
	s_and_b64 s[36:37], s[22:23], exec
	s_cselect_b32 s19, s27, s35
	s_cselect_b32 s64, s26, s34
	s_add_u32 s30, s30, 0x40080
	s_addc_u32 s31, s31, 0
	s_add_u32 s65, s34, 0x100
	v_mov_b32_e32 v0, 0
	s_addc_u32 s66, s35, 0
	s_mov_b32 s67, -2
	ds_read_b128 v[164:167], v160
	ds_read_b128 v[168:171], v160 offset:1024
	ds_read_b128 v[172:175], v160 offset:2048
	ds_read_b128 v[176:179], v160 offset:3072
	ds_read_b128 v[180:183], v161
	ds_read_b128 v[184:187], v161 offset:1024
	ds_read_b128 v[188:191], v161 offset:2048
	ds_read_b128 v[192:195], v161 offset:3072
	s_add_u32 s34, s30, 0xfffc0080
	s_addc_u32 s35, s31, -1
	s_cmp_eq_u32 s67, 12
	s_cselect_b32 s37, s21, s35
	s_cselect_b32 s36, s61, s34
	s_cselect_b32 s35, s19, s66
	s_cselect_b32 s34, s64, s65
	v_lshl_add_u64 v[142:143], s[30:31], 0, v[136:137]
	s_add_i32 m0, s29, 0xc000
	ds_read_b128 v[196:199], v162
	ds_read_b128 v[200:203], v162 offset:1024
	ds_read_b128 v[208:211], v162 offset:2048
	ds_read_b128 v[212:215], v162 offset:3072
	ds_read_b128 v[216:219], v162 offset:4096
	ds_read_b128 v[220:223], v162 offset:5120
	ds_read_b128 v[224:227], v162 offset:6144
	ds_read_b128 v[228:231], v162 offset:7168
	global_load_lds_dwordx4 v[142:143], off
	v_lshl_add_u64 v[142:143], s[30:31], 0, v[138:139]
	s_add_i32 m0, s29, 0xe000
	s_nop 0
	global_load_lds_dwordx4 v[142:143], off
	s_waitcnt vmcnt(8)
	s_waitcnt lgkmcnt(0)
	s_barrier
	s_setprio 1
	s_waitcnt lgkmcnt(0)
	v_mfma_f32_16x16x32_bf16 v[124:127], v[164:167], v[196:199], 0
	v_mfma_f32_16x16x32_bf16 v[120:123], v[172:175], v[196:199], 0
	v_mfma_f32_16x16x32_bf16 v[108:111], v[164:167], v[208:211], 0
	v_mfma_f32_16x16x32_bf16 v[104:107], v[172:175], v[208:211], 0
	v_mfma_f32_16x16x32_bf16 v[92:95], v[164:167], v[216:219], 0
	v_mfma_f32_16x16x32_bf16 v[88:91], v[172:175], v[216:219], 0
	v_mfma_f32_16x16x32_bf16 v[76:79], v[164:167], v[224:227], 0
	v_mfma_f32_16x16x32_bf16 v[72:75], v[172:175], v[224:227], 0
	v_mfma_f32_16x16x32_bf16 v[124:127], v[168:171], v[200:203], v[124:127]
	v_mfma_f32_16x16x32_bf16 v[120:123], v[176:179], v[200:203], v[120:123]
	v_mfma_f32_16x16x32_bf16 v[108:111], v[168:171], v[212:215], v[108:111]
	v_mfma_f32_16x16x32_bf16 v[104:107], v[176:179], v[212:215], v[104:107]
	v_mfma_f32_16x16x32_bf16 v[92:95], v[168:171], v[220:223], v[92:95]
	v_mfma_f32_16x16x32_bf16 v[88:91], v[176:179], v[220:223], v[88:91]
	v_mfma_f32_16x16x32_bf16 v[76:79], v[168:171], v[228:231], v[76:79]
	v_mfma_f32_16x16x32_bf16 v[72:75], v[176:179], v[228:231], v[72:75]
	v_mfma_f32_16x16x32_bf16 v[116:119], v[180:183], v[196:199], 0
	v_mfma_f32_16x16x32_bf16 v[112:115], v[188:191], v[196:199], 0
	v_mfma_f32_16x16x32_bf16 v[100:103], v[180:183], v[208:211], 0
	v_mfma_f32_16x16x32_bf16 v[96:99], v[188:191], v[208:211], 0
	v_mfma_f32_16x16x32_bf16 v[84:87], v[180:183], v[216:219], 0
	v_mfma_f32_16x16x32_bf16 v[80:83], v[188:191], v[216:219], 0
	v_mfma_f32_16x16x32_bf16 v[68:71], v[180:183], v[224:227], 0
	v_mfma_f32_16x16x32_bf16 v[64:67], v[188:191], v[224:227], 0
	v_mfma_f32_16x16x32_bf16 v[116:119], v[184:187], v[200:203], v[116:119]
	v_mfma_f32_16x16x32_bf16 v[112:115], v[192:195], v[200:203], v[112:115]
	v_mfma_f32_16x16x32_bf16 v[100:103], v[184:187], v[212:215], v[100:103]
	v_mfma_f32_16x16x32_bf16 v[96:99], v[192:195], v[212:215], v[96:99]
	v_mfma_f32_16x16x32_bf16 v[84:87], v[184:187], v[220:223], v[84:87]
	v_mfma_f32_16x16x32_bf16 v[80:83], v[192:195], v[220:223], v[80:83]
	v_mfma_f32_16x16x32_bf16 v[68:71], v[184:187], v[228:231], v[68:71]
	v_mfma_f32_16x16x32_bf16 v[64:67], v[192:195], v[228:231], v[64:67]
	s_setprio 0
	s_barrier
	s_add_i32 s68, s57, s40
	v_lshl_add_u64 v[142:143], s[34:35], 0, v[130:131]
	s_mov_b32 m0, s68
	ds_read_b128 v[196:199], v162 offset:16384
	ds_read_b128 v[200:203], v162 offset:17408
	ds_read_b128 v[208:211], v162 offset:18432
	ds_read_b128 v[212:215], v162 offset:19456
	ds_read_b128 v[216:219], v162 offset:20480
	ds_read_b128 v[220:223], v162 offset:21504
	ds_read_b128 v[224:227], v162 offset:22528
	ds_read_b128 v[228:231], v162 offset:23552
	global_load_lds_dwordx4 v[142:143], off
	s_add_i32 m0, s68, 0x2000
	s_add_u32 s68, s34, 0x40000
	v_lshl_add_u64 v[204:205], s[34:35], 0, v[134:135]
	s_addc_u32 s69, s35, 0
	s_add_i32 s70, s58, s40
	global_load_lds_dwordx4 v[204:205], off
	v_lshl_add_u64 v[232:233], s[68:69], 0, v[130:131]
	s_mov_b32 m0, s70
	v_lshl_add_u64 v[234:235], s[36:37], 0, v[132:133]
	global_load_lds_dwordx4 v[232:233], off
	v_lshl_add_u64 v[232:233], s[68:69], 0, v[134:135]
	s_add_i32 m0, s70, 0x2000
	s_nop 0
	global_load_lds_dwordx4 v[232:233], off
	v_lshl_add_u64 v[232:233], s[36:37], 0, v[128:129]
	s_mov_b32 m0, s29
	s_nop 0
	global_load_lds_dwordx4 v[232:233], off
	s_mov_b32 m0, s43
	s_nop 0
	global_load_lds_dwordx4 v[234:235], off
	s_waitcnt vmcnt(8)
	s_waitcnt lgkmcnt(0)
	s_barrier
; #define PG8_STAGE(bufoff, gbase, voff) do { _Pragma("unroll") for (int _i = 0; _i < 2; ++_i) \
;         __builtin_amdgcn_global_load_lds((const unsigned*)((const char*)(gbase) + (voff)[_i]), (PG8_LAS unsigned*)(lds + (bufoff) + ldsw + _i * 8192), 16, 0, 0); } while (0)
; #define PG8_LDA(dst, b, h) do { _Pragma("unroll") for (int m = 0; m < 4; ++m) _Pragma("unroll") for (int k = 0; k < 2; ++k) dst[m][k] = *(const PG8_LAS bf16x8*)(lds + PG8_SA(b, h) + aoff + m * 2048 + k * 1024); } while (0)
; #define PG8_LDB(dst, b, h) do { _Pragma("unroll") for (int n = 0; n < 2; ++n) _Pragma("unroll") for (int k = 0; k < 2; ++k) dst[n][k] = *(const PG8_LAS bf16x8*)(lds + PG8_SB(b, h) + boff + n * 2048 + k * 1024); } while (0)
; #define PG8_MMA(ai, bj, At, Bt) do { __builtin_amdgcn_s_setprio(1); _Pragma("unroll") for (int m = 0; m < 4; ++m) _Pragma("unroll") for (int n = 0; n < 2; ++n) _Pragma("unroll") for (int k = 0; k < 2; ++k) \
;         acc[ai][bj][m][n] = __builtin_amdgcn_mfma_f32_16x16x32_bf16(Bt[n][k], At[m][k], acc[ai][bj][m][n], 0, 0, 0); __builtin_amdgcn_s_setprio(0); } while (0)
; #define PG8_WAIT_V(n) asm volatile("s_waitcnt vmcnt(" #n ")" ::: "memory")
; #define PG8_WAIT_L(n) asm volatile("s_waitcnt lgkmcnt(" #n ")" ::: "memory")
; #define PG8_BAR __builtin_amdgcn_s_barrier()
; #define PG8_SCHED __builtin_amdgcn_sched_barrier(0)
; template <class Epi, class Sched, bool ALIGN_EPI = false, bool SP2 = false>
; __device__ __forceinline__ void gemm_phase(PG8_LAS unsigned char* lds, const Gemm g, const Sched& S, const Epi& E) {
;     ...
;             PG8_WAIT_V(8); PG8_WAIT_L(0); PG8_BAR; PG8_MMA(1, 0, At, B0); PG8_MMA(1, 1, At, B1); PG8_BAR; PG8_SCHED;
;             PG8_LDB(B0, 1, 0); PG8_LDB(B1, 1, 1); PG8_SCHED; PG8_LDA(At, 1, 0); PG8_STAGE(PG8_SA(0, 1), a2 + hstep, voffA);
;             PG8_WAIT_V(8); PG8_WAIT_L(0); PG8_BAR; PG8_MMA(0, 0, At, B0); PG8_MMA(0, 1, At, B1); PG8_BAR; PG8_SCHED;
	s_setprio 1
	s_waitcnt lgkmcnt(0)
	v_mfma_f32_16x16x32_bf16 v[60:63], v[164:167], v[196:199], 0
	v_mfma_f32_16x16x32_bf16 v[56:59], v[172:175], v[196:199], 0
	v_mfma_f32_16x16x32_bf16 v[44:47], v[164:167], v[208:211], 0
	v_mfma_f32_16x16x32_bf16 v[40:43], v[172:175], v[208:211], 0
	v_mfma_f32_16x16x32_bf16 v[28:31], v[164:167], v[216:219], 0
	v_mfma_f32_16x16x32_bf16 v[24:27], v[172:175], v[216:219], 0
	v_mfma_f32_16x16x32_bf16 v[12:15], v[164:167], v[224:227], 0
	v_mfma_f32_16x16x32_bf16 v[8:11], v[172:175], v[224:227], 0
	v_mfma_f32_16x16x32_bf16 v[60:63], v[168:171], v[200:203], v[60:63]
	v_mfma_f32_16x16x32_bf16 v[56:59], v[176:179], v[200:203], v[56:59]
	v_mfma_f32_16x16x32_bf16 v[44:47], v[168:171], v[212:215], v[44:47]
	v_mfma_f32_16x16x32_bf16 v[40:43], v[176:179], v[212:215], v[40:43]
	v_mfma_f32_16x16x32_bf16 v[28:31], v[168:171], v[220:223], v[28:31]
	v_mfma_f32_16x16x32_bf16 v[24:27], v[176:179], v[220:223], v[24:27]
	v_mfma_f32_16x16x32_bf16 v[12:15], v[168:171], v[228:231], v[12:15]
	v_mfma_f32_16x16x32_bf16 v[8:11], v[176:179], v[228:231], v[8:11]
	v_mfma_f32_16x16x32_bf16 v[52:55], v[180:183], v[196:199], 0
	v_mfma_f32_16x16x32_bf16 v[48:51], v[188:191], v[196:199], 0
	v_mfma_f32_16x16x32_bf16 v[36:39], v[180:183], v[208:211], 0
	v_mfma_f32_16x16x32_bf16 v[32:35], v[188:191], v[208:211], 0
	v_mfma_f32_16x16x32_bf16 v[20:23], v[180:183], v[216:219], 0
	v_mfma_f32_16x16x32_bf16 v[16:19], v[188:191], v[216:219], 0
	v_mfma_f32_16x16x32_bf16 v[4:7], v[180:183], v[224:227], 0
	v_mfma_f32_16x16x32_bf16 v[0:3], v[188:191], v[224:227], 0
	v_mfma_f32_16x16x32_bf16 v[52:55], v[184:187], v[200:203], v[52:55]
	v_mfma_f32_16x16x32_bf16 v[48:51], v[192:195], v[200:203], v[48:51]
	v_mfma_f32_16x16x32_bf16 v[36:39], v[184:187], v[212:215], v[36:39]
	v_mfma_f32_16x16x32_bf16 v[32:35], v[192:195], v[212:215], v[32:35]
	v_mfma_f32_16x16x32_bf16 v[20:23], v[184:187], v[220:223], v[20:23]
	v_mfma_f32_16x16x32_bf16 v[16:19], v[192:195], v[220:223], v[16:19]
	v_mfma_f32_16x16x32_bf16 v[4:7], v[184:187], v[228:231], v[4:7]
	v_mfma_f32_16x16x32_bf16 v[0:3], v[192:195], v[228:231], v[0:3]
	s_setprio 0
	s_barrier
	s_add_i32 s68, 0, 0x18000
	v_add_u32_e32 v163, s68, v158
	s_add_i32 s69, 0, 0x1c000
	ds_read_b128 v[164:167], v163
	ds_read_b128 v[168:171], v163 offset:1024
	ds_read_b128 v[172:175], v163 offset:2048
	ds_read_b128 v[176:179], v163 offset:3072
	v_add_u32_e32 v163, s69, v158
	ds_read_b128 v[180:183], v163
	ds_read_b128 v[184:187], v163 offset:1024
	ds_read_b128 v[188:191], v163 offset:2048
	ds_read_b128 v[192:195], v163 offset:3072
	s_add_u32 s36, s36, 0x40000
	s_addc_u32 s37, s37, 0
	s_mov_b32 m0, s44
	v_lshl_add_u64 v[236:237], s[36:37], 0, v[128:129]
	ds_read_b128 v[196:199], v162 offset:32768
	ds_read_b128 v[200:203], v162 offset:33792
	ds_read_b128 v[208:211], v162 offset:34816
	ds_read_b128 v[212:215], v162 offset:35840
	ds_read_b128 v[216:219], v162 offset:36864
	ds_read_b128 v[220:223], v162 offset:37888
	ds_read_b128 v[224:227], v162 offset:38912
	ds_read_b128 v[228:231], v162 offset:39936
	global_load_lds_dwordx4 v[236:237], off
	v_lshl_add_u64 v[236:237], s[36:37], 0, v[132:133]
	s_mov_b32 m0, s45
	s_nop 0
	global_load_lds_dwordx4 v[236:237], off
	s_waitcnt vmcnt(8)
	s_waitcnt lgkmcnt(0)
	s_barrier
	s_setprio 1
	s_waitcnt lgkmcnt(0)
	v_mfma_f32_16x16x32_bf16 v[124:127], v[164:167], v[196:199], v[124:127]
	v_mfma_f32_16x16x32_bf16 v[120:123], v[172:175], v[196:199], v[120:123]
	v_mfma_f32_16x16x32_bf16 v[108:111], v[164:167], v[208:211], v[108:111]
	v_mfma_f32_16x16x32_bf16 v[104:107], v[172:175], v[208:211], v[104:107]
	v_mfma_f32_16x16x32_bf16 v[92:95], v[164:167], v[216:219], v[92:95]
	v_mfma_f32_16x16x32_bf16 v[88:91], v[172:175], v[216:219], v[88:91]
	v_mfma_f32_16x16x32_bf16 v[76:79], v[164:167], v[224:227], v[76:79]
	v_mfma_f32_16x16x32_bf16 v[72:75], v[172:175], v[224:227], v[72:75]
	v_mfma_f32_16x16x32_bf16 v[124:127], v[168:171], v[200:203], v[124:127]
	v_mfma_f32_16x16x32_bf16 v[120:123], v[176:179], v[200:203], v[120:123]
	v_mfma_f32_16x16x32_bf16 v[108:111], v[168:171], v[212:215], v[108:111]
	v_mfma_f32_16x16x32_bf16 v[104:107], v[176:179], v[212:215], v[104:107]
	v_mfma_f32_16x16x32_bf16 v[92:95], v[168:171], v[220:223], v[92:95]
	v_mfma_f32_16x16x32_bf16 v[88:91], v[176:179], v[220:223], v[88:91]
	v_mfma_f32_16x16x32_bf16 v[76:79], v[168:171], v[228:231], v[76:79]
	v_mfma_f32_16x16x32_bf16 v[72:75], v[176:179], v[228:231], v[72:75]
	v_mfma_f32_16x16x32_bf16 v[116:119], v[180:183], v[196:199], v[116:119]
	v_mfma_f32_16x16x32_bf16 v[112:115], v[188:191], v[196:199], v[112:115]
	v_mfma_f32_16x16x32_bf16 v[100:103], v[180:183], v[208:211], v[100:103]
	v_mfma_f32_16x16x32_bf16 v[96:99], v[188:191], v[208:211], v[96:99]
	v_mfma_f32_16x16x32_bf16 v[84:87], v[180:183], v[216:219], v[84:87]
	v_mfma_f32_16x16x32_bf16 v[80:83], v[188:191], v[216:219], v[80:83]
	v_mfma_f32_16x16x32_bf16 v[68:71], v[180:183], v[224:227], v[68:71]
	v_mfma_f32_16x16x32_bf16 v[64:67], v[188:191], v[224:227], v[64:67]
	v_mfma_f32_16x16x32_bf16 v[116:119], v[184:187], v[200:203], v[116:119]
	v_mfma_f32_16x16x32_bf16 v[112:115], v[192:195], v[200:203], v[112:115]
	v_mfma_f32_16x16x32_bf16 v[100:103], v[184:187], v[212:215], v[100:103]
	v_mfma_f32_16x16x32_bf16 v[96:99], v[192:195], v[212:215], v[96:99]
	v_mfma_f32_16x16x32_bf16 v[84:87], v[184:187], v[220:223], v[84:87]
	v_mfma_f32_16x16x32_bf16 v[80:83], v[192:195], v[220:223], v[80:83]
	v_mfma_f32_16x16x32_bf16 v[68:71], v[184:187], v[228:231], v[68:71]
	v_mfma_f32_16x16x32_bf16 v[64:67], v[192:195], v[228:231], v[64:67]
	s_setprio 0
	s_barrier
; #define PG8_STAGE(bufoff, gbase, voff) do { _Pragma("unroll") for (int _i = 0; _i < 2; ++_i) \
;         __builtin_amdgcn_global_load_lds((const unsigned*)((const char*)(gbase) + (voff)[_i]), (PG8_LAS unsigned*)(lds + (bufoff) + ldsw + _i * 8192), 16, 0, 0); } while (0)
; #define PG8_LDA(dst, b, h) do { _Pragma("unroll") for (int m = 0; m < 4; ++m) _Pragma("unroll") for (int k = 0; k < 2; ++k) dst[m][k] = *(const PG8_LAS bf16x8*)(lds + PG8_SA(b, h) + aoff + m * 2048 + k * 1024); } while (0)
; #define PG8_LDB(dst, b, h) do { _Pragma("unroll") for (int n = 0; n < 2; ++n) _Pragma("unroll") for (int k = 0; k < 2; ++k) dst[n][k] = *(const PG8_LAS bf16x8*)(lds + PG8_SB(b, h) + boff + n * 2048 + k * 1024); } while (0)
; #define PG8_MMA(ai, bj, At, Bt) do { __builtin_amdgcn_s_setprio(1); _Pragma("unroll") for (int m = 0; m < 4; ++m) _Pragma("unroll") for (int n = 0; n < 2; ++n) _Pragma("unroll") for (int k = 0; k < 2; ++k) \
;         acc[ai][bj][m][n] = __builtin_amdgcn_mfma_f32_16x16x32_bf16(Bt[n][k], At[m][k], acc[ai][bj][m][n], 0, 0, 0); __builtin_amdgcn_s_setprio(0); } while (0)
; #define PG8_WAIT_V(n) asm volatile("s_waitcnt vmcnt(" #n ")" ::: "memory")
; #define PG8_WAIT_L(n) asm volatile("s_waitcnt lgkmcnt(" #n ")" ::: "memory")
; #define PG8_BAR __builtin_amdgcn_s_barrier()
; #define PG8_SCHED __builtin_amdgcn_sched_barrier(0)
; template <class Epi, class Sched, bool ALIGN_EPI = false, bool SP2 = false>
; __device__ __forceinline__ void gemm_phase(PG8_LAS unsigned char* lds, const Gemm g, const Sched& S, const Epi& E) {
;     ...
;             PG8_LDB(B0, 0, 0); PG8_LDB(B1, 0, 1); PG8_SCHED; PG8_LDA(At, 0, 0); PG8_STAGE(PG8_SA(1, 1), a1 + hstep, voffA);
;     ...
;             PG8_LDA(At, 1, 1); PG8_STAGE(PG8_SB(1, 0), b3, voffB); PG8_STAGE(PG8_SB(1, 1), b3 + hstep, voffB); PG8_STAGE(PG8_SA(1, 0), a3, voffA);
;             PG8_WAIT_V(8); PG8_WAIT_L(0); PG8_BAR; PG8_MMA(1, 0, At, B0); PG8_MMA(1, 1, At, B1); PG8_BAR; PG8_SCHED;
	s_add_i32 s36, s68, s40
	v_lshl_add_u64 v[142:143], v[142:143], 0, s[8:9]
	s_mov_b32 m0, s36
	ds_read_b128 v[196:199], v162 offset:49152
	ds_read_b128 v[200:203], v162 offset:50176
	ds_read_b128 v[208:211], v162 offset:51200
	ds_read_b128 v[212:215], v162 offset:52224
	ds_read_b128 v[216:219], v162 offset:53248
	ds_read_b128 v[220:223], v162 offset:54272
	ds_read_b128 v[224:227], v162 offset:55296
	ds_read_b128 v[228:231], v162 offset:56320
	global_load_lds_dwordx4 v[142:143], off
	s_add_i32 m0, s36, 0x2000
	s_add_u32 s34, s34, 0x40080
	v_lshl_add_u64 v[142:143], v[204:205], 0, s[8:9]
	s_addc_u32 s35, s35, 0
	s_add_i32 s36, s69, s40
	global_load_lds_dwordx4 v[142:143], off
	v_lshl_add_u64 v[142:143], s[34:35], 0, v[130:131]
	s_mov_b32 m0, s36
	s_nop 0
	global_load_lds_dwordx4 v[142:143], off
	v_lshl_add_u64 v[142:143], s[34:35], 0, v[134:135]
	s_add_i32 m0, s36, 0x2000
	s_nop 0
	global_load_lds_dwordx4 v[142:143], off
	v_lshl_add_u64 v[142:143], v[232:233], 0, s[8:9]
	s_mov_b32 m0, s52
	s_nop 0
	global_load_lds_dwordx4 v[142:143], off
	v_lshl_add_u64 v[142:143], v[234:235], 0, s[8:9]
	s_mov_b32 m0, s53
	s_nop 0
	global_load_lds_dwordx4 v[142:143], off
	s_waitcnt vmcnt(8)
	s_waitcnt lgkmcnt(0)
	s_barrier
	s_setprio 1
	s_waitcnt lgkmcnt(0)
	v_mfma_f32_16x16x32_bf16 v[60:63], v[164:167], v[196:199], v[60:63]
	v_mfma_f32_16x16x32_bf16 v[56:59], v[172:175], v[196:199], v[56:59]
	v_mfma_f32_16x16x32_bf16 v[44:47], v[164:167], v[208:211], v[44:47]
	v_mfma_f32_16x16x32_bf16 v[40:43], v[172:175], v[208:211], v[40:43]
	v_mfma_f32_16x16x32_bf16 v[28:31], v[164:167], v[216:219], v[28:31]
	v_mfma_f32_16x16x32_bf16 v[24:27], v[172:175], v[216:219], v[24:27]
	v_mfma_f32_16x16x32_bf16 v[12:15], v[164:167], v[224:227], v[12:15]
	v_mfma_f32_16x16x32_bf16 v[8:11], v[172:175], v[224:227], v[8:11]
	v_mfma_f32_16x16x32_bf16 v[60:63], v[168:171], v[200:203], v[60:63]
	v_mfma_f32_16x16x32_bf16 v[56:59], v[176:179], v[200:203], v[56:59]
	v_mfma_f32_16x16x32_bf16 v[44:47], v[168:171], v[212:215], v[44:47]
	v_mfma_f32_16x16x32_bf16 v[40:43], v[176:179], v[212:215], v[40:43]
	v_mfma_f32_16x16x32_bf16 v[28:31], v[168:171], v[220:223], v[28:31]
	v_mfma_f32_16x16x32_bf16 v[24:27], v[176:179], v[220:223], v[24:27]
	v_mfma_f32_16x16x32_bf16 v[12:15], v[168:171], v[228:231], v[12:15]
	v_mfma_f32_16x16x32_bf16 v[8:11], v[176:179], v[228:231], v[8:11]
	v_mfma_f32_16x16x32_bf16 v[52:55], v[180:183], v[196:199], v[52:55]
	v_mfma_f32_16x16x32_bf16 v[48:51], v[188:191], v[196:199], v[48:51]
	v_mfma_f32_16x16x32_bf16 v[36:39], v[180:183], v[208:211], v[36:39]
	v_mfma_f32_16x16x32_bf16 v[32:35], v[188:191], v[208:211], v[32:35]
	v_mfma_f32_16x16x32_bf16 v[20:23], v[180:183], v[216:219], v[20:23]
	v_mfma_f32_16x16x32_bf16 v[16:19], v[188:191], v[216:219], v[16:19]
	v_mfma_f32_16x16x32_bf16 v[4:7], v[180:183], v[224:227], v[4:7]
	v_mfma_f32_16x16x32_bf16 v[0:3], v[188:191], v[224:227], v[0:3]
	v_mfma_f32_16x16x32_bf16 v[52:55], v[184:187], v[200:203], v[52:55]
	v_mfma_f32_16x16x32_bf16 v[48:51], v[192:195], v[200:203], v[48:51]
	v_mfma_f32_16x16x32_bf16 v[36:39], v[184:187], v[212:215], v[36:39]
	v_mfma_f32_16x16x32_bf16 v[32:35], v[192:195], v[212:215], v[32:35]
	v_mfma_f32_16x16x32_bf16 v[20:23], v[184:187], v[220:223], v[20:23]
	v_mfma_f32_16x16x32_bf16 v[16:19], v[192:195], v[220:223], v[16:19]
	v_mfma_f32_16x16x32_bf16 v[4:7], v[184:187], v[228:231], v[4:7]
	v_mfma_f32_16x16x32_bf16 v[0:3], v[192:195], v[228:231], v[0:3]
	s_setprio 0
	s_barrier
	s_add_i32 s67, s67, 2
	s_add_u32 s30, s30, 0x100
	s_addc_u32 s31, s31, 0
	s_add_u32 s65, s65, 0x100
	s_addc_u32 s66, s66, 0
	s_cmp_gt_u32 s67, 13
	s_cbranch_scc0 .LBB0_1788
	s_branch .Lpeel_exit_12
.LBB0_1788:
	ds_read_b128 v[164:167], v160
	ds_read_b128 v[168:171], v160 offset:1024
	ds_read_b128 v[172:175], v160 offset:2048
	ds_read_b128 v[176:179], v160 offset:3072
	ds_read_b128 v[180:183], v161
	ds_read_b128 v[184:187], v161 offset:1024
	ds_read_b128 v[188:191], v161 offset:2048
	ds_read_b128 v[192:195], v161 offset:3072
	s_add_u32 s34, s30, 0xfffc0080
	s_addc_u32 s35, s31, -1
	s_cmp_eq_u32 s67, 12
	s_cselect_b32 s37, s21, s35
	s_cselect_b32 s36, s61, s34
	s_cselect_b32 s35, s19, s66
	s_cselect_b32 s34, s64, s65
	v_lshl_add_u64 v[142:143], s[30:31], 0, v[136:137]
	s_add_i32 m0, s29, 0xc000
	ds_read_b128 v[196:199], v162
	ds_read_b128 v[200:203], v162 offset:1024
	ds_read_b128 v[208:211], v162 offset:2048
	ds_read_b128 v[212:215], v162 offset:3072
	ds_read_b128 v[216:219], v162 offset:4096
	ds_read_b128 v[220:223], v162 offset:5120
	ds_read_b128 v[224:227], v162 offset:6144
	ds_read_b128 v[228:231], v162 offset:7168
	global_load_lds_dwordx4 v[142:143], off
	v_lshl_add_u64 v[142:143], s[30:31], 0, v[138:139]
	s_add_i32 m0, s29, 0xe000
	s_nop 0
	global_load_lds_dwordx4 v[142:143], off
	s_waitcnt vmcnt(8)
	s_waitcnt lgkmcnt(0)
	s_barrier
; #define PG8_STAGE(bufoff, gbase, voff) do { _Pragma("unroll") for (int _i = 0; _i < 2; ++_i) \
;         __builtin_amdgcn_global_load_lds((const unsigned*)((const char*)(gbase) + (voff)[_i]), (PG8_LAS unsigned*)(lds + (bufoff) + ldsw + _i * 8192), 16, 0, 0); } while (0)
; #define PG8_LDA(dst, b, h) do { _Pragma("unroll") for (int m = 0; m < 4; ++m) _Pragma("unroll") for (int k = 0; k < 2; ++k) dst[m][k] = *(const PG8_LAS bf16x8*)(lds + PG8_SA(b, h) + aoff + m * 2048 + k * 1024); } while (0)
; #define PG8_MMA(ai, bj, At, Bt) do { __builtin_amdgcn_s_setprio(1); _Pragma("unroll") for (int m = 0; m < 4; ++m) _Pragma("unroll") for (int n = 0; n < 2; ++n) _Pragma("unroll") for (int k = 0; k < 2; ++k) \
;         acc[ai][bj][m][n] = __builtin_amdgcn_mfma_f32_16x16x32_bf16(Bt[n][k], At[m][k], acc[ai][bj][m][n], 0, 0, 0); __builtin_amdgcn_s_setprio(0); } while (0)
; #define PG8_WAIT_V(n) asm volatile("s_waitcnt vmcnt(" #n ")" ::: "memory")
; #define PG8_WAIT_L(n) asm volatile("s_waitcnt lgkmcnt(" #n ")" ::: "memory")
; #define PG8_BAR __builtin_amdgcn_s_barrier()
; #define PG8_SCHED __builtin_amdgcn_sched_barrier(0)
; template <class Epi, class Sched, bool ALIGN_EPI = false, bool SP2 = false>
; __device__ __forceinline__ void gemm_phase(PG8_LAS unsigned char* lds, const Gemm g, const Sched& S, const Epi& E) {
;     ...
;             PG8_WAIT_V(8); PG8_WAIT_L(0); PG8_BAR; PG8_MMA(0, 0, At, B0); PG8_MMA(0, 1, At, B1); PG8_BAR; PG8_SCHED;
;             PG8_LDA(At, 0, 1); PG8_STAGE(PG8_SB(0, 0), b2, voffB); PG8_STAGE(PG8_SB(0, 1), b2 + hstep, voffB); PG8_STAGE(PG8_SA(0, 0), a2, voffA);
;             PG8_WAIT_V(8); PG8_WAIT_L(0); PG8_BAR; PG8_MMA(1, 0, At, B0); PG8_MMA(1, 1, At, B1); PG8_BAR; PG8_SCHED;
	s_setprio 1
	s_waitcnt lgkmcnt(0)
	v_mfma_f32_16x16x32_bf16 v[124:127], v[164:167], v[196:199], v[124:127]
	v_mfma_f32_16x16x32_bf16 v[120:123], v[172:175], v[196:199], v[120:123]
	v_mfma_f32_16x16x32_bf16 v[108:111], v[164:167], v[208:211], v[108:111]
	v_mfma_f32_16x16x32_bf16 v[104:107], v[172:175], v[208:211], v[104:107]
	v_mfma_f32_16x16x32_bf16 v[92:95], v[164:167], v[216:219], v[92:95]
	v_mfma_f32_16x16x32_bf16 v[88:91], v[172:175], v[216:219], v[88:91]
	v_mfma_f32_16x16x32_bf16 v[76:79], v[164:167], v[224:227], v[76:79]
	v_mfma_f32_16x16x32_bf16 v[72:75], v[172:175], v[224:227], v[72:75]
	v_mfma_f32_16x16x32_bf16 v[124:127], v[168:171], v[200:203], v[124:127]
	v_mfma_f32_16x16x32_bf16 v[120:123], v[176:179], v[200:203], v[120:123]
	v_mfma_f32_16x16x32_bf16 v[108:111], v[168:171], v[212:215], v[108:111]
	v_mfma_f32_16x16x32_bf16 v[104:107], v[176:179], v[212:215], v[104:107]
	v_mfma_f32_16x16x32_bf16 v[92:95], v[168:171], v[220:223], v[92:95]
	v_mfma_f32_16x16x32_bf16 v[88:91], v[176:179], v[220:223], v[88:91]
	v_mfma_f32_16x16x32_bf16 v[76:79], v[168:171], v[228:231], v[76:79]
	v_mfma_f32_16x16x32_bf16 v[72:75], v[176:179], v[228:231], v[72:75]
	v_mfma_f32_16x16x32_bf16 v[116:119], v[180:183], v[196:199], v[116:119]
	v_mfma_f32_16x16x32_bf16 v[112:115], v[188:191], v[196:199], v[112:115]
	v_mfma_f32_16x16x32_bf16 v[100:103], v[180:183], v[208:211], v[100:103]
	v_mfma_f32_16x16x32_bf16 v[96:99], v[188:191], v[208:211], v[96:99]
	v_mfma_f32_16x16x32_bf16 v[84:87], v[180:183], v[216:219], v[84:87]
	v_mfma_f32_16x16x32_bf16 v[80:83], v[188:191], v[216:219], v[80:83]
	v_mfma_f32_16x16x32_bf16 v[68:71], v[180:183], v[224:227], v[68:71]
	v_mfma_f32_16x16x32_bf16 v[64:67], v[188:191], v[224:227], v[64:67]
	v_mfma_f32_16x16x32_bf16 v[116:119], v[184:187], v[200:203], v[116:119]
	v_mfma_f32_16x16x32_bf16 v[112:115], v[192:195], v[200:203], v[112:115]
	v_mfma_f32_16x16x32_bf16 v[100:103], v[184:187], v[212:215], v[100:103]
	v_mfma_f32_16x16x32_bf16 v[96:99], v[192:195], v[212:215], v[96:99]
	v_mfma_f32_16x16x32_bf16 v[84:87], v[184:187], v[220:223], v[84:87]
	v_mfma_f32_16x16x32_bf16 v[80:83], v[192:195], v[220:223], v[80:83]
	v_mfma_f32_16x16x32_bf16 v[68:71], v[184:187], v[228:231], v[68:71]
	v_mfma_f32_16x16x32_bf16 v[64:67], v[192:195], v[228:231], v[64:67]
	s_setprio 0
	s_barrier
	s_add_i32 s68, s57, s40
	v_lshl_add_u64 v[142:143], s[34:35], 0, v[130:131]
	s_mov_b32 m0, s68
	ds_read_b128 v[196:199], v162 offset:16384
	ds_read_b128 v[200:203], v162 offset:17408
	ds_read_b128 v[208:211], v162 offset:18432
	ds_read_b128 v[212:215], v162 offset:19456
	ds_read_b128 v[216:219], v162 offset:20480
	ds_read_b128 v[220:223], v162 offset:21504
	ds_read_b128 v[224:227], v162 offset:22528
	ds_read_b128 v[228:231], v162 offset:23552
	global_load_lds_dwordx4 v[142:143], off
	s_add_i32 m0, s68, 0x2000
	s_add_u32 s68, s34, 0x40000
	v_lshl_add_u64 v[204:205], s[34:35], 0, v[134:135]
	s_addc_u32 s69, s35, 0
	s_add_i32 s70, s58, s40
	global_load_lds_dwordx4 v[204:205], off
	v_lshl_add_u64 v[232:233], s[68:69], 0, v[130:131]
	s_mov_b32 m0, s70
	v_lshl_add_u64 v[234:235], s[36:37], 0, v[132:133]
	global_load_lds_dwordx4 v[232:233], off
	v_lshl_add_u64 v[232:233], s[68:69], 0, v[134:135]
	s_add_i32 m0, s70, 0x2000
	s_nop 0
	global_load_lds_dwordx4 v[232:233], off
	v_lshl_add_u64 v[232:233], s[36:37], 0, v[128:129]
	s_mov_b32 m0, s29
	s_nop 0
	global_load_lds_dwordx4 v[232:233], off
	s_mov_b32 m0, s43
	s_nop 0
	global_load_lds_dwordx4 v[234:235], off
	s_waitcnt vmcnt(8)
	s_waitcnt lgkmcnt(0)
	s_barrier
	s_setprio 1
	s_waitcnt lgkmcnt(0)
	v_mfma_f32_16x16x32_bf16 v[60:63], v[164:167], v[196:199], v[60:63]
	v_mfma_f32_16x16x32_bf16 v[56:59], v[172:175], v[196:199], v[56:59]
	v_mfma_f32_16x16x32_bf16 v[44:47], v[164:167], v[208:211], v[44:47]
	v_mfma_f32_16x16x32_bf16 v[40:43], v[172:175], v[208:211], v[40:43]
	v_mfma_f32_16x16x32_bf16 v[28:31], v[164:167], v[216:219], v[28:31]
	v_mfma_f32_16x16x32_bf16 v[24:27], v[172:175], v[216:219], v[24:27]
	v_mfma_f32_16x16x32_bf16 v[12:15], v[164:167], v[224:227], v[12:15]
	v_mfma_f32_16x16x32_bf16 v[8:11], v[172:175], v[224:227], v[8:11]
	v_mfma_f32_16x16x32_bf16 v[60:63], v[168:171], v[200:203], v[60:63]
	v_mfma_f32_16x16x32_bf16 v[56:59], v[176:179], v[200:203], v[56:59]
	v_mfma_f32_16x16x32_bf16 v[44:47], v[168:171], v[212:215], v[44:47]
	v_mfma_f32_16x16x32_bf16 v[40:43], v[176:179], v[212:215], v[40:43]
	v_mfma_f32_16x16x32_bf16 v[28:31], v[168:171], v[220:223], v[28:31]
	v_mfma_f32_16x16x32_bf16 v[24:27], v[176:179], v[220:223], v[24:27]
	v_mfma_f32_16x16x32_bf16 v[12:15], v[168:171], v[228:231], v[12:15]
	v_mfma_f32_16x16x32_bf16 v[8:11], v[176:179], v[228:231], v[8:11]
	v_mfma_f32_16x16x32_bf16 v[52:55], v[180:183], v[196:199], v[52:55]
	v_mfma_f32_16x16x32_bf16 v[48:51], v[188:191], v[196:199], v[48:51]
	v_mfma_f32_16x16x32_bf16 v[36:39], v[180:183], v[208:211], v[36:39]
	v_mfma_f32_16x16x32_bf16 v[32:35], v[188:191], v[208:211], v[32:35]
	v_mfma_f32_16x16x32_bf16 v[20:23], v[180:183], v[216:219], v[20:23]
	v_mfma_f32_16x16x32_bf16 v[16:19], v[188:191], v[216:219], v[16:19]
	v_mfma_f32_16x16x32_bf16 v[4:7], v[180:183], v[224:227], v[4:7]
	v_mfma_f32_16x16x32_bf16 v[0:3], v[188:191], v[224:227], v[0:3]
	v_mfma_f32_16x16x32_bf16 v[52:55], v[184:187], v[200:203], v[52:55]
	v_mfma_f32_16x16x32_bf16 v[48:51], v[192:195], v[200:203], v[48:51]
	v_mfma_f32_16x16x32_bf16 v[36:39], v[184:187], v[212:215], v[36:39]
	v_mfma_f32_16x16x32_bf16 v[32:35], v[192:195], v[212:215], v[32:35]
	v_mfma_f32_16x16x32_bf16 v[20:23], v[184:187], v[220:223], v[20:23]
	v_mfma_f32_16x16x32_bf16 v[16:19], v[192:195], v[220:223], v[16:19]
	v_mfma_f32_16x16x32_bf16 v[4:7], v[184:187], v[228:231], v[4:7]
	v_mfma_f32_16x16x32_bf16 v[0:3], v[192:195], v[228:231], v[0:3]
	s_setprio 0
	s_barrier
; #define PG8_STAGE(bufoff, gbase, voff) do { _Pragma("unroll") for (int _i = 0; _i < 2; ++_i) \
;         __builtin_amdgcn_global_load_lds((const unsigned*)((const char*)(gbase) + (voff)[_i]), (PG8_LAS unsigned*)(lds + (bufoff) + ldsw + _i * 8192), 16, 0, 0); } while (0)
; #define PG8_LDA(dst, b, h) do { _Pragma("unroll") for (int m = 0; m < 4; ++m) _Pragma("unroll") for (int k = 0; k < 2; ++k) dst[m][k] = *(const PG8_LAS bf16x8*)(lds + PG8_SA(b, h) + aoff + m * 2048 + k * 1024); } while (0)
; #define PG8_LDB(dst, b, h) do { _Pragma("unroll") for (int n = 0; n < 2; ++n) _Pragma("unroll") for (int k = 0; k < 2; ++k) dst[n][k] = *(const PG8_LAS bf16x8*)(lds + PG8_SB(b, h) + boff + n * 2048 + k * 1024); } while (0)
; #define PG8_MMA(ai, bj, At, Bt) do { __builtin_amdgcn_s_setprio(1); _Pragma("unroll") for (int m = 0; m < 4; ++m) _Pragma("unroll") for (int n = 0; n < 2; ++n) _Pragma("unroll") for (int k = 0; k < 2; ++k) \
;         acc[ai][bj][m][n] = __builtin_amdgcn_mfma_f32_16x16x32_bf16(Bt[n][k], At[m][k], acc[ai][bj][m][n], 0, 0, 0); __builtin_amdgcn_s_setprio(0); } while (0)
; #define PG8_WAIT_V(n) asm volatile("s_waitcnt vmcnt(" #n ")" ::: "memory")
; #define PG8_WAIT_L(n) asm volatile("s_waitcnt lgkmcnt(" #n ")" ::: "memory")
; #define PG8_BAR __builtin_amdgcn_s_barrier()
; #define PG8_SCHED __builtin_amdgcn_sched_barrier(0)
; template <class Epi, class Sched, bool ALIGN_EPI = false, bool SP2 = false>
; __device__ __forceinline__ void gemm_phase(PG8_LAS unsigned char* lds, const Gemm g, const Sched& S, const Epi& E) {
;     ...
;             PG8_LDB(B0, 1, 0); PG8_LDB(B1, 1, 1); PG8_SCHED; PG8_LDA(At, 1, 0); PG8_STAGE(PG8_SA(0, 1), a2 + hstep, voffA);
;             PG8_WAIT_V(8); PG8_WAIT_L(0); PG8_BAR; PG8_MMA(0, 0, At, B0); PG8_MMA(0, 1, At, B1); PG8_BAR; PG8_SCHED;
	s_add_i32 s68, 0, 0x18000
	v_add_u32_e32 v163, s68, v158
	s_add_i32 s69, 0, 0x1c000
	ds_read_b128 v[164:167], v163
	ds_read_b128 v[168:171], v163 offset:1024
	ds_read_b128 v[172:175], v163 offset:2048
	ds_read_b128 v[176:179], v163 offset:3072
	v_add_u32_e32 v163, s69, v158
	ds_read_b128 v[180:183], v163
	ds_read_b128 v[184:187], v163 offset:1024
	ds_read_b128 v[188:191], v163 offset:2048
	ds_read_b128 v[192:195], v163 offset:3072
	s_add_u32 s36, s36, 0x40000
	s_addc_u32 s37, s37, 0
	s_mov_b32 m0, s44
	v_lshl_add_u64 v[236:237], s[36:37], 0, v[128:129]
	ds_read_b128 v[196:199], v162 offset:32768
	ds_read_b128 v[200:203], v162 offset:33792
	ds_read_b128 v[208:211], v162 offset:34816
	ds_read_b128 v[212:215], v162 offset:35840
	ds_read_b128 v[216:219], v162 offset:36864
	ds_read_b128 v[220:223], v162 offset:37888
	ds_read_b128 v[224:227], v162 offset:38912
	ds_read_b128 v[228:231], v162 offset:39936
	global_load_lds_dwordx4 v[236:237], off
	v_lshl_add_u64 v[236:237], s[36:37], 0, v[132:133]
	s_mov_b32 m0, s45
	s_nop 0
	global_load_lds_dwordx4 v[236:237], off
	s_waitcnt vmcnt(8)
	s_waitcnt lgkmcnt(0)
	s_barrier
	s_setprio 1
	s_waitcnt lgkmcnt(0)
	v_mfma_f32_16x16x32_bf16 v[124:127], v[164:167], v[196:199], v[124:127]
	v_mfma_f32_16x16x32_bf16 v[120:123], v[172:175], v[196:199], v[120:123]
	v_mfma_f32_16x16x32_bf16 v[108:111], v[164:167], v[208:211], v[108:111]
	v_mfma_f32_16x16x32_bf16 v[104:107], v[172:175], v[208:211], v[104:107]
	v_mfma_f32_16x16x32_bf16 v[92:95], v[164:167], v[216:219], v[92:95]
	v_mfma_f32_16x16x32_bf16 v[88:91], v[172:175], v[216:219], v[88:91]
	v_mfma_f32_16x16x32_bf16 v[76:79], v[164:167], v[224:227], v[76:79]
	v_mfma_f32_16x16x32_bf16 v[72:75], v[172:175], v[224:227], v[72:75]
	v_mfma_f32_16x16x32_bf16 v[124:127], v[168:171], v[200:203], v[124:127]
	v_mfma_f32_16x16x32_bf16 v[120:123], v[176:179], v[200:203], v[120:123]
	v_mfma_f32_16x16x32_bf16 v[108:111], v[168:171], v[212:215], v[108:111]
	v_mfma_f32_16x16x32_bf16 v[104:107], v[176:179], v[212:215], v[104:107]
	v_mfma_f32_16x16x32_bf16 v[92:95], v[168:171], v[220:223], v[92:95]
	v_mfma_f32_16x16x32_bf16 v[88:91], v[176:179], v[220:223], v[88:91]
	v_mfma_f32_16x16x32_bf16 v[76:79], v[168:171], v[228:231], v[76:79]
	v_mfma_f32_16x16x32_bf16 v[72:75], v[176:179], v[228:231], v[72:75]
	v_mfma_f32_16x16x32_bf16 v[116:119], v[180:183], v[196:199], v[116:119]
	v_mfma_f32_16x16x32_bf16 v[112:115], v[188:191], v[196:199], v[112:115]
	v_mfma_f32_16x16x32_bf16 v[100:103], v[180:183], v[208:211], v[100:103]
	v_mfma_f32_16x16x32_bf16 v[96:99], v[188:191], v[208:211], v[96:99]
	v_mfma_f32_16x16x32_bf16 v[84:87], v[180:183], v[216:219], v[84:87]
	v_mfma_f32_16x16x32_bf16 v[80:83], v[188:191], v[216:219], v[80:83]
	v_mfma_f32_16x16x32_bf16 v[68:71], v[180:183], v[224:227], v[68:71]
	v_mfma_f32_16x16x32_bf16 v[64:67], v[188:191], v[224:227], v[64:67]
	v_mfma_f32_16x16x32_bf16 v[116:119], v[184:187], v[200:203], v[116:119]
	v_mfma_f32_16x16x32_bf16 v[112:115], v[192:195], v[200:203], v[112:115]
	v_mfma_f32_16x16x32_bf16 v[100:103], v[184:187], v[212:215], v[100:103]
	v_mfma_f32_16x16x32_bf16 v[96:99], v[192:195], v[212:215], v[96:99]
	v_mfma_f32_16x16x32_bf16 v[84:87], v[184:187], v[220:223], v[84:87]
	v_mfma_f32_16x16x32_bf16 v[80:83], v[192:195], v[220:223], v[80:83]
	v_mfma_f32_16x16x32_bf16 v[68:71], v[184:187], v[228:231], v[68:71]
	v_mfma_f32_16x16x32_bf16 v[64:67], v[192:195], v[228:231], v[64:67]
	s_setprio 0
	s_barrier
; #define PG8_STAGE(bufoff, gbase, voff) do { _Pragma("unroll") for (int _i = 0; _i < 2; ++_i) \
;         __builtin_amdgcn_global_load_lds((const unsigned*)((const char*)(gbase) + (voff)[_i]), (PG8_LAS unsigned*)(lds + (bufoff) + ldsw + _i * 8192), 16, 0, 0); } while (0)
; #define PG8_LDA(dst, b, h) do { _Pragma("unroll") for (int m = 0; m < 4; ++m) _Pragma("unroll") for (int k = 0; k < 2; ++k) dst[m][k] = *(const PG8_LAS bf16x8*)(lds + PG8_SA(b, h) + aoff + m * 2048 + k * 1024); } while (0)
; #define PG8_MMA(ai, bj, At, Bt) do { __builtin_amdgcn_s_setprio(1); _Pragma("unroll") for (int m = 0; m < 4; ++m) _Pragma("unroll") for (int n = 0; n < 2; ++n) _Pragma("unroll") for (int k = 0; k < 2; ++k) \
;         acc[ai][bj][m][n] = __builtin_amdgcn_mfma_f32_16x16x32_bf16(Bt[n][k], At[m][k], acc[ai][bj][m][n], 0, 0, 0); __builtin_amdgcn_s_setprio(0); } while (0)
; #define PG8_WAIT_V(n) asm volatile("s_waitcnt vmcnt(" #n ")" ::: "memory")
; #define PG8_WAIT_L(n) asm volatile("s_waitcnt lgkmcnt(" #n ")" ::: "memory")
; #define PG8_BAR __builtin_amdgcn_s_barrier()
; #define PG8_SCHED __builtin_amdgcn_sched_barrier(0)
; template <class Epi, class Sched, bool ALIGN_EPI = false, bool SP2 = false>
; __device__ __forceinline__ void gemm_phase(PG8_LAS unsigned char* lds, const Gemm g, const Sched& S, const Epi& E) {
;     ...
;         for (int t = 0; t < nt; t += 2) {
;     ...
;             PG8_LDA(At, 1, 1); PG8_STAGE(PG8_SB(1, 0), b3, voffB); PG8_STAGE(PG8_SB(1, 1), b3 + hstep, voffB); PG8_STAGE(PG8_SA(1, 0), a3, voffA);
;             PG8_WAIT_V(8); PG8_WAIT_L(0); PG8_BAR; PG8_MMA(1, 0, At, B0); PG8_MMA(1, 1, At, B1); PG8_BAR; PG8_SCHED;
	s_add_i32 s36, s68, s40
	v_lshl_add_u64 v[142:143], v[142:143], 0, s[8:9]
	s_mov_b32 m0, s36
	ds_read_b128 v[196:199], v162 offset:49152
	ds_read_b128 v[200:203], v162 offset:50176
	ds_read_b128 v[208:211], v162 offset:51200
	ds_read_b128 v[212:215], v162 offset:52224
	ds_read_b128 v[216:219], v162 offset:53248
	ds_read_b128 v[220:223], v162 offset:54272
	ds_read_b128 v[224:227], v162 offset:55296
	ds_read_b128 v[228:231], v162 offset:56320
	global_load_lds_dwordx4 v[142:143], off
	s_add_i32 m0, s36, 0x2000
	s_add_u32 s34, s34, 0x40080
	v_lshl_add_u64 v[142:143], v[204:205], 0, s[8:9]
	s_addc_u32 s35, s35, 0
	s_add_i32 s36, s69, s40
	global_load_lds_dwordx4 v[142:143], off
	v_lshl_add_u64 v[142:143], s[34:35], 0, v[130:131]
	s_mov_b32 m0, s36
	s_nop 0
	global_load_lds_dwordx4 v[142:143], off
	v_lshl_add_u64 v[142:143], s[34:35], 0, v[134:135]
	s_add_i32 m0, s36, 0x2000
	s_nop 0
	global_load_lds_dwordx4 v[142:143], off
	v_lshl_add_u64 v[142:143], v[232:233], 0, s[8:9]
	s_mov_b32 m0, s52
	s_nop 0
	global_load_lds_dwordx4 v[142:143], off
	v_lshl_add_u64 v[142:143], v[234:235], 0, s[8:9]
	s_mov_b32 m0, s53
	s_nop 0
	global_load_lds_dwordx4 v[142:143], off
	s_waitcnt vmcnt(8)
	s_waitcnt lgkmcnt(0)
	s_barrier
	s_setprio 1
	s_waitcnt lgkmcnt(0)
	v_mfma_f32_16x16x32_bf16 v[60:63], v[164:167], v[196:199], v[60:63]
	v_mfma_f32_16x16x32_bf16 v[56:59], v[172:175], v[196:199], v[56:59]
	v_mfma_f32_16x16x32_bf16 v[44:47], v[164:167], v[208:211], v[44:47]
	v_mfma_f32_16x16x32_bf16 v[40:43], v[172:175], v[208:211], v[40:43]
	v_mfma_f32_16x16x32_bf16 v[28:31], v[164:167], v[216:219], v[28:31]
	v_mfma_f32_16x16x32_bf16 v[24:27], v[172:175], v[216:219], v[24:27]
	v_mfma_f32_16x16x32_bf16 v[12:15], v[164:167], v[224:227], v[12:15]
	v_mfma_f32_16x16x32_bf16 v[8:11], v[172:175], v[224:227], v[8:11]
	v_mfma_f32_16x16x32_bf16 v[60:63], v[168:171], v[200:203], v[60:63]
	v_mfma_f32_16x16x32_bf16 v[56:59], v[176:179], v[200:203], v[56:59]
	v_mfma_f32_16x16x32_bf16 v[44:47], v[168:171], v[212:215], v[44:47]
	v_mfma_f32_16x16x32_bf16 v[40:43], v[176:179], v[212:215], v[40:43]
	v_mfma_f32_16x16x32_bf16 v[28:31], v[168:171], v[220:223], v[28:31]
	v_mfma_f32_16x16x32_bf16 v[24:27], v[176:179], v[220:223], v[24:27]
	v_mfma_f32_16x16x32_bf16 v[12:15], v[168:171], v[228:231], v[12:15]
	v_mfma_f32_16x16x32_bf16 v[8:11], v[176:179], v[228:231], v[8:11]
	v_mfma_f32_16x16x32_bf16 v[52:55], v[180:183], v[196:199], v[52:55]
	v_mfma_f32_16x16x32_bf16 v[48:51], v[188:191], v[196:199], v[48:51]
	v_mfma_f32_16x16x32_bf16 v[36:39], v[180:183], v[208:211], v[36:39]
	v_mfma_f32_16x16x32_bf16 v[32:35], v[188:191], v[208:211], v[32:35]
	v_mfma_f32_16x16x32_bf16 v[20:23], v[180:183], v[216:219], v[20:23]
	v_mfma_f32_16x16x32_bf16 v[16:19], v[188:191], v[216:219], v[16:19]
	v_mfma_f32_16x16x32_bf16 v[4:7], v[180:183], v[224:227], v[4:7]
	v_mfma_f32_16x16x32_bf16 v[0:3], v[188:191], v[224:227], v[0:3]
	v_mfma_f32_16x16x32_bf16 v[52:55], v[184:187], v[200:203], v[52:55]
	v_mfma_f32_16x16x32_bf16 v[48:51], v[192:195], v[200:203], v[48:51]
	v_mfma_f32_16x16x32_bf16 v[36:39], v[184:187], v[212:215], v[36:39]
	v_mfma_f32_16x16x32_bf16 v[32:35], v[192:195], v[212:215], v[32:35]
	v_mfma_f32_16x16x32_bf16 v[20:23], v[184:187], v[220:223], v[20:23]
	v_mfma_f32_16x16x32_bf16 v[16:19], v[192:195], v[220:223], v[16:19]
	v_mfma_f32_16x16x32_bf16 v[4:7], v[184:187], v[228:231], v[4:7]
	v_mfma_f32_16x16x32_bf16 v[0:3], v[192:195], v[228:231], v[0:3]
	s_setprio 0
	s_barrier
	s_add_i32 s67, s67, 2
	s_add_u32 s30, s30, 0x100
	s_addc_u32 s31, s31, 0
	s_add_u32 s65, s65, 0x100
	s_addc_u32 s66, s66, 0
	s_cmp_gt_u32 s67, 13
	s_cbranch_scc0 .LBB0_1788

;     __device__ __forceinline__ bool next(int i, Unit& u) const { if (i != 0) return false; const int c0 = (G >= 8) ? G - 5 : G - 2; int k = -1; if (c == c0) k = 0; else if (c == G - 1) k = 1; if (k < 0 || k >= n) return false; u.pm = k; u.pn = 0; return true; }
; #define PG8_STAGE(bufoff, gbase, voff) do { _Pragma("unroll") for (int _i = 0; _i < 2; ++_i) \
;         __builtin_amdgcn_global_load_lds((const unsigned*)((const char*)(gbase) + (voff)[_i]), (PG8_LAS unsigned*)(lds + (bufoff) + ldsw + _i * 8192), 16, 0, 0); } while (0)
; #define PG8_LDA(dst, b, h) do { _Pragma("unroll") for (int m = 0; m < 4; ++m) _Pragma("unroll") for (int k = 0; k < 2; ++k) dst[m][k] = *(const PG8_LAS bf16x8*)(lds + PG8_SA(b, h) + aoff + m * 2048 + k * 1024); } while (0)
; #define PG8_LDB(dst, b, h) do { _Pragma("unroll") for (int n = 0; n < 2; ++n) _Pragma("unroll") for (int k = 0; k < 2; ++k) dst[n][k] = *(const PG8_LAS bf16x8*)(lds + PG8_SB(b, h) + boff + n * 2048 + k * 1024); } while (0)
; template <class Epi, class Sched, bool ALIGN_EPI = false, bool SP2 = false>
; __device__ __forceinline__ void gemm_phase(PG8_LAS unsigned char* lds, const Gemm g, const Sched& S, const Epi& E) {
;     ...
;         const bool has_next = S.next(ui + 1, nxt);
;         const char* nA = has_next ? (const char*)g.A + (size_t)nxt.pm * tstep : cA; const char* nB = has_next ? (const char*)g.Bt + (size_t)nxt.pn * tstep : cB;
;         for (int t = 0; t < nt; t += 2) {
;             const bool last = (t == nt - 2);
;             const char* a1 = cA + (size_t)(t + 1) * kstep;
;             const char* a2 = last ? nA : cA + (size_t)(t + 2) * kstep; const char* b2 = last ? nB : cB + (size_t)(t + 2) * kstep;
;             const char* a3 = a2 + kstep; const char* b3 = b2 + kstep;
;             if (last && has_next) S.a_ready(nxt);
;             if constexpr (SP2) {
;             PG8_LDB(B0, 0, 0); PG8_LDB(B1, 0, 1); PG8_SCHED; PG8_LDA(At, 0, 0); PG8_STAGE(PG8_SA(1, 1), a1 + hstep, voffA);
;             PG8_WAIT_V(8); PG8_WAIT_L(0); PG8_BAR; PG8_MMA(0, 0, At, B0); PG8_MMA(0, 1, At, B1); PG8_BAR; PG8_SCHED;
;             PG8_LDA(At, 0, 1); PG8_STAGE(PG8_SB(0, 0), b2, voffB); PG8_STAGE(PG8_SB(0, 1), b2 + hstep, voffB); PG8_STAGE(PG8_SA(0, 0), a2, voffA);
;             PG8_WAIT_V(8); PG8_WAIT_L(0); PG8_BAR; PG8_MMA(1, 0, At, B0); PG8_MMA(1, 1, At, B1); PG8_BAR; PG8_SCHED;
.LBB0_1808:
	s_ashr_i32 s19, s18, 31
	s_lshl_b64 s[24:25], s[18:19], 19
	s_add_u32 s24, s97, s24
	s_addc_u32 s25, s3, s25
	s_and_b64 s[26:27], s[22:23], exec
	s_cselect_b32 s19, s25, s31
	s_cselect_b32 s59, s24, s30
	s_ashr_i32 s21, s20, 31
	s_lshl_b64 s[26:27], s[20:21], 19
	s_add_u32 s26, s38, s26
	s_addc_u32 s27, s39, s27
	s_and_b64 s[36:37], s[22:23], exec
	s_cselect_b32 s21, s27, s35
	s_cselect_b32 s60, s26, s34
	s_add_u32 s30, s30, 0x40080
	s_addc_u32 s31, s31, 0
	s_add_u32 s61, s34, 0x100
	v_mov_b32_e32 v0, 0
	s_addc_u32 s64, s35, 0
	s_mov_b32 s65, -2
	ds_read_b128 v[164:167], v160
	ds_read_b128 v[168:171], v160 offset:1024
	ds_read_b128 v[172:175], v160 offset:2048
	ds_read_b128 v[176:179], v160 offset:3072
	ds_read_b128 v[180:183], v161
	ds_read_b128 v[184:187], v161 offset:1024
	ds_read_b128 v[188:191], v161 offset:2048
	ds_read_b128 v[192:195], v161 offset:3072
	s_add_u32 s34, s30, 0xfffc0080
	s_addc_u32 s35, s31, -1
	s_cmp_eq_u32 s65, 12
	s_cselect_b32 s37, s19, s35
	s_cselect_b32 s36, s59, s34
	s_cselect_b32 s35, s21, s64
	s_cselect_b32 s34, s60, s61
	v_lshl_add_u64 v[142:143], s[30:31], 0, v[136:137]
	s_add_i32 m0, s29, 0xc000
	ds_read_b128 v[196:199], v162
	ds_read_b128 v[200:203], v162 offset:1024
	ds_read_b128 v[208:211], v162 offset:2048
	ds_read_b128 v[212:215], v162 offset:3072
	ds_read_b128 v[216:219], v162 offset:4096
	ds_read_b128 v[220:223], v162 offset:5120
	ds_read_b128 v[224:227], v162 offset:6144
	ds_read_b128 v[228:231], v162 offset:7168
	global_load_lds_dwordx4 v[142:143], off
	v_lshl_add_u64 v[142:143], s[30:31], 0, v[138:139]
	s_add_i32 m0, s29, 0xe000
	s_nop 0
	global_load_lds_dwordx4 v[142:143], off
	s_waitcnt vmcnt(8)
	s_waitcnt lgkmcnt(0)
	s_barrier
	s_setprio 1
	s_waitcnt lgkmcnt(0)
	v_mfma_f32_16x16x32_bf16 v[124:127], v[164:167], v[196:199], 0
	v_mfma_f32_16x16x32_bf16 v[120:123], v[172:175], v[196:199], 0
	v_mfma_f32_16x16x32_bf16 v[108:111], v[164:167], v[208:211], 0
	v_mfma_f32_16x16x32_bf16 v[104:107], v[172:175], v[208:211], 0
	v_mfma_f32_16x16x32_bf16 v[92:95], v[164:167], v[216:219], 0
	v_mfma_f32_16x16x32_bf16 v[88:91], v[172:175], v[216:219], 0
	v_mfma_f32_16x16x32_bf16 v[76:79], v[164:167], v[224:227], 0
	v_mfma_f32_16x16x32_bf16 v[72:75], v[172:175], v[224:227], 0
	v_mfma_f32_16x16x32_bf16 v[124:127], v[168:171], v[200:203], v[124:127]
	v_mfma_f32_16x16x32_bf16 v[120:123], v[176:179], v[200:203], v[120:123]
	v_mfma_f32_16x16x32_bf16 v[108:111], v[168:171], v[212:215], v[108:111]
	v_mfma_f32_16x16x32_bf16 v[104:107], v[176:179], v[212:215], v[104:107]
	v_mfma_f32_16x16x32_bf16 v[92:95], v[168:171], v[220:223], v[92:95]
	v_mfma_f32_16x16x32_bf16 v[88:91], v[176:179], v[220:223], v[88:91]
	v_mfma_f32_16x16x32_bf16 v[76:79], v[168:171], v[228:231], v[76:79]
	v_mfma_f32_16x16x32_bf16 v[72:75], v[176:179], v[228:231], v[72:75]
	v_mfma_f32_16x16x32_bf16 v[116:119], v[180:183], v[196:199], 0
	v_mfma_f32_16x16x32_bf16 v[112:115], v[188:191], v[196:199], 0
	v_mfma_f32_16x16x32_bf16 v[100:103], v[180:183], v[208:211], 0
	v_mfma_f32_16x16x32_bf16 v[96:99], v[188:191], v[208:211], 0
	v_mfma_f32_16x16x32_bf16 v[84:87], v[180:183], v[216:219], 0
	v_mfma_f32_16x16x32_bf16 v[80:83], v[188:191], v[216:219], 0
	v_mfma_f32_16x16x32_bf16 v[68:71], v[180:183], v[224:227], 0
	v_mfma_f32_16x16x32_bf16 v[64:67], v[188:191], v[224:227], 0
	v_mfma_f32_16x16x32_bf16 v[116:119], v[184:187], v[200:203], v[116:119]
	v_mfma_f32_16x16x32_bf16 v[112:115], v[192:195], v[200:203], v[112:115]
	v_mfma_f32_16x16x32_bf16 v[100:103], v[184:187], v[212:215], v[100:103]
	v_mfma_f32_16x16x32_bf16 v[96:99], v[192:195], v[212:215], v[96:99]
	v_mfma_f32_16x16x32_bf16 v[84:87], v[184:187], v[220:223], v[84:87]
	v_mfma_f32_16x16x32_bf16 v[80:83], v[192:195], v[220:223], v[80:83]
	v_mfma_f32_16x16x32_bf16 v[68:71], v[184:187], v[228:231], v[68:71]
	v_mfma_f32_16x16x32_bf16 v[64:67], v[192:195], v[228:231], v[64:67]
	s_setprio 0
	s_barrier
	s_add_i32 s66, s53, s41
	v_lshl_add_u64 v[142:143], s[34:35], 0, v[130:131]
	s_mov_b32 m0, s66
	ds_read_b128 v[196:199], v162 offset:16384
	ds_read_b128 v[200:203], v162 offset:17408
	ds_read_b128 v[208:211], v162 offset:18432
	ds_read_b128 v[212:215], v162 offset:19456
	ds_read_b128 v[216:219], v162 offset:20480
	ds_read_b128 v[220:223], v162 offset:21504
	ds_read_b128 v[224:227], v162 offset:22528
	ds_read_b128 v[228:231], v162 offset:23552
	global_load_lds_dwordx4 v[142:143], off
	s_add_i32 m0, s66, 0x2000
	s_add_u32 s66, s34, 0x40000
	v_lshl_add_u64 v[204:205], s[34:35], 0, v[134:135]
	s_addc_u32 s67, s35, 0
	s_add_i32 s68, s56, s41
	global_load_lds_dwordx4 v[204:205], off
	v_lshl_add_u64 v[232:233], s[66:67], 0, v[130:131]
	s_mov_b32 m0, s68
	v_lshl_add_u64 v[234:235], s[36:37], 0, v[132:133]
	global_load_lds_dwordx4 v[232:233], off
	v_lshl_add_u64 v[232:233], s[66:67], 0, v[134:135]
	s_add_i32 m0, s68, 0x2000
	s_nop 0
	global_load_lds_dwordx4 v[232:233], off
	v_lshl_add_u64 v[232:233], s[36:37], 0, v[128:129]
	s_mov_b32 m0, s29
	s_nop 0
	global_load_lds_dwordx4 v[232:233], off
	s_mov_b32 m0, s43
	s_nop 0
	global_load_lds_dwordx4 v[234:235], off
	s_waitcnt vmcnt(8)
	s_waitcnt lgkmcnt(0)
	s_barrier
; #define PG8_STAGE(bufoff, gbase, voff) do { _Pragma("unroll") for (int _i = 0; _i < 2; ++_i) \
;         __builtin_amdgcn_global_load_lds((const unsigned*)((const char*)(gbase) + (voff)[_i]), (PG8_LAS unsigned*)(lds + (bufoff) + ldsw + _i * 8192), 16, 0, 0); } while (0)
; #define PG8_LDA(dst, b, h) do { _Pragma("unroll") for (int m = 0; m < 4; ++m) _Pragma("unroll") for (int k = 0; k < 2; ++k) dst[m][k] = *(const PG8_LAS bf16x8*)(lds + PG8_SA(b, h) + aoff + m * 2048 + k * 1024); } while (0)
; #define PG8_LDB(dst, b, h) do { _Pragma("unroll") for (int n = 0; n < 2; ++n) _Pragma("unroll") for (int k = 0; k < 2; ++k) dst[n][k] = *(const PG8_LAS bf16x8*)(lds + PG8_SB(b, h) + boff + n * 2048 + k * 1024); } while (0)
; #define PG8_MMA(ai, bj, At, Bt) do { __builtin_amdgcn_s_setprio(1); _Pragma("unroll") for (int m = 0; m < 4; ++m) _Pragma("unroll") for (int n = 0; n < 2; ++n) _Pragma("unroll") for (int k = 0; k < 2; ++k) \
;         acc[ai][bj][m][n] = __builtin_amdgcn_mfma_f32_16x16x32_bf16(Bt[n][k], At[m][k], acc[ai][bj][m][n], 0, 0, 0); __builtin_amdgcn_s_setprio(0); } while (0)
; #define PG8_WAIT_V(n) asm volatile("s_waitcnt vmcnt(" #n ")" ::: "memory")
; #define PG8_WAIT_L(n) asm volatile("s_waitcnt lgkmcnt(" #n ")" ::: "memory")
; #define PG8_BAR __builtin_amdgcn_s_barrier()
; #define PG8_SCHED __builtin_amdgcn_sched_barrier(0)
; template <class Epi, class Sched, bool ALIGN_EPI = false, bool SP2 = false>
; __device__ __forceinline__ void gemm_phase(PG8_LAS unsigned char* lds, const Gemm g, const Sched& S, const Epi& E) {
;     ...
;             PG8_WAIT_V(8); PG8_WAIT_L(0); PG8_BAR; PG8_MMA(1, 0, At, B0); PG8_MMA(1, 1, At, B1); PG8_BAR; PG8_SCHED;
;             PG8_LDB(B0, 1, 0); PG8_LDB(B1, 1, 1); PG8_SCHED; PG8_LDA(At, 1, 0); PG8_STAGE(PG8_SA(0, 1), a2 + hstep, voffA);
;             PG8_WAIT_V(8); PG8_WAIT_L(0); PG8_BAR; PG8_MMA(0, 0, At, B0); PG8_MMA(0, 1, At, B1); PG8_BAR; PG8_SCHED;
	s_setprio 1
	s_waitcnt lgkmcnt(0)
	v_mfma_f32_16x16x32_bf16 v[60:63], v[164:167], v[196:199], 0
	v_mfma_f32_16x16x32_bf16 v[56:59], v[172:175], v[196:199], 0
	v_mfma_f32_16x16x32_bf16 v[44:47], v[164:167], v[208:211], 0
	v_mfma_f32_16x16x32_bf16 v[40:43], v[172:175], v[208:211], 0
	v_mfma_f32_16x16x32_bf16 v[28:31], v[164:167], v[216:219], 0
	v_mfma_f32_16x16x32_bf16 v[24:27], v[172:175], v[216:219], 0
	v_mfma_f32_16x16x32_bf16 v[12:15], v[164:167], v[224:227], 0
	v_mfma_f32_16x16x32_bf16 v[8:11], v[172:175], v[224:227], 0
	v_mfma_f32_16x16x32_bf16 v[60:63], v[168:171], v[200:203], v[60:63]
	v_mfma_f32_16x16x32_bf16 v[56:59], v[176:179], v[200:203], v[56:59]
	v_mfma_f32_16x16x32_bf16 v[44:47], v[168:171], v[212:215], v[44:47]
	v_mfma_f32_16x16x32_bf16 v[40:43], v[176:179], v[212:215], v[40:43]
	v_mfma_f32_16x16x32_bf16 v[28:31], v[168:171], v[220:223], v[28:31]
	v_mfma_f32_16x16x32_bf16 v[24:27], v[176:179], v[220:223], v[24:27]
	v_mfma_f32_16x16x32_bf16 v[12:15], v[168:171], v[228:231], v[12:15]
	v_mfma_f32_16x16x32_bf16 v[8:11], v[176:179], v[228:231], v[8:11]
	v_mfma_f32_16x16x32_bf16 v[52:55], v[180:183], v[196:199], 0
	v_mfma_f32_16x16x32_bf16 v[48:51], v[188:191], v[196:199], 0
	v_mfma_f32_16x16x32_bf16 v[36:39], v[180:183], v[208:211], 0
	v_mfma_f32_16x16x32_bf16 v[32:35], v[188:191], v[208:211], 0
	v_mfma_f32_16x16x32_bf16 v[20:23], v[180:183], v[216:219], 0
	v_mfma_f32_16x16x32_bf16 v[16:19], v[188:191], v[216:219], 0
	v_mfma_f32_16x16x32_bf16 v[4:7], v[180:183], v[224:227], 0
	v_mfma_f32_16x16x32_bf16 v[0:3], v[188:191], v[224:227], 0
	v_mfma_f32_16x16x32_bf16 v[52:55], v[184:187], v[200:203], v[52:55]
	v_mfma_f32_16x16x32_bf16 v[48:51], v[192:195], v[200:203], v[48:51]
	v_mfma_f32_16x16x32_bf16 v[36:39], v[184:187], v[212:215], v[36:39]
	v_mfma_f32_16x16x32_bf16 v[32:35], v[192:195], v[212:215], v[32:35]
	v_mfma_f32_16x16x32_bf16 v[20:23], v[184:187], v[220:223], v[20:23]
	v_mfma_f32_16x16x32_bf16 v[16:19], v[192:195], v[220:223], v[16:19]
	v_mfma_f32_16x16x32_bf16 v[4:7], v[184:187], v[228:231], v[4:7]
	v_mfma_f32_16x16x32_bf16 v[0:3], v[192:195], v[228:231], v[0:3]
	s_setprio 0
	s_barrier
	s_add_i32 s66, 0, 0x18000
	v_add_u32_e32 v163, s66, v158
	s_add_i32 s67, 0, 0x1c000
	ds_read_b128 v[164:167], v163
	ds_read_b128 v[168:171], v163 offset:1024
	ds_read_b128 v[172:175], v163 offset:2048
	ds_read_b128 v[176:179], v163 offset:3072
	v_add_u32_e32 v163, s67, v158
	ds_read_b128 v[180:183], v163
	ds_read_b128 v[184:187], v163 offset:1024
	ds_read_b128 v[188:191], v163 offset:2048
	ds_read_b128 v[192:195], v163 offset:3072
	s_add_u32 s36, s36, 0x40000
	s_addc_u32 s37, s37, 0
	s_mov_b32 m0, s44
	v_lshl_add_u64 v[236:237], s[36:37], 0, v[128:129]
	ds_read_b128 v[196:199], v162 offset:32768
	ds_read_b128 v[200:203], v162 offset:33792
	ds_read_b128 v[208:211], v162 offset:34816
	ds_read_b128 v[212:215], v162 offset:35840
	ds_read_b128 v[216:219], v162 offset:36864
	ds_read_b128 v[220:223], v162 offset:37888
	ds_read_b128 v[224:227], v162 offset:38912
	ds_read_b128 v[228:231], v162 offset:39936
	global_load_lds_dwordx4 v[236:237], off
	v_lshl_add_u64 v[236:237], s[36:37], 0, v[132:133]
	s_mov_b32 m0, s45
	s_nop 0
	global_load_lds_dwordx4 v[236:237], off
	s_waitcnt vmcnt(8)
	s_waitcnt lgkmcnt(0)
	s_barrier
	s_setprio 1
	s_waitcnt lgkmcnt(0)
	v_mfma_f32_16x16x32_bf16 v[124:127], v[164:167], v[196:199], v[124:127]
	v_mfma_f32_16x16x32_bf16 v[120:123], v[172:175], v[196:199], v[120:123]
	v_mfma_f32_16x16x32_bf16 v[108:111], v[164:167], v[208:211], v[108:111]
	v_mfma_f32_16x16x32_bf16 v[104:107], v[172:175], v[208:211], v[104:107]
	v_mfma_f32_16x16x32_bf16 v[92:95], v[164:167], v[216:219], v[92:95]
	v_mfma_f32_16x16x32_bf16 v[88:91], v[172:175], v[216:219], v[88:91]
	v_mfma_f32_16x16x32_bf16 v[76:79], v[164:167], v[224:227], v[76:79]
	v_mfma_f32_16x16x32_bf16 v[72:75], v[172:175], v[224:227], v[72:75]
	v_mfma_f32_16x16x32_bf16 v[124:127], v[168:171], v[200:203], v[124:127]
	v_mfma_f32_16x16x32_bf16 v[120:123], v[176:179], v[200:203], v[120:123]
	v_mfma_f32_16x16x32_bf16 v[108:111], v[168:171], v[212:215], v[108:111]
	v_mfma_f32_16x16x32_bf16 v[104:107], v[176:179], v[212:215], v[104:107]
	v_mfma_f32_16x16x32_bf16 v[92:95], v[168:171], v[220:223], v[92:95]
	v_mfma_f32_16x16x32_bf16 v[88:91], v[176:179], v[220:223], v[88:91]
	v_mfma_f32_16x16x32_bf16 v[76:79], v[168:171], v[228:231], v[76:79]
	v_mfma_f32_16x16x32_bf16 v[72:75], v[176:179], v[228:231], v[72:75]
	v_mfma_f32_16x16x32_bf16 v[116:119], v[180:183], v[196:199], v[116:119]
	v_mfma_f32_16x16x32_bf16 v[112:115], v[188:191], v[196:199], v[112:115]
	v_mfma_f32_16x16x32_bf16 v[100:103], v[180:183], v[208:211], v[100:103]
	v_mfma_f32_16x16x32_bf16 v[96:99], v[188:191], v[208:211], v[96:99]
	v_mfma_f32_16x16x32_bf16 v[84:87], v[180:183], v[216:219], v[84:87]
	v_mfma_f32_16x16x32_bf16 v[80:83], v[188:191], v[216:219], v[80:83]
	v_mfma_f32_16x16x32_bf16 v[68:71], v[180:183], v[224:227], v[68:71]
	v_mfma_f32_16x16x32_bf16 v[64:67], v[188:191], v[224:227], v[64:67]
	v_mfma_f32_16x16x32_bf16 v[116:119], v[184:187], v[200:203], v[116:119]
	v_mfma_f32_16x16x32_bf16 v[112:115], v[192:195], v[200:203], v[112:115]
	v_mfma_f32_16x16x32_bf16 v[100:103], v[184:187], v[212:215], v[100:103]
	v_mfma_f32_16x16x32_bf16 v[96:99], v[192:195], v[212:215], v[96:99]
	v_mfma_f32_16x16x32_bf16 v[84:87], v[184:187], v[220:223], v[84:87]
	v_mfma_f32_16x16x32_bf16 v[80:83], v[192:195], v[220:223], v[80:83]
	v_mfma_f32_16x16x32_bf16 v[68:71], v[184:187], v[228:231], v[68:71]
	v_mfma_f32_16x16x32_bf16 v[64:67], v[192:195], v[228:231], v[64:67]
	s_setprio 0
	s_barrier
; #define PG8_STAGE(bufoff, gbase, voff) do { _Pragma("unroll") for (int _i = 0; _i < 2; ++_i) \
;         __builtin_amdgcn_global_load_lds((const unsigned*)((const char*)(gbase) + (voff)[_i]), (PG8_LAS unsigned*)(lds + (bufoff) + ldsw + _i * 8192), 16, 0, 0); } while (0)
; #define PG8_LDA(dst, b, h) do { _Pragma("unroll") for (int m = 0; m < 4; ++m) _Pragma("unroll") for (int k = 0; k < 2; ++k) dst[m][k] = *(const PG8_LAS bf16x8*)(lds + PG8_SA(b, h) + aoff + m * 2048 + k * 1024); } while (0)
; #define PG8_LDB(dst, b, h) do { _Pragma("unroll") for (int n = 0; n < 2; ++n) _Pragma("unroll") for (int k = 0; k < 2; ++k) dst[n][k] = *(const PG8_LAS bf16x8*)(lds + PG8_SB(b, h) + boff + n * 2048 + k * 1024); } while (0)
; #define PG8_MMA(ai, bj, At, Bt) do { __builtin_amdgcn_s_setprio(1); _Pragma("unroll") for (int m = 0; m < 4; ++m) _Pragma("unroll") for (int n = 0; n < 2; ++n) _Pragma("unroll") for (int k = 0; k < 2; ++k) \
;         acc[ai][bj][m][n] = __builtin_amdgcn_mfma_f32_16x16x32_bf16(Bt[n][k], At[m][k], acc[ai][bj][m][n], 0, 0, 0); __builtin_amdgcn_s_setprio(0); } while (0)
; #define PG8_WAIT_V(n) asm volatile("s_waitcnt vmcnt(" #n ")" ::: "memory")
; #define PG8_WAIT_L(n) asm volatile("s_waitcnt lgkmcnt(" #n ")" ::: "memory")
; #define PG8_BAR __builtin_amdgcn_s_barrier()
; #define PG8_SCHED __builtin_amdgcn_sched_barrier(0)
; template <class Epi, class Sched, bool ALIGN_EPI = false, bool SP2 = false>
; __device__ __forceinline__ void gemm_phase(PG8_LAS unsigned char* lds, const Gemm g, const Sched& S, const Epi& E) {
;     ...
;             PG8_LDB(B0, 0, 0); PG8_LDB(B1, 0, 1); PG8_SCHED; PG8_LDA(At, 0, 0); PG8_STAGE(PG8_SA(1, 1), a1 + hstep, voffA);
;     ...
;             PG8_LDA(At, 1, 1); PG8_STAGE(PG8_SB(1, 0), b3, voffB); PG8_STAGE(PG8_SB(1, 1), b3 + hstep, voffB); PG8_STAGE(PG8_SA(1, 0), a3, voffA);
;             PG8_WAIT_V(8); PG8_WAIT_L(0); PG8_BAR; PG8_MMA(1, 0, At, B0); PG8_MMA(1, 1, At, B1); PG8_BAR; PG8_SCHED;
	s_add_i32 s36, s66, s41
	v_lshl_add_u64 v[142:143], v[142:143], 0, s[8:9]
	s_mov_b32 m0, s36
	ds_read_b128 v[196:199], v162 offset:49152
	ds_read_b128 v[200:203], v162 offset:50176
	ds_read_b128 v[208:211], v162 offset:51200
	ds_read_b128 v[212:215], v162 offset:52224
	ds_read_b128 v[216:219], v162 offset:53248
	ds_read_b128 v[220:223], v162 offset:54272
	ds_read_b128 v[224:227], v162 offset:55296
	ds_read_b128 v[228:231], v162 offset:56320
	global_load_lds_dwordx4 v[142:143], off
	s_add_i32 m0, s36, 0x2000
	s_add_u32 s34, s34, 0x40080
	v_lshl_add_u64 v[142:143], v[204:205], 0, s[8:9]
	s_addc_u32 s35, s35, 0
	s_add_i32 s36, s67, s41
	global_load_lds_dwordx4 v[142:143], off
	v_lshl_add_u64 v[142:143], s[34:35], 0, v[130:131]
	s_mov_b32 m0, s36
	s_nop 0
	global_load_lds_dwordx4 v[142:143], off
	v_lshl_add_u64 v[142:143], s[34:35], 0, v[134:135]
	s_add_i32 m0, s36, 0x2000
	s_nop 0
	global_load_lds_dwordx4 v[142:143], off
	v_lshl_add_u64 v[142:143], v[232:233], 0, s[8:9]
	s_mov_b32 m0, s47
	s_nop 0
	global_load_lds_dwordx4 v[142:143], off
	v_lshl_add_u64 v[142:143], v[234:235], 0, s[8:9]
	s_mov_b32 m0, s52
	s_nop 0
	global_load_lds_dwordx4 v[142:143], off
	s_waitcnt vmcnt(8)
	s_waitcnt lgkmcnt(0)
	s_barrier
	s_setprio 1
	s_waitcnt lgkmcnt(0)
	v_mfma_f32_16x16x32_bf16 v[60:63], v[164:167], v[196:199], v[60:63]
	v_mfma_f32_16x16x32_bf16 v[56:59], v[172:175], v[196:199], v[56:59]
	v_mfma_f32_16x16x32_bf16 v[44:47], v[164:167], v[208:211], v[44:47]
	v_mfma_f32_16x16x32_bf16 v[40:43], v[172:175], v[208:211], v[40:43]
	v_mfma_f32_16x16x32_bf16 v[28:31], v[164:167], v[216:219], v[28:31]
	v_mfma_f32_16x16x32_bf16 v[24:27], v[172:175], v[216:219], v[24:27]
	v_mfma_f32_16x16x32_bf16 v[12:15], v[164:167], v[224:227], v[12:15]
	v_mfma_f32_16x16x32_bf16 v[8:11], v[172:175], v[224:227], v[8:11]
	v_mfma_f32_16x16x32_bf16 v[60:63], v[168:171], v[200:203], v[60:63]
	v_mfma_f32_16x16x32_bf16 v[56:59], v[176:179], v[200:203], v[56:59]
	v_mfma_f32_16x16x32_bf16 v[44:47], v[168:171], v[212:215], v[44:47]
	v_mfma_f32_16x16x32_bf16 v[40:43], v[176:179], v[212:215], v[40:43]
	v_mfma_f32_16x16x32_bf16 v[28:31], v[168:171], v[220:223], v[28:31]
	v_mfma_f32_16x16x32_bf16 v[24:27], v[176:179], v[220:223], v[24:27]
	v_mfma_f32_16x16x32_bf16 v[12:15], v[168:171], v[228:231], v[12:15]
	v_mfma_f32_16x16x32_bf16 v[8:11], v[176:179], v[228:231], v[8:11]
	v_mfma_f32_16x16x32_bf16 v[52:55], v[180:183], v[196:199], v[52:55]
	v_mfma_f32_16x16x32_bf16 v[48:51], v[188:191], v[196:199], v[48:51]
	v_mfma_f32_16x16x32_bf16 v[36:39], v[180:183], v[208:211], v[36:39]
	v_mfma_f32_16x16x32_bf16 v[32:35], v[188:191], v[208:211], v[32:35]
	v_mfma_f32_16x16x32_bf16 v[20:23], v[180:183], v[216:219], v[20:23]
	v_mfma_f32_16x16x32_bf16 v[16:19], v[188:191], v[216:219], v[16:19]
	v_mfma_f32_16x16x32_bf16 v[4:7], v[180:183], v[224:227], v[4:7]
	v_mfma_f32_16x16x32_bf16 v[0:3], v[188:191], v[224:227], v[0:3]
	v_mfma_f32_16x16x32_bf16 v[52:55], v[184:187], v[200:203], v[52:55]
	v_mfma_f32_16x16x32_bf16 v[48:51], v[192:195], v[200:203], v[48:51]
	v_mfma_f32_16x16x32_bf16 v[36:39], v[184:187], v[212:215], v[36:39]
	v_mfma_f32_16x16x32_bf16 v[32:35], v[192:195], v[212:215], v[32:35]
	v_mfma_f32_16x16x32_bf16 v[20:23], v[184:187], v[220:223], v[20:23]
	v_mfma_f32_16x16x32_bf16 v[16:19], v[192:195], v[220:223], v[16:19]
	v_mfma_f32_16x16x32_bf16 v[4:7], v[184:187], v[228:231], v[4:7]
	v_mfma_f32_16x16x32_bf16 v[0:3], v[192:195], v[228:231], v[0:3]
	s_setprio 0
	s_barrier
	s_add_i32 s65, s65, 2
	s_add_u32 s30, s30, 0x100
	s_addc_u32 s31, s31, 0
	s_add_u32 s61, s61, 0x100
	s_addc_u32 s64, s64, 0
	s_cmp_gt_u32 s65, 13
	s_cbranch_scc0 .LBB0_1809
	s_branch .Lpeel_exit_13
.LBB0_1809:
	ds_read_b128 v[164:167], v160
	ds_read_b128 v[168:171], v160 offset:1024
	ds_read_b128 v[172:175], v160 offset:2048
	ds_read_b128 v[176:179], v160 offset:3072
	ds_read_b128 v[180:183], v161
	ds_read_b128 v[184:187], v161 offset:1024
	ds_read_b128 v[188:191], v161 offset:2048
	ds_read_b128 v[192:195], v161 offset:3072
	s_add_u32 s34, s30, 0xfffc0080
	s_addc_u32 s35, s31, -1
	s_cmp_eq_u32 s65, 12
	s_cselect_b32 s37, s19, s35
	s_cselect_b32 s36, s59, s34
	s_cselect_b32 s35, s21, s64
	s_cselect_b32 s34, s60, s61
	v_lshl_add_u64 v[142:143], s[30:31], 0, v[136:137]
	s_add_i32 m0, s29, 0xc000
	ds_read_b128 v[196:199], v162
	ds_read_b128 v[200:203], v162 offset:1024
	ds_read_b128 v[208:211], v162 offset:2048
	ds_read_b128 v[212:215], v162 offset:3072
	ds_read_b128 v[216:219], v162 offset:4096
	ds_read_b128 v[220:223], v162 offset:5120
	ds_read_b128 v[224:227], v162 offset:6144
	ds_read_b128 v[228:231], v162 offset:7168
	global_load_lds_dwordx4 v[142:143], off
	v_lshl_add_u64 v[142:143], s[30:31], 0, v[138:139]
	s_add_i32 m0, s29, 0xe000
	s_nop 0
	global_load_lds_dwordx4 v[142:143], off
	s_waitcnt vmcnt(8)
	s_waitcnt lgkmcnt(0)
	s_barrier
; #define PG8_STAGE(bufoff, gbase, voff) do { _Pragma("unroll") for (int _i = 0; _i < 2; ++_i) \
;         __builtin_amdgcn_global_load_lds((const unsigned*)((const char*)(gbase) + (voff)[_i]), (PG8_LAS unsigned*)(lds + (bufoff) + ldsw + _i * 8192), 16, 0, 0); } while (0)
; #define PG8_LDA(dst, b, h) do { _Pragma("unroll") for (int m = 0; m < 4; ++m) _Pragma("unroll") for (int k = 0; k < 2; ++k) dst[m][k] = *(const PG8_LAS bf16x8*)(lds + PG8_SA(b, h) + aoff + m * 2048 + k * 1024); } while (0)
; #define PG8_MMA(ai, bj, At, Bt) do { __builtin_amdgcn_s_setprio(1); _Pragma("unroll") for (int m = 0; m < 4; ++m) _Pragma("unroll") for (int n = 0; n < 2; ++n) _Pragma("unroll") for (int k = 0; k < 2; ++k) \
;         acc[ai][bj][m][n] = __builtin_amdgcn_mfma_f32_16x16x32_bf16(Bt[n][k], At[m][k], acc[ai][bj][m][n], 0, 0, 0); __builtin_amdgcn_s_setprio(0); } while (0)
; #define PG8_WAIT_V(n) asm volatile("s_waitcnt vmcnt(" #n ")" ::: "memory")
; #define PG8_WAIT_L(n) asm volatile("s_waitcnt lgkmcnt(" #n ")" ::: "memory")
; #define PG8_BAR __builtin_amdgcn_s_barrier()
; #define PG8_SCHED __builtin_amdgcn_sched_barrier(0)
; template <class Epi, class Sched, bool ALIGN_EPI = false, bool SP2 = false>
; __device__ __forceinline__ void gemm_phase(PG8_LAS unsigned char* lds, const Gemm g, const Sched& S, const Epi& E) {
;     ...
;             PG8_WAIT_V(8); PG8_WAIT_L(0); PG8_BAR; PG8_MMA(0, 0, At, B0); PG8_MMA(0, 1, At, B1); PG8_BAR; PG8_SCHED;
;             PG8_LDA(At, 0, 1); PG8_STAGE(PG8_SB(0, 0), b2, voffB); PG8_STAGE(PG8_SB(0, 1), b2 + hstep, voffB); PG8_STAGE(PG8_SA(0, 0), a2, voffA);
;             PG8_WAIT_V(8); PG8_WAIT_L(0); PG8_BAR; PG8_MMA(1, 0, At, B0); PG8_MMA(1, 1, At, B1); PG8_BAR; PG8_SCHED;
	s_setprio 1
	s_waitcnt lgkmcnt(0)
	v_mfma_f32_16x16x32_bf16 v[124:127], v[164:167], v[196:199], v[124:127]
	v_mfma_f32_16x16x32_bf16 v[120:123], v[172:175], v[196:199], v[120:123]
	v_mfma_f32_16x16x32_bf16 v[108:111], v[164:167], v[208:211], v[108:111]
	v_mfma_f32_16x16x32_bf16 v[104:107], v[172:175], v[208:211], v[104:107]
	v_mfma_f32_16x16x32_bf16 v[92:95], v[164:167], v[216:219], v[92:95]
	v_mfma_f32_16x16x32_bf16 v[88:91], v[172:175], v[216:219], v[88:91]
	v_mfma_f32_16x16x32_bf16 v[76:79], v[164:167], v[224:227], v[76:79]
	v_mfma_f32_16x16x32_bf16 v[72:75], v[172:175], v[224:227], v[72:75]
	v_mfma_f32_16x16x32_bf16 v[124:127], v[168:171], v[200:203], v[124:127]
	v_mfma_f32_16x16x32_bf16 v[120:123], v[176:179], v[200:203], v[120:123]
	v_mfma_f32_16x16x32_bf16 v[108:111], v[168:171], v[212:215], v[108:111]
	v_mfma_f32_16x16x32_bf16 v[104:107], v[176:179], v[212:215], v[104:107]
	v_mfma_f32_16x16x32_bf16 v[92:95], v[168:171], v[220:223], v[92:95]
	v_mfma_f32_16x16x32_bf16 v[88:91], v[176:179], v[220:223], v[88:91]
	v_mfma_f32_16x16x32_bf16 v[76:79], v[168:171], v[228:231], v[76:79]
	v_mfma_f32_16x16x32_bf16 v[72:75], v[176:179], v[228:231], v[72:75]
	v_mfma_f32_16x16x32_bf16 v[116:119], v[180:183], v[196:199], v[116:119]
	v_mfma_f32_16x16x32_bf16 v[112:115], v[188:191], v[196:199], v[112:115]
	v_mfma_f32_16x16x32_bf16 v[100:103], v[180:183], v[208:211], v[100:103]
	v_mfma_f32_16x16x32_bf16 v[96:99], v[188:191], v[208:211], v[96:99]
	v_mfma_f32_16x16x32_bf16 v[84:87], v[180:183], v[216:219], v[84:87]
	v_mfma_f32_16x16x32_bf16 v[80:83], v[188:191], v[216:219], v[80:83]
	v_mfma_f32_16x16x32_bf16 v[68:71], v[180:183], v[224:227], v[68:71]
	v_mfma_f32_16x16x32_bf16 v[64:67], v[188:191], v[224:227], v[64:67]
	v_mfma_f32_16x16x32_bf16 v[116:119], v[184:187], v[200:203], v[116:119]
	v_mfma_f32_16x16x32_bf16 v[112:115], v[192:195], v[200:203], v[112:115]
	v_mfma_f32_16x16x32_bf16 v[100:103], v[184:187], v[212:215], v[100:103]
	v_mfma_f32_16x16x32_bf16 v[96:99], v[192:195], v[212:215], v[96:99]
	v_mfma_f32_16x16x32_bf16 v[84:87], v[184:187], v[220:223], v[84:87]
	v_mfma_f32_16x16x32_bf16 v[80:83], v[192:195], v[220:223], v[80:83]
	v_mfma_f32_16x16x32_bf16 v[68:71], v[184:187], v[228:231], v[68:71]
	v_mfma_f32_16x16x32_bf16 v[64:67], v[192:195], v[228:231], v[64:67]
	s_setprio 0
	s_barrier
	s_add_i32 s66, s53, s41
	v_lshl_add_u64 v[142:143], s[34:35], 0, v[130:131]
	s_mov_b32 m0, s66
	ds_read_b128 v[196:199], v162 offset:16384
	ds_read_b128 v[200:203], v162 offset:17408
	ds_read_b128 v[208:211], v162 offset:18432
	ds_read_b128 v[212:215], v162 offset:19456
	ds_read_b128 v[216:219], v162 offset:20480
	ds_read_b128 v[220:223], v162 offset:21504
	ds_read_b128 v[224:227], v162 offset:22528
	ds_read_b128 v[228:231], v162 offset:23552
	global_load_lds_dwordx4 v[142:143], off
	s_add_i32 m0, s66, 0x2000
	s_add_u32 s66, s34, 0x40000
	v_lshl_add_u64 v[204:205], s[34:35], 0, v[134:135]
	s_addc_u32 s67, s35, 0
	s_add_i32 s68, s56, s41
	global_load_lds_dwordx4 v[204:205], off
	v_lshl_add_u64 v[232:233], s[66:67], 0, v[130:131]
	s_mov_b32 m0, s68
	v_lshl_add_u64 v[234:235], s[36:37], 0, v[132:133]
	global_load_lds_dwordx4 v[232:233], off
	v_lshl_add_u64 v[232:233], s[66:67], 0, v[134:135]
	s_add_i32 m0, s68, 0x2000
	s_nop 0
	global_load_lds_dwordx4 v[232:233], off
	v_lshl_add_u64 v[232:233], s[36:37], 0, v[128:129]
	s_mov_b32 m0, s29
	s_nop 0
	global_load_lds_dwordx4 v[232:233], off
	s_mov_b32 m0, s43
	s_nop 0
	global_load_lds_dwordx4 v[234:235], off
	s_waitcnt vmcnt(8)
	s_waitcnt lgkmcnt(0)
	s_barrier
	s_setprio 1
	s_waitcnt lgkmcnt(0)
	v_mfma_f32_16x16x32_bf16 v[60:63], v[164:167], v[196:199], v[60:63]
	v_mfma_f32_16x16x32_bf16 v[56:59], v[172:175], v[196:199], v[56:59]
	v_mfma_f32_16x16x32_bf16 v[44:47], v[164:167], v[208:211], v[44:47]
	v_mfma_f32_16x16x32_bf16 v[40:43], v[172:175], v[208:211], v[40:43]
	v_mfma_f32_16x16x32_bf16 v[28:31], v[164:167], v[216:219], v[28:31]
	v_mfma_f32_16x16x32_bf16 v[24:27], v[172:175], v[216:219], v[24:27]
	v_mfma_f32_16x16x32_bf16 v[12:15], v[164:167], v[224:227], v[12:15]
	v_mfma_f32_16x16x32_bf16 v[8:11], v[172:175], v[224:227], v[8:11]
	v_mfma_f32_16x16x32_bf16 v[60:63], v[168:171], v[200:203], v[60:63]
	v_mfma_f32_16x16x32_bf16 v[56:59], v[176:179], v[200:203], v[56:59]
	v_mfma_f32_16x16x32_bf16 v[44:47], v[168:171], v[212:215], v[44:47]
	v_mfma_f32_16x16x32_bf16 v[40:43], v[176:179], v[212:215], v[40:43]
	v_mfma_f32_16x16x32_bf16 v[28:31], v[168:171], v[220:223], v[28:31]
	v_mfma_f32_16x16x32_bf16 v[24:27], v[176:179], v[220:223], v[24:27]
	v_mfma_f32_16x16x32_bf16 v[12:15], v[168:171], v[228:231], v[12:15]
	v_mfma_f32_16x16x32_bf16 v[8:11], v[176:179], v[228:231], v[8:11]
	v_mfma_f32_16x16x32_bf16 v[52:55], v[180:183], v[196:199], v[52:55]
	v_mfma_f32_16x16x32_bf16 v[48:51], v[188:191], v[196:199], v[48:51]
	v_mfma_f32_16x16x32_bf16 v[36:39], v[180:183], v[208:211], v[36:39]
	v_mfma_f32_16x16x32_bf16 v[32:35], v[188:191], v[208:211], v[32:35]
	v_mfma_f32_16x16x32_bf16 v[20:23], v[180:183], v[216:219], v[20:23]
	v_mfma_f32_16x16x32_bf16 v[16:19], v[188:191], v[216:219], v[16:19]
	v_mfma_f32_16x16x32_bf16 v[4:7], v[180:183], v[224:227], v[4:7]
	v_mfma_f32_16x16x32_bf16 v[0:3], v[188:191], v[224:227], v[0:3]
	v_mfma_f32_16x16x32_bf16 v[52:55], v[184:187], v[200:203], v[52:55]
	v_mfma_f32_16x16x32_bf16 v[48:51], v[192:195], v[200:203], v[48:51]
	v_mfma_f32_16x16x32_bf16 v[36:39], v[184:187], v[212:215], v[36:39]
	v_mfma_f32_16x16x32_bf16 v[32:35], v[192:195], v[212:215], v[32:35]
	v_mfma_f32_16x16x32_bf16 v[20:23], v[184:187], v[220:223], v[20:23]
	v_mfma_f32_16x16x32_bf16 v[16:19], v[192:195], v[220:223], v[16:19]
	v_mfma_f32_16x16x32_bf16 v[4:7], v[184:187], v[228:231], v[4:7]
	v_mfma_f32_16x16x32_bf16 v[0:3], v[192:195], v[228:231], v[0:3]
	s_setprio 0
	s_barrier
; #define PG8_STAGE(bufoff, gbase, voff) do { _Pragma("unroll") for (int _i = 0; _i < 2; ++_i) \
;         __builtin_amdgcn_global_load_lds((const unsigned*)((const char*)(gbase) + (voff)[_i]), (PG8_LAS unsigned*)(lds + (bufoff) + ldsw + _i * 8192), 16, 0, 0); } while (0)
; #define PG8_LDA(dst, b, h) do { _Pragma("unroll") for (int m = 0; m < 4; ++m) _Pragma("unroll") for (int k = 0; k < 2; ++k) dst[m][k] = *(const PG8_LAS bf16x8*)(lds + PG8_SA(b, h) + aoff + m * 2048 + k * 1024); } while (0)
; #define PG8_LDB(dst, b, h) do { _Pragma("unroll") for (int n = 0; n < 2; ++n) _Pragma("unroll") for (int k = 0; k < 2; ++k) dst[n][k] = *(const PG8_LAS bf16x8*)(lds + PG8_SB(b, h) + boff + n * 2048 + k * 1024); } while (0)
; #define PG8_MMA(ai, bj, At, Bt) do { __builtin_amdgcn_s_setprio(1); _Pragma("unroll") for (int m = 0; m < 4; ++m) _Pragma("unroll") for (int n = 0; n < 2; ++n) _Pragma("unroll") for (int k = 0; k < 2; ++k) \
;         acc[ai][bj][m][n] = __builtin_amdgcn_mfma_f32_16x16x32_bf16(Bt[n][k], At[m][k], acc[ai][bj][m][n], 0, 0, 0); __builtin_amdgcn_s_setprio(0); } while (0)
; #define PG8_WAIT_V(n) asm volatile("s_waitcnt vmcnt(" #n ")" ::: "memory")
; #define PG8_WAIT_L(n) asm volatile("s_waitcnt lgkmcnt(" #n ")" ::: "memory")
; #define PG8_BAR __builtin_amdgcn_s_barrier()
; #define PG8_SCHED __builtin_amdgcn_sched_barrier(0)
; template <class Epi, class Sched, bool ALIGN_EPI = false, bool SP2 = false>
; __device__ __forceinline__ void gemm_phase(PG8_LAS unsigned char* lds, const Gemm g, const Sched& S, const Epi& E) {
;     ...
;             PG8_LDB(B0, 1, 0); PG8_LDB(B1, 1, 1); PG8_SCHED; PG8_LDA(At, 1, 0); PG8_STAGE(PG8_SA(0, 1), a2 + hstep, voffA);
;             PG8_WAIT_V(8); PG8_WAIT_L(0); PG8_BAR; PG8_MMA(0, 0, At, B0); PG8_MMA(0, 1, At, B1); PG8_BAR; PG8_SCHED;
	s_add_i32 s66, 0, 0x18000
	v_add_u32_e32 v163, s66, v158
	s_add_i32 s67, 0, 0x1c000
	ds_read_b128 v[164:167], v163
	ds_read_b128 v[168:171], v163 offset:1024
	ds_read_b128 v[172:175], v163 offset:2048
	ds_read_b128 v[176:179], v163 offset:3072
	v_add_u32_e32 v163, s67, v158
	ds_read_b128 v[180:183], v163
	ds_read_b128 v[184:187], v163 offset:1024
	ds_read_b128 v[188:191], v163 offset:2048
	ds_read_b128 v[192:195], v163 offset:3072
	s_add_u32 s36, s36, 0x40000
	s_addc_u32 s37, s37, 0
	s_mov_b32 m0, s44
	v_lshl_add_u64 v[236:237], s[36:37], 0, v[128:129]
	ds_read_b128 v[196:199], v162 offset:32768
	ds_read_b128 v[200:203], v162 offset:33792
	ds_read_b128 v[208:211], v162 offset:34816
	ds_read_b128 v[212:215], v162 offset:35840
	ds_read_b128 v[216:219], v162 offset:36864
	ds_read_b128 v[220:223], v162 offset:37888
	ds_read_b128 v[224:227], v162 offset:38912
	ds_read_b128 v[228:231], v162 offset:39936
	global_load_lds_dwordx4 v[236:237], off
	v_lshl_add_u64 v[236:237], s[36:37], 0, v[132:133]
	s_mov_b32 m0, s45
	s_nop 0
	global_load_lds_dwordx4 v[236:237], off
	s_waitcnt vmcnt(8)
	s_waitcnt lgkmcnt(0)
	s_barrier
	s_setprio 1
	s_waitcnt lgkmcnt(0)
	v_mfma_f32_16x16x32_bf16 v[124:127], v[164:167], v[196:199], v[124:127]
	v_mfma_f32_16x16x32_bf16 v[120:123], v[172:175], v[196:199], v[120:123]
	v_mfma_f32_16x16x32_bf16 v[108:111], v[164:167], v[208:211], v[108:111]
	v_mfma_f32_16x16x32_bf16 v[104:107], v[172:175], v[208:211], v[104:107]
	v_mfma_f32_16x16x32_bf16 v[92:95], v[164:167], v[216:219], v[92:95]
	v_mfma_f32_16x16x32_bf16 v[88:91], v[172:175], v[216:219], v[88:91]
	v_mfma_f32_16x16x32_bf16 v[76:79], v[164:167], v[224:227], v[76:79]
	v_mfma_f32_16x16x32_bf16 v[72:75], v[172:175], v[224:227], v[72:75]
	v_mfma_f32_16x16x32_bf16 v[124:127], v[168:171], v[200:203], v[124:127]
	v_mfma_f32_16x16x32_bf16 v[120:123], v[176:179], v[200:203], v[120:123]
	v_mfma_f32_16x16x32_bf16 v[108:111], v[168:171], v[212:215], v[108:111]
	v_mfma_f32_16x16x32_bf16 v[104:107], v[176:179], v[212:215], v[104:107]
	v_mfma_f32_16x16x32_bf16 v[92:95], v[168:171], v[220:223], v[92:95]
	v_mfma_f32_16x16x32_bf16 v[88:91], v[176:179], v[220:223], v[88:91]
	v_mfma_f32_16x16x32_bf16 v[76:79], v[168:171], v[228:231], v[76:79]
	v_mfma_f32_16x16x32_bf16 v[72:75], v[176:179], v[228:231], v[72:75]
	v_mfma_f32_16x16x32_bf16 v[116:119], v[180:183], v[196:199], v[116:119]
	v_mfma_f32_16x16x32_bf16 v[112:115], v[188:191], v[196:199], v[112:115]
	v_mfma_f32_16x16x32_bf16 v[100:103], v[180:183], v[208:211], v[100:103]
	v_mfma_f32_16x16x32_bf16 v[96:99], v[188:191], v[208:211], v[96:99]
	v_mfma_f32_16x16x32_bf16 v[84:87], v[180:183], v[216:219], v[84:87]
	v_mfma_f32_16x16x32_bf16 v[80:83], v[188:191], v[216:219], v[80:83]
	v_mfma_f32_16x16x32_bf16 v[68:71], v[180:183], v[224:227], v[68:71]
	v_mfma_f32_16x16x32_bf16 v[64:67], v[188:191], v[224:227], v[64:67]
	v_mfma_f32_16x16x32_bf16 v[116:119], v[184:187], v[200:203], v[116:119]
	v_mfma_f32_16x16x32_bf16 v[112:115], v[192:195], v[200:203], v[112:115]
	v_mfma_f32_16x16x32_bf16 v[100:103], v[184:187], v[212:215], v[100:103]
	v_mfma_f32_16x16x32_bf16 v[96:99], v[192:195], v[212:215], v[96:99]
	v_mfma_f32_16x16x32_bf16 v[84:87], v[184:187], v[220:223], v[84:87]
	v_mfma_f32_16x16x32_bf16 v[80:83], v[192:195], v[220:223], v[80:83]
	v_mfma_f32_16x16x32_bf16 v[68:71], v[184:187], v[228:231], v[68:71]
	v_mfma_f32_16x16x32_bf16 v[64:67], v[192:195], v[228:231], v[64:67]
	s_setprio 0
	s_barrier
; #define PG8_STAGE(bufoff, gbase, voff) do { _Pragma("unroll") for (int _i = 0; _i < 2; ++_i) \
;         __builtin_amdgcn_global_load_lds((const unsigned*)((const char*)(gbase) + (voff)[_i]), (PG8_LAS unsigned*)(lds + (bufoff) + ldsw + _i * 8192), 16, 0, 0); } while (0)
; #define PG8_LDA(dst, b, h) do { _Pragma("unroll") for (int m = 0; m < 4; ++m) _Pragma("unroll") for (int k = 0; k < 2; ++k) dst[m][k] = *(const PG8_LAS bf16x8*)(lds + PG8_SA(b, h) + aoff + m * 2048 + k * 1024); } while (0)
; #define PG8_MMA(ai, bj, At, Bt) do { __builtin_amdgcn_s_setprio(1); _Pragma("unroll") for (int m = 0; m < 4; ++m) _Pragma("unroll") for (int n = 0; n < 2; ++n) _Pragma("unroll") for (int k = 0; k < 2; ++k) \
;         acc[ai][bj][m][n] = __builtin_amdgcn_mfma_f32_16x16x32_bf16(Bt[n][k], At[m][k], acc[ai][bj][m][n], 0, 0, 0); __builtin_amdgcn_s_setprio(0); } while (0)
; #define PG8_WAIT_V(n) asm volatile("s_waitcnt vmcnt(" #n ")" ::: "memory")
; #define PG8_WAIT_L(n) asm volatile("s_waitcnt lgkmcnt(" #n ")" ::: "memory")
; #define PG8_BAR __builtin_amdgcn_s_barrier()
; #define PG8_SCHED __builtin_amdgcn_sched_barrier(0)
; template <class Epi, class Sched, bool ALIGN_EPI = false, bool SP2 = false>
; __device__ __forceinline__ void gemm_phase(PG8_LAS unsigned char* lds, const Gemm g, const Sched& S, const Epi& E) {
;     ...
;         for (int t = 0; t < nt; t += 2) {
;     ...
;             PG8_LDA(At, 1, 1); PG8_STAGE(PG8_SB(1, 0), b3, voffB); PG8_STAGE(PG8_SB(1, 1), b3 + hstep, voffB); PG8_STAGE(PG8_SA(1, 0), a3, voffA);
;             PG8_WAIT_V(8); PG8_WAIT_L(0); PG8_BAR; PG8_MMA(1, 0, At, B0); PG8_MMA(1, 1, At, B1); PG8_BAR; PG8_SCHED;
	s_add_i32 s36, s66, s41
	v_lshl_add_u64 v[142:143], v[142:143], 0, s[8:9]
	s_mov_b32 m0, s36
	ds_read_b128 v[196:199], v162 offset:49152
	ds_read_b128 v[200:203], v162 offset:50176
	ds_read_b128 v[208:211], v162 offset:51200
	ds_read_b128 v[212:215], v162 offset:52224
	ds_read_b128 v[216:219], v162 offset:53248
	ds_read_b128 v[220:223], v162 offset:54272
	ds_read_b128 v[224:227], v162 offset:55296
	ds_read_b128 v[228:231], v162 offset:56320
	global_load_lds_dwordx4 v[142:143], off
	s_add_i32 m0, s36, 0x2000
	s_add_u32 s34, s34, 0x40080
	v_lshl_add_u64 v[142:143], v[204:205], 0, s[8:9]
	s_addc_u32 s35, s35, 0
	s_add_i32 s36, s67, s41
	global_load_lds_dwordx4 v[142:143], off
	v_lshl_add_u64 v[142:143], s[34:35], 0, v[130:131]
	s_mov_b32 m0, s36
	s_nop 0
	global_load_lds_dwordx4 v[142:143], off
	v_lshl_add_u64 v[142:143], s[34:35], 0, v[134:135]
	s_add_i32 m0, s36, 0x2000
	s_nop 0
	global_load_lds_dwordx4 v[142:143], off
	v_lshl_add_u64 v[142:143], v[232:233], 0, s[8:9]
	s_mov_b32 m0, s47
	s_nop 0
	global_load_lds_dwordx4 v[142:143], off
	v_lshl_add_u64 v[142:143], v[234:235], 0, s[8:9]
	s_mov_b32 m0, s52
	s_nop 0
	global_load_lds_dwordx4 v[142:143], off
	s_waitcnt vmcnt(8)
	s_waitcnt lgkmcnt(0)
	s_barrier
	s_setprio 1
	s_waitcnt lgkmcnt(0)
	v_mfma_f32_16x16x32_bf16 v[60:63], v[164:167], v[196:199], v[60:63]
	v_mfma_f32_16x16x32_bf16 v[56:59], v[172:175], v[196:199], v[56:59]
	v_mfma_f32_16x16x32_bf16 v[44:47], v[164:167], v[208:211], v[44:47]
	v_mfma_f32_16x16x32_bf16 v[40:43], v[172:175], v[208:211], v[40:43]
	v_mfma_f32_16x16x32_bf16 v[28:31], v[164:167], v[216:219], v[28:31]
	v_mfma_f32_16x16x32_bf16 v[24:27], v[172:175], v[216:219], v[24:27]
	v_mfma_f32_16x16x32_bf16 v[12:15], v[164:167], v[224:227], v[12:15]
	v_mfma_f32_16x16x32_bf16 v[8:11], v[172:175], v[224:227], v[8:11]
	v_mfma_f32_16x16x32_bf16 v[60:63], v[168:171], v[200:203], v[60:63]
	v_mfma_f32_16x16x32_bf16 v[56:59], v[176:179], v[200:203], v[56:59]
	v_mfma_f32_16x16x32_bf16 v[44:47], v[168:171], v[212:215], v[44:47]
	v_mfma_f32_16x16x32_bf16 v[40:43], v[176:179], v[212:215], v[40:43]
	v_mfma_f32_16x16x32_bf16 v[28:31], v[168:171], v[220:223], v[28:31]
	v_mfma_f32_16x16x32_bf16 v[24:27], v[176:179], v[220:223], v[24:27]
	v_mfma_f32_16x16x32_bf16 v[12:15], v[168:171], v[228:231], v[12:15]
	v_mfma_f32_16x16x32_bf16 v[8:11], v[176:179], v[228:231], v[8:11]
	v_mfma_f32_16x16x32_bf16 v[52:55], v[180:183], v[196:199], v[52:55]
	v_mfma_f32_16x16x32_bf16 v[48:51], v[188:191], v[196:199], v[48:51]
	v_mfma_f32_16x16x32_bf16 v[36:39], v[180:183], v[208:211], v[36:39]
	v_mfma_f32_16x16x32_bf16 v[32:35], v[188:191], v[208:211], v[32:35]
	v_mfma_f32_16x16x32_bf16 v[20:23], v[180:183], v[216:219], v[20:23]
	v_mfma_f32_16x16x32_bf16 v[16:19], v[188:191], v[216:219], v[16:19]
	v_mfma_f32_16x16x32_bf16 v[4:7], v[180:183], v[224:227], v[4:7]
	v_mfma_f32_16x16x32_bf16 v[0:3], v[188:191], v[224:227], v[0:3]
	v_mfma_f32_16x16x32_bf16 v[52:55], v[184:187], v[200:203], v[52:55]
	v_mfma_f32_16x16x32_bf16 v[48:51], v[192:195], v[200:203], v[48:51]
	v_mfma_f32_16x16x32_bf16 v[36:39], v[184:187], v[212:215], v[36:39]
	v_mfma_f32_16x16x32_bf16 v[32:35], v[192:195], v[212:215], v[32:35]
	v_mfma_f32_16x16x32_bf16 v[20:23], v[184:187], v[220:223], v[20:23]
	v_mfma_f32_16x16x32_bf16 v[16:19], v[192:195], v[220:223], v[16:19]
	v_mfma_f32_16x16x32_bf16 v[4:7], v[184:187], v[228:231], v[4:7]
	v_mfma_f32_16x16x32_bf16 v[0:3], v[192:195], v[228:231], v[0:3]
	s_setprio 0
	s_barrier
	s_add_i32 s65, s65, 2
	s_add_u32 s30, s30, 0x100
	s_addc_u32 s31, s31, 0
	s_add_u32 s61, s61, 0x100
	s_addc_u32 s64, s64, 0
	s_cmp_gt_u32 s65, 13
	s_cbranch_scc0 .LBB0_1809

;     __device__ __forceinline__ bool next(int i, Unit& u) const { if (i != 0) return false; const int c0 = (G >= 8) ? G - 5 : G - 2; int k = -1; if (c == c0) k = 0; else if (c == G - 1) k = 1; if (k < 0 || k >= n) return false; u.pm = k; u.pn = 0; return true; }
; #define PG8_STAGE(bufoff, gbase, voff) do { _Pragma("unroll") for (int _i = 0; _i < 2; ++_i) \
;         __builtin_amdgcn_global_load_lds((const unsigned*)((const char*)(gbase) + (voff)[_i]), (PG8_LAS unsigned*)(lds + (bufoff) + ldsw + _i * 8192), 16, 0, 0); } while (0)
; #define PG8_LDA(dst, b, h) do { _Pragma("unroll") for (int m = 0; m < 4; ++m) _Pragma("unroll") for (int k = 0; k < 2; ++k) dst[m][k] = *(const PG8_LAS bf16x8*)(lds + PG8_SA(b, h) + aoff + m * 2048 + k * 1024); } while (0)
; #define PG8_LDB(dst, b, h) do { _Pragma("unroll") for (int n = 0; n < 2; ++n) _Pragma("unroll") for (int k = 0; k < 2; ++k) dst[n][k] = *(const PG8_LAS bf16x8*)(lds + PG8_SB(b, h) + boff + n * 2048 + k * 1024); } while (0)
; #define PG8_WAIT_V(n) asm volatile("s_waitcnt vmcnt(" #n ")" ::: "memory")
; #define PG8_WAIT_L(n) asm volatile("s_waitcnt lgkmcnt(" #n ")" ::: "memory")
; #define PG8_BAR __builtin_amdgcn_s_barrier()
; #define PG8_SCHED __builtin_amdgcn_sched_barrier(0)
; template <class Epi, class Sched, bool ALIGN_EPI = false, bool SP2 = false>
; __device__ __forceinline__ void gemm_phase(PG8_LAS unsigned char* lds, const Gemm g, const Sched& S, const Epi& E) {
;     ...
;     for (;;) {
;         const bool has_next = S.next(ui + 1, nxt);
;         const char* nA = has_next ? (const char*)g.A + (size_t)nxt.pm * tstep : cA; const char* nB = has_next ? (const char*)g.Bt + (size_t)nxt.pn * tstep : cB;
;         for (int t = 0; t < nt; t += 2) {
;             const bool last = (t == nt - 2);
;             const char* a1 = cA + (size_t)(t + 1) * kstep;
;             const char* a2 = last ? nA : cA + (size_t)(t + 2) * kstep; const char* b2 = last ? nB : cB + (size_t)(t + 2) * kstep;
;             const char* a3 = a2 + kstep; const char* b3 = b2 + kstep;
;             if (last && has_next) S.a_ready(nxt);
;             if constexpr (SP2) {
;             PG8_LDB(B0, 0, 0); PG8_LDB(B1, 0, 1); PG8_SCHED; PG8_LDA(At, 0, 0); PG8_STAGE(PG8_SA(1, 1), a1 + hstep, voffA);
;             PG8_WAIT_V(8); PG8_WAIT_L(0); PG8_BAR; PG8_MMA(0, 0, At, B0); PG8_MMA(0, 1, At, B1); PG8_BAR; PG8_SCHED;
.LBB0_1897:
	v_lshlrev_b32_e32 v11, 2, v153
	v_lshl_or_b32 v129, s15, 6, v153
	v_lshl_or_b32 v10, v153, 6, v154
	s_lshl_b32 s15, s15, 13
	v_and_b32_e32 v11, 32, v11
	s_lshl_b32 s14, s14, 5
	v_bitop3_b32 v10, v10, s15, v11 bitop3:0xde
	s_and_b32 s31, s14, 0x60
	s_mov_b64 s[14:15], 0x80
	s_add_i32 m0, s27, 0x18000
	v_lshl_add_u64 v[6:7], v[6:7], 0, s[14:15]
	s_waitcnt vmcnt(2)
	s_barrier
	global_load_lds_dwordx4 v[6:7], off
	v_lshl_add_u64 v[4:5], v[4:5], 0, s[14:15]
	s_add_i32 m0, s27, 0x1a000
	s_add_i32 s34, s27, 0x8000
	s_add_i32 s35, s27, 0xa000
	global_load_lds_dwordx4 v[4:5], off
	v_lshl_add_u64 v[2:3], v[2:3], 0, s[14:15]
	s_mov_b32 m0, s34
	s_add_u32 s22, s6, 0xb0080
	global_load_lds_dwordx4 v[2:3], off
	v_lshl_add_u64 v[0:1], v[0:1], 0, s[14:15]
	s_mov_b32 m0, s35
	s_addc_u32 s23, s7, 0
	global_load_lds_dwordx4 v[0:1], off
	s_add_i32 m0, s27, 0x1c000
	v_lshl_add_u64 v[0:1], s[22:23], 0, v[138:139]
	global_load_lds_dwordx4 v[0:1], off
	v_lshl_add_u64 v[0:1], s[22:23], 0, v[142:143]
	s_add_i32 m0, s27, 0x1e000
	s_add_u32 s22, s50, s19
	global_load_lds_dwordx4 v[0:1], off
	v_add_u16_e32 v0, v148, v149
	v_lshrrev_b16_e32 v2, 1, v0
	v_lshl_or_b32 v11, s31, 7, v155
	s_waitcnt vmcnt(6)
	v_add_lshl_u32 v0, v9, v2, 1
	v_mov_b32_e32 v1, v139
	s_addc_u32 s23, s51, s18
	s_add_i32 s42, 0, 0x10000
	s_add_i32 s44, 0, 0x14000
	s_add_i32 s46, 0, 0x18000
	s_add_i32 s52, 0, 0x1c000
	v_lshl_add_u64 v[144:145], s[22:23], 0, v[0:1]
	v_add_lshl_u32 v0, v8, v2, 1
	v_add_u32_e32 v131, s42, v11
	v_add_u32_e32 v133, s44, v11
	s_add_i32 s42, s42, s20
	s_add_i32 s44, s44, s20
	v_add_u32_e32 v156, s46, v11
	v_add_u32_e32 v157, s52, v11
	s_add_i32 s46, s46, s20
	s_add_i32 s52, s52, s20
	v_lshl_add_u64 v[146:147], s[22:23], 0, v[0:1]
	s_mov_b32 s36, -2
	s_mov_b64 s[18:19], 0x78b0080
	v_add_u32_e32 v135, 0, v10
	s_add_i32 s37, s27, 0xc000
	s_add_i32 s41, s27, 0xe000
	s_add_i32 s43, s42, 0x2000
	s_add_i32 s45, s44, 0x2000
	s_add_i32 s47, s46, 0x2000
	s_add_i32 s53, s52, 0x2000
	s_barrier
	ds_read_b128 v[158:161], v131
	ds_read_b128 v[162:165], v131 offset:1024
	ds_read_b128 v[166:169], v131 offset:2048
	ds_read_b128 v[170:173], v131 offset:3072
	ds_read_b128 v[174:177], v133
	ds_read_b128 v[178:181], v133 offset:1024
	ds_read_b128 v[182:185], v133 offset:2048
	ds_read_b128 v[186:189], v133 offset:3072
	s_add_u32 s20, s18, 0xf8750080
	s_addc_u32 s21, s19, -1
	s_cmp_lg_u32 s36, 40
	s_cselect_b32 s20, s20, 0
	s_cselect_b32 s21, s21, 0
	s_add_u32 s22, s8, s20
	s_addc_u32 s23, s9, s21
	s_add_u32 s20, s6, s20
	s_addc_u32 s21, s7, s21
	s_mov_b32 m0, s37
	v_lshl_add_u64 v[224:225], v[144:145], 0, s[18:19]
	ds_read_b128 v[190:193], v135
	ds_read_b128 v[194:197], v135 offset:1024
	ds_read_b128 v[198:201], v135 offset:2048
	ds_read_b128 v[202:205], v135 offset:3072
	ds_read_b128 v[208:211], v135 offset:4096
	ds_read_b128 v[212:215], v135 offset:5120
	ds_read_b128 v[216:219], v135 offset:6144
	ds_read_b128 v[220:223], v135 offset:7168
	global_load_lds_dwordx4 v[224:225], off
	v_lshl_add_u64 v[224:225], v[146:147], 0, s[18:19]
	s_mov_b32 m0, s41
	s_nop 0
	global_load_lds_dwordx4 v[224:225], off
	s_waitcnt vmcnt(8)
	s_waitcnt lgkmcnt(0)
	s_barrier
	s_setprio 1
	s_waitcnt lgkmcnt(0)
	v_mfma_f32_16x16x32_bf16 v[124:127], v[158:161], v[190:193], 0
	v_mfma_f32_16x16x32_bf16 v[120:123], v[166:169], v[190:193], 0
	v_mfma_f32_16x16x32_bf16 v[116:119], v[158:161], v[198:201], 0
	v_mfma_f32_16x16x32_bf16 v[112:115], v[166:169], v[198:201], 0
	v_mfma_f32_16x16x32_bf16 v[100:103], v[158:161], v[208:211], 0
	v_mfma_f32_16x16x32_bf16 v[96:99], v[166:169], v[208:211], 0
	v_mfma_f32_16x16x32_bf16 v[84:87], v[158:161], v[216:219], 0
	v_mfma_f32_16x16x32_bf16 v[80:83], v[166:169], v[216:219], 0
	v_mfma_f32_16x16x32_bf16 v[124:127], v[162:165], v[194:197], v[124:127]
	v_mfma_f32_16x16x32_bf16 v[120:123], v[170:173], v[194:197], v[120:123]
	v_mfma_f32_16x16x32_bf16 v[116:119], v[162:165], v[202:205], v[116:119]
	v_mfma_f32_16x16x32_bf16 v[112:115], v[170:173], v[202:205], v[112:115]
	v_mfma_f32_16x16x32_bf16 v[100:103], v[162:165], v[212:215], v[100:103]
	v_mfma_f32_16x16x32_bf16 v[96:99], v[170:173], v[212:215], v[96:99]
	v_mfma_f32_16x16x32_bf16 v[84:87], v[162:165], v[220:223], v[84:87]
	v_mfma_f32_16x16x32_bf16 v[80:83], v[170:173], v[220:223], v[80:83]
	v_mfma_f32_16x16x32_bf16 v[108:111], v[174:177], v[190:193], 0
	v_mfma_f32_16x16x32_bf16 v[104:107], v[182:185], v[190:193], 0
	v_mfma_f32_16x16x32_bf16 v[92:95], v[174:177], v[198:201], 0
	v_mfma_f32_16x16x32_bf16 v[88:91], v[182:185], v[198:201], 0
	v_mfma_f32_16x16x32_bf16 v[76:79], v[174:177], v[208:211], 0
	v_mfma_f32_16x16x32_bf16 v[72:75], v[182:185], v[208:211], 0
	v_mfma_f32_16x16x32_bf16 v[68:71], v[174:177], v[216:219], 0
	v_mfma_f32_16x16x32_bf16 v[64:67], v[182:185], v[216:219], 0
	v_mfma_f32_16x16x32_bf16 v[108:111], v[178:181], v[194:197], v[108:111]
	v_mfma_f32_16x16x32_bf16 v[104:107], v[186:189], v[194:197], v[104:107]
	v_mfma_f32_16x16x32_bf16 v[92:95], v[178:181], v[202:205], v[92:95]
	v_mfma_f32_16x16x32_bf16 v[88:91], v[186:189], v[202:205], v[88:91]
	v_mfma_f32_16x16x32_bf16 v[76:79], v[178:181], v[212:215], v[76:79]
	v_mfma_f32_16x16x32_bf16 v[72:75], v[186:189], v[212:215], v[72:75]
	v_mfma_f32_16x16x32_bf16 v[68:71], v[178:181], v[220:223], v[68:71]
	v_mfma_f32_16x16x32_bf16 v[64:67], v[186:189], v[220:223], v[64:67]
	s_setprio 0
	s_barrier
; #define PG8_STAGE(bufoff, gbase, voff) do { _Pragma("unroll") for (int _i = 0; _i < 2; ++_i) \
;         __builtin_amdgcn_global_load_lds((const unsigned*)((const char*)(gbase) + (voff)[_i]), (PG8_LAS unsigned*)(lds + (bufoff) + ldsw + _i * 8192), 16, 0, 0); } while (0)
; #define PG8_LDA(dst, b, h) do { _Pragma("unroll") for (int m = 0; m < 4; ++m) _Pragma("unroll") for (int k = 0; k < 2; ++k) dst[m][k] = *(const PG8_LAS bf16x8*)(lds + PG8_SA(b, h) + aoff + m * 2048 + k * 1024); } while (0)
; #define PG8_LDB(dst, b, h) do { _Pragma("unroll") for (int n = 0; n < 2; ++n) _Pragma("unroll") for (int k = 0; k < 2; ++k) dst[n][k] = *(const PG8_LAS bf16x8*)(lds + PG8_SB(b, h) + boff + n * 2048 + k * 1024); } while (0)
; #define PG8_MMA(ai, bj, At, Bt) do { __builtin_amdgcn_s_setprio(1); _Pragma("unroll") for (int m = 0; m < 4; ++m) _Pragma("unroll") for (int n = 0; n < 2; ++n) _Pragma("unroll") for (int k = 0; k < 2; ++k) \
;         acc[ai][bj][m][n] = __builtin_amdgcn_mfma_f32_16x16x32_bf16(Bt[n][k], At[m][k], acc[ai][bj][m][n], 0, 0, 0); __builtin_amdgcn_s_setprio(0); } while (0)
; #define PG8_WAIT_V(n) asm volatile("s_waitcnt vmcnt(" #n ")" ::: "memory")
; #define PG8_WAIT_L(n) asm volatile("s_waitcnt lgkmcnt(" #n ")" ::: "memory")
; #define PG8_BAR __builtin_amdgcn_s_barrier()
; #define PG8_SCHED __builtin_amdgcn_sched_barrier(0)
; template <class Epi, class Sched, bool ALIGN_EPI = false, bool SP2 = false>
; __device__ __forceinline__ void gemm_phase(PG8_LAS unsigned char* lds, const Gemm g, const Sched& S, const Epi& E) {
;     ...
;             PG8_LDA(At, 0, 1); PG8_STAGE(PG8_SB(0, 0), b2, voffB); PG8_STAGE(PG8_SB(0, 1), b2 + hstep, voffB); PG8_STAGE(PG8_SA(0, 0), a2, voffA);
;             PG8_WAIT_V(8); PG8_WAIT_L(0); PG8_BAR; PG8_MMA(1, 0, At, B0); PG8_MMA(1, 1, At, B1); PG8_BAR; PG8_SCHED;
;             PG8_LDB(B0, 1, 0); PG8_LDB(B1, 1, 1); PG8_SCHED; PG8_LDA(At, 1, 0); PG8_STAGE(PG8_SA(0, 1), a2 + hstep, voffA);
;             PG8_WAIT_V(8); PG8_WAIT_L(0); PG8_BAR; PG8_MMA(0, 0, At, B0); PG8_MMA(0, 1, At, B1); PG8_BAR; PG8_SCHED;
	s_mov_b32 m0, s42
	v_lshl_add_u64 v[224:225], s[20:21], 0, v[138:139]
	s_add_u32 s56, s20, 0xb0000
	ds_read_b128 v[190:193], v135 offset:16384
	ds_read_b128 v[194:197], v135 offset:17408
	ds_read_b128 v[198:201], v135 offset:18432
	ds_read_b128 v[202:205], v135 offset:19456
	ds_read_b128 v[208:211], v135 offset:20480
	ds_read_b128 v[212:215], v135 offset:21504
	ds_read_b128 v[216:219], v135 offset:22528
	ds_read_b128 v[220:223], v135 offset:23552
	global_load_lds_dwordx4 v[224:225], off
	v_lshl_add_u64 v[226:227], s[20:21], 0, v[142:143]
	s_mov_b32 m0, s43
	s_addc_u32 s57, s21, 0
	global_load_lds_dwordx4 v[226:227], off
	v_lshl_add_u64 v[228:229], s[56:57], 0, v[138:139]
	s_mov_b32 m0, s44
	v_lshl_add_u64 v[230:231], s[22:23], 0, v[140:141]
	global_load_lds_dwordx4 v[228:229], off
	v_lshl_add_u64 v[228:229], s[56:57], 0, v[142:143]
	s_mov_b32 m0, s45
	s_nop 0
	global_load_lds_dwordx4 v[228:229], off
	v_lshl_add_u64 v[228:229], s[22:23], 0, v[136:137]
	s_mov_b32 m0, s27
	s_nop 0
	global_load_lds_dwordx4 v[228:229], off
	s_mov_b32 m0, s28
	s_nop 0
	global_load_lds_dwordx4 v[230:231], off
	s_waitcnt vmcnt(8)
	s_waitcnt lgkmcnt(0)
	s_barrier
	s_setprio 1
	s_waitcnt lgkmcnt(0)
	v_mfma_f32_16x16x32_bf16 v[60:63], v[158:161], v[190:193], 0
	v_mfma_f32_16x16x32_bf16 v[56:59], v[166:169], v[190:193], 0
	v_mfma_f32_16x16x32_bf16 v[52:55], v[158:161], v[198:201], 0
	v_mfma_f32_16x16x32_bf16 v[48:51], v[166:169], v[198:201], 0
	v_mfma_f32_16x16x32_bf16 v[36:39], v[158:161], v[208:211], 0
	v_mfma_f32_16x16x32_bf16 v[32:35], v[166:169], v[208:211], 0
	v_mfma_f32_16x16x32_bf16 v[20:23], v[158:161], v[216:219], 0
	v_mfma_f32_16x16x32_bf16 v[16:19], v[166:169], v[216:219], 0
	v_mfma_f32_16x16x32_bf16 v[60:63], v[162:165], v[194:197], v[60:63]
	v_mfma_f32_16x16x32_bf16 v[56:59], v[170:173], v[194:197], v[56:59]
	v_mfma_f32_16x16x32_bf16 v[52:55], v[162:165], v[202:205], v[52:55]
	v_mfma_f32_16x16x32_bf16 v[48:51], v[170:173], v[202:205], v[48:51]
	v_mfma_f32_16x16x32_bf16 v[36:39], v[162:165], v[212:215], v[36:39]
	v_mfma_f32_16x16x32_bf16 v[32:35], v[170:173], v[212:215], v[32:35]
	v_mfma_f32_16x16x32_bf16 v[20:23], v[162:165], v[220:223], v[20:23]
	v_mfma_f32_16x16x32_bf16 v[16:19], v[170:173], v[220:223], v[16:19]
	v_mfma_f32_16x16x32_bf16 v[44:47], v[174:177], v[190:193], 0
	v_mfma_f32_16x16x32_bf16 v[40:43], v[182:185], v[190:193], 0
	v_mfma_f32_16x16x32_bf16 v[28:31], v[174:177], v[198:201], 0
	v_mfma_f32_16x16x32_bf16 v[24:27], v[182:185], v[198:201], 0
	v_mfma_f32_16x16x32_bf16 v[12:15], v[174:177], v[208:211], 0
	v_mfma_f32_16x16x32_bf16 v[8:11], v[182:185], v[208:211], 0
	v_mfma_f32_16x16x32_bf16 v[4:7], v[174:177], v[216:219], 0
	v_mfma_f32_16x16x32_bf16 v[0:3], v[182:185], v[216:219], 0
	v_mfma_f32_16x16x32_bf16 v[44:47], v[178:181], v[194:197], v[44:47]
	v_mfma_f32_16x16x32_bf16 v[40:43], v[186:189], v[194:197], v[40:43]
	v_mfma_f32_16x16x32_bf16 v[28:31], v[178:181], v[202:205], v[28:31]
	v_mfma_f32_16x16x32_bf16 v[24:27], v[186:189], v[202:205], v[24:27]
	v_mfma_f32_16x16x32_bf16 v[12:15], v[178:181], v[212:215], v[12:15]
	v_mfma_f32_16x16x32_bf16 v[8:11], v[186:189], v[212:215], v[8:11]
	v_mfma_f32_16x16x32_bf16 v[4:7], v[178:181], v[220:223], v[4:7]
	v_mfma_f32_16x16x32_bf16 v[0:3], v[186:189], v[220:223], v[0:3]
	s_setprio 0
	s_barrier
	ds_read_b128 v[158:161], v156
	ds_read_b128 v[162:165], v156 offset:1024
	ds_read_b128 v[166:169], v156 offset:2048
	ds_read_b128 v[170:173], v156 offset:3072
	ds_read_b128 v[174:177], v157
	ds_read_b128 v[178:181], v157 offset:1024
	ds_read_b128 v[182:185], v157 offset:2048
	ds_read_b128 v[186:189], v157 offset:3072
	s_add_u32 s22, s22, 0xb0000
	s_addc_u32 s23, s23, 0
	s_mov_b32 m0, s29
	v_lshl_add_u64 v[232:233], s[22:23], 0, v[136:137]
	ds_read_b128 v[190:193], v135 offset:32768
	ds_read_b128 v[194:197], v135 offset:33792
	ds_read_b128 v[198:201], v135 offset:34816
	ds_read_b128 v[202:205], v135 offset:35840
	ds_read_b128 v[208:211], v135 offset:36864
	ds_read_b128 v[212:215], v135 offset:37888
	ds_read_b128 v[216:219], v135 offset:38912
	ds_read_b128 v[220:223], v135 offset:39936
	global_load_lds_dwordx4 v[232:233], off
	v_lshl_add_u64 v[232:233], s[22:23], 0, v[140:141]
	s_mov_b32 m0, s30
	s_nop 0
	global_load_lds_dwordx4 v[232:233], off
	s_waitcnt vmcnt(8)
	s_waitcnt lgkmcnt(0)
	s_barrier
	s_setprio 1
	s_waitcnt lgkmcnt(0)
	v_mfma_f32_16x16x32_bf16 v[124:127], v[158:161], v[190:193], v[124:127]
	v_mfma_f32_16x16x32_bf16 v[120:123], v[166:169], v[190:193], v[120:123]
	v_mfma_f32_16x16x32_bf16 v[116:119], v[158:161], v[198:201], v[116:119]
	v_mfma_f32_16x16x32_bf16 v[112:115], v[166:169], v[198:201], v[112:115]
	v_mfma_f32_16x16x32_bf16 v[100:103], v[158:161], v[208:211], v[100:103]
	v_mfma_f32_16x16x32_bf16 v[96:99], v[166:169], v[208:211], v[96:99]
	v_mfma_f32_16x16x32_bf16 v[84:87], v[158:161], v[216:219], v[84:87]
	v_mfma_f32_16x16x32_bf16 v[80:83], v[166:169], v[216:219], v[80:83]
	v_mfma_f32_16x16x32_bf16 v[124:127], v[162:165], v[194:197], v[124:127]
	v_mfma_f32_16x16x32_bf16 v[120:123], v[170:173], v[194:197], v[120:123]
	v_mfma_f32_16x16x32_bf16 v[116:119], v[162:165], v[202:205], v[116:119]
	v_mfma_f32_16x16x32_bf16 v[112:115], v[170:173], v[202:205], v[112:115]
	v_mfma_f32_16x16x32_bf16 v[100:103], v[162:165], v[212:215], v[100:103]
	v_mfma_f32_16x16x32_bf16 v[96:99], v[170:173], v[212:215], v[96:99]
	v_mfma_f32_16x16x32_bf16 v[84:87], v[162:165], v[220:223], v[84:87]
	v_mfma_f32_16x16x32_bf16 v[80:83], v[170:173], v[220:223], v[80:83]
	v_mfma_f32_16x16x32_bf16 v[108:111], v[174:177], v[190:193], v[108:111]
	v_mfma_f32_16x16x32_bf16 v[104:107], v[182:185], v[190:193], v[104:107]
	v_mfma_f32_16x16x32_bf16 v[92:95], v[174:177], v[198:201], v[92:95]
	v_mfma_f32_16x16x32_bf16 v[88:91], v[182:185], v[198:201], v[88:91]
	v_mfma_f32_16x16x32_bf16 v[76:79], v[174:177], v[208:211], v[76:79]
	v_mfma_f32_16x16x32_bf16 v[72:75], v[182:185], v[208:211], v[72:75]
	v_mfma_f32_16x16x32_bf16 v[68:71], v[174:177], v[216:219], v[68:71]
	v_mfma_f32_16x16x32_bf16 v[64:67], v[182:185], v[216:219], v[64:67]
	v_mfma_f32_16x16x32_bf16 v[108:111], v[178:181], v[194:197], v[108:111]
	v_mfma_f32_16x16x32_bf16 v[104:107], v[186:189], v[194:197], v[104:107]
	v_mfma_f32_16x16x32_bf16 v[92:95], v[178:181], v[202:205], v[92:95]
	v_mfma_f32_16x16x32_bf16 v[88:91], v[186:189], v[202:205], v[88:91]
	v_mfma_f32_16x16x32_bf16 v[76:79], v[178:181], v[212:215], v[76:79]
	v_mfma_f32_16x16x32_bf16 v[72:75], v[186:189], v[212:215], v[72:75]
	v_mfma_f32_16x16x32_bf16 v[68:71], v[178:181], v[220:223], v[68:71]
	v_mfma_f32_16x16x32_bf16 v[64:67], v[186:189], v[220:223], v[64:67]
	s_setprio 0
	s_barrier
; #define PG8_STAGE(bufoff, gbase, voff) do { _Pragma("unroll") for (int _i = 0; _i < 2; ++_i) \
;         __builtin_amdgcn_global_load_lds((const unsigned*)((const char*)(gbase) + (voff)[_i]), (PG8_LAS unsigned*)(lds + (bufoff) + ldsw + _i * 8192), 16, 0, 0); } while (0)
; #define PG8_LDA(dst, b, h) do { _Pragma("unroll") for (int m = 0; m < 4; ++m) _Pragma("unroll") for (int k = 0; k < 2; ++k) dst[m][k] = *(const PG8_LAS bf16x8*)(lds + PG8_SA(b, h) + aoff + m * 2048 + k * 1024); } while (0)
; #define PG8_LDB(dst, b, h) do { _Pragma("unroll") for (int n = 0; n < 2; ++n) _Pragma("unroll") for (int k = 0; k < 2; ++k) dst[n][k] = *(const PG8_LAS bf16x8*)(lds + PG8_SB(b, h) + boff + n * 2048 + k * 1024); } while (0)
; #define PG8_MMA(ai, bj, At, Bt) do { __builtin_amdgcn_s_setprio(1); _Pragma("unroll") for (int m = 0; m < 4; ++m) _Pragma("unroll") for (int n = 0; n < 2; ++n) _Pragma("unroll") for (int k = 0; k < 2; ++k) \
;         acc[ai][bj][m][n] = __builtin_amdgcn_mfma_f32_16x16x32_bf16(Bt[n][k], At[m][k], acc[ai][bj][m][n], 0, 0, 0); __builtin_amdgcn_s_setprio(0); } while (0)
; #define PG8_WAIT_V(n) asm volatile("s_waitcnt vmcnt(" #n ")" ::: "memory")
; template <class Epi, class Sched, bool ALIGN_EPI = false, bool SP2 = false>
; __device__ __forceinline__ void gemm_phase(PG8_LAS unsigned char* lds, const Gemm g, const Sched& S, const Epi& E) {
;     ...
;             PG8_LDB(B0, 0, 0); PG8_LDB(B1, 0, 1); PG8_SCHED; PG8_LDA(At, 0, 0); PG8_STAGE(PG8_SA(1, 1), a1 + hstep, voffA);
;             PG8_WAIT_V(8); PG8_WAIT_L(0); PG8_BAR; PG8_MMA(0, 0, At, B0); PG8_MMA(0, 1, At, B1); PG8_BAR; PG8_SCHED;
;             PG8_LDA(At, 0, 1); PG8_STAGE(PG8_SB(0, 0), b2, voffB); PG8_STAGE(PG8_SB(0, 1), b2 + hstep, voffB); PG8_STAGE(PG8_SA(0, 0), a2, voffA);
;             PG8_WAIT_V(8); PG8_WAIT_L(0); PG8_BAR; PG8_MMA(1, 0, At, B0); PG8_MMA(1, 1, At, B1); PG8_BAR; PG8_SCHED;
;             PG8_LDB(B0, 1, 0); PG8_LDB(B1, 1, 1); PG8_SCHED; PG8_LDA(At, 1, 0); PG8_STAGE(PG8_SA(0, 1), a2 + hstep, voffA);
;             PG8_WAIT_V(8); PG8_WAIT_L(0); PG8_BAR; PG8_MMA(0, 0, At, B0); PG8_MMA(0, 1, At, B1); PG8_BAR; PG8_SCHED;
;             PG8_LDA(At, 1, 1); PG8_STAGE(PG8_SB(1, 0), b3, voffB); PG8_STAGE(PG8_SB(1, 1), b3 + hstep, voffB); PG8_STAGE(PG8_SA(1, 0), a3, voffA);
;             PG8_WAIT_V(8); PG8_WAIT_L(0); PG8_BAR; PG8_MMA(1, 0, At, B0); PG8_MMA(1, 1, At, B1); PG8_BAR; PG8_SCHED;
	s_mov_b32 m0, s46
	v_lshl_add_u64 v[224:225], v[224:225], 0, s[14:15]
	s_add_u32 s20, s20, 0xb0080
	ds_read_b128 v[190:193], v135 offset:49152
	ds_read_b128 v[194:197], v135 offset:50176
	ds_read_b128 v[198:201], v135 offset:51200
	ds_read_b128 v[202:205], v135 offset:52224
	ds_read_b128 v[208:211], v135 offset:53248
	ds_read_b128 v[212:215], v135 offset:54272
	ds_read_b128 v[216:219], v135 offset:55296
	ds_read_b128 v[220:223], v135 offset:56320
	global_load_lds_dwordx4 v[224:225], off
	v_lshl_add_u64 v[224:225], v[226:227], 0, s[14:15]
	s_mov_b32 m0, s47
	s_addc_u32 s21, s21, 0
	global_load_lds_dwordx4 v[224:225], off
	v_lshl_add_u64 v[224:225], s[20:21], 0, v[138:139]
	s_mov_b32 m0, s52
	s_nop 0
	global_load_lds_dwordx4 v[224:225], off
	v_lshl_add_u64 v[224:225], s[20:21], 0, v[142:143]
	s_mov_b32 m0, s53
	s_nop 0
	global_load_lds_dwordx4 v[224:225], off
	v_lshl_add_u64 v[224:225], v[228:229], 0, s[14:15]
	s_mov_b32 m0, s34
	s_nop 0
	global_load_lds_dwordx4 v[224:225], off
	v_lshl_add_u64 v[224:225], v[230:231], 0, s[14:15]
	s_mov_b32 m0, s35
	s_nop 0
	global_load_lds_dwordx4 v[224:225], off
	s_waitcnt vmcnt(8)
	s_waitcnt lgkmcnt(0)
	s_barrier
	s_setprio 1
	s_waitcnt lgkmcnt(0)
	v_mfma_f32_16x16x32_bf16 v[60:63], v[158:161], v[190:193], v[60:63]
	v_mfma_f32_16x16x32_bf16 v[56:59], v[166:169], v[190:193], v[56:59]
	v_mfma_f32_16x16x32_bf16 v[52:55], v[158:161], v[198:201], v[52:55]
	v_mfma_f32_16x16x32_bf16 v[48:51], v[166:169], v[198:201], v[48:51]
	v_mfma_f32_16x16x32_bf16 v[36:39], v[158:161], v[208:211], v[36:39]
	v_mfma_f32_16x16x32_bf16 v[32:35], v[166:169], v[208:211], v[32:35]
	v_mfma_f32_16x16x32_bf16 v[20:23], v[158:161], v[216:219], v[20:23]
	v_mfma_f32_16x16x32_bf16 v[16:19], v[166:169], v[216:219], v[16:19]
	v_mfma_f32_16x16x32_bf16 v[60:63], v[162:165], v[194:197], v[60:63]
	v_mfma_f32_16x16x32_bf16 v[56:59], v[170:173], v[194:197], v[56:59]
	v_mfma_f32_16x16x32_bf16 v[52:55], v[162:165], v[202:205], v[52:55]
	v_mfma_f32_16x16x32_bf16 v[48:51], v[170:173], v[202:205], v[48:51]
	v_mfma_f32_16x16x32_bf16 v[36:39], v[162:165], v[212:215], v[36:39]
	v_mfma_f32_16x16x32_bf16 v[32:35], v[170:173], v[212:215], v[32:35]
	v_mfma_f32_16x16x32_bf16 v[20:23], v[162:165], v[220:223], v[20:23]
	v_mfma_f32_16x16x32_bf16 v[16:19], v[170:173], v[220:223], v[16:19]
	v_mfma_f32_16x16x32_bf16 v[44:47], v[174:177], v[190:193], v[44:47]
	v_mfma_f32_16x16x32_bf16 v[40:43], v[182:185], v[190:193], v[40:43]
	v_mfma_f32_16x16x32_bf16 v[28:31], v[174:177], v[198:201], v[28:31]
	v_mfma_f32_16x16x32_bf16 v[24:27], v[182:185], v[198:201], v[24:27]
	v_mfma_f32_16x16x32_bf16 v[12:15], v[174:177], v[208:211], v[12:15]
	v_mfma_f32_16x16x32_bf16 v[8:11], v[182:185], v[208:211], v[8:11]
	v_mfma_f32_16x16x32_bf16 v[4:7], v[174:177], v[216:219], v[4:7]
	v_mfma_f32_16x16x32_bf16 v[0:3], v[182:185], v[216:219], v[0:3]
	v_mfma_f32_16x16x32_bf16 v[44:47], v[178:181], v[194:197], v[44:47]
	v_mfma_f32_16x16x32_bf16 v[40:43], v[186:189], v[194:197], v[40:43]
	v_mfma_f32_16x16x32_bf16 v[28:31], v[178:181], v[202:205], v[28:31]
	v_mfma_f32_16x16x32_bf16 v[24:27], v[186:189], v[202:205], v[24:27]
	v_mfma_f32_16x16x32_bf16 v[12:15], v[178:181], v[212:215], v[12:15]
	v_mfma_f32_16x16x32_bf16 v[8:11], v[186:189], v[212:215], v[8:11]
	v_mfma_f32_16x16x32_bf16 v[4:7], v[178:181], v[220:223], v[4:7]
	v_mfma_f32_16x16x32_bf16 v[0:3], v[186:189], v[220:223], v[0:3]
	s_setprio 0
	s_barrier
	s_add_i32 s36, s36, 2
	s_add_u32 s18, s18, 0x100
	s_addc_u32 s19, s19, 0
	s_cmp_gt_u32 s36, 41
	s_cbranch_scc0 .LBB0_1898
	s_branch .Lpeel_exit_14
.LBB0_1898:
	ds_read_b128 v[158:161], v131
	ds_read_b128 v[162:165], v131 offset:1024
	ds_read_b128 v[166:169], v131 offset:2048
	ds_read_b128 v[170:173], v131 offset:3072
	ds_read_b128 v[174:177], v133
	ds_read_b128 v[178:181], v133 offset:1024
	ds_read_b128 v[182:185], v133 offset:2048
	ds_read_b128 v[186:189], v133 offset:3072
	s_add_u32 s20, s18, 0xf8750080
	s_addc_u32 s21, s19, -1
	s_cmp_lg_u32 s36, 40
	s_cselect_b32 s20, s20, 0
	s_cselect_b32 s21, s21, 0
	s_add_u32 s22, s8, s20
	s_addc_u32 s23, s9, s21
	s_add_u32 s20, s6, s20
	s_addc_u32 s21, s7, s21
	s_mov_b32 m0, s37
	v_lshl_add_u64 v[224:225], v[144:145], 0, s[18:19]
	ds_read_b128 v[190:193], v135
	ds_read_b128 v[194:197], v135 offset:1024
	ds_read_b128 v[198:201], v135 offset:2048
	ds_read_b128 v[202:205], v135 offset:3072
	ds_read_b128 v[208:211], v135 offset:4096
	ds_read_b128 v[212:215], v135 offset:5120
	ds_read_b128 v[216:219], v135 offset:6144
	ds_read_b128 v[220:223], v135 offset:7168
	global_load_lds_dwordx4 v[224:225], off
	v_lshl_add_u64 v[224:225], v[146:147], 0, s[18:19]
	s_mov_b32 m0, s41
	s_nop 0
	global_load_lds_dwordx4 v[224:225], off
	s_waitcnt vmcnt(8)
	s_waitcnt lgkmcnt(0)
	s_barrier
; #define PG8_STAGE(bufoff, gbase, voff) do { _Pragma("unroll") for (int _i = 0; _i < 2; ++_i) \
;         __builtin_amdgcn_global_load_lds((const unsigned*)((const char*)(gbase) + (voff)[_i]), (PG8_LAS unsigned*)(lds + (bufoff) + ldsw + _i * 8192), 16, 0, 0); } while (0)
; #define PG8_LDA(dst, b, h) do { _Pragma("unroll") for (int m = 0; m < 4; ++m) _Pragma("unroll") for (int k = 0; k < 2; ++k) dst[m][k] = *(const PG8_LAS bf16x8*)(lds + PG8_SA(b, h) + aoff + m * 2048 + k * 1024); } while (0)
; #define PG8_MMA(ai, bj, At, Bt) do { __builtin_amdgcn_s_setprio(1); _Pragma("unroll") for (int m = 0; m < 4; ++m) _Pragma("unroll") for (int n = 0; n < 2; ++n) _Pragma("unroll") for (int k = 0; k < 2; ++k) \
;         acc[ai][bj][m][n] = __builtin_amdgcn_mfma_f32_16x16x32_bf16(Bt[n][k], At[m][k], acc[ai][bj][m][n], 0, 0, 0); __builtin_amdgcn_s_setprio(0); } while (0)
; #define PG8_WAIT_V(n) asm volatile("s_waitcnt vmcnt(" #n ")" ::: "memory")
; #define PG8_WAIT_L(n) asm volatile("s_waitcnt lgkmcnt(" #n ")" ::: "memory")
; #define PG8_BAR __builtin_amdgcn_s_barrier()
; #define PG8_SCHED __builtin_amdgcn_sched_barrier(0)
; template <class Epi, class Sched, bool ALIGN_EPI = false, bool SP2 = false>
; __device__ __forceinline__ void gemm_phase(PG8_LAS unsigned char* lds, const Gemm g, const Sched& S, const Epi& E) {
;     ...
;             PG8_WAIT_V(8); PG8_WAIT_L(0); PG8_BAR; PG8_MMA(0, 0, At, B0); PG8_MMA(0, 1, At, B1); PG8_BAR; PG8_SCHED;
;             PG8_LDA(At, 0, 1); PG8_STAGE(PG8_SB(0, 0), b2, voffB); PG8_STAGE(PG8_SB(0, 1), b2 + hstep, voffB); PG8_STAGE(PG8_SA(0, 0), a2, voffA);
;             PG8_WAIT_V(8); PG8_WAIT_L(0); PG8_BAR; PG8_MMA(1, 0, At, B0); PG8_MMA(1, 1, At, B1); PG8_BAR; PG8_SCHED;
	s_setprio 1
	s_waitcnt lgkmcnt(0)
	v_mfma_f32_16x16x32_bf16 v[124:127], v[158:161], v[190:193], v[124:127]
	v_mfma_f32_16x16x32_bf16 v[120:123], v[166:169], v[190:193], v[120:123]
	v_mfma_f32_16x16x32_bf16 v[116:119], v[158:161], v[198:201], v[116:119]
	v_mfma_f32_16x16x32_bf16 v[112:115], v[166:169], v[198:201], v[112:115]
	v_mfma_f32_16x16x32_bf16 v[100:103], v[158:161], v[208:211], v[100:103]
	v_mfma_f32_16x16x32_bf16 v[96:99], v[166:169], v[208:211], v[96:99]
	v_mfma_f32_16x16x32_bf16 v[84:87], v[158:161], v[216:219], v[84:87]
	v_mfma_f32_16x16x32_bf16 v[80:83], v[166:169], v[216:219], v[80:83]
	v_mfma_f32_16x16x32_bf16 v[124:127], v[162:165], v[194:197], v[124:127]
	v_mfma_f32_16x16x32_bf16 v[120:123], v[170:173], v[194:197], v[120:123]
	v_mfma_f32_16x16x32_bf16 v[116:119], v[162:165], v[202:205], v[116:119]
	v_mfma_f32_16x16x32_bf16 v[112:115], v[170:173], v[202:205], v[112:115]
	v_mfma_f32_16x16x32_bf16 v[100:103], v[162:165], v[212:215], v[100:103]
	v_mfma_f32_16x16x32_bf16 v[96:99], v[170:173], v[212:215], v[96:99]
	v_mfma_f32_16x16x32_bf16 v[84:87], v[162:165], v[220:223], v[84:87]
	v_mfma_f32_16x16x32_bf16 v[80:83], v[170:173], v[220:223], v[80:83]
	v_mfma_f32_16x16x32_bf16 v[108:111], v[174:177], v[190:193], v[108:111]
	v_mfma_f32_16x16x32_bf16 v[104:107], v[182:185], v[190:193], v[104:107]
	v_mfma_f32_16x16x32_bf16 v[92:95], v[174:177], v[198:201], v[92:95]
	v_mfma_f32_16x16x32_bf16 v[88:91], v[182:185], v[198:201], v[88:91]
	v_mfma_f32_16x16x32_bf16 v[76:79], v[174:177], v[208:211], v[76:79]
	v_mfma_f32_16x16x32_bf16 v[72:75], v[182:185], v[208:211], v[72:75]
	v_mfma_f32_16x16x32_bf16 v[68:71], v[174:177], v[216:219], v[68:71]
	v_mfma_f32_16x16x32_bf16 v[64:67], v[182:185], v[216:219], v[64:67]
	v_mfma_f32_16x16x32_bf16 v[108:111], v[178:181], v[194:197], v[108:111]
	v_mfma_f32_16x16x32_bf16 v[104:107], v[186:189], v[194:197], v[104:107]
	v_mfma_f32_16x16x32_bf16 v[92:95], v[178:181], v[202:205], v[92:95]
	v_mfma_f32_16x16x32_bf16 v[88:91], v[186:189], v[202:205], v[88:91]
	v_mfma_f32_16x16x32_bf16 v[76:79], v[178:181], v[212:215], v[76:79]
	v_mfma_f32_16x16x32_bf16 v[72:75], v[186:189], v[212:215], v[72:75]
	v_mfma_f32_16x16x32_bf16 v[68:71], v[178:181], v[220:223], v[68:71]
	v_mfma_f32_16x16x32_bf16 v[64:67], v[186:189], v[220:223], v[64:67]
	s_setprio 0
	s_barrier
	s_mov_b32 m0, s42
	v_lshl_add_u64 v[224:225], s[20:21], 0, v[138:139]
	s_add_u32 s56, s20, 0xb0000
	ds_read_b128 v[190:193], v135 offset:16384
	ds_read_b128 v[194:197], v135 offset:17408
	ds_read_b128 v[198:201], v135 offset:18432
	ds_read_b128 v[202:205], v135 offset:19456
	ds_read_b128 v[208:211], v135 offset:20480
	ds_read_b128 v[212:215], v135 offset:21504
	ds_read_b128 v[216:219], v135 offset:22528
	ds_read_b128 v[220:223], v135 offset:23552
	global_load_lds_dwordx4 v[224:225], off
	v_lshl_add_u64 v[226:227], s[20:21], 0, v[142:143]
	s_mov_b32 m0, s43
	s_addc_u32 s57, s21, 0
	global_load_lds_dwordx4 v[226:227], off
	v_lshl_add_u64 v[228:229], s[56:57], 0, v[138:139]
	s_mov_b32 m0, s44
	v_lshl_add_u64 v[230:231], s[22:23], 0, v[140:141]
	global_load_lds_dwordx4 v[228:229], off
	v_lshl_add_u64 v[228:229], s[56:57], 0, v[142:143]
	s_mov_b32 m0, s45
	s_nop 0
	global_load_lds_dwordx4 v[228:229], off
	v_lshl_add_u64 v[228:229], s[22:23], 0, v[136:137]
	s_mov_b32 m0, s27
	s_nop 0
	global_load_lds_dwordx4 v[228:229], off
	s_mov_b32 m0, s28
	s_nop 0
	global_load_lds_dwordx4 v[230:231], off
	s_waitcnt vmcnt(8)
	s_waitcnt lgkmcnt(0)
	s_barrier
	s_setprio 1
	s_waitcnt lgkmcnt(0)
	v_mfma_f32_16x16x32_bf16 v[60:63], v[158:161], v[190:193], v[60:63]
	v_mfma_f32_16x16x32_bf16 v[56:59], v[166:169], v[190:193], v[56:59]
	v_mfma_f32_16x16x32_bf16 v[52:55], v[158:161], v[198:201], v[52:55]
	v_mfma_f32_16x16x32_bf16 v[48:51], v[166:169], v[198:201], v[48:51]
	v_mfma_f32_16x16x32_bf16 v[36:39], v[158:161], v[208:211], v[36:39]
	v_mfma_f32_16x16x32_bf16 v[32:35], v[166:169], v[208:211], v[32:35]
	v_mfma_f32_16x16x32_bf16 v[20:23], v[158:161], v[216:219], v[20:23]
	v_mfma_f32_16x16x32_bf16 v[16:19], v[166:169], v[216:219], v[16:19]
	v_mfma_f32_16x16x32_bf16 v[60:63], v[162:165], v[194:197], v[60:63]
	v_mfma_f32_16x16x32_bf16 v[56:59], v[170:173], v[194:197], v[56:59]
	v_mfma_f32_16x16x32_bf16 v[52:55], v[162:165], v[202:205], v[52:55]
	v_mfma_f32_16x16x32_bf16 v[48:51], v[170:173], v[202:205], v[48:51]
	v_mfma_f32_16x16x32_bf16 v[36:39], v[162:165], v[212:215], v[36:39]
	v_mfma_f32_16x16x32_bf16 v[32:35], v[170:173], v[212:215], v[32:35]
	v_mfma_f32_16x16x32_bf16 v[20:23], v[162:165], v[220:223], v[20:23]
	v_mfma_f32_16x16x32_bf16 v[16:19], v[170:173], v[220:223], v[16:19]
	v_mfma_f32_16x16x32_bf16 v[44:47], v[174:177], v[190:193], v[44:47]
	v_mfma_f32_16x16x32_bf16 v[40:43], v[182:185], v[190:193], v[40:43]
	v_mfma_f32_16x16x32_bf16 v[28:31], v[174:177], v[198:201], v[28:31]
	v_mfma_f32_16x16x32_bf16 v[24:27], v[182:185], v[198:201], v[24:27]
	v_mfma_f32_16x16x32_bf16 v[12:15], v[174:177], v[208:211], v[12:15]
	v_mfma_f32_16x16x32_bf16 v[8:11], v[182:185], v[208:211], v[8:11]
	v_mfma_f32_16x16x32_bf16 v[4:7], v[174:177], v[216:219], v[4:7]
	v_mfma_f32_16x16x32_bf16 v[0:3], v[182:185], v[216:219], v[0:3]
	v_mfma_f32_16x16x32_bf16 v[44:47], v[178:181], v[194:197], v[44:47]
	v_mfma_f32_16x16x32_bf16 v[40:43], v[186:189], v[194:197], v[40:43]
	v_mfma_f32_16x16x32_bf16 v[28:31], v[178:181], v[202:205], v[28:31]
	v_mfma_f32_16x16x32_bf16 v[24:27], v[186:189], v[202:205], v[24:27]
	v_mfma_f32_16x16x32_bf16 v[12:15], v[178:181], v[212:215], v[12:15]
	v_mfma_f32_16x16x32_bf16 v[8:11], v[186:189], v[212:215], v[8:11]
	v_mfma_f32_16x16x32_bf16 v[4:7], v[178:181], v[220:223], v[4:7]
	v_mfma_f32_16x16x32_bf16 v[0:3], v[186:189], v[220:223], v[0:3]
	s_setprio 0
	s_barrier
; #define PG8_STAGE(bufoff, gbase, voff) do { _Pragma("unroll") for (int _i = 0; _i < 2; ++_i) \
;         __builtin_amdgcn_global_load_lds((const unsigned*)((const char*)(gbase) + (voff)[_i]), (PG8_LAS unsigned*)(lds + (bufoff) + ldsw + _i * 8192), 16, 0, 0); } while (0)
; #define PG8_LDA(dst, b, h) do { _Pragma("unroll") for (int m = 0; m < 4; ++m) _Pragma("unroll") for (int k = 0; k < 2; ++k) dst[m][k] = *(const PG8_LAS bf16x8*)(lds + PG8_SA(b, h) + aoff + m * 2048 + k * 1024); } while (0)
; #define PG8_LDB(dst, b, h) do { _Pragma("unroll") for (int n = 0; n < 2; ++n) _Pragma("unroll") for (int k = 0; k < 2; ++k) dst[n][k] = *(const PG8_LAS bf16x8*)(lds + PG8_SB(b, h) + boff + n * 2048 + k * 1024); } while (0)
; #define PG8_MMA(ai, bj, At, Bt) do { __builtin_amdgcn_s_setprio(1); _Pragma("unroll") for (int m = 0; m < 4; ++m) _Pragma("unroll") for (int n = 0; n < 2; ++n) _Pragma("unroll") for (int k = 0; k < 2; ++k) \
;         acc[ai][bj][m][n] = __builtin_amdgcn_mfma_f32_16x16x32_bf16(Bt[n][k], At[m][k], acc[ai][bj][m][n], 0, 0, 0); __builtin_amdgcn_s_setprio(0); } while (0)
; #define PG8_WAIT_V(n) asm volatile("s_waitcnt vmcnt(" #n ")" ::: "memory")
; #define PG8_WAIT_L(n) asm volatile("s_waitcnt lgkmcnt(" #n ")" ::: "memory")
; #define PG8_BAR __builtin_amdgcn_s_barrier()
; #define PG8_SCHED __builtin_amdgcn_sched_barrier(0)
; template <class Epi, class Sched, bool ALIGN_EPI = false, bool SP2 = false>
; __device__ __forceinline__ void gemm_phase(PG8_LAS unsigned char* lds, const Gemm g, const Sched& S, const Epi& E) {
;     ...
;             PG8_LDB(B0, 1, 0); PG8_LDB(B1, 1, 1); PG8_SCHED; PG8_LDA(At, 1, 0); PG8_STAGE(PG8_SA(0, 1), a2 + hstep, voffA);
;             PG8_WAIT_V(8); PG8_WAIT_L(0); PG8_BAR; PG8_MMA(0, 0, At, B0); PG8_MMA(0, 1, At, B1); PG8_BAR; PG8_SCHED;
;             PG8_LDA(At, 1, 1); PG8_STAGE(PG8_SB(1, 0), b3, voffB); PG8_STAGE(PG8_SB(1, 1), b3 + hstep, voffB); PG8_STAGE(PG8_SA(1, 0), a3, voffA);
;             PG8_WAIT_V(8); PG8_WAIT_L(0); PG8_BAR; PG8_MMA(1, 0, At, B0); PG8_MMA(1, 1, At, B1); PG8_BAR; PG8_SCHED;
	ds_read_b128 v[158:161], v156
	ds_read_b128 v[162:165], v156 offset:1024
	ds_read_b128 v[166:169], v156 offset:2048
	ds_read_b128 v[170:173], v156 offset:3072
	ds_read_b128 v[174:177], v157
	ds_read_b128 v[178:181], v157 offset:1024
	ds_read_b128 v[182:185], v157 offset:2048
	ds_read_b128 v[186:189], v157 offset:3072
	s_add_u32 s22, s22, 0xb0000
	s_addc_u32 s23, s23, 0
	s_mov_b32 m0, s29
	v_lshl_add_u64 v[232:233], s[22:23], 0, v[136:137]
	ds_read_b128 v[190:193], v135 offset:32768
	ds_read_b128 v[194:197], v135 offset:33792
	ds_read_b128 v[198:201], v135 offset:34816
	ds_read_b128 v[202:205], v135 offset:35840
	ds_read_b128 v[208:211], v135 offset:36864
	ds_read_b128 v[212:215], v135 offset:37888
	ds_read_b128 v[216:219], v135 offset:38912
	ds_read_b128 v[220:223], v135 offset:39936
	global_load_lds_dwordx4 v[232:233], off
	v_lshl_add_u64 v[232:233], s[22:23], 0, v[140:141]
	s_mov_b32 m0, s30
	s_nop 0
	global_load_lds_dwordx4 v[232:233], off
	s_waitcnt vmcnt(8)
	s_waitcnt lgkmcnt(0)
	s_barrier
	s_setprio 1
	s_waitcnt lgkmcnt(0)
	v_mfma_f32_16x16x32_bf16 v[124:127], v[158:161], v[190:193], v[124:127]
	v_mfma_f32_16x16x32_bf16 v[120:123], v[166:169], v[190:193], v[120:123]
	v_mfma_f32_16x16x32_bf16 v[116:119], v[158:161], v[198:201], v[116:119]
	v_mfma_f32_16x16x32_bf16 v[112:115], v[166:169], v[198:201], v[112:115]
	v_mfma_f32_16x16x32_bf16 v[100:103], v[158:161], v[208:211], v[100:103]
	v_mfma_f32_16x16x32_bf16 v[96:99], v[166:169], v[208:211], v[96:99]
	v_mfma_f32_16x16x32_bf16 v[84:87], v[158:161], v[216:219], v[84:87]
	v_mfma_f32_16x16x32_bf16 v[80:83], v[166:169], v[216:219], v[80:83]
	v_mfma_f32_16x16x32_bf16 v[124:127], v[162:165], v[194:197], v[124:127]
	v_mfma_f32_16x16x32_bf16 v[120:123], v[170:173], v[194:197], v[120:123]
	v_mfma_f32_16x16x32_bf16 v[116:119], v[162:165], v[202:205], v[116:119]
	v_mfma_f32_16x16x32_bf16 v[112:115], v[170:173], v[202:205], v[112:115]
	v_mfma_f32_16x16x32_bf16 v[100:103], v[162:165], v[212:215], v[100:103]
	v_mfma_f32_16x16x32_bf16 v[96:99], v[170:173], v[212:215], v[96:99]
	v_mfma_f32_16x16x32_bf16 v[84:87], v[162:165], v[220:223], v[84:87]
	v_mfma_f32_16x16x32_bf16 v[80:83], v[170:173], v[220:223], v[80:83]
	v_mfma_f32_16x16x32_bf16 v[108:111], v[174:177], v[190:193], v[108:111]
	v_mfma_f32_16x16x32_bf16 v[104:107], v[182:185], v[190:193], v[104:107]
	v_mfma_f32_16x16x32_bf16 v[92:95], v[174:177], v[198:201], v[92:95]
	v_mfma_f32_16x16x32_bf16 v[88:91], v[182:185], v[198:201], v[88:91]
	v_mfma_f32_16x16x32_bf16 v[76:79], v[174:177], v[208:211], v[76:79]
	v_mfma_f32_16x16x32_bf16 v[72:75], v[182:185], v[208:211], v[72:75]
	v_mfma_f32_16x16x32_bf16 v[68:71], v[174:177], v[216:219], v[68:71]
	v_mfma_f32_16x16x32_bf16 v[64:67], v[182:185], v[216:219], v[64:67]
	v_mfma_f32_16x16x32_bf16 v[108:111], v[178:181], v[194:197], v[108:111]
	v_mfma_f32_16x16x32_bf16 v[104:107], v[186:189], v[194:197], v[104:107]
	v_mfma_f32_16x16x32_bf16 v[92:95], v[178:181], v[202:205], v[92:95]
	v_mfma_f32_16x16x32_bf16 v[88:91], v[186:189], v[202:205], v[88:91]
	v_mfma_f32_16x16x32_bf16 v[76:79], v[178:181], v[212:215], v[76:79]
	v_mfma_f32_16x16x32_bf16 v[72:75], v[186:189], v[212:215], v[72:75]
	v_mfma_f32_16x16x32_bf16 v[68:71], v[178:181], v[220:223], v[68:71]
	v_mfma_f32_16x16x32_bf16 v[64:67], v[186:189], v[220:223], v[64:67]
	s_setprio 0
	s_barrier
	s_mov_b32 m0, s46
	v_lshl_add_u64 v[224:225], v[224:225], 0, s[14:15]
	s_add_u32 s20, s20, 0xb0080
	ds_read_b128 v[190:193], v135 offset:49152
	ds_read_b128 v[194:197], v135 offset:50176
	ds_read_b128 v[198:201], v135 offset:51200
	ds_read_b128 v[202:205], v135 offset:52224
	ds_read_b128 v[208:211], v135 offset:53248
	ds_read_b128 v[212:215], v135 offset:54272
	ds_read_b128 v[216:219], v135 offset:55296
	ds_read_b128 v[220:223], v135 offset:56320
	global_load_lds_dwordx4 v[224:225], off
	v_lshl_add_u64 v[224:225], v[226:227], 0, s[14:15]
	s_mov_b32 m0, s47
	s_addc_u32 s21, s21, 0
	global_load_lds_dwordx4 v[224:225], off
	v_lshl_add_u64 v[224:225], s[20:21], 0, v[138:139]
	s_mov_b32 m0, s52
	s_nop 0
	global_load_lds_dwordx4 v[224:225], off
	v_lshl_add_u64 v[224:225], s[20:21], 0, v[142:143]
	s_mov_b32 m0, s53
	s_nop 0
	global_load_lds_dwordx4 v[224:225], off
	v_lshl_add_u64 v[224:225], v[228:229], 0, s[14:15]
	s_mov_b32 m0, s34
	s_nop 0
	global_load_lds_dwordx4 v[224:225], off
	v_lshl_add_u64 v[224:225], v[230:231], 0, s[14:15]
	s_mov_b32 m0, s35
	s_nop 0
	global_load_lds_dwordx4 v[224:225], off
	s_waitcnt vmcnt(8)
	s_waitcnt lgkmcnt(0)
	s_barrier
	s_setprio 1
	s_waitcnt lgkmcnt(0)
	v_mfma_f32_16x16x32_bf16 v[60:63], v[158:161], v[190:193], v[60:63]
	v_mfma_f32_16x16x32_bf16 v[56:59], v[166:169], v[190:193], v[56:59]
	v_mfma_f32_16x16x32_bf16 v[52:55], v[158:161], v[198:201], v[52:55]
	v_mfma_f32_16x16x32_bf16 v[48:51], v[166:169], v[198:201], v[48:51]
	v_mfma_f32_16x16x32_bf16 v[36:39], v[158:161], v[208:211], v[36:39]
	v_mfma_f32_16x16x32_bf16 v[32:35], v[166:169], v[208:211], v[32:35]
	v_mfma_f32_16x16x32_bf16 v[20:23], v[158:161], v[216:219], v[20:23]
	v_mfma_f32_16x16x32_bf16 v[16:19], v[166:169], v[216:219], v[16:19]
	v_mfma_f32_16x16x32_bf16 v[60:63], v[162:165], v[194:197], v[60:63]
	v_mfma_f32_16x16x32_bf16 v[56:59], v[170:173], v[194:197], v[56:59]
	v_mfma_f32_16x16x32_bf16 v[52:55], v[162:165], v[202:205], v[52:55]
	v_mfma_f32_16x16x32_bf16 v[48:51], v[170:173], v[202:205], v[48:51]
	v_mfma_f32_16x16x32_bf16 v[36:39], v[162:165], v[212:215], v[36:39]
	v_mfma_f32_16x16x32_bf16 v[32:35], v[170:173], v[212:215], v[32:35]
	v_mfma_f32_16x16x32_bf16 v[20:23], v[162:165], v[220:223], v[20:23]
	v_mfma_f32_16x16x32_bf16 v[16:19], v[170:173], v[220:223], v[16:19]
	v_mfma_f32_16x16x32_bf16 v[44:47], v[174:177], v[190:193], v[44:47]
	v_mfma_f32_16x16x32_bf16 v[40:43], v[182:185], v[190:193], v[40:43]
	v_mfma_f32_16x16x32_bf16 v[28:31], v[174:177], v[198:201], v[28:31]
	v_mfma_f32_16x16x32_bf16 v[24:27], v[182:185], v[198:201], v[24:27]
	v_mfma_f32_16x16x32_bf16 v[12:15], v[174:177], v[208:211], v[12:15]
	v_mfma_f32_16x16x32_bf16 v[8:11], v[182:185], v[208:211], v[8:11]
	v_mfma_f32_16x16x32_bf16 v[4:7], v[174:177], v[216:219], v[4:7]
	v_mfma_f32_16x16x32_bf16 v[0:3], v[182:185], v[216:219], v[0:3]
	v_mfma_f32_16x16x32_bf16 v[44:47], v[178:181], v[194:197], v[44:47]
	v_mfma_f32_16x16x32_bf16 v[40:43], v[186:189], v[194:197], v[40:43]
	v_mfma_f32_16x16x32_bf16 v[28:31], v[178:181], v[202:205], v[28:31]
	v_mfma_f32_16x16x32_bf16 v[24:27], v[186:189], v[202:205], v[24:27]
	v_mfma_f32_16x16x32_bf16 v[12:15], v[178:181], v[212:215], v[12:15]
	v_mfma_f32_16x16x32_bf16 v[8:11], v[186:189], v[212:215], v[8:11]
	v_mfma_f32_16x16x32_bf16 v[4:7], v[178:181], v[220:223], v[4:7]
	v_mfma_f32_16x16x32_bf16 v[0:3], v[186:189], v[220:223], v[0:3]
	s_setprio 0
	s_barrier
	s_add_i32 s36, s36, 2
	s_add_u32 s18, s18, 0x100
	s_addc_u32 s19, s19, 0
	s_cmp_gt_u32 s36, 41
	s_cbranch_scc0 .LBB0_1898

;     __device__ __forceinline__ bool next(int i, Unit& u) const { if (i != 0) return false; const int c0 = (G >= 8) ? G - 5 : G - 2; int k = -1; if (c == c0) k = 0; else if (c == G - 1) k = 1; if (k < 0 || k >= n) return false; u.pm = k; u.pn = 0; return true; }
; #define PG8_STAGE(bufoff, gbase, voff) do { _Pragma("unroll") for (int _i = 0; _i < 2; ++_i) \
;         __builtin_amdgcn_global_load_lds((const unsigned*)((const char*)(gbase) + (voff)[_i]), (PG8_LAS unsigned*)(lds + (bufoff) + ldsw + _i * 8192), 16, 0, 0); } while (0)
; #define PG8_LDA(dst, b, h) do { _Pragma("unroll") for (int m = 0; m < 4; ++m) _Pragma("unroll") for (int k = 0; k < 2; ++k) dst[m][k] = *(const PG8_LAS bf16x8*)(lds + PG8_SA(b, h) + aoff + m * 2048 + k * 1024); } while (0)
; #define PG8_LDB(dst, b, h) do { _Pragma("unroll") for (int n = 0; n < 2; ++n) _Pragma("unroll") for (int k = 0; k < 2; ++k) dst[n][k] = *(const PG8_LAS bf16x8*)(lds + PG8_SB(b, h) + boff + n * 2048 + k * 1024); } while (0)
; template <class Epi, class Sched, bool ALIGN_EPI = false, bool SP2 = false>
; __device__ __forceinline__ void gemm_phase(PG8_LAS unsigned char* lds, const Gemm g, const Sched& S, const Epi& E) {
;     ...
;         const bool has_next = S.next(ui + 1, nxt);
;         const char* nA = has_next ? (const char*)g.A + (size_t)nxt.pm * tstep : cA; const char* nB = has_next ? (const char*)g.Bt + (size_t)nxt.pn * tstep : cB;
;         for (int t = 0; t < nt; t += 2) {
;             const bool last = (t == nt - 2);
;             const char* a1 = cA + (size_t)(t + 1) * kstep;
;             const char* a2 = last ? nA : cA + (size_t)(t + 2) * kstep; const char* b2 = last ? nB : cB + (size_t)(t + 2) * kstep;
;             const char* a3 = a2 + kstep; const char* b3 = b2 + kstep;
;             if (last && has_next) S.a_ready(nxt);
;             if constexpr (SP2) {
;             PG8_LDB(B0, 0, 0); PG8_LDB(B1, 0, 1); PG8_SCHED; PG8_LDA(At, 0, 0); PG8_STAGE(PG8_SA(1, 1), a1 + hstep, voffA);
;             PG8_WAIT_V(8); PG8_WAIT_L(0); PG8_BAR; PG8_MMA(0, 0, At, B0); PG8_MMA(0, 1, At, B1); PG8_BAR; PG8_SCHED;
;             PG8_LDA(At, 0, 1); PG8_STAGE(PG8_SB(0, 0), b2, voffB); PG8_STAGE(PG8_SB(0, 1), b2 + hstep, voffB); PG8_STAGE(PG8_SA(0, 0), a2, voffA);
;             PG8_WAIT_V(8); PG8_WAIT_L(0); PG8_BAR; PG8_MMA(1, 0, At, B0); PG8_MMA(1, 1, At, B1); PG8_BAR; PG8_SCHED;
.LBB0_1983:
	s_ashr_i32 s19, s18, 31
	s_lshl_b64 s[24:25], s[18:19], 19
	s_add_u32 s24, s97, s24
	s_addc_u32 s25, s3, s25
	s_and_b64 s[26:27], s[22:23], exec
	s_cselect_b32 s19, s25, s31
	s_cselect_b32 s59, s24, s30
	s_ashr_i32 s21, s20, 31
	s_lshl_b64 s[26:27], s[20:21], 19
	s_add_u32 s26, s38, s26
	s_addc_u32 s27, s39, s27
	s_and_b64 s[36:37], s[22:23], exec
	s_cselect_b32 s21, s27, s35
	s_cselect_b32 s60, s26, s34
	s_add_u32 s30, s30, 0x40080
	s_addc_u32 s31, s31, 0
	s_add_u32 s61, s34, 0x100
	v_mov_b32_e32 v0, 0
	s_addc_u32 s64, s35, 0
	s_mov_b32 s65, -2
	ds_read_b128 v[150:153], v147
	ds_read_b128 v[154:157], v147 offset:1024
	ds_read_b128 v[158:161], v147 offset:2048
	ds_read_b128 v[162:165], v147 offset:3072
	ds_read_b128 v[166:169], v148
	ds_read_b128 v[170:173], v148 offset:1024
	ds_read_b128 v[174:177], v148 offset:2048
	ds_read_b128 v[178:181], v148 offset:3072
	s_add_u32 s34, s30, 0xfffc0080
	s_addc_u32 s35, s31, -1
	s_cmp_eq_u32 s65, 12
	s_cselect_b32 s37, s19, s35
	s_cselect_b32 s36, s59, s34
	s_cselect_b32 s35, s21, s64
	s_cselect_b32 s34, s60, s61
	v_lshl_add_u64 v[142:143], s[30:31], 0, v[136:137]
	s_add_i32 m0, s29, 0xc000
	ds_read_b128 v[182:185], v149
	ds_read_b128 v[186:189], v149 offset:1024
	ds_read_b128 v[190:193], v149 offset:2048
	ds_read_b128 v[194:197], v149 offset:3072
	ds_read_b128 v[198:201], v149 offset:4096
	ds_read_b128 v[202:205], v149 offset:5120
	ds_read_b128 v[208:211], v149 offset:6144
	ds_read_b128 v[212:215], v149 offset:7168
	global_load_lds_dwordx4 v[142:143], off
	v_lshl_add_u64 v[142:143], s[30:31], 0, v[138:139]
	s_add_i32 m0, s29, 0xe000
	s_nop 0
	global_load_lds_dwordx4 v[142:143], off
	s_waitcnt vmcnt(8)
	s_waitcnt lgkmcnt(0)
	s_barrier
	s_setprio 1
	s_waitcnt lgkmcnt(0)
	v_mfma_f32_16x16x32_bf16 v[124:127], v[150:153], v[182:185], 0
	v_mfma_f32_16x16x32_bf16 v[120:123], v[158:161], v[182:185], 0
	v_mfma_f32_16x16x32_bf16 v[108:111], v[150:153], v[190:193], 0
	v_mfma_f32_16x16x32_bf16 v[104:107], v[158:161], v[190:193], 0
	v_mfma_f32_16x16x32_bf16 v[92:95], v[150:153], v[198:201], 0
	v_mfma_f32_16x16x32_bf16 v[88:91], v[158:161], v[198:201], 0
	v_mfma_f32_16x16x32_bf16 v[76:79], v[150:153], v[208:211], 0
	v_mfma_f32_16x16x32_bf16 v[72:75], v[158:161], v[208:211], 0
	v_mfma_f32_16x16x32_bf16 v[124:127], v[154:157], v[186:189], v[124:127]
	v_mfma_f32_16x16x32_bf16 v[120:123], v[162:165], v[186:189], v[120:123]
	v_mfma_f32_16x16x32_bf16 v[108:111], v[154:157], v[194:197], v[108:111]
	v_mfma_f32_16x16x32_bf16 v[104:107], v[162:165], v[194:197], v[104:107]
	v_mfma_f32_16x16x32_bf16 v[92:95], v[154:157], v[202:205], v[92:95]
	v_mfma_f32_16x16x32_bf16 v[88:91], v[162:165], v[202:205], v[88:91]
	v_mfma_f32_16x16x32_bf16 v[76:79], v[154:157], v[212:215], v[76:79]
	v_mfma_f32_16x16x32_bf16 v[72:75], v[162:165], v[212:215], v[72:75]
	v_mfma_f32_16x16x32_bf16 v[116:119], v[166:169], v[182:185], 0
	v_mfma_f32_16x16x32_bf16 v[112:115], v[174:177], v[182:185], 0
	v_mfma_f32_16x16x32_bf16 v[100:103], v[166:169], v[190:193], 0
	v_mfma_f32_16x16x32_bf16 v[96:99], v[174:177], v[190:193], 0
	v_mfma_f32_16x16x32_bf16 v[84:87], v[166:169], v[198:201], 0
	v_mfma_f32_16x16x32_bf16 v[80:83], v[174:177], v[198:201], 0
	v_mfma_f32_16x16x32_bf16 v[68:71], v[166:169], v[208:211], 0
	v_mfma_f32_16x16x32_bf16 v[64:67], v[174:177], v[208:211], 0
	v_mfma_f32_16x16x32_bf16 v[116:119], v[170:173], v[186:189], v[116:119]
	v_mfma_f32_16x16x32_bf16 v[112:115], v[178:181], v[186:189], v[112:115]
	v_mfma_f32_16x16x32_bf16 v[100:103], v[170:173], v[194:197], v[100:103]
	v_mfma_f32_16x16x32_bf16 v[96:99], v[178:181], v[194:197], v[96:99]
	v_mfma_f32_16x16x32_bf16 v[84:87], v[170:173], v[202:205], v[84:87]
	v_mfma_f32_16x16x32_bf16 v[80:83], v[178:181], v[202:205], v[80:83]
	v_mfma_f32_16x16x32_bf16 v[68:71], v[170:173], v[212:215], v[68:71]
	v_mfma_f32_16x16x32_bf16 v[64:67], v[178:181], v[212:215], v[64:67]
	s_setprio 0
	s_barrier
	s_add_i32 s66, s53, s41
	v_lshl_add_u64 v[142:143], s[34:35], 0, v[130:131]
	s_mov_b32 m0, s66
	ds_read_b128 v[182:185], v149 offset:16384
	ds_read_b128 v[186:189], v149 offset:17408
	ds_read_b128 v[190:193], v149 offset:18432
	ds_read_b128 v[194:197], v149 offset:19456
	ds_read_b128 v[198:201], v149 offset:20480
	ds_read_b128 v[202:205], v149 offset:21504
	ds_read_b128 v[208:211], v149 offset:22528
	ds_read_b128 v[212:215], v149 offset:23552
	global_load_lds_dwordx4 v[142:143], off
	s_add_i32 m0, s66, 0x2000
	s_add_u32 s66, s34, 0x40000
	v_lshl_add_u64 v[216:217], s[34:35], 0, v[134:135]
	s_addc_u32 s67, s35, 0
	s_add_i32 s68, s56, s41
	global_load_lds_dwordx4 v[216:217], off
	v_lshl_add_u64 v[218:219], s[66:67], 0, v[130:131]
	s_mov_b32 m0, s68
	v_lshl_add_u64 v[220:221], s[36:37], 0, v[132:133]
	global_load_lds_dwordx4 v[218:219], off
	v_lshl_add_u64 v[218:219], s[66:67], 0, v[134:135]
	s_add_i32 m0, s68, 0x2000
	s_nop 0
	global_load_lds_dwordx4 v[218:219], off
	v_lshl_add_u64 v[218:219], s[36:37], 0, v[128:129]
	s_mov_b32 m0, s29
	s_nop 0
	global_load_lds_dwordx4 v[218:219], off
	s_mov_b32 m0, s43
	s_nop 0
	global_load_lds_dwordx4 v[220:221], off
	s_waitcnt vmcnt(8)
	s_waitcnt lgkmcnt(0)
	s_barrier
; #define PG8_STAGE(bufoff, gbase, voff) do { _Pragma("unroll") for (int _i = 0; _i < 2; ++_i) \
;         __builtin_amdgcn_global_load_lds((const unsigned*)((const char*)(gbase) + (voff)[_i]), (PG8_LAS unsigned*)(lds + (bufoff) + ldsw + _i * 8192), 16, 0, 0); } while (0)
; #define PG8_LDA(dst, b, h) do { _Pragma("unroll") for (int m = 0; m < 4; ++m) _Pragma("unroll") for (int k = 0; k < 2; ++k) dst[m][k] = *(const PG8_LAS bf16x8*)(lds + PG8_SA(b, h) + aoff + m * 2048 + k * 1024); } while (0)
; #define PG8_LDB(dst, b, h) do { _Pragma("unroll") for (int n = 0; n < 2; ++n) _Pragma("unroll") for (int k = 0; k < 2; ++k) dst[n][k] = *(const PG8_LAS bf16x8*)(lds + PG8_SB(b, h) + boff + n * 2048 + k * 1024); } while (0)
; #define PG8_MMA(ai, bj, At, Bt) do { __builtin_amdgcn_s_setprio(1); _Pragma("unroll") for (int m = 0; m < 4; ++m) _Pragma("unroll") for (int n = 0; n < 2; ++n) _Pragma("unroll") for (int k = 0; k < 2; ++k) \
;         acc[ai][bj][m][n] = __builtin_amdgcn_mfma_f32_16x16x32_bf16(Bt[n][k], At[m][k], acc[ai][bj][m][n], 0, 0, 0); __builtin_amdgcn_s_setprio(0); } while (0)
; #define PG8_WAIT_V(n) asm volatile("s_waitcnt vmcnt(" #n ")" ::: "memory")
; #define PG8_WAIT_L(n) asm volatile("s_waitcnt lgkmcnt(" #n ")" ::: "memory")
; #define PG8_BAR __builtin_amdgcn_s_barrier()
; #define PG8_SCHED __builtin_amdgcn_sched_barrier(0)
; template <class Epi, class Sched, bool ALIGN_EPI = false, bool SP2 = false>
; __device__ __forceinline__ void gemm_phase(PG8_LAS unsigned char* lds, const Gemm g, const Sched& S, const Epi& E) {
;     ...
;             PG8_WAIT_V(8); PG8_WAIT_L(0); PG8_BAR; PG8_MMA(1, 0, At, B0); PG8_MMA(1, 1, At, B1); PG8_BAR; PG8_SCHED;
;             PG8_LDB(B0, 1, 0); PG8_LDB(B1, 1, 1); PG8_SCHED; PG8_LDA(At, 1, 0); PG8_STAGE(PG8_SA(0, 1), a2 + hstep, voffA);
;             PG8_WAIT_V(8); PG8_WAIT_L(0); PG8_BAR; PG8_MMA(0, 0, At, B0); PG8_MMA(0, 1, At, B1); PG8_BAR; PG8_SCHED;
	s_setprio 1
	s_waitcnt lgkmcnt(0)
	v_mfma_f32_16x16x32_bf16 v[60:63], v[150:153], v[182:185], 0
	v_mfma_f32_16x16x32_bf16 v[56:59], v[158:161], v[182:185], 0
	v_mfma_f32_16x16x32_bf16 v[44:47], v[150:153], v[190:193], 0
	v_mfma_f32_16x16x32_bf16 v[40:43], v[158:161], v[190:193], 0
	v_mfma_f32_16x16x32_bf16 v[28:31], v[150:153], v[198:201], 0
	v_mfma_f32_16x16x32_bf16 v[24:27], v[158:161], v[198:201], 0
	v_mfma_f32_16x16x32_bf16 v[12:15], v[150:153], v[208:211], 0
	v_mfma_f32_16x16x32_bf16 v[8:11], v[158:161], v[208:211], 0
	v_mfma_f32_16x16x32_bf16 v[60:63], v[154:157], v[186:189], v[60:63]
	v_mfma_f32_16x16x32_bf16 v[56:59], v[162:165], v[186:189], v[56:59]
	v_mfma_f32_16x16x32_bf16 v[44:47], v[154:157], v[194:197], v[44:47]
	v_mfma_f32_16x16x32_bf16 v[40:43], v[162:165], v[194:197], v[40:43]
	v_mfma_f32_16x16x32_bf16 v[28:31], v[154:157], v[202:205], v[28:31]
	v_mfma_f32_16x16x32_bf16 v[24:27], v[162:165], v[202:205], v[24:27]
	v_mfma_f32_16x16x32_bf16 v[12:15], v[154:157], v[212:215], v[12:15]
	v_mfma_f32_16x16x32_bf16 v[8:11], v[162:165], v[212:215], v[8:11]
	v_mfma_f32_16x16x32_bf16 v[52:55], v[166:169], v[182:185], 0
	v_mfma_f32_16x16x32_bf16 v[48:51], v[174:177], v[182:185], 0
	v_mfma_f32_16x16x32_bf16 v[36:39], v[166:169], v[190:193], 0
	v_mfma_f32_16x16x32_bf16 v[32:35], v[174:177], v[190:193], 0
	v_mfma_f32_16x16x32_bf16 v[20:23], v[166:169], v[198:201], 0
	v_mfma_f32_16x16x32_bf16 v[16:19], v[174:177], v[198:201], 0
	v_mfma_f32_16x16x32_bf16 v[4:7], v[166:169], v[208:211], 0
	v_mfma_f32_16x16x32_bf16 v[0:3], v[174:177], v[208:211], 0
	v_mfma_f32_16x16x32_bf16 v[52:55], v[170:173], v[186:189], v[52:55]
	v_mfma_f32_16x16x32_bf16 v[48:51], v[178:181], v[186:189], v[48:51]
	v_mfma_f32_16x16x32_bf16 v[36:39], v[170:173], v[194:197], v[36:39]
	v_mfma_f32_16x16x32_bf16 v[32:35], v[178:181], v[194:197], v[32:35]
	v_mfma_f32_16x16x32_bf16 v[20:23], v[170:173], v[202:205], v[20:23]
	v_mfma_f32_16x16x32_bf16 v[16:19], v[178:181], v[202:205], v[16:19]
	v_mfma_f32_16x16x32_bf16 v[4:7], v[170:173], v[212:215], v[4:7]
	v_mfma_f32_16x16x32_bf16 v[0:3], v[178:181], v[212:215], v[0:3]
	s_setprio 0
	s_barrier
	s_add_i32 s66, 0, 0x18000
	s_add_i32 s67, 0, 0x1c000
	v_add_u32_e32 v162, s66, v145
	v_add_u32_e32 v178, s67, v145
	ds_read_b128 v[150:153], v162
	ds_read_b128 v[154:157], v162 offset:1024
	ds_read_b128 v[158:161], v162 offset:2048
	ds_read_b128 v[162:165], v162 offset:3072
	ds_read_b128 v[166:169], v178
	ds_read_b128 v[170:173], v178 offset:1024
	ds_read_b128 v[174:177], v178 offset:2048
	ds_read_b128 v[178:181], v178 offset:3072
	s_add_u32 s36, s36, 0x40000
	s_addc_u32 s37, s37, 0
	s_mov_b32 m0, s44
	v_lshl_add_u64 v[222:223], s[36:37], 0, v[128:129]
	ds_read_b128 v[182:185], v149 offset:32768
	ds_read_b128 v[186:189], v149 offset:33792
	ds_read_b128 v[190:193], v149 offset:34816
	ds_read_b128 v[194:197], v149 offset:35840
	ds_read_b128 v[198:201], v149 offset:36864
	ds_read_b128 v[202:205], v149 offset:37888
	ds_read_b128 v[208:211], v149 offset:38912
	ds_read_b128 v[212:215], v149 offset:39936
	global_load_lds_dwordx4 v[222:223], off
	v_lshl_add_u64 v[222:223], s[36:37], 0, v[132:133]
	s_mov_b32 m0, s45
	s_nop 0
	global_load_lds_dwordx4 v[222:223], off
	s_waitcnt vmcnt(8)
	s_waitcnt lgkmcnt(0)
	s_barrier
	s_setprio 1
	s_waitcnt lgkmcnt(0)
	v_mfma_f32_16x16x32_bf16 v[124:127], v[150:153], v[182:185], v[124:127]
	v_mfma_f32_16x16x32_bf16 v[120:123], v[158:161], v[182:185], v[120:123]
	v_mfma_f32_16x16x32_bf16 v[108:111], v[150:153], v[190:193], v[108:111]
	v_mfma_f32_16x16x32_bf16 v[104:107], v[158:161], v[190:193], v[104:107]
	v_mfma_f32_16x16x32_bf16 v[92:95], v[150:153], v[198:201], v[92:95]
	v_mfma_f32_16x16x32_bf16 v[88:91], v[158:161], v[198:201], v[88:91]
	v_mfma_f32_16x16x32_bf16 v[76:79], v[150:153], v[208:211], v[76:79]
	v_mfma_f32_16x16x32_bf16 v[72:75], v[158:161], v[208:211], v[72:75]
	v_mfma_f32_16x16x32_bf16 v[124:127], v[154:157], v[186:189], v[124:127]
	v_mfma_f32_16x16x32_bf16 v[120:123], v[162:165], v[186:189], v[120:123]
	v_mfma_f32_16x16x32_bf16 v[108:111], v[154:157], v[194:197], v[108:111]
	v_mfma_f32_16x16x32_bf16 v[104:107], v[162:165], v[194:197], v[104:107]
	v_mfma_f32_16x16x32_bf16 v[92:95], v[154:157], v[202:205], v[92:95]
	v_mfma_f32_16x16x32_bf16 v[88:91], v[162:165], v[202:205], v[88:91]
	v_mfma_f32_16x16x32_bf16 v[76:79], v[154:157], v[212:215], v[76:79]
	v_mfma_f32_16x16x32_bf16 v[72:75], v[162:165], v[212:215], v[72:75]
	v_mfma_f32_16x16x32_bf16 v[116:119], v[166:169], v[182:185], v[116:119]
	v_mfma_f32_16x16x32_bf16 v[112:115], v[174:177], v[182:185], v[112:115]
	v_mfma_f32_16x16x32_bf16 v[100:103], v[166:169], v[190:193], v[100:103]
	v_mfma_f32_16x16x32_bf16 v[96:99], v[174:177], v[190:193], v[96:99]
	v_mfma_f32_16x16x32_bf16 v[84:87], v[166:169], v[198:201], v[84:87]
	v_mfma_f32_16x16x32_bf16 v[80:83], v[174:177], v[198:201], v[80:83]
	v_mfma_f32_16x16x32_bf16 v[68:71], v[166:169], v[208:211], v[68:71]
	v_mfma_f32_16x16x32_bf16 v[64:67], v[174:177], v[208:211], v[64:67]
	v_mfma_f32_16x16x32_bf16 v[116:119], v[170:173], v[186:189], v[116:119]
	v_mfma_f32_16x16x32_bf16 v[112:115], v[178:181], v[186:189], v[112:115]
	v_mfma_f32_16x16x32_bf16 v[100:103], v[170:173], v[194:197], v[100:103]
	v_mfma_f32_16x16x32_bf16 v[96:99], v[178:181], v[194:197], v[96:99]
	v_mfma_f32_16x16x32_bf16 v[84:87], v[170:173], v[202:205], v[84:87]
	v_mfma_f32_16x16x32_bf16 v[80:83], v[178:181], v[202:205], v[80:83]
	v_mfma_f32_16x16x32_bf16 v[68:71], v[170:173], v[212:215], v[68:71]
	v_mfma_f32_16x16x32_bf16 v[64:67], v[178:181], v[212:215], v[64:67]
	s_setprio 0
	s_barrier
; #define PG8_STAGE(bufoff, gbase, voff) do { _Pragma("unroll") for (int _i = 0; _i < 2; ++_i) \
;         __builtin_amdgcn_global_load_lds((const unsigned*)((const char*)(gbase) + (voff)[_i]), (PG8_LAS unsigned*)(lds + (bufoff) + ldsw + _i * 8192), 16, 0, 0); } while (0)
; #define PG8_LDA(dst, b, h) do { _Pragma("unroll") for (int m = 0; m < 4; ++m) _Pragma("unroll") for (int k = 0; k < 2; ++k) dst[m][k] = *(const PG8_LAS bf16x8*)(lds + PG8_SA(b, h) + aoff + m * 2048 + k * 1024); } while (0)
; #define PG8_LDB(dst, b, h) do { _Pragma("unroll") for (int n = 0; n < 2; ++n) _Pragma("unroll") for (int k = 0; k < 2; ++k) dst[n][k] = *(const PG8_LAS bf16x8*)(lds + PG8_SB(b, h) + boff + n * 2048 + k * 1024); } while (0)
; #define PG8_MMA(ai, bj, At, Bt) do { __builtin_amdgcn_s_setprio(1); _Pragma("unroll") for (int m = 0; m < 4; ++m) _Pragma("unroll") for (int n = 0; n < 2; ++n) _Pragma("unroll") for (int k = 0; k < 2; ++k) \
;         acc[ai][bj][m][n] = __builtin_amdgcn_mfma_f32_16x16x32_bf16(Bt[n][k], At[m][k], acc[ai][bj][m][n], 0, 0, 0); __builtin_amdgcn_s_setprio(0); } while (0)
; #define PG8_WAIT_V(n) asm volatile("s_waitcnt vmcnt(" #n ")" ::: "memory")
; template <class Epi, class Sched, bool ALIGN_EPI = false, bool SP2 = false>
; __device__ __forceinline__ void gemm_phase(PG8_LAS unsigned char* lds, const Gemm g, const Sched& S, const Epi& E) {
;     ...
;             PG8_LDB(B0, 0, 0); PG8_LDB(B1, 0, 1); PG8_SCHED; PG8_LDA(At, 0, 0); PG8_STAGE(PG8_SA(1, 1), a1 + hstep, voffA);
;             PG8_WAIT_V(8); PG8_WAIT_L(0); PG8_BAR; PG8_MMA(0, 0, At, B0); PG8_MMA(0, 1, At, B1); PG8_BAR; PG8_SCHED;
;             PG8_LDA(At, 0, 1); PG8_STAGE(PG8_SB(0, 0), b2, voffB); PG8_STAGE(PG8_SB(0, 1), b2 + hstep, voffB); PG8_STAGE(PG8_SA(0, 0), a2, voffA);
;             PG8_WAIT_V(8); PG8_WAIT_L(0); PG8_BAR; PG8_MMA(1, 0, At, B0); PG8_MMA(1, 1, At, B1); PG8_BAR; PG8_SCHED;
;             PG8_LDB(B0, 1, 0); PG8_LDB(B1, 1, 1); PG8_SCHED; PG8_LDA(At, 1, 0); PG8_STAGE(PG8_SA(0, 1), a2 + hstep, voffA);
;             PG8_WAIT_V(8); PG8_WAIT_L(0); PG8_BAR; PG8_MMA(0, 0, At, B0); PG8_MMA(0, 1, At, B1); PG8_BAR; PG8_SCHED;
;             PG8_LDA(At, 1, 1); PG8_STAGE(PG8_SB(1, 0), b3, voffB); PG8_STAGE(PG8_SB(1, 1), b3 + hstep, voffB); PG8_STAGE(PG8_SA(1, 0), a3, voffA);
;             PG8_WAIT_V(8); PG8_WAIT_L(0); PG8_BAR; PG8_MMA(1, 0, At, B0); PG8_MMA(1, 1, At, B1); PG8_BAR; PG8_SCHED;
	s_add_i32 s36, s66, s41
	v_lshl_add_u64 v[142:143], v[142:143], 0, s[8:9]
	s_mov_b32 m0, s36
	ds_read_b128 v[182:185], v149 offset:49152
	ds_read_b128 v[186:189], v149 offset:50176
	ds_read_b128 v[190:193], v149 offset:51200
	ds_read_b128 v[194:197], v149 offset:52224
	ds_read_b128 v[198:201], v149 offset:53248
	ds_read_b128 v[202:205], v149 offset:54272
	ds_read_b128 v[208:211], v149 offset:55296
	ds_read_b128 v[212:215], v149 offset:56320
	global_load_lds_dwordx4 v[142:143], off
	s_add_i32 m0, s36, 0x2000
	s_add_u32 s34, s34, 0x40080
	v_lshl_add_u64 v[142:143], v[216:217], 0, s[8:9]
	s_addc_u32 s35, s35, 0
	s_add_i32 s36, s67, s41
	global_load_lds_dwordx4 v[142:143], off
	v_lshl_add_u64 v[142:143], s[34:35], 0, v[130:131]
	s_mov_b32 m0, s36
	s_nop 0
	global_load_lds_dwordx4 v[142:143], off
	v_lshl_add_u64 v[142:143], s[34:35], 0, v[134:135]
	s_add_i32 m0, s36, 0x2000
	s_nop 0
	global_load_lds_dwordx4 v[142:143], off
	v_lshl_add_u64 v[142:143], v[218:219], 0, s[8:9]
	s_mov_b32 m0, s47
	s_nop 0
	global_load_lds_dwordx4 v[142:143], off
	v_lshl_add_u64 v[142:143], v[220:221], 0, s[8:9]
	s_mov_b32 m0, s52
	s_nop 0
	global_load_lds_dwordx4 v[142:143], off
	s_waitcnt vmcnt(8)
	s_waitcnt lgkmcnt(0)
	s_barrier
	s_setprio 1
	s_waitcnt lgkmcnt(0)
	v_mfma_f32_16x16x32_bf16 v[60:63], v[150:153], v[182:185], v[60:63]
	v_mfma_f32_16x16x32_bf16 v[56:59], v[158:161], v[182:185], v[56:59]
	v_mfma_f32_16x16x32_bf16 v[44:47], v[150:153], v[190:193], v[44:47]
	v_mfma_f32_16x16x32_bf16 v[40:43], v[158:161], v[190:193], v[40:43]
	v_mfma_f32_16x16x32_bf16 v[28:31], v[150:153], v[198:201], v[28:31]
	v_mfma_f32_16x16x32_bf16 v[24:27], v[158:161], v[198:201], v[24:27]
	v_mfma_f32_16x16x32_bf16 v[12:15], v[150:153], v[208:211], v[12:15]
	v_mfma_f32_16x16x32_bf16 v[8:11], v[158:161], v[208:211], v[8:11]
	v_mfma_f32_16x16x32_bf16 v[60:63], v[154:157], v[186:189], v[60:63]
	v_mfma_f32_16x16x32_bf16 v[56:59], v[162:165], v[186:189], v[56:59]
	v_mfma_f32_16x16x32_bf16 v[44:47], v[154:157], v[194:197], v[44:47]
	v_mfma_f32_16x16x32_bf16 v[40:43], v[162:165], v[194:197], v[40:43]
	v_mfma_f32_16x16x32_bf16 v[28:31], v[154:157], v[202:205], v[28:31]
	v_mfma_f32_16x16x32_bf16 v[24:27], v[162:165], v[202:205], v[24:27]
	v_mfma_f32_16x16x32_bf16 v[12:15], v[154:157], v[212:215], v[12:15]
	v_mfma_f32_16x16x32_bf16 v[8:11], v[162:165], v[212:215], v[8:11]
	v_mfma_f32_16x16x32_bf16 v[52:55], v[166:169], v[182:185], v[52:55]
	v_mfma_f32_16x16x32_bf16 v[48:51], v[174:177], v[182:185], v[48:51]
	v_mfma_f32_16x16x32_bf16 v[36:39], v[166:169], v[190:193], v[36:39]
	v_mfma_f32_16x16x32_bf16 v[32:35], v[174:177], v[190:193], v[32:35]
	v_mfma_f32_16x16x32_bf16 v[20:23], v[166:169], v[198:201], v[20:23]
	v_mfma_f32_16x16x32_bf16 v[16:19], v[174:177], v[198:201], v[16:19]
	v_mfma_f32_16x16x32_bf16 v[4:7], v[166:169], v[208:211], v[4:7]
	v_mfma_f32_16x16x32_bf16 v[0:3], v[174:177], v[208:211], v[0:3]
	v_mfma_f32_16x16x32_bf16 v[52:55], v[170:173], v[186:189], v[52:55]
	v_mfma_f32_16x16x32_bf16 v[48:51], v[178:181], v[186:189], v[48:51]
	v_mfma_f32_16x16x32_bf16 v[36:39], v[170:173], v[194:197], v[36:39]
	v_mfma_f32_16x16x32_bf16 v[32:35], v[178:181], v[194:197], v[32:35]
	v_mfma_f32_16x16x32_bf16 v[20:23], v[170:173], v[202:205], v[20:23]
	v_mfma_f32_16x16x32_bf16 v[16:19], v[178:181], v[202:205], v[16:19]
	v_mfma_f32_16x16x32_bf16 v[4:7], v[170:173], v[212:215], v[4:7]
	v_mfma_f32_16x16x32_bf16 v[0:3], v[178:181], v[212:215], v[0:3]
	s_setprio 0
	s_barrier
	s_add_i32 s65, s65, 2
	s_add_u32 s30, s30, 0x100
	s_addc_u32 s31, s31, 0
	s_add_u32 s61, s61, 0x100
	s_addc_u32 s64, s64, 0
	s_cmp_gt_u32 s65, 13
	s_cbranch_scc0 .LBB0_1984
	s_branch .Lpeel_exit_15
.LBB0_1984:
	ds_read_b128 v[150:153], v147
	ds_read_b128 v[154:157], v147 offset:1024
	ds_read_b128 v[158:161], v147 offset:2048
	ds_read_b128 v[162:165], v147 offset:3072
	ds_read_b128 v[166:169], v148
	ds_read_b128 v[170:173], v148 offset:1024
	ds_read_b128 v[174:177], v148 offset:2048
	ds_read_b128 v[178:181], v148 offset:3072
	s_add_u32 s34, s30, 0xfffc0080
	s_addc_u32 s35, s31, -1
	s_cmp_eq_u32 s65, 12
	s_cselect_b32 s37, s19, s35
	s_cselect_b32 s36, s59, s34
	s_cselect_b32 s35, s21, s64
	s_cselect_b32 s34, s60, s61
	v_lshl_add_u64 v[142:143], s[30:31], 0, v[136:137]
	s_add_i32 m0, s29, 0xc000
	ds_read_b128 v[182:185], v149
	ds_read_b128 v[186:189], v149 offset:1024
	ds_read_b128 v[190:193], v149 offset:2048
	ds_read_b128 v[194:197], v149 offset:3072
	ds_read_b128 v[198:201], v149 offset:4096
	ds_read_b128 v[202:205], v149 offset:5120
	ds_read_b128 v[208:211], v149 offset:6144
	ds_read_b128 v[212:215], v149 offset:7168
	global_load_lds_dwordx4 v[142:143], off
	v_lshl_add_u64 v[142:143], s[30:31], 0, v[138:139]
	s_add_i32 m0, s29, 0xe000
	s_nop 0
	global_load_lds_dwordx4 v[142:143], off
	s_waitcnt vmcnt(8)
	s_waitcnt lgkmcnt(0)
	s_barrier
; #define PG8_STAGE(bufoff, gbase, voff) do { _Pragma("unroll") for (int _i = 0; _i < 2; ++_i) \
;         __builtin_amdgcn_global_load_lds((const unsigned*)((const char*)(gbase) + (voff)[_i]), (PG8_LAS unsigned*)(lds + (bufoff) + ldsw + _i * 8192), 16, 0, 0); } while (0)
; #define PG8_LDA(dst, b, h) do { _Pragma("unroll") for (int m = 0; m < 4; ++m) _Pragma("unroll") for (int k = 0; k < 2; ++k) dst[m][k] = *(const PG8_LAS bf16x8*)(lds + PG8_SA(b, h) + aoff + m * 2048 + k * 1024); } while (0)
; #define PG8_MMA(ai, bj, At, Bt) do { __builtin_amdgcn_s_setprio(1); _Pragma("unroll") for (int m = 0; m < 4; ++m) _Pragma("unroll") for (int n = 0; n < 2; ++n) _Pragma("unroll") for (int k = 0; k < 2; ++k) \
;         acc[ai][bj][m][n] = __builtin_amdgcn_mfma_f32_16x16x32_bf16(Bt[n][k], At[m][k], acc[ai][bj][m][n], 0, 0, 0); __builtin_amdgcn_s_setprio(0); } while (0)
; #define PG8_WAIT_V(n) asm volatile("s_waitcnt vmcnt(" #n ")" ::: "memory")
; #define PG8_WAIT_L(n) asm volatile("s_waitcnt lgkmcnt(" #n ")" ::: "memory")
; #define PG8_BAR __builtin_amdgcn_s_barrier()
; #define PG8_SCHED __builtin_amdgcn_sched_barrier(0)
; template <class Epi, class Sched, bool ALIGN_EPI = false, bool SP2 = false>
; __device__ __forceinline__ void gemm_phase(PG8_LAS unsigned char* lds, const Gemm g, const Sched& S, const Epi& E) {
;     ...
;             PG8_WAIT_V(8); PG8_WAIT_L(0); PG8_BAR; PG8_MMA(0, 0, At, B0); PG8_MMA(0, 1, At, B1); PG8_BAR; PG8_SCHED;
;             PG8_LDA(At, 0, 1); PG8_STAGE(PG8_SB(0, 0), b2, voffB); PG8_STAGE(PG8_SB(0, 1), b2 + hstep, voffB); PG8_STAGE(PG8_SA(0, 0), a2, voffA);
;             PG8_WAIT_V(8); PG8_WAIT_L(0); PG8_BAR; PG8_MMA(1, 0, At, B0); PG8_MMA(1, 1, At, B1); PG8_BAR; PG8_SCHED;
	s_setprio 1
	s_waitcnt lgkmcnt(0)
	v_mfma_f32_16x16x32_bf16 v[124:127], v[150:153], v[182:185], v[124:127]
	v_mfma_f32_16x16x32_bf16 v[120:123], v[158:161], v[182:185], v[120:123]
	v_mfma_f32_16x16x32_bf16 v[108:111], v[150:153], v[190:193], v[108:111]
	v_mfma_f32_16x16x32_bf16 v[104:107], v[158:161], v[190:193], v[104:107]
	v_mfma_f32_16x16x32_bf16 v[92:95], v[150:153], v[198:201], v[92:95]
	v_mfma_f32_16x16x32_bf16 v[88:91], v[158:161], v[198:201], v[88:91]
	v_mfma_f32_16x16x32_bf16 v[76:79], v[150:153], v[208:211], v[76:79]
	v_mfma_f32_16x16x32_bf16 v[72:75], v[158:161], v[208:211], v[72:75]
	v_mfma_f32_16x16x32_bf16 v[124:127], v[154:157], v[186:189], v[124:127]
	v_mfma_f32_16x16x32_bf16 v[120:123], v[162:165], v[186:189], v[120:123]
	v_mfma_f32_16x16x32_bf16 v[108:111], v[154:157], v[194:197], v[108:111]
	v_mfma_f32_16x16x32_bf16 v[104:107], v[162:165], v[194:197], v[104:107]
	v_mfma_f32_16x16x32_bf16 v[92:95], v[154:157], v[202:205], v[92:95]
	v_mfma_f32_16x16x32_bf16 v[88:91], v[162:165], v[202:205], v[88:91]
	v_mfma_f32_16x16x32_bf16 v[76:79], v[154:157], v[212:215], v[76:79]
	v_mfma_f32_16x16x32_bf16 v[72:75], v[162:165], v[212:215], v[72:75]
	v_mfma_f32_16x16x32_bf16 v[116:119], v[166:169], v[182:185], v[116:119]
	v_mfma_f32_16x16x32_bf16 v[112:115], v[174:177], v[182:185], v[112:115]
	v_mfma_f32_16x16x32_bf16 v[100:103], v[166:169], v[190:193], v[100:103]
	v_mfma_f32_16x16x32_bf16 v[96:99], v[174:177], v[190:193], v[96:99]
	v_mfma_f32_16x16x32_bf16 v[84:87], v[166:169], v[198:201], v[84:87]
	v_mfma_f32_16x16x32_bf16 v[80:83], v[174:177], v[198:201], v[80:83]
	v_mfma_f32_16x16x32_bf16 v[68:71], v[166:169], v[208:211], v[68:71]
	v_mfma_f32_16x16x32_bf16 v[64:67], v[174:177], v[208:211], v[64:67]
	v_mfma_f32_16x16x32_bf16 v[116:119], v[170:173], v[186:189], v[116:119]
	v_mfma_f32_16x16x32_bf16 v[112:115], v[178:181], v[186:189], v[112:115]
	v_mfma_f32_16x16x32_bf16 v[100:103], v[170:173], v[194:197], v[100:103]
	v_mfma_f32_16x16x32_bf16 v[96:99], v[178:181], v[194:197], v[96:99]
	v_mfma_f32_16x16x32_bf16 v[84:87], v[170:173], v[202:205], v[84:87]
	v_mfma_f32_16x16x32_bf16 v[80:83], v[178:181], v[202:205], v[80:83]
	v_mfma_f32_16x16x32_bf16 v[68:71], v[170:173], v[212:215], v[68:71]
	v_mfma_f32_16x16x32_bf16 v[64:67], v[178:181], v[212:215], v[64:67]
	s_setprio 0
	s_barrier
	s_add_i32 s66, s53, s41
	v_lshl_add_u64 v[142:143], s[34:35], 0, v[130:131]
	s_mov_b32 m0, s66
	ds_read_b128 v[182:185], v149 offset:16384
	ds_read_b128 v[186:189], v149 offset:17408
	ds_read_b128 v[190:193], v149 offset:18432
	ds_read_b128 v[194:197], v149 offset:19456
	ds_read_b128 v[198:201], v149 offset:20480
	ds_read_b128 v[202:205], v149 offset:21504
	ds_read_b128 v[208:211], v149 offset:22528
	ds_read_b128 v[212:215], v149 offset:23552
	global_load_lds_dwordx4 v[142:143], off
	s_add_i32 m0, s66, 0x2000
	s_add_u32 s66, s34, 0x40000
	v_lshl_add_u64 v[216:217], s[34:35], 0, v[134:135]
	s_addc_u32 s67, s35, 0
	s_add_i32 s68, s56, s41
	global_load_lds_dwordx4 v[216:217], off
	v_lshl_add_u64 v[218:219], s[66:67], 0, v[130:131]
	s_mov_b32 m0, s68
	v_lshl_add_u64 v[220:221], s[36:37], 0, v[132:133]
	global_load_lds_dwordx4 v[218:219], off
	v_lshl_add_u64 v[218:219], s[66:67], 0, v[134:135]
	s_add_i32 m0, s68, 0x2000
	s_nop 0
	global_load_lds_dwordx4 v[218:219], off
	v_lshl_add_u64 v[218:219], s[36:37], 0, v[128:129]
	s_mov_b32 m0, s29
	s_nop 0
	global_load_lds_dwordx4 v[218:219], off
	s_mov_b32 m0, s43
	s_nop 0
	global_load_lds_dwordx4 v[220:221], off
	s_waitcnt vmcnt(8)
	s_waitcnt lgkmcnt(0)
	s_barrier
	s_setprio 1
	s_waitcnt lgkmcnt(0)
	v_mfma_f32_16x16x32_bf16 v[60:63], v[150:153], v[182:185], v[60:63]
	v_mfma_f32_16x16x32_bf16 v[56:59], v[158:161], v[182:185], v[56:59]
	v_mfma_f32_16x16x32_bf16 v[44:47], v[150:153], v[190:193], v[44:47]
	v_mfma_f32_16x16x32_bf16 v[40:43], v[158:161], v[190:193], v[40:43]
	v_mfma_f32_16x16x32_bf16 v[28:31], v[150:153], v[198:201], v[28:31]
	v_mfma_f32_16x16x32_bf16 v[24:27], v[158:161], v[198:201], v[24:27]
	v_mfma_f32_16x16x32_bf16 v[12:15], v[150:153], v[208:211], v[12:15]
	v_mfma_f32_16x16x32_bf16 v[8:11], v[158:161], v[208:211], v[8:11]
	v_mfma_f32_16x16x32_bf16 v[60:63], v[154:157], v[186:189], v[60:63]
	v_mfma_f32_16x16x32_bf16 v[56:59], v[162:165], v[186:189], v[56:59]
	v_mfma_f32_16x16x32_bf16 v[44:47], v[154:157], v[194:197], v[44:47]
	v_mfma_f32_16x16x32_bf16 v[40:43], v[162:165], v[194:197], v[40:43]
	v_mfma_f32_16x16x32_bf16 v[28:31], v[154:157], v[202:205], v[28:31]
	v_mfma_f32_16x16x32_bf16 v[24:27], v[162:165], v[202:205], v[24:27]
	v_mfma_f32_16x16x32_bf16 v[12:15], v[154:157], v[212:215], v[12:15]
	v_mfma_f32_16x16x32_bf16 v[8:11], v[162:165], v[212:215], v[8:11]
	v_mfma_f32_16x16x32_bf16 v[52:55], v[166:169], v[182:185], v[52:55]
	v_mfma_f32_16x16x32_bf16 v[48:51], v[174:177], v[182:185], v[48:51]
	v_mfma_f32_16x16x32_bf16 v[36:39], v[166:169], v[190:193], v[36:39]
	v_mfma_f32_16x16x32_bf16 v[32:35], v[174:177], v[190:193], v[32:35]
	v_mfma_f32_16x16x32_bf16 v[20:23], v[166:169], v[198:201], v[20:23]
	v_mfma_f32_16x16x32_bf16 v[16:19], v[174:177], v[198:201], v[16:19]
	v_mfma_f32_16x16x32_bf16 v[4:7], v[166:169], v[208:211], v[4:7]
	v_mfma_f32_16x16x32_bf16 v[0:3], v[174:177], v[208:211], v[0:3]
	v_mfma_f32_16x16x32_bf16 v[52:55], v[170:173], v[186:189], v[52:55]
	v_mfma_f32_16x16x32_bf16 v[48:51], v[178:181], v[186:189], v[48:51]
	v_mfma_f32_16x16x32_bf16 v[36:39], v[170:173], v[194:197], v[36:39]
	v_mfma_f32_16x16x32_bf16 v[32:35], v[178:181], v[194:197], v[32:35]
	v_mfma_f32_16x16x32_bf16 v[20:23], v[170:173], v[202:205], v[20:23]
	v_mfma_f32_16x16x32_bf16 v[16:19], v[178:181], v[202:205], v[16:19]
	v_mfma_f32_16x16x32_bf16 v[4:7], v[170:173], v[212:215], v[4:7]
	v_mfma_f32_16x16x32_bf16 v[0:3], v[178:181], v[212:215], v[0:3]
	s_setprio 0
	s_barrier
; #define PG8_STAGE(bufoff, gbase, voff) do { _Pragma("unroll") for (int _i = 0; _i < 2; ++_i) \
;         __builtin_amdgcn_global_load_lds((const unsigned*)((const char*)(gbase) + (voff)[_i]), (PG8_LAS unsigned*)(lds + (bufoff) + ldsw + _i * 8192), 16, 0, 0); } while (0)
; #define PG8_LDA(dst, b, h) do { _Pragma("unroll") for (int m = 0; m < 4; ++m) _Pragma("unroll") for (int k = 0; k < 2; ++k) dst[m][k] = *(const PG8_LAS bf16x8*)(lds + PG8_SA(b, h) + aoff + m * 2048 + k * 1024); } while (0)
; #define PG8_LDB(dst, b, h) do { _Pragma("unroll") for (int n = 0; n < 2; ++n) _Pragma("unroll") for (int k = 0; k < 2; ++k) dst[n][k] = *(const PG8_LAS bf16x8*)(lds + PG8_SB(b, h) + boff + n * 2048 + k * 1024); } while (0)
; #define PG8_MMA(ai, bj, At, Bt) do { __builtin_amdgcn_s_setprio(1); _Pragma("unroll") for (int m = 0; m < 4; ++m) _Pragma("unroll") for (int n = 0; n < 2; ++n) _Pragma("unroll") for (int k = 0; k < 2; ++k) \
;         acc[ai][bj][m][n] = __builtin_amdgcn_mfma_f32_16x16x32_bf16(Bt[n][k], At[m][k], acc[ai][bj][m][n], 0, 0, 0); __builtin_amdgcn_s_setprio(0); } while (0)
; #define PG8_WAIT_V(n) asm volatile("s_waitcnt vmcnt(" #n ")" ::: "memory")
; #define PG8_WAIT_L(n) asm volatile("s_waitcnt lgkmcnt(" #n ")" ::: "memory")
; #define PG8_BAR __builtin_amdgcn_s_barrier()
; #define PG8_SCHED __builtin_amdgcn_sched_barrier(0)
; template <class Epi, class Sched, bool ALIGN_EPI = false, bool SP2 = false>
; __device__ __forceinline__ void gemm_phase(PG8_LAS unsigned char* lds, const Gemm g, const Sched& S, const Epi& E) {
;     ...
;             PG8_LDB(B0, 1, 0); PG8_LDB(B1, 1, 1); PG8_SCHED; PG8_LDA(At, 1, 0); PG8_STAGE(PG8_SA(0, 1), a2 + hstep, voffA);
;             PG8_WAIT_V(8); PG8_WAIT_L(0); PG8_BAR; PG8_MMA(0, 0, At, B0); PG8_MMA(0, 1, At, B1); PG8_BAR; PG8_SCHED;
	s_add_i32 s66, 0, 0x18000
	s_add_i32 s67, 0, 0x1c000
	v_add_u32_e32 v162, s66, v145
	v_add_u32_e32 v178, s67, v145
	ds_read_b128 v[150:153], v162
	ds_read_b128 v[154:157], v162 offset:1024
	ds_read_b128 v[158:161], v162 offset:2048
	ds_read_b128 v[162:165], v162 offset:3072
	ds_read_b128 v[166:169], v178
	ds_read_b128 v[170:173], v178 offset:1024
	ds_read_b128 v[174:177], v178 offset:2048
	ds_read_b128 v[178:181], v178 offset:3072
	s_add_u32 s36, s36, 0x40000
	s_addc_u32 s37, s37, 0
	s_mov_b32 m0, s44
	v_lshl_add_u64 v[222:223], s[36:37], 0, v[128:129]
	ds_read_b128 v[182:185], v149 offset:32768
	ds_read_b128 v[186:189], v149 offset:33792
	ds_read_b128 v[190:193], v149 offset:34816
	ds_read_b128 v[194:197], v149 offset:35840
	ds_read_b128 v[198:201], v149 offset:36864
	ds_read_b128 v[202:205], v149 offset:37888
	ds_read_b128 v[208:211], v149 offset:38912
	ds_read_b128 v[212:215], v149 offset:39936
	global_load_lds_dwordx4 v[222:223], off
	v_lshl_add_u64 v[222:223], s[36:37], 0, v[132:133]
	s_mov_b32 m0, s45
	s_nop 0
	global_load_lds_dwordx4 v[222:223], off
	s_waitcnt vmcnt(8)
	s_waitcnt lgkmcnt(0)
	s_barrier
	s_setprio 1
	s_waitcnt lgkmcnt(0)
	v_mfma_f32_16x16x32_bf16 v[124:127], v[150:153], v[182:185], v[124:127]
	v_mfma_f32_16x16x32_bf16 v[120:123], v[158:161], v[182:185], v[120:123]
	v_mfma_f32_16x16x32_bf16 v[108:111], v[150:153], v[190:193], v[108:111]
	v_mfma_f32_16x16x32_bf16 v[104:107], v[158:161], v[190:193], v[104:107]
	v_mfma_f32_16x16x32_bf16 v[92:95], v[150:153], v[198:201], v[92:95]
	v_mfma_f32_16x16x32_bf16 v[88:91], v[158:161], v[198:201], v[88:91]
	v_mfma_f32_16x16x32_bf16 v[76:79], v[150:153], v[208:211], v[76:79]
	v_mfma_f32_16x16x32_bf16 v[72:75], v[158:161], v[208:211], v[72:75]
	v_mfma_f32_16x16x32_bf16 v[124:127], v[154:157], v[186:189], v[124:127]
	v_mfma_f32_16x16x32_bf16 v[120:123], v[162:165], v[186:189], v[120:123]
	v_mfma_f32_16x16x32_bf16 v[108:111], v[154:157], v[194:197], v[108:111]
	v_mfma_f32_16x16x32_bf16 v[104:107], v[162:165], v[194:197], v[104:107]
	v_mfma_f32_16x16x32_bf16 v[92:95], v[154:157], v[202:205], v[92:95]
	v_mfma_f32_16x16x32_bf16 v[88:91], v[162:165], v[202:205], v[88:91]
	v_mfma_f32_16x16x32_bf16 v[76:79], v[154:157], v[212:215], v[76:79]
	v_mfma_f32_16x16x32_bf16 v[72:75], v[162:165], v[212:215], v[72:75]
	v_mfma_f32_16x16x32_bf16 v[116:119], v[166:169], v[182:185], v[116:119]
	v_mfma_f32_16x16x32_bf16 v[112:115], v[174:177], v[182:185], v[112:115]
	v_mfma_f32_16x16x32_bf16 v[100:103], v[166:169], v[190:193], v[100:103]
	v_mfma_f32_16x16x32_bf16 v[96:99], v[174:177], v[190:193], v[96:99]
	v_mfma_f32_16x16x32_bf16 v[84:87], v[166:169], v[198:201], v[84:87]
	v_mfma_f32_16x16x32_bf16 v[80:83], v[174:177], v[198:201], v[80:83]
	v_mfma_f32_16x16x32_bf16 v[68:71], v[166:169], v[208:211], v[68:71]
	v_mfma_f32_16x16x32_bf16 v[64:67], v[174:177], v[208:211], v[64:67]
	v_mfma_f32_16x16x32_bf16 v[116:119], v[170:173], v[186:189], v[116:119]
	v_mfma_f32_16x16x32_bf16 v[112:115], v[178:181], v[186:189], v[112:115]
	v_mfma_f32_16x16x32_bf16 v[100:103], v[170:173], v[194:197], v[100:103]
	v_mfma_f32_16x16x32_bf16 v[96:99], v[178:181], v[194:197], v[96:99]
	v_mfma_f32_16x16x32_bf16 v[84:87], v[170:173], v[202:205], v[84:87]
	v_mfma_f32_16x16x32_bf16 v[80:83], v[178:181], v[202:205], v[80:83]
	v_mfma_f32_16x16x32_bf16 v[68:71], v[170:173], v[212:215], v[68:71]
	v_mfma_f32_16x16x32_bf16 v[64:67], v[178:181], v[212:215], v[64:67]
	s_setprio 0
	s_barrier
; #define PG8_STAGE(bufoff, gbase, voff) do { _Pragma("unroll") for (int _i = 0; _i < 2; ++_i) \
;         __builtin_amdgcn_global_load_lds((const unsigned*)((const char*)(gbase) + (voff)[_i]), (PG8_LAS unsigned*)(lds + (bufoff) + ldsw + _i * 8192), 16, 0, 0); } while (0)
; #define PG8_LDA(dst, b, h) do { _Pragma("unroll") for (int m = 0; m < 4; ++m) _Pragma("unroll") for (int k = 0; k < 2; ++k) dst[m][k] = *(const PG8_LAS bf16x8*)(lds + PG8_SA(b, h) + aoff + m * 2048 + k * 1024); } while (0)
; #define PG8_MMA(ai, bj, At, Bt) do { __builtin_amdgcn_s_setprio(1); _Pragma("unroll") for (int m = 0; m < 4; ++m) _Pragma("unroll") for (int n = 0; n < 2; ++n) _Pragma("unroll") for (int k = 0; k < 2; ++k) \
;         acc[ai][bj][m][n] = __builtin_amdgcn_mfma_f32_16x16x32_bf16(Bt[n][k], At[m][k], acc[ai][bj][m][n], 0, 0, 0); __builtin_amdgcn_s_setprio(0); } while (0)
; #define PG8_WAIT_V(n) asm volatile("s_waitcnt vmcnt(" #n ")" ::: "memory")
; #define PG8_WAIT_L(n) asm volatile("s_waitcnt lgkmcnt(" #n ")" ::: "memory")
; #define PG8_BAR __builtin_amdgcn_s_barrier()
; #define PG8_SCHED __builtin_amdgcn_sched_barrier(0)
; template <class Epi, class Sched, bool ALIGN_EPI = false, bool SP2 = false>
; __device__ __forceinline__ void gemm_phase(PG8_LAS unsigned char* lds, const Gemm g, const Sched& S, const Epi& E) {
;     ...
;             PG8_LDA(At, 1, 1); PG8_STAGE(PG8_SB(1, 0), b3, voffB); PG8_STAGE(PG8_SB(1, 1), b3 + hstep, voffB); PG8_STAGE(PG8_SA(1, 0), a3, voffA);
;             PG8_WAIT_V(8); PG8_WAIT_L(0); PG8_BAR; PG8_MMA(1, 0, At, B0); PG8_MMA(1, 1, At, B1); PG8_BAR; PG8_SCHED;
	s_add_i32 s36, s66, s41
	v_lshl_add_u64 v[142:143], v[142:143], 0, s[8:9]
	s_mov_b32 m0, s36
	ds_read_b128 v[182:185], v149 offset:49152
	ds_read_b128 v[186:189], v149 offset:50176
	ds_read_b128 v[190:193], v149 offset:51200
	ds_read_b128 v[194:197], v149 offset:52224
	ds_read_b128 v[198:201], v149 offset:53248
	ds_read_b128 v[202:205], v149 offset:54272
	ds_read_b128 v[208:211], v149 offset:55296
	ds_read_b128 v[212:215], v149 offset:56320
	global_load_lds_dwordx4 v[142:143], off
	s_add_i32 m0, s36, 0x2000
	s_add_u32 s34, s34, 0x40080
	v_lshl_add_u64 v[142:143], v[216:217], 0, s[8:9]
	s_addc_u32 s35, s35, 0
	s_add_i32 s36, s67, s41
	global_load_lds_dwordx4 v[142:143], off
	v_lshl_add_u64 v[142:143], s[34:35], 0, v[130:131]
	s_mov_b32 m0, s36
	s_nop 0
	global_load_lds_dwordx4 v[142:143], off
	v_lshl_add_u64 v[142:143], s[34:35], 0, v[134:135]
	s_add_i32 m0, s36, 0x2000
	s_nop 0
	global_load_lds_dwordx4 v[142:143], off
	v_lshl_add_u64 v[142:143], v[218:219], 0, s[8:9]
	s_mov_b32 m0, s47
	s_nop 0
	global_load_lds_dwordx4 v[142:143], off
	v_lshl_add_u64 v[142:143], v[220:221], 0, s[8:9]
	s_mov_b32 m0, s52
	s_nop 0
	global_load_lds_dwordx4 v[142:143], off
	s_waitcnt vmcnt(8)
	s_waitcnt lgkmcnt(0)
	s_barrier
	s_setprio 1
	s_waitcnt lgkmcnt(0)
	v_mfma_f32_16x16x32_bf16 v[60:63], v[150:153], v[182:185], v[60:63]
	v_mfma_f32_16x16x32_bf16 v[56:59], v[158:161], v[182:185], v[56:59]
	v_mfma_f32_16x16x32_bf16 v[44:47], v[150:153], v[190:193], v[44:47]
	v_mfma_f32_16x16x32_bf16 v[40:43], v[158:161], v[190:193], v[40:43]
	v_mfma_f32_16x16x32_bf16 v[28:31], v[150:153], v[198:201], v[28:31]
	v_mfma_f32_16x16x32_bf16 v[24:27], v[158:161], v[198:201], v[24:27]
	v_mfma_f32_16x16x32_bf16 v[12:15], v[150:153], v[208:211], v[12:15]
	v_mfma_f32_16x16x32_bf16 v[8:11], v[158:161], v[208:211], v[8:11]
	v_mfma_f32_16x16x32_bf16 v[60:63], v[154:157], v[186:189], v[60:63]
	v_mfma_f32_16x16x32_bf16 v[56:59], v[162:165], v[186:189], v[56:59]
	v_mfma_f32_16x16x32_bf16 v[44:47], v[154:157], v[194:197], v[44:47]
	v_mfma_f32_16x16x32_bf16 v[40:43], v[162:165], v[194:197], v[40:43]
	v_mfma_f32_16x16x32_bf16 v[28:31], v[154:157], v[202:205], v[28:31]
	v_mfma_f32_16x16x32_bf16 v[24:27], v[162:165], v[202:205], v[24:27]
	v_mfma_f32_16x16x32_bf16 v[12:15], v[154:157], v[212:215], v[12:15]
	v_mfma_f32_16x16x32_bf16 v[8:11], v[162:165], v[212:215], v[8:11]
	v_mfma_f32_16x16x32_bf16 v[52:55], v[166:169], v[182:185], v[52:55]
	v_mfma_f32_16x16x32_bf16 v[48:51], v[174:177], v[182:185], v[48:51]
	v_mfma_f32_16x16x32_bf16 v[36:39], v[166:169], v[190:193], v[36:39]
	v_mfma_f32_16x16x32_bf16 v[32:35], v[174:177], v[190:193], v[32:35]
	v_mfma_f32_16x16x32_bf16 v[20:23], v[166:169], v[198:201], v[20:23]
	v_mfma_f32_16x16x32_bf16 v[16:19], v[174:177], v[198:201], v[16:19]
	v_mfma_f32_16x16x32_bf16 v[4:7], v[166:169], v[208:211], v[4:7]
	v_mfma_f32_16x16x32_bf16 v[0:3], v[174:177], v[208:211], v[0:3]
	v_mfma_f32_16x16x32_bf16 v[52:55], v[170:173], v[186:189], v[52:55]
	v_mfma_f32_16x16x32_bf16 v[48:51], v[178:181], v[186:189], v[48:51]
	v_mfma_f32_16x16x32_bf16 v[36:39], v[170:173], v[194:197], v[36:39]
	v_mfma_f32_16x16x32_bf16 v[32:35], v[178:181], v[194:197], v[32:35]
	v_mfma_f32_16x16x32_bf16 v[20:23], v[170:173], v[202:205], v[20:23]
	v_mfma_f32_16x16x32_bf16 v[16:19], v[178:181], v[202:205], v[16:19]
	v_mfma_f32_16x16x32_bf16 v[4:7], v[170:173], v[212:215], v[4:7]
	v_mfma_f32_16x16x32_bf16 v[0:3], v[178:181], v[212:215], v[0:3]
	s_setprio 0
	s_barrier
	s_add_i32 s65, s65, 2
	s_add_u32 s30, s30, 0x100
	s_addc_u32 s31, s31, 0
	s_add_u32 s61, s61, 0x100
	s_addc_u32 s64, s64, 0
	s_cmp_gt_u32 s65, 13
	s_cbranch_scc0 .LBB0_1984

;     __device__ __forceinline__ bool next(int i, Unit& u) const { if (i != 0) return false; const int c0 = (G >= 8) ? G - 5 : G - 2; int k = -1; if (c == c0) k = 0; else if (c == G - 1) k = 1; if (k < 0 || k >= n) return false; u.pm = k; u.pn = 0; return true; }
; #define PG8_STAGE(bufoff, gbase, voff) do { _Pragma("unroll") for (int _i = 0; _i < 2; ++_i) \
;         __builtin_amdgcn_global_load_lds((const unsigned*)((const char*)(gbase) + (voff)[_i]), (PG8_LAS unsigned*)(lds + (bufoff) + ldsw + _i * 8192), 16, 0, 0); } while (0)
; #define PG8_LDA(dst, b, h) do { _Pragma("unroll") for (int m = 0; m < 4; ++m) _Pragma("unroll") for (int k = 0; k < 2; ++k) dst[m][k] = *(const PG8_LAS bf16x8*)(lds + PG8_SA(b, h) + aoff + m * 2048 + k * 1024); } while (0)
; #define PG8_LDB(dst, b, h) do { _Pragma("unroll") for (int n = 0; n < 2; ++n) _Pragma("unroll") for (int k = 0; k < 2; ++k) dst[n][k] = *(const PG8_LAS bf16x8*)(lds + PG8_SB(b, h) + boff + n * 2048 + k * 1024); } while (0)
; template <class Epi, class Sched, bool ALIGN_EPI = false, bool SP2 = false>
; __device__ __forceinline__ void gemm_phase(PG8_LAS unsigned char* lds, const Gemm g, const Sched& S, const Epi& E) {
;     ...
;         const bool has_next = S.next(ui + 1, nxt);
;         const char* nA = has_next ? (const char*)g.A + (size_t)nxt.pm * tstep : cA; const char* nB = has_next ? (const char*)g.Bt + (size_t)nxt.pn * tstep : cB;
;         for (int t = 0; t < nt; t += 2) {
;             const bool last = (t == nt - 2);
;             const char* a1 = cA + (size_t)(t + 1) * kstep;
;             const char* a2 = last ? nA : cA + (size_t)(t + 2) * kstep; const char* b2 = last ? nB : cB + (size_t)(t + 2) * kstep;
;             const char* a3 = a2 + kstep; const char* b3 = b2 + kstep;
;             if (last && has_next) S.a_ready(nxt);
;             if constexpr (SP2) {
;             PG8_LDB(B0, 0, 0); PG8_LDB(B1, 0, 1); PG8_SCHED; PG8_LDA(At, 0, 0); PG8_STAGE(PG8_SA(1, 1), a1 + hstep, voffA);
;             PG8_WAIT_V(8); PG8_WAIT_L(0); PG8_BAR; PG8_MMA(0, 0, At, B0); PG8_MMA(0, 1, At, B1); PG8_BAR; PG8_SCHED;
;             PG8_LDA(At, 0, 1); PG8_STAGE(PG8_SB(0, 0), b2, voffB); PG8_STAGE(PG8_SB(0, 1), b2 + hstep, voffB); PG8_STAGE(PG8_SA(0, 0), a2, voffA);
;             PG8_WAIT_V(8); PG8_WAIT_L(0); PG8_BAR; PG8_MMA(1, 0, At, B0); PG8_MMA(1, 1, At, B1); PG8_BAR; PG8_SCHED;
.LBB0_2092:
	s_add_u32 s38, s38, 0xb0080
	s_addc_u32 s39, s39, 0
	s_add_u32 s74, s40, 0x100
	v_mov_b32_e32 v0, 0
	s_addc_u32 s75, s41, 0
	s_mov_b32 s76, -2
	ds_read_b128 v[148:151], v145
	ds_read_b128 v[152:155], v145 offset:1024
	ds_read_b128 v[156:159], v145 offset:2048
	ds_read_b128 v[160:163], v145 offset:3072
	ds_read_b128 v[164:167], v146
	ds_read_b128 v[168:171], v146 offset:1024
	ds_read_b128 v[172:175], v146 offset:2048
	ds_read_b128 v[176:179], v146 offset:3072
	s_add_u32 s40, s38, 0xfff50080
	s_addc_u32 s41, s39, -1
	s_cmp_eq_u32 s76, 40
	s_cselect_b32 s43, s35, s41
	s_cselect_b32 s42, s34, s40
	s_cselect_b32 s41, s37, s75
	s_cselect_b32 s40, s36, s74
	v_lshl_add_u64 v[204:205], s[38:39], 0, v[136:137]
	s_add_i32 m0, s57, 0xc000
	ds_read_b128 v[180:183], v147
	ds_read_b128 v[184:187], v147 offset:1024
	ds_read_b128 v[188:191], v147 offset:2048
	ds_read_b128 v[192:195], v147 offset:3072
	ds_read_b128 v[196:199], v147 offset:4096
	ds_read_b128 v[200:203], v147 offset:5120
	ds_read_b128 v[208:211], v147 offset:6144
	ds_read_b128 v[212:215], v147 offset:7168
	global_load_lds_dwordx4 v[204:205], off
	v_lshl_add_u64 v[204:205], s[38:39], 0, v[138:139]
	s_add_i32 m0, s57, 0xe000
	s_nop 0
	global_load_lds_dwordx4 v[204:205], off
	s_waitcnt vmcnt(8)
	s_waitcnt lgkmcnt(0)
	s_barrier
	s_setprio 1
	s_waitcnt lgkmcnt(0)
	v_mfma_f32_16x16x32_bf16 v[124:127], v[148:151], v[180:183], 0
	v_mfma_f32_16x16x32_bf16 v[120:123], v[156:159], v[180:183], 0
	v_mfma_f32_16x16x32_bf16 v[116:119], v[148:151], v[188:191], 0
	v_mfma_f32_16x16x32_bf16 v[112:115], v[156:159], v[188:191], 0
	v_mfma_f32_16x16x32_bf16 v[100:103], v[148:151], v[196:199], 0
	v_mfma_f32_16x16x32_bf16 v[96:99], v[156:159], v[196:199], 0
	v_mfma_f32_16x16x32_bf16 v[84:87], v[148:151], v[208:211], 0
	v_mfma_f32_16x16x32_bf16 v[80:83], v[156:159], v[208:211], 0
	v_mfma_f32_16x16x32_bf16 v[124:127], v[152:155], v[184:187], v[124:127]
	v_mfma_f32_16x16x32_bf16 v[120:123], v[160:163], v[184:187], v[120:123]
	v_mfma_f32_16x16x32_bf16 v[116:119], v[152:155], v[192:195], v[116:119]
	v_mfma_f32_16x16x32_bf16 v[112:115], v[160:163], v[192:195], v[112:115]
	v_mfma_f32_16x16x32_bf16 v[100:103], v[152:155], v[200:203], v[100:103]
	v_mfma_f32_16x16x32_bf16 v[96:99], v[160:163], v[200:203], v[96:99]
	v_mfma_f32_16x16x32_bf16 v[84:87], v[152:155], v[212:215], v[84:87]
	v_mfma_f32_16x16x32_bf16 v[80:83], v[160:163], v[212:215], v[80:83]
	v_mfma_f32_16x16x32_bf16 v[108:111], v[164:167], v[180:183], 0
	v_mfma_f32_16x16x32_bf16 v[104:107], v[172:175], v[180:183], 0
	v_mfma_f32_16x16x32_bf16 v[92:95], v[164:167], v[188:191], 0
	v_mfma_f32_16x16x32_bf16 v[88:91], v[172:175], v[188:191], 0
	v_mfma_f32_16x16x32_bf16 v[76:79], v[164:167], v[196:199], 0
	v_mfma_f32_16x16x32_bf16 v[72:75], v[172:175], v[196:199], 0
	v_mfma_f32_16x16x32_bf16 v[68:71], v[164:167], v[208:211], 0
	v_mfma_f32_16x16x32_bf16 v[64:67], v[172:175], v[208:211], 0
	v_mfma_f32_16x16x32_bf16 v[108:111], v[168:171], v[184:187], v[108:111]
	v_mfma_f32_16x16x32_bf16 v[104:107], v[176:179], v[184:187], v[104:107]
	v_mfma_f32_16x16x32_bf16 v[92:95], v[168:171], v[192:195], v[92:95]
	v_mfma_f32_16x16x32_bf16 v[88:91], v[176:179], v[192:195], v[88:91]
	v_mfma_f32_16x16x32_bf16 v[76:79], v[168:171], v[200:203], v[76:79]
	v_mfma_f32_16x16x32_bf16 v[72:75], v[176:179], v[200:203], v[72:75]
	v_mfma_f32_16x16x32_bf16 v[68:71], v[168:171], v[212:215], v[68:71]
	v_mfma_f32_16x16x32_bf16 v[64:67], v[176:179], v[212:215], v[64:67]
	s_setprio 0
	s_barrier
	s_add_i32 s77, s64, s52
	v_lshl_add_u64 v[204:205], s[40:41], 0, v[130:131]
	s_mov_b32 m0, s77
	ds_read_b128 v[180:183], v147 offset:16384
	ds_read_b128 v[184:187], v147 offset:17408
	ds_read_b128 v[188:191], v147 offset:18432
	ds_read_b128 v[192:195], v147 offset:19456
	ds_read_b128 v[196:199], v147 offset:20480
	ds_read_b128 v[200:203], v147 offset:21504
	ds_read_b128 v[208:211], v147 offset:22528
	ds_read_b128 v[212:215], v147 offset:23552
	global_load_lds_dwordx4 v[204:205], off
	s_add_i32 m0, s77, 0x2000
	s_add_u32 s78, s40, 0xb0000
	v_lshl_add_u64 v[216:217], s[40:41], 0, v[134:135]
	s_addc_u32 s79, s41, 0
	s_add_i32 s77, s65, s52
	global_load_lds_dwordx4 v[216:217], off
	v_lshl_add_u64 v[218:219], s[78:79], 0, v[130:131]
	s_mov_b32 m0, s77
	v_lshl_add_u64 v[220:221], s[42:43], 0, v[132:133]
	global_load_lds_dwordx4 v[218:219], off
	v_lshl_add_u64 v[218:219], s[78:79], 0, v[134:135]
	s_add_i32 m0, s77, 0x2000
	s_nop 0
	global_load_lds_dwordx4 v[218:219], off
	v_lshl_add_u64 v[218:219], s[42:43], 0, v[128:129]
	s_mov_b32 m0, s57
	s_nop 0
	global_load_lds_dwordx4 v[218:219], off
	s_mov_b32 m0, s58
	s_nop 0
	global_load_lds_dwordx4 v[220:221], off
	s_waitcnt vmcnt(8)
	s_waitcnt lgkmcnt(0)
	s_barrier
; #define PG8_STAGE(bufoff, gbase, voff) do { _Pragma("unroll") for (int _i = 0; _i < 2; ++_i) \
;         __builtin_amdgcn_global_load_lds((const unsigned*)((const char*)(gbase) + (voff)[_i]), (PG8_LAS unsigned*)(lds + (bufoff) + ldsw + _i * 8192), 16, 0, 0); } while (0)
; #define PG8_LDA(dst, b, h) do { _Pragma("unroll") for (int m = 0; m < 4; ++m) _Pragma("unroll") for (int k = 0; k < 2; ++k) dst[m][k] = *(const PG8_LAS bf16x8*)(lds + PG8_SA(b, h) + aoff + m * 2048 + k * 1024); } while (0)
; #define PG8_LDB(dst, b, h) do { _Pragma("unroll") for (int n = 0; n < 2; ++n) _Pragma("unroll") for (int k = 0; k < 2; ++k) dst[n][k] = *(const PG8_LAS bf16x8*)(lds + PG8_SB(b, h) + boff + n * 2048 + k * 1024); } while (0)
; #define PG8_MMA(ai, bj, At, Bt) do { __builtin_amdgcn_s_setprio(1); _Pragma("unroll") for (int m = 0; m < 4; ++m) _Pragma("unroll") for (int n = 0; n < 2; ++n) _Pragma("unroll") for (int k = 0; k < 2; ++k) \
;         acc[ai][bj][m][n] = __builtin_amdgcn_mfma_f32_16x16x32_bf16(Bt[n][k], At[m][k], acc[ai][bj][m][n], 0, 0, 0); __builtin_amdgcn_s_setprio(0); } while (0)
; #define PG8_WAIT_V(n) asm volatile("s_waitcnt vmcnt(" #n ")" ::: "memory")
; #define PG8_WAIT_L(n) asm volatile("s_waitcnt lgkmcnt(" #n ")" ::: "memory")
; #define PG8_BAR __builtin_amdgcn_s_barrier()
; #define PG8_SCHED __builtin_amdgcn_sched_barrier(0)
; template <class Epi, class Sched, bool ALIGN_EPI = false, bool SP2 = false>
; __device__ __forceinline__ void gemm_phase(PG8_LAS unsigned char* lds, const Gemm g, const Sched& S, const Epi& E) {
;     ...
;             PG8_WAIT_V(8); PG8_WAIT_L(0); PG8_BAR; PG8_MMA(1, 0, At, B0); PG8_MMA(1, 1, At, B1); PG8_BAR; PG8_SCHED;
;             PG8_LDB(B0, 1, 0); PG8_LDB(B1, 1, 1); PG8_SCHED; PG8_LDA(At, 1, 0); PG8_STAGE(PG8_SA(0, 1), a2 + hstep, voffA);
;             PG8_WAIT_V(8); PG8_WAIT_L(0); PG8_BAR; PG8_MMA(0, 0, At, B0); PG8_MMA(0, 1, At, B1); PG8_BAR; PG8_SCHED;
	s_setprio 1
	s_waitcnt lgkmcnt(0)
	v_mfma_f32_16x16x32_bf16 v[60:63], v[148:151], v[180:183], 0
	v_mfma_f32_16x16x32_bf16 v[56:59], v[156:159], v[180:183], 0
	v_mfma_f32_16x16x32_bf16 v[52:55], v[148:151], v[188:191], 0
	v_mfma_f32_16x16x32_bf16 v[48:51], v[156:159], v[188:191], 0
	v_mfma_f32_16x16x32_bf16 v[36:39], v[148:151], v[196:199], 0
	v_mfma_f32_16x16x32_bf16 v[32:35], v[156:159], v[196:199], 0
	v_mfma_f32_16x16x32_bf16 v[20:23], v[148:151], v[208:211], 0
	v_mfma_f32_16x16x32_bf16 v[16:19], v[156:159], v[208:211], 0
	v_mfma_f32_16x16x32_bf16 v[60:63], v[152:155], v[184:187], v[60:63]
	v_mfma_f32_16x16x32_bf16 v[56:59], v[160:163], v[184:187], v[56:59]
	v_mfma_f32_16x16x32_bf16 v[52:55], v[152:155], v[192:195], v[52:55]
	v_mfma_f32_16x16x32_bf16 v[48:51], v[160:163], v[192:195], v[48:51]
	v_mfma_f32_16x16x32_bf16 v[36:39], v[152:155], v[200:203], v[36:39]
	v_mfma_f32_16x16x32_bf16 v[32:35], v[160:163], v[200:203], v[32:35]
	v_mfma_f32_16x16x32_bf16 v[20:23], v[152:155], v[212:215], v[20:23]
	v_mfma_f32_16x16x32_bf16 v[16:19], v[160:163], v[212:215], v[16:19]
	v_mfma_f32_16x16x32_bf16 v[44:47], v[164:167], v[180:183], 0
	v_mfma_f32_16x16x32_bf16 v[40:43], v[172:175], v[180:183], 0
	v_mfma_f32_16x16x32_bf16 v[28:31], v[164:167], v[188:191], 0
	v_mfma_f32_16x16x32_bf16 v[24:27], v[172:175], v[188:191], 0
	v_mfma_f32_16x16x32_bf16 v[12:15], v[164:167], v[196:199], 0
	v_mfma_f32_16x16x32_bf16 v[8:11], v[172:175], v[196:199], 0
	v_mfma_f32_16x16x32_bf16 v[4:7], v[164:167], v[208:211], 0
	v_mfma_f32_16x16x32_bf16 v[0:3], v[172:175], v[208:211], 0
	v_mfma_f32_16x16x32_bf16 v[44:47], v[168:171], v[184:187], v[44:47]
	v_mfma_f32_16x16x32_bf16 v[40:43], v[176:179], v[184:187], v[40:43]
	v_mfma_f32_16x16x32_bf16 v[28:31], v[168:171], v[192:195], v[28:31]
	v_mfma_f32_16x16x32_bf16 v[24:27], v[176:179], v[192:195], v[24:27]
	v_mfma_f32_16x16x32_bf16 v[12:15], v[168:171], v[200:203], v[12:15]
	v_mfma_f32_16x16x32_bf16 v[8:11], v[176:179], v[200:203], v[8:11]
	v_mfma_f32_16x16x32_bf16 v[4:7], v[168:171], v[212:215], v[4:7]
	v_mfma_f32_16x16x32_bf16 v[0:3], v[176:179], v[212:215], v[0:3]
	s_setprio 0
	s_barrier
	s_add_i32 s77, 0, 0x18000
	s_add_i32 s78, 0, 0x1c000
	v_add_u32_e32 v160, s77, v143
	v_add_u32_e32 v176, s78, v143
	ds_read_b128 v[148:151], v160
	ds_read_b128 v[152:155], v160 offset:1024
	ds_read_b128 v[156:159], v160 offset:2048
	ds_read_b128 v[160:163], v160 offset:3072
	ds_read_b128 v[164:167], v176
	ds_read_b128 v[168:171], v176 offset:1024
	ds_read_b128 v[172:175], v176 offset:2048
	ds_read_b128 v[176:179], v176 offset:3072
	s_add_u32 s42, s42, 0xb0000
	s_addc_u32 s43, s43, 0
	s_mov_b32 m0, s59
	v_lshl_add_u64 v[222:223], s[42:43], 0, v[128:129]
	ds_read_b128 v[180:183], v147 offset:32768
	ds_read_b128 v[184:187], v147 offset:33792
	ds_read_b128 v[188:191], v147 offset:34816
	ds_read_b128 v[192:195], v147 offset:35840
	ds_read_b128 v[196:199], v147 offset:36864
	ds_read_b128 v[200:203], v147 offset:37888
	ds_read_b128 v[208:211], v147 offset:38912
	ds_read_b128 v[212:215], v147 offset:39936
	global_load_lds_dwordx4 v[222:223], off
	v_lshl_add_u64 v[222:223], s[42:43], 0, v[132:133]
	s_mov_b32 m0, s60
	s_nop 0
	global_load_lds_dwordx4 v[222:223], off
	s_waitcnt vmcnt(8)
	s_waitcnt lgkmcnt(0)
	s_barrier
	s_setprio 1
	s_waitcnt lgkmcnt(0)
	v_mfma_f32_16x16x32_bf16 v[124:127], v[148:151], v[180:183], v[124:127]
	v_mfma_f32_16x16x32_bf16 v[120:123], v[156:159], v[180:183], v[120:123]
	v_mfma_f32_16x16x32_bf16 v[116:119], v[148:151], v[188:191], v[116:119]
	v_mfma_f32_16x16x32_bf16 v[112:115], v[156:159], v[188:191], v[112:115]
	v_mfma_f32_16x16x32_bf16 v[100:103], v[148:151], v[196:199], v[100:103]
	v_mfma_f32_16x16x32_bf16 v[96:99], v[156:159], v[196:199], v[96:99]
	v_mfma_f32_16x16x32_bf16 v[84:87], v[148:151], v[208:211], v[84:87]
	v_mfma_f32_16x16x32_bf16 v[80:83], v[156:159], v[208:211], v[80:83]
	v_mfma_f32_16x16x32_bf16 v[124:127], v[152:155], v[184:187], v[124:127]
	v_mfma_f32_16x16x32_bf16 v[120:123], v[160:163], v[184:187], v[120:123]
	v_mfma_f32_16x16x32_bf16 v[116:119], v[152:155], v[192:195], v[116:119]
	v_mfma_f32_16x16x32_bf16 v[112:115], v[160:163], v[192:195], v[112:115]
	v_mfma_f32_16x16x32_bf16 v[100:103], v[152:155], v[200:203], v[100:103]
	v_mfma_f32_16x16x32_bf16 v[96:99], v[160:163], v[200:203], v[96:99]
	v_mfma_f32_16x16x32_bf16 v[84:87], v[152:155], v[212:215], v[84:87]
	v_mfma_f32_16x16x32_bf16 v[80:83], v[160:163], v[212:215], v[80:83]
	v_mfma_f32_16x16x32_bf16 v[108:111], v[164:167], v[180:183], v[108:111]
	v_mfma_f32_16x16x32_bf16 v[104:107], v[172:175], v[180:183], v[104:107]
	v_mfma_f32_16x16x32_bf16 v[92:95], v[164:167], v[188:191], v[92:95]
	v_mfma_f32_16x16x32_bf16 v[88:91], v[172:175], v[188:191], v[88:91]
	v_mfma_f32_16x16x32_bf16 v[76:79], v[164:167], v[196:199], v[76:79]
	v_mfma_f32_16x16x32_bf16 v[72:75], v[172:175], v[196:199], v[72:75]
	v_mfma_f32_16x16x32_bf16 v[68:71], v[164:167], v[208:211], v[68:71]
	v_mfma_f32_16x16x32_bf16 v[64:67], v[172:175], v[208:211], v[64:67]
	v_mfma_f32_16x16x32_bf16 v[108:111], v[168:171], v[184:187], v[108:111]
	v_mfma_f32_16x16x32_bf16 v[104:107], v[176:179], v[184:187], v[104:107]
	v_mfma_f32_16x16x32_bf16 v[92:95], v[168:171], v[192:195], v[92:95]
	v_mfma_f32_16x16x32_bf16 v[88:91], v[176:179], v[192:195], v[88:91]
	v_mfma_f32_16x16x32_bf16 v[76:79], v[168:171], v[200:203], v[76:79]
	v_mfma_f32_16x16x32_bf16 v[72:75], v[176:179], v[200:203], v[72:75]
	v_mfma_f32_16x16x32_bf16 v[68:71], v[168:171], v[212:215], v[68:71]
	v_mfma_f32_16x16x32_bf16 v[64:67], v[176:179], v[212:215], v[64:67]
	s_setprio 0
	s_barrier
; #define PG8_STAGE(bufoff, gbase, voff) do { _Pragma("unroll") for (int _i = 0; _i < 2; ++_i) \
;         __builtin_amdgcn_global_load_lds((const unsigned*)((const char*)(gbase) + (voff)[_i]), (PG8_LAS unsigned*)(lds + (bufoff) + ldsw + _i * 8192), 16, 0, 0); } while (0)
; #define PG8_LDA(dst, b, h) do { _Pragma("unroll") for (int m = 0; m < 4; ++m) _Pragma("unroll") for (int k = 0; k < 2; ++k) dst[m][k] = *(const PG8_LAS bf16x8*)(lds + PG8_SA(b, h) + aoff + m * 2048 + k * 1024); } while (0)
; #define PG8_LDB(dst, b, h) do { _Pragma("unroll") for (int n = 0; n < 2; ++n) _Pragma("unroll") for (int k = 0; k < 2; ++k) dst[n][k] = *(const PG8_LAS bf16x8*)(lds + PG8_SB(b, h) + boff + n * 2048 + k * 1024); } while (0)
; #define PG8_MMA(ai, bj, At, Bt) do { __builtin_amdgcn_s_setprio(1); _Pragma("unroll") for (int m = 0; m < 4; ++m) _Pragma("unroll") for (int n = 0; n < 2; ++n) _Pragma("unroll") for (int k = 0; k < 2; ++k) \
;         acc[ai][bj][m][n] = __builtin_amdgcn_mfma_f32_16x16x32_bf16(Bt[n][k], At[m][k], acc[ai][bj][m][n], 0, 0, 0); __builtin_amdgcn_s_setprio(0); } while (0)
; #define PG8_WAIT_V(n) asm volatile("s_waitcnt vmcnt(" #n ")" ::: "memory")
; template <class Epi, class Sched, bool ALIGN_EPI = false, bool SP2 = false>
; __device__ __forceinline__ void gemm_phase(PG8_LAS unsigned char* lds, const Gemm g, const Sched& S, const Epi& E) {
;     ...
;             PG8_LDB(B0, 0, 0); PG8_LDB(B1, 0, 1); PG8_SCHED; PG8_LDA(At, 0, 0); PG8_STAGE(PG8_SA(1, 1), a1 + hstep, voffA);
;             PG8_WAIT_V(8); PG8_WAIT_L(0); PG8_BAR; PG8_MMA(0, 0, At, B0); PG8_MMA(0, 1, At, B1); PG8_BAR; PG8_SCHED;
;             PG8_LDA(At, 0, 1); PG8_STAGE(PG8_SB(0, 0), b2, voffB); PG8_STAGE(PG8_SB(0, 1), b2 + hstep, voffB); PG8_STAGE(PG8_SA(0, 0), a2, voffA);
;             PG8_WAIT_V(8); PG8_WAIT_L(0); PG8_BAR; PG8_MMA(1, 0, At, B0); PG8_MMA(1, 1, At, B1); PG8_BAR; PG8_SCHED;
;             PG8_LDB(B0, 1, 0); PG8_LDB(B1, 1, 1); PG8_SCHED; PG8_LDA(At, 1, 0); PG8_STAGE(PG8_SA(0, 1), a2 + hstep, voffA);
;             PG8_WAIT_V(8); PG8_WAIT_L(0); PG8_BAR; PG8_MMA(0, 0, At, B0); PG8_MMA(0, 1, At, B1); PG8_BAR; PG8_SCHED;
;             PG8_LDA(At, 1, 1); PG8_STAGE(PG8_SB(1, 0), b3, voffB); PG8_STAGE(PG8_SB(1, 1), b3 + hstep, voffB); PG8_STAGE(PG8_SA(1, 0), a3, voffA);
;             PG8_WAIT_V(8); PG8_WAIT_L(0); PG8_BAR; PG8_MMA(1, 0, At, B0); PG8_MMA(1, 1, At, B1); PG8_BAR; PG8_SCHED;
	s_add_i32 s42, s77, s52
	v_lshl_add_u64 v[204:205], v[204:205], 0, s[18:19]
	s_mov_b32 m0, s42
	ds_read_b128 v[180:183], v147 offset:49152
	ds_read_b128 v[184:187], v147 offset:50176
	ds_read_b128 v[188:191], v147 offset:51200
	ds_read_b128 v[192:195], v147 offset:52224
	ds_read_b128 v[196:199], v147 offset:53248
	ds_read_b128 v[200:203], v147 offset:54272
	ds_read_b128 v[208:211], v147 offset:55296
	ds_read_b128 v[212:215], v147 offset:56320
	global_load_lds_dwordx4 v[204:205], off
	s_add_i32 m0, s42, 0x2000
	s_add_u32 s40, s40, 0xb0080
	v_lshl_add_u64 v[204:205], v[216:217], 0, s[18:19]
	s_addc_u32 s41, s41, 0
	s_add_i32 s42, s78, s52
	global_load_lds_dwordx4 v[204:205], off
	v_lshl_add_u64 v[204:205], s[40:41], 0, v[130:131]
	s_mov_b32 m0, s42
	s_nop 0
	global_load_lds_dwordx4 v[204:205], off
	v_lshl_add_u64 v[204:205], s[40:41], 0, v[134:135]
	s_add_i32 m0, s42, 0x2000
	s_nop 0
	global_load_lds_dwordx4 v[204:205], off
	v_lshl_add_u64 v[204:205], v[218:219], 0, s[18:19]
	s_mov_b32 m0, s62
	s_nop 0
	global_load_lds_dwordx4 v[204:205], off
	v_lshl_add_u64 v[204:205], v[220:221], 0, s[18:19]
	s_mov_b32 m0, s63
	s_nop 0
	global_load_lds_dwordx4 v[204:205], off
	s_waitcnt vmcnt(8)
	s_waitcnt lgkmcnt(0)
	s_barrier
	s_setprio 1
	s_waitcnt lgkmcnt(0)
	v_mfma_f32_16x16x32_bf16 v[60:63], v[148:151], v[180:183], v[60:63]
	v_mfma_f32_16x16x32_bf16 v[56:59], v[156:159], v[180:183], v[56:59]
	v_mfma_f32_16x16x32_bf16 v[52:55], v[148:151], v[188:191], v[52:55]
	v_mfma_f32_16x16x32_bf16 v[48:51], v[156:159], v[188:191], v[48:51]
	v_mfma_f32_16x16x32_bf16 v[36:39], v[148:151], v[196:199], v[36:39]
	v_mfma_f32_16x16x32_bf16 v[32:35], v[156:159], v[196:199], v[32:35]
	v_mfma_f32_16x16x32_bf16 v[20:23], v[148:151], v[208:211], v[20:23]
	v_mfma_f32_16x16x32_bf16 v[16:19], v[156:159], v[208:211], v[16:19]
	v_mfma_f32_16x16x32_bf16 v[60:63], v[152:155], v[184:187], v[60:63]
	v_mfma_f32_16x16x32_bf16 v[56:59], v[160:163], v[184:187], v[56:59]
	v_mfma_f32_16x16x32_bf16 v[52:55], v[152:155], v[192:195], v[52:55]
	v_mfma_f32_16x16x32_bf16 v[48:51], v[160:163], v[192:195], v[48:51]
	v_mfma_f32_16x16x32_bf16 v[36:39], v[152:155], v[200:203], v[36:39]
	v_mfma_f32_16x16x32_bf16 v[32:35], v[160:163], v[200:203], v[32:35]
	v_mfma_f32_16x16x32_bf16 v[20:23], v[152:155], v[212:215], v[20:23]
	v_mfma_f32_16x16x32_bf16 v[16:19], v[160:163], v[212:215], v[16:19]
	v_mfma_f32_16x16x32_bf16 v[44:47], v[164:167], v[180:183], v[44:47]
	v_mfma_f32_16x16x32_bf16 v[40:43], v[172:175], v[180:183], v[40:43]
	v_mfma_f32_16x16x32_bf16 v[28:31], v[164:167], v[188:191], v[28:31]
	v_mfma_f32_16x16x32_bf16 v[24:27], v[172:175], v[188:191], v[24:27]
	v_mfma_f32_16x16x32_bf16 v[12:15], v[164:167], v[196:199], v[12:15]
	v_mfma_f32_16x16x32_bf16 v[8:11], v[172:175], v[196:199], v[8:11]
	v_mfma_f32_16x16x32_bf16 v[4:7], v[164:167], v[208:211], v[4:7]
	v_mfma_f32_16x16x32_bf16 v[0:3], v[172:175], v[208:211], v[0:3]
	v_mfma_f32_16x16x32_bf16 v[44:47], v[168:171], v[184:187], v[44:47]
	v_mfma_f32_16x16x32_bf16 v[40:43], v[176:179], v[184:187], v[40:43]
	v_mfma_f32_16x16x32_bf16 v[28:31], v[168:171], v[192:195], v[28:31]
	v_mfma_f32_16x16x32_bf16 v[24:27], v[176:179], v[192:195], v[24:27]
	v_mfma_f32_16x16x32_bf16 v[12:15], v[168:171], v[200:203], v[12:15]
	v_mfma_f32_16x16x32_bf16 v[8:11], v[176:179], v[200:203], v[8:11]
	v_mfma_f32_16x16x32_bf16 v[4:7], v[168:171], v[212:215], v[4:7]
	v_mfma_f32_16x16x32_bf16 v[0:3], v[176:179], v[212:215], v[0:3]
	s_setprio 0
	s_barrier
	s_add_i32 s76, s76, 2
	s_add_u32 s38, s38, 0x100
	s_addc_u32 s39, s39, 0
	s_add_u32 s74, s74, 0x100
	s_addc_u32 s75, s75, 0
	s_cmp_gt_u32 s76, 41
	s_cbranch_scc0 .LBB0_2093
	s_branch .Lpeel_exit_16
.LBB0_2093:
	ds_read_b128 v[148:151], v145
	ds_read_b128 v[152:155], v145 offset:1024
	ds_read_b128 v[156:159], v145 offset:2048
	ds_read_b128 v[160:163], v145 offset:3072
	ds_read_b128 v[164:167], v146
	ds_read_b128 v[168:171], v146 offset:1024
	ds_read_b128 v[172:175], v146 offset:2048
	ds_read_b128 v[176:179], v146 offset:3072
	s_add_u32 s40, s38, 0xfff50080
	s_addc_u32 s41, s39, -1
	s_cmp_eq_u32 s76, 40
	s_cselect_b32 s43, s35, s41
	s_cselect_b32 s42, s34, s40
	s_cselect_b32 s41, s37, s75
	s_cselect_b32 s40, s36, s74
	v_lshl_add_u64 v[204:205], s[38:39], 0, v[136:137]
	s_add_i32 m0, s57, 0xc000
	ds_read_b128 v[180:183], v147
	ds_read_b128 v[184:187], v147 offset:1024
	ds_read_b128 v[188:191], v147 offset:2048
	ds_read_b128 v[192:195], v147 offset:3072
	ds_read_b128 v[196:199], v147 offset:4096
	ds_read_b128 v[200:203], v147 offset:5120
	ds_read_b128 v[208:211], v147 offset:6144
	ds_read_b128 v[212:215], v147 offset:7168
	global_load_lds_dwordx4 v[204:205], off
	v_lshl_add_u64 v[204:205], s[38:39], 0, v[138:139]
	s_add_i32 m0, s57, 0xe000
	s_nop 0
	global_load_lds_dwordx4 v[204:205], off
	s_waitcnt vmcnt(8)
	s_waitcnt lgkmcnt(0)
	s_barrier
; #define PG8_STAGE(bufoff, gbase, voff) do { _Pragma("unroll") for (int _i = 0; _i < 2; ++_i) \
;         __builtin_amdgcn_global_load_lds((const unsigned*)((const char*)(gbase) + (voff)[_i]), (PG8_LAS unsigned*)(lds + (bufoff) + ldsw + _i * 8192), 16, 0, 0); } while (0)
; #define PG8_LDA(dst, b, h) do { _Pragma("unroll") for (int m = 0; m < 4; ++m) _Pragma("unroll") for (int k = 0; k < 2; ++k) dst[m][k] = *(const PG8_LAS bf16x8*)(lds + PG8_SA(b, h) + aoff + m * 2048 + k * 1024); } while (0)
; #define PG8_MMA(ai, bj, At, Bt) do { __builtin_amdgcn_s_setprio(1); _Pragma("unroll") for (int m = 0; m < 4; ++m) _Pragma("unroll") for (int n = 0; n < 2; ++n) _Pragma("unroll") for (int k = 0; k < 2; ++k) \
;         acc[ai][bj][m][n] = __builtin_amdgcn_mfma_f32_16x16x32_bf16(Bt[n][k], At[m][k], acc[ai][bj][m][n], 0, 0, 0); __builtin_amdgcn_s_setprio(0); } while (0)
; #define PG8_WAIT_V(n) asm volatile("s_waitcnt vmcnt(" #n ")" ::: "memory")
; #define PG8_WAIT_L(n) asm volatile("s_waitcnt lgkmcnt(" #n ")" ::: "memory")
; #define PG8_BAR __builtin_amdgcn_s_barrier()
; #define PG8_SCHED __builtin_amdgcn_sched_barrier(0)
; template <class Epi, class Sched, bool ALIGN_EPI = false, bool SP2 = false>
; __device__ __forceinline__ void gemm_phase(PG8_LAS unsigned char* lds, const Gemm g, const Sched& S, const Epi& E) {
;     ...
;             PG8_WAIT_V(8); PG8_WAIT_L(0); PG8_BAR; PG8_MMA(0, 0, At, B0); PG8_MMA(0, 1, At, B1); PG8_BAR; PG8_SCHED;
;             PG8_LDA(At, 0, 1); PG8_STAGE(PG8_SB(0, 0), b2, voffB); PG8_STAGE(PG8_SB(0, 1), b2 + hstep, voffB); PG8_STAGE(PG8_SA(0, 0), a2, voffA);
;             PG8_WAIT_V(8); PG8_WAIT_L(0); PG8_BAR; PG8_MMA(1, 0, At, B0); PG8_MMA(1, 1, At, B1); PG8_BAR; PG8_SCHED;
	s_setprio 1
	s_waitcnt lgkmcnt(0)
	v_mfma_f32_16x16x32_bf16 v[124:127], v[148:151], v[180:183], v[124:127]
	v_mfma_f32_16x16x32_bf16 v[120:123], v[156:159], v[180:183], v[120:123]
	v_mfma_f32_16x16x32_bf16 v[116:119], v[148:151], v[188:191], v[116:119]
	v_mfma_f32_16x16x32_bf16 v[112:115], v[156:159], v[188:191], v[112:115]
	v_mfma_f32_16x16x32_bf16 v[100:103], v[148:151], v[196:199], v[100:103]
	v_mfma_f32_16x16x32_bf16 v[96:99], v[156:159], v[196:199], v[96:99]
	v_mfma_f32_16x16x32_bf16 v[84:87], v[148:151], v[208:211], v[84:87]
	v_mfma_f32_16x16x32_bf16 v[80:83], v[156:159], v[208:211], v[80:83]
	v_mfma_f32_16x16x32_bf16 v[124:127], v[152:155], v[184:187], v[124:127]
	v_mfma_f32_16x16x32_bf16 v[120:123], v[160:163], v[184:187], v[120:123]
	v_mfma_f32_16x16x32_bf16 v[116:119], v[152:155], v[192:195], v[116:119]
	v_mfma_f32_16x16x32_bf16 v[112:115], v[160:163], v[192:195], v[112:115]
	v_mfma_f32_16x16x32_bf16 v[100:103], v[152:155], v[200:203], v[100:103]
	v_mfma_f32_16x16x32_bf16 v[96:99], v[160:163], v[200:203], v[96:99]
	v_mfma_f32_16x16x32_bf16 v[84:87], v[152:155], v[212:215], v[84:87]
	v_mfma_f32_16x16x32_bf16 v[80:83], v[160:163], v[212:215], v[80:83]
	v_mfma_f32_16x16x32_bf16 v[108:111], v[164:167], v[180:183], v[108:111]
	v_mfma_f32_16x16x32_bf16 v[104:107], v[172:175], v[180:183], v[104:107]
	v_mfma_f32_16x16x32_bf16 v[92:95], v[164:167], v[188:191], v[92:95]
	v_mfma_f32_16x16x32_bf16 v[88:91], v[172:175], v[188:191], v[88:91]
	v_mfma_f32_16x16x32_bf16 v[76:79], v[164:167], v[196:199], v[76:79]
	v_mfma_f32_16x16x32_bf16 v[72:75], v[172:175], v[196:199], v[72:75]
	v_mfma_f32_16x16x32_bf16 v[68:71], v[164:167], v[208:211], v[68:71]
	v_mfma_f32_16x16x32_bf16 v[64:67], v[172:175], v[208:211], v[64:67]
	v_mfma_f32_16x16x32_bf16 v[108:111], v[168:171], v[184:187], v[108:111]
	v_mfma_f32_16x16x32_bf16 v[104:107], v[176:179], v[184:187], v[104:107]
	v_mfma_f32_16x16x32_bf16 v[92:95], v[168:171], v[192:195], v[92:95]
	v_mfma_f32_16x16x32_bf16 v[88:91], v[176:179], v[192:195], v[88:91]
	v_mfma_f32_16x16x32_bf16 v[76:79], v[168:171], v[200:203], v[76:79]
	v_mfma_f32_16x16x32_bf16 v[72:75], v[176:179], v[200:203], v[72:75]
	v_mfma_f32_16x16x32_bf16 v[68:71], v[168:171], v[212:215], v[68:71]
	v_mfma_f32_16x16x32_bf16 v[64:67], v[176:179], v[212:215], v[64:67]
	s_setprio 0
	s_barrier
	s_add_i32 s77, s64, s52
	v_lshl_add_u64 v[204:205], s[40:41], 0, v[130:131]
	s_mov_b32 m0, s77
	ds_read_b128 v[180:183], v147 offset:16384
	ds_read_b128 v[184:187], v147 offset:17408
	ds_read_b128 v[188:191], v147 offset:18432
	ds_read_b128 v[192:195], v147 offset:19456
	ds_read_b128 v[196:199], v147 offset:20480
	ds_read_b128 v[200:203], v147 offset:21504
	ds_read_b128 v[208:211], v147 offset:22528
	ds_read_b128 v[212:215], v147 offset:23552
	global_load_lds_dwordx4 v[204:205], off
	s_add_i32 m0, s77, 0x2000
	s_add_u32 s78, s40, 0xb0000
	v_lshl_add_u64 v[216:217], s[40:41], 0, v[134:135]
	s_addc_u32 s79, s41, 0
	s_add_i32 s77, s65, s52
	global_load_lds_dwordx4 v[216:217], off
	v_lshl_add_u64 v[218:219], s[78:79], 0, v[130:131]
	s_mov_b32 m0, s77
	v_lshl_add_u64 v[220:221], s[42:43], 0, v[132:133]
	global_load_lds_dwordx4 v[218:219], off
	v_lshl_add_u64 v[218:219], s[78:79], 0, v[134:135]
	s_add_i32 m0, s77, 0x2000
	s_nop 0
	global_load_lds_dwordx4 v[218:219], off
	v_lshl_add_u64 v[218:219], s[42:43], 0, v[128:129]
	s_mov_b32 m0, s57
	s_nop 0
	global_load_lds_dwordx4 v[218:219], off
	s_mov_b32 m0, s58
	s_nop 0
	global_load_lds_dwordx4 v[220:221], off
	s_waitcnt vmcnt(8)
	s_waitcnt lgkmcnt(0)
	s_barrier
	s_setprio 1
	s_waitcnt lgkmcnt(0)
	v_mfma_f32_16x16x32_bf16 v[60:63], v[148:151], v[180:183], v[60:63]
	v_mfma_f32_16x16x32_bf16 v[56:59], v[156:159], v[180:183], v[56:59]
	v_mfma_f32_16x16x32_bf16 v[52:55], v[148:151], v[188:191], v[52:55]
	v_mfma_f32_16x16x32_bf16 v[48:51], v[156:159], v[188:191], v[48:51]
	v_mfma_f32_16x16x32_bf16 v[36:39], v[148:151], v[196:199], v[36:39]
	v_mfma_f32_16x16x32_bf16 v[32:35], v[156:159], v[196:199], v[32:35]
	v_mfma_f32_16x16x32_bf16 v[20:23], v[148:151], v[208:211], v[20:23]
	v_mfma_f32_16x16x32_bf16 v[16:19], v[156:159], v[208:211], v[16:19]
	v_mfma_f32_16x16x32_bf16 v[60:63], v[152:155], v[184:187], v[60:63]
	v_mfma_f32_16x16x32_bf16 v[56:59], v[160:163], v[184:187], v[56:59]
	v_mfma_f32_16x16x32_bf16 v[52:55], v[152:155], v[192:195], v[52:55]
	v_mfma_f32_16x16x32_bf16 v[48:51], v[160:163], v[192:195], v[48:51]
	v_mfma_f32_16x16x32_bf16 v[36:39], v[152:155], v[200:203], v[36:39]
	v_mfma_f32_16x16x32_bf16 v[32:35], v[160:163], v[200:203], v[32:35]
	v_mfma_f32_16x16x32_bf16 v[20:23], v[152:155], v[212:215], v[20:23]
	v_mfma_f32_16x16x32_bf16 v[16:19], v[160:163], v[212:215], v[16:19]
	v_mfma_f32_16x16x32_bf16 v[44:47], v[164:167], v[180:183], v[44:47]
	v_mfma_f32_16x16x32_bf16 v[40:43], v[172:175], v[180:183], v[40:43]
	v_mfma_f32_16x16x32_bf16 v[28:31], v[164:167], v[188:191], v[28:31]
	v_mfma_f32_16x16x32_bf16 v[24:27], v[172:175], v[188:191], v[24:27]
	v_mfma_f32_16x16x32_bf16 v[12:15], v[164:167], v[196:199], v[12:15]
	v_mfma_f32_16x16x32_bf16 v[8:11], v[172:175], v[196:199], v[8:11]
	v_mfma_f32_16x16x32_bf16 v[4:7], v[164:167], v[208:211], v[4:7]
	v_mfma_f32_16x16x32_bf16 v[0:3], v[172:175], v[208:211], v[0:3]
	v_mfma_f32_16x16x32_bf16 v[44:47], v[168:171], v[184:187], v[44:47]
	v_mfma_f32_16x16x32_bf16 v[40:43], v[176:179], v[184:187], v[40:43]
	v_mfma_f32_16x16x32_bf16 v[28:31], v[168:171], v[192:195], v[28:31]
	v_mfma_f32_16x16x32_bf16 v[24:27], v[176:179], v[192:195], v[24:27]
	v_mfma_f32_16x16x32_bf16 v[12:15], v[168:171], v[200:203], v[12:15]
	v_mfma_f32_16x16x32_bf16 v[8:11], v[176:179], v[200:203], v[8:11]
	v_mfma_f32_16x16x32_bf16 v[4:7], v[168:171], v[212:215], v[4:7]
	v_mfma_f32_16x16x32_bf16 v[0:3], v[176:179], v[212:215], v[0:3]
	s_setprio 0
	s_barrier
; #define PG8_STAGE(bufoff, gbase, voff) do { _Pragma("unroll") for (int _i = 0; _i < 2; ++_i) \
;         __builtin_amdgcn_global_load_lds((const unsigned*)((const char*)(gbase) + (voff)[_i]), (PG8_LAS unsigned*)(lds + (bufoff) + ldsw + _i * 8192), 16, 0, 0); } while (0)
; #define PG8_LDA(dst, b, h) do { _Pragma("unroll") for (int m = 0; m < 4; ++m) _Pragma("unroll") for (int k = 0; k < 2; ++k) dst[m][k] = *(const PG8_LAS bf16x8*)(lds + PG8_SA(b, h) + aoff + m * 2048 + k * 1024); } while (0)
; #define PG8_LDB(dst, b, h) do { _Pragma("unroll") for (int n = 0; n < 2; ++n) _Pragma("unroll") for (int k = 0; k < 2; ++k) dst[n][k] = *(const PG8_LAS bf16x8*)(lds + PG8_SB(b, h) + boff + n * 2048 + k * 1024); } while (0)
; #define PG8_MMA(ai, bj, At, Bt) do { __builtin_amdgcn_s_setprio(1); _Pragma("unroll") for (int m = 0; m < 4; ++m) _Pragma("unroll") for (int n = 0; n < 2; ++n) _Pragma("unroll") for (int k = 0; k < 2; ++k) \
;         acc[ai][bj][m][n] = __builtin_amdgcn_mfma_f32_16x16x32_bf16(Bt[n][k], At[m][k], acc[ai][bj][m][n], 0, 0, 0); __builtin_amdgcn_s_setprio(0); } while (0)
; #define PG8_WAIT_V(n) asm volatile("s_waitcnt vmcnt(" #n ")" ::: "memory")
; #define PG8_WAIT_L(n) asm volatile("s_waitcnt lgkmcnt(" #n ")" ::: "memory")
; #define PG8_BAR __builtin_amdgcn_s_barrier()
; #define PG8_SCHED __builtin_amdgcn_sched_barrier(0)
; template <class Epi, class Sched, bool ALIGN_EPI = false, bool SP2 = false>
; __device__ __forceinline__ void gemm_phase(PG8_LAS unsigned char* lds, const Gemm g, const Sched& S, const Epi& E) {
;     ...
;             PG8_LDB(B0, 1, 0); PG8_LDB(B1, 1, 1); PG8_SCHED; PG8_LDA(At, 1, 0); PG8_STAGE(PG8_SA(0, 1), a2 + hstep, voffA);
;             PG8_WAIT_V(8); PG8_WAIT_L(0); PG8_BAR; PG8_MMA(0, 0, At, B0); PG8_MMA(0, 1, At, B1); PG8_BAR; PG8_SCHED;
	s_add_i32 s77, 0, 0x18000
	s_add_i32 s78, 0, 0x1c000
	v_add_u32_e32 v160, s77, v143
	v_add_u32_e32 v176, s78, v143
	ds_read_b128 v[148:151], v160
	ds_read_b128 v[152:155], v160 offset:1024
	ds_read_b128 v[156:159], v160 offset:2048
	ds_read_b128 v[160:163], v160 offset:3072
	ds_read_b128 v[164:167], v176
	ds_read_b128 v[168:171], v176 offset:1024
	ds_read_b128 v[172:175], v176 offset:2048
	ds_read_b128 v[176:179], v176 offset:3072
	s_add_u32 s42, s42, 0xb0000
	s_addc_u32 s43, s43, 0
	s_mov_b32 m0, s59
	v_lshl_add_u64 v[222:223], s[42:43], 0, v[128:129]
	ds_read_b128 v[180:183], v147 offset:32768
	ds_read_b128 v[184:187], v147 offset:33792
	ds_read_b128 v[188:191], v147 offset:34816
	ds_read_b128 v[192:195], v147 offset:35840
	ds_read_b128 v[196:199], v147 offset:36864
	ds_read_b128 v[200:203], v147 offset:37888
	ds_read_b128 v[208:211], v147 offset:38912
	ds_read_b128 v[212:215], v147 offset:39936
	global_load_lds_dwordx4 v[222:223], off
	v_lshl_add_u64 v[222:223], s[42:43], 0, v[132:133]
	s_mov_b32 m0, s60
	s_nop 0
	global_load_lds_dwordx4 v[222:223], off
	s_waitcnt vmcnt(8)
	s_waitcnt lgkmcnt(0)
	s_barrier
	s_setprio 1
	s_waitcnt lgkmcnt(0)
	v_mfma_f32_16x16x32_bf16 v[124:127], v[148:151], v[180:183], v[124:127]
	v_mfma_f32_16x16x32_bf16 v[120:123], v[156:159], v[180:183], v[120:123]
	v_mfma_f32_16x16x32_bf16 v[116:119], v[148:151], v[188:191], v[116:119]
	v_mfma_f32_16x16x32_bf16 v[112:115], v[156:159], v[188:191], v[112:115]
	v_mfma_f32_16x16x32_bf16 v[100:103], v[148:151], v[196:199], v[100:103]
	v_mfma_f32_16x16x32_bf16 v[96:99], v[156:159], v[196:199], v[96:99]
	v_mfma_f32_16x16x32_bf16 v[84:87], v[148:151], v[208:211], v[84:87]
	v_mfma_f32_16x16x32_bf16 v[80:83], v[156:159], v[208:211], v[80:83]
	v_mfma_f32_16x16x32_bf16 v[124:127], v[152:155], v[184:187], v[124:127]
	v_mfma_f32_16x16x32_bf16 v[120:123], v[160:163], v[184:187], v[120:123]
	v_mfma_f32_16x16x32_bf16 v[116:119], v[152:155], v[192:195], v[116:119]
	v_mfma_f32_16x16x32_bf16 v[112:115], v[160:163], v[192:195], v[112:115]
	v_mfma_f32_16x16x32_bf16 v[100:103], v[152:155], v[200:203], v[100:103]
	v_mfma_f32_16x16x32_bf16 v[96:99], v[160:163], v[200:203], v[96:99]
	v_mfma_f32_16x16x32_bf16 v[84:87], v[152:155], v[212:215], v[84:87]
	v_mfma_f32_16x16x32_bf16 v[80:83], v[160:163], v[212:215], v[80:83]
	v_mfma_f32_16x16x32_bf16 v[108:111], v[164:167], v[180:183], v[108:111]
	v_mfma_f32_16x16x32_bf16 v[104:107], v[172:175], v[180:183], v[104:107]
	v_mfma_f32_16x16x32_bf16 v[92:95], v[164:167], v[188:191], v[92:95]
	v_mfma_f32_16x16x32_bf16 v[88:91], v[172:175], v[188:191], v[88:91]
	v_mfma_f32_16x16x32_bf16 v[76:79], v[164:167], v[196:199], v[76:79]
	v_mfma_f32_16x16x32_bf16 v[72:75], v[172:175], v[196:199], v[72:75]
	v_mfma_f32_16x16x32_bf16 v[68:71], v[164:167], v[208:211], v[68:71]
	v_mfma_f32_16x16x32_bf16 v[64:67], v[172:175], v[208:211], v[64:67]
	v_mfma_f32_16x16x32_bf16 v[108:111], v[168:171], v[184:187], v[108:111]
	v_mfma_f32_16x16x32_bf16 v[104:107], v[176:179], v[184:187], v[104:107]
	v_mfma_f32_16x16x32_bf16 v[92:95], v[168:171], v[192:195], v[92:95]
	v_mfma_f32_16x16x32_bf16 v[88:91], v[176:179], v[192:195], v[88:91]
	v_mfma_f32_16x16x32_bf16 v[76:79], v[168:171], v[200:203], v[76:79]
	v_mfma_f32_16x16x32_bf16 v[72:75], v[176:179], v[200:203], v[72:75]
	v_mfma_f32_16x16x32_bf16 v[68:71], v[168:171], v[212:215], v[68:71]
	v_mfma_f32_16x16x32_bf16 v[64:67], v[176:179], v[212:215], v[64:67]
	s_setprio 0
	s_barrier
; #define PG8_STAGE(bufoff, gbase, voff) do { _Pragma("unroll") for (int _i = 0; _i < 2; ++_i) \
;         __builtin_amdgcn_global_load_lds((const unsigned*)((const char*)(gbase) + (voff)[_i]), (PG8_LAS unsigned*)(lds + (bufoff) + ldsw + _i * 8192), 16, 0, 0); } while (0)
; #define PG8_LDA(dst, b, h) do { _Pragma("unroll") for (int m = 0; m < 4; ++m) _Pragma("unroll") for (int k = 0; k < 2; ++k) dst[m][k] = *(const PG8_LAS bf16x8*)(lds + PG8_SA(b, h) + aoff + m * 2048 + k * 1024); } while (0)
; #define PG8_MMA(ai, bj, At, Bt) do { __builtin_amdgcn_s_setprio(1); _Pragma("unroll") for (int m = 0; m < 4; ++m) _Pragma("unroll") for (int n = 0; n < 2; ++n) _Pragma("unroll") for (int k = 0; k < 2; ++k) \
;         acc[ai][bj][m][n] = __builtin_amdgcn_mfma_f32_16x16x32_bf16(Bt[n][k], At[m][k], acc[ai][bj][m][n], 0, 0, 0); __builtin_amdgcn_s_setprio(0); } while (0)
; #define PG8_WAIT_V(n) asm volatile("s_waitcnt vmcnt(" #n ")" ::: "memory")
; #define PG8_WAIT_L(n) asm volatile("s_waitcnt lgkmcnt(" #n ")" ::: "memory")
; #define PG8_BAR __builtin_amdgcn_s_barrier()
; #define PG8_SCHED __builtin_amdgcn_sched_barrier(0)
; template <class Epi, class Sched, bool ALIGN_EPI = false, bool SP2 = false>
; __device__ __forceinline__ void gemm_phase(PG8_LAS unsigned char* lds, const Gemm g, const Sched& S, const Epi& E) {
;     ...
;             PG8_LDA(At, 1, 1); PG8_STAGE(PG8_SB(1, 0), b3, voffB); PG8_STAGE(PG8_SB(1, 1), b3 + hstep, voffB); PG8_STAGE(PG8_SA(1, 0), a3, voffA);
;             PG8_WAIT_V(8); PG8_WAIT_L(0); PG8_BAR; PG8_MMA(1, 0, At, B0); PG8_MMA(1, 1, At, B1); PG8_BAR; PG8_SCHED;
	s_add_i32 s42, s77, s52
	v_lshl_add_u64 v[204:205], v[204:205], 0, s[18:19]
	s_mov_b32 m0, s42
	ds_read_b128 v[180:183], v147 offset:49152
	ds_read_b128 v[184:187], v147 offset:50176
	ds_read_b128 v[188:191], v147 offset:51200
	ds_read_b128 v[192:195], v147 offset:52224
	ds_read_b128 v[196:199], v147 offset:53248
	ds_read_b128 v[200:203], v147 offset:54272
	ds_read_b128 v[208:211], v147 offset:55296
	ds_read_b128 v[212:215], v147 offset:56320
	global_load_lds_dwordx4 v[204:205], off
	s_add_i32 m0, s42, 0x2000
	s_add_u32 s40, s40, 0xb0080
	v_lshl_add_u64 v[204:205], v[216:217], 0, s[18:19]
	s_addc_u32 s41, s41, 0
	s_add_i32 s42, s78, s52
	global_load_lds_dwordx4 v[204:205], off
	v_lshl_add_u64 v[204:205], s[40:41], 0, v[130:131]
	s_mov_b32 m0, s42
	s_nop 0
	global_load_lds_dwordx4 v[204:205], off
	v_lshl_add_u64 v[204:205], s[40:41], 0, v[134:135]
	s_add_i32 m0, s42, 0x2000
	s_nop 0
	global_load_lds_dwordx4 v[204:205], off
	v_lshl_add_u64 v[204:205], v[218:219], 0, s[18:19]
	s_mov_b32 m0, s62
	s_nop 0
	global_load_lds_dwordx4 v[204:205], off
	v_lshl_add_u64 v[204:205], v[220:221], 0, s[18:19]
	s_mov_b32 m0, s63
	s_nop 0
	global_load_lds_dwordx4 v[204:205], off
	s_waitcnt vmcnt(8)
	s_waitcnt lgkmcnt(0)
	s_barrier
	s_setprio 1
	s_waitcnt lgkmcnt(0)
	v_mfma_f32_16x16x32_bf16 v[60:63], v[148:151], v[180:183], v[60:63]
	v_mfma_f32_16x16x32_bf16 v[56:59], v[156:159], v[180:183], v[56:59]
	v_mfma_f32_16x16x32_bf16 v[52:55], v[148:151], v[188:191], v[52:55]
	v_mfma_f32_16x16x32_bf16 v[48:51], v[156:159], v[188:191], v[48:51]
	v_mfma_f32_16x16x32_bf16 v[36:39], v[148:151], v[196:199], v[36:39]
	v_mfma_f32_16x16x32_bf16 v[32:35], v[156:159], v[196:199], v[32:35]
	v_mfma_f32_16x16x32_bf16 v[20:23], v[148:151], v[208:211], v[20:23]
	v_mfma_f32_16x16x32_bf16 v[16:19], v[156:159], v[208:211], v[16:19]
	v_mfma_f32_16x16x32_bf16 v[60:63], v[152:155], v[184:187], v[60:63]
	v_mfma_f32_16x16x32_bf16 v[56:59], v[160:163], v[184:187], v[56:59]
	v_mfma_f32_16x16x32_bf16 v[52:55], v[152:155], v[192:195], v[52:55]
	v_mfma_f32_16x16x32_bf16 v[48:51], v[160:163], v[192:195], v[48:51]
	v_mfma_f32_16x16x32_bf16 v[36:39], v[152:155], v[200:203], v[36:39]
	v_mfma_f32_16x16x32_bf16 v[32:35], v[160:163], v[200:203], v[32:35]
	v_mfma_f32_16x16x32_bf16 v[20:23], v[152:155], v[212:215], v[20:23]
	v_mfma_f32_16x16x32_bf16 v[16:19], v[160:163], v[212:215], v[16:19]
	v_mfma_f32_16x16x32_bf16 v[44:47], v[164:167], v[180:183], v[44:47]
	v_mfma_f32_16x16x32_bf16 v[40:43], v[172:175], v[180:183], v[40:43]
	v_mfma_f32_16x16x32_bf16 v[28:31], v[164:167], v[188:191], v[28:31]
	v_mfma_f32_16x16x32_bf16 v[24:27], v[172:175], v[188:191], v[24:27]
	v_mfma_f32_16x16x32_bf16 v[12:15], v[164:167], v[196:199], v[12:15]
	v_mfma_f32_16x16x32_bf16 v[8:11], v[172:175], v[196:199], v[8:11]
	v_mfma_f32_16x16x32_bf16 v[4:7], v[164:167], v[208:211], v[4:7]
	v_mfma_f32_16x16x32_bf16 v[0:3], v[172:175], v[208:211], v[0:3]
	v_mfma_f32_16x16x32_bf16 v[44:47], v[168:171], v[184:187], v[44:47]
	v_mfma_f32_16x16x32_bf16 v[40:43], v[176:179], v[184:187], v[40:43]
	v_mfma_f32_16x16x32_bf16 v[28:31], v[168:171], v[192:195], v[28:31]
	v_mfma_f32_16x16x32_bf16 v[24:27], v[176:179], v[192:195], v[24:27]
	v_mfma_f32_16x16x32_bf16 v[12:15], v[168:171], v[200:203], v[12:15]
	v_mfma_f32_16x16x32_bf16 v[8:11], v[176:179], v[200:203], v[8:11]
	v_mfma_f32_16x16x32_bf16 v[4:7], v[168:171], v[212:215], v[4:7]
	v_mfma_f32_16x16x32_bf16 v[0:3], v[176:179], v[212:215], v[0:3]
	s_setprio 0
	s_barrier
	s_add_i32 s76, s76, 2
	s_add_u32 s38, s38, 0x100
	s_addc_u32 s39, s39, 0
	s_add_u32 s74, s74, 0x100
	s_addc_u32 s75, s75, 0
	s_cmp_gt_u32 s76, 41
	s_cbranch_scc0 .LBB0_2093
